# flat_* memory ops converted to global_* (no LDS aperture use in file)
# speedup vs baseline: 1.0037x; 1.0037x over previous
.LBB0_60:
	global_load_dword v25, v[0:1], off offset:1024 sc1
	global_load_dword v10, v[0:1], off offset:1280 sc1
	global_load_dword v11, v[0:1], off offset:1536 sc1
	global_load_dword v12, v[0:1], off offset:1792 sc1
	global_load_dword v13, v[0:1], off offset:2048 sc1
	global_load_dword v14, v[0:1], off offset:2304 sc1
	global_load_dword v15, v[0:1], off offset:2560 sc1
	global_load_dword v16, v[0:1], off offset:2816 sc1
	global_load_dword v17, v[0:1], off offset:3072 sc1
	global_load_dword v18, v[0:1], off offset:3328 sc1
	global_load_dword v19, v[0:1], off offset:3584 sc1
	global_load_dword v20, v[0:1], off offset:3840 sc1
	global_load_dword v21, v[2:3], off sc1
	global_load_dword v22, v[4:5], off sc1
	global_load_dword v23, v[6:7], off sc1
	global_load_dword v24, v[8:9], off sc1
	s_or_b64 s[6:7], s[6:7], exec
	s_or_b64 s[4:5], s[4:5], exec
	s_waitcnt vmcnt(0) lgkmcnt(0)
	v_add_u32_e32 v26, v10, v25
	v_add_u32_e32 v26, v26, v11
	v_add_u32_e32 v26, v26, v12
	v_add_u32_e32 v26, v26, v13
	v_add_u32_e32 v26, v26, v14
	v_add_u32_e32 v26, v26, v15
	v_add_u32_e32 v26, v26, v16
	v_add_u32_e32 v26, v26, v17
	v_add_u32_e32 v26, v26, v18
	v_add_u32_e32 v26, v26, v19
	v_add_u32_e32 v26, v26, v20
	v_add_u32_e32 v26, v26, v21
	v_add_u32_e32 v26, v26, v22
	v_add_u32_e32 v26, v26, v23
	v_add_u32_e32 v26, v26, v24
	v_cmp_ne_u32_e32 vcc, s20, v26
	s_and_saveexec_b64 s[8:9], vcc
	s_cbranch_execz .LBB0_59
	s_and_b32 s12, s21, 0xff
	s_mov_b64 s[10:11], -1
	s_cmp_eq_u32 s12, 0
	s_mov_b64 s[14:15], -1
	s_mov_b64 s[12:13], -1
	s_sleep 1
	s_cbranch_scc1 .LBB0_63
	s_and_saveexec_b64 s[18:19], s[14:15]
	s_cbranch_execz .LBB0_58
	s_branch .LBB0_66
.LBB0_63:
	global_load_dword v26, v[0:1], off offset:512 sc1
	s_mov_b64 s[14:15], 0
	s_waitcnt vmcnt(0) lgkmcnt(0)
	v_cmp_eq_u32_e32 vcc, 0, v26
	s_and_saveexec_b64 s[18:19], vcc
	s_cmp_lt_u32 s21, 0x40001
	s_cselect_b64 s[14:15], -1, 0
	s_xor_b64 s[12:13], exec, -1
	s_and_b64 s[14:15], s[14:15], exec
	s_or_b64 exec, exec, s[18:19]
	s_and_saveexec_b64 s[18:19], s[14:15]
	s_cbranch_execz .LBB0_58

.LBB0_67:
	s_or_b64 exec, exec, s[0:1]
	s_xor_b64 s[0:1], s[2:3], -1
	s_and_saveexec_b64 s[2:3], s[0:1]
	s_xor_b64 s[0:1], exec, s[2:3]
	s_cbranch_execz .LBB0_69
	v_mov_b32_e32 v2, 1
	v_mov_b64_e32 v[0:1], s[36:37]
	global_atomic_add v[0:1], v2, off offset:512

.LBB0_70:
	s_lshl_b32 s0, s34, 8
	s_add_u32 s23, s36, s0
	s_addc_u32 s22, s37, 0
	v_mov_b32_e32 v1, s23
	v_add_co_u32_e32 v4, vcc, 0x1000, v1
	v_mov_b32_e32 v1, s22
	s_nop 0
	v_addc_co_u32_e32 v5, vcc, 0, v1, vcc
	v_mov_b32_e32 v1, 1
	global_atomic_add v1, v[4:5], v1, off offset:1024 sc0
	v_cvt_f32_u32_e32 v3, v2
	v_sub_u32_e32 v4, 0, v2
	v_rcp_iflag_f32_e32 v3, v3
	s_nop 0
	v_mul_f32_e32 v3, 0x4f7ffffe, v3
	v_cvt_u32_f32_e32 v3, v3
	v_mul_lo_u32 v4, v4, v3
	v_mul_hi_u32 v4, v3, v4
	v_add_u32_e32 v3, v3, v4
	s_waitcnt vmcnt(0) lgkmcnt(0)
	v_mul_hi_u32 v3, v1, v3
	v_mul_lo_u32 v5, v3, v2
	v_add_u32_e32 v4, 1, v1
	v_sub_u32_e32 v1, v1, v5
	v_add_u32_e32 v6, 1, v3
	v_cmp_ge_u32_e32 vcc, v1, v2
	v_sub_u32_e32 v5, v1, v2
	s_nop 0
	v_cndmask_b32_e32 v3, v3, v6, vcc
	v_cndmask_b32_e32 v1, v1, v5, vcc
	v_add_u32_e32 v5, 1, v3
	v_cmp_ge_u32_e32 vcc, v1, v2
	s_nop 1
	v_cndmask_b32_e32 v1, v3, v5, vcc
	v_mad_u64_u32 v[2:3], s[0:1], v2, v1, v[2:3]
	v_cmp_ne_u32_e32 vcc, v4, v2
	s_and_saveexec_b64 s[0:1], vcc
	s_xor_b64 s[0:1], exec, s[0:1]
	s_cbranch_execz .LBB0_83
	v_mov_b32_e32 v0, s23
	v_add_co_u32_e32 v2, vcc, 0x2000, v0
	v_mov_b32_e32 v0, s22
	s_nop 0
	v_addc_co_u32_e32 v3, vcc, 0, v0, vcc
	global_load_dword v0, v[2:3], off offset:1024 sc1
	s_add_u32 s4, s23, 0x2400
	s_addc_u32 s5, s22, 0
	s_waitcnt vmcnt(0) lgkmcnt(0)
	v_cmp_eq_u32_e32 vcc, v0, v1
	s_and_saveexec_b64 s[2:3], vcc
	s_cbranch_execz .LBB0_82
	s_mov_b32 s24, 1
	s_mov_b64 s[6:7], 0
	s_branch .LBB0_74

.LBB0_74:
	s_and_b32 s14, s24, 0xff
	s_mov_b64 s[12:13], -1
	s_cmp_lg_u32 s14, 0
	s_mov_b64 s[14:15], -1
	s_sleep 1
	s_cbranch_scc1 .LBB0_78
	v_mov_b64_e32 v[2:3], s[36:37]
	global_load_dword v0, v[2:3], off offset:512 sc1
	s_mov_b64 s[14:15], 0
	s_mov_b64 s[18:19], -1
	s_waitcnt vmcnt(0) lgkmcnt(0)
	v_cmp_eq_u32_e32 vcc, 0, v0
	s_and_saveexec_b64 s[20:21], vcc
	s_cmp_lt_u32 s24, 0x40001
	s_cselect_b64 s[14:15], -1, 0
	s_xor_b64 s[18:19], exec, -1
	s_and_b64 s[14:15], s[14:15], exec
	s_or_b64 exec, exec, s[20:21]
.LBB0_78:
	s_andn2_b64 s[10:11], s[10:11], exec
	s_and_b64 s[18:19], s[18:19], exec
	s_or_b64 s[10:11], s[10:11], s[18:19]
	s_and_saveexec_b64 s[18:19], s[14:15]
	s_cbranch_execz .LBB0_73
	v_mov_b64_e32 v[2:3], s[4:5]
	global_load_dword v0, v[2:3], off sc1
	s_add_i32 s24, s24, 1
	s_or_b64 s[10:11], s[10:11], exec
	s_waitcnt vmcnt(0) lgkmcnt(0)
	v_cmp_ne_u32_e32 vcc, v0, v1
	s_orn2_b64 s[12:13], vcc, exec
	s_branch .LBB0_73
.LBB0_80:
	s_or_b64 exec, exec, s[6:7]
	s_xor_b64 s[4:5], s[8:9], -1
	s_and_saveexec_b64 s[6:7], s[4:5]
	s_xor_b64 s[6:7], exec, s[6:7]
	s_cbranch_execz .LBB0_82
	v_mov_b32_e32 v2, 1
	v_mov_b64_e32 v[0:1], s[36:37]
	global_atomic_add v[0:1], v2, off offset:512

.LBB0_83:
	s_andn2_saveexec_b64 s[0:1], s[0:1]
	s_cbranch_execz .LBB0_99
	v_mov_b32_e32 v1, s36
	v_add_co_u32_e32 v2, vcc, 0x3000, v1
	v_mov_b32_e32 v1, s37
	buffer_wbl2 sc1
	s_waitcnt vmcnt(0)
	v_addc_co_u32_e32 v3, vcc, 0, v1, vcc
	v_mov_b32_e32 v1, 1
	global_atomic_add v1, v[2:3], v1, off offset:1024 sc0
	v_cvt_f32_u32_e32 v2, v0
	v_sub_u32_e32 v3, 0, v0
	s_add_u32 s0, s36, 0x3500
	s_addc_u32 s1, s37, 0
	v_rcp_iflag_f32_e32 v2, v2
	s_mov_b64 s[4:5], -1
	v_mul_f32_e32 v2, 0x4f7ffffe, v2
	v_cvt_u32_f32_e32 v2, v2
	v_mul_lo_u32 v3, v3, v2
	v_mul_hi_u32 v3, v2, v3
	v_add_u32_e32 v2, v2, v3
	s_waitcnt vmcnt(0) lgkmcnt(0)
	v_mul_hi_u32 v2, v1, v2
	v_mul_lo_u32 v4, v2, v0
	v_add_u32_e32 v3, 1, v1
	v_sub_u32_e32 v1, v1, v4
	v_add_u32_e32 v5, 1, v2
	v_cmp_ge_u32_e32 vcc, v1, v0
	v_sub_u32_e32 v4, v1, v0
	s_nop 0
	v_cndmask_b32_e32 v2, v2, v5, vcc
	v_cndmask_b32_e32 v1, v1, v4, vcc
	v_add_u32_e32 v4, 1, v2
	v_cmp_ge_u32_e32 vcc, v1, v0
	s_nop 1
	v_cndmask_b32_e32 v2, v2, v4, vcc
	v_mad_u64_u32 v[0:1], s[2:3], v0, v2, v[0:1]
	v_cmp_ne_u32_e32 vcc, v3, v0
	v_mov_b64_e32 v[0:1], s[0:1]
	s_and_saveexec_b64 s[2:3], vcc
	s_cbranch_execz .LBB0_96
	v_mov_b64_e32 v[0:1], s[0:1]
	global_load_dword v0, v[0:1], off sc1
	s_mov_b64 s[8:9], 0
	s_waitcnt vmcnt(0) lgkmcnt(0)
	v_cmp_eq_u32_e32 vcc, v0, v2
	s_and_saveexec_b64 s[6:7], vcc
	s_cbranch_execz .LBB0_95
	s_add_u32 s4, s36, 0x200
	s_addc_u32 s5, s37, 0
	s_mov_b32 s24, 1
	s_branch .LBB0_88

.LBB0_90:
	v_mov_b64_e32 v[0:1], s[4:5]
	global_load_dword v0, v[0:1], off sc1
	s_mov_b64 s[14:15], 0
	s_mov_b64 s[12:13], -1
	s_waitcnt vmcnt(0) lgkmcnt(0)
	v_cmp_eq_u32_e32 vcc, 0, v0
	s_and_saveexec_b64 s[18:19], vcc
	s_cmp_lt_u32 s24, 0x40001
	s_cselect_b64 s[14:15], -1, 0
	s_xor_b64 s[12:13], exec, -1
	s_and_b64 s[14:15], s[14:15], exec
	s_or_b64 exec, exec, s[18:19]
	s_mov_b64 s[18:19], -1
	s_and_saveexec_b64 s[20:21], s[14:15]
	s_cbranch_execz .LBB0_87
.LBB0_93:
	v_mov_b64_e32 v[0:1], s[0:1]
	global_load_dword v0, v[0:1], off sc1
	s_add_i32 s24, s24, 1
	s_or_b64 s[12:13], s[12:13], exec
	s_waitcnt vmcnt(0) lgkmcnt(0)
	v_cmp_ne_u32_e32 vcc, v0, v2
	s_orn2_b64 s[18:19], vcc, exec
	s_branch .LBB0_87

.LBB0_96:
	s_or_b64 exec, exec, s[2:3]
	s_and_saveexec_b64 s[0:1], s[4:5]
	s_cbranch_execz .LBB0_98
	v_mov_b32_e32 v2, 1
	global_atomic_add v[0:1], v2, off
.LBB0_98:
	s_or_b64 exec, exec, s[0:1]
	v_mov_b32_e32 v0, s23
	v_add_co_u32_e32 v0, vcc, 0x2000, v0
	v_mov_b32_e32 v1, s22
	s_nop 0
	v_addc_co_u32_e32 v1, vcc, 0, v1, vcc
	v_mov_b32_e32 v2, 1
	s_waitcnt vmcnt(0) lgkmcnt(0)
	buffer_inv sc1
	global_atomic_add v[0:1], v2, off offset:1024
	s_waitcnt vmcnt(0)

.LBB0_100:
	s_or_b64 exec, exec, s[0:1]
	v_mov_b32_e32 v0, s23
	v_add_co_u32_e32 v2, vcc, 0x2000, v0
	v_mov_b32_e32 v0, s22
	s_nop 0
	v_addc_co_u32_e32 v3, vcc, 0, v0, vcc
	s_waitcnt vmcnt(0) lgkmcnt(0)
	buffer_inv sc1
	global_atomic_add v[2:3], v203, off offset:1024
	s_waitcnt vmcnt(0)

.LBB0_105:
	s_or_b64 exec, exec, s[0:1]
	v_ashrrev_i32_e32 v21, 31, v20
	v_lshlrev_b32_e32 v38, 2, v30
	v_lshlrev_b64 v[20:21], 12, v[20:21]
	v_lshl_add_u64 v[22:23], s[10:11], 0, v[22:23]
	v_lshl_add_u64 v[20:21], v[24:25], 0, v[20:21]
	s_mov_b64 s[0:1], 0x1000
	v_lshlrev_b32_e32 v0, 2, v38
	v_lshl_add_u64 v[24:25], v[22:23], 0, s[0:1]
	v_lshl_add_u64 v[34:35], v[20:21], 0, v[0:1]
	global_store_dwordx4 v[34:35], v[14:17], off
	v_lshl_add_u64 v[36:37], s[6:7], 0, v[0:1]
	v_lshl_add_u64 v[30:31], v[24:25], 0, v[0:1]
	global_load_dwordx4 v[20:23], v[36:37], off
	s_nop 0
	global_load_dwordx4 v[30:33], v[30:31], off
	v_lshlrev_b64 v[18:19], 11, v[18:19]
	v_mov_b32_e32 v39, v1
	v_lshl_add_u64 v[18:19], s[22:23], 0, v[18:19]
	v_lshlrev_b32_e32 v38, 1, v38
	v_mov_b32_e32 v41, v1
	v_lshl_add_u64 v[38:39], v[18:19], 0, v[38:39]
	v_or_b32_e32 v40, 0x400, v0
	v_lshl_add_u64 v[18:19], v[24:25], 0, v[40:41]
	s_waitcnt vmcnt(0) lgkmcnt(0)
	v_pk_mul_f32 v[14:15], v[14:15], v[20:21]
	v_pk_add_f32 v[20:21], v[30:31], 1.0 op_sel_hi:[1,0]
	v_pk_mul_f32 v[16:17], v[16:17], v[22:23]
	v_pk_add_f32 v[22:23], v[32:33], 1.0 op_sel_hi:[1,0]
	v_pk_mul_f32 v[14:15], v[14:15], v[20:21]
	v_pk_mul_f32 v[16:17], v[16:17], v[22:23]
	v_cvt_pk_bf16_f32 v14, v14, v15
	v_cvt_pk_bf16_f32 v15, v16, v17
	global_store_dwordx2 v[38:39], v[14:15], off
	global_store_dwordx4 v[34:35], v[10:13], off offset:1024
	global_load_dwordx4 v[14:17], v[36:37], off offset:1024
	s_nop 0
	global_load_dwordx4 v[18:21], v[18:19], off
	v_mov_b32_e32 v23, v1
	v_or_b32_e32 v22, 0x800, v0
	v_lshl_add_u64 v[22:23], v[24:25], 0, v[22:23]
	v_or_b32_e32 v0, 0xc00, v0
	s_waitcnt vmcnt(0) lgkmcnt(0)
	v_pk_mul_f32 v[10:11], v[10:11], v[14:15]
	v_pk_add_f32 v[14:15], v[18:19], 1.0 op_sel_hi:[1,0]
	v_pk_mul_f32 v[12:13], v[12:13], v[16:17]
	v_pk_add_f32 v[16:17], v[20:21], 1.0 op_sel_hi:[1,0]
	v_pk_mul_f32 v[10:11], v[10:11], v[14:15]
	v_pk_mul_f32 v[12:13], v[12:13], v[16:17]
	v_cvt_pk_bf16_f32 v10, v10, v11
	v_cvt_pk_bf16_f32 v11, v12, v13
	global_store_dwordx2 v[38:39], v[10:11], off offset:512
	global_store_dwordx4 v[34:35], v[6:9], off offset:2048
	global_load_dwordx4 v[10:13], v[36:37], off offset:2048
	s_nop 0
	global_load_dwordx4 v[14:17], v[22:23], off
	v_lshl_add_u64 v[18:19], v[24:25], 0, v[0:1]
	s_waitcnt vmcnt(0) lgkmcnt(0)
	v_pk_mul_f32 v[6:7], v[6:7], v[10:11]
	v_pk_add_f32 v[10:11], v[14:15], 1.0 op_sel_hi:[1,0]
	v_pk_mul_f32 v[8:9], v[8:9], v[12:13]
	v_pk_add_f32 v[12:13], v[16:17], 1.0 op_sel_hi:[1,0]
	v_pk_mul_f32 v[6:7], v[6:7], v[10:11]
	v_pk_mul_f32 v[8:9], v[8:9], v[12:13]
	v_cvt_pk_bf16_f32 v6, v6, v7
	v_cvt_pk_bf16_f32 v7, v8, v9
	global_store_dwordx2 v[38:39], v[6:7], off offset:1024
	global_store_dwordx4 v[34:35], v[2:5], off offset:3072
	global_load_dwordx4 v[6:9], v[36:37], off offset:3072
	s_nop 0
	global_load_dwordx4 v[10:13], v[18:19], off
	s_waitcnt vmcnt(0) lgkmcnt(0)
	v_pk_mul_f32 v[2:3], v[2:3], v[6:7]
	v_pk_add_f32 v[6:7], v[10:11], 1.0 op_sel_hi:[1,0]
	v_pk_mul_f32 v[4:5], v[4:5], v[8:9]
	v_pk_add_f32 v[8:9], v[12:13], 1.0 op_sel_hi:[1,0]
	v_pk_mul_f32 v[2:3], v[2:3], v[6:7]
	v_pk_mul_f32 v[4:5], v[4:5], v[8:9]
	v_cvt_pk_bf16_f32 v2, v2, v3
	v_cvt_pk_bf16_f32 v3, v4, v5
	global_store_dwordx2 v[38:39], v[2:3], off offset:1536

.LBB0_107:
	v_lshl_add_u32 v3, s28, 1, v26
	s_movk_i32 s0, 0x21ff
	v_cmp_lt_i32_e32 vcc, s0, v3
	v_lshlrev_b32_e32 v2, 2, v3
	s_and_saveexec_b64 s[0:1], vcc
	s_xor_b64 s[24:25], exec, s[0:1]
	s_cbranch_execz .LBB0_147
	v_mov_b32_e32 v7, v201
	v_and_b32_e32 v0, 0x7fffffc0, v2
	v_lshlrev_b32_e32 v3, 6, v3
	v_add_u32_e32 v2, 0xffff7800, v0
	v_and_b32_e32 v6, 63, v7
	v_bfe_u32 v8, v7, 6, 2
	v_and_b32_e32 v3, 0x3c0, v3
	v_or_b32_e32 v0, v6, v2
	v_or_b32_e32 v9, v8, v3
	v_cmp_gt_u32_e64 s[0:1], s41, v0
	v_lshl_add_u64 v[4:5], v[0:1], 2, s[8:9]
	v_mul_u32_u24_e32 v0, 0x910, v9
	v_mov_b32_e32 v10, 0
	v_lshlrev_b32_e32 v0, 2, v0
	v_mov_b32_e32 v9, 0
	s_barrier
	s_and_saveexec_b64 s[26:27], s[0:1]
	s_cbranch_execz .LBB0_110
	v_lshl_add_u64 v[12:13], v[4:5], 0, v[0:1]
	global_load_dword v9, v[12:13], off
.LBB0_110:
	s_or_b64 exec, exec, s[26:27]
	s_and_saveexec_b64 s[26:27], s[0:1]
	s_cbranch_execz .LBB0_112
	v_lshl_add_u64 v[10:11], v[4:5], 0, v[0:1]
	v_add_co_u32_e32 v10, vcc, 0x9000, v10
	s_nop 1
	v_addc_co_u32_e32 v11, vcc, 0, v11, vcc
	global_load_dword v10, v[10:11], off offset:256
.LBB0_112:
	s_or_b64 exec, exec, s[26:27]
	v_mov_b32_e32 v11, 0
	v_mov_b32_e32 v12, 0
	s_and_saveexec_b64 s[26:27], s[0:1]
	s_cbranch_execz .LBB0_114
	v_lshl_add_u64 v[12:13], v[4:5], 0, v[0:1]
	v_add_co_u32_e32 v12, vcc, 0x12000, v12
	s_nop 1
	v_addc_co_u32_e32 v13, vcc, 0, v13, vcc
	global_load_dword v12, v[12:13], off offset:512
.LBB0_114:
	s_or_b64 exec, exec, s[26:27]
	s_and_saveexec_b64 s[26:27], s[0:1]
	s_cbranch_execz .LBB0_116
	v_lshl_add_u64 v[14:15], v[4:5], 0, v[0:1]
	v_add_co_u32_e32 v14, vcc, 0x1b000, v14
	s_nop 1
	v_addc_co_u32_e32 v15, vcc, 0, v15, vcc
	global_load_dword v11, v[14:15], off offset:768
.LBB0_116:
	s_or_b64 exec, exec, s[26:27]
	v_mov_b32_e32 v13, 0
	v_mov_b32_e32 v14, 0
	s_and_saveexec_b64 s[26:27], s[0:1]
	s_cbranch_execz .LBB0_118
	v_lshl_add_u64 v[14:15], v[4:5], 0, v[0:1]
	v_add_co_u32_e32 v14, vcc, 0x24000, v14
	s_nop 1
	v_addc_co_u32_e32 v15, vcc, 0, v15, vcc
	global_load_dword v14, v[14:15], off offset:1024
.LBB0_118:
	s_or_b64 exec, exec, s[26:27]
	s_and_saveexec_b64 s[26:27], s[0:1]
	s_cbranch_execz .LBB0_120
	v_lshl_add_u64 v[16:17], v[4:5], 0, v[0:1]
	v_add_co_u32_e32 v16, vcc, 0x2d000, v16
	s_nop 1
	v_addc_co_u32_e32 v17, vcc, 0, v17, vcc
	global_load_dword v13, v[16:17], off offset:1280
.LBB0_120:
	s_or_b64 exec, exec, s[26:27]
	v_mov_b32_e32 v15, 0
	v_mov_b32_e32 v16, 0
	s_and_saveexec_b64 s[26:27], s[0:1]
	s_cbranch_execz .LBB0_122
	v_lshl_add_u64 v[16:17], v[4:5], 0, v[0:1]
	v_add_co_u32_e32 v16, vcc, 0x36000, v16
	s_nop 1
	v_addc_co_u32_e32 v17, vcc, 0, v17, vcc
	global_load_dword v16, v[16:17], off offset:1536
.LBB0_122:
	s_or_b64 exec, exec, s[26:27]
	s_and_saveexec_b64 s[26:27], s[0:1]
	s_cbranch_execz .LBB0_124
	v_lshl_add_u64 v[18:19], v[4:5], 0, v[0:1]
	v_add_co_u32_e32 v18, vcc, 0x3f000, v18
	s_nop 1
	v_addc_co_u32_e32 v19, vcc, 0, v19, vcc
	global_load_dword v15, v[18:19], off offset:1792
.LBB0_124:
	s_or_b64 exec, exec, s[26:27]
	v_mov_b32_e32 v18, 0
	v_mov_b32_e32 v19, 0
	s_and_saveexec_b64 s[26:27], s[0:1]
	s_cbranch_execz .LBB0_126
	v_lshl_add_u64 v[20:21], v[4:5], 0, v[0:1]
	v_add_co_u32_e32 v20, vcc, 0x48000, v20
	s_nop 1
	v_addc_co_u32_e32 v21, vcc, 0, v21, vcc
	global_load_dword v19, v[20:21], off offset:2048
.LBB0_126:
	s_or_b64 exec, exec, s[26:27]
	s_and_saveexec_b64 s[26:27], s[0:1]
	s_cbranch_execz .LBB0_128
	v_lshl_add_u64 v[20:21], v[4:5], 0, v[0:1]
	v_add_co_u32_e32 v20, vcc, 0x51000, v20
	s_nop 1
	v_addc_co_u32_e32 v21, vcc, 0, v21, vcc
	global_load_dword v18, v[20:21], off offset:2304
.LBB0_128:
	s_or_b64 exec, exec, s[26:27]
	v_mov_b32_e32 v20, 0
	v_mov_b32_e32 v21, 0
	s_and_saveexec_b64 s[26:27], s[0:1]
	s_cbranch_execz .LBB0_130
	v_lshl_add_u64 v[22:23], v[4:5], 0, v[0:1]
	v_add_co_u32_e32 v22, vcc, 0x5a000, v22
	s_nop 1
	v_addc_co_u32_e32 v23, vcc, 0, v23, vcc
	global_load_dword v21, v[22:23], off offset:2560
.LBB0_130:
	s_or_b64 exec, exec, s[26:27]
	s_and_saveexec_b64 s[26:27], s[0:1]
	s_cbranch_execz .LBB0_132
	v_lshl_add_u64 v[22:23], v[4:5], 0, v[0:1]
	v_add_co_u32_e32 v22, vcc, 0x63000, v22
	s_nop 1
	v_addc_co_u32_e32 v23, vcc, 0, v23, vcc
	global_load_dword v20, v[22:23], off offset:2816
.LBB0_132:
	s_or_b64 exec, exec, s[26:27]
	v_mov_b32_e32 v22, 0
	v_mov_b32_e32 v23, 0
	s_and_saveexec_b64 s[26:27], s[0:1]
	s_cbranch_execz .LBB0_134
	v_lshl_add_u64 v[24:25], v[4:5], 0, v[0:1]
	v_add_co_u32_e32 v24, vcc, 0x6c000, v24
	s_nop 1
	v_addc_co_u32_e32 v25, vcc, 0, v25, vcc
	global_load_dword v23, v[24:25], off offset:3072
.LBB0_134:
	s_or_b64 exec, exec, s[26:27]
	s_and_saveexec_b64 s[26:27], s[0:1]
	s_cbranch_execz .LBB0_136
	v_lshl_add_u64 v[24:25], v[4:5], 0, v[0:1]
	v_add_co_u32_e32 v24, vcc, 0x75000, v24
	s_nop 1
	v_addc_co_u32_e32 v25, vcc, 0, v25, vcc
	global_load_dword v22, v[24:25], off offset:3328
.LBB0_136:
	s_or_b64 exec, exec, s[26:27]
	v_mov_b32_e32 v24, 0
	v_mov_b32_e32 v25, 0
	s_and_saveexec_b64 s[26:27], s[0:1]
	s_cbranch_execz .LBB0_138
	v_lshl_add_u64 v[30:31], v[4:5], 0, v[0:1]
	v_add_co_u32_e32 v30, vcc, 0x7e000, v30
	s_nop 1
	v_addc_co_u32_e32 v31, vcc, 0, v31, vcc
	global_load_dword v25, v[30:31], off offset:3584
.LBB0_138:
	s_or_b64 exec, exec, s[26:27]
	s_and_saveexec_b64 s[26:27], s[0:1]
	s_cbranch_execz .LBB0_140
	v_lshl_add_u64 v[4:5], v[4:5], 0, v[0:1]
	v_add_co_u32_e32 v4, vcc, 0x87000, v4
	s_nop 1
	v_addc_co_u32_e32 v5, vcc, 0, v5, vcc
	global_load_dword v24, v[4:5], off offset:3840

.LBB0_141:
	global_load_dword v0, v[6:7], off
	v_add_u32_e32 v9, 0x100, v9
	v_cmp_lt_u32_e32 vcc, s50, v9
	v_lshl_add_u64 v[6:7], v[6:7], 0, s[42:43]
	s_or_b64 s[0:1], vcc, s[0:1]
	s_waitcnt vmcnt(0) lgkmcnt(0)
	ds_write_b32 v5, v0
	v_add_u32_e32 v5, 0x400, v5
	s_andn2_b64 exec, exec, s[0:1]
	s_cbranch_execnz .LBB0_141
	s_or_b64 exec, exec, s[0:1]
	v_lshlrev_b32_e32 v0, 4, v17
	v_and_b32_e32 v5, 48, v0
	v_mul_u32_u24_e32 v0, 0x41, v5
	v_lshlrev_b32_e32 v0, 2, v0
	v_and_b32_e32 v9, 0xfc, v17
	v_add3_u32 v16, v27, v0, v9
	v_add3_u32 v0, v27, v9, v0
	s_waitcnt lgkmcnt(0)
	s_barrier
	ds_read2_b32 v[6:7], v16 offset1:130
	ds_read2_b32 v[10:11], v0 offset0:65 offset1:195
	v_add_u32_e32 v12, 0x400, v0
	ds_read2_b32 v[12:13], v12 offset0:69 offset1:199
	v_lshrrev_b32_e32 v9, 2, v17
	v_add_u32_e32 v14, 0x800, v16
	s_waitcnt lgkmcnt(1)
	v_cvt_pk_bf16_f32 v10, v6, v10
	v_add_u32_e32 v6, 0x400, v16
	v_cvt_pk_bf16_f32 v11, v7, v11
	ds_read2_b32 v[6:7], v6 offset0:4 offset1:134
	v_add_u32_e32 v18, 0x800, v0
	v_add_u32_e32 v16, 0xc00, v16
	v_add_u32_e32 v0, 0xc00, v0
	ds_read2_b32 v[14:15], v14 offset0:8 offset1:138
	ds_read2_b32 v[18:19], v18 offset0:73 offset1:203
	ds_read2_b32 v[20:21], v16 offset0:12 offset1:142
	ds_read2_b32 v[22:23], v0 offset0:77 offset1:207
	v_or_b32_e32 v0, v9, v2
	s_waitcnt lgkmcnt(4)
	v_cvt_pk_bf16_f32 v12, v6, v12
	v_cvt_pk_bf16_f32 v13, v7, v13
	v_lshlrev_b64 v[6:7], 11, v[0:1]
	v_lshl_add_u64 v[6:7], s[14:15], 0, v[6:7]
	v_lshlrev_b32_e32 v0, 1, v3
	v_mov_b32_e32 v3, v1
	v_lshl_add_u64 v[6:7], v[6:7], 0, v[0:1]
	v_lshlrev_b32_e32 v0, 1, v5
	v_lshl_add_u64 v[2:3], v[2:3], 2, s[16:17]
	v_mov_b32_e32 v5, v1
	v_lshl_add_u64 v[6:7], v[6:7], 0, v[0:1]
	v_lshl_add_u64 v[2:3], v[2:3], 0, v[4:5]
	v_add_u32_e32 v4, v27, v4
	v_lshl_add_u32 v5, v8, 8, v28
	s_mov_b64 s[0:1], 0
	s_waitcnt lgkmcnt(2)
	v_cvt_pk_bf16_f32 v18, v14, v18
	v_cvt_pk_bf16_f32 v19, v15, v19
	s_waitcnt lgkmcnt(0)
	v_cvt_pk_bf16_f32 v20, v20, v22
	v_cvt_pk_bf16_f32 v21, v21, v23
	global_store_dwordx4 v[6:7], v[10:13], off
	global_store_dwordx4 v[6:7], v[18:21], off offset:16

.LBB0_144:
	ds_read2_b32 v[18:19], v0 offset1:65
	ds_read2_b32 v[20:21], v0 offset0:130 offset1:195
	v_add_u32_e32 v7, s26, v5
	v_add_u32_e32 v16, 0x400, v0
	ds_read_b128 v[8:11], v7
	ds_read_b128 v[12:15], v7 offset:16
	ds_read2_b32 v[22:23], v16 offset0:4 offset1:69
	ds_read2_b32 v[24:25], v16 offset0:134 offset1:199
	s_add_i32 s26, s26, 32
	s_waitcnt lgkmcnt(0)
	v_fmac_f32_e32 v6, v8, v18
	v_fmac_f32_e32 v6, v9, v19
	v_fmac_f32_e32 v6, v10, v20
	v_fmac_f32_e32 v6, v11, v21
	v_fmac_f32_e32 v6, v12, v22
	v_fmac_f32_e32 v6, v13, v23
	v_fmac_f32_e32 v6, v14, v24
	v_add_u32_e32 v0, 0x820, v0
	s_cmpk_eq_i32 s26, 0x100
	v_fmac_f32_e32 v6, v15, v25
	s_cbranch_scc0 .LBB0_144
	v_lshrrev_b32_e32 v0, 6, v17
	v_mul_lo_u32 v0, v0, s72
	v_lshl_add_u64 v[8:9], v[0:1], 2, v[2:3]
	global_atomic_add_f32 v[8:9], v6, off
	v_add_u32_e32 v0, 0x100, v17
	v_cmp_lt_u32_e32 vcc, s50, v17
	v_add_u32_e32 v5, 0x400, v5
	s_or_b64 s[0:1], vcc, s[0:1]
	v_mov_b32_e32 v17, v0
	s_andn2_b64 exec, exec, s[0:1]
	s_cbranch_execnz .LBB0_143
	s_or_b64 exec, exec, s[0:1]
.LBB0_147:
	s_andn2_saveexec_b64 s[24:25], s[24:25]
	s_cbranch_execz .LBB0_106
	v_mov_b32_e32 v0, v201
	s_movk_i32 s0, 0xff00
	v_lshrrev_b32_e32 v3, 6, v0
	v_and_or_b32 v18, v3, 3, v2
	v_mul_hi_i32 v2, v18, s61
	v_lshrrev_b32_e32 v3, 31, v2
	v_ashrrev_i32_e32 v2, 11, v2
	v_add_u32_e32 v3, v2, v3
	v_mad_i32_i24 v6, v3, s48, v18
	v_lshlrev_b32_e32 v4, 12, v3
	v_cmp_lt_i32_e32 vcc, s49, v6
	v_add3_u32 v20, v4, v6, s0
	s_and_saveexec_b64 s[0:1], vcc
	s_xor_b64 s[0:1], exec, s[0:1]
	s_movk_i32 s26, 0xff00
	v_add3_u32 v2, v4, v6, s26
	v_mul_hi_i32_i24_e32 v23, 0x6000, v3
	v_mul_i32_i24_e32 v22, 0x6000, v3
	s_or_saveexec_b64 s[0:1], s[0:1]
	v_mov_b64_e32 v[4:5], s[2:3]
	v_lshl_add_u32 v21, v3, 8, v6
	s_xor_b64 exec, exec, s[0:1]
	v_lshl_add_u32 v2, v3, 8, v6
	v_mov_b64_e32 v[22:23], 0x30000
	v_mov_b64_e32 v[4:5], s[4:5]
	s_or_b64 exec, exec, s[0:1]
	v_ashrrev_i32_e32 v3, 31, v2
	v_and_b32_e32 v30, 63, v0
	v_lshlrev_b64 v[2:3], 12, v[2:3]
	v_lshl_add_u64 v[2:3], v[4:5], 0, v[2:3]
	v_lshlrev_b32_e32 v0, 4, v30
	v_lshl_add_u64 v[2:3], v[2:3], 0, v[0:1]
	global_load_dwordx4 v[14:17], v[2:3], off
	global_load_dwordx4 v[10:13], v[2:3], off offset:1024
	global_load_dwordx4 v[6:9], v[2:3], off offset:2048
	s_nop 0
	global_load_dwordx4 v[2:5], v[2:3], off offset:3072
	v_and_b32_e32 v0, 64, v208
	v_xor_b32_e32 v19, 32, v208
	v_add_u32_e32 v0, 64, v0
	v_cmp_lt_i32_e64 s[0:1], v19, v0
	s_waitcnt vmcnt(0) lgkmcnt(0)
	v_pk_mul_f32 v[24:25], v[14:15], v[14:15]
	v_pk_mul_f32 v[34:35], v[10:11], v[10:11]
	v_pk_mul_f32 v[32:33], v[16:17], v[16:17]
	v_pk_mul_f32 v[36:37], v[12:13], v[12:13]
	v_pk_mul_f32 v[38:39], v[6:7], v[6:7]
	v_add_f32_e32 v31, v34, v35
	v_add_f32_e32 v24, v24, v25
	v_pk_mul_f32 v[40:41], v[8:9], v[8:9]
	v_pk_mul_f32 v[42:43], v[2:3], v[2:3]
	v_add_f32_e32 v25, v38, v39
	v_add_f32_e32 v31, v31, v36
	v_add_f32_e32 v24, v24, v32
	v_pk_mul_f32 v[44:45], v[4:5], v[4:5]
	v_add_f32_e32 v34, v42, v43
	v_add_f32_e32 v25, v25, v40
	v_add_f32_e32 v31, v31, v37
	v_add_f32_e32 v24, v24, v33
	v_add_f32_e32 v32, v34, v44
	v_add_f32_e32 v25, v25, v41
	v_add_f32_e32 v24, v24, v31
	v_cndmask_b32_e64 v19, v208, v19, s[0:1]
	v_add_f32_e32 v32, v32, v45
	v_add_f32_e32 v24, v24, v25
	v_lshlrev_b32_e32 v19, 2, v19
	v_add_f32_e32 v24, v24, v32
	ds_bpermute_b32 v19, v19, v24
	v_xor_b32_e32 v25, 16, v208
	v_cmp_lt_i32_e64 s[0:1], v25, v0
	s_waitcnt lgkmcnt(0)
	v_add_f32_e32 v19, v24, v19
	v_cndmask_b32_e64 v25, v208, v25, s[0:1]
	v_lshlrev_b32_e32 v25, 2, v25
	ds_bpermute_b32 v24, v25, v19
	v_xor_b32_e32 v25, 8, v208
	v_cmp_lt_i32_e64 s[0:1], v25, v0
	s_waitcnt lgkmcnt(0)
	v_add_f32_e32 v19, v19, v24
	v_cndmask_b32_e64 v25, v208, v25, s[0:1]
	v_lshlrev_b32_e32 v25, 2, v25
	ds_bpermute_b32 v24, v25, v19
	v_xor_b32_e32 v25, 4, v208
	v_cmp_lt_i32_e64 s[0:1], v25, v0
	s_waitcnt lgkmcnt(0)
	v_add_f32_e32 v19, v19, v24
	v_cndmask_b32_e64 v25, v208, v25, s[0:1]
	v_lshlrev_b32_e32 v25, 2, v25
	ds_bpermute_b32 v24, v25, v19
	v_xor_b32_e32 v25, 2, v208
	v_cmp_lt_i32_e64 s[0:1], v25, v0
	s_waitcnt lgkmcnt(0)
	v_add_f32_e32 v19, v19, v24
	v_cndmask_b32_e64 v25, v208, v25, s[0:1]
	v_lshlrev_b32_e32 v25, 2, v25
	ds_bpermute_b32 v24, v25, v19
	v_xor_b32_e32 v25, 1, v208
	v_cmp_lt_i32_e64 s[0:1], v25, v0
	s_waitcnt lgkmcnt(0)
	v_add_f32_e32 v0, v19, v24
	v_cndmask_b32_e64 v25, v208, v25, s[0:1]
	v_lshlrev_b32_e32 v19, 2, v25
	ds_bpermute_b32 v24, v19, v0
	v_cmp_eq_u32_e64 s[0:1], 0, v30
	v_ashrrev_i32_e32 v19, 31, v18
	s_and_saveexec_b64 s[26:27], s[0:1]
	s_cbranch_execnz .LBB0_155
	s_or_b64 exec, exec, s[26:27]
	s_and_saveexec_b64 s[0:1], vcc
	s_xor_b64 s[0:1], exec, s[0:1]
	s_cbranch_execnz .LBB0_156

.LBB0_155:
	v_lshl_add_u64 v[32:33], v[18:19], 2, s[18:19]
	s_waitcnt lgkmcnt(0)
	v_add_f32_e32 v0, v0, v24
	global_store_dword v[32:33], v0, off
	s_or_b64 exec, exec, s[26:27]
	s_and_saveexec_b64 s[0:1], vcc
	s_xor_b64 s[0:1], exec, s[0:1]
	s_cbranch_execz .LBB0_154

.LBB0_163:
	v_mov_b64_e32 v[14:15], s[38:39]
	global_load_dword v12, v[14:15], off offset:1024 sc1
	s_waitcnt lgkmcnt(0)
	global_load_dword v0, v[14:15], off offset:1280 sc1
	global_load_dword v2, v[14:15], off offset:1536 sc1
	global_load_dword v3, v[14:15], off offset:1792 sc1
	global_load_dword v4, v[14:15], off offset:2048 sc1
	global_load_dword v5, v[14:15], off offset:2304 sc1
	global_load_dword v6, v[14:15], off offset:2560 sc1
	global_load_dword v7, v[14:15], off offset:2816 sc1
	global_load_dword v8, v[14:15], off offset:3072 sc1
	global_load_dword v9, v[14:15], off offset:3328 sc1
	global_load_dword v10, v[14:15], off offset:3584 sc1
	global_load_dword v11, v[14:15], off offset:3840 sc1
	v_mov_b64_e32 v[14:15], s[0:1]
	global_load_dword v13, v[14:15], off sc1
	v_mov_b64_e32 v[14:15], s[2:3]
	global_load_dword v14, v[14:15], off sc1
	v_mov_b64_e32 v[16:17], s[4:5]
	global_load_dword v15, v[16:17], off sc1
	v_mov_b64_e32 v[16:17], s[6:7]
	global_load_dword v16, v[16:17], off sc1
	v_readlane_b32 s18, v254, 5
	s_or_b64 s[14:15], s[14:15], exec
	s_or_b64 s[12:13], s[12:13], exec
	s_waitcnt vmcnt(0) lgkmcnt(0)
	v_add_u32_e32 v17, v0, v12
	v_add_u32_e32 v17, v17, v2
	v_add_u32_e32 v17, v17, v3
	v_add_u32_e32 v17, v17, v4
	v_add_u32_e32 v17, v17, v5
	v_add_u32_e32 v17, v17, v6
	v_add_u32_e32 v17, v17, v7
	v_add_u32_e32 v17, v17, v8
	v_add_u32_e32 v17, v17, v9
	v_add_u32_e32 v17, v17, v10
	v_add_u32_e32 v17, v17, v11
	v_add_u32_e32 v17, v17, v13
	v_add_u32_e32 v17, v17, v14
	v_add_u32_e32 v17, v17, v15
	v_add_u32_e32 v17, v17, v16
	v_cmp_ne_u32_e32 vcc, s18, v17
	s_and_saveexec_b64 s[18:19], vcc
	s_cbranch_execz .LBB0_162
	s_and_b32 s22, s28, 0xff
	s_mov_b64 s[20:21], -1
	s_cmp_eq_u32 s22, 0
	s_mov_b64 s[24:25], -1
	s_mov_b64 s[22:23], -1
	s_sleep 1
	s_cbranch_scc1 .LBB0_166
	s_and_saveexec_b64 s[26:27], s[24:25]
	s_cbranch_execz .LBB0_161
	s_branch .LBB0_169
.LBB0_166:
	v_mov_b64_e32 v[18:19], s[38:39]
	global_load_dword v17, v[18:19], off offset:512 sc1
	s_mov_b64 s[24:25], 0
	s_waitcnt vmcnt(0) lgkmcnt(0)
	v_cmp_eq_u32_e32 vcc, 0, v17
	s_and_saveexec_b64 s[26:27], vcc
	s_cmp_lt_u32 s28, 0x40001
	s_cselect_b64 s[24:25], -1, 0
	s_xor_b64 s[22:23], exec, -1
	s_and_b64 s[24:25], s[24:25], exec
	s_or_b64 exec, exec, s[26:27]
	s_and_saveexec_b64 s[26:27], s[24:25]
	s_cbranch_execz .LBB0_161

.LBB0_170:
	s_or_b64 exec, exec, s[8:9]
	s_xor_b64 s[0:1], s[10:11], -1
	s_and_saveexec_b64 s[2:3], s[0:1]
	s_xor_b64 s[0:1], exec, s[2:3]
	s_cbranch_execz .LBB0_172
	v_mov_b64_e32 v[18:19], s[38:39]
	global_atomic_add v[18:19], v203, off offset:512

.LBB0_173:
	s_lshl_b32 s0, s37, 8
	s_add_u32 s23, s38, s0
	s_addc_u32 s22, s39, 0
	v_mov_b32_e32 v3, s23
	v_add_co_u32_e32 v4, vcc, 0x1000, v3
	v_mov_b32_e32 v3, s22
	s_nop 0
	v_addc_co_u32_e32 v5, vcc, 0, v3, vcc
	global_atomic_add v3, v[4:5], v203, off offset:1024 sc0
	v_cvt_f32_u32_e32 v4, v2
	v_sub_u32_e32 v5, 0, v2
	v_rcp_iflag_f32_e32 v4, v4
	s_nop 0
	v_mul_f32_e32 v4, 0x4f7ffffe, v4
	v_cvt_u32_f32_e32 v4, v4
	v_mul_lo_u32 v5, v5, v4
	v_mul_hi_u32 v5, v4, v5
	v_add_u32_e32 v4, v4, v5
	s_waitcnt vmcnt(0) lgkmcnt(0)
	v_mul_hi_u32 v4, v3, v4
	v_mul_lo_u32 v5, v4, v2
	v_add_u32_e32 v6, 1, v3
	v_sub_u32_e32 v3, v3, v5
	v_add_u32_e32 v7, 1, v4
	v_cmp_ge_u32_e32 vcc, v3, v2
	v_sub_u32_e32 v5, v3, v2
	s_nop 0
	v_cndmask_b32_e32 v4, v4, v7, vcc
	v_cndmask_b32_e32 v3, v3, v5, vcc
	v_add_u32_e32 v5, 1, v4
	v_cmp_ge_u32_e32 vcc, v3, v2
	s_nop 1
	v_cndmask_b32_e32 v3, v4, v5, vcc
	v_mad_u64_u32 v[4:5], s[0:1], v2, v3, v[2:3]
	v_cmp_ne_u32_e32 vcc, v6, v4
	s_and_saveexec_b64 s[0:1], vcc
	s_xor_b64 s[0:1], exec, s[0:1]
	s_cbranch_execz .LBB0_186
	v_mov_b32_e32 v0, s23
	v_add_co_u32_e32 v4, vcc, 0x2000, v0
	v_mov_b32_e32 v0, s22
	s_nop 0
	v_addc_co_u32_e32 v5, vcc, 0, v0, vcc
	global_load_dword v0, v[4:5], off offset:1024 sc1
	s_add_u32 s4, s23, 0x2400
	s_addc_u32 s5, s22, 0
	s_waitcnt vmcnt(0) lgkmcnt(0)
	v_cmp_eq_u32_e32 vcc, v0, v3
	s_and_saveexec_b64 s[2:3], vcc
	s_cbranch_execz .LBB0_185
	s_mov_b32 s24, 1
	s_mov_b64 s[6:7], 0
	s_branch .LBB0_177

.LBB0_177:
	s_and_b32 s14, s24, 0xff
	s_mov_b64 s[12:13], -1
	s_cmp_lg_u32 s14, 0
	s_mov_b64 s[14:15], -1
	s_sleep 1
	s_cbranch_scc1 .LBB0_181
	v_mov_b64_e32 v[4:5], s[38:39]
	global_load_dword v0, v[4:5], off offset:512 sc1
	s_mov_b64 s[14:15], 0
	s_mov_b64 s[18:19], -1
	s_waitcnt vmcnt(0) lgkmcnt(0)
	v_cmp_eq_u32_e32 vcc, 0, v0
	s_and_saveexec_b64 s[20:21], vcc
	s_cmp_lt_u32 s24, 0x40001
	s_cselect_b64 s[14:15], -1, 0
	s_xor_b64 s[18:19], exec, -1
	s_and_b64 s[14:15], s[14:15], exec
	s_or_b64 exec, exec, s[20:21]
.LBB0_181:
	s_andn2_b64 s[10:11], s[10:11], exec
	s_and_b64 s[18:19], s[18:19], exec
	s_or_b64 s[10:11], s[10:11], s[18:19]
	s_and_saveexec_b64 s[18:19], s[14:15]
	s_cbranch_execz .LBB0_176
	v_mov_b64_e32 v[4:5], s[4:5]
	global_load_dword v0, v[4:5], off sc1
	s_add_i32 s24, s24, 1
	s_or_b64 s[10:11], s[10:11], exec
	s_waitcnt vmcnt(0) lgkmcnt(0)
	v_cmp_ne_u32_e32 vcc, v0, v3
	s_orn2_b64 s[12:13], vcc, exec
	s_branch .LBB0_176
.LBB0_183:
	s_or_b64 exec, exec, s[6:7]
	s_xor_b64 s[4:5], s[8:9], -1
	s_and_saveexec_b64 s[6:7], s[4:5]
	s_xor_b64 s[6:7], exec, s[6:7]
	s_cbranch_execz .LBB0_185
	v_mov_b64_e32 v[2:3], s[38:39]
	global_atomic_add v[2:3], v203, off offset:512

.LBB0_186:
	s_andn2_saveexec_b64 s[0:1], s[0:1]
	s_cbranch_execz .LBB0_202
	v_mov_b32_e32 v2, s38
	v_add_co_u32_e32 v2, vcc, 0x3000, v2
	v_mov_b32_e32 v3, s39
	buffer_wbl2 sc1
	s_waitcnt vmcnt(0)
	v_addc_co_u32_e32 v3, vcc, 0, v3, vcc
	global_atomic_add v2, v[2:3], v203, off offset:1024 sc0
	v_cvt_f32_u32_e32 v3, v0
	v_sub_u32_e32 v4, 0, v0
	s_add_u32 s0, s38, 0x3500
	s_addc_u32 s1, s39, 0
	v_rcp_iflag_f32_e32 v3, v3
	s_mov_b64 s[4:5], -1
	v_mul_f32_e32 v3, 0x4f7ffffe, v3
	v_cvt_u32_f32_e32 v3, v3
	v_mul_lo_u32 v4, v4, v3
	v_mul_hi_u32 v4, v3, v4
	v_add_u32_e32 v3, v3, v4
	s_waitcnt vmcnt(0) lgkmcnt(0)
	v_mul_hi_u32 v3, v2, v3
	v_mul_lo_u32 v4, v3, v0
	v_add_u32_e32 v5, 1, v2
	v_sub_u32_e32 v2, v2, v4
	v_add_u32_e32 v6, 1, v3
	v_cmp_ge_u32_e32 vcc, v2, v0
	v_sub_u32_e32 v4, v2, v0
	s_nop 0
	v_cndmask_b32_e32 v3, v3, v6, vcc
	v_cndmask_b32_e32 v2, v2, v4, vcc
	v_add_u32_e32 v4, 1, v3
	v_cmp_ge_u32_e32 vcc, v2, v0
	s_nop 1
	v_cndmask_b32_e32 v4, v3, v4, vcc
	v_mad_u64_u32 v[2:3], s[2:3], v0, v4, v[0:1]
	v_cmp_ne_u32_e32 vcc, v5, v2
	v_mov_b64_e32 v[2:3], s[0:1]
	s_and_saveexec_b64 s[2:3], vcc
	s_cbranch_execz .LBB0_199
	v_mov_b64_e32 v[2:3], s[0:1]
	global_load_dword v0, v[2:3], off sc1
	s_mov_b64 s[8:9], 0
	s_waitcnt vmcnt(0) lgkmcnt(0)
	v_cmp_eq_u32_e32 vcc, v0, v4
	s_and_saveexec_b64 s[6:7], vcc
	s_cbranch_execz .LBB0_198
	s_add_u32 s4, s38, 0x200
	s_addc_u32 s5, s39, 0
	s_mov_b32 s24, 1
	s_branch .LBB0_191

.LBB0_193:
	v_mov_b64_e32 v[2:3], s[4:5]
	global_load_dword v0, v[2:3], off sc1
	s_mov_b64 s[18:19], 0
	s_mov_b64 s[14:15], -1
	s_waitcnt vmcnt(0) lgkmcnt(0)
	v_cmp_eq_u32_e32 vcc, 0, v0
	s_and_saveexec_b64 s[20:21], vcc
	s_cmp_lt_u32 s24, 0x40001
	s_cselect_b64 s[18:19], -1, 0
	s_xor_b64 s[14:15], exec, -1
	s_and_b64 s[18:19], s[18:19], exec
	s_or_b64 exec, exec, s[20:21]
	s_and_saveexec_b64 s[20:21], s[18:19]
	s_cbranch_execz .LBB0_190
.LBB0_196:
	v_mov_b64_e32 v[2:3], s[0:1]
	global_load_dword v0, v[2:3], off sc1
	s_add_i32 s24, s24, 1
	s_or_b64 s[14:15], s[14:15], exec
	s_waitcnt vmcnt(0) lgkmcnt(0)
	v_cmp_ne_u32_e32 vcc, v0, v4
	s_orn2_b64 s[12:13], vcc, exec
	s_branch .LBB0_190

.LBB0_199:
	s_or_b64 exec, exec, s[2:3]
	s_and_saveexec_b64 s[0:1], s[4:5]
	s_cbranch_execz .LBB0_201
	global_atomic_add v[2:3], v203, off

.LBB0_220:
	s_andn2_saveexec_b64 s[8:9], s[8:9]
	v_add_u32_e32 v2, s22, v200
	v_ashrrev_i32_e32 v3, 31, v2
	v_lshl_add_u64 v[2:3], v[2:3], 2, s[18:19]
	s_or_b64 exec, exec, s[8:9]
	global_load_dword v0, v[2:3], off
	s_lshl_b32 s9, s71, 12
	s_ashr_i32 s25, s24, 31
	s_and_b32 s9, s9, 0x1000
	s_lshl_b64 s[10:11], s[24:25], 11
	s_add_i32 s25, s9, 0x400
	s_add_i32 s8, s24, 0x80
	s_add_i32 s25, s25, 0x20000
	s_add_u32 s44, s58, s10
	s_addc_u32 s45, s59, s11
	s_ashr_i32 s23, s22, 31
	s_lshl_b64 s[28:29], s[22:23], 11
	s_add_u32 s14, s37, s28
	v_add_u32_e32 v236, s33, v202
	s_addc_u32 s15, s56, s29
	s_ashr_i32 s9, s8, 31
	v_readfirstlane_b32 s40, v236
	v_add_u32_e32 v239, 0x2000, v236
	s_lshl_b64 s[30:31], s[8:9], 11
	v_add_u32_e32 v237, 0x400, v202
	v_readfirstlane_b32 s43, v239
	v_lshl_add_u32 v18, v200, 2, s25
	v_lshl_add_u64 v[2:3], s[44:45], 0, v[196:197]
	s_add_u32 s8, s58, s30
	s_mov_b32 m0, s40
	v_readfirstlane_b32 s41, v237
	v_add_u32_e32 v240, 0x2000, v237
	v_lshl_add_u64 v[4:5], s[44:45], 0, v[198:199]
	s_addc_u32 s9, s59, s31
	s_add_i32 s26, s22, 0x80
	v_add_u32_e32 v238, s52, v202
	v_readfirstlane_b32 s54, v240
	v_lshl_add_u64 v[6:7], s[14:15], 0, v[196:197]
	s_ashr_i32 s27, s26, 31
	v_readfirstlane_b32 s42, v238
	v_add_u32_e32 v241, 0x2000, v238
	v_lshl_add_u64 v[8:9], s[14:15], 0, v[198:199]
	s_lshl_b64 s[38:39], s[26:27], 11
	v_add_u32_e32 v242, 0x4000, v237
	v_readfirstlane_b32 s55, v241
	v_lshl_add_u64 v[10:11], s[8:9], 0, v[196:197]
	s_add_u32 s12, s37, s38
	v_add_u32_e32 v243, 0x6000, v237
	v_readfirstlane_b32 s72, v242
	v_lshl_add_u64 v[12:13], s[8:9], 0, v[198:199]
	s_addc_u32 s13, s56, s39
	v_readfirstlane_b32 s73, v243
	v_lshl_add_u64 v[14:15], s[12:13], 0, v[196:197]
	v_lshl_add_u64 v[16:17], s[12:13], 0, v[198:199]
	s_waitcnt vmcnt(0) lgkmcnt(0)
	ds_write_b32 v18, v0
	s_waitcnt lgkmcnt(0)
	s_barrier
	global_load_lds_dwordx4 v[2:3], off
	s_mov_b32 m0, s43
	s_nop 0
	global_load_lds_dwordx4 v[4:5], off
	s_mov_b32 m0, s41
	s_nop 0
	global_load_lds_dwordx4 v[6:7], off
	s_mov_b32 m0, s54
	s_nop 0
	global_load_lds_dwordx4 v[8:9], off
	s_mov_b32 m0, s42
	s_nop 0
	global_load_lds_dwordx4 v[10:11], off
	s_mov_b32 m0, s55
	s_nop 0
	global_load_lds_dwordx4 v[12:13], off
	s_mov_b32 m0, s72
	s_nop 0
	global_load_lds_dwordx4 v[14:15], off
	s_mov_b32 m0, s73
	s_nop 0
	global_load_lds_dwordx4 v[16:17], off
	s_and_saveexec_b64 s[40:41], s[2:3]
	s_cbranch_execz .LBB0_224
	s_barrier

.LBB0_252:
	s_or_b64 exec, exec, s[6:7]
	s_waitcnt lgkmcnt(0)
	v_lshl_add_u32 v139, v204, 2, s25
	ds_read_b32 v0, v139
	v_add_u32_e32 v2, s22, v204
	v_ashrrev_i32_e32 v3, 31, v2
	v_mov_b64_e32 v[132:133], s[20:21]
	v_lshl_add_u32 v138, v205, 2, s25
	v_mad_i64_i32 v[132:133], s[6:7], v2, s83, v[132:133]
	v_lshlrev_b64 v[2:3], 9, v[2:3]
	ds_read_b128 v[140:143], v138 offset:1024
	s_waitcnt lgkmcnt(0)
	v_fmamk_f32 v0, v0, 0x3a800000, v206
	v_lshl_add_u64 v[134:135], s[16:17], 0, v[2:3]
	v_cmp_gt_f32_e32 vcc, s35, v0
	v_mul_f32_e32 v2, 0x4b800000, v0
	s_nop 0
	v_cndmask_b32_e32 v0, v0, v2, vcc
	v_rsq_f32_e32 v0, v0
	s_nop 0
	v_mul_f32_e32 v2, 0x45800000, v0
	v_cndmask_b32_e32 v136, v0, v2, vcc
	v_add_u32_e32 v2, s24, v205
	v_pk_fma_f32 v[128:129], v[128:129], v[136:137], v[140:141] op_sel_hi:[1,0,1]
	v_pk_fma_f32 v[130:131], v[130:131], v[136:137], v[142:143] op_sel_hi:[1,0,1]
	v_cvt_pk_bf16_f32 v128, v128, v129
	v_cvt_pk_bf16_f32 v129, v130, v131
	v_cmp_lt_i32_e64 s[6:7], s95, v2
	s_and_saveexec_b64 s[8:9], s[6:7]
	s_xor_b64 s[8:9], exec, s[8:9]
	s_cbranch_execz .LBB0_260
	v_cmp_lt_u32_e32 vcc, s60, v2
	s_and_saveexec_b64 s[10:11], vcc
	s_xor_b64 s[10:11], exec, s[10:11]
	s_cbranch_execz .LBB0_257
	v_cmp_gt_u32_e32 vcc, s23, v2
	s_and_saveexec_b64 s[12:13], vcc
	s_cbranch_execz .LBB0_256
	v_mov_b32_e32 v3, v1
	v_lshl_add_u64 v[130:131], v[2:3], 1, v[132:133]
	v_add_co_u32_e32 v130, vcc, 0xfffffe00, v130
	s_nop 1
	v_addc_co_u32_e32 v131, vcc, -1, v131, vcc
	s_waitcnt vmcnt(0)
	global_store_dwordx2 v[130:131], v[128:129], off

.LBB0_257:
	s_andn2_saveexec_b64 s[10:11], s[10:11]
	s_cbranch_execz .LBB0_259
	v_mov_b32_e32 v3, v1
	v_lshl_add_u64 v[130:131], v[2:3], 1, v[134:135]
	v_add_co_u32_e32 v130, vcc, 0xd78f000, v130
	s_nop 1
	v_addc_co_u32_e32 v131, vcc, 0, v131, vcc
	s_waitcnt vmcnt(0)
	global_store_dwordx2 v[130:131], v[128:129], off offset:2560

.LBB0_260:
	s_or_saveexec_b64 s[8:9], s[8:9]
	v_ashrrev_i32_e32 v3, 31, v2
	s_xor_b64 exec, exec, s[8:9]
	s_cbranch_execz .LBB0_262
	v_lshl_add_u64 v[130:131], v[2:3], 1, v[132:133]
	s_waitcnt vmcnt(0)
	global_store_dwordx2 v[130:131], v[128:129], off
.LBB0_262:
	s_or_b64 exec, exec, s[8:9]
	ds_read_b128 v[128:131], v138 offset:1088
	v_mov_b32_e32 v137, v136
	v_or_b32_e32 v0, 16, v205
	v_add_u32_e32 v0, s24, v0
	v_cmp_lt_i32_e64 s[10:11], s95, v0
	s_waitcnt lgkmcnt(0)
	v_pk_fma_f32 v[124:125], v[124:125], v[136:137], v[128:129]
	v_pk_fma_f32 v[126:127], v[126:127], v[136:137], v[130:131]
	v_cvt_pk_bf16_f32 v124, v124, v125
	v_cvt_pk_bf16_f32 v125, v126, v127
	s_and_saveexec_b64 s[8:9], s[10:11]
	s_xor_b64 s[8:9], exec, s[8:9]
	s_cbranch_execz .LBB0_270
	v_cmp_lt_u32_e32 vcc, s60, v0
	s_and_saveexec_b64 s[12:13], vcc
	s_xor_b64 s[12:13], exec, s[12:13]
	s_cbranch_execz .LBB0_267
	v_cmp_gt_u32_e32 vcc, s23, v0
	s_and_saveexec_b64 s[28:29], vcc
	s_cbranch_execz .LBB0_266
	v_lshl_add_u64 v[126:127], v[0:1], 1, v[132:133]
	v_add_co_u32_e32 v126, vcc, 0xfffffe00, v126
	s_nop 1
	v_addc_co_u32_e32 v127, vcc, -1, v127, vcc
	s_waitcnt vmcnt(0)
	global_store_dwordx2 v[126:127], v[124:125], off

.LBB0_267:
	s_andn2_saveexec_b64 s[12:13], s[12:13]
	s_cbranch_execz .LBB0_269
	v_lshl_add_u64 v[126:127], v[0:1], 1, v[134:135]
	v_add_co_u32_e32 v126, vcc, 0xd78f000, v126
	s_nop 1
	v_addc_co_u32_e32 v127, vcc, 0, v127, vcc
	s_waitcnt vmcnt(0)
	global_store_dwordx2 v[126:127], v[124:125], off offset:2560

.LBB0_270:
	s_andn2_saveexec_b64 s[8:9], s[8:9]
	s_cbranch_execz .LBB0_272
	v_lshl_add_u64 v[126:127], v[2:3], 1, v[132:133]
	s_waitcnt vmcnt(0)
	global_store_dwordx2 v[126:127], v[124:125], off offset:32
.LBB0_272:
	s_or_b64 exec, exec, s[8:9]
	ds_read_b128 v[126:129], v138 offset:1536
	v_or_b32_e32 v124, 0x80, v205
	v_add_u32_e32 v124, s24, v124
	v_cmp_lt_i32_e64 s[12:13], s95, v124
	s_waitcnt lgkmcnt(0)
	v_pk_fma_f32 v[104:105], v[104:105], v[136:137], v[126:127]
	v_pk_fma_f32 v[106:107], v[106:107], v[136:137], v[128:129]
	v_cvt_pk_bf16_f32 v104, v104, v105
	v_cvt_pk_bf16_f32 v105, v106, v107
	s_and_saveexec_b64 s[8:9], s[12:13]
	s_xor_b64 s[8:9], exec, s[8:9]
	s_cbranch_execz .LBB0_280
	v_cmp_lt_u32_e32 vcc, s60, v124
	s_and_saveexec_b64 s[28:29], vcc
	s_xor_b64 s[28:29], exec, s[28:29]
	s_cbranch_execz .LBB0_277
	v_cmp_gt_u32_e32 vcc, s23, v124
	s_and_saveexec_b64 s[30:31], vcc
	s_cbranch_execz .LBB0_276
	v_mov_b32_e32 v125, v1
	v_lshl_add_u64 v[106:107], v[124:125], 1, v[132:133]
	v_add_co_u32_e32 v106, vcc, 0xfffffe00, v106
	s_nop 1
	v_addc_co_u32_e32 v107, vcc, -1, v107, vcc
	s_waitcnt vmcnt(0)
	global_store_dwordx2 v[106:107], v[104:105], off

.LBB0_277:
	s_andn2_saveexec_b64 s[28:29], s[28:29]
	s_cbranch_execz .LBB0_279
	v_mov_b32_e32 v125, v1
	v_lshl_add_u64 v[106:107], v[124:125], 1, v[134:135]
	v_add_co_u32_e32 v106, vcc, 0xd78f000, v106
	s_nop 1
	v_addc_co_u32_e32 v107, vcc, 0, v107, vcc
	s_waitcnt vmcnt(0)
	global_store_dwordx2 v[106:107], v[104:105], off offset:2560

.LBB0_280:
	s_andn2_saveexec_b64 s[8:9], s[8:9]
	s_cbranch_execz .LBB0_282
	v_lshl_add_u64 v[106:107], v[2:3], 1, v[132:133]
	s_waitcnt vmcnt(0)
	global_store_dwordx2 v[106:107], v[104:105], off offset:256
.LBB0_282:
	s_or_b64 exec, exec, s[8:9]
	ds_read_b128 v[126:129], v138 offset:1600
	v_or_b32_e32 v104, 0x90, v205
	v_add_u32_e32 v104, s24, v104
	v_cmp_lt_i32_e64 s[8:9], s95, v104
	s_waitcnt lgkmcnt(0)
	v_pk_fma_f32 v[100:101], v[100:101], v[136:137], v[126:127]
	v_pk_fma_f32 v[102:103], v[102:103], v[136:137], v[128:129]
	v_cvt_pk_bf16_f32 v100, v100, v101
	v_cvt_pk_bf16_f32 v101, v102, v103
	s_and_saveexec_b64 s[28:29], s[8:9]
	s_xor_b64 s[28:29], exec, s[28:29]
	s_cbranch_execz .LBB0_290
	v_cmp_lt_u32_e32 vcc, s60, v104
	s_and_saveexec_b64 s[30:31], vcc
	s_xor_b64 s[30:31], exec, s[30:31]
	s_cbranch_execz .LBB0_287
	v_cmp_gt_u32_e32 vcc, s23, v104
	s_and_saveexec_b64 s[38:39], vcc
	s_cbranch_execz .LBB0_286
	v_mov_b32_e32 v105, v1
	v_lshl_add_u64 v[102:103], v[104:105], 1, v[132:133]
	v_add_co_u32_e32 v102, vcc, 0xfffffe00, v102
	s_nop 1
	v_addc_co_u32_e32 v103, vcc, -1, v103, vcc
	s_waitcnt vmcnt(0)
	global_store_dwordx2 v[102:103], v[100:101], off

.LBB0_287:
	s_andn2_saveexec_b64 s[30:31], s[30:31]
	s_cbranch_execz .LBB0_289
	v_mov_b32_e32 v105, v1
	v_lshl_add_u64 v[102:103], v[104:105], 1, v[134:135]
	v_add_co_u32_e32 v102, vcc, 0xd78f000, v102
	s_nop 1
	v_addc_co_u32_e32 v103, vcc, 0, v103, vcc
	s_waitcnt vmcnt(0)
	global_store_dwordx2 v[102:103], v[100:101], off offset:2560

.LBB0_290:
	s_andn2_saveexec_b64 s[28:29], s[28:29]
	s_cbranch_execz .LBB0_292
	v_lshl_add_u64 v[102:103], v[2:3], 1, v[132:133]
	s_waitcnt vmcnt(0)
	global_store_dwordx2 v[102:103], v[100:101], off offset:288
.LBB0_292:
	s_or_b64 exec, exec, s[28:29]
	ds_read_b32 v105, v139 offset:64
	ds_read_b128 v[126:129], v138 offset:1024
	v_or_b32_e32 v100, 16, v204
	v_add_u32_e32 v102, s22, v100
	v_ashrrev_i32_e32 v103, 31, v102
	s_waitcnt lgkmcnt(0)
	v_fmamk_f32 v105, v105, 0x3a800000, v206
	v_cmp_gt_f32_e32 vcc, s35, v105
	v_mul_f32_e32 v106, 0x4b800000, v105
	v_mov_b64_e32 v[100:101], s[20:21]
	v_cndmask_b32_e32 v105, v105, v106, vcc
	v_rsq_f32_e32 v105, v105
	v_mad_i64_i32 v[100:101], s[28:29], v102, s83, v[100:101]
	v_lshlrev_b64 v[102:103], 9, v[102:103]
	v_mul_f32_e32 v106, 0x45800000, v105
	v_cndmask_b32_e32 v106, v105, v106, vcc
	v_pk_fma_f32 v[120:121], v[120:121], v[106:107], v[126:127] op_sel_hi:[1,0,1]
	v_pk_fma_f32 v[122:123], v[122:123], v[106:107], v[128:129] op_sel_hi:[1,0,1]
	v_lshl_add_u64 v[102:103], s[16:17], 0, v[102:103]
	v_cvt_pk_bf16_f32 v120, v120, v121
	v_cvt_pk_bf16_f32 v121, v122, v123
	s_and_saveexec_b64 s[28:29], s[6:7]
	s_xor_b64 s[28:29], exec, s[28:29]
	s_cbranch_execz .LBB0_300
	v_cmp_lt_u32_e32 vcc, s60, v2
	s_and_saveexec_b64 s[30:31], vcc
	s_xor_b64 s[30:31], exec, s[30:31]
	s_cbranch_execz .LBB0_297
	v_cmp_gt_u32_e32 vcc, s23, v2
	s_and_saveexec_b64 s[38:39], vcc
	s_cbranch_execz .LBB0_296
	v_mov_b32_e32 v122, v2
	v_mov_b32_e32 v123, v1
	v_lshl_add_u64 v[122:123], v[122:123], 1, v[100:101]
	v_add_co_u32_e32 v122, vcc, 0xfffffe00, v122
	s_nop 1
	v_addc_co_u32_e32 v123, vcc, -1, v123, vcc
	s_waitcnt vmcnt(0)
	global_store_dwordx2 v[122:123], v[120:121], off

.LBB0_297:
	s_andn2_saveexec_b64 s[30:31], s[30:31]
	s_cbranch_execz .LBB0_299
	v_mov_b32_e32 v122, v2
	v_mov_b32_e32 v123, v1
	v_lshl_add_u64 v[122:123], v[122:123], 1, v[102:103]
	v_add_co_u32_e32 v122, vcc, 0xd78f000, v122
	s_nop 1
	v_addc_co_u32_e32 v123, vcc, 0, v123, vcc
	s_waitcnt vmcnt(0)
	global_store_dwordx2 v[122:123], v[120:121], off offset:2560

.LBB0_300:
	s_andn2_saveexec_b64 s[28:29], s[28:29]
	s_cbranch_execz .LBB0_302
	v_lshl_add_u64 v[122:123], v[2:3], 1, v[100:101]
	s_waitcnt vmcnt(0)
	global_store_dwordx2 v[122:123], v[120:121], off
.LBB0_302:
	s_or_b64 exec, exec, s[28:29]
	ds_read_b128 v[120:123], v138 offset:1088
	v_mov_b32_e32 v107, v106
	s_waitcnt lgkmcnt(0)
	v_pk_fma_f32 v[116:117], v[116:117], v[106:107], v[120:121]
	v_pk_fma_f32 v[118:119], v[118:119], v[106:107], v[122:123]
	v_cvt_pk_bf16_f32 v116, v116, v117
	v_cvt_pk_bf16_f32 v117, v118, v119
	s_and_saveexec_b64 s[28:29], s[10:11]
	s_xor_b64 s[28:29], exec, s[28:29]
	s_cbranch_execz .LBB0_310
	v_cmp_lt_u32_e32 vcc, s60, v0
	s_and_saveexec_b64 s[30:31], vcc
	s_xor_b64 s[30:31], exec, s[30:31]
	s_cbranch_execz .LBB0_307
	v_cmp_gt_u32_e32 vcc, s23, v0
	s_and_saveexec_b64 s[38:39], vcc
	s_cbranch_execz .LBB0_306
	v_lshl_add_u64 v[118:119], v[0:1], 1, v[100:101]
	v_add_co_u32_e32 v118, vcc, 0xfffffe00, v118
	s_nop 1
	v_addc_co_u32_e32 v119, vcc, -1, v119, vcc
	s_waitcnt vmcnt(0)
	global_store_dwordx2 v[118:119], v[116:117], off

.LBB0_307:
	s_andn2_saveexec_b64 s[30:31], s[30:31]
	s_cbranch_execz .LBB0_309
	v_lshl_add_u64 v[118:119], v[0:1], 1, v[102:103]
	v_add_co_u32_e32 v118, vcc, 0xd78f000, v118
	s_nop 1
	v_addc_co_u32_e32 v119, vcc, 0, v119, vcc
	s_waitcnt vmcnt(0)
	global_store_dwordx2 v[118:119], v[116:117], off offset:2560

.LBB0_310:
	s_andn2_saveexec_b64 s[28:29], s[28:29]
	s_cbranch_execz .LBB0_312
	v_lshl_add_u64 v[118:119], v[2:3], 1, v[100:101]
	s_waitcnt vmcnt(0)
	global_store_dwordx2 v[118:119], v[116:117], off offset:32
.LBB0_312:
	s_or_b64 exec, exec, s[28:29]
	ds_read_b128 v[116:119], v138 offset:1536
	s_waitcnt lgkmcnt(0)
	v_pk_fma_f32 v[88:89], v[88:89], v[106:107], v[116:117]
	v_pk_fma_f32 v[90:91], v[90:91], v[106:107], v[118:119]
	v_cvt_pk_bf16_f32 v88, v88, v89
	v_cvt_pk_bf16_f32 v89, v90, v91
	s_and_saveexec_b64 s[28:29], s[12:13]
	s_xor_b64 s[28:29], exec, s[28:29]
	s_cbranch_execz .LBB0_320
	v_cmp_lt_u32_e32 vcc, s60, v124
	s_and_saveexec_b64 s[30:31], vcc
	s_xor_b64 s[30:31], exec, s[30:31]
	s_cbranch_execz .LBB0_317
	v_cmp_gt_u32_e32 vcc, s23, v124
	s_and_saveexec_b64 s[38:39], vcc
	s_cbranch_execz .LBB0_316
	v_mov_b32_e32 v125, v1
	v_lshl_add_u64 v[90:91], v[124:125], 1, v[100:101]
	v_add_co_u32_e32 v90, vcc, 0xfffffe00, v90
	s_nop 1
	v_addc_co_u32_e32 v91, vcc, -1, v91, vcc
	s_waitcnt vmcnt(0)
	global_store_dwordx2 v[90:91], v[88:89], off

.LBB0_317:
	s_andn2_saveexec_b64 s[30:31], s[30:31]
	s_cbranch_execz .LBB0_319
	v_mov_b32_e32 v125, v1
	v_lshl_add_u64 v[90:91], v[124:125], 1, v[102:103]
	v_add_co_u32_e32 v90, vcc, 0xd78f000, v90
	s_nop 1
	v_addc_co_u32_e32 v91, vcc, 0, v91, vcc
	s_waitcnt vmcnt(0)
	global_store_dwordx2 v[90:91], v[88:89], off offset:2560

.LBB0_320:
	s_andn2_saveexec_b64 s[28:29], s[28:29]
	s_cbranch_execz .LBB0_322
	v_lshl_add_u64 v[90:91], v[2:3], 1, v[100:101]
	s_waitcnt vmcnt(0)
	global_store_dwordx2 v[90:91], v[88:89], off offset:256
.LBB0_322:
	s_or_b64 exec, exec, s[28:29]
	ds_read_b128 v[88:91], v138 offset:1600
	s_waitcnt lgkmcnt(0)
	v_pk_fma_f32 v[84:85], v[84:85], v[106:107], v[88:89]
	v_pk_fma_f32 v[86:87], v[86:87], v[106:107], v[90:91]
	v_cvt_pk_bf16_f32 v84, v84, v85
	v_cvt_pk_bf16_f32 v85, v86, v87
	s_and_saveexec_b64 s[28:29], s[8:9]
	s_xor_b64 s[28:29], exec, s[28:29]
	s_cbranch_execz .LBB0_330
	v_cmp_lt_u32_e32 vcc, s60, v104
	s_and_saveexec_b64 s[30:31], vcc
	s_xor_b64 s[30:31], exec, s[30:31]
	s_cbranch_execz .LBB0_327
	v_cmp_gt_u32_e32 vcc, s23, v104
	s_and_saveexec_b64 s[38:39], vcc
	s_cbranch_execz .LBB0_326
	v_mov_b32_e32 v105, v1
	v_lshl_add_u64 v[86:87], v[104:105], 1, v[100:101]
	v_add_co_u32_e32 v86, vcc, 0xfffffe00, v86
	s_nop 1
	v_addc_co_u32_e32 v87, vcc, -1, v87, vcc
	s_waitcnt vmcnt(0)
	global_store_dwordx2 v[86:87], v[84:85], off

.LBB0_327:
	s_andn2_saveexec_b64 s[30:31], s[30:31]
	s_cbranch_execz .LBB0_329
	v_mov_b32_e32 v105, v1
	v_lshl_add_u64 v[86:87], v[104:105], 1, v[102:103]
	v_add_co_u32_e32 v86, vcc, 0xd78f000, v86
	s_nop 1
	v_addc_co_u32_e32 v87, vcc, 0, v87, vcc
	s_waitcnt vmcnt(0)
	global_store_dwordx2 v[86:87], v[84:85], off offset:2560

.LBB0_330:
	s_andn2_saveexec_b64 s[28:29], s[28:29]
	s_cbranch_execz .LBB0_332
	v_lshl_add_u64 v[86:87], v[2:3], 1, v[100:101]
	s_waitcnt vmcnt(0)
	global_store_dwordx2 v[86:87], v[84:85], off offset:288
.LBB0_332:
	s_or_b64 exec, exec, s[28:29]
	ds_read_b32 v88, v139 offset:128
	ds_read_b128 v[100:103], v138 offset:1024
	v_or_b32_e32 v84, 32, v204
	v_add_u32_e32 v86, s22, v84
	v_ashrrev_i32_e32 v87, 31, v86
	s_waitcnt lgkmcnt(0)
	v_fmamk_f32 v88, v88, 0x3a800000, v206
	v_cmp_gt_f32_e32 vcc, s35, v88
	v_mul_f32_e32 v89, 0x4b800000, v88
	v_mov_b64_e32 v[84:85], s[20:21]
	v_cndmask_b32_e32 v88, v88, v89, vcc
	v_rsq_f32_e32 v88, v88
	v_mad_i64_i32 v[84:85], s[28:29], v86, s83, v[84:85]
	v_lshlrev_b64 v[86:87], 9, v[86:87]
	v_mul_f32_e32 v89, 0x45800000, v88
	v_cndmask_b32_e32 v88, v88, v89, vcc
	v_pk_fma_f32 v[90:91], v[112:113], v[88:89], v[100:101] op_sel_hi:[1,0,1]
	v_pk_fma_f32 v[100:101], v[114:115], v[88:89], v[102:103] op_sel_hi:[1,0,1]
	v_lshl_add_u64 v[86:87], s[16:17], 0, v[86:87]
	v_cvt_pk_bf16_f32 v90, v90, v91
	v_cvt_pk_bf16_f32 v91, v100, v101
	s_and_saveexec_b64 s[28:29], s[6:7]
	s_xor_b64 s[28:29], exec, s[28:29]
	s_cbranch_execz .LBB0_340
	v_cmp_lt_u32_e32 vcc, s60, v2
	s_and_saveexec_b64 s[30:31], vcc
	s_xor_b64 s[30:31], exec, s[30:31]
	s_cbranch_execz .LBB0_337
	v_cmp_gt_u32_e32 vcc, s23, v2
	s_and_saveexec_b64 s[38:39], vcc
	s_cbranch_execz .LBB0_336
	v_mov_b32_e32 v100, v2
	v_mov_b32_e32 v101, v1
	v_lshl_add_u64 v[100:101], v[100:101], 1, v[84:85]
	v_add_co_u32_e32 v100, vcc, 0xfffffe00, v100
	s_nop 1
	v_addc_co_u32_e32 v101, vcc, -1, v101, vcc
	s_waitcnt vmcnt(0)
	global_store_dwordx2 v[100:101], v[90:91], off

.LBB0_337:
	s_andn2_saveexec_b64 s[30:31], s[30:31]
	s_cbranch_execz .LBB0_339
	v_mov_b32_e32 v100, v2
	v_mov_b32_e32 v101, v1
	v_lshl_add_u64 v[100:101], v[100:101], 1, v[86:87]
	v_add_co_u32_e32 v100, vcc, 0xd78f000, v100
	s_nop 1
	v_addc_co_u32_e32 v101, vcc, 0, v101, vcc
	s_waitcnt vmcnt(0)
	global_store_dwordx2 v[100:101], v[90:91], off offset:2560

.LBB0_340:
	s_andn2_saveexec_b64 s[28:29], s[28:29]
	s_cbranch_execz .LBB0_342
	v_lshl_add_u64 v[100:101], v[2:3], 1, v[84:85]
	s_waitcnt vmcnt(0)
	global_store_dwordx2 v[100:101], v[90:91], off
.LBB0_342:
	s_or_b64 exec, exec, s[28:29]
	ds_read_b128 v[100:103], v138 offset:1088
	v_mov_b32_e32 v89, v88
	s_waitcnt lgkmcnt(0)
	v_pk_fma_f32 v[90:91], v[108:109], v[88:89], v[100:101]
	v_pk_fma_f32 v[100:101], v[110:111], v[88:89], v[102:103]
	v_cvt_pk_bf16_f32 v90, v90, v91
	v_cvt_pk_bf16_f32 v91, v100, v101
	s_and_saveexec_b64 s[28:29], s[10:11]
	s_xor_b64 s[28:29], exec, s[28:29]
	s_cbranch_execz .LBB0_350
	v_cmp_lt_u32_e32 vcc, s60, v0
	s_and_saveexec_b64 s[30:31], vcc
	s_xor_b64 s[30:31], exec, s[30:31]
	s_cbranch_execz .LBB0_347
	v_cmp_gt_u32_e32 vcc, s23, v0
	s_and_saveexec_b64 s[38:39], vcc
	s_cbranch_execz .LBB0_346
	v_lshl_add_u64 v[100:101], v[0:1], 1, v[84:85]
	v_add_co_u32_e32 v100, vcc, 0xfffffe00, v100
	s_nop 1
	v_addc_co_u32_e32 v101, vcc, -1, v101, vcc
	s_waitcnt vmcnt(0)
	global_store_dwordx2 v[100:101], v[90:91], off

.LBB0_347:
	s_andn2_saveexec_b64 s[30:31], s[30:31]
	s_cbranch_execz .LBB0_349
	v_lshl_add_u64 v[100:101], v[0:1], 1, v[86:87]
	v_add_co_u32_e32 v100, vcc, 0xd78f000, v100
	s_nop 1
	v_addc_co_u32_e32 v101, vcc, 0, v101, vcc
	s_waitcnt vmcnt(0)
	global_store_dwordx2 v[100:101], v[90:91], off offset:2560

.LBB0_350:
	s_andn2_saveexec_b64 s[28:29], s[28:29]
	s_cbranch_execz .LBB0_352
	v_lshl_add_u64 v[100:101], v[2:3], 1, v[84:85]
	s_waitcnt vmcnt(0)
	global_store_dwordx2 v[100:101], v[90:91], off offset:32
.LBB0_352:
	s_or_b64 exec, exec, s[28:29]
	ds_read_b128 v[100:103], v138 offset:1536
	s_waitcnt lgkmcnt(0)
	v_pk_fma_f32 v[80:81], v[80:81], v[88:89], v[100:101]
	v_pk_fma_f32 v[82:83], v[82:83], v[88:89], v[102:103]
	v_cvt_pk_bf16_f32 v80, v80, v81
	v_cvt_pk_bf16_f32 v81, v82, v83
	s_and_saveexec_b64 s[28:29], s[12:13]
	s_xor_b64 s[28:29], exec, s[28:29]
	s_cbranch_execz .LBB0_360
	v_cmp_lt_u32_e32 vcc, s60, v124
	s_and_saveexec_b64 s[30:31], vcc
	s_xor_b64 s[30:31], exec, s[30:31]
	s_cbranch_execz .LBB0_357
	v_cmp_gt_u32_e32 vcc, s23, v124
	s_and_saveexec_b64 s[38:39], vcc
	s_cbranch_execz .LBB0_356
	v_mov_b32_e32 v125, v1
	v_lshl_add_u64 v[82:83], v[124:125], 1, v[84:85]
	v_add_co_u32_e32 v82, vcc, 0xfffffe00, v82
	s_nop 1
	v_addc_co_u32_e32 v83, vcc, -1, v83, vcc
	s_waitcnt vmcnt(0)
	global_store_dwordx2 v[82:83], v[80:81], off

.LBB0_357:
	s_andn2_saveexec_b64 s[30:31], s[30:31]
	s_cbranch_execz .LBB0_359
	v_mov_b32_e32 v125, v1
	v_lshl_add_u64 v[82:83], v[124:125], 1, v[86:87]
	v_add_co_u32_e32 v82, vcc, 0xd78f000, v82
	s_nop 1
	v_addc_co_u32_e32 v83, vcc, 0, v83, vcc
	s_waitcnt vmcnt(0)
	global_store_dwordx2 v[82:83], v[80:81], off offset:2560

.LBB0_360:
	s_andn2_saveexec_b64 s[28:29], s[28:29]
	s_cbranch_execz .LBB0_362
	v_lshl_add_u64 v[82:83], v[2:3], 1, v[84:85]
	s_waitcnt vmcnt(0)
	global_store_dwordx2 v[82:83], v[80:81], off offset:256
.LBB0_362:
	s_or_b64 exec, exec, s[28:29]
	ds_read_b128 v[80:83], v138 offset:1600
	s_waitcnt lgkmcnt(0)
	v_pk_fma_f32 v[76:77], v[76:77], v[88:89], v[80:81]
	v_pk_fma_f32 v[78:79], v[78:79], v[88:89], v[82:83]
	v_cvt_pk_bf16_f32 v76, v76, v77
	v_cvt_pk_bf16_f32 v77, v78, v79
	s_and_saveexec_b64 s[28:29], s[8:9]
	s_xor_b64 s[28:29], exec, s[28:29]
	s_cbranch_execz .LBB0_370
	v_cmp_lt_u32_e32 vcc, s60, v104
	s_and_saveexec_b64 s[30:31], vcc
	s_xor_b64 s[30:31], exec, s[30:31]
	s_cbranch_execz .LBB0_367
	v_cmp_gt_u32_e32 vcc, s23, v104
	s_and_saveexec_b64 s[38:39], vcc
	s_cbranch_execz .LBB0_366
	v_mov_b32_e32 v105, v1
	v_lshl_add_u64 v[78:79], v[104:105], 1, v[84:85]
	v_add_co_u32_e32 v78, vcc, 0xfffffe00, v78
	s_nop 1
	v_addc_co_u32_e32 v79, vcc, -1, v79, vcc
	s_waitcnt vmcnt(0)
	global_store_dwordx2 v[78:79], v[76:77], off

.LBB0_367:
	s_andn2_saveexec_b64 s[30:31], s[30:31]
	s_cbranch_execz .LBB0_369
	v_mov_b32_e32 v105, v1
	v_lshl_add_u64 v[78:79], v[104:105], 1, v[86:87]
	v_add_co_u32_e32 v78, vcc, 0xd78f000, v78
	s_nop 1
	v_addc_co_u32_e32 v79, vcc, 0, v79, vcc
	s_waitcnt vmcnt(0)
	global_store_dwordx2 v[78:79], v[76:77], off offset:2560

.LBB0_370:
	s_andn2_saveexec_b64 s[28:29], s[28:29]
	s_cbranch_execz .LBB0_372
	v_lshl_add_u64 v[78:79], v[2:3], 1, v[84:85]
	s_waitcnt vmcnt(0)
	global_store_dwordx2 v[78:79], v[76:77], off offset:288
.LBB0_372:
	s_or_b64 exec, exec, s[28:29]
	ds_read_b32 v80, v139 offset:192
	ds_read_b128 v[82:85], v138 offset:1024
	v_or_b32_e32 v76, 48, v204
	v_add_u32_e32 v78, s22, v76
	v_ashrrev_i32_e32 v79, 31, v78
	s_waitcnt lgkmcnt(0)
	v_fmamk_f32 v80, v80, 0x3a800000, v206
	v_cmp_gt_f32_e32 vcc, s35, v80
	v_mul_f32_e32 v81, 0x4b800000, v80
	v_mov_b64_e32 v[76:77], s[20:21]
	v_cndmask_b32_e32 v80, v80, v81, vcc
	v_rsq_f32_e32 v80, v80
	v_mad_i64_i32 v[76:77], s[28:29], v78, s83, v[76:77]
	v_lshlrev_b64 v[78:79], 9, v[78:79]
	v_mul_f32_e32 v81, 0x45800000, v80
	v_cndmask_b32_e32 v80, v80, v81, vcc
	v_pk_fma_f32 v[82:83], v[96:97], v[80:81], v[82:83] op_sel_hi:[1,0,1]
	v_pk_fma_f32 v[84:85], v[98:99], v[80:81], v[84:85] op_sel_hi:[1,0,1]
	v_lshl_add_u64 v[78:79], s[16:17], 0, v[78:79]
	v_cvt_pk_bf16_f32 v82, v82, v83
	v_cvt_pk_bf16_f32 v83, v84, v85
	s_and_saveexec_b64 s[28:29], s[6:7]
	s_xor_b64 s[28:29], exec, s[28:29]
	s_cbranch_execz .LBB0_380
	v_cmp_lt_u32_e32 vcc, s60, v2
	s_and_saveexec_b64 s[30:31], vcc
	s_xor_b64 s[30:31], exec, s[30:31]
	s_cbranch_execz .LBB0_377
	v_cmp_gt_u32_e32 vcc, s23, v2
	s_and_saveexec_b64 s[38:39], vcc
	s_cbranch_execz .LBB0_376
	v_mov_b32_e32 v84, v2
	v_mov_b32_e32 v85, v1
	v_lshl_add_u64 v[84:85], v[84:85], 1, v[76:77]
	v_add_co_u32_e32 v84, vcc, 0xfffffe00, v84
	s_nop 1
	v_addc_co_u32_e32 v85, vcc, -1, v85, vcc
	s_waitcnt vmcnt(0)
	global_store_dwordx2 v[84:85], v[82:83], off

.LBB0_377:
	s_andn2_saveexec_b64 s[30:31], s[30:31]
	s_cbranch_execz .LBB0_379
	v_mov_b32_e32 v84, v2
	v_mov_b32_e32 v85, v1
	v_lshl_add_u64 v[84:85], v[84:85], 1, v[78:79]
	v_add_co_u32_e32 v84, vcc, 0xd78f000, v84
	s_nop 1
	v_addc_co_u32_e32 v85, vcc, 0, v85, vcc
	s_waitcnt vmcnt(0)
	global_store_dwordx2 v[84:85], v[82:83], off offset:2560

.LBB0_380:
	s_andn2_saveexec_b64 s[28:29], s[28:29]
	s_cbranch_execz .LBB0_382
	v_lshl_add_u64 v[84:85], v[2:3], 1, v[76:77]
	s_waitcnt vmcnt(0)
	global_store_dwordx2 v[84:85], v[82:83], off
.LBB0_382:
	s_or_b64 exec, exec, s[28:29]
	ds_read_b128 v[82:85], v138 offset:1088
	v_mov_b32_e32 v81, v80
	s_waitcnt lgkmcnt(0)
	v_pk_fma_f32 v[82:83], v[92:93], v[80:81], v[82:83]
	v_pk_fma_f32 v[84:85], v[94:95], v[80:81], v[84:85]
	v_cvt_pk_bf16_f32 v82, v82, v83
	v_cvt_pk_bf16_f32 v83, v84, v85
	s_and_saveexec_b64 s[28:29], s[10:11]
	s_xor_b64 s[28:29], exec, s[28:29]
	s_cbranch_execz .LBB0_390
	v_cmp_lt_u32_e32 vcc, s60, v0
	s_and_saveexec_b64 s[30:31], vcc
	s_xor_b64 s[30:31], exec, s[30:31]
	s_cbranch_execz .LBB0_387
	v_cmp_gt_u32_e32 vcc, s23, v0
	s_and_saveexec_b64 s[38:39], vcc
	s_cbranch_execz .LBB0_386
	v_lshl_add_u64 v[84:85], v[0:1], 1, v[76:77]
	v_add_co_u32_e32 v84, vcc, 0xfffffe00, v84
	s_nop 1
	v_addc_co_u32_e32 v85, vcc, -1, v85, vcc
	s_waitcnt vmcnt(0)
	global_store_dwordx2 v[84:85], v[82:83], off

.LBB0_387:
	s_andn2_saveexec_b64 s[30:31], s[30:31]
	s_cbranch_execz .LBB0_389
	v_lshl_add_u64 v[84:85], v[0:1], 1, v[78:79]
	v_add_co_u32_e32 v84, vcc, 0xd78f000, v84
	s_nop 1
	v_addc_co_u32_e32 v85, vcc, 0, v85, vcc
	s_waitcnt vmcnt(0)
	global_store_dwordx2 v[84:85], v[82:83], off offset:2560

.LBB0_390:
	s_andn2_saveexec_b64 s[28:29], s[28:29]
	s_cbranch_execz .LBB0_392
	v_lshl_add_u64 v[84:85], v[2:3], 1, v[76:77]
	s_waitcnt vmcnt(0)
	global_store_dwordx2 v[84:85], v[82:83], off offset:32
.LBB0_392:
	s_or_b64 exec, exec, s[28:29]
	ds_read_b128 v[82:85], v138 offset:1536
	s_waitcnt lgkmcnt(0)
	v_pk_fma_f32 v[72:73], v[72:73], v[80:81], v[82:83]
	v_pk_fma_f32 v[74:75], v[74:75], v[80:81], v[84:85]
	v_cvt_pk_bf16_f32 v72, v72, v73
	v_cvt_pk_bf16_f32 v73, v74, v75
	s_and_saveexec_b64 s[28:29], s[12:13]
	s_xor_b64 s[28:29], exec, s[28:29]
	s_cbranch_execz .LBB0_400
	v_cmp_lt_u32_e32 vcc, s60, v124
	s_and_saveexec_b64 s[30:31], vcc
	s_xor_b64 s[30:31], exec, s[30:31]
	s_cbranch_execz .LBB0_397
	v_cmp_gt_u32_e32 vcc, s23, v124
	s_and_saveexec_b64 s[38:39], vcc
	s_cbranch_execz .LBB0_396
	v_mov_b32_e32 v125, v1
	v_lshl_add_u64 v[74:75], v[124:125], 1, v[76:77]
	v_add_co_u32_e32 v74, vcc, 0xfffffe00, v74
	s_nop 1
	v_addc_co_u32_e32 v75, vcc, -1, v75, vcc
	s_waitcnt vmcnt(0)
	global_store_dwordx2 v[74:75], v[72:73], off

.LBB0_397:
	s_andn2_saveexec_b64 s[30:31], s[30:31]
	s_cbranch_execz .LBB0_399
	v_mov_b32_e32 v125, v1
	v_lshl_add_u64 v[74:75], v[124:125], 1, v[78:79]
	v_add_co_u32_e32 v74, vcc, 0xd78f000, v74
	s_nop 1
	v_addc_co_u32_e32 v75, vcc, 0, v75, vcc
	s_waitcnt vmcnt(0)
	global_store_dwordx2 v[74:75], v[72:73], off offset:2560

.LBB0_400:
	s_andn2_saveexec_b64 s[28:29], s[28:29]
	s_cbranch_execz .LBB0_402
	v_lshl_add_u64 v[74:75], v[2:3], 1, v[76:77]
	s_waitcnt vmcnt(0)
	global_store_dwordx2 v[74:75], v[72:73], off offset:256

.LBB0_405:
	v_cmp_lt_u32_e32 vcc, s60, v104
	s_and_saveexec_b64 s[30:31], vcc
	s_xor_b64 s[30:31], exec, s[30:31]
	s_cbranch_execz .LBB0_409
	v_cmp_gt_u32_e32 vcc, s23, v104
	s_and_saveexec_b64 s[38:39], vcc
	s_cbranch_execz .LBB0_408
	v_mov_b32_e32 v105, v1
	v_lshl_add_u64 v[70:71], v[104:105], 1, v[76:77]
	v_add_co_u32_e32 v70, vcc, 0xfffffe00, v70
	s_nop 1
	v_addc_co_u32_e32 v71, vcc, -1, v71, vcc
	s_waitcnt vmcnt(0)
	global_store_dwordx2 v[70:71], v[68:69], off

.LBB0_409:
	s_andn2_saveexec_b64 s[30:31], s[30:31]
	s_cbranch_execz .LBB0_411
	v_mov_b32_e32 v105, v1
	v_lshl_add_u64 v[70:71], v[104:105], 1, v[78:79]
	v_add_co_u32_e32 v70, vcc, 0xd78f000, v70
	s_nop 1
	v_addc_co_u32_e32 v71, vcc, 0, v71, vcc
	s_waitcnt vmcnt(0)
	global_store_dwordx2 v[70:71], v[68:69], off offset:2560

.LBB0_412:
	v_lshl_add_u64 v[70:71], v[2:3], 1, v[76:77]
	s_waitcnt vmcnt(0)
	global_store_dwordx2 v[70:71], v[68:69], off offset:288
	s_or_b64 exec, exec, s[28:29]
	s_and_b64 vcc, exec, s[14:15]
	s_cbranch_vccnz .LBB0_205
.LBB0_413:
	ds_read_b32 v72, v139 offset:512
	ds_read_b128 v[74:77], v138 offset:1024
	v_add_u32_e32 v70, s26, v204
	v_ashrrev_i32_e32 v71, 31, v70
	v_mov_b64_e32 v[68:69], s[20:21]
	s_waitcnt lgkmcnt(0)
	v_fmamk_f32 v72, v72, 0x3a800000, v206
	v_cmp_gt_f32_e32 vcc, s35, v72
	v_mul_f32_e32 v73, 0x4b800000, v72
	v_mad_i64_i32 v[68:69], s[14:15], v70, s83, v[68:69]
	v_cndmask_b32_e32 v72, v72, v73, vcc
	v_rsq_f32_e32 v72, v72
	v_lshlrev_b64 v[70:71], 9, v[70:71]
	v_lshl_add_u64 v[70:71], s[16:17], 0, v[70:71]
	v_mul_f32_e32 v73, 0x45800000, v72
	v_cndmask_b32_e32 v72, v72, v73, vcc
	v_pk_fma_f32 v[64:65], v[64:65], v[72:73], v[74:75] op_sel_hi:[1,0,1]
	v_pk_fma_f32 v[66:67], v[66:67], v[72:73], v[76:77] op_sel_hi:[1,0,1]
	v_cvt_pk_bf16_f32 v64, v64, v65
	v_cvt_pk_bf16_f32 v65, v66, v67
	s_and_saveexec_b64 s[14:15], s[6:7]
	s_xor_b64 s[14:15], exec, s[14:15]
	s_cbranch_execz .LBB0_421
	v_cmp_lt_u32_e32 vcc, s60, v2
	s_and_saveexec_b64 s[26:27], vcc
	s_xor_b64 s[26:27], exec, s[26:27]
	s_cbranch_execz .LBB0_418
	v_cmp_gt_u32_e32 vcc, s23, v2
	s_and_saveexec_b64 s[28:29], vcc
	s_cbranch_execz .LBB0_417
	v_mov_b32_e32 v66, v2
	v_mov_b32_e32 v67, v1
	v_lshl_add_u64 v[66:67], v[66:67], 1, v[68:69]
	v_add_co_u32_e32 v66, vcc, 0xfffffe00, v66
	s_nop 1
	v_addc_co_u32_e32 v67, vcc, -1, v67, vcc
	s_waitcnt vmcnt(0)
	global_store_dwordx2 v[66:67], v[64:65], off

.LBB0_418:
	s_andn2_saveexec_b64 s[26:27], s[26:27]
	s_cbranch_execz .LBB0_420
	v_mov_b32_e32 v66, v2
	v_mov_b32_e32 v67, v1
	v_lshl_add_u64 v[66:67], v[66:67], 1, v[70:71]
	v_add_co_u32_e32 v66, vcc, 0xd78f000, v66
	s_nop 1
	v_addc_co_u32_e32 v67, vcc, 0, v67, vcc
	s_waitcnt vmcnt(0)
	global_store_dwordx2 v[66:67], v[64:65], off offset:2560

.LBB0_421:
	s_andn2_saveexec_b64 s[14:15], s[14:15]
	s_cbranch_execz .LBB0_423
	v_lshl_add_u64 v[66:67], v[2:3], 1, v[68:69]
	s_waitcnt vmcnt(0)
	global_store_dwordx2 v[66:67], v[64:65], off
.LBB0_423:
	s_or_b64 exec, exec, s[14:15]
	ds_read_b128 v[64:67], v138 offset:1088
	v_mov_b32_e32 v73, v72
	s_waitcnt lgkmcnt(0)
	v_pk_fma_f32 v[60:61], v[60:61], v[72:73], v[64:65]
	v_pk_fma_f32 v[62:63], v[62:63], v[72:73], v[66:67]
	v_cvt_pk_bf16_f32 v60, v60, v61
	v_cvt_pk_bf16_f32 v61, v62, v63
	s_and_saveexec_b64 s[14:15], s[10:11]
	s_xor_b64 s[14:15], exec, s[14:15]
	s_cbranch_execz .LBB0_431
	v_cmp_lt_u32_e32 vcc, s60, v0
	s_and_saveexec_b64 s[26:27], vcc
	s_xor_b64 s[26:27], exec, s[26:27]
	s_cbranch_execz .LBB0_428
	v_cmp_gt_u32_e32 vcc, s23, v0
	s_and_saveexec_b64 s[28:29], vcc
	s_cbranch_execz .LBB0_427
	v_lshl_add_u64 v[62:63], v[0:1], 1, v[68:69]
	v_add_co_u32_e32 v62, vcc, 0xfffffe00, v62
	s_nop 1
	v_addc_co_u32_e32 v63, vcc, -1, v63, vcc
	s_waitcnt vmcnt(0)
	global_store_dwordx2 v[62:63], v[60:61], off

.LBB0_428:
	s_andn2_saveexec_b64 s[26:27], s[26:27]
	s_cbranch_execz .LBB0_430
	v_lshl_add_u64 v[62:63], v[0:1], 1, v[70:71]
	v_add_co_u32_e32 v62, vcc, 0xd78f000, v62
	s_nop 1
	v_addc_co_u32_e32 v63, vcc, 0, v63, vcc
	s_waitcnt vmcnt(0)
	global_store_dwordx2 v[62:63], v[60:61], off offset:2560

.LBB0_431:
	s_andn2_saveexec_b64 s[14:15], s[14:15]
	s_cbranch_execz .LBB0_433
	v_lshl_add_u64 v[62:63], v[2:3], 1, v[68:69]
	s_waitcnt vmcnt(0)
	global_store_dwordx2 v[62:63], v[60:61], off offset:32
.LBB0_433:
	s_or_b64 exec, exec, s[14:15]
	ds_read_b128 v[60:63], v138 offset:1536
	s_waitcnt lgkmcnt(0)
	v_pk_fma_f32 v[56:57], v[56:57], v[72:73], v[60:61]
	v_pk_fma_f32 v[58:59], v[58:59], v[72:73], v[62:63]
	v_cvt_pk_bf16_f32 v56, v56, v57
	v_cvt_pk_bf16_f32 v57, v58, v59
	s_and_saveexec_b64 s[14:15], s[12:13]
	s_xor_b64 s[14:15], exec, s[14:15]
	s_cbranch_execz .LBB0_441
	v_cmp_lt_u32_e32 vcc, s60, v124
	s_and_saveexec_b64 s[26:27], vcc
	s_xor_b64 s[26:27], exec, s[26:27]
	s_cbranch_execz .LBB0_438
	v_cmp_gt_u32_e32 vcc, s23, v124
	s_and_saveexec_b64 s[28:29], vcc
	s_cbranch_execz .LBB0_437
	v_mov_b32_e32 v125, v1
	v_lshl_add_u64 v[58:59], v[124:125], 1, v[68:69]
	v_add_co_u32_e32 v58, vcc, 0xfffffe00, v58
	s_nop 1
	v_addc_co_u32_e32 v59, vcc, -1, v59, vcc
	s_waitcnt vmcnt(0)
	global_store_dwordx2 v[58:59], v[56:57], off

.LBB0_438:
	s_andn2_saveexec_b64 s[26:27], s[26:27]
	s_cbranch_execz .LBB0_440
	v_mov_b32_e32 v125, v1
	v_lshl_add_u64 v[58:59], v[124:125], 1, v[70:71]
	v_add_co_u32_e32 v58, vcc, 0xd78f000, v58
	s_nop 1
	v_addc_co_u32_e32 v59, vcc, 0, v59, vcc
	s_waitcnt vmcnt(0)
	global_store_dwordx2 v[58:59], v[56:57], off offset:2560

.LBB0_441:
	s_andn2_saveexec_b64 s[14:15], s[14:15]
	s_cbranch_execz .LBB0_443
	v_lshl_add_u64 v[58:59], v[2:3], 1, v[68:69]
	s_waitcnt vmcnt(0)
	global_store_dwordx2 v[58:59], v[56:57], off offset:256
.LBB0_443:
	s_or_b64 exec, exec, s[14:15]
	ds_read_b128 v[56:59], v138 offset:1600
	s_waitcnt lgkmcnt(0)
	v_pk_fma_f32 v[52:53], v[52:53], v[72:73], v[56:57]
	v_pk_fma_f32 v[54:55], v[54:55], v[72:73], v[58:59]
	v_cvt_pk_bf16_f32 v52, v52, v53
	v_cvt_pk_bf16_f32 v53, v54, v55
	s_and_saveexec_b64 s[14:15], s[8:9]
	s_xor_b64 s[14:15], exec, s[14:15]
	s_cbranch_execz .LBB0_451
	v_cmp_lt_u32_e32 vcc, s60, v104
	s_and_saveexec_b64 s[26:27], vcc
	s_xor_b64 s[26:27], exec, s[26:27]
	s_cbranch_execz .LBB0_448
	v_cmp_gt_u32_e32 vcc, s23, v104
	s_and_saveexec_b64 s[28:29], vcc
	s_cbranch_execz .LBB0_447
	v_mov_b32_e32 v105, v1
	v_lshl_add_u64 v[54:55], v[104:105], 1, v[68:69]
	v_add_co_u32_e32 v54, vcc, 0xfffffe00, v54
	s_nop 1
	v_addc_co_u32_e32 v55, vcc, -1, v55, vcc
	s_waitcnt vmcnt(0)
	global_store_dwordx2 v[54:55], v[52:53], off

.LBB0_448:
	s_andn2_saveexec_b64 s[26:27], s[26:27]
	s_cbranch_execz .LBB0_450
	v_mov_b32_e32 v105, v1
	v_lshl_add_u64 v[54:55], v[104:105], 1, v[70:71]
	v_add_co_u32_e32 v54, vcc, 0xd78f000, v54
	s_nop 1
	v_addc_co_u32_e32 v55, vcc, 0, v55, vcc
	s_waitcnt vmcnt(0)
	global_store_dwordx2 v[54:55], v[52:53], off offset:2560

.LBB0_451:
	s_andn2_saveexec_b64 s[14:15], s[14:15]
	s_cbranch_execz .LBB0_453
	v_lshl_add_u64 v[54:55], v[2:3], 1, v[68:69]
	s_waitcnt vmcnt(0)
	global_store_dwordx2 v[54:55], v[52:53], off offset:288
.LBB0_453:
	s_or_b64 exec, exec, s[14:15]
	ds_read_b32 v56, v139 offset:576
	ds_read_b128 v[58:61], v138 offset:1024
	v_add_u32_e32 v52, 0x90, v204
	v_add_u32_e32 v54, s22, v52
	v_ashrrev_i32_e32 v55, 31, v54
	s_waitcnt lgkmcnt(0)
	v_fmamk_f32 v56, v56, 0x3a800000, v206
	v_cmp_gt_f32_e32 vcc, s35, v56
	v_mul_f32_e32 v57, 0x4b800000, v56
	v_mov_b64_e32 v[52:53], s[20:21]
	v_cndmask_b32_e32 v56, v56, v57, vcc
	v_rsq_f32_e32 v56, v56
	v_mad_i64_i32 v[52:53], s[14:15], v54, s83, v[52:53]
	v_lshlrev_b64 v[54:55], 9, v[54:55]
	v_mul_f32_e32 v57, 0x45800000, v56
	v_cndmask_b32_e32 v56, v56, v57, vcc
	v_pk_fma_f32 v[48:49], v[48:49], v[56:57], v[58:59] op_sel_hi:[1,0,1]
	v_pk_fma_f32 v[50:51], v[50:51], v[56:57], v[60:61] op_sel_hi:[1,0,1]
	v_lshl_add_u64 v[54:55], s[16:17], 0, v[54:55]
	v_cvt_pk_bf16_f32 v48, v48, v49
	v_cvt_pk_bf16_f32 v49, v50, v51
	s_and_saveexec_b64 s[14:15], s[6:7]
	s_xor_b64 s[14:15], exec, s[14:15]
	s_cbranch_execz .LBB0_461
	v_cmp_lt_u32_e32 vcc, s60, v2
	s_and_saveexec_b64 s[26:27], vcc
	s_xor_b64 s[26:27], exec, s[26:27]
	s_cbranch_execz .LBB0_458
	v_cmp_gt_u32_e32 vcc, s23, v2
	s_and_saveexec_b64 s[28:29], vcc
	s_cbranch_execz .LBB0_457
	v_mov_b32_e32 v50, v2
	v_mov_b32_e32 v51, v1
	v_lshl_add_u64 v[50:51], v[50:51], 1, v[52:53]
	v_add_co_u32_e32 v50, vcc, 0xfffffe00, v50
	s_nop 1
	v_addc_co_u32_e32 v51, vcc, -1, v51, vcc
	s_waitcnt vmcnt(0)
	global_store_dwordx2 v[50:51], v[48:49], off

.LBB0_458:
	s_andn2_saveexec_b64 s[26:27], s[26:27]
	s_cbranch_execz .LBB0_460
	v_mov_b32_e32 v50, v2
	v_mov_b32_e32 v51, v1
	v_lshl_add_u64 v[50:51], v[50:51], 1, v[54:55]
	v_add_co_u32_e32 v50, vcc, 0xd78f000, v50
	s_nop 1
	v_addc_co_u32_e32 v51, vcc, 0, v51, vcc
	s_waitcnt vmcnt(0)
	global_store_dwordx2 v[50:51], v[48:49], off offset:2560

.LBB0_461:
	s_andn2_saveexec_b64 s[14:15], s[14:15]
	s_cbranch_execz .LBB0_463
	v_lshl_add_u64 v[50:51], v[2:3], 1, v[52:53]
	s_waitcnt vmcnt(0)
	global_store_dwordx2 v[50:51], v[48:49], off
.LBB0_463:
	s_or_b64 exec, exec, s[14:15]
	ds_read_b128 v[48:51], v138 offset:1088
	v_mov_b32_e32 v57, v56
	s_waitcnt lgkmcnt(0)
	v_pk_fma_f32 v[44:45], v[44:45], v[56:57], v[48:49]
	v_pk_fma_f32 v[46:47], v[46:47], v[56:57], v[50:51]
	v_cvt_pk_bf16_f32 v44, v44, v45
	v_cvt_pk_bf16_f32 v45, v46, v47
	s_and_saveexec_b64 s[14:15], s[10:11]
	s_xor_b64 s[14:15], exec, s[14:15]
	s_cbranch_execz .LBB0_471
	v_cmp_lt_u32_e32 vcc, s60, v0
	s_and_saveexec_b64 s[26:27], vcc
	s_xor_b64 s[26:27], exec, s[26:27]
	s_cbranch_execz .LBB0_468
	v_cmp_gt_u32_e32 vcc, s23, v0
	s_and_saveexec_b64 s[28:29], vcc
	s_cbranch_execz .LBB0_467
	v_lshl_add_u64 v[46:47], v[0:1], 1, v[52:53]
	v_add_co_u32_e32 v46, vcc, 0xfffffe00, v46
	s_nop 1
	v_addc_co_u32_e32 v47, vcc, -1, v47, vcc
	s_waitcnt vmcnt(0)
	global_store_dwordx2 v[46:47], v[44:45], off

.LBB0_468:
	s_andn2_saveexec_b64 s[26:27], s[26:27]
	s_cbranch_execz .LBB0_470
	v_lshl_add_u64 v[46:47], v[0:1], 1, v[54:55]
	v_add_co_u32_e32 v46, vcc, 0xd78f000, v46
	s_nop 1
	v_addc_co_u32_e32 v47, vcc, 0, v47, vcc
	s_waitcnt vmcnt(0)
	global_store_dwordx2 v[46:47], v[44:45], off offset:2560

.LBB0_471:
	s_andn2_saveexec_b64 s[14:15], s[14:15]
	s_cbranch_execz .LBB0_473
	v_lshl_add_u64 v[46:47], v[2:3], 1, v[52:53]
	s_waitcnt vmcnt(0)
	global_store_dwordx2 v[46:47], v[44:45], off offset:32
.LBB0_473:
	s_or_b64 exec, exec, s[14:15]
	ds_read_b128 v[44:47], v138 offset:1536
	s_waitcnt lgkmcnt(0)
	v_pk_fma_f32 v[40:41], v[40:41], v[56:57], v[44:45]
	v_pk_fma_f32 v[42:43], v[42:43], v[56:57], v[46:47]
	v_cvt_pk_bf16_f32 v40, v40, v41
	v_cvt_pk_bf16_f32 v41, v42, v43
	s_and_saveexec_b64 s[14:15], s[12:13]
	s_xor_b64 s[14:15], exec, s[14:15]
	s_cbranch_execz .LBB0_481
	v_cmp_lt_u32_e32 vcc, s60, v124
	s_and_saveexec_b64 s[26:27], vcc
	s_xor_b64 s[26:27], exec, s[26:27]
	s_cbranch_execz .LBB0_478
	v_cmp_gt_u32_e32 vcc, s23, v124
	s_and_saveexec_b64 s[28:29], vcc
	s_cbranch_execz .LBB0_477
	v_mov_b32_e32 v125, v1
	v_lshl_add_u64 v[42:43], v[124:125], 1, v[52:53]
	v_add_co_u32_e32 v42, vcc, 0xfffffe00, v42
	s_nop 1
	v_addc_co_u32_e32 v43, vcc, -1, v43, vcc
	s_waitcnt vmcnt(0)
	global_store_dwordx2 v[42:43], v[40:41], off

.LBB0_478:
	s_andn2_saveexec_b64 s[26:27], s[26:27]
	s_cbranch_execz .LBB0_480
	v_mov_b32_e32 v125, v1
	v_lshl_add_u64 v[42:43], v[124:125], 1, v[54:55]
	v_add_co_u32_e32 v42, vcc, 0xd78f000, v42
	s_nop 1
	v_addc_co_u32_e32 v43, vcc, 0, v43, vcc
	s_waitcnt vmcnt(0)
	global_store_dwordx2 v[42:43], v[40:41], off offset:2560

.LBB0_481:
	s_andn2_saveexec_b64 s[14:15], s[14:15]
	s_cbranch_execz .LBB0_483
	v_lshl_add_u64 v[42:43], v[2:3], 1, v[52:53]
	s_waitcnt vmcnt(0)
	global_store_dwordx2 v[42:43], v[40:41], off offset:256
.LBB0_483:
	s_or_b64 exec, exec, s[14:15]
	ds_read_b128 v[40:43], v138 offset:1600
	s_waitcnt lgkmcnt(0)
	v_pk_fma_f32 v[36:37], v[36:37], v[56:57], v[40:41]
	v_pk_fma_f32 v[38:39], v[38:39], v[56:57], v[42:43]
	v_cvt_pk_bf16_f32 v36, v36, v37
	v_cvt_pk_bf16_f32 v37, v38, v39
	s_and_saveexec_b64 s[14:15], s[8:9]
	s_xor_b64 s[14:15], exec, s[14:15]
	s_cbranch_execz .LBB0_491
	v_cmp_lt_u32_e32 vcc, s60, v104
	s_and_saveexec_b64 s[26:27], vcc
	s_xor_b64 s[26:27], exec, s[26:27]
	s_cbranch_execz .LBB0_488
	v_cmp_gt_u32_e32 vcc, s23, v104
	s_and_saveexec_b64 s[28:29], vcc
	s_cbranch_execz .LBB0_487
	v_mov_b32_e32 v105, v1
	v_lshl_add_u64 v[38:39], v[104:105], 1, v[52:53]
	v_add_co_u32_e32 v38, vcc, 0xfffffe00, v38
	s_nop 1
	v_addc_co_u32_e32 v39, vcc, -1, v39, vcc
	s_waitcnt vmcnt(0)
	global_store_dwordx2 v[38:39], v[36:37], off

.LBB0_488:
	s_andn2_saveexec_b64 s[26:27], s[26:27]
	s_cbranch_execz .LBB0_490
	v_mov_b32_e32 v105, v1
	v_lshl_add_u64 v[38:39], v[104:105], 1, v[54:55]
	v_add_co_u32_e32 v38, vcc, 0xd78f000, v38
	s_nop 1
	v_addc_co_u32_e32 v39, vcc, 0, v39, vcc
	s_waitcnt vmcnt(0)
	global_store_dwordx2 v[38:39], v[36:37], off offset:2560

.LBB0_491:
	s_andn2_saveexec_b64 s[14:15], s[14:15]
	s_cbranch_execz .LBB0_493
	v_lshl_add_u64 v[38:39], v[2:3], 1, v[52:53]
	s_waitcnt vmcnt(0)
	global_store_dwordx2 v[38:39], v[36:37], off offset:288
.LBB0_493:
	s_or_b64 exec, exec, s[14:15]
	ds_read_b32 v40, v139 offset:640
	ds_read_b128 v[42:45], v138 offset:1024
	v_add_u32_e32 v36, 0xa0, v204
	v_add_u32_e32 v38, s22, v36
	v_ashrrev_i32_e32 v39, 31, v38
	s_waitcnt lgkmcnt(0)
	v_fmamk_f32 v40, v40, 0x3a800000, v206
	v_cmp_gt_f32_e32 vcc, s35, v40
	v_mul_f32_e32 v41, 0x4b800000, v40
	v_mov_b64_e32 v[36:37], s[20:21]
	v_cndmask_b32_e32 v40, v40, v41, vcc
	v_rsq_f32_e32 v40, v40
	v_mad_i64_i32 v[36:37], s[14:15], v38, s83, v[36:37]
	v_lshlrev_b64 v[38:39], 9, v[38:39]
	v_mul_f32_e32 v41, 0x45800000, v40
	v_cndmask_b32_e32 v40, v40, v41, vcc
	v_pk_fma_f32 v[32:33], v[32:33], v[40:41], v[42:43] op_sel_hi:[1,0,1]
	v_pk_fma_f32 v[34:35], v[34:35], v[40:41], v[44:45] op_sel_hi:[1,0,1]
	v_lshl_add_u64 v[38:39], s[16:17], 0, v[38:39]
	v_cvt_pk_bf16_f32 v32, v32, v33
	v_cvt_pk_bf16_f32 v33, v34, v35
	s_and_saveexec_b64 s[14:15], s[6:7]
	s_xor_b64 s[14:15], exec, s[14:15]
	s_cbranch_execz .LBB0_501
	v_cmp_lt_u32_e32 vcc, s60, v2
	s_and_saveexec_b64 s[26:27], vcc
	s_xor_b64 s[26:27], exec, s[26:27]
	s_cbranch_execz .LBB0_498
	v_cmp_gt_u32_e32 vcc, s23, v2
	s_and_saveexec_b64 s[28:29], vcc
	s_cbranch_execz .LBB0_497
	v_mov_b32_e32 v34, v2
	v_mov_b32_e32 v35, v1
	v_lshl_add_u64 v[34:35], v[34:35], 1, v[36:37]
	v_add_co_u32_e32 v34, vcc, 0xfffffe00, v34
	s_nop 1
	v_addc_co_u32_e32 v35, vcc, -1, v35, vcc
	s_waitcnt vmcnt(0)
	global_store_dwordx2 v[34:35], v[32:33], off

.LBB0_498:
	s_andn2_saveexec_b64 s[26:27], s[26:27]
	s_cbranch_execz .LBB0_500
	v_mov_b32_e32 v34, v2
	v_mov_b32_e32 v35, v1
	v_lshl_add_u64 v[34:35], v[34:35], 1, v[38:39]
	v_add_co_u32_e32 v34, vcc, 0xd78f000, v34
	s_nop 1
	v_addc_co_u32_e32 v35, vcc, 0, v35, vcc
	s_waitcnt vmcnt(0)
	global_store_dwordx2 v[34:35], v[32:33], off offset:2560

.LBB0_501:
	s_andn2_saveexec_b64 s[14:15], s[14:15]
	s_cbranch_execz .LBB0_503
	v_lshl_add_u64 v[34:35], v[2:3], 1, v[36:37]
	s_waitcnt vmcnt(0)
	global_store_dwordx2 v[34:35], v[32:33], off
.LBB0_503:
	s_or_b64 exec, exec, s[14:15]
	ds_read_b128 v[32:35], v138 offset:1088
	v_mov_b32_e32 v41, v40
	s_waitcnt lgkmcnt(0)
	v_pk_fma_f32 v[28:29], v[28:29], v[40:41], v[32:33]
	v_pk_fma_f32 v[30:31], v[30:31], v[40:41], v[34:35]
	v_cvt_pk_bf16_f32 v28, v28, v29
	v_cvt_pk_bf16_f32 v29, v30, v31
	s_and_saveexec_b64 s[14:15], s[10:11]
	s_xor_b64 s[14:15], exec, s[14:15]
	s_cbranch_execz .LBB0_511
	v_cmp_lt_u32_e32 vcc, s60, v0
	s_and_saveexec_b64 s[26:27], vcc
	s_xor_b64 s[26:27], exec, s[26:27]
	s_cbranch_execz .LBB0_508
	v_cmp_gt_u32_e32 vcc, s23, v0
	s_and_saveexec_b64 s[28:29], vcc
	s_cbranch_execz .LBB0_507
	v_lshl_add_u64 v[30:31], v[0:1], 1, v[36:37]
	v_add_co_u32_e32 v30, vcc, 0xfffffe00, v30
	s_nop 1
	v_addc_co_u32_e32 v31, vcc, -1, v31, vcc
	s_waitcnt vmcnt(0)
	global_store_dwordx2 v[30:31], v[28:29], off

.LBB0_508:
	s_andn2_saveexec_b64 s[26:27], s[26:27]
	s_cbranch_execz .LBB0_510
	v_lshl_add_u64 v[30:31], v[0:1], 1, v[38:39]
	v_add_co_u32_e32 v30, vcc, 0xd78f000, v30
	s_nop 1
	v_addc_co_u32_e32 v31, vcc, 0, v31, vcc
	s_waitcnt vmcnt(0)
	global_store_dwordx2 v[30:31], v[28:29], off offset:2560

.LBB0_511:
	s_andn2_saveexec_b64 s[14:15], s[14:15]
	s_cbranch_execz .LBB0_513
	v_lshl_add_u64 v[30:31], v[2:3], 1, v[36:37]
	s_waitcnt vmcnt(0)
	global_store_dwordx2 v[30:31], v[28:29], off offset:32
.LBB0_513:
	s_or_b64 exec, exec, s[14:15]
	ds_read_b128 v[28:31], v138 offset:1536
	s_waitcnt lgkmcnt(0)
	v_pk_fma_f32 v[24:25], v[24:25], v[40:41], v[28:29]
	v_pk_fma_f32 v[26:27], v[26:27], v[40:41], v[30:31]
	v_cvt_pk_bf16_f32 v24, v24, v25
	v_cvt_pk_bf16_f32 v25, v26, v27
	s_and_saveexec_b64 s[14:15], s[12:13]
	s_xor_b64 s[14:15], exec, s[14:15]
	s_cbranch_execz .LBB0_521
	v_cmp_lt_u32_e32 vcc, s60, v124
	s_and_saveexec_b64 s[26:27], vcc
	s_xor_b64 s[26:27], exec, s[26:27]
	s_cbranch_execz .LBB0_518
	v_cmp_gt_u32_e32 vcc, s23, v124
	s_and_saveexec_b64 s[28:29], vcc
	s_cbranch_execz .LBB0_517
	v_mov_b32_e32 v125, v1
	v_lshl_add_u64 v[26:27], v[124:125], 1, v[36:37]
	v_add_co_u32_e32 v26, vcc, 0xfffffe00, v26
	s_nop 1
	v_addc_co_u32_e32 v27, vcc, -1, v27, vcc
	s_waitcnt vmcnt(0)
	global_store_dwordx2 v[26:27], v[24:25], off

.LBB0_518:
	s_andn2_saveexec_b64 s[26:27], s[26:27]
	s_cbranch_execz .LBB0_520
	v_mov_b32_e32 v125, v1
	v_lshl_add_u64 v[26:27], v[124:125], 1, v[38:39]
	v_add_co_u32_e32 v26, vcc, 0xd78f000, v26
	s_nop 1
	v_addc_co_u32_e32 v27, vcc, 0, v27, vcc
	s_waitcnt vmcnt(0)
	global_store_dwordx2 v[26:27], v[24:25], off offset:2560

.LBB0_521:
	s_andn2_saveexec_b64 s[14:15], s[14:15]
	s_cbranch_execz .LBB0_523
	v_lshl_add_u64 v[26:27], v[2:3], 1, v[36:37]
	s_waitcnt vmcnt(0)
	global_store_dwordx2 v[26:27], v[24:25], off offset:256
.LBB0_523:
	s_or_b64 exec, exec, s[14:15]
	ds_read_b128 v[24:27], v138 offset:1600
	s_waitcnt lgkmcnt(0)
	v_pk_fma_f32 v[20:21], v[20:21], v[40:41], v[24:25]
	v_pk_fma_f32 v[22:23], v[22:23], v[40:41], v[26:27]
	v_cvt_pk_bf16_f32 v20, v20, v21
	v_cvt_pk_bf16_f32 v21, v22, v23
	s_and_saveexec_b64 s[14:15], s[8:9]
	s_xor_b64 s[14:15], exec, s[14:15]
	s_cbranch_execz .LBB0_531
	v_cmp_lt_u32_e32 vcc, s60, v104
	s_and_saveexec_b64 s[26:27], vcc
	s_xor_b64 s[26:27], exec, s[26:27]
	s_cbranch_execz .LBB0_528
	v_cmp_gt_u32_e32 vcc, s23, v104
	s_and_saveexec_b64 s[28:29], vcc
	s_cbranch_execz .LBB0_527
	v_mov_b32_e32 v105, v1
	v_lshl_add_u64 v[22:23], v[104:105], 1, v[36:37]
	v_add_co_u32_e32 v22, vcc, 0xfffffe00, v22
	s_nop 1
	v_addc_co_u32_e32 v23, vcc, -1, v23, vcc
	s_waitcnt vmcnt(0)
	global_store_dwordx2 v[22:23], v[20:21], off

.LBB0_528:
	s_andn2_saveexec_b64 s[26:27], s[26:27]
	s_cbranch_execz .LBB0_530
	v_mov_b32_e32 v105, v1
	v_lshl_add_u64 v[22:23], v[104:105], 1, v[38:39]
	v_add_co_u32_e32 v22, vcc, 0xd78f000, v22
	s_nop 1
	v_addc_co_u32_e32 v23, vcc, 0, v23, vcc
	s_waitcnt vmcnt(0)
	global_store_dwordx2 v[22:23], v[20:21], off offset:2560

.LBB0_531:
	s_andn2_saveexec_b64 s[14:15], s[14:15]
	s_cbranch_execz .LBB0_533
	v_lshl_add_u64 v[22:23], v[2:3], 1, v[36:37]
	s_waitcnt vmcnt(0)
	global_store_dwordx2 v[22:23], v[20:21], off offset:288
.LBB0_533:
	s_or_b64 exec, exec, s[14:15]
	ds_read_b32 v24, v139 offset:704
	ds_read_b128 v[26:29], v138 offset:1024
	v_add_u32_e32 v20, 0xb0, v204
	v_add_u32_e32 v22, s22, v20
	v_ashrrev_i32_e32 v23, 31, v22
	s_waitcnt lgkmcnt(0)
	v_fmamk_f32 v24, v24, 0x3a800000, v206
	v_cmp_gt_f32_e32 vcc, s35, v24
	v_mul_f32_e32 v25, 0x4b800000, v24
	v_mov_b64_e32 v[20:21], s[20:21]
	v_cndmask_b32_e32 v24, v24, v25, vcc
	v_rsq_f32_e32 v24, v24
	v_mad_i64_i32 v[20:21], s[14:15], v22, s83, v[20:21]
	v_lshlrev_b64 v[22:23], 9, v[22:23]
	v_mul_f32_e32 v25, 0x45800000, v24
	v_cndmask_b32_e32 v24, v24, v25, vcc
	v_pk_fma_f32 v[16:17], v[16:17], v[24:25], v[26:27] op_sel_hi:[1,0,1]
	v_pk_fma_f32 v[18:19], v[18:19], v[24:25], v[28:29] op_sel_hi:[1,0,1]
	v_lshl_add_u64 v[22:23], s[16:17], 0, v[22:23]
	v_cvt_pk_bf16_f32 v16, v16, v17
	v_cvt_pk_bf16_f32 v17, v18, v19
	s_and_saveexec_b64 s[14:15], s[6:7]
	s_xor_b64 s[6:7], exec, s[14:15]
	s_cbranch_execz .LBB0_541
	v_cmp_lt_u32_e32 vcc, s60, v2
	s_and_saveexec_b64 s[14:15], vcc
	s_xor_b64 s[14:15], exec, s[14:15]
	s_cbranch_execz .LBB0_538
	v_cmp_gt_u32_e32 vcc, s23, v2
	s_and_saveexec_b64 s[26:27], vcc
	s_cbranch_execz .LBB0_537
	v_mov_b32_e32 v18, v2
	v_mov_b32_e32 v19, v1
	v_lshl_add_u64 v[18:19], v[18:19], 1, v[20:21]
	v_add_co_u32_e32 v18, vcc, 0xfffffe00, v18
	s_nop 1
	v_addc_co_u32_e32 v19, vcc, -1, v19, vcc
	s_waitcnt vmcnt(0)
	global_store_dwordx2 v[18:19], v[16:17], off

.LBB0_538:
	s_andn2_saveexec_b64 s[14:15], s[14:15]
	s_cbranch_execz .LBB0_540
	v_mov_b32_e32 v18, v2
	v_mov_b32_e32 v19, v1
	v_lshl_add_u64 v[18:19], v[18:19], 1, v[22:23]
	v_add_co_u32_e32 v18, vcc, 0xd78f000, v18
	s_nop 1
	v_addc_co_u32_e32 v19, vcc, 0, v19, vcc
	s_waitcnt vmcnt(0)
	global_store_dwordx2 v[18:19], v[16:17], off offset:2560

.LBB0_541:
	s_andn2_saveexec_b64 s[6:7], s[6:7]
	s_cbranch_execz .LBB0_543
	v_lshl_add_u64 v[18:19], v[2:3], 1, v[20:21]
	s_waitcnt vmcnt(0)
	global_store_dwordx2 v[18:19], v[16:17], off
.LBB0_543:
	s_or_b64 exec, exec, s[6:7]
	ds_read_b128 v[16:19], v138 offset:1088
	v_mov_b32_e32 v25, v24
	s_waitcnt lgkmcnt(0)
	v_pk_fma_f32 v[12:13], v[12:13], v[24:25], v[16:17]
	v_pk_fma_f32 v[14:15], v[14:15], v[24:25], v[18:19]
	v_cvt_pk_bf16_f32 v12, v12, v13
	v_cvt_pk_bf16_f32 v13, v14, v15
	s_and_saveexec_b64 s[6:7], s[10:11]
	s_xor_b64 s[6:7], exec, s[6:7]
	s_cbranch_execz .LBB0_551
	v_cmp_lt_u32_e32 vcc, s60, v0
	s_and_saveexec_b64 s[10:11], vcc
	s_xor_b64 s[10:11], exec, s[10:11]
	s_cbranch_execz .LBB0_548
	v_cmp_gt_u32_e32 vcc, s23, v0
	s_and_saveexec_b64 s[14:15], vcc
	s_cbranch_execz .LBB0_547
	v_lshl_add_u64 v[14:15], v[0:1], 1, v[20:21]
	v_add_co_u32_e32 v14, vcc, 0xfffffe00, v14
	s_nop 1
	v_addc_co_u32_e32 v15, vcc, -1, v15, vcc
	s_waitcnt vmcnt(0)
	global_store_dwordx2 v[14:15], v[12:13], off

.LBB0_548:
	s_andn2_saveexec_b64 s[10:11], s[10:11]
	s_cbranch_execz .LBB0_550
	v_lshl_add_u64 v[14:15], v[0:1], 1, v[22:23]
	v_add_co_u32_e32 v14, vcc, 0xd78f000, v14
	s_nop 1
	v_addc_co_u32_e32 v15, vcc, 0, v15, vcc
	s_waitcnt vmcnt(0)
	global_store_dwordx2 v[14:15], v[12:13], off offset:2560

.LBB0_551:
	s_andn2_saveexec_b64 s[6:7], s[6:7]
	s_cbranch_execz .LBB0_553
	v_lshl_add_u64 v[14:15], v[2:3], 1, v[20:21]
	s_waitcnt vmcnt(0)
	global_store_dwordx2 v[14:15], v[12:13], off offset:32
.LBB0_553:
	s_or_b64 exec, exec, s[6:7]
	ds_read_b128 v[12:15], v138 offset:1536
	s_waitcnt lgkmcnt(0)
	v_pk_fma_f32 v[8:9], v[8:9], v[24:25], v[12:13]
	v_pk_fma_f32 v[10:11], v[10:11], v[24:25], v[14:15]
	v_cvt_pk_bf16_f32 v8, v8, v9
	v_cvt_pk_bf16_f32 v9, v10, v11
	s_and_saveexec_b64 s[6:7], s[12:13]
	s_xor_b64 s[6:7], exec, s[6:7]
	s_cbranch_execz .LBB0_561
	v_cmp_lt_u32_e32 vcc, s60, v124
	s_and_saveexec_b64 s[10:11], vcc
	s_xor_b64 s[10:11], exec, s[10:11]
	s_cbranch_execz .LBB0_558
	v_cmp_gt_u32_e32 vcc, s23, v124
	s_and_saveexec_b64 s[12:13], vcc
	s_cbranch_execz .LBB0_557
	v_mov_b32_e32 v125, v1
	v_lshl_add_u64 v[10:11], v[124:125], 1, v[20:21]
	v_add_co_u32_e32 v10, vcc, 0xfffffe00, v10
	s_nop 1
	v_addc_co_u32_e32 v11, vcc, -1, v11, vcc
	s_waitcnt vmcnt(0)
	global_store_dwordx2 v[10:11], v[8:9], off

.LBB0_558:
	s_andn2_saveexec_b64 s[10:11], s[10:11]
	s_cbranch_execz .LBB0_560
	v_mov_b32_e32 v125, v1
	v_lshl_add_u64 v[10:11], v[124:125], 1, v[22:23]
	v_add_co_u32_e32 v10, vcc, 0xd78f000, v10
	s_nop 1
	v_addc_co_u32_e32 v11, vcc, 0, v11, vcc
	s_waitcnt vmcnt(0)
	global_store_dwordx2 v[10:11], v[8:9], off offset:2560

.LBB0_561:
	s_andn2_saveexec_b64 s[6:7], s[6:7]
	s_cbranch_execz .LBB0_563
	v_lshl_add_u64 v[10:11], v[2:3], 1, v[20:21]
	s_waitcnt vmcnt(0)
	global_store_dwordx2 v[10:11], v[8:9], off offset:256
.LBB0_563:
	s_or_b64 exec, exec, s[6:7]
	ds_read_b128 v[8:11], v138 offset:1600
	s_waitcnt lgkmcnt(0)
	v_pk_fma_f32 v[4:5], v[4:5], v[24:25], v[8:9]
	v_pk_fma_f32 v[6:7], v[6:7], v[24:25], v[10:11]
	v_cvt_pk_bf16_f32 v4, v4, v5
	v_cvt_pk_bf16_f32 v5, v6, v7
	s_and_saveexec_b64 s[6:7], s[8:9]
	s_xor_b64 s[6:7], exec, s[6:7]
	s_cbranch_execz .LBB0_571
	v_cmp_lt_u32_e32 vcc, s60, v104
	s_and_saveexec_b64 s[8:9], vcc
	s_xor_b64 s[8:9], exec, s[8:9]
	s_cbranch_execz .LBB0_568
	v_cmp_gt_u32_e32 vcc, s23, v104
	s_and_saveexec_b64 s[10:11], vcc
	s_cbranch_execz .LBB0_567
	v_mov_b32_e32 v105, v1
	v_lshl_add_u64 v[2:3], v[104:105], 1, v[20:21]
	v_add_co_u32_e32 v2, vcc, 0xfffffe00, v2
	s_nop 1
	v_addc_co_u32_e32 v3, vcc, -1, v3, vcc
	s_waitcnt vmcnt(0)
	global_store_dwordx2 v[2:3], v[4:5], off

.LBB0_568:
	s_andn2_saveexec_b64 s[8:9], s[8:9]
	s_cbranch_execz .LBB0_570
	v_mov_b32_e32 v105, v1
	v_lshl_add_u64 v[2:3], v[104:105], 1, v[22:23]
	v_add_co_u32_e32 v2, vcc, 0xd78f000, v2
	s_nop 1
	v_addc_co_u32_e32 v3, vcc, 0, v3, vcc
	s_waitcnt vmcnt(0)
	global_store_dwordx2 v[2:3], v[4:5], off offset:2560

.LBB0_571:
	s_andn2_saveexec_b64 s[6:7], s[6:7]
	s_cbranch_execz .LBB0_204
	v_lshl_add_u64 v[2:3], v[2:3], 1, v[20:21]
	s_waitcnt vmcnt(0)
	global_store_dwordx2 v[2:3], v[4:5], off offset:288
	s_branch .LBB0_204

.LBB0_578:
	v_mov_b64_e32 v[14:15], s[16:17]
	global_load_dword v12, v[14:15], off offset:1024 sc1
	s_waitcnt lgkmcnt(0)
	global_load_dword v0, v[14:15], off offset:1280 sc1
	global_load_dword v2, v[14:15], off offset:1536 sc1
	global_load_dword v3, v[14:15], off offset:1792 sc1
	global_load_dword v4, v[14:15], off offset:2048 sc1
	global_load_dword v5, v[14:15], off offset:2304 sc1
	global_load_dword v6, v[14:15], off offset:2560 sc1
	global_load_dword v7, v[14:15], off offset:2816 sc1
	global_load_dword v8, v[14:15], off offset:3072 sc1
	global_load_dword v9, v[14:15], off offset:3328 sc1
	global_load_dword v10, v[14:15], off offset:3584 sc1
	global_load_dword v11, v[14:15], off offset:3840 sc1
	v_mov_b64_e32 v[14:15], s[0:1]
	global_load_dword v13, v[14:15], off sc1
	v_mov_b64_e32 v[14:15], s[2:3]
	global_load_dword v14, v[14:15], off sc1
	v_mov_b64_e32 v[16:17], s[4:5]
	global_load_dword v15, v[16:17], off sc1
	v_mov_b64_e32 v[16:17], s[6:7]
	global_load_dword v16, v[16:17], off sc1
	v_readlane_b32 s18, v254, 5
	s_or_b64 s[14:15], s[14:15], exec
	s_or_b64 s[12:13], s[12:13], exec
	s_waitcnt vmcnt(0) lgkmcnt(0)
	v_add_u32_e32 v17, v0, v12
	v_add_u32_e32 v17, v17, v2
	v_add_u32_e32 v17, v17, v3
	v_add_u32_e32 v17, v17, v4
	v_add_u32_e32 v17, v17, v5
	v_add_u32_e32 v17, v17, v6
	v_add_u32_e32 v17, v17, v7
	v_add_u32_e32 v17, v17, v8
	v_add_u32_e32 v17, v17, v9
	v_add_u32_e32 v17, v17, v10
	v_add_u32_e32 v17, v17, v11
	v_add_u32_e32 v17, v17, v13
	v_add_u32_e32 v17, v17, v14
	v_add_u32_e32 v17, v17, v15
	v_add_u32_e32 v17, v17, v16
	v_cmp_ne_u32_e32 vcc, s18, v17
	s_and_saveexec_b64 s[18:19], vcc
	s_cbranch_execz .LBB0_577
	s_and_b32 s22, s28, 0xff
	s_mov_b64 s[20:21], -1
	s_cmp_eq_u32 s22, 0
	s_mov_b64 s[24:25], -1
	s_mov_b64 s[22:23], -1
	s_sleep 1
	s_cbranch_scc1 .LBB0_581
	s_and_saveexec_b64 s[26:27], s[24:25]
	s_cbranch_execz .LBB0_576
	s_branch .LBB0_584
.LBB0_581:
	v_mov_b64_e32 v[18:19], s[16:17]
	global_load_dword v17, v[18:19], off offset:512 sc1
	s_mov_b64 s[24:25], 0
	s_waitcnt vmcnt(0) lgkmcnt(0)
	v_cmp_eq_u32_e32 vcc, 0, v17
	s_and_saveexec_b64 s[26:27], vcc
	s_cmp_lt_u32 s28, 0x40001
	s_cselect_b64 s[24:25], -1, 0
	s_xor_b64 s[22:23], exec, -1
	s_and_b64 s[24:25], s[24:25], exec
	s_or_b64 exec, exec, s[26:27]
	s_and_saveexec_b64 s[26:27], s[24:25]
	s_cbranch_execz .LBB0_576

.LBB0_585:
	s_or_b64 exec, exec, s[8:9]
	s_xor_b64 s[0:1], s[10:11], -1
	s_and_saveexec_b64 s[2:3], s[0:1]
	s_xor_b64 s[0:1], exec, s[2:3]
	s_cbranch_execz .LBB0_587
	v_mov_b64_e32 v[18:19], s[16:17]
	global_atomic_add v[18:19], v203, off offset:512

.LBB0_588:
	s_lshl_b32 s0, s37, 8
	s_add_u32 s23, s16, s0
	s_addc_u32 s22, s17, 0
	v_mov_b32_e32 v3, s23
	v_add_co_u32_e32 v4, vcc, 0x1000, v3
	v_mov_b32_e32 v3, s22
	s_nop 0
	v_addc_co_u32_e32 v5, vcc, 0, v3, vcc
	global_atomic_add v4, v[4:5], v203, off offset:1024 sc0
	v_cvt_f32_u32_e32 v3, v2
	v_sub_u32_e32 v5, 0, v2
	v_rcp_iflag_f32_e32 v3, v3
	s_nop 0
	v_mul_f32_e32 v3, 0x4f7ffffe, v3
	v_cvt_u32_f32_e32 v3, v3
	v_mul_lo_u32 v5, v5, v3
	v_mul_hi_u32 v5, v3, v5
	v_add_u32_e32 v3, v3, v5
	s_waitcnt vmcnt(0) lgkmcnt(0)
	v_mul_hi_u32 v3, v4, v3
	v_mul_lo_u32 v5, v3, v2
	v_sub_u32_e32 v5, v4, v5
	v_cmp_ge_u32_e32 vcc, v5, v2
	v_add_u32_e32 v6, 1, v3
	s_nop 0
	v_cndmask_b32_e32 v3, v3, v6, vcc
	v_sub_u32_e32 v6, v5, v2
	v_cndmask_b32_e32 v5, v5, v6, vcc
	v_cmp_ge_u32_e32 vcc, v5, v2
	v_add_u32_e32 v5, 1, v3
	v_add_u32_e32 v6, 1, v4
	v_cndmask_b32_e32 v3, v3, v5, vcc
	v_mad_u64_u32 v[4:5], s[0:1], v2, v3, v[2:3]
	v_cmp_ne_u32_e32 vcc, v6, v4
	s_and_saveexec_b64 s[0:1], vcc
	s_xor_b64 s[0:1], exec, s[0:1]
	s_cbranch_execz .LBB0_601
	v_mov_b32_e32 v0, s23
	v_add_co_u32_e32 v4, vcc, 0x2000, v0
	v_mov_b32_e32 v0, s22
	s_nop 0
	v_addc_co_u32_e32 v5, vcc, 0, v0, vcc
	global_load_dword v0, v[4:5], off offset:1024 sc1
	s_add_u32 s4, s23, 0x2400
	s_addc_u32 s5, s22, 0
	s_waitcnt vmcnt(0) lgkmcnt(0)
	v_cmp_eq_u32_e32 vcc, v0, v3
	s_and_saveexec_b64 s[2:3], vcc
	s_cbranch_execz .LBB0_600
	s_mov_b32 s24, 1
	s_mov_b64 s[6:7], 0
	s_branch .LBB0_592

.LBB0_592:
	s_and_b32 s14, s24, 0xff
	s_mov_b64 s[12:13], -1
	s_cmp_lg_u32 s14, 0
	s_mov_b64 s[14:15], -1
	s_sleep 1
	s_cbranch_scc1 .LBB0_596
	v_mov_b64_e32 v[4:5], s[16:17]
	global_load_dword v0, v[4:5], off offset:512 sc1
	s_mov_b64 s[14:15], 0
	s_mov_b64 s[18:19], -1
	s_waitcnt vmcnt(0) lgkmcnt(0)
	v_cmp_eq_u32_e32 vcc, 0, v0
	s_and_saveexec_b64 s[20:21], vcc
	s_cmp_lt_u32 s24, 0x40001
	s_cselect_b64 s[14:15], -1, 0
	s_xor_b64 s[18:19], exec, -1
	s_and_b64 s[14:15], s[14:15], exec
	s_or_b64 exec, exec, s[20:21]

.LBB0_598:
	s_or_b64 exec, exec, s[6:7]
	s_xor_b64 s[4:5], s[8:9], -1
	s_and_saveexec_b64 s[6:7], s[4:5]
	s_xor_b64 s[6:7], exec, s[6:7]
	s_cbranch_execz .LBB0_600
	v_mov_b64_e32 v[2:3], s[16:17]
	global_atomic_add v[2:3], v203, off offset:512

.LBB0_601:
	s_andn2_saveexec_b64 s[0:1], s[0:1]
	s_cbranch_execz .LBB0_617
	v_mov_b32_e32 v2, s16
	v_add_co_u32_e32 v2, vcc, 0x3000, v2
	v_mov_b32_e32 v3, s17
	buffer_wbl2 sc1
	s_waitcnt vmcnt(0)
	v_addc_co_u32_e32 v3, vcc, 0, v3, vcc
	global_atomic_add v2, v[2:3], v203, off offset:1024 sc0
	v_cvt_f32_u32_e32 v3, v0
	v_sub_u32_e32 v4, 0, v0
	s_mov_b64 s[4:5], -1
	v_rcp_iflag_f32_e32 v3, v3
	s_nop 0
	v_mul_f32_e32 v3, 0x4f7ffffe, v3
	v_cvt_u32_f32_e32 v3, v3
	v_mul_lo_u32 v4, v4, v3
	v_mul_hi_u32 v4, v3, v4
	v_add_u32_e32 v3, v3, v4
	s_waitcnt vmcnt(0) lgkmcnt(0)
	v_mul_hi_u32 v3, v2, v3
	v_mul_lo_u32 v4, v3, v0
	v_sub_u32_e32 v4, v2, v4
	v_cmp_ge_u32_e32 vcc, v4, v0
	v_add_u32_e32 v5, 1, v3
	s_nop 0
	v_cndmask_b32_e32 v3, v3, v5, vcc
	v_sub_u32_e32 v5, v4, v0
	v_cndmask_b32_e32 v4, v4, v5, vcc
	v_cmp_ge_u32_e32 vcc, v4, v0
	v_add_u32_e32 v4, 1, v3
	v_add_u32_e32 v5, 1, v2
	v_cndmask_b32_e32 v4, v3, v4, vcc
	v_mad_u64_u32 v[2:3], s[0:1], v0, v4, v[0:1]
	s_add_u32 s0, s16, 0x3500
	s_addc_u32 s1, s17, 0
	v_cmp_ne_u32_e32 vcc, v5, v2
	v_mov_b64_e32 v[2:3], s[0:1]
	s_and_saveexec_b64 s[2:3], vcc
	s_cbranch_execz .LBB0_614
	v_mov_b64_e32 v[2:3], s[0:1]
	global_load_dword v0, v[2:3], off sc1
	s_mov_b64 s[8:9], 0
	s_waitcnt vmcnt(0) lgkmcnt(0)
	v_cmp_eq_u32_e32 vcc, v0, v4
	s_and_saveexec_b64 s[6:7], vcc
	s_cbranch_execz .LBB0_613
	s_add_u32 s4, s16, 0x200
	s_addc_u32 s5, s17, 0
	s_mov_b32 s20, 1
	s_branch .LBB0_606

.LBB0_608:
	v_mov_b64_e32 v[2:3], s[4:5]
	global_load_dword v0, v[2:3], off sc1
	s_mov_b64 s[16:17], 0
	s_mov_b64 s[14:15], -1
	s_waitcnt vmcnt(0) lgkmcnt(0)
	v_cmp_eq_u32_e32 vcc, 0, v0
	s_and_saveexec_b64 s[18:19], vcc
	s_cmp_lt_u32 s20, 0x40001
	s_cselect_b64 s[16:17], -1, 0
	s_xor_b64 s[14:15], exec, -1
	s_and_b64 s[16:17], s[16:17], exec
	s_or_b64 exec, exec, s[18:19]
	s_and_saveexec_b64 s[18:19], s[16:17]
	s_cbranch_execz .LBB0_605
.LBB0_611:
	v_mov_b64_e32 v[2:3], s[0:1]
	global_load_dword v0, v[2:3], off sc1
	s_add_i32 s20, s20, 1
	s_or_b64 s[14:15], s[14:15], exec
	s_waitcnt vmcnt(0) lgkmcnt(0)
	v_cmp_ne_u32_e32 vcc, v0, v4
	s_orn2_b64 s[12:13], vcc, exec
	s_branch .LBB0_605

.LBB0_621:
	v_mov_b32_e32 v0, v201
	s_barrier
	s_nop 0
	v_cmp_eq_u32_e32 vcc, 0, v0
	s_and_saveexec_b64 s[0:1], vcc
	s_cbranch_execz .LBB0_623
	v_mov_b64_e32 v[2:3], s[14:15]
	global_atomic_add v0, v[2:3], v203, off sc0
	s_waitcnt vmcnt(0) lgkmcnt(0)
	ds_write_b32 v1, v0 offset:208
.LBB0_623:
	s_or_b64 exec, exec, s[0:1]
	s_waitcnt lgkmcnt(0)
	s_barrier
	ds_read_b32 v0, v1 offset:208
	s_movk_i32 s0, 0x54f
	s_waitcnt lgkmcnt(0)
	v_cmp_lt_i32_e32 vcc, s0, v0
	s_mov_b64 s[0:1], -1
	s_cbranch_vccnz .LBB0_620
	v_mov_b32_e32 v2, v201
	s_mov_b32 s0, 0xd000
	v_ashrrev_i32_e32 v2, 8, v2
	v_mad_i32_i24 v174, v2, s0, v207
	v_lshl_add_u32 v0, v0, 1, v2
	s_movk_i32 s0, 0x87f
	v_cmp_lt_i32_e32 vcc, s0, v0
	s_and_saveexec_b64 s[0:1], vcc
	s_xor_b64 s[44:45], exec, s[0:1]
	s_cbranch_execz .LBB0_709
	v_add_u32_e32 v0, 0xfffff780, v0
	s_mov_b32 s0, 0xf0f0f0f1
	v_mul_hi_u32 v2, v0, s0
	v_lshrrev_b32_e32 v32, 6, v2
	s_movk_i32 s0, 0x44
	v_mul_lo_u32 v2, v32, s0
	v_sub_u32_e32 v33, v0, v2
	s_movk_i32 s0, 0x1100
	v_mul_lo_u32 v35, v32, s0
	v_lshlrev_b32_e32 v34, 6, v33
	v_mov_b32_e32 v37, v201
	v_add_u32_e32 v36, v35, v34
	v_mov_b64_e32 v[2:3], s[20:21]
	v_bfe_u32 v41, v37, 2, 6
	v_lshlrev_b32_sdwa v38, v198, v37 dst_sel:DWORD dst_unused:UNUSED_PAD src0_sel:DWORD src1_sel:BYTE_0
	v_and_b32_e32 v8, 24, v38
	v_or_b32_e32 v0, v41, v36
	v_mad_u64_u32 v[4:5], s[0:1], v0, s83, v[2:3]
	v_lshlrev_b32_e32 v2, 1, v8
	v_mov_b32_e32 v3, v1
	v_lshl_add_u64 v[6:7], v[4:5], 0, v[2:3]
	global_load_dwordx4 v[12:15], v[6:7], off offset:1568
	global_load_dwordx4 v[16:19], v[6:7], off offset:1632
	v_mov_b32_e32 v5, v1
	v_lshlrev_b32_e32 v4, 2, v8
	v_lshl_add_u64 v[10:11], s[22:23], 0, v[4:5]
	global_load_dwordx4 v[20:23], v[10:11], off
	global_load_dwordx4 v[24:27], v[10:11], off offset:128
	global_load_dwordx4 v[28:31], v[10:11], off offset:16
	global_load_dwordx4 v[42:45], v[10:11], off offset:144
	v_and_b32_e32 v9, 64, v208
	v_xor_b32_e32 v8, 1, v208
	v_add_u32_e32 v40, 64, v9
	v_cmp_lt_i32_e32 vcc, v8, v40
	v_or_b32_e32 v60, v41, v34
	v_cmp_gt_u32_e64 s[0:1], 4, v33
	v_cndmask_b32_e32 v8, v208, v8, vcc
	v_lshlrev_b32_e32 v39, 2, v8
	v_cmp_lt_u32_e64 s[2:3], 3, v33
	s_waitcnt vmcnt(0) lgkmcnt(0)
	v_lshlrev_b32_e32 v8, 16, v12
	v_lshlrev_b32_e32 v48, 16, v16
	v_and_b32_e32 v49, 0xffff0000, v16
	v_and_b32_e32 v9, 0xffff0000, v12
	v_lshlrev_b32_e32 v16, 16, v17
	v_and_b32_e32 v17, 0xffff0000, v17
	v_pk_mul_f32 v[56:57], v[48:49], v[48:49]
	v_lshlrev_b32_e32 v12, 16, v13
	v_and_b32_e32 v13, 0xffff0000, v13
	v_pk_mul_f32 v[54:55], v[16:17], v[16:17]
	v_pk_fma_f32 v[56:57], v[8:9], v[8:9], v[56:57]
	v_lshlrev_b32_e32 v50, 16, v18
	v_and_b32_e32 v51, 0xffff0000, v18
	v_pk_fma_f32 v[54:55], v[12:13], v[12:13], v[54:55]
	v_add_f32_e32 v56, v56, v57
	v_lshlrev_b32_e32 v46, 16, v14
	v_and_b32_e32 v47, 0xffff0000, v14
	v_pk_mul_f32 v[52:53], v[50:51], v[50:51]
	v_add_f32_e32 v54, v56, v54
	v_lshlrev_b32_e32 v18, 16, v19
	v_and_b32_e32 v19, 0xffff0000, v19
	v_pk_fma_f32 v[52:53], v[46:47], v[46:47], v[52:53]
	v_add_f32_e32 v54, v55, v54
	v_lshlrev_b32_e32 v14, 16, v15
	v_and_b32_e32 v15, 0xffff0000, v15
	v_pk_mul_f32 v[58:59], v[18:19], v[18:19]
	v_add_f32_e32 v52, v52, v54
	v_pk_fma_f32 v[58:59], v[14:15], v[14:15], v[58:59]
	v_add_f32_e32 v52, v53, v52
	v_add_f32_e32 v52, v58, v52
	v_add_f32_e32 v52, v59, v52
	ds_bpermute_b32 v53, v39, v52
	v_xor_b32_e32 v54, 2, v208
	v_cmp_lt_i32_e32 vcc, v54, v40
	s_waitcnt lgkmcnt(0)
	v_add_f32_e32 v52, v52, v53
	v_cndmask_b32_e32 v40, v208, v54, vcc
	v_lshlrev_b32_e32 v40, 2, v40
	ds_bpermute_b32 v53, v40, v52
	s_waitcnt lgkmcnt(0)
	v_add_f32_e32 v52, v52, v53
	v_fmamk_f32 v52, v52, 0x3c800000, v206
	v_mul_f32_e32 v53, 0x4b800000, v52
	v_cmp_gt_f32_e32 vcc, s35, v52
	s_nop 1
	v_cndmask_b32_e32 v52, v52, v53, vcc
	v_rsq_f32_e32 v52, v52
	s_nop 0
	v_mul_f32_e32 v53, 0x45800000, v52
	v_cndmask_b32_e32 v52, v52, v53, vcc
	v_pk_mul_f32 v[8:9], v[52:53], v[8:9] op_sel_hi:[0,1]
	v_pk_mul_f32 v[48:49], v[52:53], v[48:49] op_sel_hi:[0,1]
	v_pk_mul_f32 v[54:55], v[52:53], v[12:13] op_sel_hi:[0,1]
	v_pk_mul_f32 v[56:57], v[52:53], v[16:17] op_sel_hi:[0,1]
	v_pk_mul_f32 v[46:47], v[52:53], v[46:47] op_sel_hi:[0,1]
	v_pk_mul_f32 v[50:51], v[52:53], v[50:51] op_sel_hi:[0,1]
	v_pk_mul_f32 v[58:59], v[52:53], v[14:15] op_sel_hi:[0,1]
	v_pk_mul_f32 v[52:53], v[52:53], v[18:19] op_sel_hi:[0,1]
	v_pk_mul_f32 v[16:17], v[20:21], v[8:9]
	v_pk_mul_f32 v[12:13], v[24:25], v[48:49]
	v_pk_mul_f32 v[20:21], v[22:23], v[54:55]
	v_pk_mul_f32 v[14:15], v[26:27], v[56:57]
	v_pk_mul_f32 v[24:25], v[28:29], v[46:47]
	v_pk_mul_f32 v[18:19], v[42:43], v[50:51]
	v_pk_mul_f32 v[26:27], v[30:31], v[58:59]
	v_pk_mul_f32 v[22:23], v[44:45], v[52:53]
	v_lshlrev_b32_e32 v8, 5, v60
	s_and_saveexec_b64 s[4:5], s[2:3]
	s_cbranch_execz .LBB0_627
	v_mov_b32_e32 v9, v1
	v_lshl_add_u64 v[28:29], v[8:9], 2, s[64:65]
	v_lshl_add_u64 v[30:31], s[24:25], 0, v[28:29]
	v_lshl_add_u64 v[46:47], v[30:31], 0, v[4:5]
	v_lshl_add_u64 v[28:29], s[26:27], 0, v[28:29]
	v_lshl_add_u64 v[48:49], v[28:29], 0, v[4:5]
	global_load_dwordx4 v[28:31], v[46:47], off
	global_load_dwordx4 v[42:45], v[48:49], off
	s_waitcnt vmcnt(0) lgkmcnt(0)
	v_pk_mul_f32 v[50:51], v[16:17], v[42:43]
	v_pk_mul_f32 v[42:43], v[12:13], v[42:43]
	v_pk_fma_f32 v[12:13], v[12:13], v[28:29], v[50:51]
	v_pk_fma_f32 v[16:17], v[16:17], v[28:29], v[42:43] neg_lo:[0,0,1] neg_hi:[0,0,1]
	v_pk_mul_f32 v[28:29], v[20:21], v[44:45]
	v_pk_mul_f32 v[42:43], v[14:15], v[44:45]
	v_pk_fma_f32 v[14:15], v[14:15], v[30:31], v[28:29]
	v_pk_fma_f32 v[20:21], v[20:21], v[30:31], v[42:43] neg_lo:[0,0,1] neg_hi:[0,0,1]
	global_load_dwordx4 v[28:31], v[46:47], off offset:16
	global_load_dwordx4 v[42:45], v[48:49], off offset:16
	s_waitcnt vmcnt(0) lgkmcnt(0)
	v_pk_mul_f32 v[46:47], v[24:25], v[42:43]
	v_pk_mul_f32 v[42:43], v[18:19], v[42:43]
	v_pk_fma_f32 v[18:19], v[18:19], v[28:29], v[46:47]
	v_pk_fma_f32 v[24:25], v[24:25], v[28:29], v[42:43] neg_lo:[0,0,1] neg_hi:[0,0,1]
	v_pk_mul_f32 v[28:29], v[26:27], v[44:45]
	v_pk_mul_f32 v[42:43], v[22:23], v[44:45]
	v_pk_fma_f32 v[22:23], v[22:23], v[30:31], v[28:29]
	v_pk_fma_f32 v[26:27], v[26:27], v[30:31], v[42:43] neg_lo:[0,0,1] neg_hi:[0,0,1]
.LBB0_627:
	s_or_b64 exec, exec, s[4:5]
	global_load_dwordx4 v[28:31], v[6:7], off offset:1696
	global_load_dwordx4 v[42:45], v[6:7], off offset:1760
	v_pk_mul_f32 v[46:47], v[12:13], s[66:67] op_sel_hi:[1,0]
	v_lshlrev_b64 v[12:13], 9, v[0:1]
	v_pk_mul_f32 v[26:27], v[26:27], s[66:67] op_sel_hi:[1,0]
	v_pk_mul_f32 v[24:25], v[24:25], s[66:67] op_sel_hi:[1,0]
	v_pk_mul_f32 v[20:21], v[20:21], s[66:67] op_sel_hi:[1,0]
	v_pk_mul_f32 v[16:17], v[16:17], s[66:67] op_sel_hi:[1,0]
	v_pk_mul_f32 v[22:23], v[22:23], s[66:67] op_sel_hi:[1,0]
	v_lshl_add_u64 v[52:53], s[28:29], 0, v[12:13]
	v_pk_mul_f32 v[48:49], v[14:15], s[66:67] op_sel_hi:[1,0]
	v_pk_mul_f32 v[50:51], v[18:19], s[66:67] op_sel_hi:[1,0]
	v_cvt_pk_bf16_f32 v14, v16, v17
	v_cvt_pk_bf16_f32 v15, v20, v21
	v_cvt_pk_bf16_f32 v16, v24, v25
	v_cvt_pk_bf16_f32 v17, v26, v27
	v_cvt_pk_bf16_f32 v21, v22, v23
	v_lshl_add_u64 v[22:23], v[52:53], 0, v[2:3]
	v_cvt_pk_bf16_f32 v18, v46, v47
	v_cvt_pk_bf16_f32 v19, v48, v49
	v_cvt_pk_bf16_f32 v20, v50, v51
	global_store_dwordx4 v[22:23], v[14:17], off
	global_store_dwordx4 v[22:23], v[18:21], off offset:64
	global_load_dwordx4 v[14:17], v[10:11], off
	s_nop 0
	global_load_dwordx4 v[22:25], v[10:11], off offset:128
	global_load_dwordx4 v[46:49], v[10:11], off offset:16
	global_load_dwordx4 v[50:53], v[10:11], off offset:144
	s_waitcnt vmcnt(0) lgkmcnt(0)
	v_lshlrev_b32_e32 v18, 16, v28
	v_and_b32_e32 v19, 0xffff0000, v28
	v_lshlrev_b32_e32 v20, 16, v29
	v_and_b32_e32 v21, 0xffff0000, v29
	v_lshlrev_b32_e32 v26, 16, v30
	v_and_b32_e32 v27, 0xffff0000, v30
	v_lshlrev_b32_e32 v28, 16, v31
	v_and_b32_e32 v29, 0xffff0000, v31
	v_lshlrev_b32_e32 v30, 16, v42
	v_and_b32_e32 v31, 0xffff0000, v42
	v_lshlrev_b32_e32 v42, 16, v43
	v_and_b32_e32 v43, 0xffff0000, v43
	v_pk_mul_f32 v[60:61], v[30:31], v[30:31]
	v_pk_mul_f32 v[58:59], v[42:43], v[42:43]
	v_pk_fma_f32 v[60:61], v[18:19], v[18:19], v[60:61]
	v_lshlrev_b32_e32 v54, 16, v44
	v_and_b32_e32 v55, 0xffff0000, v44
	v_pk_fma_f32 v[58:59], v[20:21], v[20:21], v[58:59]
	v_add_f32_e32 v3, v60, v61
	v_pk_mul_f32 v[56:57], v[54:55], v[54:55]
	v_add_f32_e32 v3, v3, v58
	v_lshlrev_b32_e32 v44, 16, v45
	v_and_b32_e32 v45, 0xffff0000, v45
	v_pk_fma_f32 v[56:57], v[26:27], v[26:27], v[56:57]
	v_add_f32_e32 v3, v59, v3
	v_pk_mul_f32 v[62:63], v[44:45], v[44:45]
	v_add_f32_e32 v3, v56, v3
	v_pk_fma_f32 v[62:63], v[28:29], v[28:29], v[62:63]
	v_add_f32_e32 v3, v57, v3
	v_add_f32_e32 v3, v62, v3
	v_add_f32_e32 v3, v63, v3
	ds_bpermute_b32 v5, v39, v3
	s_waitcnt lgkmcnt(0)
	v_add_f32_e32 v3, v3, v5
	ds_bpermute_b32 v5, v40, v3
	s_waitcnt lgkmcnt(0)
	v_add_f32_e32 v3, v3, v5
	v_fmamk_f32 v3, v3, 0x3c800000, v206
	v_mul_f32_e32 v5, 0x4b800000, v3
	v_cmp_gt_f32_e32 vcc, s35, v3
	s_nop 1
	v_cndmask_b32_e32 v3, v3, v5, vcc
	v_rsq_f32_e32 v3, v3
	s_nop 0
	v_mul_f32_e32 v5, 0x45800000, v3
	v_cndmask_b32_e32 v56, v3, v5, vcc
	v_pk_mul_f32 v[18:19], v[56:57], v[18:19] op_sel_hi:[0,1]
	v_pk_mul_f32 v[30:31], v[56:57], v[30:31] op_sel_hi:[0,1]
	v_pk_mul_f32 v[20:21], v[56:57], v[20:21] op_sel_hi:[0,1]
	v_pk_mul_f32 v[42:43], v[56:57], v[42:43] op_sel_hi:[0,1]
	v_pk_mul_f32 v[26:27], v[56:57], v[26:27] op_sel_hi:[0,1]
	v_pk_mul_f32 v[54:55], v[56:57], v[54:55] op_sel_hi:[0,1]
	v_pk_mul_f32 v[28:29], v[56:57], v[28:29] op_sel_hi:[0,1]
	v_pk_mul_f32 v[44:45], v[56:57], v[44:45] op_sel_hi:[0,1]
	v_pk_mul_f32 v[18:19], v[14:15], v[18:19]
	v_pk_mul_f32 v[14:15], v[22:23], v[30:31]
	v_pk_mul_f32 v[22:23], v[16:17], v[20:21]
	v_pk_mul_f32 v[16:17], v[24:25], v[42:43]
	v_pk_mul_f32 v[26:27], v[46:47], v[26:27]
	v_pk_mul_f32 v[20:21], v[50:51], v[54:55]
	v_pk_mul_f32 v[28:29], v[48:49], v[28:29]
	v_pk_mul_f32 v[24:25], v[52:53], v[44:45]
	s_and_saveexec_b64 s[4:5], s[2:3]
	s_cbranch_execz .LBB0_629
	v_mov_b32_e32 v9, v1
	v_lshl_add_u64 v[30:31], v[8:9], 2, s[64:65]
	v_lshl_add_u64 v[42:43], s[24:25], 0, v[30:31]
	v_mov_b32_e32 v5, v1
	v_lshl_add_u64 v[50:51], v[42:43], 0, v[4:5]
	v_lshl_add_u64 v[30:31], s[26:27], 0, v[30:31]
	v_lshl_add_u64 v[30:31], v[30:31], 0, v[4:5]
	global_load_dwordx4 v[42:45], v[50:51], off
	global_load_dwordx4 v[46:49], v[30:31], off
	s_waitcnt vmcnt(0) lgkmcnt(0)
	v_pk_mul_f32 v[52:53], v[18:19], v[46:47]
	v_pk_mul_f32 v[46:47], v[14:15], v[46:47]
	v_pk_fma_f32 v[14:15], v[14:15], v[42:43], v[52:53]
	v_pk_fma_f32 v[18:19], v[18:19], v[42:43], v[46:47] neg_lo:[0,0,1] neg_hi:[0,0,1]
	v_pk_mul_f32 v[42:43], v[22:23], v[48:49]
	v_pk_mul_f32 v[46:47], v[16:17], v[48:49]
	v_pk_fma_f32 v[16:17], v[16:17], v[44:45], v[42:43]
	v_pk_fma_f32 v[22:23], v[22:23], v[44:45], v[46:47] neg_lo:[0,0,1] neg_hi:[0,0,1]
	global_load_dwordx4 v[42:45], v[50:51], off offset:16
	global_load_dwordx4 v[46:49], v[30:31], off offset:16
	s_waitcnt vmcnt(0) lgkmcnt(0)
	v_pk_mul_f32 v[30:31], v[26:27], v[46:47]
	v_pk_mul_f32 v[46:47], v[20:21], v[46:47]
	v_pk_fma_f32 v[20:21], v[20:21], v[42:43], v[30:31]
	v_pk_fma_f32 v[26:27], v[26:27], v[42:43], v[46:47] neg_lo:[0,0,1] neg_hi:[0,0,1]
	v_pk_mul_f32 v[30:31], v[28:29], v[48:49]
	v_pk_mul_f32 v[42:43], v[24:25], v[48:49]
	v_pk_fma_f32 v[24:25], v[24:25], v[44:45], v[30:31]
	v_pk_fma_f32 v[28:29], v[28:29], v[44:45], v[42:43] neg_lo:[0,0,1] neg_hi:[0,0,1]
.LBB0_629:
	s_or_b64 exec, exec, s[4:5]
	v_lshl_add_u64 v[12:13], s[12:13], 0, v[12:13]
	v_mov_b32_e32 v3, v1
	v_pk_mul_f32 v[30:31], v[14:15], s[66:67] op_sel_hi:[1,0]
	v_lshl_add_u64 v[14:15], v[12:13], 0, v[2:3]
	s_mov_b32 s4, 0xa80000
	v_pk_mul_f32 v[28:29], v[28:29], s[66:67] op_sel_hi:[1,0]
	v_pk_mul_f32 v[26:27], v[26:27], s[66:67] op_sel_hi:[1,0]
	v_pk_mul_f32 v[22:23], v[22:23], s[66:67] op_sel_hi:[1,0]
	v_pk_mul_f32 v[18:19], v[18:19], s[66:67] op_sel_hi:[1,0]
	v_add_co_u32_e32 v14, vcc, s4, v14
	v_pk_mul_f32 v[24:25], v[24:25], s[66:67] op_sel_hi:[1,0]
	v_pk_mul_f32 v[42:43], v[16:17], s[66:67] op_sel_hi:[1,0]
	v_pk_mul_f32 v[20:21], v[20:21], s[66:67] op_sel_hi:[1,0]
	v_cvt_pk_bf16_f32 v16, v18, v19
	v_cvt_pk_bf16_f32 v17, v22, v23
	v_cvt_pk_bf16_f32 v18, v26, v27
	v_cvt_pk_bf16_f32 v19, v28, v29
	v_addc_co_u32_e32 v15, vcc, 0, v15, vcc
	global_store_dwordx4 v[14:15], v[16:19], off offset:128
	s_nop 1
	v_cvt_pk_bf16_f32 v16, v30, v31
	v_cvt_pk_bf16_f32 v17, v42, v43
	v_cvt_pk_bf16_f32 v18, v20, v21
	v_cvt_pk_bf16_f32 v19, v24, v25
	global_store_dwordx4 v[14:15], v[16:19], off offset:192
	global_load_dwordx4 v[16:19], v[6:7], off offset:1824
	s_nop 0
	global_load_dwordx4 v[20:23], v[6:7], off offset:1888
	global_load_dwordx4 v[24:27], v[10:11], off
	global_load_dwordx4 v[28:31], v[10:11], off offset:128
	global_load_dwordx4 v[42:45], v[10:11], off offset:16
	global_load_dwordx4 v[46:49], v[10:11], off offset:144
	s_waitcnt vmcnt(0) lgkmcnt(0)
	v_lshlrev_b32_e32 v50, 16, v16
	v_lshlrev_b32_e32 v54, 16, v20
	v_and_b32_e32 v55, 0xffff0000, v20
	v_and_b32_e32 v51, 0xffff0000, v16
	v_lshlrev_b32_e32 v20, 16, v21
	v_and_b32_e32 v21, 0xffff0000, v21
	v_pk_mul_f32 v[62:63], v[54:55], v[54:55]
	v_lshlrev_b32_e32 v16, 16, v17
	v_and_b32_e32 v17, 0xffff0000, v17
	v_pk_mul_f32 v[60:61], v[20:21], v[20:21]
	v_pk_fma_f32 v[62:63], v[50:51], v[50:51], v[62:63]
	v_lshlrev_b32_e32 v56, 16, v22
	v_and_b32_e32 v57, 0xffff0000, v22
	v_pk_fma_f32 v[60:61], v[16:17], v[16:17], v[60:61]
	v_add_f32_e32 v3, v62, v63
	v_lshlrev_b32_e32 v52, 16, v18
	v_and_b32_e32 v53, 0xffff0000, v18
	v_pk_mul_f32 v[58:59], v[56:57], v[56:57]
	v_add_f32_e32 v3, v3, v60
	v_lshlrev_b32_e32 v22, 16, v23
	v_and_b32_e32 v23, 0xffff0000, v23
	v_pk_fma_f32 v[58:59], v[52:53], v[52:53], v[58:59]
	v_add_f32_e32 v3, v61, v3
	v_lshlrev_b32_e32 v18, 16, v19
	v_and_b32_e32 v19, 0xffff0000, v19
	v_pk_mul_f32 v[64:65], v[22:23], v[22:23]
	v_add_f32_e32 v3, v58, v3
	v_pk_fma_f32 v[64:65], v[18:19], v[18:19], v[64:65]
	v_add_f32_e32 v3, v59, v3
	v_add_f32_e32 v3, v64, v3
	v_add_f32_e32 v3, v65, v3
	ds_bpermute_b32 v5, v39, v3
	s_waitcnt lgkmcnt(0)
	v_add_f32_e32 v3, v3, v5
	ds_bpermute_b32 v5, v40, v3
	s_waitcnt lgkmcnt(0)
	v_add_f32_e32 v3, v3, v5
	v_fmamk_f32 v3, v3, 0x3c800000, v206
	v_mul_f32_e32 v5, 0x4b800000, v3
	v_cmp_gt_f32_e32 vcc, s35, v3
	s_nop 1
	v_cndmask_b32_e32 v3, v3, v5, vcc
	v_rsq_f32_e32 v3, v3
	s_nop 0
	v_mul_f32_e32 v5, 0x45800000, v3
	v_cndmask_b32_e32 v58, v3, v5, vcc
	v_pk_mul_f32 v[50:51], v[58:59], v[50:51] op_sel_hi:[0,1]
	v_pk_mul_f32 v[54:55], v[58:59], v[54:55] op_sel_hi:[0,1]
	v_pk_mul_f32 v[60:61], v[58:59], v[16:17] op_sel_hi:[0,1]
	v_pk_mul_f32 v[62:63], v[58:59], v[20:21] op_sel_hi:[0,1]
	v_pk_mul_f32 v[52:53], v[58:59], v[52:53] op_sel_hi:[0,1]
	v_pk_mul_f32 v[56:57], v[58:59], v[56:57] op_sel_hi:[0,1]
	v_pk_mul_f32 v[64:65], v[58:59], v[18:19] op_sel_hi:[0,1]
	v_pk_mul_f32 v[58:59], v[58:59], v[22:23] op_sel_hi:[0,1]
	v_pk_mul_f32 v[20:21], v[24:25], v[50:51]
	v_pk_mul_f32 v[16:17], v[28:29], v[54:55]
	v_pk_mul_f32 v[24:25], v[26:27], v[60:61]
	v_pk_mul_f32 v[18:19], v[30:31], v[62:63]
	v_pk_mul_f32 v[28:29], v[42:43], v[52:53]
	v_pk_mul_f32 v[22:23], v[46:47], v[56:57]
	v_pk_mul_f32 v[30:31], v[44:45], v[64:65]
	v_pk_mul_f32 v[26:27], v[48:49], v[58:59]
	s_and_saveexec_b64 s[4:5], s[2:3]
	s_cbranch_execz .LBB0_631
	v_mov_b32_e32 v9, v1
	v_lshl_add_u64 v[42:43], v[8:9], 2, s[64:65]
	v_lshl_add_u64 v[44:45], s[24:25], 0, v[42:43]
	v_mov_b32_e32 v5, v1
	v_lshl_add_u64 v[50:51], v[44:45], 0, v[4:5]
	v_lshl_add_u64 v[42:43], s[26:27], 0, v[42:43]
	v_lshl_add_u64 v[52:53], v[42:43], 0, v[4:5]
	global_load_dwordx4 v[42:45], v[50:51], off
	global_load_dwordx4 v[46:49], v[52:53], off
	s_waitcnt vmcnt(0) lgkmcnt(0)
	v_pk_mul_f32 v[54:55], v[20:21], v[46:47]
	v_pk_mul_f32 v[46:47], v[16:17], v[46:47]
	v_pk_fma_f32 v[16:17], v[16:17], v[42:43], v[54:55]
	v_pk_fma_f32 v[20:21], v[20:21], v[42:43], v[46:47] neg_lo:[0,0,1] neg_hi:[0,0,1]
	v_pk_mul_f32 v[42:43], v[24:25], v[48:49]
	v_pk_mul_f32 v[46:47], v[18:19], v[48:49]
	v_pk_fma_f32 v[18:19], v[18:19], v[44:45], v[42:43]
	v_pk_fma_f32 v[24:25], v[24:25], v[44:45], v[46:47] neg_lo:[0,0,1] neg_hi:[0,0,1]
	global_load_dwordx4 v[42:45], v[50:51], off offset:16
	global_load_dwordx4 v[46:49], v[52:53], off offset:16
	s_waitcnt vmcnt(0) lgkmcnt(0)
	v_pk_mul_f32 v[50:51], v[28:29], v[46:47]
	v_pk_mul_f32 v[46:47], v[22:23], v[46:47]
	v_pk_fma_f32 v[22:23], v[22:23], v[42:43], v[50:51]
	v_pk_fma_f32 v[28:29], v[28:29], v[42:43], v[46:47] neg_lo:[0,0,1] neg_hi:[0,0,1]
	v_pk_mul_f32 v[42:43], v[30:31], v[48:49]
	v_pk_mul_f32 v[46:47], v[26:27], v[48:49]
	v_pk_fma_f32 v[26:27], v[26:27], v[44:45], v[42:43]
	v_pk_fma_f32 v[30:31], v[30:31], v[44:45], v[46:47] neg_lo:[0,0,1] neg_hi:[0,0,1]
.LBB0_631:
	s_or_b64 exec, exec, s[4:5]
	v_pk_mul_f32 v[30:31], v[30:31], s[66:67] op_sel_hi:[1,0]
	v_pk_mul_f32 v[28:29], v[28:29], s[66:67] op_sel_hi:[1,0]
	v_pk_mul_f32 v[24:25], v[24:25], s[66:67] op_sel_hi:[1,0]
	v_pk_mul_f32 v[20:21], v[20:21], s[66:67] op_sel_hi:[1,0]
	v_pk_mul_f32 v[26:27], v[26:27], s[66:67] op_sel_hi:[1,0]
	v_pk_mul_f32 v[42:43], v[16:17], s[66:67] op_sel_hi:[1,0]
	v_pk_mul_f32 v[44:45], v[18:19], s[66:67] op_sel_hi:[1,0]
	v_pk_mul_f32 v[22:23], v[22:23], s[66:67] op_sel_hi:[1,0]
	v_cvt_pk_bf16_f32 v16, v20, v21
	v_cvt_pk_bf16_f32 v17, v24, v25
	v_cvt_pk_bf16_f32 v18, v28, v29
	v_cvt_pk_bf16_f32 v19, v30, v31
	global_store_dwordx4 v[14:15], v[16:19], off offset:256
	s_nop 1
	v_cvt_pk_bf16_f32 v16, v42, v43
	v_cvt_pk_bf16_f32 v17, v44, v45
	v_cvt_pk_bf16_f32 v18, v22, v23
	v_cvt_pk_bf16_f32 v19, v26, v27
	global_store_dwordx4 v[14:15], v[16:19], off offset:320
	global_load_dwordx4 v[14:17], v[6:7], off offset:1952
	s_nop 0
	global_load_dwordx4 v[18:21], v[6:7], off offset:2016
	global_load_dwordx4 v[22:25], v[10:11], off
	global_load_dwordx4 v[26:29], v[10:11], off offset:128
	global_load_dwordx4 v[42:45], v[10:11], off offset:16
	global_load_dwordx4 v[46:49], v[10:11], off offset:144
	s_waitcnt vmcnt(0) lgkmcnt(0)
	v_lshlrev_b32_e32 v10, 16, v14
	v_lshlrev_b32_e32 v50, 16, v18
	v_and_b32_e32 v51, 0xffff0000, v18
	v_and_b32_e32 v11, 0xffff0000, v14
	v_lshlrev_b32_e32 v18, 16, v19
	v_and_b32_e32 v19, 0xffff0000, v19
	v_pk_mul_f32 v[58:59], v[50:51], v[50:51]
	v_lshlrev_b32_e32 v14, 16, v15
	v_and_b32_e32 v15, 0xffff0000, v15
	v_pk_mul_f32 v[56:57], v[18:19], v[18:19]
	v_pk_fma_f32 v[58:59], v[10:11], v[10:11], v[58:59]
	v_lshlrev_b32_e32 v52, 16, v20
	v_and_b32_e32 v53, 0xffff0000, v20
	v_pk_fma_f32 v[56:57], v[14:15], v[14:15], v[56:57]
	v_add_f32_e32 v3, v58, v59
	v_lshlrev_b32_e32 v30, 16, v16
	v_and_b32_e32 v31, 0xffff0000, v16
	v_pk_mul_f32 v[54:55], v[52:53], v[52:53]
	v_add_f32_e32 v3, v3, v56
	v_lshlrev_b32_e32 v20, 16, v21
	v_and_b32_e32 v21, 0xffff0000, v21
	v_pk_fma_f32 v[54:55], v[30:31], v[30:31], v[54:55]
	v_add_f32_e32 v3, v57, v3
	v_lshlrev_b32_e32 v16, 16, v17
	v_and_b32_e32 v17, 0xffff0000, v17
	v_pk_mul_f32 v[60:61], v[20:21], v[20:21]
	v_add_f32_e32 v3, v54, v3
	v_pk_fma_f32 v[60:61], v[16:17], v[16:17], v[60:61]
	v_add_f32_e32 v3, v55, v3
	v_add_f32_e32 v3, v60, v3
	v_add_f32_e32 v3, v61, v3
	ds_bpermute_b32 v5, v39, v3
	s_waitcnt lgkmcnt(0)
	v_add_f32_e32 v3, v3, v5
	ds_bpermute_b32 v5, v40, v3
	s_waitcnt lgkmcnt(0)
	v_add_f32_e32 v3, v3, v5
	v_fmamk_f32 v3, v3, 0x3c800000, v206
	v_mul_f32_e32 v5, 0x4b800000, v3
	v_cmp_gt_f32_e32 vcc, s35, v3
	s_nop 1
	v_cndmask_b32_e32 v3, v3, v5, vcc
	v_rsq_f32_e32 v3, v3
	s_nop 0
	v_mul_f32_e32 v5, 0x45800000, v3
	v_cndmask_b32_e32 v54, v3, v5, vcc
	v_pk_mul_f32 v[10:11], v[54:55], v[10:11] op_sel_hi:[0,1]
	v_pk_mul_f32 v[50:51], v[54:55], v[50:51] op_sel_hi:[0,1]
	v_pk_mul_f32 v[14:15], v[54:55], v[14:15] op_sel_hi:[0,1]
	v_pk_mul_f32 v[18:19], v[54:55], v[18:19] op_sel_hi:[0,1]
	v_pk_mul_f32 v[30:31], v[54:55], v[30:31] op_sel_hi:[0,1]
	v_pk_mul_f32 v[52:53], v[54:55], v[52:53] op_sel_hi:[0,1]
	v_pk_mul_f32 v[56:57], v[54:55], v[16:17] op_sel_hi:[0,1]
	v_pk_mul_f32 v[54:55], v[54:55], v[20:21] op_sel_hi:[0,1]
	v_pk_mul_f32 v[16:17], v[22:23], v[10:11]
	v_pk_mul_f32 v[10:11], v[26:27], v[50:51]
	v_pk_mul_f32 v[20:21], v[24:25], v[14:15]
	v_pk_mul_f32 v[14:15], v[28:29], v[18:19]
	v_pk_mul_f32 v[24:25], v[42:43], v[30:31]
	v_pk_mul_f32 v[18:19], v[46:47], v[52:53]
	v_pk_mul_f32 v[26:27], v[44:45], v[56:57]
	v_pk_mul_f32 v[22:23], v[48:49], v[54:55]
	s_and_saveexec_b64 s[4:5], s[2:3]
	s_cbranch_execz .LBB0_633
	v_mov_b32_e32 v9, v1
	v_lshl_add_u64 v[28:29], v[8:9], 2, s[64:65]
	v_lshl_add_u64 v[30:31], s[24:25], 0, v[28:29]
	v_mov_b32_e32 v5, v1
	v_lshl_add_u64 v[46:47], v[30:31], 0, v[4:5]
	v_lshl_add_u64 v[28:29], s[26:27], 0, v[28:29]
	v_lshl_add_u64 v[48:49], v[28:29], 0, v[4:5]
	global_load_dwordx4 v[28:31], v[46:47], off
	global_load_dwordx4 v[42:45], v[48:49], off
	s_waitcnt vmcnt(0) lgkmcnt(0)
	v_pk_mul_f32 v[50:51], v[16:17], v[42:43]
	v_pk_mul_f32 v[42:43], v[10:11], v[42:43]
	v_pk_fma_f32 v[10:11], v[10:11], v[28:29], v[50:51]
	v_pk_fma_f32 v[16:17], v[16:17], v[28:29], v[42:43] neg_lo:[0,0,1] neg_hi:[0,0,1]
	v_pk_mul_f32 v[28:29], v[20:21], v[44:45]
	v_pk_mul_f32 v[42:43], v[14:15], v[44:45]
	v_pk_fma_f32 v[14:15], v[14:15], v[30:31], v[28:29]
	v_pk_fma_f32 v[20:21], v[20:21], v[30:31], v[42:43] neg_lo:[0,0,1] neg_hi:[0,0,1]
	global_load_dwordx4 v[28:31], v[46:47], off offset:16
	global_load_dwordx4 v[42:45], v[48:49], off offset:16
	s_waitcnt vmcnt(0) lgkmcnt(0)
	v_pk_mul_f32 v[46:47], v[24:25], v[42:43]
	v_pk_mul_f32 v[42:43], v[18:19], v[42:43]
	v_pk_fma_f32 v[18:19], v[18:19], v[28:29], v[46:47]
	v_pk_fma_f32 v[24:25], v[24:25], v[28:29], v[42:43] neg_lo:[0,0,1] neg_hi:[0,0,1]
	v_pk_mul_f32 v[28:29], v[26:27], v[44:45]
	v_pk_mul_f32 v[42:43], v[22:23], v[44:45]
	v_pk_fma_f32 v[22:23], v[22:23], v[30:31], v[28:29]
	v_pk_fma_f32 v[26:27], v[26:27], v[30:31], v[42:43] neg_lo:[0,0,1] neg_hi:[0,0,1]
.LBB0_633:
	s_or_b64 exec, exec, s[4:5]
	v_mov_b32_e32 v3, v1
	v_pk_mul_f32 v[20:21], v[20:21], s[66:67] op_sel_hi:[1,0]
	v_lshl_add_u64 v[12:13], v[12:13], 0, v[2:3]
	s_mov_b32 s4, 0xa80000
	v_pk_mul_f32 v[26:27], v[26:27], s[66:67] op_sel_hi:[1,0]
	v_pk_mul_f32 v[24:25], v[24:25], s[66:67] op_sel_hi:[1,0]
	v_pk_mul_f32 v[16:17], v[16:17], s[66:67] op_sel_hi:[1,0]
	v_pk_mul_f32 v[22:23], v[22:23], s[66:67] op_sel_hi:[1,0]
	v_pk_mul_f32 v[10:11], v[10:11], s[66:67] op_sel_hi:[1,0]
	v_pk_mul_f32 v[28:29], v[14:15], s[66:67] op_sel_hi:[1,0]
	v_pk_mul_f32 v[18:19], v[18:19], s[66:67] op_sel_hi:[1,0]
	v_cvt_pk_bf16_f32 v15, v20, v21
	v_add_co_u32_e32 v20, vcc, s4, v12
	v_cvt_pk_bf16_f32 v14, v16, v17
	v_cvt_pk_bf16_f32 v16, v24, v25
	v_cvt_pk_bf16_f32 v17, v26, v27
	v_addc_co_u32_e32 v21, vcc, 0, v13, vcc
	v_cvt_pk_bf16_f32 v10, v10, v11
	v_cvt_pk_bf16_f32 v11, v28, v29
	v_cvt_pk_bf16_f32 v12, v18, v19
	v_cvt_pk_bf16_f32 v13, v22, v23
	global_store_dwordx4 v[20:21], v[14:17], off offset:384
	global_store_dwordx4 v[20:21], v[10:13], off offset:448
	global_load_dwordx4 v[12:15], v[6:7], off offset:2080
	s_nop 0
	global_load_dwordx4 v[16:19], v[6:7], off offset:2144
	v_mov_b32_e32 v5, v1
	v_lshl_add_u64 v[10:11], s[30:31], 0, v[4:5]
	global_load_dwordx4 v[22:25], v[10:11], off
	global_load_dwordx4 v[26:29], v[10:11], off offset:128
	global_load_dwordx4 v[42:45], v[10:11], off offset:16
	global_load_dwordx4 v[46:49], v[10:11], off offset:144
	s_waitcnt vmcnt(0) lgkmcnt(0)
	v_lshlrev_b32_e32 v20, 16, v12
	v_lshlrev_b32_e32 v50, 16, v16
	v_and_b32_e32 v51, 0xffff0000, v16
	v_and_b32_e32 v21, 0xffff0000, v12
	v_lshlrev_b32_e32 v16, 16, v17
	v_and_b32_e32 v17, 0xffff0000, v17
	v_pk_mul_f32 v[58:59], v[50:51], v[50:51]
	v_lshlrev_b32_e32 v12, 16, v13
	v_and_b32_e32 v13, 0xffff0000, v13
	v_pk_mul_f32 v[56:57], v[16:17], v[16:17]
	v_pk_fma_f32 v[58:59], v[20:21], v[20:21], v[58:59]
	v_lshlrev_b32_e32 v52, 16, v18
	v_and_b32_e32 v53, 0xffff0000, v18
	v_pk_fma_f32 v[56:57], v[12:13], v[12:13], v[56:57]
	v_add_f32_e32 v9, v58, v59
	v_lshlrev_b32_e32 v30, 16, v14
	v_and_b32_e32 v31, 0xffff0000, v14
	v_pk_mul_f32 v[54:55], v[52:53], v[52:53]
	v_add_f32_e32 v9, v9, v56
	v_lshlrev_b32_e32 v18, 16, v19
	v_and_b32_e32 v19, 0xffff0000, v19
	v_pk_fma_f32 v[54:55], v[30:31], v[30:31], v[54:55]
	v_add_f32_e32 v9, v57, v9
	v_lshlrev_b32_e32 v14, 16, v15
	v_and_b32_e32 v15, 0xffff0000, v15
	v_pk_mul_f32 v[60:61], v[18:19], v[18:19]
	v_add_f32_e32 v9, v54, v9
	v_pk_fma_f32 v[60:61], v[14:15], v[14:15], v[60:61]
	v_add_f32_e32 v9, v55, v9
	v_add_f32_e32 v9, v60, v9
	v_add_f32_e32 v9, v61, v9
	ds_bpermute_b32 v54, v39, v9
	s_waitcnt lgkmcnt(0)
	v_add_f32_e32 v9, v9, v54
	ds_bpermute_b32 v54, v40, v9
	s_waitcnt lgkmcnt(0)
	v_add_f32_e32 v9, v9, v54
	v_fmamk_f32 v9, v9, 0x3c800000, v206
	v_mul_f32_e32 v54, 0x4b800000, v9
	v_cmp_gt_f32_e32 vcc, s35, v9
	s_nop 1
	v_cndmask_b32_e32 v9, v9, v54, vcc
	v_rsq_f32_e32 v9, v9
	s_nop 0
	v_mul_f32_e32 v54, 0x45800000, v9
	v_cndmask_b32_e32 v54, v9, v54, vcc
	v_pk_mul_f32 v[20:21], v[54:55], v[20:21] op_sel_hi:[0,1]
	v_pk_mul_f32 v[50:51], v[54:55], v[50:51] op_sel_hi:[0,1]
	v_pk_mul_f32 v[12:13], v[54:55], v[12:13] op_sel_hi:[0,1]
	v_pk_mul_f32 v[16:17], v[54:55], v[16:17] op_sel_hi:[0,1]
	v_pk_mul_f32 v[30:31], v[54:55], v[30:31] op_sel_hi:[0,1]
	v_pk_mul_f32 v[52:53], v[54:55], v[52:53] op_sel_hi:[0,1]
	v_pk_mul_f32 v[56:57], v[54:55], v[14:15] op_sel_hi:[0,1]
	v_pk_mul_f32 v[54:55], v[54:55], v[18:19] op_sel_hi:[0,1]
	v_pk_mul_f32 v[22:23], v[22:23], v[20:21]
	v_pk_mul_f32 v[14:15], v[26:27], v[50:51]
	v_pk_mul_f32 v[24:25], v[24:25], v[12:13]
	v_pk_mul_f32 v[16:17], v[28:29], v[16:17]
	v_pk_mul_f32 v[26:27], v[42:43], v[30:31]
	v_pk_mul_f32 v[18:19], v[46:47], v[52:53]
	v_pk_mul_f32 v[28:29], v[44:45], v[56:57]
	v_pk_mul_f32 v[20:21], v[48:49], v[54:55]
	s_and_saveexec_b64 s[4:5], s[2:3]
	s_cbranch_execz .LBB0_635
	v_mov_b32_e32 v9, v1
	v_lshl_add_u64 v[12:13], v[8:9], 2, s[64:65]
	v_lshl_add_u64 v[30:31], s[24:25], 0, v[12:13]
	v_lshl_add_u64 v[30:31], v[30:31], 0, v[4:5]
	v_lshl_add_u64 v[12:13], s[26:27], 0, v[12:13]
	v_lshl_add_u64 v[12:13], v[12:13], 0, v[4:5]
	global_load_dwordx4 v[42:45], v[30:31], off
	global_load_dwordx4 v[46:49], v[12:13], off
	s_waitcnt vmcnt(0) lgkmcnt(0)
	v_pk_mul_f32 v[50:51], v[22:23], v[46:47]
	v_pk_mul_f32 v[46:47], v[14:15], v[46:47]
	v_pk_fma_f32 v[14:15], v[14:15], v[42:43], v[50:51]
	v_pk_fma_f32 v[22:23], v[22:23], v[42:43], v[46:47] neg_lo:[0,0,1] neg_hi:[0,0,1]
	v_pk_mul_f32 v[42:43], v[24:25], v[48:49]
	v_pk_mul_f32 v[46:47], v[16:17], v[48:49]
	v_pk_fma_f32 v[16:17], v[16:17], v[44:45], v[42:43]
	v_pk_fma_f32 v[24:25], v[24:25], v[44:45], v[46:47] neg_lo:[0,0,1] neg_hi:[0,0,1]
	global_load_dwordx4 v[42:45], v[30:31], off offset:16
	global_load_dwordx4 v[46:49], v[12:13], off offset:16
	s_waitcnt vmcnt(0) lgkmcnt(0)
	v_pk_mul_f32 v[12:13], v[26:27], v[46:47]
	v_pk_mul_f32 v[30:31], v[18:19], v[46:47]
	v_pk_fma_f32 v[18:19], v[18:19], v[42:43], v[12:13]
	v_pk_fma_f32 v[26:27], v[26:27], v[42:43], v[30:31] neg_lo:[0,0,1] neg_hi:[0,0,1]
	v_pk_mul_f32 v[12:13], v[28:29], v[48:49]
	v_pk_mul_f32 v[30:31], v[20:21], v[48:49]
	v_pk_fma_f32 v[20:21], v[20:21], v[44:45], v[12:13]
	v_pk_fma_f32 v[28:29], v[28:29], v[44:45], v[30:31] neg_lo:[0,0,1] neg_hi:[0,0,1]
.LBB0_635:
	s_or_b64 exec, exec, s[4:5]
	v_lshlrev_b64 v[12:13], 8, v[0:1]
	v_lshl_add_u64 v[12:13], s[12:13], 0, v[12:13]
	v_cvt_pk_bf16_f32 v22, v22, v23
	v_cvt_pk_bf16_f32 v23, v24, v25
	v_cvt_pk_bf16_f32 v24, v26, v27
	v_lshl_add_u64 v[26:27], v[12:13], 0, v[2:3]
	s_mov_b32 s4, 0x2c80000
	v_add_co_u32_e32 v26, vcc, s4, v26
	v_cvt_pk_bf16_f32 v25, v28, v29
	s_nop 0
	v_addc_co_u32_e32 v27, vcc, 0, v27, vcc
	v_cvt_pk_bf16_f32 v14, v14, v15
	v_cvt_pk_bf16_f32 v15, v16, v17
	v_cvt_pk_bf16_f32 v16, v18, v19
	v_cvt_pk_bf16_f32 v17, v20, v21
	global_store_dwordx4 v[26:27], v[22:25], off
	global_store_dwordx4 v[26:27], v[14:17], off offset:64
	global_load_dwordx4 v[14:17], v[6:7], off offset:2208
	s_nop 0
	global_load_dwordx4 v[18:21], v[6:7], off offset:2272
	global_load_dwordx4 v[22:25], v[10:11], off
	global_load_dwordx4 v[26:29], v[10:11], off offset:128
	global_load_dwordx4 v[42:45], v[10:11], off offset:16
	global_load_dwordx4 v[46:49], v[10:11], off offset:144
	s_waitcnt vmcnt(0) lgkmcnt(0)
	v_lshlrev_b32_e32 v6, 16, v14
	v_lshlrev_b32_e32 v30, 16, v18
	v_and_b32_e32 v31, 0xffff0000, v18
	v_and_b32_e32 v7, 0xffff0000, v14
	v_lshlrev_b32_e32 v18, 16, v19
	v_and_b32_e32 v19, 0xffff0000, v19
	v_pk_mul_f32 v[56:57], v[30:31], v[30:31]
	v_lshlrev_b32_e32 v10, 16, v15
	v_and_b32_e32 v11, 0xffff0000, v15
	v_pk_mul_f32 v[54:55], v[18:19], v[18:19]
	v_pk_fma_f32 v[56:57], v[6:7], v[6:7], v[56:57]
	v_lshlrev_b32_e32 v50, 16, v20
	v_and_b32_e32 v51, 0xffff0000, v20
	v_pk_fma_f32 v[54:55], v[10:11], v[10:11], v[54:55]
	v_add_f32_e32 v0, v56, v57
	v_lshlrev_b32_e32 v14, 16, v16
	v_and_b32_e32 v15, 0xffff0000, v16
	v_pk_mul_f32 v[52:53], v[50:51], v[50:51]
	v_add_f32_e32 v0, v0, v54
	v_lshlrev_b32_e32 v20, 16, v21
	v_and_b32_e32 v21, 0xffff0000, v21
	v_pk_fma_f32 v[52:53], v[14:15], v[14:15], v[52:53]
	v_add_f32_e32 v0, v55, v0
	v_lshlrev_b32_e32 v16, 16, v17
	v_and_b32_e32 v17, 0xffff0000, v17
	v_pk_mul_f32 v[58:59], v[20:21], v[20:21]
	v_add_f32_e32 v0, v52, v0
	v_pk_fma_f32 v[58:59], v[16:17], v[16:17], v[58:59]
	v_add_f32_e32 v0, v53, v0
	v_add_f32_e32 v0, v58, v0
	v_add_f32_e32 v0, v59, v0
	ds_bpermute_b32 v3, v39, v0
	s_waitcnt lgkmcnt(0)
	v_add_f32_e32 v0, v0, v3
	ds_bpermute_b32 v3, v40, v0
	s_waitcnt lgkmcnt(0)
	v_add_f32_e32 v0, v0, v3
	v_fmamk_f32 v0, v0, 0x3c800000, v206
	v_mul_f32_e32 v3, 0x4b800000, v0
	v_cmp_gt_f32_e32 vcc, s35, v0
	s_nop 1
	v_cndmask_b32_e32 v0, v0, v3, vcc
	v_rsq_f32_e32 v0, v0
	s_nop 0
	v_mul_f32_e32 v3, 0x45800000, v0
	v_cndmask_b32_e32 v0, v0, v3, vcc
	v_pk_mul_f32 v[6:7], v[0:1], v[6:7] op_sel_hi:[0,1]
	v_pk_mul_f32 v[30:31], v[0:1], v[30:31] op_sel_hi:[0,1]
	v_pk_mul_f32 v[52:53], v[0:1], v[10:11] op_sel_hi:[0,1]
	v_pk_mul_f32 v[18:19], v[0:1], v[18:19] op_sel_hi:[0,1]
	v_pk_mul_f32 v[54:55], v[0:1], v[14:15] op_sel_hi:[0,1]
	v_pk_mul_f32 v[50:51], v[0:1], v[50:51] op_sel_hi:[0,1]
	v_pk_mul_f32 v[56:57], v[0:1], v[16:17] op_sel_hi:[0,1]
	v_pk_mul_f32 v[58:59], v[0:1], v[20:21] op_sel_hi:[0,1]
	v_pk_mul_f32 v[6:7], v[22:23], v[6:7]
	v_pk_mul_f32 v[10:11], v[26:27], v[30:31]
	v_pk_mul_f32 v[20:21], v[24:25], v[52:53]
	v_pk_mul_f32 v[14:15], v[28:29], v[18:19]
	v_pk_mul_f32 v[22:23], v[42:43], v[54:55]
	v_pk_mul_f32 v[16:17], v[46:47], v[50:51]
	v_pk_mul_f32 v[24:25], v[44:45], v[56:57]
	v_pk_mul_f32 v[18:19], v[48:49], v[58:59]
	s_and_saveexec_b64 s[4:5], s[2:3]
	s_cbranch_execz .LBB0_637
	v_mov_b32_e32 v9, v1
	v_lshl_add_u64 v[8:9], v[8:9], 2, s[64:65]
	v_lshl_add_u64 v[26:27], s[24:25], 0, v[8:9]
	v_mov_b32_e32 v5, v1
	v_lshl_add_u64 v[30:31], v[26:27], 0, v[4:5]
	v_lshl_add_u64 v[8:9], s[26:27], 0, v[8:9]
	v_lshl_add_u64 v[8:9], v[8:9], 0, v[4:5]
	global_load_dwordx4 v[26:29], v[30:31], off
	global_load_dwordx4 v[42:45], v[8:9], off
	s_waitcnt vmcnt(0) lgkmcnt(0)
	v_pk_mul_f32 v[46:47], v[6:7], v[42:43]
	v_pk_mul_f32 v[42:43], v[10:11], v[42:43]
	v_pk_fma_f32 v[10:11], v[10:11], v[26:27], v[46:47]
	v_pk_fma_f32 v[6:7], v[6:7], v[26:27], v[42:43] neg_lo:[0,0,1] neg_hi:[0,0,1]
	v_pk_mul_f32 v[26:27], v[20:21], v[44:45]
	v_pk_mul_f32 v[42:43], v[14:15], v[44:45]
	v_pk_fma_f32 v[14:15], v[14:15], v[28:29], v[26:27]
	v_pk_fma_f32 v[20:21], v[20:21], v[28:29], v[42:43] neg_lo:[0,0,1] neg_hi:[0,0,1]
	global_load_dwordx4 v[26:29], v[30:31], off offset:16
	global_load_dwordx4 v[42:45], v[8:9], off offset:16
	s_waitcnt vmcnt(0) lgkmcnt(0)
	v_pk_mul_f32 v[8:9], v[22:23], v[42:43]
	v_pk_mul_f32 v[30:31], v[16:17], v[42:43]
	v_pk_fma_f32 v[16:17], v[16:17], v[26:27], v[8:9]
	v_pk_fma_f32 v[22:23], v[22:23], v[26:27], v[30:31] neg_lo:[0,0,1] neg_hi:[0,0,1]
	v_pk_mul_f32 v[8:9], v[24:25], v[44:45]
	v_pk_mul_f32 v[26:27], v[18:19], v[44:45]
	v_pk_fma_f32 v[18:19], v[18:19], v[28:29], v[8:9]
	v_pk_fma_f32 v[24:25], v[24:25], v[28:29], v[26:27] neg_lo:[0,0,1] neg_hi:[0,0,1]
.LBB0_637:
	s_or_b64 exec, exec, s[4:5]
	v_cvt_pk_bf16_f32 v26, v6, v7
	v_mov_b32_e32 v6, v2
	v_mov_b32_e32 v7, v1
	v_lshl_add_u64 v[8:9], v[12:13], 0, v[6:7]
	s_mov_b32 s4, 0x2c80000
	v_add_co_u32_e32 v12, vcc, s4, v8
	v_cvt_pk_bf16_f32 v8, v10, v11
	s_nop 0
	v_addc_co_u32_e32 v13, vcc, 0, v9, vcc
	v_cvt_pk_bf16_f32 v9, v14, v15
	v_cvt_pk_bf16_f32 v10, v16, v17
	v_cvt_pk_bf16_f32 v11, v18, v19
	v_mov_b32_e32 v5, v1
	v_cvt_pk_bf16_f32 v27, v20, v21
	v_cvt_pk_bf16_f32 v28, v22, v23
	v_cvt_pk_bf16_f32 v29, v24, v25
	global_store_dwordx4 v[12:13], v[8:11], off offset:192
	v_or_b32_e32 v41, 0x180, v41
	s_mov_b32 s54, 6
	v_lshl_add_u64 v[8:9], s[24:25], 0, v[4:5]
	v_lshl_add_u64 v[10:11], s[26:27], 0, v[4:5]
	global_store_dwordx4 v[12:13], v[26:29], off offset:128
	s_branch .LBB0_639
.LBB0_638:
	s_or_b64 exec, exec, s[4:5]
	v_mov_b32_e32 v0, 0x3e38aa3b
	v_cndmask_b32_e32 v0, 1.0, v0, vcc
	v_pk_mul_f32 v[30:31], v[0:1], v[14:15] op_sel_hi:[0,1]
	v_pk_mul_f32 v[14:15], v[0:1], v[18:19] op_sel_hi:[0,1]
	v_pk_mul_f32 v[18:19], v[0:1], v[22:23] op_sel_hi:[0,1]
	v_pk_mul_f32 v[22:23], v[0:1], v[26:27] op_sel_hi:[0,1]
	v_mov_b32_e32 v3, v1
	v_pk_mul_f32 v[26:27], v[0:1], v[12:13] op_sel_hi:[0,1]
	v_pk_mul_f32 v[24:25], v[0:1], v[24:25] op_sel_hi:[0,1]
	v_pk_mul_f32 v[20:21], v[0:1], v[20:21] op_sel_hi:[0,1]
	v_pk_mul_f32 v[16:17], v[0:1], v[16:17] op_sel_hi:[0,1]
	v_cvt_pk_bf16_f32 v12, v22, v23
	v_cvt_pk_bf16_f32 v13, v18, v19
	v_cvt_pk_bf16_f32 v14, v14, v15
	v_cvt_pk_bf16_f32 v15, v30, v31
	v_lshl_add_u64 v[18:19], v[28:29], 0, v[2:3]
	s_add_i32 s54, s54, -1
	global_store_dwordx4 v[18:19], v[12:15], off
	s_cmp_eq_u32 s54, 0
	v_add_u32_e32 v41, 64, v41
	v_cvt_pk_bf16_f32 v12, v24, v25
	v_cvt_pk_bf16_f32 v13, v20, v21
	v_cvt_pk_bf16_f32 v14, v16, v17
	v_cvt_pk_bf16_f32 v15, v26, v27
	global_store_dwordx4 v[18:19], v[12:15], off offset:64
	s_cbranch_scc1 .LBB0_645
.LBB0_639:
	s_mov_b32 s4, 0xaaaaaaab
	v_mul_hi_u32 v0, v41, s4
	v_lshrrev_b32_e32 v0, 8, v0
	v_mul_u32_u24_e32 v0, 0x180, v0
	v_sub_u32_e32 v29, v41, v0
	v_and_b32_e32 v28, 63, v29
	v_and_b32_e32 v0, 0x1c0, v29
	v_or_b32_e32 v3, v28, v36
	v_mov_b64_e32 v[12:13], s[20:21]
	v_mad_u64_u32 v[12:13], s[4:5], v3, s83, v[12:13]
	v_lshlrev_b32_e32 v0, 1, v0
	v_lshl_add_u64 v[12:13], v[12:13], 0, v[0:1]
	v_lshl_add_u64 v[16:17], v[12:13], 0, v[6:7]
	global_load_dwordx4 v[12:15], v[16:17], off offset:2592
	global_load_dwordx4 v[42:45], v[16:17], off offset:2656
	v_cmp_lt_u32_e64 s[4:5], s49, v29
	v_cmp_gt_u32_e32 vcc, s47, v29
	v_mov_b32_e32 v29, s10
	v_mov_b32_e32 v30, s8
	v_cndmask_b32_e32 v31, v29, v30, vcc
	v_mov_b32_e32 v29, s9
	v_mov_b32_e32 v30, s37
	v_cndmask_b32_e32 v30, v29, v30, vcc
	v_lshl_add_u64 v[30:31], s[18:19], 2, v[30:31]
	v_lshl_add_u64 v[30:31], v[30:31], 0, v[4:5]
	s_waitcnt vmcnt(0) lgkmcnt(0)
	v_lshlrev_b32_e32 v24, 16, v12
	v_and_b32_e32 v25, 0xffff0000, v12
	v_lshlrev_b32_e32 v20, 16, v13
	v_and_b32_e32 v21, 0xffff0000, v13
	v_lshlrev_b32_e32 v16, 16, v14
	v_and_b32_e32 v17, 0xffff0000, v14
	v_lshlrev_b32_e32 v12, 16, v15
	v_and_b32_e32 v13, 0xffff0000, v15
	v_lshlrev_b32_e32 v14, 16, v45
	v_and_b32_e32 v15, 0xffff0000, v45
	v_lshlrev_b32_e32 v26, 16, v42
	v_and_b32_e32 v27, 0xffff0000, v42
	v_lshlrev_b32_e32 v22, 16, v43
	v_and_b32_e32 v23, 0xffff0000, v43
	v_lshlrev_b32_e32 v18, 16, v44
	v_and_b32_e32 v19, 0xffff0000, v44
	v_pk_mul_f32 v[42:43], v[14:15], v[14:15]
	v_pk_mul_f32 v[50:51], v[22:23], v[22:23]
	v_pk_fma_f32 v[58:59], v[12:13], v[12:13], v[42:43]
	v_pk_mul_f32 v[42:43], v[18:19], v[18:19]
	v_pk_fma_f32 v[62:63], v[20:21], v[20:21], v[50:51]
	v_pk_fma_f32 v[60:61], v[16:17], v[16:17], v[42:43]
	global_load_dwordx4 v[42:45], v[30:31], off offset:16
	global_load_dwordx4 v[46:49], v[30:31], off offset:144
	global_load_dwordx4 v[50:53], v[30:31], off
	global_load_dwordx4 v[54:57], v[30:31], off offset:128
	v_pk_mul_f32 v[30:31], v[26:27], v[26:27]
	s_nop 0
	v_pk_fma_f32 v[30:31], v[24:25], v[24:25], v[30:31]
	s_nop 0
	v_add_f32_e32 v29, v30, v31
	v_add_f32_e32 v29, v29, v62
	v_add_f32_e32 v29, v63, v29
	v_add_f32_e32 v29, v60, v29
	v_add_f32_e32 v29, v61, v29
	v_add_f32_e32 v29, v58, v29
	v_add_f32_e32 v29, v59, v29
	ds_bpermute_b32 v30, v39, v29
	s_waitcnt lgkmcnt(0)
	v_add_f32_e32 v29, v29, v30
	ds_bpermute_b32 v30, v40, v29
	s_waitcnt lgkmcnt(0)
	v_add_f32_e32 v29, v29, v30
	v_fmamk_f32 v29, v29, 0x3c800000, v206
	v_cmp_gt_f32_e64 s[6:7], s35, v29
	v_mul_f32_e32 v30, 0x4b800000, v29
	s_nop 0
	v_cndmask_b32_e64 v29, v29, v30, s[6:7]
	v_rsq_f32_e32 v29, v29
	s_nop 0
	v_mul_f32_e32 v30, 0x45800000, v29
	v_cndmask_b32_e64 v30, v29, v30, s[6:7]
	v_pk_mul_f32 v[24:25], v[30:31], v[24:25] op_sel_hi:[0,1]
	v_pk_mul_f32 v[58:59], v[30:31], v[26:27] op_sel_hi:[0,1]
	v_pk_mul_f32 v[20:21], v[30:31], v[20:21] op_sel_hi:[0,1]
	v_pk_mul_f32 v[16:17], v[30:31], v[16:17] op_sel_hi:[0,1]
	v_pk_mul_f32 v[12:13], v[30:31], v[12:13] op_sel_hi:[0,1]
	s_waitcnt vmcnt(0)
	v_pk_mul_f32 v[26:27], v[50:51], v[24:25]
	v_pk_mul_f32 v[50:51], v[30:31], v[22:23] op_sel_hi:[0,1]
	v_pk_mul_f32 v[22:23], v[52:53], v[20:21]
	v_pk_mul_f32 v[20:21], v[56:57], v[50:51]
	v_pk_mul_f32 v[50:51], v[30:31], v[18:19] op_sel_hi:[0,1]
	v_pk_mul_f32 v[30:31], v[30:31], v[14:15] op_sel_hi:[0,1]
	v_pk_mul_f32 v[24:25], v[54:55], v[58:59]
	v_pk_mul_f32 v[18:19], v[42:43], v[16:17]
	v_pk_mul_f32 v[16:17], v[46:47], v[50:51]
	v_pk_mul_f32 v[14:15], v[44:45], v[12:13]
	v_pk_mul_f32 v[12:13], v[48:49], v[30:31]
	s_and_saveexec_b64 s[6:7], s[2:3]
	s_cbranch_execz .LBB0_641
	v_or_b32_e32 v28, v28, v34
	v_lshlrev_b32_e32 v28, 5, v28
	v_mov_b32_e32 v29, v1
	v_lshl_add_u64 v[28:29], v[28:29], 2, s[64:65]
	v_lshl_add_u64 v[46:47], v[8:9], 0, v[28:29]
	v_lshl_add_u64 v[48:49], v[10:11], 0, v[28:29]
	global_load_dwordx4 v[28:31], v[46:47], off
	global_load_dwordx4 v[42:45], v[48:49], off
	s_waitcnt vmcnt(0) lgkmcnt(0)
	v_pk_mul_f32 v[50:51], v[24:25], v[42:43]
	s_nop 0
	v_pk_fma_f32 v[50:51], v[26:27], v[28:29], v[50:51] neg_lo:[0,0,1] neg_hi:[0,0,1]
	v_pk_mul_f32 v[26:27], v[26:27], v[42:43]
	s_nop 0
	v_pk_fma_f32 v[24:25], v[24:25], v[28:29], v[26:27]
	v_pk_mul_f32 v[26:27], v[20:21], v[44:45]
	s_nop 0
	v_pk_fma_f32 v[52:53], v[22:23], v[30:31], v[26:27] neg_lo:[0,0,1] neg_hi:[0,0,1]
	v_pk_mul_f32 v[22:23], v[22:23], v[44:45]
	global_load_dwordx4 v[26:29], v[46:47], off offset:16
	global_load_dwordx4 v[42:45], v[48:49], off offset:16
	v_pk_fma_f32 v[20:21], v[20:21], v[30:31], v[22:23]
	s_waitcnt vmcnt(0) lgkmcnt(0)
	v_pk_mul_f32 v[22:23], v[16:17], v[42:43]
	s_nop 0
	v_pk_fma_f32 v[22:23], v[18:19], v[26:27], v[22:23] neg_lo:[0,0,1] neg_hi:[0,0,1]
	v_pk_mul_f32 v[18:19], v[18:19], v[42:43]
	s_nop 0
	v_pk_fma_f32 v[16:17], v[16:17], v[26:27], v[18:19]
	v_pk_mul_f32 v[18:19], v[12:13], v[44:45]
	v_mov_b64_e32 v[26:27], v[50:51]
	v_pk_fma_f32 v[18:19], v[14:15], v[28:29], v[18:19] neg_lo:[0,0,1] neg_hi:[0,0,1]
	v_pk_mul_f32 v[14:15], v[14:15], v[44:45]
	s_nop 0
	v_pk_fma_f32 v[12:13], v[12:13], v[28:29], v[14:15]
	v_mov_b64_e32 v[14:15], v[18:19]
	v_mov_b64_e32 v[18:19], v[22:23]
	v_mov_b64_e32 v[22:23], v[52:53]

.LBB0_646:
	v_cndmask_b32_e64 v0, 0, 1, s[4:5]
	s_and_b64 s[4:5], s[4:5], exec
	s_movk_i32 s4, 0x920
	s_cselect_b32 s56, s4, 0xd20
	v_lshl_add_u64 v[26:27], v[2:3], 0, s[56:57]
	v_lshl_add_u64 v[22:23], v[26:27], 0, v[4:5]
	s_waitcnt lgkmcnt(0)
	s_barrier
	global_load_dwordx4 v[22:25], v[22:23], off
	v_cmp_ne_u32_e32 vcc, 1, v0
	v_add_u32_e32 v0, s6, v14
	s_movk_i32 s6, 0x400
	s_and_b64 vcc, exec, vcc
	s_waitcnt vmcnt(0) lgkmcnt(0)
	ds_write_b128 v16, v[22:25]
	v_lshl_add_u64 v[22:23], v[26:27], 0, v[6:7]
	global_load_dwordx4 v[22:25], v[22:23], off
	s_waitcnt vmcnt(0) lgkmcnt(0)
	ds_write_b128 v17, v[22:25]
	v_lshl_add_u64 v[22:23], v[26:27], 0, v[8:9]
	global_load_dwordx4 v[22:25], v[22:23], off
	s_waitcnt vmcnt(0) lgkmcnt(0)
	ds_write_b128 v18, v[22:25]
	v_lshl_add_u64 v[22:23], v[26:27], 0, v[10:11]
	global_load_dwordx4 v[22:25], v[22:23], off
	v_mad_u64_u32 v[26:27], s[4:5], v0, s85, v[12:13]
	s_mov_b64 s[4:5], 0
	s_waitcnt vmcnt(0) lgkmcnt(0)
	ds_write_b128 v19, v[22:25]
	s_waitcnt lgkmcnt(0)
	s_barrier
	ds_read_u16 v0, v15
	ds_read_u16 v21, v20 offset:272
	s_waitcnt lgkmcnt(0)
	v_lshl_or_b32 v22, v21, 16, v0
	ds_read_u16 v0, v15 offset:544
	ds_read_u16 v21, v20 offset:816
	s_waitcnt lgkmcnt(0)
	v_lshl_or_b32 v23, v21, 16, v0
	ds_read_u16 v0, v15 offset:1088
	ds_read_u16 v21, v20 offset:1360
	s_waitcnt lgkmcnt(0)
	v_lshl_or_b32 v24, v21, 16, v0
	ds_read_u16 v0, v15 offset:1632
	ds_read_u16 v21, v20 offset:1904
	s_waitcnt lgkmcnt(0)
	v_lshl_or_b32 v25, v21, 16, v0
	global_store_dwordx4 v[26:27], v[22:25], off
	ds_read_u16 v0, v15 offset:2176
	ds_read_u16 v21, v20 offset:2448
	s_waitcnt lgkmcnt(0)
	v_lshl_or_b32 v22, v21, 16, v0
	ds_read_u16 v0, v15 offset:2720
	ds_read_u16 v21, v20 offset:2992
	s_waitcnt lgkmcnt(0)
	v_lshl_or_b32 v23, v21, 16, v0
	ds_read_u16 v0, v15 offset:3264
	ds_read_u16 v21, v20 offset:3536
	s_waitcnt lgkmcnt(0)
	v_lshl_or_b32 v24, v21, 16, v0
	ds_read_u16 v0, v15 offset:3808
	ds_read_u16 v21, v20 offset:4080
	s_waitcnt lgkmcnt(0)
	v_lshl_or_b32 v25, v21, 16, v0
	global_store_dwordx4 v[26:27], v[22:25], off offset:16
	ds_read_u16 v0, v15 offset:4352
	ds_read_u16 v21, v20 offset:4624
	s_waitcnt lgkmcnt(0)
	v_lshl_or_b32 v22, v21, 16, v0
	ds_read_u16 v0, v15 offset:4896
	ds_read_u16 v21, v20 offset:5168
	s_waitcnt lgkmcnt(0)
	v_lshl_or_b32 v23, v21, 16, v0
	ds_read_u16 v0, v15 offset:5440
	ds_read_u16 v21, v20 offset:5712
	s_waitcnt lgkmcnt(0)
	v_lshl_or_b32 v24, v21, 16, v0
	ds_read_u16 v0, v15 offset:5984
	ds_read_u16 v21, v20 offset:6256
	s_waitcnt lgkmcnt(0)
	v_lshl_or_b32 v25, v21, 16, v0
	global_store_dwordx4 v[26:27], v[22:25], off offset:32
	ds_read_u16 v0, v15 offset:6528
	ds_read_u16 v21, v20 offset:6800
	s_waitcnt lgkmcnt(0)
	v_lshl_or_b32 v22, v21, 16, v0
	ds_read_u16 v0, v15 offset:7072
	ds_read_u16 v21, v20 offset:7344
	s_waitcnt lgkmcnt(0)
	v_lshl_or_b32 v23, v21, 16, v0
	ds_read_u16 v0, v15 offset:7616
	ds_read_u16 v21, v20 offset:7888
	s_waitcnt lgkmcnt(0)
	v_lshl_or_b32 v24, v21, 16, v0
	ds_read_u16 v0, v15 offset:8160
	ds_read_u16 v21, v20 offset:8432
	s_waitcnt lgkmcnt(0)
	v_lshl_or_b32 v25, v21, 16, v0
	global_store_dwordx4 v[26:27], v[22:25], off offset:48
	s_cbranch_vccz .LBB0_646
	v_cmp_gt_u32_e32 vcc, 37, v33
	s_and_saveexec_b64 s[54:55], vcc
	s_cbranch_execz .LBB0_708
	v_and_b32_e32 v0, 0xc0, v37
	v_bfe_u32 v3, v37, 4, 2
	v_lshl_or_b32 v46, v3, 3, v0
	v_lshl_or_b32 v70, v32, 8, v0
	v_lshlrev_b32_e32 v0, 1, v46
	v_and_b32_e32 v2, 15, v37
	v_lshl_add_u64 v[48:49], s[20:21], 0, v[0:1]
	v_lshlrev_b32_e32 v0, 4, v3
	s_movk_i32 s4, 0xff00
	v_lshl_or_b32 v0, v2, 7, v0
	v_add3_u32 v47, v34, v2, s4
	v_or_b32_e32 v51, v2, v36
	v_add_u32_e32 v68, 0x1100, v35
	v_lshlrev_b32_e32 v69, 2, v3
	v_cmp_ne_u32_e64 s[4:5], 36, v33
	v_or_b32_e32 v71, v34, v2
	v_or_b32_e32 v50, 32, v46
	s_mov_b32 s11, 0
	v_lshl_add_u64 v[52:53], s[38:39], 0, v[0:1]
	s_mov_b64 s[6:7], -1
	s_xor_b64 s[72:73], s[0:1], -1
	s_branch .LBB0_650

.LBB0_650:
	v_or_b32_e32 v0, s11, v51
	v_mad_u64_u32 v[2:3], s[42:43], v0, s83, v[48:49]
	global_load_dwordx4 v[24:27], v[2:3], off offset:3616
	v_or_b32_e32 v38, s11, v47
	v_add_u32_e32 v0, 0xfffff800, v38
	v_cmp_lt_u32_e32 vcc, s81, v0
	v_sub_u32_e32 v0, v68, v38
	v_mov_b64_e32 v[4:5], s[20:21]
	s_and_b64 s[74:75], s[72:73], vcc
	v_mad_u64_u32 v[4:5], s[42:43], v0, s83, v[4:5]
	v_mov_b32_e32 v12, 0
	v_lshlrev_b32_e32 v0, 1, v46
	v_mov_b32_e32 v20, 0
	v_mov_b32_e32 v21, 0
	v_mov_b32_e32 v22, 0
	v_mov_b32_e32 v23, 0
	s_and_saveexec_b64 s[76:77], s[74:75]
	s_cbranch_execz .LBB0_652
	v_lshl_add_u64 v[6:7], v[4:5], 0, v[0:1]
	global_load_dwordx4 v[20:23], v[6:7], off offset:3616
.LBB0_652:
	s_or_b64 exec, exec, s[76:77]
	global_load_dwordx4 v[16:19], v[2:3], off offset:3680
	v_lshlrev_b32_e32 v2, 1, v50
	v_mov_b32_e32 v13, 0
	v_mov_b32_e32 v14, 0
	v_mov_b32_e32 v15, 0
	s_and_saveexec_b64 s[76:77], s[74:75]
	s_cbranch_execz .LBB0_654
	v_mov_b32_e32 v3, v1
	v_lshl_add_u64 v[4:5], v[4:5], 0, v[2:3]
	global_load_dwordx4 v[12:15], v[4:5], off offset:3616
.LBB0_654:
	s_or_b64 exec, exec, s[76:77]
	s_or_b32 s56, s11, 16
	v_or_b32_e32 v3, s56, v51
	v_mad_u64_u32 v[30:31], s[42:43], v3, s83, v[48:49]
	global_load_dwordx4 v[8:11], v[30:31], off offset:3616
	v_or_b32_e32 v39, s56, v47
	v_add_u32_e32 v3, 0xfffff800, v39
	v_cmp_lt_u32_e32 vcc, s81, v3
	v_sub_u32_e32 v3, v68, v39
	v_mov_b64_e32 v[4:5], s[20:21]
	s_and_b64 s[74:75], s[72:73], vcc
	v_mad_u64_u32 v[36:37], s[42:43], v3, s83, v[4:5]
	v_mov_b32_e32 v28, 0
	v_mov_b32_e32 v4, 0
	v_mov_b32_e32 v5, 0
	v_mov_b32_e32 v6, 0
	v_mov_b32_e32 v7, 0
	s_and_saveexec_b64 s[76:77], s[74:75]
	s_cbranch_execz .LBB0_656
	v_lshl_add_u64 v[4:5], v[36:37], 0, v[0:1]
	global_load_dwordx4 v[4:7], v[4:5], off offset:3616
.LBB0_656:
	s_or_b64 exec, exec, s[76:77]
	global_load_dwordx4 v[32:35], v[30:31], off offset:3680
	v_mov_b32_e32 v29, 0
	v_mov_b32_e32 v30, 0
	v_mov_b32_e32 v31, 0
	s_and_saveexec_b64 s[76:77], s[74:75]
	s_cbranch_execz .LBB0_658
	v_mov_b32_e32 v3, v1
	v_lshl_add_u64 v[2:3], v[36:37], 0, v[2:3]
	global_load_dwordx4 v[28:31], v[2:3], off offset:3616

.LBB0_660:
	v_add_co_u32_e32 v34, vcc, 0xffffffc0, v58
	s_cmp_lt_u32 s11, 4
	s_nop 0
	v_addc_co_u32_e32 v35, vcc, -1, v59, vcc
	global_load_dwordx4 v[38:41], v[34:35], off
	s_nop 0
	global_load_dwordx4 v[34:37], v[58:59], off
	s_cselect_b64 s[58:59], -1, 0
	s_or_b64 s[6:7], s[58:59], s[0:1]
	v_cndmask_b32_e64 v45, v25, v23, s[6:7]
	v_cndmask_b32_e64 v44, v24, v22, s[6:7]
	v_cndmask_b32_e64 v43, v21, v19, s[6:7]
	v_cndmask_b32_e64 v42, v20, v18, s[6:7]
	v_cndmask_b32_e64 v63, v17, v15, s[6:7]
	v_cndmask_b32_e64 v62, v16, v14, s[6:7]
	v_cndmask_b32_e64 v61, v13, v11, s[6:7]
	v_cndmask_b32_e64 v60, v12, v10, s[6:7]
	s_lshr_b32 s42, s11, 2
	s_mul_i32 s56, s42, 0x840
	v_and_or_b32 v72, s91, 48, v69
	s_or_b64 s[76:77], s[4:5], s[58:59]
	s_waitcnt vmcnt(0) lgkmcnt(0)
	v_mfma_f32_16x16x32_bf16 v[42:45], v[38:41], v[42:45], 0
	v_mfma_f32_16x16x32_bf16 v[42:45], v[34:37], v[60:63], v[42:45]
	v_lshl_add_u64 v[60:61], s[56:57], 1, v[54:55]
	s_and_saveexec_b64 s[58:59], s[2:3]
	s_xor_b64 s[94:95], exec, s[58:59]
	s_cbranch_execz .LBB0_664
	s_and_saveexec_b64 s[58:59], s[76:77]
	s_cbranch_execz .LBB0_663
	v_or_b32_e32 v62, v72, v70
	v_mad_u64_u32 v[62:63], vcc, v62, s63, v[60:61]
	v_add_co_u32_e32 v62, vcc, 0xe88f000, v62
	v_cvt_pk_bf16_f32 v0, v42, s0
	s_nop 0
	v_addc_co_u32_e32 v63, vcc, 0, v63, vcc
	global_store_short v[62:63], v0, off offset:3584

.LBB0_664:
	s_or_saveexec_b64 s[94:95], s[94:95]
	s_lshl_b32 s56, s42, 9
	v_lshl_add_u64 v[62:63], v[56:57], 0, s[56:57]
	v_or_b32_e32 v0, v72, v70
	s_xor_b64 exec, exec, s[94:95]
	s_cbranch_execz .LBB0_666
	v_lshlrev_b64 v[64:65], 10, v[0:1]
	v_cvt_pk_bf16_f32 v42, v42, s0
	v_lshl_add_u64 v[64:65], v[62:63], 0, v[64:65]
	global_store_short v[64:65], v42, off
.LBB0_666:
	s_or_b64 exec, exec, s[94:95]
	v_or_b32_e32 v42, 1, v72
	s_and_saveexec_b64 s[42:43], s[2:3]
	s_xor_b64 s[94:95], exec, s[42:43]
	s_cbranch_execz .LBB0_670
	s_and_saveexec_b64 s[58:59], s[76:77]
	s_cbranch_execz .LBB0_669
	v_or_b32_e32 v64, v42, v70
	v_mad_u64_u32 v[64:65], s[42:43], v64, s63, v[60:61]
	v_add_co_u32_e32 v64, vcc, 0xe88f000, v64
	v_cvt_pk_bf16_f32 v66, v43, s0
	s_nop 0
	v_addc_co_u32_e32 v65, vcc, 0, v65, vcc
	global_store_short v[64:65], v66, off offset:3584

.LBB0_670:
	s_or_saveexec_b64 s[58:59], s[94:95]
	v_or_b32_e32 v64, v42, v70
	s_xor_b64 exec, exec, s[58:59]
	s_cbranch_execz .LBB0_672
	v_mov_b32_e32 v65, v1
	v_cvt_pk_bf16_f32 v66, v43, s0
	v_lshlrev_b64 v[42:43], 10, v[64:65]
	v_lshl_add_u64 v[42:43], v[62:63], 0, v[42:43]
	global_store_short v[42:43], v66, off
.LBB0_672:
	s_or_b64 exec, exec, s[58:59]
	v_or_b32_e32 v42, 2, v72
	s_and_saveexec_b64 s[42:43], s[2:3]
	s_xor_b64 s[94:95], exec, s[42:43]
	s_cbranch_execz .LBB0_676
	s_and_saveexec_b64 s[58:59], s[76:77]
	s_cbranch_execz .LBB0_675
	v_or_b32_e32 v65, v42, v70
	v_mad_u64_u32 v[66:67], s[42:43], v65, s63, v[60:61]
	v_add_co_u32_e32 v66, vcc, 0xe88f000, v66
	v_cvt_pk_bf16_f32 v43, v44, s0
	s_nop 0
	v_addc_co_u32_e32 v67, vcc, 0, v67, vcc
	global_store_short v[66:67], v43, off offset:3584

.LBB0_676:
	s_or_saveexec_b64 s[58:59], s[94:95]
	v_or_b32_e32 v66, v42, v70
	s_xor_b64 exec, exec, s[58:59]
	s_cbranch_execz .LBB0_678
	v_mov_b32_e32 v67, v1
	v_lshlrev_b64 v[42:43], 10, v[66:67]
	v_cvt_pk_bf16_f32 v44, v44, s0
	v_lshl_add_u64 v[42:43], v[62:63], 0, v[42:43]
	global_store_short v[42:43], v44, off
.LBB0_678:
	s_or_b64 exec, exec, s[58:59]
	v_or_b32_e32 v65, 3, v72
	s_and_saveexec_b64 s[42:43], s[2:3]
	s_xor_b64 s[94:95], exec, s[42:43]
	s_cbranch_execz .LBB0_682
	s_and_saveexec_b64 s[58:59], s[76:77]
	s_cbranch_execz .LBB0_681
	v_or_b32_e32 v42, v65, v70
	v_mad_u64_u32 v[42:43], s[42:43], v42, s63, v[60:61]
	v_add_co_u32_e32 v42, vcc, 0xe88f000, v42
	v_cvt_pk_bf16_f32 v44, v45, s0
	s_nop 0
	v_addc_co_u32_e32 v43, vcc, 0, v43, vcc
	global_store_short v[42:43], v44, off offset:3584

.LBB0_682:
	s_or_saveexec_b64 s[58:59], s[94:95]
	v_or_b32_e32 v42, v65, v70
	s_xor_b64 exec, exec, s[58:59]
	s_cbranch_execz .LBB0_684
	v_mov_b32_e32 v43, v1
	v_cvt_pk_bf16_f32 v65, v45, s0
	v_lshlrev_b64 v[44:45], 10, v[42:43]
	v_lshl_add_u64 v[44:45], v[62:63], 0, v[44:45]
	global_store_short v[44:45], v65, off

.LBB0_692:
	s_and_saveexec_b64 s[58:59], s[76:77]
	s_cbranch_execz .LBB0_694
	v_mad_u64_u32 v[38:39], s[42:43], v0, s63, v[60:61]
	v_add_co_u32_e32 v38, vcc, 0xe88f000, v38
	s_nop 0
	v_cvt_pk_bf16_f32 v40, v34, s0
	v_addc_co_u32_e32 v39, vcc, 0, v39, vcc
	global_store_short v[38:39], v40, off offset:3616

.LBB0_695:
	v_lshlrev_b64 v[38:39], 10, v[0:1]
	s_nop 1
	v_cvt_pk_bf16_f32 v34, v34, s0
	v_lshl_add_u64 v[38:39], v[62:63], 0, v[38:39]
	global_store_short v[38:39], v34, off offset:32
	s_or_b64 exec, exec, s[6:7]
	s_and_saveexec_b64 s[6:7], s[2:3]
	s_xor_b64 s[6:7], exec, s[6:7]
	s_cbranch_execz .LBB0_687
.LBB0_696:
	s_and_saveexec_b64 s[58:59], s[76:77]
	s_cbranch_execz .LBB0_698
	v_mad_u64_u32 v[38:39], s[42:43], v64, s63, v[60:61]
	v_add_co_u32_e32 v38, vcc, 0xe88f000, v38
	v_cvt_pk_bf16_f32 v0, v35, s0
	s_nop 0
	v_addc_co_u32_e32 v39, vcc, 0, v39, vcc
	global_store_short v[38:39], v0, off offset:3616

.LBB0_699:
	v_mov_b32_e32 v65, v1
	v_cvt_pk_bf16_f32 v0, v35, s0
	v_lshlrev_b64 v[34:35], 10, v[64:65]
	v_lshl_add_u64 v[34:35], v[62:63], 0, v[34:35]
	global_store_short v[34:35], v0, off offset:32
	s_or_b64 exec, exec, s[6:7]
	s_and_saveexec_b64 s[6:7], s[2:3]
	s_xor_b64 s[6:7], exec, s[6:7]
	s_cbranch_execz .LBB0_689
.LBB0_700:
	s_and_saveexec_b64 s[58:59], s[76:77]
	s_cbranch_execz .LBB0_702
	v_mad_u64_u32 v[34:35], s[42:43], v66, s63, v[60:61]
	v_add_co_u32_e32 v34, vcc, 0xe88f000, v34
	v_cvt_pk_bf16_f32 v0, v36, s0
	s_nop 0
	v_addc_co_u32_e32 v35, vcc, 0, v35, vcc
	global_store_short v[34:35], v0, off offset:3616

.LBB0_703:
	v_mov_b32_e32 v67, v1
	v_lshlrev_b64 v[34:35], 10, v[66:67]
	v_cvt_pk_bf16_f32 v0, v36, s0
	v_lshl_add_u64 v[34:35], v[62:63], 0, v[34:35]
	global_store_short v[34:35], v0, off offset:32
	s_or_b64 exec, exec, s[6:7]
	s_and_saveexec_b64 s[6:7], s[2:3]
	s_xor_b64 s[6:7], exec, s[6:7]
	s_cbranch_execz .LBB0_691
.LBB0_704:
	s_and_saveexec_b64 s[58:59], s[76:77]
	s_cbranch_execz .LBB0_706
	v_mad_u64_u32 v[34:35], s[42:43], v42, s63, v[60:61]
	v_add_co_u32_e32 v34, vcc, 0xe88f000, v34
	v_cvt_pk_bf16_f32 v0, v37, s0
	s_nop 0
	v_addc_co_u32_e32 v35, vcc, 0, v35, vcc
	global_store_short v[34:35], v0, off offset:3616

.LBB0_707:
	v_mov_b32_e32 v43, v1
	v_lshlrev_b64 v[34:35], 10, v[42:43]
	v_cvt_pk_bf16_f32 v0, v37, s0
	v_lshl_add_u64 v[34:35], v[62:63], 0, v[34:35]
	global_store_short v[34:35], v0, off offset:32
	s_branch .LBB0_659

.LBB0_709:
	s_andn2_saveexec_b64 s[6:7], s[44:45]
	s_cbranch_execz .LBB0_619
	v_mul_hi_i32 v2, v0, s61
	v_ashrrev_i32_e32 v3, 7, v2
	v_lshrrev_b32_e32 v4, 31, v2
	v_ashrrev_i32_e32 v2, 5, v2
	v_add_u32_e32 v2, v2, v4
	s_movk_i32 s0, 0x44
	v_and_b32_e32 v180, 3, v2
	v_mul_lo_u32 v2, v2, s0
	v_sub_u32_e32 v176, v0, v2
	v_mov_b32_e32 v175, v201
	v_add_u32_e32 v179, v3, v4
	v_lshlrev_b32_e32 v0, 6, v176
	s_movk_i32 s2, 0x1100
	v_lshlrev_b32_e32 v178, 4, v175
	v_mad_i32_i24 v182, v179, s2, v0
	v_bfe_u32 v177, v175, 2, 6
	v_and_b32_e32 v181, 48, v178
	v_or_b32_e32 v5, v177, v182
	v_lshl_or_b32 v4, v180, 6, v181
	v_mov_b64_e32 v[8:9], s[20:21]
	v_mad_i64_i32 v[2:3], s[0:1], v5, s83, v[8:9]
	v_lshlrev_b32_e32 v0, 1, v4
	v_lshl_add_u64 v[2:3], v[2:3], 0, v[0:1]
	s_waitcnt lgkmcnt(0)
	s_barrier
	global_load_dwordx4 v[50:53], v[2:3], off
	global_load_dwordx4 v[26:29], v[2:3], off offset:16
	v_mul_i32_i24_e32 v6, 0x1100, v179
	v_mad_i32_i24 v7, v179, s2, v210
	v_cmp_gt_i32_e32 vcc, 4, v176
	v_mov_b32_e32 v30, 0
	v_mov_b32_e32 v34, 0
	v_cndmask_b32_e32 v10, v7, v6, vcc
	v_cmp_gt_i32_e64 s[0:1], v5, v10
	v_add_u32_e32 v10, -1, v5
	v_mad_i64_i32 v[8:9], s[2:3], v10, s83, v[8:9]
	v_mov_b32_e32 v35, 0
	v_mov_b32_e32 v36, 0
	v_mov_b32_e32 v37, 0
	v_mov_b32_e32 v54, 0
	v_mov_b32_e32 v55, 0
	v_mov_b32_e32 v56, 0
	v_mov_b32_e32 v57, 0
	s_and_saveexec_b64 s[2:3], s[0:1]
	s_cbranch_execz .LBB0_712
	v_lshl_add_u64 v[10:11], v[8:9], 0, v[0:1]
	global_load_dwordx4 v[54:57], v[10:11], off
	global_load_dwordx4 v[34:37], v[10:11], off offset:16
.LBB0_712:
	s_or_b64 exec, exec, s[2:3]
	v_add_u32_e32 v6, 0x1100, v6
	v_cndmask_b32_e32 v6, v6, v7, vcc
	v_add_u32_e32 v5, 1, v5
	v_cmp_lt_i32_e64 s[2:3], v5, v6
	v_mov_b64_e32 v[6:7], s[20:21]
	v_mad_i64_i32 v[172:173], s[4:5], v5, s83, v[6:7]
	v_mov_b32_e32 v31, 0
	v_mov_b32_e32 v32, 0
	v_mov_b32_e32 v33, 0
	v_mov_b32_e32 v70, 0
	v_mov_b32_e32 v71, 0
	v_mov_b32_e32 v72, 0
	v_mov_b32_e32 v73, 0
	s_and_saveexec_b64 s[4:5], s[2:3]
	s_cbranch_execz .LBB0_714
	v_lshl_add_u64 v[6:7], v[172:173], 0, v[0:1]
	global_load_dwordx4 v[70:73], v[6:7], off
	global_load_dwordx4 v[30:33], v[6:7], off offset:16
.LBB0_714:
	s_or_b64 exec, exec, s[4:5]
	v_lshlrev_b32_e32 v4, 2, v4
	v_mov_b32_e32 v5, v1
	v_lshl_add_u64 v[170:171], s[40:41], 0, v[4:5]
	v_add_co_u32_e32 v4, vcc, 0x1000, v170
	v_mov_b32_e32 v102, 0
	s_nop 0
	v_addc_co_u32_e32 v5, vcc, 0, v171, vcc
	global_load_dwordx4 v[86:89], v[170:171], off
	global_load_dwordx4 v[78:81], v[170:171], off offset:16
	global_load_dwordx4 v[94:97], v[170:171], off offset:3072
	global_load_dwordx4 v[82:85], v[170:171], off offset:3088
	global_load_dwordx4 v[90:93], v[4:5], off offset:2048
	global_load_dwordx4 v[74:77], v[4:5], off offset:2064
	global_load_dwordx4 v[58:61], v[170:171], off offset:32
	global_load_dwordx4 v[42:45], v[170:171], off offset:48
	global_load_dwordx4 v[66:69], v[170:171], off offset:3104
	global_load_dwordx4 v[46:49], v[170:171], off offset:3120
	global_load_dwordx4 v[62:65], v[4:5], off offset:2080
	global_load_dwordx4 v[38:41], v[4:5], off offset:2096
	global_load_dwordx4 v[122:125], v[2:3], off offset:512
	global_load_dwordx4 v[98:101], v[2:3], off offset:528
	v_mov_b32_e32 v106, 0
	v_mov_b32_e32 v107, 0
	v_mov_b32_e32 v108, 0
	v_mov_b32_e32 v109, 0
	v_mov_b32_e32 v126, 0
	v_mov_b32_e32 v127, 0
	v_mov_b32_e32 v128, 0
	v_mov_b32_e32 v129, 0
	s_and_saveexec_b64 s[4:5], s[0:1]
	s_cbranch_execz .LBB0_716
	v_lshl_add_u64 v[4:5], v[8:9], 0, v[0:1]
	global_load_dwordx4 v[126:129], v[4:5], off offset:512
	global_load_dwordx4 v[106:109], v[4:5], off offset:528
.LBB0_716:
	s_or_b64 exec, exec, s[4:5]
	v_mov_b32_e32 v103, 0
	v_mov_b32_e32 v104, 0
	v_mov_b32_e32 v105, 0
	v_mov_b32_e32 v142, 0
	v_mov_b32_e32 v143, 0
	v_mov_b32_e32 v144, 0
	v_mov_b32_e32 v145, 0
	s_and_saveexec_b64 s[4:5], s[2:3]
	s_cbranch_execz .LBB0_718
	v_lshl_add_u64 v[4:5], v[172:173], 0, v[0:1]
	global_load_dwordx4 v[142:145], v[4:5], off offset:512
	global_load_dwordx4 v[102:105], v[4:5], off offset:528
.LBB0_718:
	s_or_b64 exec, exec, s[4:5]
	s_mov_b64 s[4:5], 0x400
	v_add_co_u32_e32 v6, vcc, 0x1000, v170
	v_lshl_add_u64 v[4:5], v[170:171], 0, s[4:5]
	s_nop 0
	v_addc_co_u32_e32 v7, vcc, 0, v171, vcc
	global_load_dwordx4 v[158:161], v[170:171], off offset:1024
	global_load_dwordx4 v[146:149], v[170:171], off offset:1040
	global_load_dwordx4 v[162:165], v[4:5], off offset:3072
	global_load_dwordx4 v[150:153], v[4:5], off offset:3088
	global_load_dwordx4 v[166:169], v[6:7], off offset:3072
	global_load_dwordx4 v[154:157], v[6:7], off offset:3088
	global_load_dwordx4 v[130:133], v[170:171], off offset:1056
	global_load_dwordx4 v[110:113], v[170:171], off offset:1072
	global_load_dwordx4 v[134:137], v[4:5], off offset:3104
	global_load_dwordx4 v[114:117], v[4:5], off offset:3120
	global_load_dwordx4 v[138:141], v[6:7], off offset:3104
	global_load_dwordx4 v[118:121], v[6:7], off offset:3120
	global_load_dwordx4 v[14:17], v[2:3], off offset:1024
	s_nop 0
	global_load_dwordx4 v[2:5], v[2:3], off offset:1040
	v_mov_b32_e32 v6, 0
	v_mov_b32_e32 v10, 0
	v_mov_b32_e32 v11, 0
	v_mov_b32_e32 v12, 0
	v_mov_b32_e32 v13, 0
	v_mov_b32_e32 v18, 0
	v_mov_b32_e32 v19, 0
	v_mov_b32_e32 v20, 0
	v_mov_b32_e32 v21, 0
	s_and_saveexec_b64 s[4:5], s[0:1]
	s_cbranch_execz .LBB0_720
	v_lshl_add_u64 v[8:9], v[8:9], 0, v[0:1]
	global_load_dwordx4 v[18:21], v[8:9], off offset:1024
	global_load_dwordx4 v[10:13], v[8:9], off offset:1040
.LBB0_720:
	s_or_b64 exec, exec, s[4:5]
	v_mov_b32_e32 v7, 0
	v_mov_b32_e32 v8, 0
	v_mov_b32_e32 v9, 0
	v_mov_b32_e32 v22, 0
	v_mov_b32_e32 v23, 0
	v_mov_b32_e32 v24, 0
	v_mov_b32_e32 v25, 0
	s_and_saveexec_b64 s[0:1], s[2:3]
	s_cbranch_execz .LBB0_722
	v_lshl_add_u64 v[6:7], v[172:173], 0, v[0:1]
	global_load_dwordx4 v[22:25], v[6:7], off offset:1024
	s_nop 0
	global_load_dwordx4 v[6:9], v[6:7], off offset:1040
.LBB0_722:
	s_or_b64 exec, exec, s[0:1]
	s_waitcnt vmcnt(0) lgkmcnt(0)
	v_lshlrev_b32_e32 v184, 16, v122
	v_and_b32_e32 v185, 0xffff0000, v122
	v_lshlrev_b32_e32 v172, 16, v126
	v_and_b32_e32 v173, 0xffff0000, v126
	v_pk_mul_f32 v[162:163], v[162:163], v[184:185]
	v_lshlrev_b32_e32 v186, 16, v142
	v_and_b32_e32 v187, 0xffff0000, v142
	v_pk_fma_f32 v[158:159], v[158:159], v[172:173], v[162:163]
	v_lshlrev_b32_e32 v126, 16, v127
	v_pk_fma_f32 v[158:159], v[166:167], v[186:187], v[158:159]
	v_and_b32_e32 v127, 0xffff0000, v127
	v_mul_f32_e32 v0, 0xbfb8aa3b, v158
	v_exp_f32_e32 v0, v0
	v_mul_f32_e32 v122, 0xbfb8aa3b, v159
	v_exp_f32_e32 v122, v122
	v_lshlrev_b32_e32 v166, 16, v143
	v_add_f32_e32 v0, 1.0, v0
	v_rcp_f32_e32 v162, v0
	v_add_f32_e32 v0, 1.0, v122
	v_lshlrev_b32_e32 v122, 16, v123
	v_and_b32_e32 v123, 0xffff0000, v123
	v_pk_mul_f32 v[122:123], v[164:165], v[122:123]
	v_and_b32_e32 v167, 0xffff0000, v143
	v_pk_fma_f32 v[122:123], v[160:161], v[126:127], v[122:123]
	v_rcp_f32_e32 v163, v0
	v_pk_fma_f32 v[126:127], v[168:169], v[166:167], v[122:123]
	v_lshlrev_b32_e32 v160, 16, v128
	v_mul_f32_e32 v0, 0xbfb8aa3b, v126
	v_exp_f32_e32 v0, v0
	v_mul_f32_e32 v122, 0xbfb8aa3b, v127
	v_exp_f32_e32 v143, v122
	v_pk_mul_f32 v[122:123], v[158:159], v[162:163]
	v_lshlrev_b32_e32 v162, 16, v124
	v_and_b32_e32 v163, 0xffff0000, v124
	v_and_b32_e32 v161, 0xffff0000, v128
	v_pk_mul_f32 v[150:151], v[150:151], v[162:163]
	v_add_f32_e32 v0, 1.0, v0
	v_lshlrev_b32_e32 v164, 16, v144
	v_and_b32_e32 v165, 0xffff0000, v144
	v_pk_fma_f32 v[146:147], v[146:147], v[160:161], v[150:151]
	v_rcp_f32_e32 v158, v0
	v_add_f32_e32 v0, 1.0, v143
	v_pk_fma_f32 v[146:147], v[154:155], v[164:165], v[146:147]
	v_rcp_f32_e32 v159, v0
	v_mul_f32_e32 v0, 0xbfb8aa3b, v146
	v_exp_f32_e32 v0, v0
	v_mul_f32_e32 v124, 0xbfb8aa3b, v147
	v_exp_f32_e32 v124, v124
	v_lshlrev_b32_e32 v128, 16, v129
	v_add_f32_e32 v0, 1.0, v0
	v_rcp_f32_e32 v150, v0
	v_add_f32_e32 v0, 1.0, v124
	v_lshlrev_b32_e32 v124, 16, v125
	v_and_b32_e32 v125, 0xffff0000, v125
	v_and_b32_e32 v129, 0xffff0000, v129
	v_pk_mul_f32 v[124:125], v[152:153], v[124:125]
	v_lshlrev_b32_e32 v144, 16, v145
	v_and_b32_e32 v145, 0xffff0000, v145
	v_pk_fma_f32 v[124:125], v[148:149], v[128:129], v[124:125]
	v_rcp_f32_e32 v151, v0
	v_pk_fma_f32 v[128:129], v[156:157], v[144:145], v[124:125]
	v_lshlrev_b32_e32 v148, 16, v98
	v_mul_f32_e32 v0, 0xbfb8aa3b, v128
	v_exp_f32_e32 v0, v0
	v_mul_f32_e32 v124, 0xbfb8aa3b, v129
	v_exp_f32_e32 v143, v124
	v_and_b32_e32 v149, 0xffff0000, v98
	v_pk_mul_f32 v[124:125], v[146:147], v[150:151]
	v_lshlrev_b32_e32 v146, 16, v106
	v_and_b32_e32 v147, 0xffff0000, v106
	v_pk_mul_f32 v[134:135], v[134:135], v[148:149]
	v_add_f32_e32 v0, 1.0, v0
	v_lshlrev_b32_e32 v150, 16, v102
	v_and_b32_e32 v151, 0xffff0000, v102
	v_pk_fma_f32 v[130:131], v[130:131], v[146:147], v[134:135]
	v_rcp_f32_e32 v144, v0
	v_add_f32_e32 v0, 1.0, v143
	v_pk_fma_f32 v[130:131], v[138:139], v[150:151], v[130:131]
	v_rcp_f32_e32 v145, v0
	v_mul_f32_e32 v0, 0xbfb8aa3b, v130
	v_exp_f32_e32 v0, v0
	v_mul_f32_e32 v98, 0xbfb8aa3b, v131
	v_exp_f32_e32 v102, v98
	v_lshlrev_b32_e32 v134, 16, v99
	v_and_b32_e32 v135, 0xffff0000, v99
	v_add_f32_e32 v0, 1.0, v0
	v_lshlrev_b32_e32 v106, 16, v107
	v_and_b32_e32 v107, 0xffff0000, v107
	v_pk_mul_f32 v[134:135], v[136:137], v[134:135]
	v_rcp_f32_e32 v98, v0
	v_add_f32_e32 v0, 1.0, v102
	v_lshlrev_b32_e32 v102, 16, v103
	v_and_b32_e32 v103, 0xffff0000, v103
	v_pk_fma_f32 v[106:107], v[132:133], v[106:107], v[134:135]
	v_lshlrev_b32_e32 v134, 16, v100
	v_and_b32_e32 v135, 0xffff0000, v100
	v_pk_fma_f32 v[102:103], v[140:141], v[102:103], v[106:107]
	v_lshlrev_b32_e32 v132, 16, v108
	v_and_b32_e32 v133, 0xffff0000, v108
	v_pk_mul_f32 v[114:115], v[114:115], v[134:135]
	v_mul_f32_e32 v99, 0xbfb8aa3b, v102
	v_lshlrev_b32_e32 v136, 16, v104
	v_and_b32_e32 v137, 0xffff0000, v104
	v_pk_fma_f32 v[110:111], v[110:111], v[132:133], v[114:115]
	v_exp_f32_e32 v106, v99
	v_mul_f32_e32 v99, 0xbfb8aa3b, v103
	v_pk_fma_f32 v[110:111], v[118:119], v[136:137], v[110:111]
	v_exp_f32_e32 v107, v99
	v_mul_f32_e32 v100, 0xbfb8aa3b, v110
	v_exp_f32_e32 v100, v100
	v_mul_f32_e32 v104, 0xbfb8aa3b, v111
	v_rcp_f32_e32 v99, v0
	v_add_f32_e32 v0, 1.0, v106
	v_exp_f32_e32 v104, v104
	v_rcp_f32_e32 v106, v0
	v_add_f32_e32 v0, 1.0, v107
	v_rcp_f32_e32 v107, v0
	v_add_f32_e32 v0, 1.0, v100
	v_lshlrev_b32_e32 v100, 16, v101
	v_and_b32_e32 v101, 0xffff0000, v101
	v_lshlrev_b32_e32 v114, 16, v109
	v_and_b32_e32 v115, 0xffff0000, v109
	v_pk_mul_f32 v[100:101], v[116:117], v[100:101]
	v_rcp_f32_e32 v108, v0
	v_add_f32_e32 v0, 1.0, v104
	v_lshlrev_b32_e32 v104, 16, v105
	v_and_b32_e32 v105, 0xffff0000, v105
	v_pk_fma_f32 v[100:101], v[112:113], v[114:115], v[100:101]
	v_rcp_f32_e32 v109, v0
	v_pk_fma_f32 v[112:113], v[120:121], v[104:105], v[100:101]
	v_pk_mul_f32 v[104:105], v[130:131], v[98:99]
	v_mul_f32_e32 v100, 0xbfb8aa3b, v112
	v_exp_f32_e32 v100, v100
	v_mul_f32_e32 v101, 0xbfb8aa3b, v113
	v_exp_f32_e32 v101, v101
	v_pk_mul_f32 v[98:99], v[110:111], v[108:109]
	v_add_f32_e32 v0, 1.0, v100
	v_lshlrev_b32_e32 v108, 16, v50
	v_and_b32_e32 v109, 0xffff0000, v50
	v_rcp_f32_e32 v114, v0
	v_add_f32_e32 v0, 1.0, v101
	v_pk_mul_f32 v[100:101], v[102:103], v[106:107]
	v_lshlrev_b32_e32 v106, 16, v54
	v_and_b32_e32 v107, 0xffff0000, v54
	v_pk_mul_f32 v[94:95], v[94:95], v[108:109]
	v_rcp_f32_e32 v115, v0
	v_pk_fma_f32 v[86:87], v[86:87], v[106:107], v[94:95]
	v_lshlrev_b32_e32 v94, 16, v70
	v_and_b32_e32 v95, 0xffff0000, v70
	v_pk_fma_f32 v[86:87], v[90:91], v[94:95], v[86:87]
	v_lshlrev_b32_e32 v54, 16, v55
	v_mul_f32_e32 v0, 0xbfb8aa3b, v86
	v_exp_f32_e32 v0, v0
	v_mul_f32_e32 v50, 0xbfb8aa3b, v87
	v_exp_f32_e32 v50, v50
	v_and_b32_e32 v55, 0xffff0000, v55
	v_add_f32_e32 v0, 1.0, v0
	v_rcp_f32_e32 v94, v0
	v_add_f32_e32 v0, 1.0, v50
	v_lshlrev_b32_e32 v50, 16, v51
	v_and_b32_e32 v51, 0xffff0000, v51
	v_pk_mul_f32 v[50:51], v[96:97], v[50:51]
	v_rcp_f32_e32 v95, v0
	v_pk_fma_f32 v[50:51], v[88:89], v[54:55], v[50:51]
	v_lshlrev_b32_e32 v54, 16, v71
	v_and_b32_e32 v55, 0xffff0000, v71
	v_pk_fma_f32 v[50:51], v[92:93], v[54:55], v[50:51]
	v_lshlrev_b32_e32 v88, 16, v52
	v_mul_f32_e32 v0, 0xbfb8aa3b, v50
	v_exp_f32_e32 v0, v0
	v_mul_f32_e32 v54, 0xbfb8aa3b, v51
	v_exp_f32_e32 v55, v54
	v_and_b32_e32 v89, 0xffff0000, v52
	v_lshlrev_b32_e32 v70, 16, v56
	v_and_b32_e32 v71, 0xffff0000, v56
	v_pk_mul_f32 v[82:83], v[82:83], v[88:89]
	v_add_f32_e32 v0, 1.0, v0
	v_pk_fma_f32 v[70:71], v[78:79], v[70:71], v[82:83]
	v_lshlrev_b32_e32 v78, 16, v72
	v_and_b32_e32 v79, 0xffff0000, v72
	v_rcp_f32_e32 v54, v0
	v_add_f32_e32 v0, 1.0, v55
	v_pk_fma_f32 v[70:71], v[74:75], v[78:79], v[70:71]
	v_rcp_f32_e32 v55, v0
	v_mul_f32_e32 v0, 0xbfb8aa3b, v70
	v_exp_f32_e32 v0, v0
	v_mul_f32_e32 v52, 0xbfb8aa3b, v71
	v_exp_f32_e32 v52, v52
	v_pk_mul_f32 v[74:75], v[50:51], v[54:55]
	v_add_f32_e32 v0, 1.0, v0
	v_rcp_f32_e32 v50, v0
	v_add_f32_e32 v0, 1.0, v52
	v_lshlrev_b32_e32 v52, 16, v53
	v_and_b32_e32 v53, 0xffff0000, v53
	v_lshlrev_b32_e32 v54, 16, v57
	v_and_b32_e32 v55, 0xffff0000, v57
	v_pk_mul_f32 v[52:53], v[84:85], v[52:53]
	v_rcp_f32_e32 v51, v0
	v_pk_fma_f32 v[52:53], v[80:81], v[54:55], v[52:53]
	v_lshlrev_b32_e32 v54, 16, v73
	v_and_b32_e32 v55, 0xffff0000, v73
	v_pk_fma_f32 v[52:53], v[76:77], v[54:55], v[52:53]
	v_lshlrev_b32_e32 v56, 16, v26
	v_mul_f32_e32 v0, 0xbfb8aa3b, v52
	v_exp_f32_e32 v0, v0
	v_mul_f32_e32 v54, 0xbfb8aa3b, v53
	v_exp_f32_e32 v54, v54
	v_and_b32_e32 v57, 0xffff0000, v26
	v_add_f32_e32 v0, 1.0, v0
	v_pk_mul_f32 v[76:77], v[70:71], v[50:51]
	v_rcp_f32_e32 v50, v0
	v_add_f32_e32 v0, 1.0, v54
	v_lshlrev_b32_e32 v54, 16, v34
	v_and_b32_e32 v55, 0xffff0000, v34
	v_pk_mul_f32 v[56:57], v[66:67], v[56:57]
	v_rcp_f32_e32 v51, v0
	v_pk_fma_f32 v[54:55], v[58:59], v[54:55], v[56:57]
	v_lshlrev_b32_e32 v56, 16, v30
	v_and_b32_e32 v57, 0xffff0000, v30
	v_pk_fma_f32 v[54:55], v[62:63], v[56:57], v[54:55]
	v_pk_mul_f32 v[78:79], v[52:53], v[50:51]
	v_mul_f32_e32 v0, 0xbfb8aa3b, v54
	v_exp_f32_e32 v0, v0
	v_mul_f32_e32 v26, 0xbfb8aa3b, v55
	v_exp_f32_e32 v26, v26
	v_lshlrev_b32_e32 v34, 16, v35
	v_add_f32_e32 v0, 1.0, v0
	v_rcp_f32_e32 v50, v0
	v_add_f32_e32 v0, 1.0, v26
	v_lshlrev_b32_e32 v26, 16, v27
	v_and_b32_e32 v27, 0xffff0000, v27
	v_and_b32_e32 v35, 0xffff0000, v35
	v_pk_mul_f32 v[26:27], v[68:69], v[26:27]
	v_lshlrev_b32_e32 v30, 16, v31
	v_pk_fma_f32 v[26:27], v[60:61], v[34:35], v[26:27]
	v_and_b32_e32 v31, 0xffff0000, v31
	v_pk_fma_f32 v[82:83], v[64:65], v[30:31], v[26:27]
	v_rcp_f32_e32 v51, v0
	v_mul_f32_e32 v0, 0xbfb8aa3b, v82
	v_exp_f32_e32 v0, v0
	v_mul_f32_e32 v26, 0xbfb8aa3b, v83
	v_exp_f32_e32 v26, v26
	v_lshlrev_b32_e32 v30, 16, v28
	v_add_f32_e32 v0, 1.0, v0
	v_and_b32_e32 v31, 0xffff0000, v28
	v_rcp_f32_e32 v84, v0
	v_add_f32_e32 v0, 1.0, v26
	v_lshlrev_b32_e32 v26, 16, v36
	v_and_b32_e32 v27, 0xffff0000, v36
	v_pk_mul_f32 v[30:31], v[46:47], v[30:31]
	v_rcp_f32_e32 v85, v0
	v_pk_fma_f32 v[26:27], v[42:43], v[26:27], v[30:31]
	v_lshlrev_b32_e32 v30, 16, v32
	v_and_b32_e32 v31, 0xffff0000, v32
	v_pk_fma_f32 v[92:93], v[38:39], v[30:31], v[26:27]
	v_lshlrev_b32_e32 v28, 16, v29
	v_mul_f32_e32 v26, 0xbfb8aa3b, v92
	v_exp_f32_e32 v26, v26
	v_mul_f32_e32 v27, 0xbfb8aa3b, v93
	v_exp_f32_e32 v27, v27
	v_and_b32_e32 v29, 0xffff0000, v29
	v_add_f32_e32 v0, 1.0, v26
	v_pk_mul_f32 v[86:87], v[86:87], v[94:95]
	v_rcp_f32_e32 v94, v0
	v_add_f32_e32 v0, 1.0, v27
	v_lshlrev_b32_e32 v26, 16, v37
	v_and_b32_e32 v27, 0xffff0000, v37
	v_pk_mul_f32 v[28:29], v[48:49], v[28:29]
	s_movk_i32 s0, 0x2000
	v_pk_fma_f32 v[26:27], v[44:45], v[26:27], v[28:29]
	v_lshlrev_b32_e32 v28, 16, v33
	v_and_b32_e32 v29, 0xffff0000, v33
	v_pk_fma_f32 v[96:97], v[40:41], v[28:29], v[26:27]
	v_add_co_u32_e32 v34, vcc, s0, v170
	v_mul_f32_e32 v26, 0xbfb8aa3b, v96
	v_exp_f32_e32 v26, v26
	v_mul_f32_e32 v27, 0xbfb8aa3b, v97
	v_exp_f32_e32 v27, v27
	v_rcp_f32_e32 v95, v0
	v_add_f32_e32 v0, 1.0, v26
	v_addc_co_u32_e32 v35, vcc, 0, v171, vcc
	v_lshl_add_u64 v[90:91], v[170:171], 0, s[68:69]
	v_pk_mul_f32 v[80:81], v[54:55], v[50:51]
	v_rcp_f32_e32 v106, v0
	v_add_f32_e32 v0, 1.0, v27
	global_load_dwordx4 v[62:65], v[170:171], off offset:2048
	global_load_dwordx4 v[50:53], v[170:171], off offset:2064
	global_load_dwordx4 v[66:69], v[90:91], off offset:3072
	global_load_dwordx4 v[54:57], v[90:91], off offset:3088
	global_load_dwordx4 v[70:73], v[34:35], off
	global_load_dwordx4 v[58:61], v[34:35], off offset:16
	global_load_dwordx4 v[38:41], v[170:171], off offset:2080
	global_load_dwordx4 v[26:29], v[170:171], off offset:2096
	global_load_dwordx4 v[42:45], v[90:91], off offset:3104
	global_load_dwordx4 v[30:33], v[90:91], off offset:3120
	global_load_dwordx4 v[46:49], v[34:35], off offset:32
	s_nop 0
	global_load_dwordx4 v[34:37], v[34:35], off offset:48
	v_rcp_f32_e32 v107, v0
	v_mov_b32_e32 v108, v123
	v_mov_b32_e32 v109, v87
	v_pk_mul_f32 v[126:127], v[126:127], v[158:159]
	v_pk_mul_f32 v[88:89], v[82:83], v[84:85]
	v_pk_mul_f32 v[82:83], v[96:97], v[106:107]
	v_mov_b32_e32 v106, v122
	v_mov_b32_e32 v107, v86
	v_pk_mul_f32 v[108:109], v[108:109], v[108:109]
	v_pk_mul_f32 v[128:129], v[128:129], v[144:145]
	v_pk_fma_f32 v[106:107], v[106:107], v[106:107], v[108:109]
	v_mov_b32_e32 v108, v126
	v_mov_b32_e32 v109, v74
	v_pk_fma_f32 v[106:107], v[108:109], v[108:109], v[106:107]
	v_mov_b32_e32 v108, v127
	v_mov_b32_e32 v109, v75
	v_pk_fma_f32 v[106:107], v[108:109], v[108:109], v[106:107]
	v_mov_b32_e32 v108, v124
	v_mov_b32_e32 v109, v76
	v_pk_mul_f32 v[84:85], v[92:93], v[94:95]
	v_pk_mul_f32 v[90:91], v[78:79], v[78:79]
	v_pk_mul_f32 v[92:93], v[128:129], v[128:129]
	v_pk_fma_f32 v[106:107], v[108:109], v[108:109], v[106:107]
	v_mov_b32_e32 v108, v125
	v_mov_b32_e32 v109, v77
	v_pk_fma_f32 v[106:107], v[108:109], v[108:109], v[106:107]
	v_mov_b32_e32 v108, v92
	v_mov_b32_e32 v109, v90
	v_pk_add_f32 v[106:107], v[106:107], v[108:109]
	v_mov_b32_e32 v90, v93
	v_pk_add_f32 v[90:91], v[106:107], v[90:91]
	v_pk_mul_f32 v[92:93], v[80:81], v[80:81]
	v_pk_mul_f32 v[106:107], v[104:105], v[104:105]
	v_mov_b32_e32 v121, v92
	v_mov_b32_e32 v120, v106
	v_pk_mul_f32 v[108:109], v[88:89], v[88:89]
	v_pk_mul_f32 v[110:111], v[100:101], v[100:101]
	v_pk_add_f32 v[90:91], v[90:91], v[120:121]
	v_mov_b32_e32 v92, v107
	v_pk_add_f32 v[90:91], v[90:91], v[92:93]
	v_mov_b32_e32 v92, v110
	v_mov_b32_e32 v93, v108
	v_pk_mul_f32 v[102:103], v[112:113], v[114:115]
	v_pk_mul_f32 v[112:113], v[84:85], v[84:85]
	v_pk_mul_f32 v[114:115], v[98:99], v[98:99]
	v_pk_add_f32 v[90:91], v[90:91], v[92:93]
	v_mov_b32_e32 v108, v111
	v_and_b32_e32 v97, 64, v208
	v_pk_add_f32 v[90:91], v[90:91], v[108:109]
	v_mov_b32_e32 v92, v114
	v_mov_b32_e32 v93, v112
	v_pk_mul_f32 v[116:117], v[82:83], v[82:83]
	v_pk_mul_f32 v[118:119], v[102:103], v[102:103]
	v_xor_b32_e32 v0, 1, v208
	v_add_u32_e32 v95, 64, v97
	v_pk_add_f32 v[90:91], v[90:91], v[92:93]
	v_mov_b32_e32 v112, v115
	v_cmp_lt_i32_e32 vcc, v0, v95
	v_pk_add_f32 v[90:91], v[90:91], v[112:113]
	v_mov_b32_e32 v92, v118
	v_mov_b32_e32 v93, v116
	v_cndmask_b32_e32 v0, v208, v0, vcc
	v_pk_add_f32 v[90:91], v[90:91], v[92:93]
	v_mov_b32_e32 v116, v119
	v_lshlrev_b32_e32 v0, 2, v0
	v_pk_add_f32 v[90:91], v[90:91], v[116:117]
	ds_bpermute_b32 v93, v0, v91
	ds_bpermute_b32 v92, v0, v90
	v_xor_b32_e32 v0, 2, v208
	v_cmp_lt_i32_e32 vcc, v0, v95
	s_mov_b32 s0, 0xd000
	s_waitcnt lgkmcnt(0)
	v_pk_add_f32 v[90:91], v[90:91], v[92:93]
	v_cndmask_b32_e32 v0, v208, v0, vcc
	v_lshlrev_b32_e32 v0, 2, v0
	ds_bpermute_b32 v93, v0, v91
	ds_bpermute_b32 v92, v0, v90
	v_mov_b32_e32 v0, v201
	v_and_b32_e32 v142, 0xff, v175
	v_lshrrev_b32_e32 v0, 8, v0
	v_mad_i32_i24 v95, v0, s0, v207
	s_movk_i32 s0, 0x80
	v_and_b32_e32 v94, 63, v175
	v_lshrrev_b32_e32 v96, 6, v142
	v_cmp_gt_u32_e64 s[0:1], s0, v142
	s_and_saveexec_b64 s[4:5], s[0:1]
	s_cbranch_execz .LBB0_730
	v_cmp_gt_u32_e32 vcc, 64, v142
	v_xor_b32_e32 v0, 63, v94
	v_mov_b64_e32 v[106:107], s[20:21]
	v_cndmask_b32_e32 v0, v0, v94, vcc
	v_or_b32_e32 v0, v0, v182
	v_lshl_or_b32 v108, v96, 2, v180
	v_mad_i64_i32 v[106:107], s[2:3], v0, s83, v[106:107]
	v_lshlrev_b32_e32 v0, 1, v108
	v_lshl_add_u64 v[106:107], v[106:107], 0, v[0:1]
	global_load_ushort v0, v[106:107], off offset:1536
	v_readlane_b32 s2, v254, 51
	global_load_ushort v106, v[106:107], off offset:1552
	s_waitcnt vmcnt(0) lgkmcnt(0)
	v_lshlrev_b32_e32 v110, 16, v0
	v_or_b32_e32 v0, s2, v108
	v_readlane_b32 s2, v254, 47
	v_readlane_b32 s3, v254, 48
	s_nop 1
	v_lshl_add_u64 v[108:109], v[0:1], 2, s[2:3]
	global_load_dword v107, v[108:109], off
	s_mov_b32 s2, 0x41a00000
	s_waitcnt vmcnt(0) lgkmcnt(0)
	v_add_f32_e32 v107, v107, v110
	v_cmp_nlt_f32_e32 vcc, s2, v107
	s_and_saveexec_b64 s[44:45], vcc
	s_cbranch_execz .LBB0_729
	v_mul_f32_e32 v107, 0x3fb8aa3b, v107
	v_exp_f32_e32 v108, v107
	s_mov_b32 s2, 0x3cf5c28f
	v_cmp_ngt_f32_e32 vcc, s2, v108
	s_and_saveexec_b64 s[2:3], vcc
	s_xor_b64 s[54:55], exec, s[2:3]
	s_cbranch_execz .LBB0_726
	v_add_f32_e32 v107, 1.0, v108
	v_cmp_gt_f32_e32 vcc, s35, v107
	s_mov_b32 s2, 0x3f317217
	s_nop 0
	v_cndmask_b32_e64 v108, 0, 32, vcc
	v_ldexp_f32 v107, v107, v108
	v_log_f32_e32 v107, v107
	s_nop 0
	v_mul_f32_e32 v108, 0x3f317217, v107
	v_fma_f32 v108, v107, s2, -v108
	v_fmac_f32_e32 v108, 0x3377d1cf, v107
	s_mov_b32 s2, 0x7f800000
	v_fmac_f32_e32 v108, 0x3f317217, v107
	v_cmp_lt_f32_e64 s[2:3], |v107|, s2
	s_nop 1
	v_cndmask_b32_e64 v107, v107, v108, s[2:3]
	v_mov_b32_e32 v108, 0x41b17218
	v_cndmask_b32_e32 v108, 0, v108, vcc
	v_sub_f32_e32 v107, v107, v108

.LBB0_729:
	s_or_b64 exec, exec, s[44:45]
	v_readlane_b32 s2, v254, 45
	v_readlane_b32 s3, v254, 46
	v_lshlrev_b32_e32 v106, 16, v106
	v_mul_f32_e32 v106, 0xbfb8aa3b, v106
	v_lshl_add_u64 v[108:109], v[0:1], 2, s[2:3]
	global_load_dword v0, v[108:109], off
	v_add_u32_e32 v109, -1, v208
	v_cmp_lt_i32_e32 vcc, v109, v97
	v_exp_f32_e32 v106, v106
	s_waitcnt vmcnt(0) lgkmcnt(0)
	v_mul_f32_e32 v0, 0x3fb8aa3b, v0
	v_exp_f32_e32 v0, v0
	v_cndmask_b32_e32 v109, v109, v208, vcc
	v_lshlrev_b32_e32 v109, 2, v109
	v_cmp_eq_u32_e32 vcc, 0, v94
	v_mul_f32_e64 v108, v107, -v0
	ds_bpermute_b32 v109, v109, v108
	v_add_f32_e32 v106, 1.0, v106
	s_waitcnt lgkmcnt(0)
	v_fma_f32 v0, v107, -v0, v109
	v_add_u32_e32 v107, -2, v208
	v_cndmask_b32_e32 v0, v0, v108, vcc
	v_cmp_lt_i32_e32 vcc, v107, v97
	s_nop 1
	v_cndmask_b32_e32 v107, v107, v208, vcc
	v_lshlrev_b32_e32 v107, 2, v107
	ds_bpermute_b32 v107, v107, v0
	v_cmp_gt_u32_e32 vcc, 2, v94
	s_waitcnt lgkmcnt(0)
	v_add_f32_e32 v107, v0, v107
	v_cndmask_b32_e32 v0, v107, v0, vcc
	v_add_u32_e32 v107, -4, v208
	v_cmp_lt_i32_e32 vcc, v107, v97
	s_nop 1
	v_cndmask_b32_e32 v107, v107, v208, vcc
	v_lshlrev_b32_e32 v107, 2, v107
	ds_bpermute_b32 v107, v107, v0
	v_cmp_gt_u32_e32 vcc, 4, v94
	s_waitcnt lgkmcnt(0)
	v_add_f32_e32 v107, v0, v107
	v_cndmask_b32_e32 v0, v107, v0, vcc
	v_add_u32_e32 v107, -8, v208
	v_cmp_lt_i32_e32 vcc, v107, v97
	s_nop 1
	v_cndmask_b32_e32 v107, v107, v208, vcc
	v_lshlrev_b32_e32 v107, 2, v107
	ds_bpermute_b32 v107, v107, v0
	v_cmp_gt_u32_e32 vcc, 8, v94
	s_waitcnt lgkmcnt(0)
	v_add_f32_e32 v107, v0, v107
	v_cndmask_b32_e32 v0, v107, v0, vcc
	v_add_u32_e32 v107, -16, v208
	v_cmp_lt_i32_e32 vcc, v107, v97
	s_nop 1
	v_cndmask_b32_e32 v107, v107, v208, vcc
	v_lshlrev_b32_e32 v107, 2, v107
	ds_bpermute_b32 v107, v107, v0
	v_cmp_gt_u32_e32 vcc, 16, v94
	s_waitcnt lgkmcnt(0)
	v_add_f32_e32 v107, v0, v107
	v_cndmask_b32_e32 v0, v107, v0, vcc
	v_subrev_u32_e32 v107, 32, v208
	v_cmp_lt_i32_e32 vcc, v107, v97
	s_nop 1
	v_cndmask_b32_e32 v97, v107, v208, vcc
	v_lshlrev_b32_e32 v97, 2, v97
	ds_bpermute_b32 v97, v97, v0
	v_div_scale_f32 v107, s[2:3], v106, v106, 1.0
	v_rcp_f32_e32 v108, v107
	v_cmp_gt_u32_e32 vcc, 32, v94
	s_waitcnt lgkmcnt(0)
	v_add_f32_e32 v97, v0, v97
	v_fma_f32 v109, -v107, v108, 1.0
	v_cndmask_b32_e32 v0, v97, v0, vcc
	v_fmac_f32_e32 v108, v109, v108
	v_div_scale_f32 v109, vcc, 1.0, v106, 1.0
	v_mul_f32_e32 v110, v109, v108
	v_fma_f32 v111, -v107, v110, v109
	v_fmac_f32_e32 v110, v111, v108
	v_fma_f32 v107, -v107, v110, v109
	v_div_fmas_f32 v107, v107, v108, v110
	v_lshl_add_u32 v97, v142, 2, v95
	v_div_fixup_f32 v106, v107, v106, 1.0
	ds_write2st64_b32 v97, v0, v106 offset0:204 offset1:206
.LBB0_730:
	s_or_b64 exec, exec, s[4:5]
	v_lshlrev_b32_e32 v108, 16, v14
	v_and_b32_e32 v109, 0xffff0000, v14
	v_lshlrev_b32_e32 v106, 16, v18
	v_and_b32_e32 v107, 0xffff0000, v18
	s_waitcnt vmcnt(0)
	v_pk_mul_f32 v[66:67], v[66:67], v[108:109]
	v_lshlrev_b32_e32 v110, 16, v22
	v_and_b32_e32 v111, 0xffff0000, v22
	v_pk_fma_f32 v[62:63], v[62:63], v[106:107], v[66:67]
	v_lshlrev_b32_e32 v18, 16, v19
	v_pk_fma_f32 v[62:63], v[70:71], v[110:111], v[62:63]
	v_and_b32_e32 v19, 0xffff0000, v19
	v_mul_f32_e32 v0, 0xbfb8aa3b, v62
	v_exp_f32_e32 v0, v0
	v_mul_f32_e32 v14, 0xbfb8aa3b, v63
	v_exp_f32_e32 v14, v14
	v_lshlrev_b32_e32 v22, 16, v23
	v_add_f32_e32 v0, 1.0, v0
	v_rcp_f32_e32 v66, v0
	v_add_f32_e32 v0, 1.0, v14
	v_lshlrev_b32_e32 v14, 16, v15
	v_and_b32_e32 v15, 0xffff0000, v15
	v_pk_mul_f32 v[14:15], v[68:69], v[14:15]
	v_and_b32_e32 v23, 0xffff0000, v23
	v_pk_fma_f32 v[14:15], v[64:65], v[18:19], v[14:15]
	v_rcp_f32_e32 v67, v0
	v_pk_fma_f32 v[14:15], v[72:73], v[22:23], v[14:15]
	v_lshlrev_b32_e32 v64, 16, v16
	v_mul_f32_e32 v0, 0xbfb8aa3b, v14
	v_exp_f32_e32 v0, v0
	v_mul_f32_e32 v18, 0xbfb8aa3b, v15
	v_exp_f32_e32 v19, v18
	v_and_b32_e32 v65, 0xffff0000, v16
	v_lshlrev_b32_e32 v22, 16, v20
	v_and_b32_e32 v23, 0xffff0000, v20
	v_pk_mul_f32 v[54:55], v[54:55], v[64:65]
	v_pk_mul_f32 v[62:63], v[62:63], v[66:67]
	v_add_f32_e32 v0, 1.0, v0
	v_lshlrev_b32_e32 v66, 16, v24
	v_and_b32_e32 v67, 0xffff0000, v24
	v_pk_fma_f32 v[22:23], v[50:51], v[22:23], v[54:55]
	v_rcp_f32_e32 v18, v0
	v_add_f32_e32 v0, 1.0, v19
	v_pk_fma_f32 v[22:23], v[58:59], v[66:67], v[22:23]
	v_rcp_f32_e32 v19, v0
	v_mul_f32_e32 v0, 0xbfb8aa3b, v22
	v_exp_f32_e32 v0, v0
	v_mul_f32_e32 v16, 0xbfb8aa3b, v23
	v_exp_f32_e32 v16, v16
	v_pk_mul_f32 v[64:65], v[14:15], v[18:19]
	v_add_f32_e32 v0, 1.0, v0
	v_rcp_f32_e32 v14, v0
	v_add_f32_e32 v0, 1.0, v16
	v_lshlrev_b32_e32 v16, 16, v17
	v_and_b32_e32 v17, 0xffff0000, v17
	v_lshlrev_b32_e32 v18, 16, v21
	v_and_b32_e32 v19, 0xffff0000, v21
	v_pk_mul_f32 v[16:17], v[56:57], v[16:17]
	v_lshlrev_b32_e32 v20, 16, v25
	v_and_b32_e32 v21, 0xffff0000, v25
	v_pk_fma_f32 v[16:17], v[52:53], v[18:19], v[16:17]
	v_rcp_f32_e32 v15, v0
	v_pk_fma_f32 v[16:17], v[60:61], v[20:21], v[16:17]
	v_lshlrev_b32_e32 v20, 16, v10
	v_mul_f32_e32 v0, 0xbfb8aa3b, v16
	v_exp_f32_e32 v0, v0
	v_mul_f32_e32 v18, 0xbfb8aa3b, v17
	v_exp_f32_e32 v19, v18
	v_pk_mul_f32 v[14:15], v[22:23], v[14:15]
	v_lshlrev_b32_e32 v22, 16, v2
	v_and_b32_e32 v23, 0xffff0000, v2
	v_and_b32_e32 v21, 0xffff0000, v10
	v_pk_mul_f32 v[22:23], v[42:43], v[22:23]
	v_add_f32_e32 v0, 1.0, v0
	v_lshlrev_b32_e32 v24, 16, v6
	v_and_b32_e32 v25, 0xffff0000, v6
	v_pk_fma_f32 v[20:21], v[38:39], v[20:21], v[22:23]
	v_rcp_f32_e32 v18, v0
	v_add_f32_e32 v0, 1.0, v19
	v_pk_fma_f32 v[20:21], v[46:47], v[24:25], v[20:21]
	v_rcp_f32_e32 v19, v0
	v_mul_f32_e32 v0, 0xbfb8aa3b, v20
	v_exp_f32_e32 v0, v0
	v_mul_f32_e32 v2, 0xbfb8aa3b, v21
	v_exp_f32_e32 v6, v2
	v_pk_mul_f32 v[16:17], v[16:17], v[18:19]
	v_lshlrev_b32_e32 v18, 16, v3
	v_and_b32_e32 v19, 0xffff0000, v3
	v_add_f32_e32 v0, 1.0, v0
	v_lshlrev_b32_e32 v10, 16, v11
	v_and_b32_e32 v11, 0xffff0000, v11
	v_pk_mul_f32 v[18:19], v[44:45], v[18:19]
	v_rcp_f32_e32 v2, v0
	v_add_f32_e32 v0, 1.0, v6
	v_lshlrev_b32_e32 v6, 16, v7
	v_and_b32_e32 v7, 0xffff0000, v7
	v_pk_fma_f32 v[10:11], v[40:41], v[10:11], v[18:19]
	v_lshlrev_b32_e32 v22, 16, v4
	v_and_b32_e32 v23, 0xffff0000, v4
	v_pk_fma_f32 v[6:7], v[48:49], v[6:7], v[10:11]
	v_lshlrev_b32_e32 v18, 16, v12
	v_and_b32_e32 v19, 0xffff0000, v12
	v_pk_mul_f32 v[22:23], v[30:31], v[22:23]
	v_mul_f32_e32 v3, 0xbfb8aa3b, v6
	v_lshlrev_b32_e32 v24, 16, v8
	v_and_b32_e32 v25, 0xffff0000, v8
	v_pk_fma_f32 v[18:19], v[26:27], v[18:19], v[22:23]
	v_exp_f32_e32 v10, v3
	v_mul_f32_e32 v3, 0xbfb8aa3b, v7
	v_pk_fma_f32 v[18:19], v[34:35], v[24:25], v[18:19]
	v_exp_f32_e32 v11, v3
	v_mul_f32_e32 v4, 0xbfb8aa3b, v18
	v_exp_f32_e32 v4, v4
	v_mul_f32_e32 v8, 0xbfb8aa3b, v19
	v_exp_f32_e32 v12, v8
	v_rcp_f32_e32 v3, v0
	v_add_f32_e32 v0, 1.0, v10
	v_rcp_f32_e32 v10, v0
	v_add_f32_e32 v0, 1.0, v11
	v_rcp_f32_e32 v11, v0
	v_add_f32_e32 v0, 1.0, v4
	v_lshlrev_b32_e32 v4, 16, v5
	v_and_b32_e32 v5, 0xffff0000, v5
	v_rcp_f32_e32 v8, v0
	v_add_f32_e32 v0, 1.0, v12
	v_lshlrev_b32_e32 v12, 16, v13
	v_and_b32_e32 v13, 0xffff0000, v13
	v_pk_mul_f32 v[4:5], v[32:33], v[4:5]
	v_lshlrev_b32_e32 v22, 16, v9
	v_and_b32_e32 v23, 0xffff0000, v9
	v_pk_fma_f32 v[4:5], v[28:29], v[12:13], v[4:5]
	v_rcp_f32_e32 v9, v0
	v_pk_fma_f32 v[12:13], v[36:37], v[22:23], v[4:5]
	s_mov_b32 s2, 0x358637bd
	v_mul_f32_e32 v4, 0xbfb8aa3b, v12
	v_exp_f32_e32 v4, v4
	v_mul_f32_e32 v5, 0xbfb8aa3b, v13
	v_exp_f32_e32 v5, v5
	v_pk_mul_f32 v[6:7], v[6:7], v[10:11]
	v_add_f32_e32 v0, 1.0, v4
	v_rcp_f32_e32 v22, v0
	v_add_f32_e32 v0, 1.0, v5
	v_pk_mul_f32 v[4:5], v[20:21], v[2:3]
	s_waitcnt lgkmcnt(0)
	v_pk_add_f32 v[2:3], v[90:91], v[92:93]
	v_rcp_f32_e32 v23, v0
	v_pk_add_f32 v[2:3], v[2:3], s[2:3] op_sel_hi:[1,0]
	v_pk_mul_f32 v[8:9], v[18:19], v[8:9]
	v_mul_f32_e32 v0, 0x4b800000, v3
	v_cmp_gt_f32_e32 vcc, s35, v3
	v_cmp_gt_f32_e64 s[2:3], s35, v2
	v_pk_mul_f32 v[10:11], v[12:13], v[22:23]
	v_cndmask_b32_e32 v0, v3, v0, vcc
	v_rsq_f32_e32 v0, v0
	v_mul_f32_e32 v3, 0x4b800000, v2
	v_cndmask_b32_e64 v2, v2, v3, s[2:3]
	v_rsq_f32_e32 v2, v2
	v_mul_f32_e32 v3, 0x45800000, v0
	v_cndmask_b32_e32 v0, v0, v3, vcc
	v_mul_f32_e32 v0, 0x3e000000, v0
	v_mul_f32_e32 v3, 0x45800000, v2
	v_cndmask_b32_e64 v2, v2, v3, s[2:3]
	v_pk_mul_f32 v[12:13], v[86:87], v[0:1] op_sel_hi:[1,0]
	v_pk_mul_f32 v[40:41], v[74:75], v[0:1] op_sel_hi:[1,0]
	v_pk_mul_f32 v[42:43], v[76:77], v[0:1] op_sel_hi:[1,0]
	v_pk_mul_f32 v[44:45], v[78:79], v[0:1] op_sel_hi:[1,0]
	v_pk_mul_f32 v[46:47], v[80:81], v[0:1] op_sel_hi:[1,0]
	v_pk_mul_f32 v[48:49], v[88:89], v[0:1] op_sel_hi:[1,0]
	v_pk_mul_f32 v[50:51], v[84:85], v[0:1] op_sel_hi:[1,0]
	v_pk_mul_f32 v[52:53], v[82:83], v[0:1] op_sel_hi:[1,0]
	v_mul_u32_u24_e32 v0, 0x48, v177
	v_pk_mul_f32 v[18:19], v[122:123], v[2:3] op_sel_hi:[1,0]
	v_pk_mul_f32 v[20:21], v[126:127], v[2:3] op_sel_hi:[1,0]
	v_pk_mul_f32 v[22:23], v[124:125], v[2:3] op_sel_hi:[1,0]
	v_pk_mul_f32 v[24:25], v[128:129], v[2:3] op_sel_hi:[1,0]
	v_pk_mul_f32 v[26:27], v[104:105], v[2:3] op_sel_hi:[1,0]
	v_pk_mul_f32 v[28:29], v[100:101], v[2:3] op_sel_hi:[1,0]
	v_pk_mul_f32 v[30:31], v[98:99], v[2:3] op_sel_hi:[1,0]
	v_pk_mul_f32 v[32:33], v[102:103], v[2:3] op_sel_hi:[1,0]
	v_lshl_add_u32 v0, v0, 1, v174
	v_lshlrev_b32_e32 v2, 1, v181
	v_mul_u32_u24_e32 v34, 0x70, v177
	v_lshlrev_b32_e32 v35, 2, v181
	v_add_u32_e32 v3, v0, v2
	v_add3_u32 v0, v0, v34, v35
	v_cvt_pk_bf16_f32 v34, v12, v13
	v_cvt_pk_bf16_f32 v35, v40, v41
	ds_write_b64 v3, v[34:35]
	v_cvt_pk_bf16_f32 v34, v18, v19
	v_cvt_pk_bf16_f32 v35, v20, v21
	ds_write_b64 v3, v[34:35] offset:9216
	ds_write_b128 v0, v[18:21] offset:18432
	ds_write_b128 v0, v[62:65] offset:34816
	v_cvt_pk_bf16_f32 v18, v42, v43
	v_cvt_pk_bf16_f32 v19, v44, v45
	ds_write_b64 v3, v[18:19] offset:8
	v_cvt_pk_bf16_f32 v18, v22, v23
	v_cvt_pk_bf16_f32 v19, v24, v25
	ds_write_b64 v3, v[18:19] offset:9224
	ds_write_b128 v0, v[22:25] offset:18448
	ds_write_b128 v0, v[14:17] offset:34832
	v_cvt_pk_bf16_f32 v14, v46, v47
	v_cvt_pk_bf16_f32 v15, v48, v49
	ds_write_b64 v3, v[14:15] offset:16
	v_cvt_pk_bf16_f32 v14, v26, v27
	v_cvt_pk_bf16_f32 v15, v28, v29
	ds_write_b64 v3, v[14:15] offset:9232
	ds_write_b128 v0, v[26:29] offset:18464
	ds_write_b128 v0, v[4:7] offset:34848
	v_cvt_pk_bf16_f32 v4, v50, v51
	v_cvt_pk_bf16_f32 v5, v52, v53
	ds_write_b64 v3, v[4:5] offset:24
	v_cvt_pk_bf16_f32 v4, v30, v31
	v_cvt_pk_bf16_f32 v5, v32, v33
	v_lshlrev_b32_e32 v25, 2, v177
	ds_write_b64 v3, v[4:5] offset:9240
	ds_write_b128 v0, v[30:33] offset:18480
	ds_write_b128 v0, v[8:11] offset:34864
	v_add_u32_e32 v5, v95, v25
	s_waitcnt lgkmcnt(0)
	s_barrier
	ds_read_b32 v5, v5 offset:52224
	v_lshlrev_b32_e32 v0, 3, v179
	v_lshl_or_b32 v38, v180, 1, v0
	v_cmp_lt_i32_e32 vcc, 3, v176
	v_mov_b32_e32 v0, 0x47
	v_lshlrev_b32_e32 v4, 2, v142
	v_cndmask_b32_e32 v20, 3, v0, vcc
	v_lshlrev_b32_e32 v0, 4, v142
	v_and_b32_e32 v4, 4, v4
	v_and_or_b32 v9, v0, 32, v4
	s_waitcnt lgkmcnt(0)
	v_mul_f32_e32 v4, 0x3fb8aa3b, v5
	v_exp_f32_e32 v8, v4
	s_movk_i32 s4, 0x44
	v_mul_lo_u32 v21, v38, s4
	v_add_u32_e32 v0, v21, v176
	v_mov_b64_e32 v[6:7], s[12:13]
	v_pk_mul_f32 v[4:5], v[12:13], v[8:9] op_sel_hi:[1,0]
	v_mad_i64_i32 v[36:37], s[2:3], v0, s82, v[6:7]
	v_lshlrev_b32_e32 v0, 7, v177
	v_cvt_pk_bf16_f32 v10, v4, v5
	v_pk_mul_f32 v[4:5], v[40:41], v[8:9] op_sel_hi:[1,0]
	v_lshlrev_b32_e32 v14, 1, v9
	v_cvt_pk_bf16_f32 v11, v4, v5
	v_mov_b32_e32 v15, v1
	v_lshl_add_u64 v[4:5], v[36:37], 0, v[0:1]
	v_lshl_add_u64 v[16:17], v[4:5], 0, v[14:15]
	s_mov_b64 s[42:43], 0x14a92000
	s_mov_b32 s5, 0x14a92000
	v_lshl_add_u64 v[18:19], v[16:17], 0, s[42:43]
	v_add_co_u32_e32 v16, vcc, s5, v16
	v_xor_b32_e32 v3, 63, v177
	s_nop 0
	v_addc_co_u32_e32 v17, vcc, 0, v17, vcc
	global_store_dwordx2 v[16:17], v[10:11], off
	v_pk_mul_f32 v[10:11], v[42:43], v[8:9] op_sel_hi:[1,0]
	v_pk_mul_f32 v[16:17], v[44:45], v[8:9] op_sel_hi:[1,0]
	v_cvt_pk_bf16_f32 v10, v10, v11
	v_cvt_pk_bf16_f32 v11, v16, v17
	global_store_dwordx2 v[18:19], v[10:11], off offset:16
	v_pk_mul_f32 v[10:11], v[46:47], v[8:9] op_sel_hi:[1,0]
	v_pk_mul_f32 v[16:17], v[48:49], v[8:9] op_sel_hi:[1,0]
	v_cvt_pk_bf16_f32 v10, v10, v11
	v_cvt_pk_bf16_f32 v11, v16, v17
	global_store_dwordx2 v[18:19], v[10:11], off offset:32
	v_pk_mul_f32 v[10:11], v[50:51], v[8:9] op_sel_hi:[1,0]
	v_pk_mul_f32 v[8:9], v[52:53], v[8:9] op_sel_hi:[1,0]
	v_cvt_pk_bf16_f32 v10, v10, v11
	v_cvt_pk_bf16_f32 v11, v8, v9
	global_store_dwordx2 v[18:19], v[10:11], off offset:48
	v_lshl_add_u32 v8, v3, 2, v95
	ds_read_b32 v8, v8 offset:52480
	v_sub_u32_e32 v39, v20, v176
	v_add3_u32 v9, v39, v21, s4
	v_mad_i64_i32 v[34:35], s[2:3], v9, s82, v[6:7]
	s_waitcnt lgkmcnt(0)
	v_mul_f32_e32 v6, 0x3fb8aa3b, v8
	v_exp_f32_e32 v6, v6
	v_lshlrev_b32_e32 v8, 7, v3
	v_mov_b32_e32 v9, v1
	v_lshl_add_u64 v[8:9], v[34:35], 0, v[8:9]
	v_pk_mul_f32 v[10:11], v[12:13], v[6:7] op_sel_hi:[1,0]
	v_pk_mul_f32 v[12:13], v[40:41], v[6:7] op_sel_hi:[1,0]
	v_lshl_add_u64 v[8:9], v[8:9], 0, v[14:15]
	v_cvt_pk_bf16_f32 v10, v10, v11
	v_cvt_pk_bf16_f32 v11, v12, v13
	v_lshl_add_u64 v[12:13], v[8:9], 0, s[42:43]
	v_add_co_u32_e32 v8, vcc, s5, v8
	v_lshlrev_b32_e32 v3, 3, v142
	s_nop 0
	v_addc_co_u32_e32 v9, vcc, 0, v9, vcc
	global_store_dwordx2 v[8:9], v[10:11], off
	v_pk_mul_f32 v[8:9], v[42:43], v[6:7] op_sel_hi:[1,0]
	v_pk_mul_f32 v[10:11], v[44:45], v[6:7] op_sel_hi:[1,0]
	v_cvt_pk_bf16_f32 v8, v8, v9
	v_cvt_pk_bf16_f32 v9, v10, v11
	global_store_dwordx2 v[12:13], v[8:9], off offset:16
	v_pk_mul_f32 v[8:9], v[46:47], v[6:7] op_sel_hi:[1,0]
	v_pk_mul_f32 v[10:11], v[48:49], v[6:7] op_sel_hi:[1,0]
	v_and_b32_e32 v3, 8, v3
	v_and_b32_e32 v19, 32, v178
	v_cvt_pk_bf16_f32 v8, v8, v9
	v_cvt_pk_bf16_f32 v9, v10, v11
	v_or_b32_e32 v11, v3, v19
	global_store_dwordx2 v[12:13], v[8:9], off offset:32
	v_pk_mul_f32 v[8:9], v[50:51], v[6:7] op_sel_hi:[1,0]
	v_pk_mul_f32 v[6:7], v[52:53], v[6:7] op_sel_hi:[1,0]
	v_lshlrev_b32_e32 v26, 6, v11
	v_cvt_pk_bf16_f32 v8, v8, v9
	v_cvt_pk_bf16_f32 v9, v6, v7
	v_or_b32_e32 v6, v26, v177
	global_store_dwordx2 v[12:13], v[8:9], off offset:48
	v_lshl_add_u32 v10, v6, 2, v174
	v_lshl_add_u32 v27, v11, 2, v95
	ds_read_b32 v28, v95 offset:52476
	ds_read_b128 v[6:9], v27 offset:52224
	ds_read_b32 v10, v10 offset:18432
	v_lshlrev_b32_e32 v11, 8, v11
	v_add3_u32 v11, v174, v11, v25
	ds_read2st64_b32 v[14:15], v11 offset0:73 offset1:74
	s_waitcnt lgkmcnt(0)
	v_sub_f32_e32 v6, v28, v6
	v_sub_f32_e32 v7, v28, v7
	v_or_b32_e32 v12, 16, v19
	v_mul_f32_e32 v6, 0x3fb8aa3b, v6
	v_mul_f32_e32 v7, 0x3fb8aa3b, v7
	v_or_b32_e32 v24, 4, v3
	v_exp_f32_e32 v6, v6
	v_exp_f32_e32 v7, v7
	v_or_b32_e32 v3, v12, v3
	v_lshlrev_b32_e32 v30, 6, v3
	v_or_b32_e32 v29, v24, v12
	v_or_b32_e32 v12, v30, v177
	v_lshl_add_u32 v12, v12, 2, v174
	ds_read_b32 v17, v11 offset:19200
	ds_read_b32 v18, v12 offset:18432
	v_mov_b32_e32 v11, v14
	v_pk_mul_f32 v[20:21], v[10:11], v[6:7]
	v_sub_f32_e32 v6, v28, v8
	v_mul_f32_e32 v6, 0x3fb8aa3b, v6
	v_exp_f32_e32 v22, v6
	v_sub_f32_e32 v6, v28, v9
	v_mul_f32_e32 v6, 0x3fb8aa3b, v6
	v_exp_f32_e32 v23, v6
	ds_read_b128 v[6:9], v27 offset:52240
	ds_read_b128 v[10:13], v27 offset:52288
	v_mov_b32_e32 v16, v15
	v_cvt_pk_bf16_f32 v14, v20, v21
	s_waitcnt lgkmcnt(0)
	v_pk_mul_f32 v[16:17], v[16:17], v[22:23]
	v_or_b32_e32 v23, v24, v19
	v_cvt_pk_bf16_f32 v15, v16, v17
	v_lshlrev_b32_e32 v16, 8, v3
	v_add3_u32 v20, v174, v16, v25
	v_sub_f32_e32 v10, v28, v10
	ds_read2st64_b32 v[16:17], v20 offset0:73 offset1:74
	v_sub_f32_e32 v11, v28, v11
	v_mul_f32_e32 v10, 0x3fb8aa3b, v10
	v_mul_f32_e32 v11, 0x3fb8aa3b, v11
	v_lshlrev_b32_e32 v31, 6, v23
	v_sub_f32_e32 v12, v28, v12
	v_sub_f32_e32 v13, v28, v13
	v_exp_f32_e32 v10, v10
	v_exp_f32_e32 v11, v11
	v_or_b32_e32 v19, v31, v177
	v_mul_f32_e32 v12, 0x3fb8aa3b, v12
	v_mul_f32_e32 v13, 0x3fb8aa3b, v13
	v_lshl_add_u32 v19, v19, 2, v174
	ds_read_b32 v21, v20 offset:19200
	ds_read_b32 v22, v19 offset:18432
	v_exp_f32_e32 v12, v12
	v_exp_f32_e32 v13, v13
	s_waitcnt lgkmcnt(0)
	v_mov_b32_e32 v19, v16
	v_pk_mul_f32 v[10:11], v[18:19], v[10:11]
	v_mov_b32_e32 v20, v17
	v_cvt_pk_bf16_f32 v16, v10, v11
	v_pk_mul_f32 v[10:11], v[20:21], v[12:13]
	v_lshlrev_b32_e32 v32, 6, v29
	v_cvt_pk_bf16_f32 v17, v10, v11
	v_lshlrev_b32_e32 v10, 8, v23
	v_or_b32_e32 v11, v32, v177
	v_lshl_add_u32 v33, v3, 2, v95
	v_sub_f32_e32 v3, v28, v8
	v_add3_u32 v10, v174, v10, v25
	v_lshl_add_u32 v11, v11, 2, v174
	v_mul_f32_e32 v3, 0x3fb8aa3b, v3
	v_sub_f32_e32 v6, v28, v6
	ds_read2st64_b32 v[18:19], v10 offset0:73 offset1:74
	v_sub_f32_e32 v7, v28, v7
	ds_read_b32 v21, v10 offset:19200
	ds_read_b32 v24, v11 offset:18432
	ds_read_b128 v[10:13], v33 offset:52240
	v_exp_f32_e32 v8, v3
	v_sub_f32_e32 v3, v28, v9
	v_mul_f32_e32 v6, 0x3fb8aa3b, v6
	v_mul_f32_e32 v7, 0x3fb8aa3b, v7
	v_mul_f32_e32 v3, 0x3fb8aa3b, v3
	v_exp_f32_e32 v6, v6
	v_exp_f32_e32 v7, v7
	v_exp_f32_e32 v9, v3
	s_waitcnt lgkmcnt(0)
	v_mov_b32_e32 v23, v18
	v_mov_b32_e32 v20, v19
	v_sub_f32_e32 v3, v28, v10
	v_pk_mul_f32 v[6:7], v[22:23], v[6:7]
	v_pk_mul_f32 v[8:9], v[20:21], v[8:9]
	v_mul_f32_e32 v3, 0x3fb8aa3b, v3
	v_cvt_pk_bf16_f32 v6, v6, v7
	v_cvt_pk_bf16_f32 v7, v8, v9
	v_exp_f32_e32 v8, v3
	v_lshlrev_b32_e32 v3, 8, v29
	v_add3_u32 v3, v174, v3, v25
	ds_read2st64_b32 v[18:19], v3 offset0:73 offset1:74
	v_sub_f32_e32 v9, v28, v11
	ds_read_b32 v11, v3 offset:19200
	v_sub_f32_e32 v3, v28, v12
	v_mul_f32_e32 v3, 0x3fb8aa3b, v3
	v_exp_f32_e32 v12, v3
	v_sub_f32_e32 v3, v28, v13
	v_mul_f32_e32 v9, 0x3fb8aa3b, v9
	v_mul_f32_e32 v3, 0x3fb8aa3b, v3
	v_exp_f32_e32 v9, v9
	v_exp_f32_e32 v13, v3
	s_waitcnt lgkmcnt(0)
	v_mov_b32_e32 v25, v18
	v_mov_b32_e32 v10, v19
	v_mov_b32_e32 v3, v1
	v_pk_mul_f32 v[8:9], v[24:25], v[8:9]
	v_pk_mul_f32 v[10:11], v[10:11], v[12:13]
	v_lshl_add_u64 v[4:5], v[4:5], 0, v[2:3]
	s_mov_b64 s[4:5], 0x14a96000
	s_mov_b32 s2, 0x14a96000
	v_cvt_pk_bf16_f32 v8, v8, v9
	v_cvt_pk_bf16_f32 v9, v10, v11
	v_lshl_add_u64 v[10:11], v[4:5], 0, s[4:5]
	v_add_co_u32_e32 v4, vcc, s2, v4
	s_movk_i32 s2, 0xe00
	s_nop 0
	v_addc_co_u32_e32 v5, vcc, 0, v5, vcc
	global_store_dwordx4 v[4:5], v[14:17], off
	global_store_dwordx4 v[10:11], v[6:9], off offset:16
	ds_read_b32 v22, v95 offset:52732
	ds_read_b128 v[4:7], v27 offset:52480
	v_lshl_add_u64 v[16:17], v[34:35], 0, v[0:1]
	v_bitop3_b32 v0, v26, s72, v177 bitop3:0x36
	v_lshl_add_u32 v0, v0, 2, v174
	ds_read2st64_b32 v[8:9], v0 offset0:94 offset1:95
	ds_read2st64_b32 v[10:11], v0 offset0:92 offset1:93
	s_waitcnt lgkmcnt(0)
	v_sub_f32_e32 v0, v22, v6
	v_mul_f32_e32 v0, 0x3fb8aa3b, v0
	v_sub_f32_e32 v4, v22, v4
	v_sub_f32_e32 v5, v22, v5
	v_exp_f32_e32 v6, v0
	v_sub_f32_e32 v0, v22, v7
	v_mul_f32_e32 v4, 0x3fb8aa3b, v4
	v_mul_f32_e32 v5, 0x3fb8aa3b, v5
	v_mul_f32_e32 v0, 0x3fb8aa3b, v0
	v_exp_f32_e32 v4, v4
	v_exp_f32_e32 v5, v5
	v_exp_f32_e32 v7, v0
	v_mov_b32_e32 v12, v9
	v_mov_b32_e32 v13, v8
	v_mov_b32_e32 v8, v11
	v_mov_b32_e32 v9, v10
	v_pk_mul_f32 v[4:5], v[12:13], v[4:5]
	v_pk_mul_f32 v[6:7], v[8:9], v[6:7]
	ds_read_b128 v[8:11], v27 offset:52496
	ds_read_b128 v[12:15], v27 offset:52544
	v_bitop3_b32 v0, v30, s2, v177 bitop3:0x36
	v_lshl_add_u32 v0, v0, 2, v174
	v_cvt_pk_bf16_f32 v4, v4, v5
	v_cvt_pk_bf16_f32 v5, v6, v7
	ds_read2st64_b32 v[6:7], v0 offset0:78 offset1:79
	ds_read2st64_b32 v[18:19], v0 offset0:76 offset1:77
	s_waitcnt lgkmcnt(0)
	v_sub_f32_e32 v12, v22, v12
	v_sub_f32_e32 v13, v22, v13
	v_mul_f32_e32 v12, 0x3fb8aa3b, v12
	v_mul_f32_e32 v13, 0x3fb8aa3b, v13
	v_exp_f32_e32 v12, v12
	v_exp_f32_e32 v13, v13
	v_sub_f32_e32 v0, v22, v14
	v_mov_b32_e32 v20, v7
	v_mov_b32_e32 v21, v6
	v_mul_f32_e32 v0, 0x3fb8aa3b, v0
	v_pk_mul_f32 v[6:7], v[20:21], v[12:13]
	v_exp_f32_e32 v12, v0
	v_sub_f32_e32 v0, v22, v15
	v_mul_f32_e32 v0, 0x3fb8aa3b, v0
	v_exp_f32_e32 v13, v0
	s_movk_i32 s2, 0xb00
	v_mov_b32_e32 v14, v19
	v_mov_b32_e32 v15, v18
	v_bitop3_b32 v0, v31, s2, v177 bitop3:0x36
	v_pk_mul_f32 v[12:13], v[14:15], v[12:13]
	v_lshl_add_u32 v0, v0, 2, v174
	v_cvt_pk_bf16_f32 v6, v6, v7
	v_cvt_pk_bf16_f32 v7, v12, v13
	ds_read2st64_b32 v[12:13], v0 offset0:90 offset1:91
	ds_read2st64_b32 v[14:15], v0 offset0:88 offset1:89
	v_sub_f32_e32 v0, v22, v10
	v_mul_f32_e32 v0, 0x3fb8aa3b, v0
	v_exp_f32_e32 v10, v0
	v_sub_f32_e32 v0, v22, v11
	v_mul_f32_e32 v0, 0x3fb8aa3b, v0
	v_exp_f32_e32 v11, v0
	v_sub_f32_e32 v8, v22, v8
	v_sub_f32_e32 v9, v22, v9
	v_mul_f32_e32 v8, 0x3fb8aa3b, v8
	v_mul_f32_e32 v9, 0x3fb8aa3b, v9
	s_waitcnt lgkmcnt(0)
	v_mov_b32_e32 v18, v13
	v_mov_b32_e32 v19, v12
	v_mov_b32_e32 v12, v15
	v_mov_b32_e32 v13, v14
	v_exp_f32_e32 v8, v8
	v_exp_f32_e32 v9, v9
	v_pk_mul_f32 v[14:15], v[12:13], v[10:11]
	ds_read_b128 v[10:13], v33 offset:52496
	s_movk_i32 s2, 0xf00
	v_bitop3_b32 v0, v32, s2, v177 bitop3:0x36
	v_pk_mul_f32 v[8:9], v[18:19], v[8:9]
	v_lshl_add_u32 v0, v0, 2, v174
	v_cvt_pk_bf16_f32 v8, v8, v9
	v_cvt_pk_bf16_f32 v9, v14, v15
	ds_read2st64_b32 v[14:15], v0 offset0:74 offset1:75
	ds_read2st64_b32 v[18:19], v0 offset0:72 offset1:73
	s_waitcnt lgkmcnt(0)
	v_sub_f32_e32 v0, v22, v12
	v_mul_f32_e32 v0, 0x3fb8aa3b, v0
	v_sub_f32_e32 v10, v22, v10
	v_sub_f32_e32 v11, v22, v11
	v_exp_f32_e32 v12, v0
	v_sub_f32_e32 v0, v22, v13
	v_mul_f32_e32 v10, 0x3fb8aa3b, v10
	v_mul_f32_e32 v11, 0x3fb8aa3b, v11
	v_mul_f32_e32 v0, 0x3fb8aa3b, v0
	v_exp_f32_e32 v10, v10
	v_exp_f32_e32 v11, v11
	v_exp_f32_e32 v13, v0
	v_mov_b32_e32 v20, v15
	v_mov_b32_e32 v21, v14
	v_mov_b32_e32 v14, v19
	v_mov_b32_e32 v15, v18
	v_pk_mul_f32 v[10:11], v[20:21], v[10:11]
	v_pk_mul_f32 v[12:13], v[14:15], v[12:13]
	v_lshl_add_u64 v[2:3], v[16:17], 0, v[2:3]
	v_cvt_pk_bf16_f32 v10, v10, v11
	v_cvt_pk_bf16_f32 v11, v12, v13
	v_lshl_add_u64 v[12:13], v[2:3], 0, s[4:5]
	v_add_co_u32_e32 v2, vcc, 0x14a96000, v2
	v_mov_b32_e32 v41, 0xfc0
	s_nop 0
	v_addc_co_u32_e32 v3, vcc, 0, v3, vcc
	global_store_dwordx4 v[2:3], v[4:7], off
	global_store_dwordx4 v[12:13], v[8:11], off offset:16
	s_and_saveexec_b64 s[2:3], s[0:1]
	s_cbranch_execz .LBB0_732
	v_bfrev_b32_e32 v0, 0.5
	v_lshl_or_b32 v0, v142, 2, v0
	v_add_u32_e32 v0, v95, v0
	ds_read_b32 v4, v0 offset:52224
	v_cmp_gt_u32_e32 vcc, 64, v142
	v_or_b32_e32 v2, v96, v38
	s_movk_i32 s4, 0x44
	v_cndmask_b32_e32 v0, v39, v176, vcc
	v_mad_u64_u32 v[2:3], s[4:5], v2, s4, v[0:1]
	s_waitcnt lgkmcnt(0)
	v_mul_f32_e32 v0, 0x3fb8aa3b, v4
	v_exp_f32_e32 v4, v0
	v_ashrrev_i32_e32 v3, 31, v2
	v_readlane_b32 s4, v254, 55
	v_lshlrev_b64 v[2:3], 8, v[2:3]
	v_readlane_b32 s5, v254, 56
	v_lshlrev_b32_e32 v0, 2, v94
	v_mov_b32_e32 v41, 0
	v_lshl_add_u64 v[2:3], s[4:5], 0, v[2:3]
	v_lshl_add_u64 v[2:3], v[2:3], 0, v[0:1]
	global_store_dword v[2:3], v4, off

.LBB0_992:
	s_or_b64 exec, exec, s[44:45]
	v_lshlrev_b32_e32 v111, 1, v40
	v_and_b32_e32 v116, 24, v111
	v_lshlrev_b32_e32 v114, 8, v109
	v_lshlrev_b32_e32 v111, 2, v40
	v_add3_u32 v118, v174, v114, v111
	v_and_or_b32 v125, v175, 3, v116
	v_lshlrev_b32_e32 v115, 6, v109
	ds_write_b32 v118, v0 offset:18432
	v_mul_f32_e32 v0, v26, v113
	s_mov_b64 s[4:5], 0x14a94000
	v_cvt_pk_bf16_f32 v113, v0, s0
	v_or_b32_e32 v0, v115, v125
	v_lshl_add_u64 v[36:37], v[36:37], 0, s[4:5]
	v_lshlrev_b32_e32 v0, 1, v0
	v_lshl_add_u64 v[120:121], v[36:37], 0, v[0:1]
	v_or_b32_e32 v119, 1, v109
	global_store_short v[120:121], v113, off
	v_cmp_ge_u32_e64 s[4:5], v119, v40
	v_mov_b32_e32 v0, 0
	v_mov_b32_e32 v113, 0
	s_and_saveexec_b64 s[44:45], s[4:5]
	s_cbranch_execz .LBB0_994
	ds_read_b32 v113, v110 offset:52228
	ds_read_b32 v114, v112 offset:52224
	s_waitcnt lgkmcnt(0)
	v_sub_f32_e32 v113, v113, v114
	v_mul_f32_e32 v113, 0x3fb8aa3b, v113
	v_exp_f32_e32 v113, v113

.LBB0_996:
	s_or_b64 exec, exec, s[4:5]
	v_lshlrev_b32_e32 v114, 8, v119
	v_add3_u32 v121, v174, v114, v111
	v_lshlrev_b32_e32 v117, 6, v119
	ds_write_b32 v121, v0 offset:18432
	v_mul_f32_e32 v0, v27, v113
	v_cvt_pk_bf16_f32 v113, v0, s0
	v_or_b32_e32 v0, v117, v125
	v_lshlrev_b32_e32 v0, 1, v0
	v_lshl_add_u64 v[122:123], v[36:37], 0, v[0:1]
	global_store_short v[122:123], v113, off
	v_or_b32_e32 v113, 2, v109
	v_cmp_ge_u32_e64 s[2:3], v113, v40
	v_mov_b32_e32 v0, 0
	v_mov_b32_e32 v114, 0
	s_and_saveexec_b64 s[4:5], s[2:3]
	s_cbranch_execz .LBB0_998
	ds_read_b32 v114, v110 offset:52232
	ds_read_b32 v120, v112 offset:52224
	s_waitcnt lgkmcnt(0)
	v_sub_f32_e32 v114, v114, v120
	v_mul_f32_e32 v114, 0x3fb8aa3b, v114
	v_exp_f32_e32 v114, v114

.LBB0_1000:
	s_or_b64 exec, exec, s[4:5]
	v_lshlrev_b32_e32 v122, 8, v113
	v_add3_u32 v122, v174, v122, v111
	v_lshlrev_b32_e32 v120, 6, v113
	ds_write_b32 v122, v0 offset:18432
	v_mul_f32_e32 v0, v28, v114
	v_cvt_pk_bf16_f32 v114, v0, s0
	v_or_b32_e32 v0, v120, v125
	v_lshlrev_b32_e32 v0, 1, v0
	v_lshl_add_u64 v[126:127], v[36:37], 0, v[0:1]
	global_store_short v[126:127], v114, off
	v_or_b32_e32 v114, 3, v109
	v_cmp_ge_u32_e64 s[2:3], v114, v40
	v_mov_b32_e32 v0, 0
	v_mov_b32_e32 v127, 0
	s_and_saveexec_b64 s[4:5], s[2:3]
	s_cbranch_execz .LBB0_1002
	ds_read_b32 v123, v110 offset:52236
	ds_read_b32 v124, v112 offset:52224
	s_waitcnt lgkmcnt(0)
	v_sub_f32_e32 v123, v123, v124
	v_mul_f32_e32 v123, 0x3fb8aa3b, v123
	v_exp_f32_e32 v127, v123

.LBB0_1004:
	s_or_b64 exec, exec, s[4:5]
	v_lshlrev_b32_e32 v124, 8, v114
	v_add3_u32 v124, v174, v124, v111
	v_lshlrev_b32_e32 v123, 6, v114
	ds_write_b32 v124, v0 offset:18432
	v_mul_f32_e32 v0, v29, v127
	v_cvt_pk_bf16_f32 v127, v0, s0
	v_or_b32_e32 v0, v123, v125
	v_lshlrev_b32_e32 v0, 1, v0
	v_lshl_add_u64 v[128:129], v[36:37], 0, v[0:1]
	global_store_short v[128:129], v127, off
	v_or_b32_e32 v126, 16, v40
	v_cmp_ge_u32_e64 s[2:3], v109, v126
	v_mov_b32_e32 v0, 0
	v_mov_b32_e32 v128, 0
	s_and_saveexec_b64 s[4:5], s[2:3]
	s_cbranch_execz .LBB0_1006
	ds_read_b32 v127, v110 offset:52224
	ds_read_b32 v128, v112 offset:52288
	s_waitcnt lgkmcnt(0)
	v_sub_f32_e32 v127, v127, v128
	v_mul_f32_e32 v127, 0x3fb8aa3b, v127
	v_exp_f32_e32 v128, v127

.LBB0_1008:
	s_or_b64 exec, exec, s[44:45]
	v_or_b32_e32 v127, 4, v125
	ds_write_b32 v118, v0 offset:18496
	v_mul_f32_e32 v0, v18, v128
	v_cvt_pk_bf16_f32 v125, v0, s0
	v_or_b32_e32 v0, v127, v115
	v_lshlrev_b32_e32 v0, 1, v0
	v_lshl_add_u64 v[128:129], v[36:37], 0, v[0:1]
	global_store_short v[128:129], v125, off
	v_cmp_ge_u32_e64 s[4:5], v119, v126
	v_mov_b32_e32 v0, 0
	v_mov_b32_e32 v125, 0
	s_and_saveexec_b64 s[44:45], s[4:5]
	s_cbranch_execz .LBB0_1010
	ds_read_b32 v125, v110 offset:52228
	ds_read_b32 v128, v112 offset:52288
	s_waitcnt lgkmcnt(0)
	v_sub_f32_e32 v125, v125, v128
	v_mul_f32_e32 v125, 0x3fb8aa3b, v125
	v_exp_f32_e32 v125, v125

.LBB0_1012:
	s_or_b64 exec, exec, s[4:5]
	ds_write_b32 v121, v0 offset:18496
	v_mul_f32_e32 v0, v19, v125
	v_cvt_pk_bf16_f32 v125, v0, s0
	v_or_b32_e32 v0, v117, v127
	v_lshlrev_b32_e32 v0, 1, v0
	v_lshl_add_u64 v[128:129], v[36:37], 0, v[0:1]
	global_store_short v[128:129], v125, off
	v_cmp_ge_u32_e64 s[2:3], v113, v126
	v_mov_b32_e32 v0, 0
	v_mov_b32_e32 v125, 0
	s_and_saveexec_b64 s[4:5], s[2:3]
	s_cbranch_execz .LBB0_1014
	ds_read_b32 v125, v110 offset:52232
	ds_read_b32 v128, v112 offset:52288
	s_waitcnt lgkmcnt(0)
	v_sub_f32_e32 v125, v125, v128
	v_mul_f32_e32 v125, 0x3fb8aa3b, v125
	v_exp_f32_e32 v125, v125

.LBB0_1016:
	s_or_b64 exec, exec, s[4:5]
	ds_write_b32 v122, v0 offset:18496
	v_mul_f32_e32 v0, v20, v125
	v_cvt_pk_bf16_f32 v125, v0, s0
	v_or_b32_e32 v0, v120, v127
	v_lshlrev_b32_e32 v0, 1, v0
	v_lshl_add_u64 v[128:129], v[36:37], 0, v[0:1]
	global_store_short v[128:129], v125, off
	v_cmp_ge_u32_e64 s[2:3], v114, v126
	v_mov_b32_e32 v0, 0
	v_mov_b32_e32 v128, 0
	s_and_saveexec_b64 s[4:5], s[2:3]
	s_cbranch_execz .LBB0_1018
	ds_read_b32 v125, v110 offset:52236
	ds_read_b32 v128, v112 offset:52288
	s_waitcnt lgkmcnt(0)
	v_sub_f32_e32 v125, v125, v128
	v_mul_f32_e32 v125, 0x3fb8aa3b, v125
	v_exp_f32_e32 v128, v125

.LBB0_1020:
	s_or_b64 exec, exec, s[4:5]
	ds_write_b32 v124, v0 offset:18496
	v_mul_f32_e32 v0, v21, v128
	v_cvt_pk_bf16_f32 v128, v0, s0
	v_or_b32_e32 v0, v123, v127
	v_lshlrev_b32_e32 v0, 1, v0
	v_lshl_add_u64 v[126:127], v[36:37], 0, v[0:1]
	global_store_short v[126:127], v128, off
	v_or_b32_e32 v125, 32, v40
	v_cmp_ge_u32_e64 s[2:3], v109, v125
	v_mov_b32_e32 v0, 0
	v_mov_b32_e32 v127, 0
	s_and_saveexec_b64 s[4:5], s[2:3]
	s_cbranch_execz .LBB0_1022
	ds_read_b32 v126, v110 offset:52224
	ds_read_b32 v127, v112 offset:52352
	s_waitcnt lgkmcnt(0)
	v_sub_f32_e32 v126, v126, v127
	v_mul_f32_e32 v126, 0x3fb8aa3b, v126
	v_exp_f32_e32 v127, v126

.LBB0_1024:
	s_or_b64 exec, exec, s[44:45]
	v_and_or_b32 v126, v125, 35, v116
	ds_write_b32 v118, v0 offset:18560
	v_mul_f32_e32 v0, v10, v127
	v_cvt_pk_bf16_f32 v127, v0, s0
	v_or_b32_e32 v0, v115, v126
	v_lshlrev_b32_e32 v0, 1, v0
	v_lshl_add_u64 v[128:129], v[36:37], 0, v[0:1]
	global_store_short v[128:129], v127, off
	v_cmp_ge_u32_e64 s[4:5], v119, v125
	v_mov_b32_e32 v0, 0
	v_mov_b32_e32 v127, 0
	s_and_saveexec_b64 s[44:45], s[4:5]
	s_cbranch_execz .LBB0_1026
	ds_read_b32 v127, v110 offset:52228
	ds_read_b32 v128, v112 offset:52352
	s_waitcnt lgkmcnt(0)
	v_sub_f32_e32 v127, v127, v128
	v_mul_f32_e32 v127, 0x3fb8aa3b, v127
	v_exp_f32_e32 v127, v127

.LBB0_1028:
	s_or_b64 exec, exec, s[4:5]
	ds_write_b32 v121, v0 offset:18560
	v_mul_f32_e32 v0, v11, v127
	v_cvt_pk_bf16_f32 v127, v0, s0
	v_or_b32_e32 v0, v117, v126
	v_lshlrev_b32_e32 v0, 1, v0
	v_lshl_add_u64 v[128:129], v[36:37], 0, v[0:1]
	global_store_short v[128:129], v127, off
	v_cmp_ge_u32_e64 s[2:3], v113, v125
	v_mov_b32_e32 v0, 0
	v_mov_b32_e32 v127, 0
	s_and_saveexec_b64 s[4:5], s[2:3]
	s_cbranch_execz .LBB0_1030
	ds_read_b32 v127, v110 offset:52232
	ds_read_b32 v128, v112 offset:52352
	s_waitcnt lgkmcnt(0)
	v_sub_f32_e32 v127, v127, v128
	v_mul_f32_e32 v127, 0x3fb8aa3b, v127
	v_exp_f32_e32 v127, v127

.LBB0_1032:
	s_or_b64 exec, exec, s[4:5]
	ds_write_b32 v122, v0 offset:18560
	v_mul_f32_e32 v0, v12, v127
	v_cvt_pk_bf16_f32 v127, v0, s0
	v_or_b32_e32 v0, v120, v126
	v_lshlrev_b32_e32 v0, 1, v0
	v_lshl_add_u64 v[128:129], v[36:37], 0, v[0:1]
	global_store_short v[128:129], v127, off
	v_cmp_ge_u32_e64 s[2:3], v114, v125
	v_mov_b32_e32 v0, 0
	v_mov_b32_e32 v127, 0
	s_and_saveexec_b64 s[4:5], s[2:3]
	s_cbranch_execz .LBB0_1034
	ds_read_b32 v127, v110 offset:52236
	ds_read_b32 v128, v112 offset:52352
	s_waitcnt lgkmcnt(0)
	v_sub_f32_e32 v127, v127, v128
	v_mul_f32_e32 v127, 0x3fb8aa3b, v127
	v_exp_f32_e32 v127, v127

.LBB0_1036:
	s_or_b64 exec, exec, s[4:5]
	ds_write_b32 v124, v0 offset:18560
	v_mul_f32_e32 v0, v13, v127
	v_cvt_pk_bf16_f32 v128, v0, s0
	v_or_b32_e32 v0, v123, v126
	v_lshlrev_b32_e32 v0, 1, v0
	v_lshl_add_u64 v[126:127], v[36:37], 0, v[0:1]
	global_store_short v[126:127], v128, off
	v_or_b32_e32 v125, 48, v40
	v_cmp_ge_u32_e64 s[2:3], v109, v125
	v_mov_b32_e32 v0, 0
	v_mov_b32_e32 v126, 0
	s_and_saveexec_b64 s[4:5], s[2:3]
	s_cbranch_execz .LBB0_1038
	ds_read_b32 v126, v110 offset:52224
	ds_read_b32 v127, v112 offset:52416
	s_waitcnt lgkmcnt(0)
	v_sub_f32_e32 v126, v126, v127
	v_mul_f32_e32 v126, 0x3fb8aa3b, v126
	v_exp_f32_e32 v126, v126

.LBB0_1040:
	s_or_b64 exec, exec, s[44:45]
	v_and_b32_e32 v127, 35, v125
	v_or3_b32 v116, v127, v116, 4
	ds_write_b32 v118, v0 offset:18624
	v_mul_f32_e32 v0, v2, v126
	v_cvt_pk_bf16_f32 v118, v0, s0
	v_or_b32_e32 v0, v116, v115
	v_lshlrev_b32_e32 v0, 1, v0
	v_lshl_add_u64 v[126:127], v[36:37], 0, v[0:1]
	v_cmp_ge_u32_e64 s[4:5], v119, v125
	v_mov_b32_e32 v0, 0
	v_mov_b32_e32 v115, 0
	global_store_short v[126:127], v118, off
	s_and_saveexec_b64 s[44:45], s[4:5]
	s_cbranch_execz .LBB0_1042
	ds_read_b32 v115, v110 offset:52228
	ds_read_b32 v118, v112 offset:52416
	s_waitcnt lgkmcnt(0)
	v_sub_f32_e32 v115, v115, v118
	v_mul_f32_e32 v115, 0x3fb8aa3b, v115
	v_exp_f32_e32 v115, v115

.LBB0_1044:
	s_or_b64 exec, exec, s[4:5]
	ds_write_b32 v121, v0 offset:18624
	v_mul_f32_e32 v0, v3, v115
	v_cvt_pk_bf16_f32 v115, v0, s0
	v_or_b32_e32 v0, v117, v116
	v_lshlrev_b32_e32 v0, 1, v0
	v_lshl_add_u64 v[118:119], v[36:37], 0, v[0:1]
	global_store_short v[118:119], v115, off
	v_cmp_ge_u32_e64 s[2:3], v113, v125
	v_mov_b32_e32 v0, 0
	v_mov_b32_e32 v115, 0
	s_and_saveexec_b64 s[4:5], s[2:3]
	s_cbranch_execz .LBB0_1046
	ds_read_b32 v115, v110 offset:52232
	ds_read_b32 v117, v112 offset:52416
	s_waitcnt lgkmcnt(0)
	v_sub_f32_e32 v115, v115, v117
	v_mul_f32_e32 v115, 0x3fb8aa3b, v115
	v_exp_f32_e32 v115, v115

.LBB0_1048:
	s_or_b64 exec, exec, s[4:5]
	ds_write_b32 v122, v0 offset:18624
	v_mul_f32_e32 v0, v4, v115
	v_cvt_pk_bf16_f32 v113, v0, s0
	v_or_b32_e32 v0, v120, v116
	v_lshlrev_b32_e32 v0, 1, v0
	v_lshl_add_u64 v[118:119], v[36:37], 0, v[0:1]
	global_store_short v[118:119], v113, off
	v_cmp_ge_u32_e64 s[2:3], v114, v125
	v_mov_b32_e32 v0, 0
	v_mov_b32_e32 v113, 0
	s_and_saveexec_b64 s[4:5], s[2:3]
	s_cbranch_execz .LBB0_1050
	ds_read_b32 v113, v110 offset:52236
	ds_read_b32 v112, v112 offset:52416
	s_waitcnt lgkmcnt(0)
	v_sub_f32_e32 v112, v113, v112
	v_mul_f32_e32 v112, 0x3fb8aa3b, v112
	v_exp_f32_e32 v113, v112

.LBB0_1052:
	s_or_b64 exec, exec, s[4:5]
	ds_write_b32 v124, v0 offset:18624
	v_mul_f32_e32 v0, v5, v113
	v_cvt_pk_bf16_f32 v110, v0, s0
	v_or_b32_e32 v0, v123, v116
	v_lshlrev_b32_e32 v0, 1, v0
	v_lshl_add_u64 v[36:37], v[36:37], 0, v[0:1]
	global_store_short v[36:37], v110, off
	v_xor_b32_e32 v116, 63, v40
	v_xor_b32_e32 v36, 15, v40
	v_xor_b32_e32 v112, 63, v109
	v_lshl_add_u32 v110, v36, 2, v95
	v_cmp_ge_u32_e64 s[2:3], v112, v116
	v_mov_b32_e32 v0, 0
	v_xor_b32_e32 v37, 60, v109
	v_mov_b32_e32 v113, 0
	s_and_saveexec_b64 s[4:5], s[2:3]
	s_cbranch_execz .LBB0_1054
	v_xor_b32_e32 v113, 60, v109
	v_lshl_add_u32 v113, v113, 2, v95
	ds_read_b32 v113, v113 offset:52492
	ds_read_b32 v114, v110 offset:52672
	s_waitcnt lgkmcnt(0)
	v_sub_f32_e32 v113, v113, v114
	v_mul_f32_e32 v113, 0x3fb8aa3b, v113
	v_exp_f32_e32 v113, v113

.LBB0_1056:
	s_or_b64 exec, exec, s[4:5]
	v_lshlrev_b32_e32 v30, 1, v116
	v_and_b32_e32 v30, 24, v30
	v_and_b32_e32 v114, 35, v116
	v_or3_b32 v118, v114, v30, 4
	v_lshl_add_u32 v114, v112, 8, v174
	v_sub_u32_e32 v111, v114, v111
	v_lshlrev_b32_e32 v30, 6, v112
	ds_write_b32 v111, v0 offset:35068
	v_mul_f32_e32 v0, v26, v113
	s_mov_b64 s[2:3], 0x14a94000
	v_cvt_pk_bf16_f32 v26, v0, s0
	v_or_b32_e32 v0, v30, v118
	v_lshl_add_u64 v[34:35], v[34:35], 0, s[2:3]
	v_lshlrev_b32_e32 v0, 1, v0
	v_lshl_add_u64 v[120:121], v[34:35], 0, v[0:1]
	global_store_short v[120:121], v26, off
	v_xor_b32_e32 v26, 62, v109
	v_cmp_ge_u32_e64 s[2:3], v26, v116
	v_mov_b32_e32 v0, 0
	v_mov_b32_e32 v117, 0
	s_and_saveexec_b64 s[4:5], s[2:3]
	s_cbranch_execz .LBB0_1058
	v_xor_b32_e32 v113, 60, v109
	v_lshl_add_u32 v113, v113, 2, v95
	ds_read_b32 v113, v113 offset:52488
	ds_read_b32 v115, v110 offset:52672
	s_waitcnt lgkmcnt(0)
	v_sub_f32_e32 v113, v113, v115
	v_mul_f32_e32 v113, 0x3fb8aa3b, v113
	v_exp_f32_e32 v117, v113

.LBB0_1060:
	s_or_b64 exec, exec, s[4:5]
	v_sub_u32_e32 v119, 0, v40
	v_lshl_add_u32 v115, v26, 8, v174
	v_lshl_add_u32 v113, v119, 2, v115
	v_lshlrev_b32_e32 v31, 6, v26
	ds_write_b32 v113, v0 offset:35068
	v_mul_f32_e32 v0, v27, v117
	v_cvt_pk_bf16_f32 v27, v0, s0
	v_or_b32_e32 v0, v31, v118
	v_lshlrev_b32_e32 v0, 1, v0
	v_lshl_add_u64 v[120:121], v[34:35], 0, v[0:1]
	global_store_short v[120:121], v27, off
	v_xor_b32_e32 v27, 61, v109
	v_cmp_ge_u32_e64 s[2:3], v27, v116
	v_mov_b32_e32 v0, 0
	s_and_saveexec_b64 s[4:5], s[2:3]
	s_cbranch_execz .LBB0_1062
	v_xor_b32_e32 v0, 60, v109
	v_lshl_add_u32 v0, v0, 2, v95
	ds_read_b32 v0, v0 offset:52484
	ds_read_b32 v117, v110 offset:52672
	s_waitcnt lgkmcnt(0)
	v_sub_f32_e32 v0, v0, v117
	v_mul_f32_e32 v0, 0x3fb8aa3b, v0
	v_exp_f32_e32 v0, v0

.LBB0_1066:
	s_or_b64 exec, exec, s[2:3]
	v_lshlrev_b32_e32 v32, 6, v27
	v_mul_f32_e32 v0, v28, v0
	v_cvt_pk_bf16_f32 v28, v0, s0
	v_or_b32_e32 v0, v32, v118
	v_lshlrev_b32_e32 v0, 1, v0
	v_lshl_add_u32 v117, v27, 8, v174
	v_lshl_add_u64 v[122:123], v[34:35], 0, v[0:1]
	v_lshl_add_u32 v109, v119, 2, v117
	global_store_short v[122:123], v28, off
	v_cmp_ge_u32_e64 s[2:3], v37, v116
	v_lshl_add_u32 v28, v37, 2, v95
	ds_write_b32 v109, v121 offset:35068
	s_and_saveexec_b64 s[4:5], s[2:3]
	s_cbranch_execz .LBB0_1068
	ds_read_b32 v0, v28 offset:52480
	ds_read_b32 v95, v110 offset:52672
	s_waitcnt lgkmcnt(0)
	v_sub_f32_e32 v0, v0, v95
	v_mul_f32_e32 v0, 0x3fb8aa3b, v0
	v_exp_f32_e32 v120, v0

.LBB0_1070:
	s_or_b64 exec, exec, s[4:5]
	v_lshl_add_u32 v116, v37, 8, v174
	v_lshl_add_u32 v95, v119, 2, v116
	v_lshlrev_b32_e32 v33, 6, v37
	ds_write_b32 v95, v0 offset:35068
	v_mul_f32_e32 v0, v29, v120
	v_cvt_pk_bf16_f32 v29, v0, s0
	v_or_b32_e32 v0, v33, v118
	v_lshlrev_b32_e32 v0, 1, v0
	v_lshl_add_u64 v[118:119], v[34:35], 0, v[0:1]
	global_store_short v[118:119], v29, off
	v_xor_b32_e32 v29, 47, v40
	v_cmp_ge_u32_e64 s[2:3], v112, v29
	s_and_saveexec_b64 s[4:5], s[2:3]
	s_cbranch_execz .LBB0_1072
	ds_read_b32 v0, v28 offset:52492
	ds_read_b32 v118, v110 offset:52608
	s_waitcnt lgkmcnt(0)
	v_sub_f32_e32 v0, v0, v118
	v_mul_f32_e32 v0, 0x3fb8aa3b, v0
	v_exp_f32_e32 v121, v0

.LBB0_1074:
	s_or_b64 exec, exec, s[4:5]
	v_lshlrev_b32_e32 v22, 1, v29
	v_and_b32_e32 v118, 35, v29
	v_and_or_b32 v22, v22, 24, v118
	v_or_b32_e32 v118, 0x1000, v36
	v_lshl_add_u32 v114, v118, 2, v114
	ds_write_b32 v114, v0 offset:18560
	v_mul_f32_e32 v0, v18, v121
	v_cvt_pk_bf16_f32 v18, v0, s0
	v_or_b32_e32 v0, v30, v22
	v_lshlrev_b32_e32 v0, 1, v0
	v_lshl_add_u64 v[120:121], v[34:35], 0, v[0:1]
	v_cmp_ge_u32_e64 s[2:3], v26, v29
	global_store_short v[120:121], v18, off
	s_and_saveexec_b64 s[4:5], s[2:3]
	s_cbranch_execz .LBB0_1076
	ds_read_b32 v0, v28 offset:52488
	ds_read_b32 v18, v110 offset:52608
	s_waitcnt lgkmcnt(0)
	v_sub_f32_e32 v0, v0, v18
	v_mul_f32_e32 v0, 0x3fb8aa3b, v0
	v_exp_f32_e32 v119, v0

.LBB0_1078:
	s_or_b64 exec, exec, s[4:5]
	v_lshl_add_u32 v23, v118, 2, v115
	ds_write_b32 v23, v0 offset:18560
	v_mul_f32_e32 v0, v19, v119
	v_cvt_pk_bf16_f32 v19, v0, s0
	v_or_b32_e32 v0, v31, v22
	v_lshlrev_b32_e32 v0, 1, v0
	v_lshl_add_u64 v[114:115], v[34:35], 0, v[0:1]
	v_cmp_ge_u32_e64 s[2:3], v27, v29
	global_store_short v[114:115], v19, off
	s_and_saveexec_b64 s[4:5], s[2:3]
	s_cbranch_execz .LBB0_1080
	ds_read_b32 v0, v28 offset:52484
	ds_read_b32 v18, v110 offset:52608
	s_waitcnt lgkmcnt(0)
	v_sub_f32_e32 v0, v0, v18
	v_mul_f32_e32 v0, 0x3fb8aa3b, v0
	v_exp_f32_e32 v18, v0

.LBB0_1082:
	s_or_b64 exec, exec, s[4:5]
	v_lshl_add_u32 v19, v118, 2, v117
	ds_write_b32 v19, v0 offset:18560
	v_mul_f32_e32 v0, v20, v18
	v_cvt_pk_bf16_f32 v20, v0, s0
	v_or_b32_e32 v0, v32, v22
	v_lshlrev_b32_e32 v0, 1, v0
	v_lshl_add_u64 v[18:19], v[34:35], 0, v[0:1]
	v_cmp_ge_u32_e64 s[2:3], v37, v29
	global_store_short v[18:19], v20, off
	s_and_saveexec_b64 s[4:5], s[2:3]
	s_cbranch_execz .LBB0_1084
	ds_read_b32 v0, v28 offset:52480
	ds_read_b32 v18, v110 offset:52608
	s_waitcnt lgkmcnt(0)
	v_sub_f32_e32 v0, v0, v18
	v_mul_f32_e32 v0, 0x3fb8aa3b, v0
	v_exp_f32_e32 v23, v0

.LBB0_1086:
	s_or_b64 exec, exec, s[4:5]
	v_lshl_add_u32 v18, v118, 2, v116
	ds_write_b32 v18, v0 offset:18560
	v_mul_f32_e32 v0, v21, v23
	v_cvt_pk_bf16_f32 v18, v0, s0
	v_or_b32_e32 v0, v33, v22
	v_lshlrev_b32_e32 v0, 1, v0
	v_lshl_add_u64 v[20:21], v[34:35], 0, v[0:1]
	global_store_short v[20:21], v18, off
	v_xor_b32_e32 v18, 31, v40
	v_cmp_ge_u32_e64 s[2:3], v112, v18
	s_and_saveexec_b64 s[4:5], s[2:3]
	s_cbranch_execz .LBB0_1088
	ds_read_b32 v0, v28 offset:52492
	ds_read_b32 v19, v110 offset:52544
	s_waitcnt lgkmcnt(0)
	v_sub_f32_e32 v0, v0, v19
	v_mul_f32_e32 v0, 0x3fb8aa3b, v0
	v_exp_f32_e32 v19, v0

.LBB0_1090:
	s_or_b64 exec, exec, s[4:5]
	v_lshlrev_b32_e32 v14, 1, v18
	v_and_b32_e32 v14, 24, v14
	v_and_b32_e32 v21, 3, v18
	v_or3_b32 v14, v21, v14, 4
	ds_write_b32 v111, v0 offset:34940
	v_mul_f32_e32 v0, v10, v19
	v_cvt_pk_bf16_f32 v10, v0, s0
	v_or_b32_e32 v0, v30, v14
	v_lshlrev_b32_e32 v0, 1, v0
	v_lshl_add_u64 v[22:23], v[34:35], 0, v[0:1]
	v_cmp_ge_u32_e64 s[2:3], v26, v18
	global_store_short v[22:23], v10, off
	s_and_saveexec_b64 s[4:5], s[2:3]
	s_cbranch_execz .LBB0_1092
	ds_read_b32 v0, v28 offset:52488
	ds_read_b32 v10, v110 offset:52544
	s_waitcnt lgkmcnt(0)
	v_sub_f32_e32 v0, v0, v10
	v_mul_f32_e32 v0, 0x3fb8aa3b, v0
	v_exp_f32_e32 v20, v0

.LBB0_1094:
	s_or_b64 exec, exec, s[4:5]
	ds_write_b32 v113, v0 offset:34940
	v_mul_f32_e32 v0, v11, v20
	v_cvt_pk_bf16_f32 v11, v0, s0
	v_or_b32_e32 v0, v31, v14
	v_lshlrev_b32_e32 v0, 1, v0
	v_lshl_add_u64 v[20:21], v[34:35], 0, v[0:1]
	v_cmp_ge_u32_e64 s[2:3], v27, v18
	global_store_short v[20:21], v11, off
	s_and_saveexec_b64 s[4:5], s[2:3]
	s_cbranch_execz .LBB0_1096
	ds_read_b32 v0, v28 offset:52484
	ds_read_b32 v10, v110 offset:52544
	s_waitcnt lgkmcnt(0)
	v_sub_f32_e32 v0, v0, v10
	v_mul_f32_e32 v0, 0x3fb8aa3b, v0
	v_exp_f32_e32 v10, v0

.LBB0_1098:
	s_or_b64 exec, exec, s[4:5]
	ds_write_b32 v109, v0 offset:34940
	v_mul_f32_e32 v0, v12, v10
	v_cvt_pk_bf16_f32 v10, v0, s0
	v_or_b32_e32 v0, v32, v14
	v_lshlrev_b32_e32 v0, 1, v0
	v_lshl_add_u64 v[20:21], v[34:35], 0, v[0:1]
	v_cmp_ge_u32_e64 s[2:3], v37, v18
	global_store_short v[20:21], v10, off
	s_and_saveexec_b64 s[4:5], s[2:3]
	s_cbranch_execz .LBB0_1100
	ds_read_b32 v0, v28 offset:52480
	ds_read_b32 v10, v110 offset:52544
	s_waitcnt lgkmcnt(0)
	v_sub_f32_e32 v0, v0, v10
	v_mul_f32_e32 v0, 0x3fb8aa3b, v0
	v_exp_f32_e32 v11, v0

.LBB0_1102:
	s_or_b64 exec, exec, s[4:5]
	ds_write_b32 v95, v0 offset:34940
	v_mul_f32_e32 v0, v13, v11
	v_cvt_pk_bf16_f32 v11, v0, s0
	v_or_b32_e32 v0, v33, v14
	v_lshlrev_b32_e32 v0, 1, v0
	v_lshl_add_u64 v[12:13], v[34:35], 0, v[0:1]
	global_store_short v[12:13], v11, off
	v_cmp_ge_u32_e64 s[2:3], v112, v36
	s_and_saveexec_b64 s[4:5], s[2:3]
	s_cbranch_execz .LBB0_1104
	ds_read_b32 v0, v28 offset:52492
	ds_read_b32 v10, v110 offset:52480
	s_waitcnt lgkmcnt(0)
	v_sub_f32_e32 v0, v0, v10
	v_mul_f32_e32 v0, 0x3fb8aa3b, v0
	v_exp_f32_e32 v10, v0

.LBB0_1106:
	s_or_b64 exec, exec, s[4:5]
	v_lshlrev_b32_e32 v6, 1, v36
	v_and_b32_e32 v12, 3, v36
	v_and_or_b32 v6, v6, 24, v12
	ds_write_b32 v111, v0 offset:34876
	v_mul_f32_e32 v0, v2, v10
	v_cvt_pk_bf16_f32 v2, v0, s0
	v_or_b32_e32 v0, v30, v6
	v_lshlrev_b32_e32 v0, 1, v0
	v_lshl_add_u64 v[12:13], v[34:35], 0, v[0:1]
	v_cmp_ge_u32_e64 s[2:3], v26, v36
	global_store_short v[12:13], v2, off
	s_and_saveexec_b64 s[4:5], s[2:3]
	s_cbranch_execz .LBB0_1108
	ds_read_b32 v0, v28 offset:52488
	ds_read_b32 v2, v110 offset:52480
	s_waitcnt lgkmcnt(0)
	v_sub_f32_e32 v0, v0, v2
	v_mul_f32_e32 v0, 0x3fb8aa3b, v0
	v_exp_f32_e32 v11, v0

.LBB0_1110:
	s_or_b64 exec, exec, s[4:5]
	ds_write_b32 v113, v0 offset:34876
	v_mul_f32_e32 v0, v3, v11
	v_cvt_pk_bf16_f32 v3, v0, s0
	v_or_b32_e32 v0, v31, v6
	v_lshlrev_b32_e32 v0, 1, v0
	v_lshl_add_u64 v[10:11], v[34:35], 0, v[0:1]
	v_cmp_ge_u32_e64 s[2:3], v27, v36
	global_store_short v[10:11], v3, off
	s_and_saveexec_b64 s[4:5], s[2:3]
	s_cbranch_execz .LBB0_1112
	ds_read_b32 v0, v28 offset:52484
	ds_read_b32 v2, v110 offset:52480
	s_waitcnt lgkmcnt(0)
	v_sub_f32_e32 v0, v0, v2
	v_mul_f32_e32 v0, 0x3fb8aa3b, v0
	v_exp_f32_e32 v2, v0

.LBB0_1114:
	s_or_b64 exec, exec, s[4:5]
	ds_write_b32 v109, v0 offset:34876
	v_mul_f32_e32 v0, v4, v2
	v_cvt_pk_bf16_f32 v2, v0, s0
	v_or_b32_e32 v0, v32, v6
	v_lshlrev_b32_e32 v0, 1, v0
	v_lshl_add_u64 v[10:11], v[34:35], 0, v[0:1]
	v_cmp_ge_u32_e64 s[2:3], v37, v36
	global_store_short v[10:11], v2, off
	s_and_saveexec_b64 s[4:5], s[2:3]
	s_cbranch_execz .LBB0_1116
	ds_read_b32 v0, v28 offset:52480
	ds_read_b32 v2, v110 offset:52480
	s_waitcnt lgkmcnt(0)
	v_sub_f32_e32 v0, v0, v2
	v_mul_f32_e32 v0, 0x3fb8aa3b, v0
	v_exp_f32_e32 v3, v0

.LBB0_1118:
	s_or_b64 exec, exec, s[4:5]
	ds_write_b32 v95, v0 offset:34876
	v_mul_f32_e32 v0, v5, v3
	v_cvt_pk_bf16_f32 v4, v0, s0
	v_or_b32_e32 v0, v33, v6
	v_lshlrev_b32_e32 v0, 1, v0
	v_lshl_add_u64 v[2:3], v[34:35], 0, v[0:1]
	global_store_short v[2:3], v4, off
	v_lshl_add_u32 v0, v42, 14, v174
	s_waitcnt lgkmcnt(0)
	s_barrier
	ds_read_b128 v[2:5], v0 offset:18688
	ds_read_b128 v[6:9], v0 offset:18944
	ds_read_b128 v[10:13], v0 offset:19200
	s_waitcnt lgkmcnt(0)
	v_fma_f32 v2, -v41, v2, v43
	v_fma_f32 v2, -v43, v3, v2
	v_fma_f32 v2, -v44, v4, v2
	v_fma_f32 v5, -v45, v5, v2
	v_fma_f32 v2, -v41, v6, v44
	v_fma_f32 v2, -v7, v5, v2
	v_fma_f32 v2, -v44, v8, v2
	ds_read_b128 v[14:17], v0 offset:19456
	v_fma_f32 v6, -v45, v9, v2
	v_fma_f32 v2, -v41, v10, v45
	v_fma_f32 v2, -v11, v5, v2
	v_fma_f32 v2, -v12, v6, v2
	v_fma_f32 v8, -v45, v13, v2
	ds_read_b128 v[10:13], v0 offset:19712
	ds_read_b128 v[18:21], v0 offset:19728
	s_waitcnt lgkmcnt(0)
	v_fma_f32 v2, -v41, v14, v46
	v_fma_f32 v2, -v15, v5, v2
	v_fma_f32 v2, -v16, v6, v2
	v_fma_f32 v4, -v17, v8, v2
	v_fma_f32 v2, -v41, v10, v47
	v_fma_f32 v2, -v5, v11, v2
	v_fma_f32 v2, -v12, v6, v2
	ds_read_b128 v[14:17], v0 offset:19968
	ds_read_b128 v[22:25], v0 offset:19984
	v_fma_f32 v2, -v13, v8, v2
	v_fma_f32 v2, -v18, v4, v2
	v_fma_f32 v2, -v47, v19, v2
	v_fma_f32 v2, -v48, v20, v2
	v_fma_f32 v7, -v49, v21, v2
	s_waitcnt lgkmcnt(0)
	v_fma_f32 v2, -v41, v14, v48
	v_fma_f32 v2, -v5, v15, v2
	v_fma_f32 v2, -v6, v16, v2
	ds_read_b128 v[10:13], v0 offset:20224
	ds_read_b128 v[18:21], v0 offset:20240
	v_fma_f32 v2, -v17, v8, v2
	v_fma_f32 v2, -v22, v4, v2
	v_fma_f32 v2, -v23, v7, v2
	v_fma_f32 v2, -v48, v24, v2
	v_fma_f32 v9, -v49, v25, v2
	s_waitcnt lgkmcnt(0)
	v_fma_f32 v2, -v41, v10, v49
	v_fma_f32 v2, -v5, v11, v2
	v_fma_f32 v2, -v6, v12, v2
	ds_read_b128 v[14:17], v0 offset:20480
	ds_read_b128 v[22:25], v0 offset:20496
	v_fma_f32 v2, -v8, v13, v2
	v_fma_f32 v2, -v18, v4, v2
	v_fma_f32 v2, -v19, v7, v2
	v_fma_f32 v2, -v20, v9, v2
	v_fma_f32 v10, -v49, v21, v2
	s_waitcnt lgkmcnt(0)
	v_fma_f32 v2, -v41, v14, v50
	v_fma_f32 v2, -v5, v15, v2
	v_fma_f32 v2, -v6, v16, v2
	v_fma_f32 v2, -v8, v17, v2
	ds_read_b128 v[18:21], v0 offset:20736
	ds_read_b128 v[26:29], v0 offset:20752
	ds_read_b128 v[30:33], v0 offset:20768
	v_fma_f32 v2, -v4, v22, v2
	v_fma_f32 v2, -v23, v7, v2
	v_fma_f32 v2, -v24, v9, v2
	v_fma_f32 v11, -v25, v10, v2
	s_waitcnt lgkmcnt(0)
	v_fma_f32 v2, -v41, v18, v51
	v_fma_f32 v2, -v5, v19, v2
	v_fma_f32 v2, -v6, v20, v2
	v_fma_f32 v2, -v8, v21, v2
	v_fma_f32 v2, -v4, v26, v2
	v_fma_f32 v2, -v7, v27, v2
	v_fma_f32 v2, -v28, v9, v2
	v_fma_f32 v2, -v29, v10, v2
	ds_read_b128 v[14:17], v0 offset:20992
	ds_read_b128 v[22:25], v0 offset:21008
	ds_read_b128 v[34:37], v0 offset:21024
	v_fma_f32 v2, -v30, v11, v2
	v_fma_f32 v2, -v51, v31, v2
	v_fma_f32 v2, -v52, v32, v2
	v_fma_f32 v12, -v53, v33, v2
	s_waitcnt lgkmcnt(0)
	v_fma_f32 v2, -v41, v14, v52
	v_fma_f32 v2, -v5, v15, v2
	v_fma_f32 v2, -v6, v16, v2
	v_fma_f32 v2, -v8, v17, v2
	v_fma_f32 v2, -v4, v22, v2
	v_fma_f32 v2, -v7, v23, v2
	v_fma_f32 v2, -v9, v24, v2
	v_fma_f32 v2, -v25, v10, v2
	ds_read_b128 v[18:21], v0 offset:21248
	ds_read_b128 v[26:29], v0 offset:21264
	ds_read_b128 v[30:33], v0 offset:21280
	v_fma_f32 v2, -v34, v11, v2
	v_fma_f32 v2, -v35, v12, v2
	v_fma_f32 v2, -v52, v36, v2
	v_fma_f32 v13, -v53, v37, v2
	s_waitcnt lgkmcnt(0)
	v_fma_f32 v2, -v41, v18, v53
	v_fma_f32 v2, -v5, v19, v2
	v_fma_f32 v2, -v6, v20, v2
	v_fma_f32 v2, -v8, v21, v2
	v_fma_f32 v2, -v4, v26, v2
	v_fma_f32 v2, -v7, v27, v2
	v_fma_f32 v2, -v9, v28, v2
	v_fma_f32 v2, -v10, v29, v2
	ds_read_b128 v[22:25], v0 offset:21504
	ds_read_b128 v[34:37], v0 offset:21520
	ds_read_b128 v[44:47], v0 offset:21536
	v_fma_f32 v2, -v11, v30, v2
	v_fma_f32 v2, -v31, v12, v2
	v_fma_f32 v2, -v32, v13, v2
	v_fma_f32 v14, -v53, v33, v2
	s_waitcnt lgkmcnt(0)
	v_fma_f32 v2, -v41, v22, v54
	v_fma_f32 v2, -v5, v23, v2
	v_fma_f32 v2, -v6, v24, v2
	v_fma_f32 v2, -v8, v25, v2
	v_fma_f32 v2, -v4, v34, v2
	v_fma_f32 v2, -v7, v35, v2
	v_fma_f32 v2, -v9, v36, v2
	v_fma_f32 v2, -v10, v37, v2
	v_fma_f32 v2, -v11, v44, v2
	ds_read_b128 v[16:19], v0 offset:21760
	ds_read_b128 v[26:29], v0 offset:21776
	ds_read_b128 v[30:33], v0 offset:21792
	ds_read_b128 v[48:51], v0 offset:21808
	v_fma_f32 v2, -v45, v12, v2
	v_fma_f32 v2, -v46, v13, v2
	v_fma_f32 v15, -v47, v14, v2
	s_waitcnt lgkmcnt(0)
	v_fma_f32 v2, -v41, v16, v55
	v_fma_f32 v2, -v5, v17, v2
	v_fma_f32 v2, -v6, v18, v2
	v_fma_f32 v2, -v8, v19, v2
	v_fma_f32 v2, -v4, v26, v2
	v_fma_f32 v2, -v7, v27, v2
	v_fma_f32 v2, -v9, v28, v2
	v_fma_f32 v2, -v10, v29, v2
	v_fma_f32 v2, -v11, v30, v2
	v_fma_f32 v2, -v12, v31, v2
	v_fma_f32 v2, -v32, v13, v2
	v_fma_f32 v2, -v33, v14, v2
	v_fma_f32 v2, -v48, v15, v2
	ds_read_b128 v[20:23], v0 offset:22016
	ds_read_b128 v[34:37], v0 offset:22032
	ds_read_b128 v[44:47], v0 offset:22048
	ds_read_b128 v[110:113], v0 offset:22064
	v_fma_f32 v2, -v55, v49, v2
	v_fma_f32 v2, -v56, v50, v2
	v_fma_f32 v16, -v57, v51, v2
	s_waitcnt lgkmcnt(0)
	v_fma_f32 v2, -v41, v20, v56
	v_fma_f32 v2, -v5, v21, v2
	v_fma_f32 v2, -v6, v22, v2
	v_fma_f32 v2, -v8, v23, v2
	v_fma_f32 v2, -v4, v34, v2
	v_fma_f32 v2, -v7, v35, v2
	v_fma_f32 v2, -v9, v36, v2
	v_fma_f32 v2, -v10, v37, v2
	v_fma_f32 v2, -v11, v44, v2
	v_fma_f32 v2, -v12, v45, v2
	v_fma_f32 v2, -v13, v46, v2
	v_fma_f32 v2, -v14, v47, v2
	v_fma_f32 v2, -v110, v15, v2
	ds_read_b128 v[24:27], v0 offset:22272
	ds_read_b128 v[28:31], v0 offset:22288
	ds_read_b128 v[48:51], v0 offset:22304
	ds_read_b128 v[52:55], v0 offset:22320
	v_fma_f32 v2, -v111, v16, v2
	v_fma_f32 v2, -v56, v112, v2
	v_fma_f32 v17, -v57, v113, v2
	s_waitcnt lgkmcnt(0)
	v_fma_f32 v2, -v41, v24, v57
	v_fma_f32 v2, -v5, v25, v2
	v_fma_f32 v2, -v6, v26, v2
	v_fma_f32 v2, -v8, v27, v2
	v_fma_f32 v2, -v4, v28, v2
	v_fma_f32 v2, -v7, v29, v2
	v_fma_f32 v2, -v9, v30, v2
	v_fma_f32 v2, -v10, v31, v2
	v_fma_f32 v2, -v11, v48, v2
	v_fma_f32 v2, -v12, v49, v2
	v_fma_f32 v2, -v13, v50, v2
	v_fma_f32 v2, -v14, v51, v2
	v_fma_f32 v2, -v15, v52, v2
	ds_read_b128 v[20:23], v0 offset:22528
	ds_read_b128 v[32:35], v0 offset:22544
	ds_read_b128 v[44:47], v0 offset:22560
	ds_read_b128 v[110:113], v0 offset:22576
	v_fma_f32 v2, -v53, v16, v2
	v_fma_f32 v2, -v54, v17, v2
	v_fma_f32 v18, -v57, v55, v2
	s_waitcnt lgkmcnt(0)
	v_fma_f32 v2, -v41, v20, v59
	v_fma_f32 v2, -v5, v21, v2
	v_fma_f32 v2, -v6, v22, v2
	v_fma_f32 v2, -v8, v23, v2
	v_fma_f32 v2, -v4, v32, v2
	v_fma_f32 v2, -v7, v33, v2
	v_fma_f32 v2, -v9, v34, v2
	v_fma_f32 v2, -v10, v35, v2
	v_fma_f32 v2, -v11, v44, v2
	v_fma_f32 v2, -v12, v45, v2
	v_fma_f32 v2, -v13, v46, v2
	v_fma_f32 v2, -v14, v47, v2
	v_fma_f32 v2, -v15, v110, v2
	v_fma_f32 v2, -v16, v111, v2
	ds_read_b128 v[24:27], v0 offset:22784
	ds_read_b128 v[28:31], v0 offset:22800
	ds_read_b128 v[48:51], v0 offset:22816
	ds_read_b128 v[52:55], v0 offset:22832
	ds_read_b128 v[114:117], v0 offset:22848
	v_fma_f32 v2, -v112, v17, v2
	v_fma_f32 v19, -v113, v18, v2
	s_waitcnt lgkmcnt(0)
	v_fma_f32 v2, -v41, v24, v60
	v_fma_f32 v2, -v5, v25, v2
	v_fma_f32 v2, -v6, v26, v2
	v_fma_f32 v2, -v8, v27, v2
	v_fma_f32 v2, -v4, v28, v2
	v_fma_f32 v2, -v7, v29, v2
	v_fma_f32 v2, -v9, v30, v2
	v_fma_f32 v2, -v10, v31, v2
	v_fma_f32 v2, -v11, v48, v2
	v_fma_f32 v2, -v12, v49, v2
	v_fma_f32 v2, -v13, v50, v2
	v_fma_f32 v2, -v14, v51, v2
	v_fma_f32 v2, -v15, v52, v2
	v_fma_f32 v2, -v16, v53, v2
	v_fma_f32 v2, -v17, v54, v2
	v_fma_f32 v2, -v55, v18, v2
	v_fma_f32 v2, -v114, v19, v2
	v_fma_f32 v2, -v60, v115, v2
	ds_read_b128 v[32:35], v0 offset:23040
	ds_read_b128 v[44:47], v0 offset:23056
	ds_read_b128 v[110:113], v0 offset:23072
	ds_read_b128 v[118:121], v0 offset:23088
	ds_read_b128 v[122:125], v0 offset:23104
	v_fma_f32 v2, -v61, v116, v2
	v_fma_f32 v20, -v62, v117, v2
	s_waitcnt lgkmcnt(0)
	v_fma_f32 v2, -v41, v32, v61
	v_fma_f32 v2, -v5, v33, v2
	v_fma_f32 v2, -v6, v34, v2
	v_fma_f32 v2, -v8, v35, v2
	v_fma_f32 v2, -v4, v44, v2
	v_fma_f32 v2, -v7, v45, v2
	v_fma_f32 v2, -v9, v46, v2
	v_fma_f32 v2, -v10, v47, v2
	v_fma_f32 v2, -v11, v110, v2
	v_fma_f32 v2, -v12, v111, v2
	v_fma_f32 v2, -v13, v112, v2
	v_fma_f32 v2, -v14, v113, v2
	v_fma_f32 v2, -v15, v118, v2
	v_fma_f32 v2, -v16, v119, v2
	v_fma_f32 v2, -v17, v120, v2
	v_fma_f32 v2, -v18, v121, v2
	v_fma_f32 v2, -v122, v19, v2
	v_fma_f32 v2, -v123, v20, v2
	ds_read_b128 v[22:25], v0 offset:23296
	ds_read_b128 v[26:29], v0 offset:23312
	ds_read_b128 v[48:51], v0 offset:23328
	ds_read_b128 v[52:55], v0 offset:23344
	ds_read_b128 v[114:117], v0 offset:23360
	v_fma_f32 v2, -v61, v124, v2
	v_fma_f32 v21, -v62, v125, v2
	s_waitcnt lgkmcnt(0)
	v_fma_f32 v2, -v41, v22, v62
	v_fma_f32 v2, -v5, v23, v2
	v_fma_f32 v2, -v6, v24, v2
	v_fma_f32 v2, -v8, v25, v2
	v_fma_f32 v2, -v4, v26, v2
	v_fma_f32 v2, -v7, v27, v2
	v_fma_f32 v2, -v9, v28, v2
	v_fma_f32 v2, -v10, v29, v2
	v_fma_f32 v2, -v11, v48, v2
	v_fma_f32 v2, -v12, v49, v2
	v_fma_f32 v2, -v13, v50, v2
	v_fma_f32 v2, -v14, v51, v2
	v_fma_f32 v2, -v15, v52, v2
	v_fma_f32 v2, -v16, v53, v2
	v_fma_f32 v2, -v17, v54, v2
	v_fma_f32 v2, -v18, v55, v2
	v_fma_f32 v2, -v19, v114, v2
	v_fma_f32 v2, -v115, v20, v2
	ds_read_b128 v[30:33], v0 offset:23552
	ds_read_b128 v[34:37], v0 offset:23568
	ds_read_b128 v[44:47], v0 offset:23584
	ds_read_b128 v[110:113], v0 offset:23600
	ds_read_b128 v[118:121], v0 offset:23616
	v_fma_f32 v2, -v116, v21, v2
	v_fma_f32 v22, -v62, v117, v2
	s_waitcnt lgkmcnt(0)
	v_fma_f32 v2, -v41, v30, v63
	v_fma_f32 v2, -v5, v31, v2
	v_fma_f32 v2, -v6, v32, v2
	v_fma_f32 v2, -v8, v33, v2
	v_fma_f32 v2, -v4, v34, v2
	v_fma_f32 v2, -v7, v35, v2
	v_fma_f32 v2, -v9, v36, v2
	v_fma_f32 v2, -v10, v37, v2
	v_fma_f32 v2, -v11, v44, v2
	v_fma_f32 v2, -v12, v45, v2
	v_fma_f32 v2, -v13, v46, v2
	v_fma_f32 v2, -v14, v47, v2
	v_fma_f32 v2, -v15, v110, v2
	v_fma_f32 v2, -v16, v111, v2
	v_fma_f32 v2, -v17, v112, v2
	v_fma_f32 v2, -v18, v113, v2
	v_fma_f32 v2, -v19, v118, v2
	v_fma_f32 v2, -v20, v119, v2
	v_fma_f32 v2, -v120, v21, v2
	ds_read_b128 v[24:27], v0 offset:23808
	ds_read_b128 v[48:51], v0 offset:23824
	ds_read_b128 v[52:55], v0 offset:23840
	ds_read_b128 v[114:117], v0 offset:23856
	ds_read_b128 v[122:125], v0 offset:23872
	ds_read_b128 v[126:129], v0 offset:23888
	v_fma_f32 v23, -v121, v22, v2
	s_waitcnt lgkmcnt(0)
	v_fma_f32 v2, -v41, v24, v64
	v_fma_f32 v2, -v5, v25, v2
	v_fma_f32 v2, -v6, v26, v2
	v_fma_f32 v2, -v8, v27, v2
	v_fma_f32 v2, -v4, v48, v2
	v_fma_f32 v2, -v7, v49, v2
	v_fma_f32 v2, -v9, v50, v2
	v_fma_f32 v2, -v10, v51, v2
	v_fma_f32 v2, -v11, v52, v2
	v_fma_f32 v2, -v12, v53, v2
	v_fma_f32 v2, -v13, v54, v2
	v_fma_f32 v2, -v14, v55, v2
	v_fma_f32 v2, -v15, v114, v2
	v_fma_f32 v2, -v16, v115, v2
	v_fma_f32 v2, -v17, v116, v2
	v_fma_f32 v2, -v18, v117, v2
	v_fma_f32 v2, -v19, v122, v2
	v_fma_f32 v2, -v20, v123, v2
	v_fma_f32 v2, -v21, v124, v2
	v_fma_f32 v2, -v125, v22, v2
	v_fma_f32 v2, -v126, v23, v2
	v_fma_f32 v2, -v64, v127, v2
	v_fma_f32 v2, -v65, v128, v2
	ds_read_b128 v[28:31], v0 offset:24064
	ds_read_b128 v[32:35], v0 offset:24080
	ds_read_b128 v[44:47], v0 offset:24096
	ds_read_b128 v[60:63], v0 offset:24112
	ds_read_b128 v[110:113], v0 offset:24128
	ds_read_b128 v[118:121], v0 offset:24144
	v_fma_f32 v24, -v67, v129, v2
	s_waitcnt lgkmcnt(0)
	v_fma_f32 v2, -v41, v28, v65
	v_fma_f32 v2, -v5, v29, v2
	v_fma_f32 v2, -v6, v30, v2
	v_fma_f32 v2, -v8, v31, v2
	v_fma_f32 v2, -v4, v32, v2
	v_fma_f32 v2, -v7, v33, v2
	v_fma_f32 v2, -v9, v34, v2
	v_fma_f32 v2, -v10, v35, v2
	v_fma_f32 v2, -v11, v44, v2
	v_fma_f32 v2, -v12, v45, v2
	v_fma_f32 v2, -v13, v46, v2
	v_fma_f32 v2, -v14, v47, v2
	v_fma_f32 v2, -v15, v60, v2
	v_fma_f32 v2, -v16, v61, v2
	v_fma_f32 v2, -v17, v62, v2
	v_fma_f32 v2, -v18, v63, v2
	v_fma_f32 v2, -v19, v110, v2
	v_fma_f32 v2, -v20, v111, v2
	v_fma_f32 v2, -v21, v112, v2
	v_fma_f32 v2, -v22, v113, v2
	v_fma_f32 v2, -v118, v23, v2
	v_fma_f32 v2, -v119, v24, v2
	v_fma_f32 v2, -v65, v120, v2
	ds_read_b128 v[48:51], v0 offset:24320
	ds_read_b128 v[52:55], v0 offset:24336
	ds_read_b128 v[114:117], v0 offset:24352
	ds_read_b128 v[122:125], v0 offset:24368
	ds_read_b128 v[126:129], v0 offset:24384
	ds_read_b128 v[130:133], v0 offset:24400
	v_fma_f32 v25, -v67, v121, v2
	s_waitcnt lgkmcnt(0)
	v_fma_f32 v2, -v41, v48, v67
	v_fma_f32 v2, -v5, v49, v2
	v_fma_f32 v2, -v6, v50, v2
	v_fma_f32 v2, -v8, v51, v2
	v_fma_f32 v2, -v4, v52, v2
	v_fma_f32 v2, -v7, v53, v2
	v_fma_f32 v2, -v9, v54, v2
	v_fma_f32 v2, -v10, v55, v2
	v_fma_f32 v2, -v11, v114, v2
	v_fma_f32 v2, -v12, v115, v2
	v_fma_f32 v2, -v13, v116, v2
	v_fma_f32 v2, -v14, v117, v2
	v_fma_f32 v2, -v15, v122, v2
	v_fma_f32 v2, -v16, v123, v2
	v_fma_f32 v2, -v17, v124, v2
	v_fma_f32 v2, -v18, v125, v2
	v_fma_f32 v2, -v19, v126, v2
	v_fma_f32 v2, -v20, v127, v2
	v_fma_f32 v2, -v21, v128, v2
	v_fma_f32 v2, -v22, v129, v2
	v_fma_f32 v2, -v23, v130, v2
	v_fma_f32 v2, -v131, v24, v2
	v_fma_f32 v2, -v132, v25, v2
	ds_read_b128 v[28:31], v0 offset:24576
	ds_read_b128 v[32:35], v0 offset:24592
	ds_read_b128 v[44:47], v0 offset:24608
	ds_read_b128 v[60:63], v0 offset:24624
	ds_read_b128 v[110:113], v0 offset:24640
	ds_read_b128 v[118:121], v0 offset:24656
	v_fma_f32 v26, -v67, v133, v2
	s_waitcnt lgkmcnt(0)
	v_fma_f32 v2, -v41, v28, v70
	v_fma_f32 v2, -v5, v29, v2
	v_fma_f32 v2, -v6, v30, v2
	v_fma_f32 v2, -v8, v31, v2
	v_fma_f32 v2, -v4, v32, v2
	v_fma_f32 v2, -v7, v33, v2
	v_fma_f32 v2, -v9, v34, v2
	v_fma_f32 v2, -v10, v35, v2
	v_fma_f32 v2, -v11, v44, v2
	v_fma_f32 v2, -v12, v45, v2
	v_fma_f32 v2, -v13, v46, v2
	v_fma_f32 v2, -v14, v47, v2
	v_fma_f32 v2, -v15, v60, v2
	v_fma_f32 v2, -v16, v61, v2
	v_fma_f32 v2, -v17, v62, v2
	v_fma_f32 v2, -v18, v63, v2
	v_fma_f32 v2, -v19, v110, v2
	v_fma_f32 v2, -v20, v111, v2
	v_fma_f32 v2, -v21, v112, v2
	v_fma_f32 v2, -v22, v113, v2
	v_fma_f32 v2, -v23, v118, v2
	v_fma_f32 v2, -v24, v119, v2
	v_fma_f32 v2, -v120, v25, v2
	ds_read_b128 v[48:51], v0 offset:24832
	ds_read_b128 v[52:55], v0 offset:24848
	ds_read_b128 v[114:117], v0 offset:24864
	ds_read_b128 v[122:125], v0 offset:24880
	ds_read_b128 v[126:129], v0 offset:24896
	ds_read_b128 v[130:133], v0 offset:24912
	ds_read_b128 v[134:137], v0 offset:24928
	v_fma_f32 v27, -v121, v26, v2
	s_waitcnt lgkmcnt(0)
	v_fma_f32 v2, -v41, v48, v71
	v_fma_f32 v2, -v5, v49, v2
	v_fma_f32 v2, -v6, v50, v2
	v_fma_f32 v2, -v8, v51, v2
	v_fma_f32 v2, -v4, v52, v2
	v_fma_f32 v2, -v7, v53, v2
	v_fma_f32 v2, -v9, v54, v2
	v_fma_f32 v2, -v10, v55, v2
	v_fma_f32 v2, -v11, v114, v2
	v_fma_f32 v2, -v12, v115, v2
	v_fma_f32 v2, -v13, v116, v2
	v_fma_f32 v2, -v14, v117, v2
	v_fma_f32 v2, -v15, v122, v2
	v_fma_f32 v2, -v16, v123, v2
	v_fma_f32 v2, -v17, v124, v2
	v_fma_f32 v2, -v18, v125, v2
	v_fma_f32 v2, -v19, v126, v2
	v_fma_f32 v2, -v20, v127, v2
	v_fma_f32 v2, -v21, v128, v2
	v_fma_f32 v2, -v22, v129, v2
	v_fma_f32 v2, -v23, v130, v2
	v_fma_f32 v2, -v24, v131, v2
	v_fma_f32 v2, -v25, v132, v2
	v_fma_f32 v2, -v133, v26, v2
	v_fma_f32 v2, -v134, v27, v2
	v_fma_f32 v2, -v71, v135, v2
	v_fma_f32 v2, -v72, v136, v2
	ds_read_b128 v[30:33], v0 offset:25088
	ds_read_b128 v[34:37], v0 offset:25104
	ds_read_b128 v[44:47], v0 offset:25120
	ds_read_b128 v[60:63], v0 offset:25136
	ds_read_b128 v[110:113], v0 offset:25152
	ds_read_b128 v[118:121], v0 offset:25168
	ds_read_b128 v[138:141], v0 offset:25184
	v_fma_f32 v28, -v74, v137, v2
	s_waitcnt lgkmcnt(0)
	v_fma_f32 v2, -v41, v30, v72
	v_fma_f32 v2, -v5, v31, v2
	v_fma_f32 v2, -v6, v32, v2
	v_fma_f32 v2, -v8, v33, v2
	v_fma_f32 v2, -v4, v34, v2
	v_fma_f32 v2, -v7, v35, v2
	v_fma_f32 v2, -v9, v36, v2
	v_fma_f32 v2, -v10, v37, v2
	v_fma_f32 v2, -v11, v44, v2
	v_fma_f32 v2, -v12, v45, v2
	v_fma_f32 v2, -v13, v46, v2
	v_fma_f32 v2, -v14, v47, v2
	v_fma_f32 v2, -v15, v60, v2
	v_fma_f32 v2, -v16, v61, v2
	v_fma_f32 v2, -v17, v62, v2
	v_fma_f32 v2, -v18, v63, v2
	v_fma_f32 v2, -v19, v110, v2
	v_fma_f32 v2, -v20, v111, v2
	v_fma_f32 v2, -v21, v112, v2
	v_fma_f32 v2, -v22, v113, v2
	v_fma_f32 v2, -v23, v118, v2
	v_fma_f32 v2, -v24, v119, v2
	v_fma_f32 v2, -v25, v120, v2
	v_fma_f32 v2, -v26, v121, v2
	v_fma_f32 v2, -v138, v27, v2
	v_fma_f32 v2, -v139, v28, v2
	v_fma_f32 v2, -v72, v140, v2
	ds_read_b128 v[48:51], v0 offset:25344
	ds_read_b128 v[52:55], v0 offset:25360
	ds_read_b128 v[114:117], v0 offset:25376
	ds_read_b128 v[122:125], v0 offset:25392
	ds_read_b128 v[126:129], v0 offset:25408
	ds_read_b128 v[130:133], v0 offset:25424
	ds_read_b128 v[134:137], v0 offset:25440
	v_fma_f32 v29, -v74, v141, v2
	s_waitcnt lgkmcnt(0)
	v_fma_f32 v2, -v41, v48, v74
	v_fma_f32 v2, -v5, v49, v2
	v_fma_f32 v2, -v6, v50, v2
	v_fma_f32 v2, -v8, v51, v2
	v_fma_f32 v2, -v4, v52, v2
	v_fma_f32 v2, -v7, v53, v2
	v_fma_f32 v2, -v9, v54, v2
	v_fma_f32 v2, -v10, v55, v2
	v_fma_f32 v2, -v11, v114, v2
	v_fma_f32 v2, -v12, v115, v2
	v_fma_f32 v2, -v13, v116, v2
	v_fma_f32 v2, -v14, v117, v2
	v_fma_f32 v2, -v15, v122, v2
	v_fma_f32 v2, -v16, v123, v2
	v_fma_f32 v2, -v17, v124, v2
	v_fma_f32 v2, -v18, v125, v2
	v_fma_f32 v2, -v19, v126, v2
	v_fma_f32 v2, -v20, v127, v2
	v_fma_f32 v2, -v21, v128, v2
	v_fma_f32 v2, -v22, v129, v2
	v_fma_f32 v2, -v23, v130, v2
	v_fma_f32 v2, -v24, v131, v2
	v_fma_f32 v2, -v25, v132, v2
	v_fma_f32 v2, -v26, v133, v2
	v_fma_f32 v2, -v27, v134, v2
	v_fma_f32 v2, -v135, v28, v2
	v_fma_f32 v2, -v136, v29, v2
	ds_read_b128 v[32:35], v0 offset:25600
	ds_read_b128 v[44:47], v0 offset:25616
	ds_read_b128 v[60:63], v0 offset:25632
	ds_read_b128 v[110:113], v0 offset:25648
	ds_read_b128 v[118:121], v0 offset:25664
	ds_read_b128 v[138:141], v0 offset:25680
	ds_read_b128 v[142:145], v0 offset:25696
	v_fma_f32 v30, -v74, v137, v2
	s_waitcnt lgkmcnt(0)
	v_fma_f32 v2, -v41, v32, v79
	v_fma_f32 v2, -v5, v33, v2
	v_fma_f32 v2, -v6, v34, v2
	v_fma_f32 v2, -v8, v35, v2
	v_fma_f32 v2, -v4, v44, v2
	v_fma_f32 v2, -v7, v45, v2
	v_fma_f32 v2, -v9, v46, v2
	v_fma_f32 v2, -v10, v47, v2
	v_fma_f32 v2, -v11, v60, v2
	v_fma_f32 v2, -v12, v61, v2
	v_fma_f32 v2, -v13, v62, v2
	v_fma_f32 v2, -v14, v63, v2
	v_fma_f32 v2, -v15, v110, v2
	v_fma_f32 v2, -v16, v111, v2
	v_fma_f32 v2, -v17, v112, v2
	v_fma_f32 v2, -v18, v113, v2
	v_fma_f32 v2, -v19, v118, v2
	v_fma_f32 v2, -v20, v119, v2
	v_fma_f32 v2, -v21, v120, v2
	v_fma_f32 v2, -v22, v121, v2
	v_fma_f32 v2, -v23, v138, v2
	v_fma_f32 v2, -v24, v139, v2
	v_fma_f32 v2, -v25, v140, v2
	v_fma_f32 v2, -v26, v141, v2
	v_fma_f32 v2, -v27, v142, v2
	v_fma_f32 v2, -v28, v143, v2
	v_fma_f32 v2, -v144, v29, v2
	ds_read_b128 v[48:51], v0 offset:25856
	ds_read_b128 v[52:55], v0 offset:25872
	ds_read_b128 v[114:117], v0 offset:25888
	ds_read_b128 v[122:125], v0 offset:25904
	ds_read_b128 v[126:129], v0 offset:25920
	ds_read_b128 v[130:133], v0 offset:25936
	ds_read_b128 v[134:137], v0 offset:25952
	ds_read_b128 v[146:149], v0 offset:25968
	v_fma_f32 v31, -v145, v30, v2
	s_waitcnt lgkmcnt(0)
	v_fma_f32 v2, -v41, v48, v78
	v_fma_f32 v2, -v5, v49, v2
	v_fma_f32 v2, -v6, v50, v2
	v_fma_f32 v2, -v8, v51, v2
	v_fma_f32 v2, -v4, v52, v2
	v_fma_f32 v2, -v7, v53, v2
	v_fma_f32 v2, -v9, v54, v2
	v_fma_f32 v2, -v10, v55, v2
	v_fma_f32 v2, -v11, v114, v2
	v_fma_f32 v2, -v12, v115, v2
	v_fma_f32 v2, -v13, v116, v2
	v_fma_f32 v2, -v14, v117, v2
	v_fma_f32 v2, -v15, v122, v2
	v_fma_f32 v2, -v16, v123, v2
	v_fma_f32 v2, -v17, v124, v2
	v_fma_f32 v2, -v18, v125, v2
	v_fma_f32 v2, -v19, v126, v2
	v_fma_f32 v2, -v20, v127, v2
	v_fma_f32 v2, -v21, v128, v2
	v_fma_f32 v2, -v22, v129, v2
	v_fma_f32 v2, -v23, v130, v2
	v_fma_f32 v2, -v24, v131, v2
	v_fma_f32 v2, -v25, v132, v2
	v_fma_f32 v2, -v26, v133, v2
	v_fma_f32 v2, -v27, v134, v2
	v_fma_f32 v2, -v28, v135, v2
	v_fma_f32 v2, -v29, v136, v2
	v_fma_f32 v2, -v137, v30, v2
	v_fma_f32 v2, -v146, v31, v2
	v_fma_f32 v2, -v78, v147, v2
	v_fma_f32 v2, -v80, v148, v2
	ds_read_b128 v[34:37], v0 offset:26112
	ds_read_b128 v[44:47], v0 offset:26128
	ds_read_b128 v[60:63], v0 offset:26144
	ds_read_b128 v[110:113], v0 offset:26160
	ds_read_b128 v[118:121], v0 offset:26176
	ds_read_b128 v[138:141], v0 offset:26192
	ds_read_b128 v[142:145], v0 offset:26208
	ds_read_b128 v[150:153], v0 offset:26224
	v_fma_f32 v32, -v82, v149, v2
	s_waitcnt lgkmcnt(0)
	v_fma_f32 v2, -v41, v34, v80
	v_fma_f32 v2, -v5, v35, v2
	v_fma_f32 v2, -v6, v36, v2
	v_fma_f32 v2, -v8, v37, v2
	v_fma_f32 v2, -v4, v44, v2
	v_fma_f32 v2, -v7, v45, v2
	v_fma_f32 v2, -v9, v46, v2
	v_fma_f32 v2, -v10, v47, v2
	v_fma_f32 v2, -v11, v60, v2
	v_fma_f32 v2, -v12, v61, v2
	v_fma_f32 v2, -v13, v62, v2
	v_fma_f32 v2, -v14, v63, v2
	v_fma_f32 v2, -v15, v110, v2
	v_fma_f32 v2, -v16, v111, v2
	v_fma_f32 v2, -v17, v112, v2
	v_fma_f32 v2, -v18, v113, v2
	v_fma_f32 v2, -v19, v118, v2
	v_fma_f32 v2, -v20, v119, v2
	v_fma_f32 v2, -v21, v120, v2
	v_fma_f32 v2, -v22, v121, v2
	v_fma_f32 v2, -v23, v138, v2
	v_fma_f32 v2, -v24, v139, v2
	v_fma_f32 v2, -v25, v140, v2
	v_fma_f32 v2, -v26, v141, v2
	v_fma_f32 v2, -v27, v142, v2
	v_fma_f32 v2, -v28, v143, v2
	v_fma_f32 v2, -v29, v144, v2
	v_fma_f32 v2, -v30, v145, v2
	v_fma_f32 v2, -v150, v31, v2
	v_fma_f32 v2, -v151, v32, v2
	v_fma_f32 v2, -v80, v152, v2
	ds_read_b128 v[48:51], v0 offset:26368
	ds_read_b128 v[52:55], v0 offset:26384
	ds_read_b128 v[114:117], v0 offset:26400
	ds_read_b128 v[122:125], v0 offset:26416
	ds_read_b128 v[126:129], v0 offset:26432
	ds_read_b128 v[130:133], v0 offset:26448
	ds_read_b128 v[134:137], v0 offset:26464
	ds_read_b128 v[146:149], v0 offset:26480
	v_fma_f32 v33, -v82, v153, v2
	s_waitcnt lgkmcnt(0)
	v_fma_f32 v2, -v41, v48, v82
	v_fma_f32 v2, -v5, v49, v2
	v_fma_f32 v2, -v6, v50, v2
	v_fma_f32 v2, -v8, v51, v2
	v_fma_f32 v2, -v4, v52, v2
	v_fma_f32 v2, -v7, v53, v2
	v_fma_f32 v2, -v9, v54, v2
	v_fma_f32 v2, -v10, v55, v2
	v_fma_f32 v2, -v11, v114, v2
	v_fma_f32 v2, -v12, v115, v2
	v_fma_f32 v2, -v13, v116, v2
	v_fma_f32 v2, -v14, v117, v2
	v_fma_f32 v2, -v15, v122, v2
	v_fma_f32 v2, -v16, v123, v2
	v_fma_f32 v2, -v17, v124, v2
	v_fma_f32 v2, -v18, v125, v2
	v_fma_f32 v2, -v19, v126, v2
	v_fma_f32 v2, -v20, v127, v2
	v_fma_f32 v2, -v21, v128, v2
	v_fma_f32 v2, -v22, v129, v2
	v_fma_f32 v2, -v23, v130, v2
	v_fma_f32 v2, -v24, v131, v2
	v_fma_f32 v2, -v25, v132, v2
	v_fma_f32 v2, -v26, v133, v2
	v_fma_f32 v2, -v27, v134, v2
	v_fma_f32 v2, -v28, v135, v2
	v_fma_f32 v2, -v29, v136, v2
	v_fma_f32 v2, -v30, v137, v2
	v_fma_f32 v2, -v31, v146, v2
	v_fma_f32 v2, -v147, v32, v2
	v_fma_f32 v2, -v148, v33, v2
	ds_read_b128 v[44:47], v0 offset:26624
	ds_read_b128 v[60:63], v0 offset:26640
	ds_read_b128 v[110:113], v0 offset:26656
	ds_read_b128 v[118:121], v0 offset:26672
	ds_read_b128 v[138:141], v0 offset:26688
	ds_read_b128 v[142:145], v0 offset:26704
	ds_read_b128 v[150:153], v0 offset:26720
	ds_read_b128 v[154:157], v0 offset:26736
	v_fma_f32 v34, -v82, v149, v2
	s_waitcnt lgkmcnt(0)
	v_fma_f32 v2, -v41, v44, v89
	v_fma_f32 v2, -v5, v45, v2
	v_fma_f32 v2, -v6, v46, v2
	v_fma_f32 v2, -v8, v47, v2
	v_fma_f32 v2, -v4, v60, v2
	v_fma_f32 v2, -v7, v61, v2
	v_fma_f32 v2, -v9, v62, v2
	v_fma_f32 v2, -v10, v63, v2
	v_fma_f32 v2, -v11, v110, v2
	v_fma_f32 v2, -v12, v111, v2
	v_fma_f32 v2, -v13, v112, v2
	v_fma_f32 v2, -v14, v113, v2
	v_fma_f32 v2, -v15, v118, v2
	v_fma_f32 v2, -v16, v119, v2
	v_fma_f32 v2, -v17, v120, v2
	v_fma_f32 v2, -v18, v121, v2
	v_fma_f32 v2, -v19, v138, v2
	v_fma_f32 v2, -v20, v139, v2
	v_fma_f32 v2, -v21, v140, v2
	v_fma_f32 v2, -v22, v141, v2
	v_fma_f32 v2, -v23, v142, v2
	v_fma_f32 v2, -v24, v143, v2
	v_fma_f32 v2, -v25, v144, v2
	v_fma_f32 v2, -v26, v145, v2
	v_fma_f32 v2, -v27, v150, v2
	v_fma_f32 v2, -v28, v151, v2
	v_fma_f32 v2, -v29, v152, v2
	v_fma_f32 v2, -v30, v153, v2
	v_fma_f32 v2, -v31, v154, v2
	v_fma_f32 v2, -v32, v155, v2
	v_fma_f32 v2, -v156, v33, v2
	ds_read_b128 v[48:51], v0 offset:26880
	ds_read_b128 v[52:55], v0 offset:26896
	ds_read_b128 v[114:117], v0 offset:26912
	ds_read_b128 v[122:125], v0 offset:26928
	ds_read_b128 v[126:129], v0 offset:26944
	ds_read_b128 v[130:133], v0 offset:26960
	ds_read_b128 v[134:137], v0 offset:26976
	ds_read_b128 v[146:149], v0 offset:26992
	ds_read_b128 v[158:161], v0 offset:27008
	v_fma_f32 v35, -v157, v34, v2
	s_waitcnt lgkmcnt(0)
	v_fma_f32 v2, -v41, v48, v85
	v_fma_f32 v2, -v5, v49, v2
	v_fma_f32 v2, -v6, v50, v2
	v_fma_f32 v2, -v8, v51, v2
	v_fma_f32 v2, -v4, v52, v2
	v_fma_f32 v2, -v7, v53, v2
	v_fma_f32 v2, -v9, v54, v2
	v_fma_f32 v2, -v10, v55, v2
	v_fma_f32 v2, -v11, v114, v2
	v_fma_f32 v2, -v12, v115, v2
	v_fma_f32 v2, -v13, v116, v2
	v_fma_f32 v2, -v14, v117, v2
	v_fma_f32 v2, -v15, v122, v2
	v_fma_f32 v2, -v16, v123, v2
	v_fma_f32 v2, -v17, v124, v2
	v_fma_f32 v2, -v18, v125, v2
	v_fma_f32 v2, -v19, v126, v2
	v_fma_f32 v2, -v20, v127, v2
	v_fma_f32 v2, -v21, v128, v2
	v_fma_f32 v2, -v22, v129, v2
	v_fma_f32 v2, -v23, v130, v2
	v_fma_f32 v2, -v24, v131, v2
	v_fma_f32 v2, -v25, v132, v2
	v_fma_f32 v2, -v26, v133, v2
	v_fma_f32 v2, -v27, v134, v2
	v_fma_f32 v2, -v28, v135, v2
	v_fma_f32 v2, -v29, v136, v2
	v_fma_f32 v2, -v30, v137, v2
	v_fma_f32 v2, -v31, v146, v2
	v_fma_f32 v2, -v32, v147, v2
	v_fma_f32 v2, -v33, v148, v2
	v_fma_f32 v2, -v149, v34, v2
	v_fma_f32 v2, -v158, v35, v2
	v_fma_f32 v2, -v85, v159, v2
	v_fma_f32 v2, -v87, v160, v2
	ds_read_b128 v[44:47], v0 offset:27136
	ds_read_b128 v[60:63], v0 offset:27152
	ds_read_b128 v[110:113], v0 offset:27168
	ds_read_b128 v[118:121], v0 offset:27184
	ds_read_b128 v[138:141], v0 offset:27200
	ds_read_b128 v[142:145], v0 offset:27216
	ds_read_b128 v[150:153], v0 offset:27232
	ds_read_b128 v[154:157], v0 offset:27248
	ds_read_b128 v[162:165], v0 offset:27264
	v_fma_f32 v36, -v90, v161, v2
	s_waitcnt lgkmcnt(0)
	v_fma_f32 v2, -v41, v44, v87
	v_fma_f32 v2, -v5, v45, v2
	v_fma_f32 v2, -v6, v46, v2
	v_fma_f32 v2, -v8, v47, v2
	v_fma_f32 v2, -v4, v60, v2
	v_fma_f32 v2, -v7, v61, v2
	v_fma_f32 v2, -v9, v62, v2
	v_fma_f32 v2, -v10, v63, v2
	v_fma_f32 v2, -v11, v110, v2
	v_fma_f32 v2, -v12, v111, v2
	v_fma_f32 v2, -v13, v112, v2
	v_fma_f32 v2, -v14, v113, v2
	v_fma_f32 v2, -v15, v118, v2
	v_fma_f32 v2, -v16, v119, v2
	v_fma_f32 v2, -v17, v120, v2
	v_fma_f32 v2, -v18, v121, v2
	v_fma_f32 v2, -v19, v138, v2
	v_fma_f32 v2, -v20, v139, v2
	v_fma_f32 v2, -v21, v140, v2
	v_fma_f32 v2, -v22, v141, v2
	v_fma_f32 v2, -v23, v142, v2
	v_fma_f32 v2, -v24, v143, v2
	v_fma_f32 v2, -v25, v144, v2
	v_fma_f32 v2, -v26, v145, v2
	v_fma_f32 v2, -v27, v150, v2
	v_fma_f32 v2, -v28, v151, v2
	v_fma_f32 v2, -v29, v152, v2
	v_fma_f32 v2, -v30, v153, v2
	v_fma_f32 v2, -v31, v154, v2
	v_fma_f32 v2, -v32, v155, v2
	v_fma_f32 v2, -v33, v156, v2
	v_fma_f32 v2, -v34, v157, v2
	v_fma_f32 v2, -v162, v35, v2
	v_fma_f32 v2, -v163, v36, v2
	v_fma_f32 v2, -v87, v164, v2
	ds_read_b128 v[48:51], v0 offset:27392
	ds_read_b128 v[52:55], v0 offset:27408
	ds_read_b128 v[114:117], v0 offset:27424
	ds_read_b128 v[122:125], v0 offset:27440
	ds_read_b128 v[126:129], v0 offset:27456
	ds_read_b128 v[130:133], v0 offset:27472
	ds_read_b128 v[134:137], v0 offset:27488
	ds_read_b128 v[146:149], v0 offset:27504
	ds_read_b128 v[158:161], v0 offset:27520
	v_fma_f32 v37, -v90, v165, v2
	s_waitcnt lgkmcnt(0)
	v_fma_f32 v2, -v41, v48, v90
	v_fma_f32 v2, -v5, v49, v2
	v_fma_f32 v2, -v6, v50, v2
	v_fma_f32 v2, -v8, v51, v2
	v_fma_f32 v2, -v4, v52, v2
	v_fma_f32 v2, -v7, v53, v2
	v_fma_f32 v2, -v9, v54, v2
	v_fma_f32 v2, -v10, v55, v2
	v_fma_f32 v2, -v11, v114, v2
	v_fma_f32 v2, -v12, v115, v2
	v_fma_f32 v2, -v13, v116, v2
	v_fma_f32 v2, -v14, v117, v2
	v_fma_f32 v2, -v15, v122, v2
	v_fma_f32 v2, -v16, v123, v2
	v_fma_f32 v2, -v17, v124, v2
	v_fma_f32 v2, -v18, v125, v2
	v_fma_f32 v2, -v19, v126, v2
	v_fma_f32 v2, -v20, v127, v2
	v_fma_f32 v2, -v21, v128, v2
	v_fma_f32 v2, -v22, v129, v2
	v_fma_f32 v2, -v23, v130, v2
	v_fma_f32 v2, -v24, v131, v2
	v_fma_f32 v2, -v25, v132, v2
	v_fma_f32 v2, -v26, v133, v2
	v_fma_f32 v2, -v27, v134, v2
	v_fma_f32 v2, -v28, v135, v2
	v_fma_f32 v2, -v29, v136, v2
	v_fma_f32 v2, -v30, v137, v2
	v_fma_f32 v2, -v31, v146, v2
	v_fma_f32 v2, -v32, v147, v2
	v_fma_f32 v2, -v33, v148, v2
	v_fma_f32 v2, -v34, v149, v2
	v_fma_f32 v2, -v35, v158, v2
	v_fma_f32 v2, -v159, v36, v2
	v_fma_f32 v2, -v160, v37, v2
	ds_read_b128 v[44:47], v0 offset:27648
	ds_read_b128 v[60:63], v0 offset:27664
	ds_read_b128 v[110:113], v0 offset:27680
	ds_read_b128 v[118:121], v0 offset:27696
	ds_read_b128 v[138:141], v0 offset:27712
	ds_read_b128 v[142:145], v0 offset:27728
	ds_read_b128 v[150:153], v0 offset:27744
	ds_read_b128 v[154:157], v0 offset:27760
	ds_read_b128 v[162:165], v0 offset:27776
	v_fma_f32 v43, -v90, v161, v2
	s_waitcnt lgkmcnt(0)
	v_fma_f32 v2, -v41, v44, v105
	v_fma_f32 v2, -v5, v45, v2
	v_fma_f32 v2, -v6, v46, v2
	v_fma_f32 v2, -v8, v47, v2
	v_fma_f32 v2, -v4, v60, v2
	v_fma_f32 v2, -v7, v61, v2
	v_fma_f32 v2, -v9, v62, v2
	v_fma_f32 v2, -v10, v63, v2
	v_fma_f32 v2, -v11, v110, v2
	v_fma_f32 v2, -v12, v111, v2
	v_fma_f32 v2, -v13, v112, v2
	v_fma_f32 v2, -v14, v113, v2
	v_fma_f32 v2, -v15, v118, v2
	v_fma_f32 v2, -v16, v119, v2
	v_fma_f32 v2, -v17, v120, v2
	v_fma_f32 v2, -v18, v121, v2
	v_fma_f32 v2, -v19, v138, v2
	v_fma_f32 v2, -v20, v139, v2
	v_fma_f32 v2, -v21, v140, v2
	v_fma_f32 v2, -v22, v141, v2
	v_fma_f32 v2, -v23, v142, v2
	v_fma_f32 v2, -v24, v143, v2
	v_fma_f32 v2, -v25, v144, v2
	v_fma_f32 v2, -v26, v145, v2
	v_fma_f32 v2, -v27, v150, v2
	v_fma_f32 v2, -v28, v151, v2
	v_fma_f32 v2, -v29, v152, v2
	v_fma_f32 v2, -v30, v153, v2
	v_fma_f32 v2, -v31, v154, v2
	v_fma_f32 v2, -v32, v155, v2
	v_fma_f32 v2, -v33, v156, v2
	v_fma_f32 v2, -v34, v157, v2
	v_fma_f32 v2, -v35, v162, v2
	v_fma_f32 v2, -v36, v163, v2
	v_fma_f32 v2, -v164, v37, v2
	ds_read_b128 v[48:51], v0 offset:27904
	ds_read_b128 v[52:55], v0 offset:27920
	ds_read_b128 v[114:117], v0 offset:27936
	ds_read_b128 v[122:125], v0 offset:27952
	ds_read_b128 v[126:129], v0 offset:27968
	ds_read_b128 v[130:133], v0 offset:27984
	ds_read_b128 v[134:137], v0 offset:28000
	ds_read_b128 v[146:149], v0 offset:28016
	ds_read_b128 v[158:161], v0 offset:28032
	ds_read_b128 v[166:169], v0 offset:28048
	v_fma_f32 v44, -v165, v43, v2
	s_waitcnt lgkmcnt(0)
	v_fma_f32 v2, -v41, v48, v93
	v_fma_f32 v2, -v5, v49, v2
	v_fma_f32 v2, -v6, v50, v2
	v_fma_f32 v2, -v8, v51, v2
	v_fma_f32 v2, -v4, v52, v2
	v_fma_f32 v2, -v7, v53, v2
	v_fma_f32 v2, -v9, v54, v2
	v_fma_f32 v2, -v10, v55, v2
	v_fma_f32 v2, -v11, v114, v2
	v_fma_f32 v2, -v12, v115, v2
	v_fma_f32 v2, -v13, v116, v2
	v_fma_f32 v2, -v14, v117, v2
	v_fma_f32 v2, -v15, v122, v2
	v_fma_f32 v2, -v16, v123, v2
	v_fma_f32 v2, -v17, v124, v2
	v_fma_f32 v2, -v18, v125, v2
	v_fma_f32 v2, -v19, v126, v2
	v_fma_f32 v2, -v20, v127, v2
	v_fma_f32 v2, -v21, v128, v2
	v_fma_f32 v2, -v22, v129, v2
	v_fma_f32 v2, -v23, v130, v2
	v_fma_f32 v2, -v24, v131, v2
	v_fma_f32 v2, -v25, v132, v2
	v_fma_f32 v2, -v26, v133, v2
	v_fma_f32 v2, -v27, v134, v2
	v_fma_f32 v2, -v28, v135, v2
	v_fma_f32 v2, -v29, v136, v2
	v_fma_f32 v2, -v30, v137, v2
	v_fma_f32 v2, -v31, v146, v2
	v_fma_f32 v2, -v32, v147, v2
	v_fma_f32 v2, -v33, v148, v2
	v_fma_f32 v2, -v34, v149, v2
	v_fma_f32 v2, -v35, v158, v2
	v_fma_f32 v2, -v36, v159, v2
	v_fma_f32 v2, -v37, v160, v2
	v_fma_f32 v2, -v161, v43, v2
	v_fma_f32 v2, -v166, v44, v2
	v_fma_f32 v2, -v93, v167, v2
	v_fma_f32 v2, -v96, v168, v2
	ds_read_b128 v[60:63], v0 offset:28160
	ds_read_b128 v[110:113], v0 offset:28176
	ds_read_b128 v[118:121], v0 offset:28192
	ds_read_b128 v[138:141], v0 offset:28208
	ds_read_b128 v[142:145], v0 offset:28224
	ds_read_b128 v[150:153], v0 offset:28240
	ds_read_b128 v[154:157], v0 offset:28256
	ds_read_b128 v[162:165], v0 offset:28272
	ds_read_b128 v[170:173], v0 offset:28288
	ds_read_b128 v[178:181], v0 offset:28304
	v_fma_f32 v45, -v98, v169, v2
	s_waitcnt lgkmcnt(0)
	v_fma_f32 v2, -v41, v60, v96
	v_fma_f32 v2, -v5, v61, v2
	v_fma_f32 v2, -v6, v62, v2
	v_fma_f32 v2, -v8, v63, v2
	v_fma_f32 v2, -v4, v110, v2
	v_fma_f32 v2, -v7, v111, v2
	v_fma_f32 v2, -v9, v112, v2
	v_fma_f32 v2, -v10, v113, v2
	v_fma_f32 v2, -v11, v118, v2
	v_fma_f32 v2, -v12, v119, v2
	v_fma_f32 v2, -v13, v120, v2
	v_fma_f32 v2, -v14, v121, v2
	v_fma_f32 v2, -v15, v138, v2
	v_fma_f32 v2, -v16, v139, v2
	v_fma_f32 v2, -v17, v140, v2
	v_fma_f32 v2, -v18, v141, v2
	v_fma_f32 v2, -v19, v142, v2
	v_fma_f32 v2, -v20, v143, v2
	v_fma_f32 v2, -v21, v144, v2
	v_fma_f32 v2, -v22, v145, v2
	v_fma_f32 v2, -v23, v150, v2
	v_fma_f32 v2, -v24, v151, v2
	v_fma_f32 v2, -v25, v152, v2
	v_fma_f32 v2, -v26, v153, v2
	v_fma_f32 v2, -v27, v154, v2
	v_fma_f32 v2, -v28, v155, v2
	v_fma_f32 v2, -v29, v156, v2
	v_fma_f32 v2, -v30, v157, v2
	v_fma_f32 v2, -v31, v162, v2
	v_fma_f32 v2, -v32, v163, v2
	v_fma_f32 v2, -v33, v164, v2
	v_fma_f32 v2, -v34, v165, v2
	v_fma_f32 v2, -v35, v170, v2
	v_fma_f32 v2, -v36, v171, v2
	v_fma_f32 v2, -v37, v172, v2
	v_fma_f32 v2, -v43, v173, v2
	v_fma_f32 v2, -v178, v44, v2
	v_fma_f32 v2, -v179, v45, v2
	v_fma_f32 v2, -v96, v180, v2
	ds_read_b128 v[48:51], v0 offset:28416
	ds_read_b128 v[52:55], v0 offset:28432
	ds_read_b128 v[114:117], v0 offset:28448
	ds_read_b128 v[122:125], v0 offset:28464
	ds_read_b128 v[126:129], v0 offset:28480
	ds_read_b128 v[130:133], v0 offset:28496
	ds_read_b128 v[134:137], v0 offset:28512
	ds_read_b128 v[146:149], v0 offset:28528
	ds_read_b128 v[158:161], v0 offset:28544
	ds_read_b128 v[166:169], v0 offset:28560
	v_fma_f32 v46, -v98, v181, v2
	s_waitcnt lgkmcnt(0)
	v_fma_f32 v2, -v41, v48, v98
	v_fma_f32 v2, -v5, v49, v2
	v_fma_f32 v2, -v6, v50, v2
	v_fma_f32 v2, -v8, v51, v2
	v_fma_f32 v2, -v4, v52, v2
	v_fma_f32 v2, -v7, v53, v2
	v_fma_f32 v2, -v9, v54, v2
	v_fma_f32 v2, -v10, v55, v2
	v_fma_f32 v2, -v11, v114, v2
	v_fma_f32 v2, -v12, v115, v2
	v_fma_f32 v2, -v13, v116, v2
	v_fma_f32 v2, -v14, v117, v2
	v_fma_f32 v2, -v15, v122, v2
	v_fma_f32 v2, -v16, v123, v2
	v_fma_f32 v2, -v17, v124, v2
	v_fma_f32 v2, -v18, v125, v2
	v_fma_f32 v2, -v19, v126, v2
	v_fma_f32 v2, -v20, v127, v2
	v_fma_f32 v2, -v21, v128, v2
	v_fma_f32 v2, -v22, v129, v2
	v_fma_f32 v2, -v23, v130, v2
	v_fma_f32 v2, -v24, v131, v2
	v_fma_f32 v2, -v25, v132, v2
	v_fma_f32 v2, -v26, v133, v2
	v_fma_f32 v2, -v27, v134, v2
	v_fma_f32 v2, -v28, v135, v2
	v_fma_f32 v2, -v29, v136, v2
	v_fma_f32 v2, -v30, v137, v2
	v_fma_f32 v2, -v31, v146, v2
	v_fma_f32 v2, -v32, v147, v2
	v_fma_f32 v2, -v33, v148, v2
	v_fma_f32 v2, -v34, v149, v2
	v_fma_f32 v2, -v35, v158, v2
	v_fma_f32 v2, -v36, v159, v2
	v_fma_f32 v2, -v37, v160, v2
	v_fma_f32 v2, -v43, v161, v2
	v_fma_f32 v2, -v44, v166, v2
	v_fma_f32 v2, -v167, v45, v2
	v_fma_f32 v2, -v168, v46, v2
	ds_read_b128 v[60:63], v0 offset:28672
	ds_read_b128 v[110:113], v0 offset:28688
	ds_read_b128 v[118:121], v0 offset:28704
	ds_read_b128 v[138:141], v0 offset:28720
	ds_read_b128 v[142:145], v0 offset:28736
	ds_read_b128 v[150:153], v0 offset:28752
	ds_read_b128 v[154:157], v0 offset:28768
	ds_read_b128 v[162:165], v0 offset:28784
	ds_read_b128 v[170:173], v0 offset:28800
	ds_read_b128 v[178:181], v0 offset:28816
	v_fma_f32 v47, -v98, v169, v2
	s_waitcnt lgkmcnt(0)
	v_fma_f32 v2, -v41, v60, v107
	v_fma_f32 v2, -v5, v61, v2
	v_fma_f32 v2, -v6, v62, v2
	v_fma_f32 v2, -v8, v63, v2
	v_fma_f32 v2, -v4, v110, v2
	v_fma_f32 v2, -v7, v111, v2
	v_fma_f32 v2, -v9, v112, v2
	v_fma_f32 v2, -v10, v113, v2
	v_fma_f32 v2, -v11, v118, v2
	v_fma_f32 v2, -v12, v119, v2
	v_fma_f32 v2, -v13, v120, v2
	v_fma_f32 v2, -v14, v121, v2
	v_fma_f32 v2, -v15, v138, v2
	v_fma_f32 v2, -v16, v139, v2
	v_fma_f32 v2, -v17, v140, v2
	v_fma_f32 v2, -v18, v141, v2
	v_fma_f32 v2, -v19, v142, v2
	v_fma_f32 v2, -v20, v143, v2
	v_fma_f32 v2, -v21, v144, v2
	v_fma_f32 v2, -v22, v145, v2
	v_fma_f32 v2, -v23, v150, v2
	v_fma_f32 v2, -v24, v151, v2
	v_fma_f32 v2, -v25, v152, v2
	v_fma_f32 v2, -v26, v153, v2
	v_fma_f32 v2, -v27, v154, v2
	v_fma_f32 v2, -v28, v155, v2
	v_fma_f32 v2, -v29, v156, v2
	v_fma_f32 v2, -v30, v157, v2
	v_fma_f32 v2, -v31, v162, v2
	v_fma_f32 v2, -v32, v163, v2
	v_fma_f32 v2, -v33, v164, v2
	v_fma_f32 v2, -v34, v165, v2
	v_fma_f32 v2, -v35, v170, v2
	v_fma_f32 v2, -v36, v171, v2
	v_fma_f32 v2, -v37, v172, v2
	v_fma_f32 v2, -v43, v173, v2
	v_fma_f32 v2, -v44, v178, v2
	v_fma_f32 v2, -v45, v179, v2
	v_fma_f32 v2, -v180, v46, v2
	ds_read_b128 v[50:53], v0 offset:28928
	ds_read_b128 v[54:57], v0 offset:28944
	ds_read_b128 v[114:117], v0 offset:28960
	ds_read_b128 v[122:125], v0 offset:28976
	ds_read_b128 v[126:129], v0 offset:28992
	ds_read_b128 v[130:133], v0 offset:29008
	ds_read_b128 v[134:137], v0 offset:29024
	ds_read_b128 v[146:149], v0 offset:29040
	ds_read_b128 v[158:161], v0 offset:29056
	ds_read_b128 v[166:169], v0 offset:29072
	ds_read_b128 v[182:185], v0 offset:29088
	v_fma_f32 v48, -v181, v47, v2
	s_waitcnt lgkmcnt(0)
	v_fma_f32 v2, -v41, v50, v102
	v_fma_f32 v2, -v5, v51, v2
	v_fma_f32 v2, -v6, v52, v2
	v_fma_f32 v2, -v8, v53, v2
	v_fma_f32 v2, -v4, v54, v2
	v_fma_f32 v2, -v7, v55, v2
	v_fma_f32 v2, -v9, v56, v2
	v_fma_f32 v2, -v10, v57, v2
	v_fma_f32 v2, -v11, v114, v2
	v_fma_f32 v2, -v12, v115, v2
	v_fma_f32 v2, -v13, v116, v2
	v_fma_f32 v2, -v14, v117, v2
	v_fma_f32 v2, -v15, v122, v2
	v_fma_f32 v2, -v16, v123, v2
	v_fma_f32 v2, -v17, v124, v2
	v_fma_f32 v2, -v18, v125, v2
	v_fma_f32 v2, -v19, v126, v2
	v_fma_f32 v2, -v20, v127, v2
	v_fma_f32 v2, -v21, v128, v2
	v_fma_f32 v2, -v22, v129, v2
	v_fma_f32 v2, -v23, v130, v2
	v_fma_f32 v2, -v24, v131, v2
	v_fma_f32 v2, -v25, v132, v2
	v_fma_f32 v2, -v26, v133, v2
	v_fma_f32 v2, -v27, v134, v2
	v_fma_f32 v2, -v28, v135, v2
	v_fma_f32 v2, -v29, v136, v2
	v_fma_f32 v2, -v30, v137, v2
	v_fma_f32 v2, -v31, v146, v2
	v_fma_f32 v2, -v32, v147, v2
	v_fma_f32 v2, -v33, v148, v2
	v_fma_f32 v2, -v34, v149, v2
	v_fma_f32 v2, -v35, v158, v2
	v_fma_f32 v2, -v36, v159, v2
	v_fma_f32 v2, -v37, v160, v2
	v_fma_f32 v2, -v43, v161, v2
	v_fma_f32 v2, -v44, v166, v2
	v_fma_f32 v2, -v45, v167, v2
	v_fma_f32 v2, -v46, v168, v2
	v_fma_f32 v2, -v169, v47, v2
	v_fma_f32 v2, -v182, v48, v2
	v_fma_f32 v2, -v102, v183, v2
	v_fma_f32 v2, -v103, v184, v2
	ds_read_b128 v[60:63], v0 offset:29184
	ds_read_b128 v[110:113], v0 offset:29200
	ds_read_b128 v[118:121], v0 offset:29216
	ds_read_b128 v[138:141], v0 offset:29232
	ds_read_b128 v[142:145], v0 offset:29248
	ds_read_b128 v[150:153], v0 offset:29264
	ds_read_b128 v[154:157], v0 offset:29280
	ds_read_b128 v[162:165], v0 offset:29296
	ds_read_b128 v[170:173], v0 offset:29312
	ds_read_b128 v[178:181], v0 offset:29328
	ds_read_b128 v[186:189], v0 offset:29344
	v_fma_f32 v49, -v104, v185, v2
	s_waitcnt lgkmcnt(0)
	v_fma_f32 v2, -v41, v60, v103
	v_fma_f32 v2, -v5, v61, v2
	v_fma_f32 v2, -v6, v62, v2
	v_fma_f32 v2, -v8, v63, v2
	v_fma_f32 v2, -v4, v110, v2
	v_fma_f32 v2, -v7, v111, v2
	v_fma_f32 v2, -v9, v112, v2
	v_fma_f32 v2, -v10, v113, v2
	v_fma_f32 v2, -v11, v118, v2
	v_fma_f32 v2, -v12, v119, v2
	v_fma_f32 v2, -v13, v120, v2
	v_fma_f32 v2, -v14, v121, v2
	v_fma_f32 v2, -v15, v138, v2
	v_fma_f32 v2, -v16, v139, v2
	v_fma_f32 v2, -v17, v140, v2
	v_fma_f32 v2, -v18, v141, v2
	v_fma_f32 v2, -v19, v142, v2
	v_fma_f32 v2, -v20, v143, v2
	v_fma_f32 v2, -v21, v144, v2
	v_fma_f32 v2, -v22, v145, v2
	v_fma_f32 v2, -v23, v150, v2
	v_fma_f32 v2, -v24, v151, v2
	v_fma_f32 v2, -v25, v152, v2
	v_fma_f32 v2, -v26, v153, v2
	v_fma_f32 v2, -v27, v154, v2
	v_fma_f32 v2, -v28, v155, v2
	v_fma_f32 v2, -v29, v156, v2
	v_fma_f32 v2, -v30, v157, v2
	v_fma_f32 v2, -v31, v162, v2
	v_fma_f32 v2, -v32, v163, v2
	v_fma_f32 v2, -v33, v164, v2
	v_fma_f32 v2, -v34, v165, v2
	v_fma_f32 v2, -v35, v170, v2
	v_fma_f32 v2, -v36, v171, v2
	v_fma_f32 v2, -v37, v172, v2
	v_fma_f32 v2, -v43, v173, v2
	v_fma_f32 v2, -v44, v178, v2
	v_fma_f32 v2, -v45, v179, v2
	v_fma_f32 v2, -v46, v180, v2
	v_fma_f32 v2, -v47, v181, v2
	v_fma_f32 v2, -v186, v48, v2
	v_fma_f32 v2, -v187, v49, v2
	v_fma_f32 v2, -v103, v188, v2
	ds_read_b128 v[52:55], v0 offset:29440
	ds_read_b128 v[114:117], v0 offset:29456
	ds_read_b128 v[122:125], v0 offset:29472
	ds_read_b128 v[126:129], v0 offset:29488
	ds_read_b128 v[130:133], v0 offset:29504
	ds_read_b128 v[134:137], v0 offset:29520
	ds_read_b128 v[146:149], v0 offset:29536
	ds_read_b128 v[158:161], v0 offset:29552
	ds_read_b128 v[166:169], v0 offset:29568
	ds_read_b128 v[182:185], v0 offset:29584
	ds_read_b128 v[190:193], v0 offset:29600
	v_fma_f32 v50, -v104, v189, v2
	s_waitcnt lgkmcnt(0)
	v_fma_f32 v2, -v41, v52, v104
	v_fma_f32 v2, -v5, v53, v2
	v_fma_f32 v2, -v6, v54, v2
	v_fma_f32 v2, -v8, v55, v2
	v_fma_f32 v2, -v4, v114, v2
	v_fma_f32 v2, -v7, v115, v2
	v_fma_f32 v2, -v9, v116, v2
	v_fma_f32 v2, -v10, v117, v2
	v_fma_f32 v2, -v11, v122, v2
	v_fma_f32 v2, -v12, v123, v2
	v_fma_f32 v2, -v13, v124, v2
	v_fma_f32 v2, -v14, v125, v2
	v_fma_f32 v2, -v15, v126, v2
	v_fma_f32 v2, -v16, v127, v2
	v_fma_f32 v2, -v17, v128, v2
	v_fma_f32 v2, -v18, v129, v2
	v_fma_f32 v2, -v19, v130, v2
	v_fma_f32 v2, -v20, v131, v2
	v_fma_f32 v2, -v21, v132, v2
	v_fma_f32 v2, -v22, v133, v2
	v_fma_f32 v2, -v23, v134, v2
	v_fma_f32 v2, -v24, v135, v2
	v_fma_f32 v2, -v25, v136, v2
	v_fma_f32 v2, -v26, v137, v2
	v_fma_f32 v2, -v27, v146, v2
	v_fma_f32 v2, -v28, v147, v2
	v_fma_f32 v2, -v29, v148, v2
	v_fma_f32 v2, -v30, v149, v2
	v_fma_f32 v2, -v31, v158, v2
	v_fma_f32 v2, -v32, v159, v2
	v_fma_f32 v2, -v33, v160, v2
	v_fma_f32 v2, -v34, v161, v2
	v_fma_f32 v2, -v35, v166, v2
	v_fma_f32 v2, -v36, v167, v2
	v_fma_f32 v2, -v37, v168, v2
	v_fma_f32 v2, -v43, v169, v2
	v_fma_f32 v2, -v44, v182, v2
	v_fma_f32 v2, -v45, v183, v2
	v_fma_f32 v2, -v46, v184, v2
	v_fma_f32 v2, -v47, v185, v2
	v_fma_f32 v2, -v48, v190, v2
	v_fma_f32 v2, -v191, v49, v2
	v_fma_f32 v2, -v192, v50, v2
	ds_read_b128 v[60:63], v0 offset:29696
	ds_read_b128 v[110:113], v0 offset:29712
	ds_read_b128 v[118:121], v0 offset:29728
	ds_read_b128 v[138:141], v0 offset:29744
	ds_read_b128 v[142:145], v0 offset:29760
	ds_read_b128 v[150:153], v0 offset:29776
	ds_read_b128 v[154:157], v0 offset:29792
	ds_read_b128 v[162:165], v0 offset:29808
	ds_read_b128 v[170:173], v0 offset:29824
	ds_read_b128 v[178:181], v0 offset:29840
	ds_read_b128 v[186:189], v0 offset:29856
	v_fma_f32 v51, -v104, v193, v2
	s_waitcnt lgkmcnt(0)
	v_fma_f32 v2, -v41, v60, v108
	v_fma_f32 v2, -v5, v61, v2
	v_fma_f32 v2, -v6, v62, v2
	v_fma_f32 v2, -v8, v63, v2
	v_fma_f32 v2, -v4, v110, v2
	v_fma_f32 v2, -v7, v111, v2
	v_fma_f32 v2, -v9, v112, v2
	v_fma_f32 v2, -v10, v113, v2
	v_fma_f32 v2, -v11, v118, v2
	v_fma_f32 v2, -v12, v119, v2
	v_fma_f32 v2, -v13, v120, v2
	v_fma_f32 v2, -v14, v121, v2
	v_fma_f32 v2, -v15, v138, v2
	v_fma_f32 v2, -v16, v139, v2
	v_fma_f32 v2, -v17, v140, v2
	v_fma_f32 v2, -v18, v141, v2
	v_fma_f32 v2, -v19, v142, v2
	v_fma_f32 v2, -v20, v143, v2
	v_fma_f32 v2, -v21, v144, v2
	v_fma_f32 v2, -v22, v145, v2
	v_fma_f32 v2, -v23, v150, v2
	v_fma_f32 v2, -v24, v151, v2
	v_fma_f32 v2, -v25, v152, v2
	v_fma_f32 v2, -v26, v153, v2
	v_fma_f32 v2, -v27, v154, v2
	v_fma_f32 v2, -v28, v155, v2
	v_fma_f32 v2, -v29, v156, v2
	v_fma_f32 v2, -v30, v157, v2
	v_fma_f32 v2, -v31, v162, v2
	v_fma_f32 v2, -v32, v163, v2
	v_fma_f32 v2, -v33, v164, v2
	v_fma_f32 v2, -v34, v165, v2
	v_fma_f32 v2, -v35, v170, v2
	v_fma_f32 v2, -v36, v171, v2
	v_fma_f32 v2, -v37, v172, v2
	v_fma_f32 v2, -v43, v173, v2
	v_fma_f32 v2, -v44, v178, v2
	v_fma_f32 v2, -v45, v179, v2
	v_fma_f32 v2, -v46, v180, v2
	v_fma_f32 v2, -v47, v181, v2
	v_fma_f32 v2, -v48, v186, v2
	v_fma_f32 v2, -v49, v187, v2
	v_fma_f32 v2, -v188, v50, v2
	ds_read_b128 v[54:57], v0 offset:29952
	ds_read_b128 v[102:105], v0 offset:29968
	ds_read_b128 v[114:117], v0 offset:29984
	ds_read_b128 v[122:125], v0 offset:30000
	ds_read_b128 v[126:129], v0 offset:30016
	ds_read_b128 v[130:133], v0 offset:30032
	ds_read_b128 v[134:137], v0 offset:30048
	ds_read_b128 v[146:149], v0 offset:30064
	ds_read_b128 v[158:161], v0 offset:30080
	ds_read_b128 v[166:169], v0 offset:30096
	ds_read_b128 v[182:185], v0 offset:30112
	ds_read_b128 v[190:193], v0 offset:30128
	v_fma_f32 v52, -v189, v51, v2
	s_waitcnt lgkmcnt(0)
	v_fma_f32 v2, -v41, v54, v100
	v_fma_f32 v2, -v5, v55, v2
	v_fma_f32 v2, -v6, v56, v2
	v_fma_f32 v2, -v8, v57, v2
	v_fma_f32 v2, -v4, v102, v2
	v_fma_f32 v2, -v7, v103, v2
	v_fma_f32 v2, -v9, v104, v2
	v_fma_f32 v2, -v10, v105, v2
	v_fma_f32 v2, -v11, v114, v2
	v_fma_f32 v2, -v12, v115, v2
	v_fma_f32 v2, -v13, v116, v2
	v_fma_f32 v2, -v14, v117, v2
	v_fma_f32 v2, -v15, v122, v2
	v_fma_f32 v2, -v16, v123, v2
	v_fma_f32 v2, -v17, v124, v2
	v_fma_f32 v2, -v18, v125, v2
	v_fma_f32 v2, -v19, v126, v2
	v_fma_f32 v2, -v20, v127, v2
	v_fma_f32 v2, -v21, v128, v2
	v_fma_f32 v2, -v22, v129, v2
	v_fma_f32 v2, -v23, v130, v2
	v_fma_f32 v2, -v24, v131, v2
	v_fma_f32 v2, -v25, v132, v2
	v_fma_f32 v2, -v26, v133, v2
	v_fma_f32 v2, -v27, v134, v2
	v_fma_f32 v2, -v28, v135, v2
	v_fma_f32 v2, -v29, v136, v2
	v_fma_f32 v2, -v30, v137, v2
	v_fma_f32 v2, -v31, v146, v2
	v_fma_f32 v2, -v32, v147, v2
	v_fma_f32 v2, -v33, v148, v2
	v_fma_f32 v2, -v34, v149, v2
	v_fma_f32 v2, -v35, v158, v2
	v_fma_f32 v2, -v36, v159, v2
	v_fma_f32 v2, -v37, v160, v2
	v_fma_f32 v2, -v43, v161, v2
	v_fma_f32 v2, -v44, v166, v2
	v_fma_f32 v2, -v45, v167, v2
	v_fma_f32 v2, -v46, v168, v2
	v_fma_f32 v2, -v47, v169, v2
	v_fma_f32 v2, -v48, v182, v2
	v_fma_f32 v2, -v49, v183, v2
	v_fma_f32 v2, -v50, v184, v2
	v_fma_f32 v2, -v185, v51, v2
	v_fma_f32 v2, -v190, v52, v2
	v_fma_f32 v2, -v100, v191, v2
	v_fma_f32 v2, -v99, v192, v2
	ds_read_b128 v[60:63], v0 offset:30208
	ds_read_b128 v[108:111], v0 offset:30224
	ds_read_b128 v[118:121], v0 offset:30240
	ds_read_b128 v[138:141], v0 offset:30256
	ds_read_b128 v[142:145], v0 offset:30272
	ds_read_b128 v[150:153], v0 offset:30288
	ds_read_b128 v[154:157], v0 offset:30304
	ds_read_b128 v[162:165], v0 offset:30320
	ds_read_b128 v[170:173], v0 offset:30336
	ds_read_b128 v[178:181], v0 offset:30352
	ds_read_b128 v[186:189], v0 offset:30368
	ds_read_b128 v[194:197], v0 offset:30384
	v_fma_f32 v53, -v97, v193, v2
	s_waitcnt lgkmcnt(0)
	v_fma_f32 v2, -v41, v60, v99
	v_fma_f32 v2, -v5, v61, v2
	v_fma_f32 v2, -v6, v62, v2
	v_fma_f32 v2, -v8, v63, v2
	v_fma_f32 v2, -v4, v108, v2
	v_fma_f32 v2, -v7, v109, v2
	v_fma_f32 v2, -v9, v110, v2
	v_fma_f32 v2, -v10, v111, v2
	v_fma_f32 v2, -v11, v118, v2
	v_fma_f32 v2, -v12, v119, v2
	v_fma_f32 v2, -v13, v120, v2
	v_fma_f32 v2, -v14, v121, v2
	v_fma_f32 v2, -v15, v138, v2
	v_fma_f32 v2, -v16, v139, v2
	v_fma_f32 v2, -v17, v140, v2
	v_fma_f32 v2, -v18, v141, v2
	v_fma_f32 v2, -v19, v142, v2
	v_fma_f32 v2, -v20, v143, v2
	v_fma_f32 v2, -v21, v144, v2
	v_fma_f32 v2, -v22, v145, v2
	v_fma_f32 v2, -v23, v150, v2
	v_fma_f32 v2, -v24, v151, v2
	v_fma_f32 v2, -v25, v152, v2
	v_fma_f32 v2, -v26, v153, v2
	v_fma_f32 v2, -v27, v154, v2
	v_fma_f32 v2, -v28, v155, v2
	v_fma_f32 v2, -v29, v156, v2
	v_fma_f32 v2, -v30, v157, v2
	v_fma_f32 v2, -v31, v162, v2
	v_fma_f32 v2, -v32, v163, v2
	v_fma_f32 v2, -v33, v164, v2
	v_fma_f32 v2, -v34, v165, v2
	v_fma_f32 v2, -v35, v170, v2
	v_fma_f32 v2, -v36, v171, v2
	v_fma_f32 v2, -v37, v172, v2
	v_fma_f32 v2, -v43, v173, v2
	v_fma_f32 v2, -v44, v178, v2
	v_fma_f32 v2, -v45, v179, v2
	v_fma_f32 v2, -v46, v180, v2
	v_fma_f32 v2, -v47, v181, v2
	v_fma_f32 v2, -v48, v186, v2
	v_fma_f32 v2, -v49, v187, v2
	v_fma_f32 v2, -v50, v188, v2
	v_fma_f32 v2, -v51, v189, v2
	v_fma_f32 v2, -v194, v52, v2
	v_fma_f32 v2, -v195, v53, v2
	v_fma_f32 v2, -v99, v196, v2
	ds_read_b128 v[102:105], v0 offset:30464
	ds_read_b128 v[112:115], v0 offset:30480
	ds_read_b128 v[122:125], v0 offset:30496
	ds_read_b128 v[126:129], v0 offset:30512
	ds_read_b128 v[130:133], v0 offset:30528
	ds_read_b128 v[134:137], v0 offset:30544
	ds_read_b128 v[146:149], v0 offset:30560
	ds_read_b128 v[158:161], v0 offset:30576
	ds_read_b128 v[166:169], v0 offset:30592
	ds_read_b128 v[182:185], v0 offset:30608
	ds_read_b128 v[190:193], v0 offset:30624
	ds_read_b128 v[228:231], v0 offset:30640
	v_fma_f32 v54, -v97, v197, v2
	s_waitcnt lgkmcnt(0)
	v_fma_f32 v2, -v41, v102, v97
	v_fma_f32 v2, -v5, v103, v2
	v_fma_f32 v2, -v6, v104, v2
	v_fma_f32 v2, -v8, v105, v2
	v_fma_f32 v2, -v4, v112, v2
	v_fma_f32 v2, -v7, v113, v2
	v_fma_f32 v2, -v9, v114, v2
	v_fma_f32 v2, -v10, v115, v2
	v_fma_f32 v2, -v11, v122, v2
	v_fma_f32 v2, -v12, v123, v2
	v_fma_f32 v2, -v13, v124, v2
	v_fma_f32 v2, -v14, v125, v2
	v_fma_f32 v2, -v15, v126, v2
	v_fma_f32 v2, -v16, v127, v2
	v_fma_f32 v2, -v17, v128, v2
	v_fma_f32 v2, -v18, v129, v2
	v_fma_f32 v2, -v19, v130, v2
	v_fma_f32 v2, -v20, v131, v2
	v_fma_f32 v2, -v21, v132, v2
	v_fma_f32 v2, -v22, v133, v2
	v_fma_f32 v2, -v23, v134, v2
	v_fma_f32 v2, -v24, v135, v2
	v_fma_f32 v2, -v25, v136, v2
	v_fma_f32 v2, -v26, v137, v2
	v_fma_f32 v2, -v27, v146, v2
	v_fma_f32 v2, -v28, v147, v2
	v_fma_f32 v2, -v29, v148, v2
	v_fma_f32 v2, -v30, v149, v2
	v_fma_f32 v2, -v31, v158, v2
	v_fma_f32 v2, -v32, v159, v2
	v_fma_f32 v2, -v33, v160, v2
	v_fma_f32 v2, -v34, v161, v2
	v_fma_f32 v2, -v35, v166, v2
	v_fma_f32 v2, -v36, v167, v2
	v_fma_f32 v2, -v37, v168, v2
	v_fma_f32 v2, -v43, v169, v2
	v_fma_f32 v2, -v44, v182, v2
	v_fma_f32 v2, -v45, v183, v2
	v_fma_f32 v2, -v46, v184, v2
	v_fma_f32 v2, -v47, v185, v2
	v_fma_f32 v2, -v48, v190, v2
	v_fma_f32 v2, -v49, v191, v2
	v_fma_f32 v2, -v50, v192, v2
	v_fma_f32 v2, -v51, v193, v2
	v_fma_f32 v2, -v52, v228, v2
	v_fma_f32 v2, -v229, v53, v2
	v_fma_f32 v2, -v230, v54, v2
	ds_read_b128 v[60:63], v0 offset:30720
	ds_read_b128 v[108:111], v0 offset:30736
	ds_read_b128 v[116:119], v0 offset:30752
	ds_read_b128 v[138:141], v0 offset:30768
	ds_read_b128 v[142:145], v0 offset:30784
	ds_read_b128 v[150:153], v0 offset:30800
	ds_read_b128 v[154:157], v0 offset:30816
	ds_read_b128 v[162:165], v0 offset:30832
	ds_read_b128 v[170:173], v0 offset:30848
	ds_read_b128 v[178:181], v0 offset:30864
	ds_read_b128 v[186:189], v0 offset:30880
	ds_read_b128 v[194:197], v0 offset:30896
	v_fma_f32 v55, -v97, v231, v2
	s_waitcnt lgkmcnt(0)
	v_fma_f32 v2, -v41, v60, v106
	v_fma_f32 v2, -v5, v61, v2
	v_fma_f32 v2, -v6, v62, v2
	v_fma_f32 v2, -v8, v63, v2
	v_fma_f32 v2, -v4, v108, v2
	v_fma_f32 v2, -v7, v109, v2
	v_fma_f32 v2, -v9, v110, v2
	v_fma_f32 v2, -v10, v111, v2
	v_fma_f32 v2, -v11, v116, v2
	v_fma_f32 v2, -v12, v117, v2
	v_fma_f32 v2, -v13, v118, v2
	v_fma_f32 v2, -v14, v119, v2
	v_fma_f32 v2, -v15, v138, v2
	v_fma_f32 v2, -v16, v139, v2
	v_fma_f32 v2, -v17, v140, v2
	v_fma_f32 v2, -v18, v141, v2
	v_fma_f32 v2, -v19, v142, v2
	v_fma_f32 v2, -v20, v143, v2
	v_fma_f32 v2, -v21, v144, v2
	v_fma_f32 v2, -v22, v145, v2
	v_fma_f32 v2, -v23, v150, v2
	v_fma_f32 v2, -v24, v151, v2
	v_fma_f32 v2, -v25, v152, v2
	v_fma_f32 v2, -v26, v153, v2
	v_fma_f32 v2, -v27, v154, v2
	v_fma_f32 v2, -v28, v155, v2
	v_fma_f32 v2, -v29, v156, v2
	v_fma_f32 v2, -v30, v157, v2
	v_fma_f32 v2, -v31, v162, v2
	v_fma_f32 v2, -v32, v163, v2
	v_fma_f32 v2, -v33, v164, v2
	v_fma_f32 v2, -v34, v165, v2
	v_fma_f32 v2, -v35, v170, v2
	v_fma_f32 v2, -v36, v171, v2
	v_fma_f32 v2, -v37, v172, v2
	v_fma_f32 v2, -v43, v173, v2
	v_fma_f32 v2, -v44, v178, v2
	v_fma_f32 v2, -v45, v179, v2
	v_fma_f32 v2, -v46, v180, v2
	v_fma_f32 v2, -v47, v181, v2
	v_fma_f32 v2, -v48, v186, v2
	v_fma_f32 v2, -v49, v187, v2
	v_fma_f32 v2, -v50, v188, v2
	v_fma_f32 v2, -v51, v189, v2
	v_fma_f32 v2, -v52, v194, v2
	v_fma_f32 v2, -v53, v195, v2
	v_fma_f32 v2, -v196, v54, v2
	ds_read_b128 v[96:99], v0 offset:30976
	ds_read_b128 v[102:105], v0 offset:30992
	ds_read_b128 v[112:115], v0 offset:31008
	ds_read_b128 v[120:123], v0 offset:31024
	ds_read_b128 v[124:127], v0 offset:31040
	ds_read_b128 v[128:131], v0 offset:31056
	ds_read_b128 v[132:135], v0 offset:31072
	ds_read_b128 v[146:149], v0 offset:31088
	ds_read_b128 v[158:161], v0 offset:31104
	ds_read_b128 v[166:169], v0 offset:31120
	ds_read_b128 v[182:185], v0 offset:31136
	ds_read_b128 v[190:193], v0 offset:31152
	ds_read_b128 v[228:231], v0 offset:31168
	v_fma_f32 v56, -v197, v55, v2
	s_waitcnt lgkmcnt(0)
	v_fma_f32 v2, -v41, v96, v92
	v_fma_f32 v2, -v5, v97, v2
	v_fma_f32 v2, -v6, v98, v2
	v_fma_f32 v2, -v8, v99, v2
	v_fma_f32 v2, -v4, v102, v2
	v_fma_f32 v2, -v7, v103, v2
	v_fma_f32 v2, -v9, v104, v2
	v_fma_f32 v2, -v10, v105, v2
	v_fma_f32 v2, -v11, v112, v2
	v_fma_f32 v2, -v12, v113, v2
	v_fma_f32 v2, -v13, v114, v2
	v_fma_f32 v2, -v14, v115, v2
	v_fma_f32 v2, -v15, v120, v2
	v_fma_f32 v2, -v16, v121, v2
	v_fma_f32 v2, -v17, v122, v2
	v_fma_f32 v2, -v18, v123, v2
	v_fma_f32 v2, -v19, v124, v2
	v_fma_f32 v2, -v20, v125, v2
	v_fma_f32 v2, -v21, v126, v2
	v_fma_f32 v2, -v22, v127, v2
	v_fma_f32 v2, -v23, v128, v2
	v_fma_f32 v2, -v24, v129, v2
	v_fma_f32 v2, -v25, v130, v2
	v_fma_f32 v2, -v26, v131, v2
	v_fma_f32 v2, -v27, v132, v2
	v_fma_f32 v2, -v28, v133, v2
	v_fma_f32 v2, -v29, v134, v2
	v_fma_f32 v2, -v30, v135, v2
	v_fma_f32 v2, -v31, v146, v2
	v_fma_f32 v2, -v32, v147, v2
	v_fma_f32 v2, -v33, v148, v2
	v_fma_f32 v2, -v34, v149, v2
	v_fma_f32 v2, -v35, v158, v2
	v_fma_f32 v2, -v36, v159, v2
	v_fma_f32 v2, -v37, v160, v2
	v_fma_f32 v2, -v43, v161, v2
	v_fma_f32 v2, -v44, v166, v2
	v_fma_f32 v2, -v45, v167, v2
	v_fma_f32 v2, -v46, v168, v2
	v_fma_f32 v2, -v47, v169, v2
	v_fma_f32 v2, -v48, v182, v2
	v_fma_f32 v2, -v49, v183, v2
	v_fma_f32 v2, -v50, v184, v2
	v_fma_f32 v2, -v51, v185, v2
	v_fma_f32 v2, -v52, v190, v2
	v_fma_f32 v2, -v53, v191, v2
	v_fma_f32 v2, -v54, v192, v2
	v_fma_f32 v2, -v193, v55, v2
	v_fma_f32 v2, -v228, v56, v2
	v_fma_f32 v2, -v92, v229, v2
	v_fma_f32 v2, -v91, v230, v2
	ds_read_b128 v[60:63], v0 offset:31232
	ds_read_b128 v[106:109], v0 offset:31248
	ds_read_b128 v[116:119], v0 offset:31264
	ds_read_b128 v[136:139], v0 offset:31280
	ds_read_b128 v[140:143], v0 offset:31296
	ds_read_b128 v[150:153], v0 offset:31312
	ds_read_b128 v[154:157], v0 offset:31328
	ds_read_b128 v[162:165], v0 offset:31344
	ds_read_b128 v[170:173], v0 offset:31360
	ds_read_b128 v[178:181], v0 offset:31376
	ds_read_b128 v[186:189], v0 offset:31392
	ds_read_b128 v[194:197], v0 offset:31408
	ds_read_b128 v[232:235], v0 offset:31424
	v_fma_f32 v57, -v88, v231, v2
	s_waitcnt lgkmcnt(0)
	v_fma_f32 v2, -v41, v60, v91
	v_fma_f32 v2, -v5, v61, v2
	v_fma_f32 v2, -v6, v62, v2
	v_fma_f32 v2, -v8, v63, v2
	v_fma_f32 v2, -v4, v106, v2
	v_fma_f32 v2, -v7, v107, v2
	v_fma_f32 v2, -v9, v108, v2
	v_fma_f32 v2, -v10, v109, v2
	v_fma_f32 v2, -v11, v116, v2
	v_fma_f32 v2, -v12, v117, v2
	v_fma_f32 v2, -v13, v118, v2
	v_fma_f32 v2, -v14, v119, v2
	v_fma_f32 v2, -v15, v136, v2
	v_fma_f32 v2, -v16, v137, v2
	v_fma_f32 v2, -v17, v138, v2
	v_fma_f32 v2, -v18, v139, v2
	v_fma_f32 v2, -v19, v140, v2
	v_fma_f32 v2, -v20, v141, v2
	v_fma_f32 v2, -v21, v142, v2
	v_fma_f32 v2, -v22, v143, v2
	v_fma_f32 v2, -v23, v150, v2
	v_fma_f32 v2, -v24, v151, v2
	v_fma_f32 v2, -v25, v152, v2
	v_fma_f32 v2, -v26, v153, v2
	v_fma_f32 v2, -v27, v154, v2
	v_fma_f32 v2, -v28, v155, v2
	v_fma_f32 v2, -v29, v156, v2
	v_fma_f32 v2, -v30, v157, v2
	v_fma_f32 v2, -v31, v162, v2
	v_fma_f32 v2, -v32, v163, v2
	v_fma_f32 v2, -v33, v164, v2
	v_fma_f32 v2, -v34, v165, v2
	v_fma_f32 v2, -v35, v170, v2
	v_fma_f32 v2, -v36, v171, v2
	v_fma_f32 v2, -v37, v172, v2
	v_fma_f32 v2, -v43, v173, v2
	v_fma_f32 v2, -v44, v178, v2
	v_fma_f32 v2, -v45, v179, v2
	v_fma_f32 v2, -v46, v180, v2
	v_fma_f32 v2, -v47, v181, v2
	v_fma_f32 v2, -v48, v186, v2
	v_fma_f32 v2, -v49, v187, v2
	v_fma_f32 v2, -v50, v188, v2
	v_fma_f32 v2, -v51, v189, v2
	v_fma_f32 v2, -v52, v194, v2
	v_fma_f32 v2, -v53, v195, v2
	v_fma_f32 v2, -v54, v196, v2
	v_fma_f32 v2, -v55, v197, v2
	v_fma_f32 v2, -v232, v56, v2
	v_fma_f32 v2, -v233, v57, v2
	v_fma_f32 v2, -v91, v234, v2
	ds_read_b128 v[96:99], v0 offset:31488
	ds_read_b128 v[102:105], v0 offset:31504
	ds_read_b128 v[110:113], v0 offset:31520
	ds_read_b128 v[120:123], v0 offset:31536
	ds_read_b128 v[124:127], v0 offset:31552
	ds_read_b128 v[128:131], v0 offset:31568
	ds_read_b128 v[132:135], v0 offset:31584
	ds_read_b128 v[144:147], v0 offset:31600
	ds_read_b128 v[158:161], v0 offset:31616
	ds_read_b128 v[166:169], v0 offset:31632
	ds_read_b128 v[182:185], v0 offset:31648
	ds_read_b128 v[190:193], v0 offset:31664
	ds_read_b128 v[228:231], v0 offset:31680
	v_fma_f32 v59, -v88, v235, v2
	s_waitcnt lgkmcnt(0)
	v_fma_f32 v2, -v41, v96, v88
	v_fma_f32 v2, -v5, v97, v2
	v_fma_f32 v2, -v6, v98, v2
	v_fma_f32 v2, -v8, v99, v2
	v_fma_f32 v2, -v4, v102, v2
	v_fma_f32 v2, -v7, v103, v2
	v_fma_f32 v2, -v9, v104, v2
	v_fma_f32 v2, -v10, v105, v2
	v_fma_f32 v2, -v11, v110, v2
	v_fma_f32 v2, -v12, v111, v2
	v_fma_f32 v2, -v13, v112, v2
	v_fma_f32 v2, -v14, v113, v2
	v_fma_f32 v2, -v15, v120, v2
	v_fma_f32 v2, -v16, v121, v2
	v_fma_f32 v2, -v17, v122, v2
	v_fma_f32 v2, -v18, v123, v2
	v_fma_f32 v2, -v19, v124, v2
	v_fma_f32 v2, -v20, v125, v2
	v_fma_f32 v2, -v21, v126, v2
	v_fma_f32 v2, -v22, v127, v2
	v_fma_f32 v2, -v23, v128, v2
	v_fma_f32 v2, -v24, v129, v2
	v_fma_f32 v2, -v25, v130, v2
	v_fma_f32 v2, -v26, v131, v2
	v_fma_f32 v2, -v27, v132, v2
	v_fma_f32 v2, -v28, v133, v2
	v_fma_f32 v2, -v29, v134, v2
	v_fma_f32 v2, -v30, v135, v2
	v_fma_f32 v2, -v31, v144, v2
	v_fma_f32 v2, -v32, v145, v2
	v_fma_f32 v2, -v33, v146, v2
	v_fma_f32 v2, -v34, v147, v2
	v_fma_f32 v2, -v35, v158, v2
	v_fma_f32 v2, -v36, v159, v2
	v_fma_f32 v2, -v37, v160, v2
	v_fma_f32 v2, -v43, v161, v2
	v_fma_f32 v2, -v44, v166, v2
	v_fma_f32 v2, -v45, v167, v2
	v_fma_f32 v2, -v46, v168, v2
	v_fma_f32 v2, -v47, v169, v2
	v_fma_f32 v2, -v48, v182, v2
	v_fma_f32 v2, -v49, v183, v2
	v_fma_f32 v2, -v50, v184, v2
	v_fma_f32 v2, -v51, v185, v2
	v_fma_f32 v2, -v52, v190, v2
	v_fma_f32 v2, -v53, v191, v2
	v_fma_f32 v2, -v54, v192, v2
	v_fma_f32 v2, -v55, v193, v2
	v_fma_f32 v2, -v56, v228, v2
	v_fma_f32 v2, -v229, v57, v2
	v_fma_f32 v2, -v230, v59, v2
	ds_read_b128 v[62:65], v0 offset:31744
	ds_read_b128 v[90:93], v0 offset:31760
	ds_read_b128 v[106:109], v0 offset:31776
	ds_read_b128 v[114:117], v0 offset:31792
	ds_read_b128 v[136:139], v0 offset:31808
	ds_read_b128 v[140:143], v0 offset:31824
	ds_read_b128 v[148:151], v0 offset:31840
	ds_read_b128 v[152:155], v0 offset:31856
	ds_read_b128 v[162:165], v0 offset:31872
	ds_read_b128 v[170:173], v0 offset:31888
	ds_read_b128 v[178:181], v0 offset:31904
	ds_read_b128 v[186:189], v0 offset:31920
	ds_read_b128 v[194:197], v0 offset:31936
	v_fma_f32 v60, -v88, v231, v2
	s_waitcnt lgkmcnt(0)
	v_fma_f32 v2, -v41, v62, v101
	v_fma_f32 v2, -v5, v63, v2
	v_fma_f32 v2, -v6, v64, v2
	v_fma_f32 v2, -v8, v65, v2
	v_fma_f32 v2, -v4, v90, v2
	v_fma_f32 v2, -v7, v91, v2
	v_fma_f32 v2, -v9, v92, v2
	v_fma_f32 v2, -v10, v93, v2
	v_fma_f32 v2, -v11, v106, v2
	v_fma_f32 v2, -v12, v107, v2
	v_fma_f32 v2, -v13, v108, v2
	v_fma_f32 v2, -v14, v109, v2
	v_fma_f32 v2, -v15, v114, v2
	v_fma_f32 v2, -v16, v115, v2
	v_fma_f32 v2, -v17, v116, v2
	v_fma_f32 v2, -v18, v117, v2
	v_fma_f32 v2, -v19, v136, v2
	v_fma_f32 v2, -v20, v137, v2
	v_fma_f32 v2, -v21, v138, v2
	v_fma_f32 v2, -v22, v139, v2
	v_fma_f32 v2, -v23, v140, v2
	v_fma_f32 v2, -v24, v141, v2
	v_fma_f32 v2, -v25, v142, v2
	v_fma_f32 v2, -v26, v143, v2
	v_fma_f32 v2, -v27, v148, v2
	v_fma_f32 v2, -v28, v149, v2
	v_fma_f32 v2, -v29, v150, v2
	v_fma_f32 v2, -v30, v151, v2
	v_fma_f32 v2, -v31, v152, v2
	v_fma_f32 v2, -v32, v153, v2
	v_fma_f32 v2, -v33, v154, v2
	v_fma_f32 v2, -v34, v155, v2
	v_fma_f32 v2, -v35, v162, v2
	v_fma_f32 v2, -v36, v163, v2
	v_fma_f32 v2, -v37, v164, v2
	v_fma_f32 v2, -v43, v165, v2
	v_fma_f32 v2, -v44, v170, v2
	v_fma_f32 v2, -v45, v171, v2
	v_fma_f32 v2, -v46, v172, v2
	v_fma_f32 v2, -v47, v173, v2
	v_fma_f32 v2, -v48, v178, v2
	v_fma_f32 v2, -v49, v179, v2
	v_fma_f32 v2, -v50, v180, v2
	v_fma_f32 v2, -v51, v181, v2
	v_fma_f32 v2, -v52, v186, v2
	v_fma_f32 v2, -v53, v187, v2
	v_fma_f32 v2, -v54, v188, v2
	v_fma_f32 v2, -v55, v189, v2
	v_fma_f32 v2, -v56, v194, v2
	v_fma_f32 v2, -v57, v195, v2
	v_fma_f32 v2, -v196, v59, v2
	ds_read_b128 v[96:99], v0 offset:32000
	ds_read_b128 v[102:105], v0 offset:32016
	ds_read_b128 v[110:113], v0 offset:32032
	ds_read_b128 v[118:121], v0 offset:32048
	ds_read_b128 v[122:125], v0 offset:32064
	ds_read_b128 v[126:129], v0 offset:32080
	ds_read_b128 v[130:133], v0 offset:32096
	ds_read_b128 v[144:147], v0 offset:32112
	ds_read_b128 v[156:159], v0 offset:32128
	ds_read_b128 v[166:169], v0 offset:32144
	ds_read_b128 v[182:185], v0 offset:32160
	ds_read_b128 v[190:193], v0 offset:32176
	ds_read_b128 v[228:231], v0 offset:32192
	ds_read_b128 v[232:235], v0 offset:32208
	v_fma_f32 v61, -v197, v60, v2
	s_waitcnt lgkmcnt(0)
	v_fma_f32 v2, -v41, v96, v84
	v_fma_f32 v2, -v5, v97, v2
	v_fma_f32 v2, -v6, v98, v2
	v_fma_f32 v2, -v8, v99, v2
	v_fma_f32 v2, -v4, v102, v2
	v_fma_f32 v2, -v7, v103, v2
	v_fma_f32 v2, -v9, v104, v2
	v_fma_f32 v2, -v10, v105, v2
	v_fma_f32 v2, -v11, v110, v2
	v_fma_f32 v2, -v12, v111, v2
	v_fma_f32 v2, -v13, v112, v2
	v_fma_f32 v2, -v14, v113, v2
	v_fma_f32 v2, -v15, v118, v2
	v_fma_f32 v2, -v16, v119, v2
	v_fma_f32 v2, -v17, v120, v2
	v_fma_f32 v2, -v18, v121, v2
	v_fma_f32 v2, -v19, v122, v2
	v_fma_f32 v2, -v20, v123, v2
	v_fma_f32 v2, -v21, v124, v2
	v_fma_f32 v2, -v22, v125, v2
	v_fma_f32 v2, -v23, v126, v2
	v_fma_f32 v2, -v24, v127, v2
	v_fma_f32 v2, -v25, v128, v2
	v_fma_f32 v2, -v26, v129, v2
	v_fma_f32 v2, -v27, v130, v2
	v_fma_f32 v2, -v28, v131, v2
	v_fma_f32 v2, -v29, v132, v2
	v_fma_f32 v2, -v30, v133, v2
	v_fma_f32 v2, -v31, v144, v2
	v_fma_f32 v2, -v32, v145, v2
	v_fma_f32 v2, -v33, v146, v2
	v_fma_f32 v2, -v34, v147, v2
	v_fma_f32 v2, -v35, v156, v2
	v_fma_f32 v2, -v36, v157, v2
	v_fma_f32 v2, -v37, v158, v2
	v_fma_f32 v2, -v43, v159, v2
	v_fma_f32 v2, -v44, v166, v2
	v_fma_f32 v2, -v45, v167, v2
	v_fma_f32 v2, -v46, v168, v2
	v_fma_f32 v2, -v47, v169, v2
	v_fma_f32 v2, -v48, v182, v2
	v_fma_f32 v2, -v49, v183, v2
	v_fma_f32 v2, -v50, v184, v2
	v_fma_f32 v2, -v51, v185, v2
	v_fma_f32 v2, -v52, v190, v2
	v_fma_f32 v2, -v53, v191, v2
	v_fma_f32 v2, -v54, v192, v2
	v_fma_f32 v2, -v55, v193, v2
	v_fma_f32 v2, -v56, v228, v2
	v_fma_f32 v2, -v57, v229, v2
	v_fma_f32 v2, -v59, v230, v2
	v_fma_f32 v2, -v231, v60, v2
	v_fma_f32 v2, -v232, v61, v2
	v_fma_f32 v2, -v84, v233, v2
	v_fma_f32 v2, -v83, v234, v2
	ds_read_b128 v[88:91], v0 offset:32256
	ds_read_b128 v[106:109], v0 offset:32272
	ds_read_b128 v[114:117], v0 offset:32288
	ds_read_b128 v[134:137], v0 offset:32304
	ds_read_b128 v[138:141], v0 offset:32320
	ds_read_b128 v[148:151], v0 offset:32336
	ds_read_b128 v[152:155], v0 offset:32352
	ds_read_b128 v[160:163], v0 offset:32368
	ds_read_b128 v[170:173], v0 offset:32384
	ds_read_b128 v[178:181], v0 offset:32400
	ds_read_b128 v[186:189], v0 offset:32416
	ds_read_b128 v[194:197], v0 offset:32432
	ds_read_b128 v[236:239], v0 offset:32448
	ds_read_b128 v[240:243], v0 offset:32464
	v_fma_f32 v62, -v81, v235, v2
	s_waitcnt lgkmcnt(0)
	v_fma_f32 v2, -v41, v88, v83
	v_fma_f32 v2, -v5, v89, v2
	v_fma_f32 v2, -v6, v90, v2
	v_fma_f32 v2, -v8, v91, v2
	v_fma_f32 v2, -v4, v106, v2
	v_fma_f32 v2, -v7, v107, v2
	v_fma_f32 v2, -v9, v108, v2
	v_fma_f32 v2, -v10, v109, v2
	v_fma_f32 v2, -v11, v114, v2
	v_fma_f32 v2, -v12, v115, v2
	v_fma_f32 v2, -v13, v116, v2
	v_fma_f32 v2, -v14, v117, v2
	v_fma_f32 v2, -v15, v134, v2
	v_fma_f32 v2, -v16, v135, v2
	v_fma_f32 v2, -v17, v136, v2
	v_fma_f32 v2, -v18, v137, v2
	v_fma_f32 v2, -v19, v138, v2
	v_fma_f32 v2, -v20, v139, v2
	v_fma_f32 v2, -v21, v140, v2
	v_fma_f32 v2, -v22, v141, v2
	v_fma_f32 v2, -v23, v148, v2
	v_fma_f32 v2, -v24, v149, v2
	v_fma_f32 v2, -v25, v150, v2
	v_fma_f32 v2, -v26, v151, v2
	v_fma_f32 v2, -v27, v152, v2
	v_fma_f32 v2, -v28, v153, v2
	v_fma_f32 v2, -v29, v154, v2
	v_fma_f32 v2, -v30, v155, v2
	v_fma_f32 v2, -v31, v160, v2
	v_fma_f32 v2, -v32, v161, v2
	v_fma_f32 v2, -v33, v162, v2
	v_fma_f32 v2, -v34, v163, v2
	v_fma_f32 v2, -v35, v170, v2
	v_fma_f32 v2, -v36, v171, v2
	v_fma_f32 v2, -v37, v172, v2
	v_fma_f32 v2, -v43, v173, v2
	v_fma_f32 v2, -v44, v178, v2
	v_fma_f32 v2, -v45, v179, v2
	v_fma_f32 v2, -v46, v180, v2
	v_fma_f32 v2, -v47, v181, v2
	v_fma_f32 v2, -v48, v186, v2
	v_fma_f32 v2, -v49, v187, v2
	v_fma_f32 v2, -v50, v188, v2
	v_fma_f32 v2, -v51, v189, v2
	v_fma_f32 v2, -v52, v194, v2
	v_fma_f32 v2, -v53, v195, v2
	v_fma_f32 v2, -v54, v196, v2
	v_fma_f32 v2, -v55, v197, v2
	v_fma_f32 v2, -v56, v236, v2
	v_fma_f32 v2, -v57, v237, v2
	v_fma_f32 v2, -v59, v238, v2
	v_fma_f32 v2, -v60, v239, v2
	v_fma_f32 v2, -v240, v61, v2
	v_fma_f32 v2, -v241, v62, v2
	v_fma_f32 v2, -v83, v242, v2
	ds_read_b128 v[96:99], v0 offset:32512
	ds_read_b128 v[100:103], v0 offset:32528
	ds_read_b128 v[110:113], v0 offset:32544
	ds_read_b128 v[118:121], v0 offset:32560
	ds_read_b128 v[122:125], v0 offset:32576
	ds_read_b128 v[126:129], v0 offset:32592
	ds_read_b128 v[130:133], v0 offset:32608
	ds_read_b128 v[142:145], v0 offset:32624
	ds_read_b128 v[156:159], v0 offset:32640
	ds_read_b128 v[164:167], v0 offset:32656
	ds_read_b128 v[182:185], v0 offset:32672
	ds_read_b128 v[190:193], v0 offset:32688
	ds_read_b128 v[228:231], v0 offset:32704
	ds_read_b128 v[232:235], v0 offset:32720
	v_fma_f32 v63, -v81, v243, v2
	s_waitcnt lgkmcnt(0)
	v_fma_f32 v2, -v41, v96, v81
	v_fma_f32 v2, -v5, v97, v2
	v_fma_f32 v2, -v6, v98, v2
	v_fma_f32 v2, -v8, v99, v2
	v_fma_f32 v2, -v4, v100, v2
	v_fma_f32 v2, -v7, v101, v2
	v_fma_f32 v2, -v9, v102, v2
	v_fma_f32 v2, -v10, v103, v2
	v_fma_f32 v2, -v11, v110, v2
	v_fma_f32 v2, -v12, v111, v2
	v_fma_f32 v2, -v13, v112, v2
	v_fma_f32 v2, -v14, v113, v2
	v_fma_f32 v2, -v15, v118, v2
	v_fma_f32 v2, -v16, v119, v2
	v_fma_f32 v2, -v17, v120, v2
	v_fma_f32 v2, -v18, v121, v2
	v_fma_f32 v2, -v19, v122, v2
	v_fma_f32 v2, -v20, v123, v2
	v_fma_f32 v2, -v21, v124, v2
	v_fma_f32 v2, -v22, v125, v2
	v_fma_f32 v2, -v23, v126, v2
	v_fma_f32 v2, -v24, v127, v2
	v_fma_f32 v2, -v25, v128, v2
	v_fma_f32 v2, -v26, v129, v2
	v_fma_f32 v2, -v27, v130, v2
	v_fma_f32 v2, -v28, v131, v2
	v_fma_f32 v2, -v29, v132, v2
	v_fma_f32 v2, -v30, v133, v2
	v_fma_f32 v2, -v31, v142, v2
	v_fma_f32 v2, -v32, v143, v2
	v_fma_f32 v2, -v33, v144, v2
	v_fma_f32 v2, -v34, v145, v2
	v_fma_f32 v2, -v35, v156, v2
	v_fma_f32 v2, -v36, v157, v2
	v_fma_f32 v2, -v37, v158, v2
	v_fma_f32 v2, -v43, v159, v2
	v_fma_f32 v2, -v44, v164, v2
	v_fma_f32 v2, -v45, v165, v2
	v_fma_f32 v2, -v46, v166, v2
	v_fma_f32 v2, -v47, v167, v2
	v_fma_f32 v2, -v48, v182, v2
	v_fma_f32 v2, -v49, v183, v2
	v_fma_f32 v2, -v50, v184, v2
	v_fma_f32 v2, -v51, v185, v2
	v_fma_f32 v2, -v52, v190, v2
	v_fma_f32 v2, -v53, v191, v2
	v_fma_f32 v2, -v54, v192, v2
	v_fma_f32 v2, -v55, v193, v2
	v_fma_f32 v2, -v56, v228, v2
	v_fma_f32 v2, -v57, v229, v2
	v_fma_f32 v2, -v59, v230, v2
	v_fma_f32 v2, -v60, v231, v2
	v_fma_f32 v2, -v61, v232, v2
	v_fma_f32 v2, -v233, v62, v2
	v_fma_f32 v2, -v234, v63, v2
	ds_read_b128 v[82:85], v0 offset:32768
	ds_read_b128 v[88:91], v0 offset:32784
	ds_read_b128 v[104:107], v0 offset:32800
	ds_read_b128 v[114:117], v0 offset:32816
	ds_read_b128 v[134:137], v0 offset:32832
	ds_read_b128 v[138:141], v0 offset:32848
	ds_read_b128 v[146:149], v0 offset:32864
	ds_read_b128 v[150:153], v0 offset:32880
	ds_read_b128 v[160:163], v0 offset:32896
	ds_read_b128 v[168:171], v0 offset:32912
	ds_read_b128 v[178:181], v0 offset:32928
	ds_read_b128 v[186:189], v0 offset:32944
	ds_read_b128 v[194:197], v0 offset:32960
	ds_read_b128 v[236:239], v0 offset:32976
	v_fma_f32 v64, -v81, v235, v2
	s_waitcnt lgkmcnt(0)
	v_fma_f32 v2, -v41, v82, v86
	v_fma_f32 v2, -v5, v83, v2
	v_fma_f32 v2, -v6, v84, v2
	v_fma_f32 v2, -v8, v85, v2
	v_fma_f32 v2, -v4, v88, v2
	v_fma_f32 v2, -v7, v89, v2
	v_fma_f32 v2, -v9, v90, v2
	v_fma_f32 v2, -v10, v91, v2
	v_fma_f32 v2, -v11, v104, v2
	v_fma_f32 v2, -v12, v105, v2
	v_fma_f32 v2, -v13, v106, v2
	v_fma_f32 v2, -v14, v107, v2
	v_fma_f32 v2, -v15, v114, v2
	v_fma_f32 v2, -v16, v115, v2
	v_fma_f32 v2, -v17, v116, v2
	v_fma_f32 v2, -v18, v117, v2
	v_fma_f32 v2, -v19, v134, v2
	v_fma_f32 v2, -v20, v135, v2
	v_fma_f32 v2, -v21, v136, v2
	v_fma_f32 v2, -v22, v137, v2
	v_fma_f32 v2, -v23, v138, v2
	v_fma_f32 v2, -v24, v139, v2
	v_fma_f32 v2, -v25, v140, v2
	v_fma_f32 v2, -v26, v141, v2
	v_fma_f32 v2, -v27, v146, v2
	v_fma_f32 v2, -v28, v147, v2
	v_fma_f32 v2, -v29, v148, v2
	v_fma_f32 v2, -v30, v149, v2
	v_fma_f32 v2, -v31, v150, v2
	v_fma_f32 v2, -v32, v151, v2
	v_fma_f32 v2, -v33, v152, v2
	v_fma_f32 v2, -v34, v153, v2
	v_fma_f32 v2, -v35, v160, v2
	v_fma_f32 v2, -v36, v161, v2
	v_fma_f32 v2, -v37, v162, v2
	v_fma_f32 v2, -v43, v163, v2
	v_fma_f32 v2, -v44, v168, v2
	v_fma_f32 v2, -v45, v169, v2
	v_fma_f32 v2, -v46, v170, v2
	v_fma_f32 v2, -v47, v171, v2
	v_fma_f32 v2, -v48, v178, v2
	v_fma_f32 v2, -v49, v179, v2
	v_fma_f32 v2, -v50, v180, v2
	v_fma_f32 v2, -v51, v181, v2
	v_fma_f32 v2, -v52, v186, v2
	v_fma_f32 v2, -v53, v187, v2
	v_fma_f32 v2, -v54, v188, v2
	v_fma_f32 v2, -v55, v189, v2
	v_fma_f32 v2, -v56, v194, v2
	v_fma_f32 v2, -v57, v195, v2
	v_fma_f32 v2, -v59, v196, v2
	v_fma_f32 v2, -v60, v197, v2
	v_fma_f32 v2, -v61, v236, v2
	v_fma_f32 v2, -v62, v237, v2
	v_fma_f32 v2, -v238, v63, v2
	ds_read_b128 v[78:81], v0 offset:33024
	ds_read_b128 v[96:99], v0 offset:33040
	ds_read_b128 v[100:103], v0 offset:33056
	ds_read_b128 v[108:111], v0 offset:33072
	ds_read_b128 v[118:121], v0 offset:33088
	ds_read_b128 v[122:125], v0 offset:33104
	ds_read_b128 v[126:129], v0 offset:33120
	ds_read_b128 v[130:133], v0 offset:33136
	ds_read_b128 v[142:145], v0 offset:33152
	ds_read_b128 v[154:157], v0 offset:33168
	ds_read_b128 v[164:167], v0 offset:33184
	ds_read_b128 v[182:185], v0 offset:33200
	ds_read_b128 v[190:193], v0 offset:33216
	ds_read_b128 v[228:231], v0 offset:33232
	ds_read_b128 v[232:235], v0 offset:33248
	v_fma_f32 v65, -v239, v64, v2
	s_waitcnt lgkmcnt(0)
	v_fma_f32 v2, -v41, v78, v77
	v_fma_f32 v2, -v5, v79, v2
	v_fma_f32 v2, -v6, v80, v2
	v_fma_f32 v2, -v8, v81, v2
	v_fma_f32 v2, -v4, v96, v2
	v_fma_f32 v2, -v7, v97, v2
	v_fma_f32 v2, -v9, v98, v2
	v_fma_f32 v2, -v10, v99, v2
	v_fma_f32 v2, -v11, v100, v2
	v_fma_f32 v2, -v12, v101, v2
	v_fma_f32 v2, -v13, v102, v2
	v_fma_f32 v2, -v14, v103, v2
	v_fma_f32 v2, -v15, v108, v2
	v_fma_f32 v2, -v16, v109, v2
	v_fma_f32 v2, -v17, v110, v2
	v_fma_f32 v2, -v18, v111, v2
	v_fma_f32 v2, -v19, v118, v2
	v_fma_f32 v2, -v20, v119, v2
	v_fma_f32 v2, -v21, v120, v2
	v_fma_f32 v2, -v22, v121, v2
	v_fma_f32 v2, -v23, v122, v2
	v_fma_f32 v2, -v24, v123, v2
	v_fma_f32 v2, -v25, v124, v2
	v_fma_f32 v2, -v26, v125, v2
	v_fma_f32 v2, -v27, v126, v2
	v_fma_f32 v2, -v28, v127, v2
	v_fma_f32 v2, -v29, v128, v2
	v_fma_f32 v2, -v30, v129, v2
	v_fma_f32 v2, -v31, v130, v2
	v_fma_f32 v2, -v32, v131, v2
	v_fma_f32 v2, -v33, v132, v2
	v_fma_f32 v2, -v34, v133, v2
	v_fma_f32 v2, -v35, v142, v2
	v_fma_f32 v2, -v36, v143, v2
	v_fma_f32 v2, -v37, v144, v2
	v_fma_f32 v2, -v43, v145, v2
	v_fma_f32 v2, -v44, v154, v2
	v_fma_f32 v2, -v45, v155, v2
	v_fma_f32 v2, -v46, v156, v2
	v_fma_f32 v2, -v47, v157, v2
	v_fma_f32 v2, -v48, v164, v2
	v_fma_f32 v2, -v49, v165, v2
	v_fma_f32 v2, -v50, v166, v2
	v_fma_f32 v2, -v51, v167, v2
	v_fma_f32 v2, -v52, v182, v2
	v_fma_f32 v2, -v53, v183, v2
	v_fma_f32 v2, -v54, v184, v2
	v_fma_f32 v2, -v55, v185, v2
	v_fma_f32 v2, -v56, v190, v2
	v_fma_f32 v2, -v57, v191, v2
	v_fma_f32 v2, -v59, v192, v2
	v_fma_f32 v2, -v60, v193, v2
	v_fma_f32 v2, -v61, v228, v2
	v_fma_f32 v2, -v62, v229, v2
	v_fma_f32 v2, -v63, v230, v2
	v_fma_f32 v2, -v231, v64, v2
	v_fma_f32 v2, -v232, v65, v2
	v_fma_f32 v2, -v77, v233, v2
	v_fma_f32 v2, -v75, v234, v2
	ds_read_b128 v[82:85], v0 offset:33280
	ds_read_b128 v[86:89], v0 offset:33296
	ds_read_b128 v[90:93], v0 offset:33312
	ds_read_b128 v[104:107], v0 offset:33328
	ds_read_b128 v[112:115], v0 offset:33344
	ds_read_b128 v[134:137], v0 offset:33360
	ds_read_b128 v[138:141], v0 offset:33376
	ds_read_b128 v[146:149], v0 offset:33392
	ds_read_b128 v[150:153], v0 offset:33408
	ds_read_b128 v[158:161], v0 offset:33424
	ds_read_b128 v[168:171], v0 offset:33440
	ds_read_b128 v[178:181], v0 offset:33456
	ds_read_b128 v[186:189], v0 offset:33472
	ds_read_b128 v[194:197], v0 offset:33488
	ds_read_b128 v[236:239], v0 offset:33504
	v_fma_f32 v67, -v73, v235, v2
	s_waitcnt lgkmcnt(0)
	v_fma_f32 v2, -v41, v82, v75
	v_fma_f32 v2, -v5, v83, v2
	v_fma_f32 v2, -v6, v84, v2
	v_fma_f32 v2, -v8, v85, v2
	v_fma_f32 v2, -v4, v86, v2
	v_fma_f32 v2, -v7, v87, v2
	v_fma_f32 v2, -v9, v88, v2
	v_fma_f32 v2, -v10, v89, v2
	v_fma_f32 v2, -v11, v90, v2
	v_fma_f32 v2, -v12, v91, v2
	v_fma_f32 v2, -v13, v92, v2
	v_fma_f32 v2, -v14, v93, v2
	v_fma_f32 v2, -v15, v104, v2
	v_fma_f32 v2, -v16, v105, v2
	v_fma_f32 v2, -v17, v106, v2
	v_fma_f32 v2, -v18, v107, v2
	v_fma_f32 v2, -v19, v112, v2
	v_fma_f32 v2, -v20, v113, v2
	v_fma_f32 v2, -v21, v114, v2
	v_fma_f32 v2, -v22, v115, v2
	v_fma_f32 v2, -v23, v134, v2
	v_fma_f32 v2, -v24, v135, v2
	v_fma_f32 v2, -v25, v136, v2
	v_fma_f32 v2, -v26, v137, v2
	v_fma_f32 v2, -v27, v138, v2
	v_fma_f32 v2, -v28, v139, v2
	v_fma_f32 v2, -v29, v140, v2
	v_fma_f32 v2, -v30, v141, v2
	v_fma_f32 v2, -v31, v146, v2
	v_fma_f32 v2, -v32, v147, v2
	v_fma_f32 v2, -v33, v148, v2
	v_fma_f32 v2, -v34, v149, v2
	v_fma_f32 v2, -v35, v150, v2
	v_fma_f32 v2, -v36, v151, v2
	v_fma_f32 v2, -v37, v152, v2
	v_fma_f32 v2, -v43, v153, v2
	v_fma_f32 v2, -v44, v158, v2
	v_fma_f32 v2, -v45, v159, v2
	v_fma_f32 v2, -v46, v160, v2
	v_fma_f32 v2, -v47, v161, v2
	v_fma_f32 v2, -v48, v168, v2
	v_fma_f32 v2, -v49, v169, v2
	v_fma_f32 v2, -v50, v170, v2
	v_fma_f32 v2, -v51, v171, v2
	v_fma_f32 v2, -v52, v178, v2
	v_fma_f32 v2, -v53, v179, v2
	v_fma_f32 v2, -v54, v180, v2
	v_fma_f32 v2, -v55, v181, v2
	v_fma_f32 v2, -v56, v186, v2
	v_fma_f32 v2, -v57, v187, v2
	v_fma_f32 v2, -v59, v188, v2
	v_fma_f32 v2, -v60, v189, v2
	v_fma_f32 v2, -v61, v194, v2
	v_fma_f32 v2, -v62, v195, v2
	v_fma_f32 v2, -v63, v196, v2
	v_fma_f32 v2, -v64, v197, v2
	v_fma_f32 v2, -v236, v65, v2
	v_fma_f32 v2, -v237, v67, v2
	v_fma_f32 v2, -v75, v238, v2
	ds_read_b128 v[78:81], v0 offset:33536
	ds_read_b128 v[96:99], v0 offset:33552
	ds_read_b128 v[100:103], v0 offset:33568
	ds_read_b128 v[108:111], v0 offset:33584
	ds_read_b128 v[116:119], v0 offset:33600
	ds_read_b128 v[120:123], v0 offset:33616
	ds_read_b128 v[124:127], v0 offset:33632
	ds_read_b128 v[128:131], v0 offset:33648
	ds_read_b128 v[142:145], v0 offset:33664
	ds_read_b128 v[154:157], v0 offset:33680
	ds_read_b128 v[162:165], v0 offset:33696
	ds_read_b128 v[182:185], v0 offset:33712
	ds_read_b128 v[190:193], v0 offset:33728
	ds_read_b128 v[228:231], v0 offset:33744
	ds_read_b128 v[232:235], v0 offset:33760
	v_fma_f32 v70, -v73, v239, v2
	s_waitcnt lgkmcnt(0)
	v_fma_f32 v2, -v41, v78, v73
	v_fma_f32 v2, -v5, v79, v2
	v_fma_f32 v2, -v6, v80, v2
	v_fma_f32 v2, -v8, v81, v2
	v_fma_f32 v2, -v4, v96, v2
	v_fma_f32 v2, -v7, v97, v2
	v_fma_f32 v2, -v9, v98, v2
	v_fma_f32 v2, -v10, v99, v2
	v_fma_f32 v2, -v11, v100, v2
	v_fma_f32 v2, -v12, v101, v2
	v_fma_f32 v2, -v13, v102, v2
	v_fma_f32 v2, -v14, v103, v2
	v_fma_f32 v2, -v15, v108, v2
	v_fma_f32 v2, -v16, v109, v2
	v_fma_f32 v2, -v17, v110, v2
	v_fma_f32 v2, -v18, v111, v2
	v_fma_f32 v2, -v19, v116, v2
	v_fma_f32 v2, -v20, v117, v2
	v_fma_f32 v2, -v21, v118, v2
	v_fma_f32 v2, -v22, v119, v2
	v_fma_f32 v2, -v23, v120, v2
	v_fma_f32 v2, -v24, v121, v2
	v_fma_f32 v2, -v25, v122, v2
	v_fma_f32 v2, -v26, v123, v2
	v_fma_f32 v2, -v27, v124, v2
	v_fma_f32 v2, -v28, v125, v2
	v_fma_f32 v2, -v29, v126, v2
	v_fma_f32 v2, -v30, v127, v2
	v_fma_f32 v2, -v31, v128, v2
	v_fma_f32 v2, -v32, v129, v2
	v_fma_f32 v2, -v33, v130, v2
	v_fma_f32 v2, -v34, v131, v2
	v_fma_f32 v2, -v35, v142, v2
	v_fma_f32 v2, -v36, v143, v2
	v_fma_f32 v2, -v37, v144, v2
	v_fma_f32 v2, -v43, v145, v2
	v_fma_f32 v2, -v44, v154, v2
	v_fma_f32 v2, -v45, v155, v2
	v_fma_f32 v2, -v46, v156, v2
	v_fma_f32 v2, -v47, v157, v2
	v_fma_f32 v2, -v48, v162, v2
	v_fma_f32 v2, -v49, v163, v2
	v_fma_f32 v2, -v50, v164, v2
	v_fma_f32 v2, -v51, v165, v2
	v_fma_f32 v2, -v52, v182, v2
	v_fma_f32 v2, -v53, v183, v2
	v_fma_f32 v2, -v54, v184, v2
	v_fma_f32 v2, -v55, v185, v2
	v_fma_f32 v2, -v56, v190, v2
	v_fma_f32 v2, -v57, v191, v2
	v_fma_f32 v2, -v59, v192, v2
	v_fma_f32 v2, -v60, v193, v2
	v_fma_f32 v2, -v61, v228, v2
	v_fma_f32 v2, -v62, v229, v2
	v_fma_f32 v2, -v63, v230, v2
	v_fma_f32 v2, -v64, v231, v2
	v_fma_f32 v2, -v65, v232, v2
	v_fma_f32 v2, -v233, v67, v2
	v_fma_f32 v2, -v234, v70, v2
	ds_read_b128 v[82:85], v0 offset:33792
	ds_read_b128 v[86:89], v0 offset:33808
	ds_read_b128 v[90:93], v0 offset:33824
	ds_read_b128 v[104:107], v0 offset:33840
	ds_read_b128 v[112:115], v0 offset:33856
	ds_read_b128 v[132:135], v0 offset:33872
	ds_read_b128 v[136:139], v0 offset:33888
	ds_read_b128 v[146:149], v0 offset:33904
	ds_read_b128 v[150:153], v0 offset:33920
	ds_read_b128 v[158:161], v0 offset:33936
	ds_read_b128 v[166:169], v0 offset:33952
	ds_read_b128 v[170:173], v0 offset:33968
	ds_read_b128 v[178:181], v0 offset:33984
	ds_read_b128 v[186:189], v0 offset:34000
	ds_read_b128 v[194:197], v0 offset:34016
	v_fma_f32 v71, -v73, v235, v2
	s_waitcnt lgkmcnt(0)
	v_fma_f32 v2, -v41, v82, v76
	v_fma_f32 v2, -v5, v83, v2
	v_fma_f32 v2, -v6, v84, v2
	v_fma_f32 v2, -v8, v85, v2
	v_fma_f32 v2, -v4, v86, v2
	v_fma_f32 v2, -v7, v87, v2
	v_fma_f32 v2, -v9, v88, v2
	v_fma_f32 v2, -v10, v89, v2
	v_fma_f32 v2, -v11, v90, v2
	v_fma_f32 v2, -v12, v91, v2
	v_fma_f32 v2, -v13, v92, v2
	v_fma_f32 v2, -v14, v93, v2
	v_fma_f32 v2, -v15, v104, v2
	v_fma_f32 v2, -v16, v105, v2
	v_fma_f32 v2, -v17, v106, v2
	v_fma_f32 v2, -v18, v107, v2
	v_fma_f32 v2, -v19, v112, v2
	v_fma_f32 v2, -v20, v113, v2
	v_fma_f32 v2, -v21, v114, v2
	v_fma_f32 v2, -v22, v115, v2
	v_fma_f32 v2, -v23, v132, v2
	v_fma_f32 v2, -v24, v133, v2
	v_fma_f32 v2, -v25, v134, v2
	v_fma_f32 v2, -v26, v135, v2
	v_fma_f32 v2, -v27, v136, v2
	v_fma_f32 v2, -v28, v137, v2
	v_fma_f32 v2, -v29, v138, v2
	v_fma_f32 v2, -v30, v139, v2
	v_fma_f32 v2, -v31, v146, v2
	v_fma_f32 v2, -v32, v147, v2
	v_fma_f32 v2, -v33, v148, v2
	v_fma_f32 v2, -v34, v149, v2
	v_fma_f32 v2, -v35, v150, v2
	v_fma_f32 v2, -v36, v151, v2
	v_fma_f32 v2, -v37, v152, v2
	v_fma_f32 v2, -v43, v153, v2
	v_fma_f32 v2, -v44, v158, v2
	v_fma_f32 v2, -v45, v159, v2
	v_fma_f32 v2, -v46, v160, v2
	v_fma_f32 v2, -v47, v161, v2
	v_fma_f32 v2, -v48, v166, v2
	v_fma_f32 v2, -v49, v167, v2
	v_fma_f32 v2, -v50, v168, v2
	v_fma_f32 v2, -v51, v169, v2
	v_fma_f32 v2, -v52, v170, v2
	v_fma_f32 v2, -v53, v171, v2
	v_fma_f32 v2, -v54, v172, v2
	v_fma_f32 v2, -v55, v173, v2
	v_fma_f32 v2, -v56, v178, v2
	v_fma_f32 v2, -v57, v179, v2
	v_fma_f32 v2, -v59, v180, v2
	v_fma_f32 v2, -v60, v181, v2
	v_fma_f32 v2, -v61, v186, v2
	v_fma_f32 v2, -v62, v187, v2
	v_fma_f32 v2, -v63, v188, v2
	v_fma_f32 v2, -v64, v189, v2
	v_fma_f32 v2, -v65, v194, v2
	v_fma_f32 v2, -v67, v195, v2
	v_fma_f32 v2, -v196, v70, v2
	ds_read_b128 v[78:81], v0 offset:34048
	ds_read_b128 v[96:99], v0 offset:34064
	ds_read_b128 v[100:103], v0 offset:34080
	ds_read_b128 v[108:111], v0 offset:34096
	ds_read_b128 v[116:119], v0 offset:34112
	ds_read_b128 v[120:123], v0 offset:34128
	ds_read_b128 v[124:127], v0 offset:34144
	ds_read_b128 v[128:131], v0 offset:34160
	ds_read_b128 v[140:143], v0 offset:34176
	ds_read_b128 v[154:157], v0 offset:34192
	ds_read_b128 v[162:165], v0 offset:34208
	ds_read_b128 v[182:185], v0 offset:34224
	ds_read_b128 v[190:193], v0 offset:34240
	ds_read_b128 v[228:231], v0 offset:34256
	ds_read_b128 v[232:235], v0 offset:34272
	ds_read_b128 v[236:239], v0 offset:34288
	v_fma_f32 v72, -v197, v71, v2
	s_waitcnt lgkmcnt(0)
	v_fma_f32 v2, -v41, v78, v69
	v_fma_f32 v2, -v5, v79, v2
	v_fma_f32 v2, -v6, v80, v2
	v_fma_f32 v2, -v8, v81, v2
	v_fma_f32 v2, -v4, v96, v2
	v_fma_f32 v2, -v7, v97, v2
	v_fma_f32 v2, -v9, v98, v2
	v_fma_f32 v2, -v10, v99, v2
	v_fma_f32 v2, -v11, v100, v2
	v_fma_f32 v2, -v12, v101, v2
	v_fma_f32 v2, -v13, v102, v2
	v_fma_f32 v2, -v14, v103, v2
	v_fma_f32 v2, -v15, v108, v2
	v_fma_f32 v2, -v16, v109, v2
	v_fma_f32 v2, -v17, v110, v2
	v_fma_f32 v2, -v18, v111, v2
	v_fma_f32 v2, -v19, v116, v2
	v_fma_f32 v2, -v20, v117, v2
	v_fma_f32 v2, -v21, v118, v2
	v_fma_f32 v2, -v22, v119, v2
	v_fma_f32 v2, -v23, v120, v2
	v_fma_f32 v2, -v24, v121, v2
	v_fma_f32 v2, -v25, v122, v2
	v_fma_f32 v2, -v26, v123, v2
	v_fma_f32 v2, -v27, v124, v2
	v_fma_f32 v2, -v28, v125, v2
	v_fma_f32 v2, -v29, v126, v2
	v_fma_f32 v2, -v30, v127, v2
	v_fma_f32 v2, -v31, v128, v2
	v_fma_f32 v2, -v32, v129, v2
	v_fma_f32 v2, -v33, v130, v2
	v_fma_f32 v2, -v34, v131, v2
	v_fma_f32 v2, -v35, v140, v2
	v_fma_f32 v2, -v36, v141, v2
	v_fma_f32 v2, -v37, v142, v2
	v_fma_f32 v2, -v43, v143, v2
	v_fma_f32 v2, -v44, v154, v2
	v_fma_f32 v2, -v45, v155, v2
	v_fma_f32 v2, -v46, v156, v2
	v_fma_f32 v2, -v47, v157, v2
	v_fma_f32 v2, -v48, v162, v2
	v_fma_f32 v2, -v49, v163, v2
	v_fma_f32 v2, -v50, v164, v2
	v_fma_f32 v2, -v51, v165, v2
	v_fma_f32 v2, -v52, v182, v2
	v_fma_f32 v2, -v53, v183, v2
	v_fma_f32 v2, -v54, v184, v2
	v_fma_f32 v2, -v55, v185, v2
	v_fma_f32 v2, -v56, v190, v2
	v_fma_f32 v2, -v57, v191, v2
	v_fma_f32 v2, -v59, v192, v2
	v_fma_f32 v2, -v60, v193, v2
	v_fma_f32 v2, -v61, v228, v2
	v_fma_f32 v2, -v62, v229, v2
	v_fma_f32 v2, -v63, v230, v2
	v_fma_f32 v2, -v64, v231, v2
	v_fma_f32 v2, -v65, v232, v2
	v_fma_f32 v2, -v67, v233, v2
	v_fma_f32 v2, -v70, v234, v2
	v_fma_f32 v2, -v235, v71, v2
	v_fma_f32 v2, -v236, v72, v2
	v_fma_f32 v2, -v69, v237, v2
	ds_read_b128 v[74:77], v0 offset:34304
	ds_read_b128 v[82:85], v0 offset:34320
	ds_read_b128 v[86:89], v0 offset:34336
	ds_read_b128 v[90:93], v0 offset:34352
	ds_read_b128 v[104:107], v0 offset:34368
	ds_read_b128 v[112:115], v0 offset:34384
	ds_read_b128 v[132:135], v0 offset:34400
	ds_read_b128 v[136:139], v0 offset:34416
	ds_read_b128 v[144:147], v0 offset:34432
	ds_read_b128 v[148:151], v0 offset:34448
	ds_read_b128 v[158:161], v0 offset:34464
	ds_read_b128 v[166:169], v0 offset:34480
	ds_read_b128 v[170:173], v0 offset:34496
	ds_read_b128 v[178:181], v0 offset:34512
	ds_read_b128 v[186:189], v0 offset:34528
	ds_read_b128 v[194:197], v0 offset:34544
	v_fma_f32 v2, -v68, v238, v2
	v_fma_f32 v69, -v66, v239, v2
	ds_read_b128 v[78:81], v0 offset:34560
	ds_read_b128 v[96:99], v0 offset:34576
	ds_read_b128 v[100:103], v0 offset:34592
	ds_read_b128 v[108:111], v0 offset:34608
	ds_read_b128 v[116:119], v0 offset:34624
	ds_read_b128 v[120:123], v0 offset:34640
	ds_read_b128 v[124:127], v0 offset:34656
	ds_read_b128 v[128:131], v0 offset:34672
	ds_read_b128 v[140:143], v0 offset:34688
	ds_read_b128 v[152:155], v0 offset:34704
	ds_read_b128 v[162:165], v0 offset:34720
	ds_read_b128 v[182:185], v0 offset:34736
	ds_read_b128 v[190:193], v0 offset:34752
	ds_read_b128 v[228:231], v0 offset:34768
	ds_read_b128 v[232:235], v0 offset:34784
	ds_read_b128 v[236:239], v0 offset:34800
	s_waitcnt lgkmcnt(0)
	v_fma_f32 v0, -v41, v74, v68
	v_fma_f32 v0, -v5, v75, v0
	v_fma_f32 v0, -v6, v76, v0
	v_fma_f32 v0, -v8, v77, v0
	v_fma_f32 v0, -v4, v82, v0
	v_fma_f32 v0, -v7, v83, v0
	v_fma_f32 v0, -v9, v84, v0
	v_fma_f32 v0, -v10, v85, v0
	v_fma_f32 v0, -v11, v86, v0
	v_fma_f32 v0, -v12, v87, v0
	v_fma_f32 v0, -v13, v88, v0
	v_fma_f32 v0, -v14, v89, v0
	v_fma_f32 v0, -v15, v90, v0
	v_fma_f32 v0, -v16, v91, v0
	v_fma_f32 v0, -v17, v92, v0
	v_fma_f32 v0, -v18, v93, v0
	v_fma_f32 v0, -v19, v104, v0
	v_fma_f32 v0, -v20, v105, v0
	v_fma_f32 v0, -v21, v106, v0
	v_fma_f32 v0, -v22, v107, v0
	v_fma_f32 v0, -v23, v112, v0
	v_fma_f32 v0, -v24, v113, v0
	v_fma_f32 v0, -v25, v114, v0
	v_fma_f32 v0, -v26, v115, v0
	v_fma_f32 v0, -v27, v132, v0
	v_fma_f32 v0, -v28, v133, v0
	v_fma_f32 v0, -v29, v134, v0
	v_fma_f32 v0, -v30, v135, v0
	v_fma_f32 v0, -v31, v136, v0
	v_fma_f32 v0, -v32, v137, v0
	v_fma_f32 v0, -v33, v138, v0
	v_fma_f32 v0, -v34, v139, v0
	v_fma_f32 v0, -v35, v144, v0
	v_fma_f32 v0, -v36, v145, v0
	v_fma_f32 v0, -v37, v146, v0
	v_fma_f32 v0, -v43, v147, v0
	v_fma_f32 v0, -v44, v148, v0
	v_fma_f32 v0, -v45, v149, v0
	v_fma_f32 v0, -v46, v150, v0
	v_fma_f32 v0, -v47, v151, v0
	v_fma_f32 v0, -v48, v158, v0
	v_fma_f32 v0, -v49, v159, v0
	v_fma_f32 v0, -v50, v160, v0
	v_fma_f32 v0, -v51, v161, v0
	v_fma_f32 v0, -v52, v166, v0
	v_fma_f32 v0, -v53, v167, v0
	v_fma_f32 v0, -v54, v168, v0
	v_fma_f32 v0, -v55, v169, v0
	v_fma_f32 v0, -v56, v170, v0
	v_fma_f32 v0, -v57, v171, v0
	v_fma_f32 v0, -v59, v172, v0
	v_fma_f32 v0, -v60, v173, v0
	v_fma_f32 v0, -v61, v178, v0
	v_fma_f32 v0, -v62, v179, v0
	v_fma_f32 v0, -v63, v180, v0
	v_fma_f32 v0, -v64, v181, v0
	v_fma_f32 v0, -v65, v186, v0
	v_fma_f32 v0, -v67, v187, v0
	v_fma_f32 v0, -v70, v188, v0
	v_fma_f32 v0, -v71, v189, v0
	v_fma_f32 v0, -v194, v72, v0
	v_fma_f32 v0, -v195, v69, v0
	v_fma_f32 v0, -v68, v196, v0
	v_fma_f32 v68, -v66, v197, v0
	v_fma_f32 v0, -v41, v78, v66
	v_fma_f32 v0, -v5, v79, v0
	v_fma_f32 v0, -v6, v80, v0
	v_fma_f32 v0, -v8, v81, v0
	v_fma_f32 v0, -v4, v96, v0
	v_fma_f32 v0, -v7, v97, v0
	v_fma_f32 v0, -v9, v98, v0
	v_fma_f32 v0, -v10, v99, v0
	v_fma_f32 v0, -v11, v100, v0
	v_fma_f32 v0, -v12, v101, v0
	v_fma_f32 v0, -v13, v102, v0
	v_fma_f32 v0, -v14, v103, v0
	v_fma_f32 v0, -v15, v108, v0
	v_fma_f32 v0, -v16, v109, v0
	v_fma_f32 v0, -v17, v110, v0
	v_fma_f32 v0, -v18, v111, v0
	v_fma_f32 v0, -v19, v116, v0
	v_fma_f32 v0, -v20, v117, v0
	v_fma_f32 v0, -v21, v118, v0
	v_fma_f32 v0, -v22, v119, v0
	v_fma_f32 v0, -v23, v120, v0
	v_fma_f32 v0, -v24, v121, v0
	v_fma_f32 v0, -v25, v122, v0
	v_fma_f32 v0, -v26, v123, v0
	v_fma_f32 v0, -v27, v124, v0
	v_fma_f32 v0, -v28, v125, v0
	v_fma_f32 v0, -v29, v126, v0
	v_fma_f32 v0, -v30, v127, v0
	v_fma_f32 v0, -v31, v128, v0
	v_fma_f32 v0, -v32, v129, v0
	v_fma_f32 v0, -v33, v130, v0
	v_fma_f32 v0, -v34, v131, v0
	v_fma_f32 v0, -v35, v140, v0
	v_fma_f32 v0, -v36, v141, v0
	v_fma_f32 v0, -v37, v142, v0
	v_fma_f32 v0, -v43, v143, v0
	v_fma_f32 v0, -v44, v152, v0
	v_fma_f32 v0, -v45, v153, v0
	v_fma_f32 v0, -v46, v154, v0
	v_fma_f32 v0, -v47, v155, v0
	v_fma_f32 v0, -v48, v162, v0
	v_fma_f32 v0, -v49, v163, v0
	v_fma_f32 v0, -v50, v164, v0
	v_fma_f32 v0, -v51, v165, v0
	v_fma_f32 v0, -v52, v182, v0
	v_fma_f32 v0, -v53, v183, v0
	v_fma_f32 v0, -v54, v184, v0
	v_fma_f32 v0, -v55, v185, v0
	v_fma_f32 v0, -v56, v190, v0
	v_fma_f32 v0, -v57, v191, v0
	v_fma_f32 v0, -v59, v192, v0
	v_fma_f32 v0, -v60, v193, v0
	v_fma_f32 v0, -v61, v228, v0
	v_fma_f32 v0, -v62, v229, v0
	v_fma_f32 v0, -v63, v230, v0
	v_fma_f32 v0, -v64, v231, v0
	v_fma_f32 v0, -v65, v232, v0
	v_fma_f32 v0, -v67, v233, v0
	v_fma_f32 v0, -v70, v234, v0
	v_fma_f32 v0, -v71, v235, v0
	v_fma_f32 v0, -v72, v236, v0
	v_fma_f32 v0, -v237, v69, v0
	v_fma_f32 v0, -v238, v68, v0
	v_fma_f32 v66, -v66, v239, v0
	v_or_b32_e32 v2, v42, v38
	v_cndmask_b32_e64 v0, v39, v176, s[0:1]
	s_movk_i32 s0, 0x44
	v_mad_u64_u32 v[2:3], s[0:1], v2, s0, v[0:1]
	v_mov_b64_e32 v[38:39], s[16:17]
	v_mad_i64_i32 v[2:3], s[0:1], v2, s82, v[38:39]
	s_and_saveexec_b64 s[0:1], vcc
	s_xor_b64 s[0:1], exec, s[0:1]
	s_cbranch_execz .LBB0_1120
	v_lshlrev_b32_e32 v0, 1, v94
	v_lshrrev_b32_e32 v38, 2, v175
	v_and_b32_e32 v0, 24, v0
	v_and_b32_e32 v38, 4, v38
	v_and_b32_e32 v39, 35, v175
	v_or3_b32 v0, v38, v39, v0
	v_lshlrev_b32_e32 v0, 1, v0
	v_lshl_add_u64 v[2:3], v[2:3], 0, v[0:1]
	v_cvt_pk_bf16_f32 v0, -v5, s0
	global_store_short v[2:3], v0, off offset:128
	v_cvt_pk_bf16_f32 v0, -v6, s0
	global_store_short v[2:3], v0, off offset:256
	v_cvt_pk_bf16_f32 v0, -v8, s0
	global_store_short v[2:3], v0, off offset:384
	v_cvt_pk_bf16_f32 v0, -v4, s0
	global_store_short v[2:3], v0, off offset:512
	v_cvt_pk_bf16_f32 v0, -v7, s0
	global_store_short v[2:3], v0, off offset:640
	v_cvt_pk_bf16_f32 v0, -v9, s0
	global_store_short v[2:3], v0, off offset:768
	v_cvt_pk_bf16_f32 v0, -v10, s0
	global_store_short v[2:3], v0, off offset:896
	v_cvt_pk_bf16_f32 v0, -v11, s0
	global_store_short v[2:3], v0, off offset:1024
	v_cvt_pk_bf16_f32 v0, -v12, s0
	global_store_short v[2:3], v0, off offset:1152
	v_cvt_pk_bf16_f32 v0, -v13, s0
	global_store_short v[2:3], v0, off offset:1280
	v_cvt_pk_bf16_f32 v0, -v14, s0
	global_store_short v[2:3], v0, off offset:1408
	v_cvt_pk_bf16_f32 v0, -v15, s0
	global_store_short v[2:3], v0, off offset:1536
	v_cvt_pk_bf16_f32 v0, -v16, s0
	global_store_short v[2:3], v0, off offset:1664
	v_cvt_pk_bf16_f32 v0, -v17, s0
	global_store_short v[2:3], v0, off offset:1792
	v_cvt_pk_bf16_f32 v0, -v18, s0
	global_store_short v[2:3], v0, off offset:1920
	v_cvt_pk_bf16_f32 v0, -v19, s0
	global_store_short v[2:3], v0, off offset:2048
	v_cvt_pk_bf16_f32 v0, -v20, s0
	global_store_short v[2:3], v0, off offset:2176
	v_cvt_pk_bf16_f32 v0, -v21, s0
	global_store_short v[2:3], v0, off offset:2304
	v_cvt_pk_bf16_f32 v0, -v22, s0
	global_store_short v[2:3], v0, off offset:2432
	v_cvt_pk_bf16_f32 v0, -v23, s0
	global_store_short v[2:3], v0, off offset:2560
	v_cvt_pk_bf16_f32 v0, -v24, s0
	global_store_short v[2:3], v0, off offset:2688
	v_cvt_pk_bf16_f32 v0, -v25, s0
	global_store_short v[2:3], v0, off offset:2816
	v_cvt_pk_bf16_f32 v0, -v26, s0
	global_store_short v[2:3], v0, off offset:2944
	v_cvt_pk_bf16_f32 v0, -v27, s0
	global_store_short v[2:3], v0, off offset:3072
	v_cvt_pk_bf16_f32 v0, -v28, s0
	global_store_short v[2:3], v0, off offset:3200
	v_cvt_pk_bf16_f32 v0, -v29, s0
	global_store_short v[2:3], v0, off offset:3328
	v_cvt_pk_bf16_f32 v0, -v30, s0
	global_store_short v[2:3], v0, off offset:3456
	v_cvt_pk_bf16_f32 v0, -v31, s0
	global_store_short v[2:3], v0, off offset:3584
	v_cvt_pk_bf16_f32 v0, -v32, s0
	global_store_short v[2:3], v0, off offset:3712
	v_cvt_pk_bf16_f32 v0, -v33, s0
	v_cvt_pk_bf16_f32 v38, -v41, s0
	global_store_short v[2:3], v0, off offset:3840
	v_cvt_pk_bf16_f32 v0, -v34, s0
	s_movk_i32 s2, 0x1000
	global_store_short v[2:3], v38, off
	global_store_short v[2:3], v0, off offset:3968
	v_add_co_u32_e32 v2, vcc, s2, v2
	v_cvt_pk_bf16_f32 v0, -v35, s0
	s_nop 0
	v_addc_co_u32_e32 v3, vcc, 0, v3, vcc
	global_store_short v[2:3], v0, off
	v_cvt_pk_bf16_f32 v0, -v36, s0
	global_store_short v[2:3], v0, off offset:128
	v_cvt_pk_bf16_f32 v0, -v37, s0
	global_store_short v[2:3], v0, off offset:256
	v_cvt_pk_bf16_f32 v0, -v43, s0
	global_store_short v[2:3], v0, off offset:384
	v_cvt_pk_bf16_f32 v0, -v44, s0
	global_store_short v[2:3], v0, off offset:512
	v_cvt_pk_bf16_f32 v0, -v45, s0
	global_store_short v[2:3], v0, off offset:640
	v_cvt_pk_bf16_f32 v0, -v46, s0
	global_store_short v[2:3], v0, off offset:768
	v_cvt_pk_bf16_f32 v0, -v47, s0
	global_store_short v[2:3], v0, off offset:896
	v_cvt_pk_bf16_f32 v0, -v48, s0
	global_store_short v[2:3], v0, off offset:1024
	v_cvt_pk_bf16_f32 v0, -v49, s0
	global_store_short v[2:3], v0, off offset:1152
	v_cvt_pk_bf16_f32 v0, -v50, s0
	global_store_short v[2:3], v0, off offset:1280
	v_cvt_pk_bf16_f32 v0, -v51, s0
	global_store_short v[2:3], v0, off offset:1408
	v_cvt_pk_bf16_f32 v0, -v52, s0
	global_store_short v[2:3], v0, off offset:1536
	v_cvt_pk_bf16_f32 v0, -v53, s0
	global_store_short v[2:3], v0, off offset:1664
	v_cvt_pk_bf16_f32 v0, -v54, s0
	global_store_short v[2:3], v0, off offset:1792
	v_cvt_pk_bf16_f32 v0, -v55, s0
	global_store_short v[2:3], v0, off offset:1920
	v_cvt_pk_bf16_f32 v0, -v56, s0
	global_store_short v[2:3], v0, off offset:2048
	v_cvt_pk_bf16_f32 v0, -v57, s0
	global_store_short v[2:3], v0, off offset:2176
	v_cvt_pk_bf16_f32 v0, -v59, s0
	global_store_short v[2:3], v0, off offset:2304
	v_cvt_pk_bf16_f32 v0, -v60, s0
	global_store_short v[2:3], v0, off offset:2432
	v_cvt_pk_bf16_f32 v0, -v61, s0
	global_store_short v[2:3], v0, off offset:2560
	v_cvt_pk_bf16_f32 v0, -v62, s0
	global_store_short v[2:3], v0, off offset:2688
	v_cvt_pk_bf16_f32 v0, -v63, s0
	global_store_short v[2:3], v0, off offset:2816
	v_cvt_pk_bf16_f32 v0, -v64, s0
	global_store_short v[2:3], v0, off offset:2944
	v_cvt_pk_bf16_f32 v0, -v65, s0
	global_store_short v[2:3], v0, off offset:3072
	v_cvt_pk_bf16_f32 v0, -v67, s0
	global_store_short v[2:3], v0, off offset:3200
	v_cvt_pk_bf16_f32 v0, -v70, s0
	global_store_short v[2:3], v0, off offset:3328
	v_cvt_pk_bf16_f32 v0, -v71, s0
	global_store_short v[2:3], v0, off offset:3456
	v_cvt_pk_bf16_f32 v0, -v72, s0
	global_store_short v[2:3], v0, off offset:3584
	v_cvt_pk_bf16_f32 v0, -v69, s0
	global_store_short v[2:3], v0, off offset:3712
	v_cvt_pk_bf16_f32 v0, -v68, s0
	global_store_short v[2:3], v0, off offset:3840
	v_cvt_pk_bf16_f32 v0, -v66, s0
	global_store_short v[2:3], v0, off offset:3968
.LBB0_1120:
	s_andn2_saveexec_b64 s[0:1], s[0:1]
	s_cbranch_execz .LBB0_618
	v_lshlrev_b32_e32 v0, 3, v40
	v_lshl_or_b32 v0, v58, 9, v0
	v_lshl_add_u64 v[2:3], v[2:3], 0, v[0:1]
	s_mov_b64 s[2:3], 0x8000
	v_cvt_pk_bf16_f32 v38, v41, v5
	v_lshl_add_u64 v[40:41], v[2:3], 0, s[2:3]
	v_cvt_pk_bf16_f32 v4, v4, v7
	v_cvt_pk_bf16_f32 v5, v9, v10
	global_store_dwordx2 v[40:41], v[4:5], off offset:128
	v_cvt_pk_bf16_f32 v4, v11, v12
	v_cvt_pk_bf16_f32 v5, v13, v14
	global_store_dwordx2 v[40:41], v[4:5], off offset:256
	v_cvt_pk_bf16_f32 v4, v15, v16
	v_cvt_pk_bf16_f32 v5, v17, v18
	global_store_dwordx2 v[40:41], v[4:5], off offset:384
	v_cvt_pk_bf16_f32 v4, v19, v20
	v_cvt_pk_bf16_f32 v5, v21, v22
	v_add_co_u32_e32 v74, vcc, 0x8000, v2
	global_store_dwordx2 v[40:41], v[4:5], off offset:2048
	v_cvt_pk_bf16_f32 v4, v23, v24
	v_cvt_pk_bf16_f32 v5, v25, v26
	v_addc_co_u32_e32 v75, vcc, 0, v3, vcc
	global_store_dwordx2 v[40:41], v[4:5], off offset:2176
	v_cvt_pk_bf16_f32 v4, v27, v28
	v_cvt_pk_bf16_f32 v5, v29, v30
	s_mov_b32 s2, 0x9000
	global_store_dwordx2 v[40:41], v[4:5], off offset:2304
	v_cvt_pk_bf16_f32 v4, v31, v32
	v_cvt_pk_bf16_f32 v5, v33, v34
	v_add_co_u32_e32 v2, vcc, s2, v2
	global_store_dwordx2 v[40:41], v[4:5], off offset:2432
	v_cvt_pk_bf16_f32 v4, v35, v36
	v_cvt_pk_bf16_f32 v5, v37, v43
	v_addc_co_u32_e32 v3, vcc, 0, v3, vcc
	global_store_dwordx2 v[2:3], v[4:5], off
	v_cvt_pk_bf16_f32 v4, v44, v45
	v_cvt_pk_bf16_f32 v5, v46, v47
	global_store_dwordx2 v[2:3], v[4:5], off offset:128
	v_cvt_pk_bf16_f32 v4, v48, v49
	v_cvt_pk_bf16_f32 v5, v50, v51
	global_store_dwordx2 v[2:3], v[4:5], off offset:256
	v_cvt_pk_bf16_f32 v4, v52, v53
	v_cvt_pk_bf16_f32 v5, v54, v55
	global_store_dwordx2 v[2:3], v[4:5], off offset:384
	v_cvt_pk_bf16_f32 v4, v56, v57
	v_cvt_pk_bf16_f32 v5, v59, v60
	global_store_dwordx2 v[2:3], v[4:5], off offset:2048
	v_cvt_pk_bf16_f32 v4, v61, v62
	v_cvt_pk_bf16_f32 v5, v63, v64
	global_store_dwordx2 v[2:3], v[4:5], off offset:2176
	v_cvt_pk_bf16_f32 v4, v65, v67
	v_cvt_pk_bf16_f32 v5, v70, v71
	v_cvt_pk_bf16_f32 v39, v6, v8
	global_store_dwordx2 v[2:3], v[4:5], off offset:2304
	v_cvt_pk_bf16_f32 v4, v72, v69
	v_cvt_pk_bf16_f32 v5, v68, v66
	global_store_dwordx2 v[74:75], v[38:39], off
	global_store_dwordx2 v[2:3], v[4:5], off offset:2432
	s_branch .LBB0_618

.LBB0_1127:
	v_mov_b64_e32 v[14:15], s[40:41]
	global_load_dword v12, v[14:15], off offset:1024 sc1
	s_waitcnt lgkmcnt(0)
	global_load_dword v0, v[14:15], off offset:1280 sc1
	global_load_dword v2, v[14:15], off offset:1536 sc1
	global_load_dword v3, v[14:15], off offset:1792 sc1
	global_load_dword v4, v[14:15], off offset:2048 sc1
	global_load_dword v5, v[14:15], off offset:2304 sc1
	global_load_dword v6, v[14:15], off offset:2560 sc1
	global_load_dword v7, v[14:15], off offset:2816 sc1
	global_load_dword v8, v[14:15], off offset:3072 sc1
	global_load_dword v9, v[14:15], off offset:3328 sc1
	global_load_dword v10, v[14:15], off offset:3584 sc1
	global_load_dword v11, v[14:15], off offset:3840 sc1
	v_mov_b64_e32 v[14:15], s[0:1]
	global_load_dword v13, v[14:15], off sc1
	v_mov_b64_e32 v[14:15], s[2:3]
	global_load_dword v14, v[14:15], off sc1
	v_mov_b64_e32 v[16:17], s[4:5]
	global_load_dword v15, v[16:17], off sc1
	v_mov_b64_e32 v[16:17], s[6:7]
	global_load_dword v16, v[16:17], off sc1
	v_readlane_b32 s18, v254, 5
	s_or_b64 s[14:15], s[14:15], exec
	s_or_b64 s[12:13], s[12:13], exec
	s_waitcnt vmcnt(0) lgkmcnt(0)
	v_add_u32_e32 v17, v0, v12
	v_add_u32_e32 v17, v17, v2
	v_add_u32_e32 v17, v17, v3
	v_add_u32_e32 v17, v17, v4
	v_add_u32_e32 v17, v17, v5
	v_add_u32_e32 v17, v17, v6
	v_add_u32_e32 v17, v17, v7
	v_add_u32_e32 v17, v17, v8
	v_add_u32_e32 v17, v17, v9
	v_add_u32_e32 v17, v17, v10
	v_add_u32_e32 v17, v17, v11
	v_add_u32_e32 v17, v17, v13
	v_add_u32_e32 v17, v17, v14
	v_add_u32_e32 v17, v17, v15
	v_add_u32_e32 v17, v17, v16
	v_cmp_ne_u32_e32 vcc, s18, v17
	s_and_saveexec_b64 s[18:19], vcc
	s_cbranch_execz .LBB0_1126
	s_and_b32 s22, s28, 0xff
	s_mov_b64 s[20:21], -1
	s_cmp_eq_u32 s22, 0
	s_mov_b64 s[24:25], -1
	s_mov_b64 s[22:23], -1
	s_sleep 1
	s_cbranch_scc1 .LBB0_1130
	s_and_saveexec_b64 s[26:27], s[24:25]
	s_cbranch_execz .LBB0_1125
	s_branch .LBB0_1133
.LBB0_1130:
	v_mov_b64_e32 v[18:19], s[40:41]
	global_load_dword v17, v[18:19], off offset:512 sc1
	s_mov_b64 s[24:25], 0
	s_waitcnt vmcnt(0) lgkmcnt(0)
	v_cmp_eq_u32_e32 vcc, 0, v17
	s_and_saveexec_b64 s[26:27], vcc
	s_cmp_lt_u32 s28, 0x40001
	s_cselect_b64 s[24:25], -1, 0
	s_xor_b64 s[22:23], exec, -1
	s_and_b64 s[24:25], s[24:25], exec
	s_or_b64 exec, exec, s[26:27]
	s_and_saveexec_b64 s[26:27], s[24:25]
	s_cbranch_execz .LBB0_1125

.LBB0_1134:
	s_or_b64 exec, exec, s[8:9]
	s_xor_b64 s[0:1], s[10:11], -1
	s_and_saveexec_b64 s[2:3], s[0:1]
	s_xor_b64 s[0:1], exec, s[2:3]
	s_cbranch_execz .LBB0_1136
	v_mov_b64_e32 v[18:19], s[40:41]
	global_atomic_add v[18:19], v203, off offset:512

.LBB0_1137:
	s_lshl_b32 s0, s37, 8
	s_add_u32 s23, s40, s0
	s_addc_u32 s22, s41, 0
	v_mov_b32_e32 v3, s23
	v_add_co_u32_e32 v4, vcc, 0x1000, v3
	v_mov_b32_e32 v3, s22
	s_nop 0
	v_addc_co_u32_e32 v5, vcc, 0, v3, vcc
	global_atomic_add v4, v[4:5], v203, off offset:1024 sc0
	v_cvt_f32_u32_e32 v3, v2
	v_sub_u32_e32 v5, 0, v2
	v_rcp_iflag_f32_e32 v3, v3
	s_nop 0
	v_mul_f32_e32 v3, 0x4f7ffffe, v3
	v_cvt_u32_f32_e32 v3, v3
	v_mul_lo_u32 v5, v5, v3
	v_mul_hi_u32 v5, v3, v5
	v_add_u32_e32 v3, v3, v5
	s_waitcnt vmcnt(0) lgkmcnt(0)
	v_mul_hi_u32 v3, v4, v3
	v_mul_lo_u32 v5, v3, v2
	v_sub_u32_e32 v5, v4, v5
	v_cmp_ge_u32_e32 vcc, v5, v2
	v_add_u32_e32 v6, 1, v3
	s_nop 0
	v_cndmask_b32_e32 v3, v3, v6, vcc
	v_sub_u32_e32 v6, v5, v2
	v_cndmask_b32_e32 v5, v5, v6, vcc
	v_cmp_ge_u32_e32 vcc, v5, v2
	v_add_u32_e32 v5, 1, v3
	v_add_u32_e32 v6, 1, v4
	v_cndmask_b32_e32 v3, v3, v5, vcc
	v_mad_u64_u32 v[4:5], s[0:1], v2, v3, v[2:3]
	v_cmp_ne_u32_e32 vcc, v6, v4
	s_and_saveexec_b64 s[0:1], vcc
	s_xor_b64 s[0:1], exec, s[0:1]
	s_cbranch_execz .LBB0_1150
	v_mov_b32_e32 v0, s23
	v_add_co_u32_e32 v4, vcc, 0x2000, v0
	v_mov_b32_e32 v0, s22
	s_nop 0
	v_addc_co_u32_e32 v5, vcc, 0, v0, vcc
	global_load_dword v0, v[4:5], off offset:1024 sc1
	s_add_u32 s4, s23, 0x2400
	s_addc_u32 s5, s22, 0
	s_waitcnt vmcnt(0) lgkmcnt(0)
	v_cmp_eq_u32_e32 vcc, v0, v3
	s_and_saveexec_b64 s[2:3], vcc
	s_cbranch_execz .LBB0_1149
	s_mov_b32 s24, 1
	s_mov_b64 s[6:7], 0
	s_branch .LBB0_1141

.LBB0_1141:
	s_and_b32 s14, s24, 0xff
	s_mov_b64 s[12:13], -1
	s_cmp_lg_u32 s14, 0
	s_mov_b64 s[14:15], -1
	s_sleep 1
	s_cbranch_scc1 .LBB0_1145
	v_mov_b64_e32 v[4:5], s[40:41]
	global_load_dword v0, v[4:5], off offset:512 sc1
	s_mov_b64 s[14:15], 0
	s_mov_b64 s[18:19], -1
	s_waitcnt vmcnt(0) lgkmcnt(0)
	v_cmp_eq_u32_e32 vcc, 0, v0
	s_and_saveexec_b64 s[20:21], vcc
	s_cmp_lt_u32 s24, 0x40001
	s_cselect_b64 s[14:15], -1, 0
	s_xor_b64 s[18:19], exec, -1
	s_and_b64 s[14:15], s[14:15], exec
	s_or_b64 exec, exec, s[20:21]

.LBB0_1147:
	s_or_b64 exec, exec, s[6:7]
	s_xor_b64 s[4:5], s[8:9], -1
	s_and_saveexec_b64 s[6:7], s[4:5]
	s_xor_b64 s[6:7], exec, s[6:7]
	s_cbranch_execz .LBB0_1149
	v_mov_b64_e32 v[2:3], s[40:41]
	global_atomic_add v[2:3], v203, off offset:512

.LBB0_1150:
	s_andn2_saveexec_b64 s[0:1], s[0:1]
	s_cbranch_execz .LBB0_1166
	v_mov_b32_e32 v2, s40
	v_add_co_u32_e32 v2, vcc, 0x3000, v2
	v_mov_b32_e32 v3, s41
	buffer_wbl2 sc1
	s_waitcnt vmcnt(0)
	v_addc_co_u32_e32 v3, vcc, 0, v3, vcc
	global_atomic_add v2, v[2:3], v203, off offset:1024 sc0
	v_cvt_f32_u32_e32 v3, v0
	v_sub_u32_e32 v4, 0, v0
	s_mov_b64 s[4:5], -1
	v_rcp_iflag_f32_e32 v3, v3
	s_nop 0
	v_mul_f32_e32 v3, 0x4f7ffffe, v3
	v_cvt_u32_f32_e32 v3, v3
	v_mul_lo_u32 v4, v4, v3
	v_mul_hi_u32 v4, v3, v4
	v_add_u32_e32 v3, v3, v4
	s_waitcnt vmcnt(0) lgkmcnt(0)
	v_mul_hi_u32 v3, v2, v3
	v_mul_lo_u32 v4, v3, v0
	v_sub_u32_e32 v4, v2, v4
	v_cmp_ge_u32_e32 vcc, v4, v0
	v_add_u32_e32 v5, 1, v3
	s_nop 0
	v_cndmask_b32_e32 v3, v3, v5, vcc
	v_sub_u32_e32 v5, v4, v0
	v_cndmask_b32_e32 v4, v4, v5, vcc
	v_cmp_ge_u32_e32 vcc, v4, v0
	v_add_u32_e32 v4, 1, v3
	v_add_u32_e32 v5, 1, v2
	v_cndmask_b32_e32 v4, v3, v4, vcc
	v_mad_u64_u32 v[2:3], s[0:1], v0, v4, v[0:1]
	s_add_u32 s0, s40, 0x3500
	s_addc_u32 s1, s41, 0
	v_cmp_ne_u32_e32 vcc, v5, v2
	v_mov_b64_e32 v[2:3], s[0:1]
	s_and_saveexec_b64 s[2:3], vcc
	s_cbranch_execz .LBB0_1163
	v_mov_b64_e32 v[2:3], s[0:1]
	global_load_dword v0, v[2:3], off sc1
	s_mov_b64 s[8:9], 0
	s_waitcnt vmcnt(0) lgkmcnt(0)
	v_cmp_eq_u32_e32 vcc, v0, v4
	s_and_saveexec_b64 s[6:7], vcc
	s_cbranch_execz .LBB0_1162
	s_add_u32 s4, s40, 0x200
	s_addc_u32 s5, s41, 0
	s_mov_b32 s24, 1
	s_branch .LBB0_1155

.LBB0_1171:
	v_mov_b32_e32 v0, v201
	s_barrier
	s_nop 0
	v_cmp_eq_u32_e32 vcc, 0, v0
	s_and_saveexec_b64 s[0:1], vcc
	s_cbranch_execz .LBB0_1173
	v_mov_b64_e32 v[2:3], s[12:13]
	global_atomic_add v0, v[2:3], v203, off sc0
	s_waitcnt vmcnt(0) lgkmcnt(0)
	ds_write_b32 v1, v0 offset:208
.LBB0_1173:
	s_or_b64 exec, exec, s[0:1]
	s_waitcnt lgkmcnt(0)
	s_barrier
	ds_read_b32 v0, v1 offset:208
	s_mov_b64 s[0:1], -1
	s_waitcnt lgkmcnt(0)
	v_cmp_le_i32_e32 vcc, s24, v0
	v_readfirstlane_b32 s22, v0
	s_cbranch_vccnz .LBB0_1170
	v_mov_b32_e32 v148, v201
	s_mov_b32 s0, 0xd000
	v_ashrrev_i32_e32 v149, 8, v148
	v_mad_i32_i24 v150, v149, s0, v207
	s_cmp_gt_i32 s22, 31
	s_mov_b64 s[0:1], -1
	s_cbranch_scc0 .LBB0_1298
	s_cmpk_gt_u32 s22, 0x9f
	s_cbranch_scc0 .LBB0_1293
	s_cmpk_gt_u32 s22, 0xa7
	s_cbranch_scc0 .LBB0_1288
	s_cmpk_gt_u32 s22, 0x2a7
	s_cbranch_scc0 .LBB0_1273
	s_cmpk_gt_u32 s22, 0x4a7
	s_cbranch_scc0 .LBB0_1255
	s_add_i32 s23, s22, 0xfffffb58
	v_readlane_b32 s0, v254, 61
	s_cmp_ge_i32 s23, s0
	s_mov_b64 s[0:1], -1
	s_cbranch_scc0 .LBB0_1236
	v_readlane_b32 s0, v254, 61
	s_sub_i32 s0, s23, s0
	s_nop 0
	v_lshl_add_u32 v3, s0, 1, v149
	v_cmp_lt_i32_e32 vcc, s49, v3
	s_and_saveexec_b64 s[0:1], vcc
	s_xor_b64 s[2:3], exec, s[0:1]
	s_cbranch_execz .LBB0_1233
	s_movk_i32 s0, 0x67f
	v_mul_i32_i24_e32 v8, 0xd000, v149
	v_cmp_lt_u32_e32 vcc, s0, v3
	s_and_saveexec_b64 s[0:1], vcc
	s_xor_b64 s[4:5], exec, s[0:1]
	s_cbranch_execz .LBB0_1224
	s_movk_i32 s0, 0x93f
	v_cmp_lt_u32_e32 vcc, s0, v3
	s_and_saveexec_b64 s[0:1], vcc
	s_xor_b64 s[6:7], exec, s[0:1]
	s_cbranch_execz .LBB0_1222
	v_lshlrev_b32_e32 v0, 2, v3
	v_mov_b32_e32 v7, v201
	v_and_b32_e32 v0, 0x7fffffc0, v0
	v_lshlrev_b32_e32 v3, 6, v3
	v_add_u32_e32 v2, 0xffffdb00, v0
	v_and_b32_e32 v6, 63, v7
	v_bfe_u32 v9, v7, 6, 2
	v_and_b32_e32 v3, 0x3c0, v3
	v_readlane_b32 s38, v254, 63
	v_or_b32_e32 v0, v6, v2
	s_movk_i32 s0, 0x910
	v_or_b32_e32 v10, v9, v3
	v_readlane_b32 s39, v255, 0
	v_cmp_gt_u32_e64 s[0:1], s0, v0
	v_mov_b32_e32 v11, 0
	v_lshl_add_u64 v[4:5], v[0:1], 2, s[38:39]
	v_mul_u32_u24_e32 v0, 0x910, v10
	v_lshlrev_b32_e32 v0, 2, v0
	v_mov_b32_e32 v10, 0
	s_barrier
	s_and_saveexec_b64 s[38:39], s[0:1]
	s_cbranch_execz .LBB0_1185
	v_lshl_add_u64 v[12:13], v[4:5], 0, v[0:1]
	global_load_dword v10, v[12:13], off
.LBB0_1185:
	s_or_b64 exec, exec, s[38:39]
	s_and_saveexec_b64 s[38:39], s[0:1]
	s_cbranch_execz .LBB0_1187
	v_lshl_add_u64 v[12:13], v[4:5], 0, v[0:1]
	v_add_co_u32_e32 v12, vcc, 0x9000, v12
	s_nop 1
	v_addc_co_u32_e32 v13, vcc, 0, v13, vcc
	global_load_dword v11, v[12:13], off offset:256
.LBB0_1187:
	s_or_b64 exec, exec, s[38:39]
	v_mov_b32_e32 v13, 0
	v_mov_b32_e32 v14, 0
	s_and_saveexec_b64 s[38:39], s[0:1]
	s_cbranch_execz .LBB0_1189
	v_lshl_add_u64 v[14:15], v[4:5], 0, v[0:1]
	v_add_co_u32_e32 v14, vcc, 0x12000, v14
	s_nop 1
	v_addc_co_u32_e32 v15, vcc, 0, v15, vcc
	global_load_dword v14, v[14:15], off offset:512
.LBB0_1189:
	s_or_b64 exec, exec, s[38:39]
	s_and_saveexec_b64 s[38:39], s[0:1]
	s_cbranch_execz .LBB0_1191
	v_lshl_add_u64 v[12:13], v[4:5], 0, v[0:1]
	v_add_co_u32_e32 v12, vcc, 0x1b000, v12
	s_nop 1
	v_addc_co_u32_e32 v13, vcc, 0, v13, vcc
	global_load_dword v13, v[12:13], off offset:768
.LBB0_1191:
	s_or_b64 exec, exec, s[38:39]
	v_mov_b32_e32 v15, 0
	v_mov_b32_e32 v16, 0
	s_and_saveexec_b64 s[38:39], s[0:1]
	s_cbranch_execz .LBB0_1193
	v_lshl_add_u64 v[16:17], v[4:5], 0, v[0:1]
	v_add_co_u32_e32 v16, vcc, 0x24000, v16
	s_nop 1
	v_addc_co_u32_e32 v17, vcc, 0, v17, vcc
	global_load_dword v16, v[16:17], off offset:1024
.LBB0_1193:
	s_or_b64 exec, exec, s[38:39]
	s_and_saveexec_b64 s[38:39], s[0:1]
	s_cbranch_execz .LBB0_1195
	v_lshl_add_u64 v[18:19], v[4:5], 0, v[0:1]
	v_add_co_u32_e32 v18, vcc, 0x2d000, v18
	s_nop 1
	v_addc_co_u32_e32 v19, vcc, 0, v19, vcc
	global_load_dword v15, v[18:19], off offset:1280
.LBB0_1195:
	s_or_b64 exec, exec, s[38:39]
	v_mov_b32_e32 v17, 0
	v_mov_b32_e32 v18, 0
	s_and_saveexec_b64 s[38:39], s[0:1]
	s_cbranch_execz .LBB0_1197
	v_lshl_add_u64 v[18:19], v[4:5], 0, v[0:1]
	v_add_co_u32_e32 v18, vcc, 0x36000, v18
	s_nop 1
	v_addc_co_u32_e32 v19, vcc, 0, v19, vcc
	global_load_dword v18, v[18:19], off offset:1536
.LBB0_1197:
	s_or_b64 exec, exec, s[38:39]
	s_and_saveexec_b64 s[38:39], s[0:1]
	s_cbranch_execz .LBB0_1199
	v_lshl_add_u64 v[20:21], v[4:5], 0, v[0:1]
	v_add_co_u32_e32 v20, vcc, 0x3f000, v20
	s_nop 1
	v_addc_co_u32_e32 v21, vcc, 0, v21, vcc
	global_load_dword v17, v[20:21], off offset:1792
.LBB0_1199:
	s_or_b64 exec, exec, s[38:39]
	v_mov_b32_e32 v19, 0
	v_mov_b32_e32 v20, 0
	s_and_saveexec_b64 s[38:39], s[0:1]
	s_cbranch_execz .LBB0_1201
	v_lshl_add_u64 v[20:21], v[4:5], 0, v[0:1]
	v_add_co_u32_e32 v20, vcc, 0x48000, v20
	s_nop 1
	v_addc_co_u32_e32 v21, vcc, 0, v21, vcc
	global_load_dword v20, v[20:21], off offset:2048
.LBB0_1201:
	s_or_b64 exec, exec, s[38:39]
	s_and_saveexec_b64 s[38:39], s[0:1]
	s_cbranch_execz .LBB0_1203
	v_lshl_add_u64 v[22:23], v[4:5], 0, v[0:1]
	v_add_co_u32_e32 v22, vcc, 0x51000, v22
	s_nop 1
	v_addc_co_u32_e32 v23, vcc, 0, v23, vcc
	global_load_dword v19, v[22:23], off offset:2304
.LBB0_1203:
	s_or_b64 exec, exec, s[38:39]
	v_mov_b32_e32 v21, 0
	v_mov_b32_e32 v22, 0
	s_and_saveexec_b64 s[38:39], s[0:1]
	s_cbranch_execz .LBB0_1205
	v_lshl_add_u64 v[22:23], v[4:5], 0, v[0:1]
	v_add_co_u32_e32 v22, vcc, 0x5a000, v22
	s_nop 1
	v_addc_co_u32_e32 v23, vcc, 0, v23, vcc
	global_load_dword v22, v[22:23], off offset:2560
.LBB0_1205:
	s_or_b64 exec, exec, s[38:39]
	s_and_saveexec_b64 s[38:39], s[0:1]
	s_cbranch_execz .LBB0_1207
	v_lshl_add_u64 v[24:25], v[4:5], 0, v[0:1]
	v_add_co_u32_e32 v24, vcc, 0x63000, v24
	s_nop 1
	v_addc_co_u32_e32 v25, vcc, 0, v25, vcc
	global_load_dword v21, v[24:25], off offset:2816
.LBB0_1207:
	s_or_b64 exec, exec, s[38:39]
	v_mov_b32_e32 v23, 0
	v_mov_b32_e32 v24, 0
	s_and_saveexec_b64 s[38:39], s[0:1]
	s_cbranch_execz .LBB0_1209
	v_lshl_add_u64 v[24:25], v[4:5], 0, v[0:1]
	v_add_co_u32_e32 v24, vcc, 0x6c000, v24
	s_nop 1
	v_addc_co_u32_e32 v25, vcc, 0, v25, vcc
	global_load_dword v24, v[24:25], off offset:3072
.LBB0_1209:
	s_or_b64 exec, exec, s[38:39]
	s_and_saveexec_b64 s[38:39], s[0:1]
	s_cbranch_execz .LBB0_1211
	v_lshl_add_u64 v[26:27], v[4:5], 0, v[0:1]
	v_add_co_u32_e32 v26, vcc, 0x75000, v26
	s_nop 1
	v_addc_co_u32_e32 v27, vcc, 0, v27, vcc
	global_load_dword v23, v[26:27], off offset:3328
.LBB0_1211:
	s_or_b64 exec, exec, s[38:39]
	v_mov_b32_e32 v25, 0
	v_mov_b32_e32 v26, 0
	s_and_saveexec_b64 s[38:39], s[0:1]
	s_cbranch_execz .LBB0_1213
	v_lshl_add_u64 v[26:27], v[4:5], 0, v[0:1]
	v_add_co_u32_e32 v26, vcc, 0x7e000, v26
	s_nop 1
	v_addc_co_u32_e32 v27, vcc, 0, v27, vcc
	global_load_dword v26, v[26:27], off offset:3584
.LBB0_1213:
	s_or_b64 exec, exec, s[38:39]
	s_and_saveexec_b64 s[38:39], s[0:1]
	s_cbranch_execz .LBB0_1215
	v_lshl_add_u64 v[4:5], v[4:5], 0, v[0:1]
	v_add_co_u32_e32 v4, vcc, 0x87000, v4
	s_nop 1
	v_addc_co_u32_e32 v5, vcc, 0, v5, vcc
	global_load_dword v25, v[4:5], off offset:3840

.LBB0_1216:
	global_load_dword v0, v[6:7], off
	v_add_u32_e32 v10, 0x100, v10
	v_cmp_lt_u32_e32 vcc, s50, v10
	v_lshl_add_u64 v[6:7], v[6:7], 0, s[38:39]
	s_or_b64 s[0:1], vcc, s[0:1]
	s_waitcnt vmcnt(0) lgkmcnt(0)
	ds_write_b32 v5, v0
	v_add_u32_e32 v5, 0x400, v5
	s_andn2_b64 exec, exec, s[0:1]
	s_cbranch_execnz .LBB0_1216
	s_or_b64 exec, exec, s[0:1]
	v_lshlrev_b32_e32 v5, 4, v12
	v_and_b32_e32 v5, 48, v5
	v_mul_u32_u24_e32 v6, 0x41, v5
	v_lshlrev_b32_e32 v10, 2, v6
	v_and_b32_e32 v11, 0xfc, v12
	v_add3_u32 v13, v150, v10, v11
	v_add3_u32 v20, v150, v11, v10
	s_waitcnt lgkmcnt(0)
	s_barrier
	ds_read2_b32 v[6:7], v13 offset1:130
	ds_read2_b32 v[10:11], v20 offset0:65 offset1:195
	v_lshrrev_b32_e32 v0, 2, v12
	v_or_b32_e32 v0, v0, v2
	v_readlane_b32 s0, v255, 1
	v_readlane_b32 s1, v255, 2
	s_waitcnt lgkmcnt(0)
	v_cvt_pk_bf16_f32 v14, v6, v10
	v_add_u32_e32 v6, 0x400, v13
	v_add_u32_e32 v10, 0x400, v20
	v_cvt_pk_bf16_f32 v15, v7, v11
	ds_read2_b32 v[6:7], v6 offset0:4 offset1:134
	ds_read2_b32 v[10:11], v10 offset0:69 offset1:199
	s_waitcnt lgkmcnt(0)
	v_cvt_pk_bf16_f32 v16, v6, v10
	v_add_u32_e32 v6, 0x800, v13
	v_add_u32_e32 v10, 0x800, v20
	v_cvt_pk_bf16_f32 v17, v7, v11
	ds_read2_b32 v[6:7], v6 offset0:8 offset1:138
	ds_read2_b32 v[10:11], v10 offset0:73 offset1:203
	s_waitcnt lgkmcnt(0)
	v_cvt_pk_bf16_f32 v18, v6, v10
	v_add_u32_e32 v6, 0xc00, v13
	v_add_u32_e32 v10, 0xc00, v20
	v_cvt_pk_bf16_f32 v19, v7, v11
	ds_read2_b32 v[6:7], v6 offset0:12 offset1:142
	ds_read2_b32 v[10:11], v10 offset0:77 offset1:207
	s_waitcnt lgkmcnt(0)
	v_cvt_pk_bf16_f32 v20, v6, v10
	v_cvt_pk_bf16_f32 v21, v7, v11
	v_lshlrev_b64 v[6:7], 11, v[0:1]
	v_lshl_add_u64 v[6:7], s[0:1], 0, v[6:7]
	v_lshlrev_b32_e32 v0, 1, v3
	v_readlane_b32 s0, v255, 3
	v_lshl_add_u64 v[6:7], v[6:7], 0, v[0:1]
	v_lshlrev_b32_e32 v0, 1, v5
	v_mov_b32_e32 v3, v1
	v_readlane_b32 s1, v255, 4
	v_lshl_add_u64 v[6:7], v[6:7], 0, v[0:1]
	v_mov_b32_e32 v5, v1
	v_lshl_add_u64 v[2:3], v[2:3], 2, s[0:1]
	v_lshlrev_b32_e32 v0, 8, v9
	v_readlane_b32 s0, v254, 35
	v_lshl_add_u64 v[2:3], v[2:3], 0, v[4:5]
	v_add_u32_e32 v4, v150, v4
	v_add3_u32 v5, v8, v0, s0
	s_mov_b64 s[0:1], 0
	global_store_dwordx4 v[6:7], v[14:17], off
	global_store_dwordx4 v[6:7], v[18:21], off offset:16

.LBB0_1219:
	v_add_u32_e32 v7, s37, v5
	ds_read_b128 v[8:11], v7
	ds_read_b128 v[14:17], v7 offset:16
	ds_read2_b32 v[18:19], v0 offset1:65
	v_add_u32_e32 v7, 0x400, v0
	s_add_i32 s37, s37, 32
	s_cmpk_eq_i32 s37, 0x100
	s_waitcnt lgkmcnt(0)
	v_fmac_f32_e32 v6, v8, v18
	v_fmac_f32_e32 v6, v9, v19
	ds_read2_b32 v[8:9], v0 offset0:130 offset1:195
	v_add_u32_e32 v0, 0x820, v0
	s_waitcnt lgkmcnt(0)
	v_fmac_f32_e32 v6, v10, v8
	v_fmac_f32_e32 v6, v11, v9
	ds_read2_b32 v[8:9], v7 offset0:4 offset1:69
	s_waitcnt lgkmcnt(0)
	v_fmac_f32_e32 v6, v14, v8
	v_fmac_f32_e32 v6, v15, v9
	ds_read2_b32 v[8:9], v7 offset0:134 offset1:199
	s_waitcnt lgkmcnt(0)
	v_fmac_f32_e32 v6, v16, v8
	v_fmac_f32_e32 v6, v17, v9
	s_cbranch_scc0 .LBB0_1219
	v_lshrrev_b32_e32 v0, 6, v12
	s_movk_i32 s37, 0xa00
	v_mul_lo_u32 v0, v0, s37
	v_lshl_add_u64 v[8:9], v[0:1], 2, v[2:3]
	global_atomic_add_f32 v[8:9], v6, off
	v_add_u32_e32 v0, 0x100, v12
	v_cmp_lt_u32_e32 vcc, s50, v12
	v_add_u32_e32 v5, 0x400, v5
	s_or_b64 s[0:1], vcc, s[0:1]
	v_mov_b32_e32 v12, v0
	s_andn2_b64 exec, exec, s[0:1]
	s_cbranch_execnz .LBB0_1218
	s_or_b64 exec, exec, s[0:1]
.LBB0_1222:
	s_andn2_saveexec_b64 s[0:1], s[6:7]
	s_cbranch_execz .LBB0_1311
	v_add_u16_e32 v0, 0xf980, v3
	v_mul_u32_u24_e32 v2, 0xba2f, v0
	v_lshrrev_b32_e32 v2, 21, v2
	v_mul_lo_u16_e32 v3, 44, v2
	v_mov_b32_e32 v6, v201
	v_sub_u16_e32 v0, v0, v3
	v_lshlrev_b32_e32 v12, 6, v2
	v_and_b32_e32 v7, 63, v6
	v_bfe_u32 v8, v6, 6, 2
	v_or_b32_e32 v2, v7, v12
	v_lshlrev_b16_e32 v13, 6, v0
	v_readlane_b32 s6, v255, 5
	v_or_b32_e32 v4, v8, v13
	v_lshlrev_b32_e32 v0, 2, v2
	v_readlane_b32 s7, v255, 6
	s_waitcnt lgkmcnt(0)
	s_barrier
	v_lshl_add_u64 v[2:3], s[6:7], 0, v[0:1]
	v_lshlrev_b32_e32 v0, 12, v4
	v_lshl_add_u64 v[2:3], v[2:3], 0, v[0:1]
	s_movk_i32 s6, 0x4000
	v_add_co_u32_e32 v4, vcc, s6, v2
	s_mov_b32 s6, 0x8000
	s_nop 0
	v_addc_co_u32_e32 v5, vcc, 0, v3, vcc
	global_load_dword v9, v[4:5], off
	v_add_co_u32_e32 v4, vcc, s6, v2
	s_mov_b32 s6, 0xc000
	s_nop 0
	v_addc_co_u32_e32 v5, vcc, 0, v3, vcc
	global_load_dword v10, v[4:5], off
	v_add_co_u32_e32 v4, vcc, s6, v2
	s_mov_b32 s6, 0x10000
	s_nop 0
	v_addc_co_u32_e32 v5, vcc, 0, v3, vcc
	global_load_dword v11, v[4:5], off
	v_add_co_u32_e32 v4, vcc, s6, v2
	s_mov_b32 s6, 0x14000
	s_nop 0
	v_addc_co_u32_e32 v5, vcc, 0, v3, vcc
	global_load_dword v14, v[4:5], off
	v_add_co_u32_e32 v4, vcc, s6, v2
	s_mov_b32 s6, 0x18000
	s_nop 0
	v_addc_co_u32_e32 v5, vcc, 0, v3, vcc
	global_load_dword v15, v[4:5], off
	v_add_co_u32_e32 v4, vcc, s6, v2
	s_mov_b32 s6, 0x1c000
	s_nop 0
	v_addc_co_u32_e32 v5, vcc, 0, v3, vcc
	global_load_dword v16, v[4:5], off
	v_add_co_u32_e32 v4, vcc, s6, v2
	s_mov_b32 s6, 0x20000
	s_nop 0
	v_addc_co_u32_e32 v5, vcc, 0, v3, vcc
	global_load_dword v17, v[4:5], off
	v_add_co_u32_e32 v4, vcc, s6, v2
	global_load_dword v0, v[2:3], off
	s_nop 0
	v_addc_co_u32_e32 v5, vcc, 0, v3, vcc
	s_mov_b32 s6, 0x24000
	global_load_dword v18, v[4:5], off
	v_add_co_u32_e32 v4, vcc, s6, v2
	s_mov_b32 s6, 0x28000
	s_nop 0
	v_addc_co_u32_e32 v5, vcc, 0, v3, vcc
	global_load_dword v19, v[4:5], off
	v_add_co_u32_e32 v4, vcc, s6, v2
	s_mov_b32 s6, 0x2c000
	s_nop 0
	v_addc_co_u32_e32 v5, vcc, 0, v3, vcc
	global_load_dword v20, v[4:5], off
	v_add_co_u32_e32 v4, vcc, s6, v2
	s_mov_b32 s6, 0x30000
	s_nop 0
	v_addc_co_u32_e32 v5, vcc, 0, v3, vcc
	global_load_dword v21, v[4:5], off
	v_add_co_u32_e32 v4, vcc, s6, v2
	s_mov_b32 s6, 0x34000
	s_nop 0
	v_addc_co_u32_e32 v5, vcc, 0, v3, vcc
	global_load_dword v22, v[4:5], off
	v_add_co_u32_e32 v4, vcc, s6, v2
	s_mov_b32 s6, 0x38000
	s_nop 0
	v_addc_co_u32_e32 v5, vcc, 0, v3, vcc
	global_load_dword v23, v[4:5], off
	v_add_co_u32_e32 v4, vcc, s6, v2
	s_mov_b32 s6, 0x3c000
	s_nop 0
	v_addc_co_u32_e32 v5, vcc, 0, v3, vcc
	v_add_co_u32_e32 v2, vcc, s6, v2
	global_load_dword v4, v[4:5], off
	s_nop 0
	v_addc_co_u32_e32 v3, vcc, 0, v3, vcc
	global_load_dword v2, v[2:3], off
	v_mul_u32_u24_e32 v3, 0x104, v8
	v_lshlrev_b32_e32 v5, 2, v7
	v_add3_u32 v3, v150, v3, v5
	s_waitcnt vmcnt(0) lgkmcnt(0)
	ds_write_b32 v3, v0
	ds_write_b32 v3, v9 offset:1040
	ds_write_b32 v3, v10 offset:2080
	ds_write_b32 v3, v11 offset:3120
	ds_write_b32 v3, v14 offset:4160
	ds_write_b32 v3, v15 offset:5200
	ds_write_b32 v3, v16 offset:6240
	ds_write_b32 v3, v17 offset:7280
	ds_write_b32 v3, v18 offset:8320
	ds_write_b32 v3, v19 offset:9360
	ds_write_b32 v3, v20 offset:10400
	ds_write_b32 v3, v21 offset:11440
	ds_write_b32 v3, v22 offset:12480
	ds_write_b32 v3, v23 offset:13520
	ds_write_b32 v3, v4 offset:14560
	ds_write_b32 v3, v2 offset:15600
	v_lshlrev_b32_e32 v2, 4, v6
	v_and_b32_e32 v14, 48, v2
	v_mul_u32_u24_e32 v2, 0x41, v14
	v_lshlrev_b32_e32 v4, 2, v2
	v_and_b32_e32 v5, 0xfc, v6
	v_add3_u32 v10, v150, v4, v5
	v_add3_u32 v11, v150, v5, v4
	s_waitcnt lgkmcnt(0)
	s_barrier
	ds_read2_b32 v[2:3], v10 offset1:130
	ds_read2_b32 v[4:5], v11 offset0:65 offset1:195
	v_bfe_u32 v0, v6, 2, 6
	v_add_u32_e32 v6, 0x400, v11
	ds_read2_b32 v[6:7], v6 offset0:69 offset1:199
	v_add_u32_e32 v8, 0x800, v11
	s_waitcnt lgkmcnt(1)
	v_cvt_pk_bf16_f32 v2, v2, v4
	v_add_u32_e32 v4, 0x400, v10
	v_cvt_pk_bf16_f32 v3, v3, v5
	ds_read2_b32 v[4:5], v4 offset0:4 offset1:134
	ds_read2_b32 v[8:9], v8 offset0:73 offset1:203
	v_or_b32_e32 v0, v0, v12
	v_mul_u32_u24_e32 v0, 0xb00, v0
	v_readlane_b32 s6, v255, 7
	s_waitcnt lgkmcnt(1)
	v_cvt_pk_bf16_f32 v4, v4, v6
	v_add_u32_e32 v6, 0x800, v10
	v_cvt_pk_bf16_f32 v5, v5, v7
	ds_read2_b32 v[6:7], v6 offset0:8 offset1:138
	v_lshlrev_b32_e32 v0, 1, v0
	v_readlane_b32 s7, v255, 8
	s_waitcnt lgkmcnt(0)
	v_cvt_pk_bf16_f32 v6, v6, v8
	v_add_u32_e32 v8, 0xc00, v10
	v_add_u32_e32 v10, 0xc00, v11
	v_cvt_pk_bf16_f32 v7, v7, v9
	ds_read2_b32 v[8:9], v8 offset0:12 offset1:142
	ds_read2_b32 v[10:11], v10 offset0:77 offset1:207
	s_waitcnt lgkmcnt(0)
	v_cvt_pk_bf16_f32 v8, v8, v10
	v_cvt_pk_bf16_f32 v9, v9, v11
	v_lshl_add_u64 v[10:11], s[6:7], 0, v[0:1]
	v_lshlrev_b32_e32 v0, 1, v13
	v_lshl_add_u64 v[10:11], v[10:11], 0, v[0:1]
	v_lshlrev_b32_e32 v0, 1, v14
	v_lshl_add_u64 v[10:11], v[10:11], 0, v[0:1]
	global_store_dwordx4 v[10:11], v[2:5], off
	global_store_dwordx4 v[10:11], v[6:9], off offset:16
	s_or_b64 exec, exec, s[0:1]

.LBB0_1225:
	v_lshlrev_b32_e32 v2, 2, v3
	v_mov_b32_e32 v0, v201
	v_and_b32_e32 v2, 0x1fc0, v2
	v_add_u32_e32 v2, 0xfffffc00, v2
	v_and_b32_e32 v12, 63, v0
	v_or_b32_e32 v4, v12, v2
	v_lshrrev_b32_e32 v4, 1, v4
	v_and_b32_e32 v5, 15, v0
	s_mov_b32 s4, 0x1fffff0
	v_and_b32_e32 v9, 0xff, v0
	v_bfe_u32 v10, v0, 6, 2
	v_and_or_b32 v6, v4, s4, v5
	v_and_b32_e32 v0, 16, v0
	v_readlane_b32 s4, v254, 60
	v_cmp_eq_u32_e32 vcc, 0, v0
	s_waitcnt lgkmcnt(0)
	v_mov_b32_e32 v0, s4
	v_readlane_b32 s4, v254, 58
	s_barrier
	s_nop 0
	v_mov_b32_e32 v4, s4
	v_readlane_b32 s4, v254, 59
	v_cndmask_b32_e32 v5, v0, v4, vcc
	s_mov_b64 s[6:7], 0x18000
	v_mov_b32_e32 v0, s4
	v_readlane_b32 s4, v254, 57
	s_nop 1
	v_mov_b32_e32 v4, s4
	v_cndmask_b32_e32 v4, v0, v4, vcc
	v_lshlrev_b32_e32 v0, 6, v3
	v_and_b32_e32 v3, 0x3c0, v0
	v_lshl_add_u64 v[4:5], v[4:5], 0, s[14:15]
	v_or_b32_e32 v7, v10, v3
	v_lshlrev_b32_e32 v0, 2, v6
	v_lshl_add_u64 v[4:5], v[4:5], 0, v[0:1]
	v_mul_u32_u24_e32 v0, 0xb00, v7
	v_lshlrev_b32_e32 v0, 2, v0
	v_lshl_add_u64 v[4:5], v[4:5], 0, v[0:1]
	s_mov_b32 s4, 0xb000
	v_add_co_u32_e32 v6, vcc, s4, v4
	s_mov_b32 s4, 0x16000
	s_nop 0
	v_addc_co_u32_e32 v7, vcc, 0, v5, vcc
	global_load_dword v11, v[6:7], off
	v_add_co_u32_e32 v6, vcc, s4, v4
	s_mov_b32 s4, 0x21000
	s_nop 0
	v_addc_co_u32_e32 v7, vcc, 0, v5, vcc
	global_load_dword v13, v[6:7], off
	v_add_co_u32_e32 v6, vcc, s4, v4
	s_mov_b32 s4, 0x2c000
	s_nop 0
	v_addc_co_u32_e32 v7, vcc, 0, v5, vcc
	global_load_dword v14, v[6:7], off
	v_add_co_u32_e32 v6, vcc, s4, v4
	s_mov_b32 s4, 0x37000
	s_nop 0
	v_addc_co_u32_e32 v7, vcc, 0, v5, vcc
	global_load_dword v15, v[6:7], off
	v_add_co_u32_e32 v6, vcc, s4, v4
	s_mov_b32 s4, 0x42000
	s_nop 0
	v_addc_co_u32_e32 v7, vcc, 0, v5, vcc
	global_load_dword v16, v[6:7], off
	v_add_co_u32_e32 v6, vcc, s4, v4
	s_mov_b32 s4, 0x4d000
	s_nop 0
	v_addc_co_u32_e32 v7, vcc, 0, v5, vcc
	global_load_dword v17, v[6:7], off
	v_add_co_u32_e32 v6, vcc, s4, v4
	s_mov_b32 s4, 0x58000
	s_nop 0
	v_addc_co_u32_e32 v7, vcc, 0, v5, vcc
	global_load_dword v18, v[6:7], off
	v_add_co_u32_e32 v6, vcc, s4, v4
	global_load_dword v0, v[4:5], off
	s_nop 0
	v_addc_co_u32_e32 v7, vcc, 0, v5, vcc
	s_mov_b32 s4, 0x63000
	global_load_dword v19, v[6:7], off
	v_add_co_u32_e32 v6, vcc, s4, v4
	s_mov_b32 s4, 0x6e000
	s_nop 0
	v_addc_co_u32_e32 v7, vcc, 0, v5, vcc
	global_load_dword v20, v[6:7], off
	v_add_co_u32_e32 v6, vcc, s4, v4
	s_mov_b32 s4, 0x79000
	s_nop 0
	v_addc_co_u32_e32 v7, vcc, 0, v5, vcc
	global_load_dword v21, v[6:7], off
	v_add_co_u32_e32 v6, vcc, s4, v4
	s_mov_b32 s4, 0x84000
	s_nop 0
	v_addc_co_u32_e32 v7, vcc, 0, v5, vcc
	global_load_dword v22, v[6:7], off
	v_add_co_u32_e32 v6, vcc, s4, v4
	s_mov_b32 s4, 0x8f000
	s_nop 0
	v_addc_co_u32_e32 v7, vcc, 0, v5, vcc
	global_load_dword v23, v[6:7], off
	v_add_co_u32_e32 v6, vcc, s4, v4
	s_mov_b32 s4, 0x9a000
	s_nop 0
	v_addc_co_u32_e32 v7, vcc, 0, v5, vcc
	global_load_dword v24, v[6:7], off
	v_add_co_u32_e32 v6, vcc, s4, v4
	s_mov_b32 s4, 0xa5000
	s_nop 0
	v_addc_co_u32_e32 v7, vcc, 0, v5, vcc
	v_add_co_u32_e32 v4, vcc, s4, v4
	global_load_dword v6, v[6:7], off
	s_nop 0
	v_addc_co_u32_e32 v5, vcc, 0, v5, vcc
	global_load_dword v5, v[4:5], off
	v_mul_u32_u24_e32 v7, 0x104, v10
	v_lshlrev_b32_e32 v4, 2, v12
	v_add3_u32 v7, v150, v7, v4
	s_waitcnt vmcnt(0) lgkmcnt(0)
	ds_write_b32 v7, v0
	ds_write_b32 v7, v11 offset:1040
	ds_write_b32 v7, v13 offset:2080
	ds_write_b32 v7, v14 offset:3120
	ds_write_b32 v7, v15 offset:4160
	ds_write_b32 v7, v16 offset:5200
	ds_write_b32 v7, v17 offset:6240
	ds_write_b32 v7, v18 offset:7280
	ds_write_b32 v7, v19 offset:8320
	ds_write_b32 v7, v20 offset:9360
	ds_write_b32 v7, v21 offset:10400
	ds_write_b32 v7, v22 offset:11440
	ds_write_b32 v7, v23 offset:12480
	ds_write_b32 v7, v24 offset:13520
	ds_write_b32 v7, v6 offset:14560
	ds_write_b32 v7, v5 offset:15600
	v_lshlrev_b32_e32 v0, 2, v9
	v_readlane_b32 s4, v254, 35
	v_or_b32_e32 v11, 0xffffff00, v9
	s_nop 0
	v_add3_u32 v5, v8, v0, s4
	v_mul_u32_u24_e32 v0, 0x1800, v10
	v_or3_b32 v0, v0, v3, v12
	v_readlane_b32 s4, v255, 15
	v_lshlrev_b32_e32 v0, 2, v0
	v_readlane_b32 s5, v255, 16
	s_nop 1
	v_lshl_add_u64 v[6:7], s[4:5], 0, v[0:1]
	s_mov_b64 s[4:5], 0
.LBB0_1226:
	global_load_dword v0, v[6:7], off
	v_add_u32_e32 v11, 0x100, v11
	v_cmp_lt_u32_e32 vcc, s50, v11
	v_lshl_add_u64 v[6:7], v[6:7], 0, s[6:7]
	s_or_b64 s[4:5], vcc, s[4:5]
	s_waitcnt vmcnt(0) lgkmcnt(0)
	ds_write_b32 v5, v0
	v_add_u32_e32 v5, 0x400, v5
	s_andn2_b64 exec, exec, s[4:5]
	s_cbranch_execnz .LBB0_1226
	s_or_b64 exec, exec, s[4:5]
	v_lshlrev_b32_e32 v5, 4, v9
	v_and_b32_e32 v5, 48, v5
	v_mul_u32_u24_e32 v6, 0x41, v5
	v_lshlrev_b32_e32 v11, 2, v6
	v_and_b32_e32 v12, 0xfc, v9
	v_add3_u32 v18, v150, v11, v12
	v_add3_u32 v11, v150, v12, v11
	s_waitcnt lgkmcnt(0)
	s_barrier
	ds_read2_b32 v[6:7], v18 offset1:130
	ds_read2_b32 v[12:13], v11 offset0:65 offset1:195
	v_add_u32_e32 v14, 0x400, v11
	ds_read2_b32 v[14:15], v14 offset0:69 offset1:199
	v_add_u32_e32 v16, 0x800, v11
	ds_read2_b32 v[16:17], v16 offset0:73 offset1:203
	s_waitcnt lgkmcnt(2)
	v_cvt_pk_bf16_f32 v12, v6, v12
	v_add_u32_e32 v6, 0x400, v18
	v_cvt_pk_bf16_f32 v13, v7, v13
	ds_read2_b32 v[6:7], v6 offset0:4 offset1:134
	v_add_u32_e32 v11, 0xc00, v11
	v_lshrrev_b32_e32 v0, 2, v9
	v_or_b32_e32 v0, v0, v2
	v_readlane_b32 s4, v255, 9
	s_waitcnt lgkmcnt(0)
	v_cvt_pk_bf16_f32 v14, v6, v14
	v_add_u32_e32 v6, 0x800, v18
	v_cvt_pk_bf16_f32 v15, v7, v15
	ds_read2_b32 v[6:7], v6 offset0:8 offset1:138
	v_readlane_b32 s5, v255, 10
	s_waitcnt lgkmcnt(0)
	v_cvt_pk_bf16_f32 v16, v6, v16
	v_add_u32_e32 v6, 0xc00, v18
	v_cvt_pk_bf16_f32 v17, v7, v17
	ds_read2_b32 v[6:7], v6 offset0:12 offset1:142
	ds_read2_b32 v[18:19], v11 offset0:77 offset1:207
	s_waitcnt lgkmcnt(0)
	v_cvt_pk_bf16_f32 v18, v6, v18
	v_cvt_pk_bf16_f32 v19, v7, v19
	v_lshlrev_b64 v[6:7], 11, v[0:1]
	v_lshl_add_u64 v[6:7], s[4:5], 0, v[6:7]
	v_lshlrev_b32_e32 v0, 1, v3
	v_readlane_b32 s4, v255, 11
	v_lshl_add_u64 v[6:7], v[6:7], 0, v[0:1]
	v_lshlrev_b32_e32 v0, 1, v5
	v_mov_b32_e32 v3, v1
	v_readlane_b32 s5, v255, 12
	v_lshl_add_u64 v[6:7], v[6:7], 0, v[0:1]
	v_mov_b32_e32 v5, v1
	v_lshl_add_u64 v[2:3], v[2:3], 2, s[4:5]
	v_lshlrev_b32_e32 v0, 8, v10
	v_readlane_b32 s4, v254, 35
	v_lshl_add_u64 v[2:3], v[2:3], 0, v[4:5]
	v_add_u32_e32 v4, v150, v4
	v_add3_u32 v5, v8, v0, s4
	s_mov_b64 s[4:5], 0
	global_store_dwordx4 v[6:7], v[12:15], off
	global_store_dwordx4 v[6:7], v[16:19], off offset:16

.LBB0_1229:
	v_add_u32_e32 v7, s6, v5
	ds_read_b128 v[10:13], v7
	ds_read_b128 v[14:17], v7 offset:16
	ds_read2_b32 v[18:19], v0 offset1:65
	v_add_u32_e32 v7, 0x400, v0
	s_add_i32 s6, s6, 32
	s_cmpk_eq_i32 s6, 0x100
	s_waitcnt lgkmcnt(0)
	v_fmac_f32_e32 v6, v10, v18
	v_fmac_f32_e32 v6, v11, v19
	ds_read2_b32 v[10:11], v0 offset0:130 offset1:195
	v_add_u32_e32 v0, 0x820, v0
	s_waitcnt lgkmcnt(0)
	v_fmac_f32_e32 v6, v12, v10
	v_fmac_f32_e32 v6, v13, v11
	ds_read2_b32 v[10:11], v7 offset0:4 offset1:69
	s_waitcnt lgkmcnt(0)
	v_fmac_f32_e32 v6, v14, v10
	v_fmac_f32_e32 v6, v15, v11
	ds_read2_b32 v[10:11], v7 offset0:134 offset1:199
	s_waitcnt lgkmcnt(0)
	v_fmac_f32_e32 v6, v16, v10
	v_fmac_f32_e32 v6, v17, v11
	s_cbranch_scc0 .LBB0_1229
	v_lshrrev_b32_e32 v0, 6, v9
	v_mul_lo_u32 v0, v0, s46
	v_lshl_add_u64 v[10:11], v[0:1], 2, v[2:3]
	global_atomic_add_f32 v[10:11], v6, off
	v_add_u32_e32 v0, 0x100, v9
	v_cmp_lt_u32_e32 vcc, s50, v9
	v_add_u32_e32 v5, 0x400, v5
	s_or_b64 s[4:5], vcc, s[4:5]
	v_mov_b32_e32 v9, v0
	s_andn2_b64 exec, exec, s[4:5]
	s_cbranch_execnz .LBB0_1228
	s_or_b64 exec, exec, s[4:5]

.LBB0_1233:
	s_andn2_saveexec_b64 s[0:1], s[2:3]
	s_cbranch_execz .LBB0_1235
	v_ashrrev_i32_e32 v0, 31, v3
	v_lshrrev_b32_e32 v0, 28, v0
	v_add_u32_e32 v0, v3, v0
	v_and_b32_e32 v2, 0x3fffff0, v0
	v_sub_u32_e32 v2, v3, v2
	v_mov_b32_e32 v3, v201
	v_lshlrev_b32_e32 v0, 2, v0
	v_bfe_u32 v11, v3, 6, 2
	v_lshlrev_b32_e32 v2, 6, v2
	v_bfi_b32 v4, 63, v3, v0
	v_or_b32_e32 v6, v11, v2
	v_ashrrev_i32_e32 v5, 31, v4
	v_ashrrev_i32_e32 v7, 31, v6
	v_lshl_add_u64 v[4:5], v[4:5], 2, s[30:31]
	v_lshlrev_b64 v[8:9], 12, v[6:7]
	v_lshl_add_u64 v[8:9], v[4:5], 0, v[8:9]
	s_waitcnt lgkmcnt(0)
	s_barrier
	v_and_b32_e32 v14, 0xffffffc0, v0
	global_load_dword v0, v[8:9], off
	v_or_b32_e32 v8, 4, v6
	v_ashrrev_i32_e32 v9, 31, v8
	v_lshlrev_b64 v[8:9], 12, v[8:9]
	v_lshl_add_u64 v[8:9], v[4:5], 0, v[8:9]
	global_load_dword v12, v[8:9], off
	v_or_b32_e32 v8, 8, v6
	v_ashrrev_i32_e32 v9, 31, v8
	v_lshlrev_b64 v[8:9], 12, v[8:9]
	v_lshl_add_u64 v[8:9], v[4:5], 0, v[8:9]
	global_load_dword v13, v[8:9], off
	v_or_b32_e32 v8, 12, v6
	v_ashrrev_i32_e32 v9, 31, v8
	v_lshlrev_b64 v[8:9], 12, v[8:9]
	v_lshl_add_u64 v[8:9], v[4:5], 0, v[8:9]
	global_load_dword v15, v[8:9], off
	v_or_b32_e32 v8, 16, v6
	v_ashrrev_i32_e32 v9, 31, v8
	v_lshlrev_b64 v[8:9], 12, v[8:9]
	v_lshl_add_u64 v[8:9], v[4:5], 0, v[8:9]
	global_load_dword v16, v[8:9], off
	v_or_b32_e32 v8, 20, v6
	v_ashrrev_i32_e32 v9, 31, v8
	v_lshlrev_b64 v[8:9], 12, v[8:9]
	v_lshl_add_u64 v[8:9], v[4:5], 0, v[8:9]
	global_load_dword v17, v[8:9], off
	v_or_b32_e32 v8, 24, v6
	v_ashrrev_i32_e32 v9, 31, v8
	v_lshlrev_b64 v[8:9], 12, v[8:9]
	v_lshl_add_u64 v[8:9], v[4:5], 0, v[8:9]
	global_load_dword v18, v[8:9], off
	v_or_b32_e32 v8, 28, v6
	v_ashrrev_i32_e32 v9, 31, v8
	v_lshlrev_b64 v[8:9], 12, v[8:9]
	v_lshl_add_u64 v[8:9], v[4:5], 0, v[8:9]
	global_load_dword v19, v[8:9], off
	v_or_b32_e32 v8, 32, v6
	v_ashrrev_i32_e32 v9, 31, v8
	v_lshlrev_b64 v[8:9], 12, v[8:9]
	v_lshl_add_u64 v[8:9], v[4:5], 0, v[8:9]
	global_load_dword v20, v[8:9], off
	v_or_b32_e32 v8, 36, v6
	v_ashrrev_i32_e32 v9, 31, v8
	v_lshlrev_b64 v[8:9], 12, v[8:9]
	v_lshl_add_u64 v[8:9], v[4:5], 0, v[8:9]
	global_load_dword v21, v[8:9], off
	v_or_b32_e32 v8, 40, v6
	v_ashrrev_i32_e32 v9, 31, v8
	v_lshlrev_b64 v[8:9], 12, v[8:9]
	v_lshl_add_u64 v[8:9], v[4:5], 0, v[8:9]
	global_load_dword v22, v[8:9], off
	v_or_b32_e32 v8, 44, v6
	v_ashrrev_i32_e32 v9, 31, v8
	v_lshlrev_b64 v[8:9], 12, v[8:9]
	v_lshl_add_u64 v[8:9], v[4:5], 0, v[8:9]
	global_load_dword v23, v[8:9], off
	v_or_b32_e32 v8, 48, v6
	v_ashrrev_i32_e32 v9, 31, v8
	v_lshlrev_b64 v[8:9], 12, v[8:9]
	v_lshl_add_u64 v[8:9], v[4:5], 0, v[8:9]
	global_load_dword v24, v[8:9], off
	v_or_b32_e32 v8, 52, v6
	v_ashrrev_i32_e32 v9, 31, v8
	v_lshlrev_b64 v[8:9], 12, v[8:9]
	v_lshl_add_u64 v[8:9], v[4:5], 0, v[8:9]
	global_load_dword v25, v[8:9], off
	v_or_b32_e32 v8, 56, v6
	v_ashrrev_i32_e32 v9, 31, v8
	v_or_b32_e32 v6, 60, v6
	v_lshlrev_b64 v[8:9], 12, v[8:9]
	v_ashrrev_i32_e32 v7, 31, v6
	v_lshl_add_u64 v[8:9], v[4:5], 0, v[8:9]
	v_lshlrev_b64 v[6:7], 12, v[6:7]
	global_load_dword v8, v[8:9], off
	v_lshl_add_u64 v[4:5], v[4:5], 0, v[6:7]
	global_load_dword v4, v[4:5], off
	v_and_b32_e32 v10, 63, v3
	v_mul_u32_u24_e32 v5, 0x104, v11
	v_lshlrev_b32_e32 v6, 2, v10
	v_add3_u32 v5, v150, v5, v6
	s_waitcnt vmcnt(0) lgkmcnt(0)
	ds_write_b32 v5, v0
	ds_write_b32 v5, v12 offset:1040
	ds_write_b32 v5, v13 offset:2080
	ds_write_b32 v5, v15 offset:3120
	ds_write_b32 v5, v16 offset:4160
	ds_write_b32 v5, v17 offset:5200
	ds_write_b32 v5, v18 offset:6240
	ds_write_b32 v5, v19 offset:7280
	ds_write_b32 v5, v20 offset:8320
	ds_write_b32 v5, v21 offset:9360
	ds_write_b32 v5, v22 offset:10400
	ds_write_b32 v5, v23 offset:11440
	ds_write_b32 v5, v24 offset:12480
	ds_write_b32 v5, v25 offset:13520
	ds_write_b32 v5, v8 offset:14560
	ds_write_b32 v5, v4 offset:15600
	v_lshlrev_b32_e32 v4, 4, v3
	v_and_b32_e32 v15, 48, v4
	v_mul_u32_u24_e32 v4, 0x41, v15
	v_bfe_u32 v0, v3, 2, 6
	v_lshlrev_b32_e32 v6, 2, v4
	v_and_b32_e32 v3, 0xfc, v3
	v_add3_u32 v12, v150, v6, v3
	v_add3_u32 v3, v150, v3, v6
	s_waitcnt lgkmcnt(0)
	s_barrier
	ds_read2_b32 v[4:5], v12 offset1:130
	ds_read2_b32 v[6:7], v3 offset0:65 offset1:195
	v_add_u32_e32 v8, 0x400, v3
	ds_read2_b32 v[8:9], v8 offset0:69 offset1:199
	v_add_u32_e32 v10, 0x800, v3
	ds_read2_b32 v[10:11], v10 offset0:73 offset1:203
	s_waitcnt lgkmcnt(2)
	v_cvt_pk_bf16_f32 v4, v4, v6
	v_add_u32_e32 v6, 0x400, v12
	v_cvt_pk_bf16_f32 v5, v5, v7
	ds_read2_b32 v[6:7], v6 offset0:4 offset1:134
	v_add_u32_e32 v3, 0xc00, v3
	s_waitcnt lgkmcnt(0)
	v_cvt_pk_bf16_f32 v6, v6, v8
	v_add_u32_e32 v8, 0x800, v12
	v_cvt_pk_bf16_f32 v7, v7, v9
	ds_read2_b32 v[8:9], v8 offset0:8 offset1:138
	s_waitcnt lgkmcnt(0)
	v_cvt_pk_bf16_f32 v8, v8, v10
	v_add_u32_e32 v10, 0xc00, v12
	v_cvt_pk_bf16_f32 v9, v9, v11
	ds_read2_b32 v[10:11], v10 offset0:12 offset1:142
	ds_read2_b32 v[12:13], v3 offset0:77 offset1:207
	v_ashrrev_i32_e32 v3, 31, v2
	s_waitcnt lgkmcnt(0)
	v_cvt_pk_bf16_f32 v10, v10, v12
	v_or_b32_e32 v12, v0, v14
	v_cvt_pk_bf16_f32 v11, v11, v13
	v_ashrrev_i32_e32 v13, 31, v12
	v_lshlrev_b64 v[12:13], 11, v[12:13]
	v_lshl_add_u64 v[12:13], s[40:41], 0, v[12:13]
	v_lshl_add_u64 v[2:3], v[2:3], 1, v[12:13]
	v_lshlrev_b32_e32 v0, 1, v15
	v_lshl_add_u64 v[2:3], v[2:3], 0, v[0:1]
	global_store_dwordx4 v[2:3], v[4:7], off
	global_store_dwordx4 v[2:3], v[8:11], off offset:16

.LBB0_1236:
	s_andn2_b64 vcc, exec, s[0:1]
	s_cbranch_vccnz .LBB0_1254
	v_lshl_add_u32 v107, s23, 1, v149
	v_mov_b32_e32 v7, v201
	v_bfe_u32 v11, v107, 2, 1
	v_bfe_u32 v13, v107, 3, 3
	v_bfe_u32 v0, v7, 7, 1
	v_lshl_or_b32 v12, v11, 1, v0
	v_lshlrev_b32_e32 v0, 6, v107
	v_and_b32_e32 v0, 0xc0, v0
	v_lshrrev_b32_e32 v2, 1, v7
	v_ashrrev_i32_e32 v10, 6, v107
	v_and_or_b32 v121, v2, 32, v0
	v_mul_u32_u24_e32 v0, 0x1100, v13
	s_mov_b32 s0, 0x8800
	v_mad_i64_i32 v[4:5], s[0:1], v10, s0, v[0:1]
	v_lshlrev_b64 v[8:9], 9, v[4:5]
	v_and_b32_e32 v120, 15, v7
	v_bfe_u32 v3, v7, 4, 2
	v_lshl_add_u64 v[8:9], s[42:43], 0, v[8:9]
	v_lshlrev_b32_e32 v14, 7, v12
	v_mov_b32_e32 v15, v1
	v_lshl_add_u64 v[8:9], v[8:9], 0, v[14:15]
	v_or_b32_e32 v2, v121, v120
	v_lshlrev_b32_e32 v14, 4, v3
	v_lshl_add_u64 v[8:9], v[8:9], 0, v[14:15]
	v_lshlrev_b32_e32 v14, 9, v2
	v_lshl_add_u64 v[8:9], v[8:9], 0, v[14:15]
	global_load_dwordx4 v[46:49], v[8:9], off
	global_load_dwordx4 v[42:45], v[8:9], off offset:64
	v_add_co_u32_e32 v8, vcc, 0x2000, v8
	v_readlane_b32 s0, v254, 62
	s_nop 0
	v_addc_co_u32_e32 v9, vcc, 0, v9, vcc
	global_load_dwordx4 v[50:53], v[8:9], off
	global_load_dwordx4 v[54:57], v[8:9], off offset:64
	v_or_b32_e32 v8, s0, v12
	v_mov_b32_e32 v9, v1
	v_mov_b32 v117, 0xf149f2ca
	v_cmp_eq_u32_e32 vcc, 1, v10
	v_lshl_add_u64 v[8:9], v[8:9], 2, s[8:9]
	v_mov_b32_e32 v2, 0
	v_mov_b32_e32 v116, v117
	v_mov_b32_e32 v6, 0
	s_and_saveexec_b64 s[0:1], vcc
	s_cbranch_execz .LBB0_1239
	global_load_dword v6, v[8:9], off
	s_waitcnt vmcnt(0) lgkmcnt(0)
	v_mul_f32_e32 v116, 0x3fb8aa3b, v6
	v_mov_b32_e32 v6, 1.0
.LBB0_1239:
	s_or_b64 exec, exec, s[0:1]
	s_and_saveexec_b64 s[0:1], vcc
	s_cbranch_execz .LBB0_1241
	global_load_dword v2, v[8:9], off
	s_waitcnt vmcnt(0) lgkmcnt(0)
	v_mul_f32_e32 v117, 0x3fb8aa3b, v2
	v_mov_b32_e32 v2, 1.0
.LBB0_1241:
	s_or_b64 exec, exec, s[0:1]
	v_lshlrev_b64 v[4:5], 8, v[4:5]
	v_lshl_add_u64 v[4:5], s[58:59], 0, v[4:5]
	v_lshlrev_b32_e32 v8, 7, v11
	v_mov_b32_e32 v9, v1
	v_lshl_add_u64 v[4:5], v[4:5], 0, v[8:9]
	v_lshl_or_b32 v8, v10, 3, v13
	v_ashrrev_i32_e32 v9, 31, v8
	v_lshlrev_b64 v[14:15], 7, v[8:9]
	v_lshl_or_b32 v9, v11, 6, v14
	v_mov_b64_e32 v[16:17], s[44:45]
	v_mad_u64_u32 v[16:17], s[0:1], v9, s85, v[16:17]
	v_and_b32_e32 v31, 7, v7
	v_mad_i32_i24 v17, v15, s85, v17
	v_lshrrev_b32_sdwa v30, v198, v7 dst_sel:DWORD dst_unused:UNUSED_PAD src0_sel:DWORD src1_sel:BYTE_0
	v_lshlrev_b32_e32 v108, 4, v31
	v_mov_b32_e32 v109, v1
	v_lshl_add_u64 v[4:5], v[4:5], 0, v[108:109]
	v_lshl_add_u64 v[26:27], v[16:17], 0, v[108:109]
	v_lshlrev_b32_e32 v14, 8, v30
	v_mov_b32_e32 v15, v1
	v_or_b32_e32 v32, 32, v30
	v_lshl_add_u64 v[14:15], v[4:5], 0, v[14:15]
	v_mad_u64_u32 v[18:19], s[0:1], v30, s85, v[26:27]
	v_lshlrev_b32_e32 v22, 8, v32
	v_mov_b32_e32 v23, v1
	global_load_dwordx4 v[14:17], v[14:15], off
	s_nop 0
	global_load_dwordx4 v[18:21], v[18:19], off
	v_lshl_add_u64 v[4:5], v[4:5], 0, v[22:23]
	global_load_dwordx4 v[22:25], v[4:5], off
	v_mad_u64_u32 v[4:5], s[0:1], v32, s85, v[26:27]
	global_load_dwordx4 v[26:29], v[4:5], off
	v_and_b32_e32 v35, 64, v208
	v_lshlrev_b32_e32 v106, 3, v3
	v_bitop3_b32 v33, v3, v7, 7 bitop3:0x78
	v_xor_b32_e32 v34, 16, v208
	s_mov_b32 s1, 0x880000
	v_and_b32_e32 v37, 0xf8, v7
	v_xor_b32_sdwa v7, v30, v7 dst_sel:DWORD dst_unused:UNUSED_PAD src0_sel:DWORD src1_sel:BYTE_0
	v_bitop3_b32 v3, v3, v31, 4 bitop3:0x36
	v_add_u32_e32 v31, 64, v35
	v_mul_hi_u32_u24_e32 v5, 0x88000, v11
	v_mul_u32_u24_e32 v4, 0x88000, v11
	v_mad_i64_i32 v[10:11], s[2:3], v10, s1, 0
	v_lshlrev_b32_e32 v128, 7, v30
	v_mul_u32_u24_e32 v129, 0x90, v30
	v_mul_u32_u24_e32 v30, 0x1100, v30
	s_mov_b32 s1, 0x110000
	v_lshlrev_b32_e32 v7, 4, v7
	v_cmp_lt_i32_e32 vcc, v34, v31
	v_mov_b32_e32 v9, v1
	v_mad_i64_i32 v[4:5], s[2:3], v8, s1, v[4:5]
	v_lshlrev_b32_e32 v130, 4, v3
	v_cndmask_b32_e32 v3, v208, v34, vcc
	v_lshlrev_b32_e32 v8, 1, v30
	v_and_b32_e32 v132, 0x70, v7
	v_lshlrev_b32_e32 v122, 6, v12
	v_xor_b32_e32 v36, 32, v208
	v_lshlrev_b32_e32 v12, 8, v0
	v_mov_b32_e32 v13, v1
	v_lshl_or_b32 v10, v37, 5, v10
	v_lshlrev_b32_e32 v125, 2, v3
	v_lshl_add_u64 v[4:5], v[4:5], 0, v[8:9]
	v_add_u32_e32 v3, v150, v132
	v_lshlrev_b32_e32 v38, 5, v107
	v_lshlrev_b32_e32 v131, 7, v32
	v_cmp_lt_i32_e32 vcc, v36, v31
	v_lshl_add_u64 v[10:11], v[10:11], 0, v[12:13]
	s_movk_i32 s1, 0x80
	v_lshl_add_u64 v[112:113], s[10:11], 0, v[4:5]
	v_add_u32_e32 v4, v3, v128
	v_lshlrev_b32_e32 v127, 4, v33
	v_add3_u32 v33, v150, v108, v129
	v_cndmask_b32_e32 v31, v208, v36, vcc
	v_and_or_b32 v10, v38, s1, v10
	v_add_u32_e32 v3, v3, v131
	v_lshlrev_b32_e32 v124, 2, v31
	v_lshl_add_u64 v[114:115], s[10:11], 0, v[10:11]
	v_lshlrev_b32_e32 v126, 7, v120
	v_mul_u32_u24_e32 v123, 0x90, v120
	s_mov_b32 s0, 1
	v_mov_b32_e32 v7, v6
	v_mov_b32_e32 v8, v6
	v_mov_b32_e32 v9, v6
	v_mov_b32_e32 v5, v2
	s_waitcnt vmcnt(0) lgkmcnt(0)
	ds_write_b128 v4, v[14:17]
	ds_write_b128 v3, v[22:25]
	ds_write_b128 v33, v[18:21] offset:8192
	ds_write_b128 v33, v[26:29] offset:12800
	v_mov_b32_e32 v26, v1
	v_mov_b32_e32 v27, v1
	v_mov_b32_e32 v28, v1
	v_mov_b32_e32 v29, v1
	v_mov_b64_e32 v[32:33], v[28:29]
	v_mov_b64_e32 v[36:37], v[28:29]
	v_mov_b64_e32 v[40:41], v[28:29]
	v_mov_b64_e32 v[18:19], v[26:27]
	v_mov_b64_e32 v[22:23], v[26:27]
	v_mov_b64_e32 v[14:15], v[26:27]
	v_mov_b64_e32 v[10:11], v[26:27]
	v_mov_b64_e32 v[30:31], v[26:27]
	v_mov_b64_e32 v[34:35], v[26:27]
	v_mov_b64_e32 v[38:39], v[26:27]
	v_mov_b64_e32 v[20:21], v[28:29]
	v_mov_b64_e32 v[24:25], v[28:29]
	v_mov_b64_e32 v[16:17], v[28:29]
	v_mov_b64_e32 v[12:13], v[28:29]
	v_mov_b32_e32 v3, v2
	v_mov_b32_e32 v4, v2
	s_waitcnt lgkmcnt(0)
	s_barrier
.LBB0_1242:
	v_lshl_add_u64 v[66:67], v[114:115], 0, v[108:109]
	s_mov_b32 s1, 0x2c84000
	v_add_co_u32_e32 v58, vcc, s1, v66
	v_lshl_add_u64 v[70:71], v[112:113], 0, v[108:109]
	s_nop 0
	v_addc_co_u32_e32 v59, vcc, 0, v67, vcc
	s_mov_b32 s1, 0x3d80000
	v_add_co_u32_e32 v62, vcc, s1, v70
	s_mov_b32 s1, 0x2c86000
	s_nop 0
	v_addc_co_u32_e32 v63, vcc, 0, v71, vcc
	v_add_co_u32_e32 v66, vcc, s1, v66
	s_mov_b32 s1, 0x3dc4000
	s_nop 0
	v_addc_co_u32_e32 v67, vcc, 0, v67, vcc
	v_add_co_u32_e32 v70, vcc, s1, v70
	global_load_dwordx4 v[58:61], v[58:59], off
	s_nop 0
	v_addc_co_u32_e32 v71, vcc, 0, v71, vcc
	global_load_dwordx4 v[62:65], v[62:63], off offset:128
	s_and_b32 s1, 1, s0
	global_load_dwordx4 v[66:69], v[66:67], off
	s_cselect_b32 s2, 0, 0x4400
	global_load_dwordx4 v[70:73], v[70:71], off offset:128
	v_add_u32_e32 v133, s2, v150
	s_setprio 1
	v_add_u32_e32 v86, v133, v126
	v_add_u32_e32 v102, v86, v127
	ds_read_b128 v[74:77], v102
	ds_read_b128 v[82:85], v102 offset:2048
	v_add_u32_e32 v103, v86, v130
	ds_read_b128 v[86:89], v103
	ds_read_b128 v[98:101], v103 offset:2048
	s_waitcnt lgkmcnt(0)
	v_mfma_f32_16x16x32_bf16 v[78:81], v[74:77], v[46:49], 0
	v_mfma_f32_16x16x32_bf16 v[74:77], v[74:77], v[50:53], 0
	v_mfma_f32_16x16x32_bf16 v[94:97], v[86:89], v[42:45], v[78:81]
	v_mfma_f32_16x16x32_bf16 v[78:81], v[86:89], v[54:57], v[74:77]
	v_mfma_f32_16x16x32_bf16 v[74:77], v[82:85], v[46:49], 0
	v_mfma_f32_16x16x32_bf16 v[90:93], v[98:101], v[42:45], v[74:77]
	v_mfma_f32_16x16x32_bf16 v[74:77], v[82:85], v[50:53], 0
	ds_read_b128 v[82:85], v102 offset:4096
	ds_read_b128 v[134:137], v102 offset:6144
	v_mfma_f32_16x16x32_bf16 v[74:77], v[98:101], v[54:57], v[74:77]
	ds_read_b128 v[98:101], v103 offset:4096
	ds_read_b128 v[138:141], v103 offset:6144
	s_waitcnt lgkmcnt(0)
	v_mfma_f32_16x16x32_bf16 v[86:89], v[82:85], v[46:49], 0
	v_mfma_f32_16x16x32_bf16 v[82:85], v[82:85], v[50:53], 0
	v_mfma_f32_16x16x32_bf16 v[102:105], v[98:101], v[42:45], v[86:89]
	v_mfma_f32_16x16x32_bf16 v[86:89], v[98:101], v[54:57], v[82:85]
	v_mfma_f32_16x16x32_bf16 v[82:85], v[134:137], v[46:49], 0
	v_mfma_f32_16x16x32_bf16 v[98:101], v[138:141], v[42:45], v[82:85]
	v_mfma_f32_16x16x32_bf16 v[82:85], v[134:137], v[50:53], 0
	v_mfma_f32_16x16x32_bf16 v[82:85], v[138:141], v[54:57], v[82:85]
	s_setprio 0
	v_max_f32_e32 v110, v95, v95
	v_max_f32_e32 v111, v94, v94
	v_max_f32_e32 v110, v111, v110
	v_max_f32_e32 v111, v97, v97
	v_max_f32_e32 v118, v96, v96
	v_max_f32_e32 v111, v118, v111
	v_max_f32_e32 v118, v93, v93
	v_max_f32_e32 v119, v92, v92
	v_max_f32_e32 v118, v119, v118
	v_max3_f32 v118, v90, v91, v118
	v_max3_f32 v110, v110, v111, v118
	v_max_f32_e32 v111, v105, v105
	v_max_f32_e32 v118, v104, v104
	v_max_f32_e32 v111, v118, v111
	v_max_f32_e32 v118, v101, v101
	v_max_f32_e32 v119, v100, v100
	v_max_f32_e32 v118, v119, v118
	v_max3_f32 v111, v102, v103, v111
	v_max3_f32 v118, v98, v99, v118
	v_max3_f32 v110, v110, v111, v118
	ds_bpermute_b32 v111, v125, v110
	s_waitcnt lgkmcnt(0)
	v_max_f32_e32 v111, v111, v111
	v_max_f32_e32 v110, v110, v111
	ds_bpermute_b32 v111, v124, v110
	s_waitcnt lgkmcnt(0)
	v_max_f32_e32 v111, v111, v111
	v_max_f32_e32 v110, v110, v111
	v_add_f32_e32 v111, 0x41000000, v116
	v_cmp_gt_f32_e32 vcc, v110, v111
	s_cbranch_vccz .LBB0_1244
	v_max_f32_e32 v110, v110, v110
	v_max_f32_e32 v111, v116, v116
	v_max_f32_e32 v118, v111, v110
	v_sub_f32_e32 v110, v116, v118
	v_exp_f32_e32 v110, v110
	v_mov_b32_e32 v119, v117
	v_mov_b32_e32 v116, v118
	v_pk_mul_f32 v[6:7], v[6:7], v[110:111] op_sel_hi:[1,0]
	v_pk_mul_f32 v[8:9], v[8:9], v[110:111] op_sel_hi:[1,0]
	v_pk_mul_f32 v[40:41], v[40:41], v[110:111] op_sel_hi:[1,0]
	v_pk_mul_f32 v[38:39], v[38:39], v[110:111] op_sel_hi:[1,0]
	v_pk_mul_f32 v[32:33], v[32:33], v[110:111] op_sel_hi:[1,0]
	v_pk_mul_f32 v[30:31], v[30:31], v[110:111] op_sel_hi:[1,0]
	v_pk_mul_f32 v[20:21], v[20:21], v[110:111] op_sel_hi:[1,0]
	v_pk_mul_f32 v[18:19], v[18:19], v[110:111] op_sel_hi:[1,0]
	v_pk_mul_f32 v[16:17], v[16:17], v[110:111] op_sel_hi:[1,0]
	v_pk_mul_f32 v[14:15], v[14:15], v[110:111] op_sel_hi:[1,0]
	s_branch .LBB0_1245

.LBB0_1253:
	v_sub_f32_e32 v46, v46, v110
	v_sub_f32_e32 v50, v62, v110
	v_sub_f32_e32 v62, v74, v110
	v_exp_f32_e32 v74, v46
	v_sub_f32_e32 v46, v47, v110
	v_sub_f32_e32 v51, v63, v110
	v_sub_f32_e32 v63, v75, v110
	v_exp_f32_e32 v75, v46
	v_sub_f32_e32 v46, v48, v110
	v_sub_f32_e32 v52, v64, v110
	v_sub_f32_e32 v64, v76, v110
	v_exp_f32_e32 v76, v46
	v_sub_f32_e32 v46, v49, v110
	v_exp_f32_e32 v49, v46
	v_sub_f32_e32 v46, v58, v111
	v_exp_f32_e32 v58, v46
	v_sub_f32_e32 v46, v59, v111
	v_sub_f32_e32 v53, v65, v110
	v_exp_f32_e32 v59, v46
	v_sub_f32_e32 v46, v60, v111
	v_exp_f32_e32 v50, v50
	v_exp_f32_e32 v51, v51
	v_exp_f32_e32 v52, v52
	v_exp_f32_e32 v53, v53
	v_exp_f32_e32 v60, v46
	v_sub_f32_e32 v46, v61, v111
	v_sub_f32_e32 v42, v42, v111
	v_sub_f32_e32 v65, v77, v110
	v_exp_f32_e32 v61, v46
	v_sub_f32_e32 v46, v70, v111
	v_exp_f32_e32 v77, v42
	v_sub_f32_e32 v42, v43, v111
	v_sub_f32_e32 v54, v78, v110
	v_exp_f32_e32 v70, v46
	v_sub_f32_e32 v46, v71, v111
	v_exp_f32_e32 v78, v42
	v_sub_f32_e32 v42, v44, v111
	v_sub_f32_e32 v55, v79, v110
	v_exp_f32_e32 v71, v46
	v_sub_f32_e32 v46, v72, v111
	v_exp_f32_e32 v79, v42
	v_sub_f32_e32 v42, v45, v111
	s_mov_b32 s38, s36
	s_mov_b32 s39, s36
	v_sub_f32_e32 v56, v80, v110
	v_sub_f32_e32 v57, v81, v110
	v_exp_f32_e32 v72, v46
	v_sub_f32_e32 v46, v73, v111
	v_exp_f32_e32 v80, v42
	v_cvt_pk_bf16_f32 v42, v50, v51
	v_cvt_pk_bf16_f32 v43, v52, v53
	s_mov_b32 s37, s36
	v_mov_b64_e32 v[52:53], s[38:39]
	v_exp_f32_e32 v54, v54
	v_exp_f32_e32 v55, v55
	v_exp_f32_e32 v56, v56
	v_exp_f32_e32 v57, v57
	v_exp_f32_e32 v73, v46
	v_sub_f32_e32 v46, v66, v111
	v_mov_b64_e32 v[50:51], s[36:37]
	v_exp_f32_e32 v66, v46
	v_sub_f32_e32 v46, v67, v111
	v_exp_f32_e32 v67, v46
	v_sub_f32_e32 v46, v68, v111
	v_exp_f32_e32 v68, v46
	v_sub_f32_e32 v46, v69, v111
	v_exp_f32_e32 v62, v62
	v_exp_f32_e32 v63, v63
	v_exp_f32_e32 v64, v64
	v_exp_f32_e32 v65, v65
	v_exp_f32_e32 v69, v46
	v_cvt_pk_bf16_f32 v44, v54, v55
	v_cvt_pk_bf16_f32 v45, v56, v57
	v_cvt_pk_bf16_f32 v54, v58, v59
	v_cvt_pk_bf16_f32 v55, v60, v61
	v_cvt_pk_bf16_f32 v56, v70, v71
	v_cvt_pk_bf16_f32 v57, v72, v73
	v_mfma_f32_16x16x32_bf16 v[6:9], v[50:53], v[42:45], v[6:9]
	v_cvt_pk_bf16_f32 v46, v62, v63
	v_cvt_pk_bf16_f32 v47, v64, v65
	v_cvt_pk_bf16_f32 v48, v74, v75
	v_mfma_f32_16x16x32_bf16 v[2:5], v[50:53], v[54:57], v[2:5]
	v_cvt_pk_bf16_f32 v49, v76, v49
	v_cvt_pk_bf16_f32 v58, v66, v67
	v_cvt_pk_bf16_f32 v59, v68, v69
	v_cvt_pk_bf16_f32 v60, v77, v78
	v_cvt_pk_bf16_f32 v61, v79, v80
	v_mfma_f32_16x16x32_bf16 v[6:9], v[50:53], v[46:49], v[6:9]
	s_nop 0
	v_mfma_f32_16x16x32_bf16 v[2:5], v[50:53], v[58:61], v[2:5]
	s_setprio 1
	s_nop 6
	v_add3_u32 v3, v150, v123, v106
	v_add_u32_e32 v4, 0x6000, v3
	ds_read2_b64 v[50:53], v4 offset0:128 offset1:132
	s_waitcnt lgkmcnt(0)
	v_mfma_f32_16x16x32_bf16 v[38:41], v[50:53], v[42:45], v[38:41]
	v_mfma_f32_16x16x32_bf16 v[34:37], v[50:53], v[54:57], v[34:37]
	ds_read2_b64 v[50:53], v4 offset0:136 offset1:140
	v_add_u32_e32 v4, 0x6800, v3
	s_waitcnt lgkmcnt(0)
	v_mfma_f32_16x16x32_bf16 v[38:41], v[50:53], v[46:49], v[38:41]
	v_mfma_f32_16x16x32_bf16 v[34:37], v[50:53], v[58:61], v[34:37]
	ds_read2_b64 v[50:53], v4 offset0:160 offset1:164
	s_waitcnt lgkmcnt(0)
	v_mfma_f32_16x16x32_bf16 v[30:33], v[50:53], v[42:45], v[30:33]
	v_mfma_f32_16x16x32_bf16 v[26:29], v[50:53], v[54:57], v[26:29]
	ds_read2_b64 v[50:53], v4 offset0:168 offset1:172
	v_add_u32_e32 v4, 0x7000, v3
	v_add_u32_e32 v3, 0x7800, v3
	s_waitcnt lgkmcnt(0)
	v_mfma_f32_16x16x32_bf16 v[30:33], v[50:53], v[46:49], v[30:33]
	v_mfma_f32_16x16x32_bf16 v[26:29], v[50:53], v[58:61], v[26:29]
	ds_read2_b64 v[50:53], v4 offset0:192 offset1:196
	s_waitcnt lgkmcnt(0)
	v_mfma_f32_16x16x32_bf16 v[18:21], v[50:53], v[42:45], v[18:21]
	v_mfma_f32_16x16x32_bf16 v[22:25], v[50:53], v[54:57], v[22:25]
	ds_read2_b64 v[50:53], v4 offset0:200 offset1:204
	s_waitcnt lgkmcnt(0)
	v_mfma_f32_16x16x32_bf16 v[18:21], v[50:53], v[46:49], v[18:21]
	v_mfma_f32_16x16x32_bf16 v[22:25], v[50:53], v[58:61], v[22:25]
	ds_read2_b64 v[50:53], v3 offset0:224 offset1:228
	s_waitcnt lgkmcnt(0)
	v_mfma_f32_16x16x32_bf16 v[14:17], v[50:53], v[42:45], v[14:17]
	ds_read2_b64 v[42:45], v3 offset0:232 offset1:236
	v_mfma_f32_16x16x32_bf16 v[8:11], v[50:53], v[54:57], v[10:13]
	s_waitcnt lgkmcnt(0)
	v_mfma_f32_16x16x32_bf16 v[12:15], v[42:45], v[46:49], v[14:17]
	v_mfma_f32_16x16x32_bf16 v[8:11], v[42:45], v[58:61], v[8:11]
	s_setprio 0
	v_cmp_gt_u32_e32 vcc, 64, v107
	v_or3_b32 v3, v0, v121, v120
	v_mov_b32_e32 v107, v1
	v_cndmask_b32_e32 v0, v207, v224, vcc
	v_lshl_add_u64 v[4:5], s[54:55], 0, v[0:1]
	v_lshlrev_b32_e32 v0, 1, v122
	v_lshl_add_u64 v[4:5], v[4:5], 0, v[0:1]
	v_div_scale_f32 v0, s[0:1], v6, v6, 1.0
	v_rcp_f32_e32 v7, v0
	v_lshl_add_u64 v[4:5], v[4:5], 0, v[106:107]
	s_barrier
	v_fma_f32 v16, -v0, v7, 1.0
	v_fmac_f32_e32 v7, v16, v7
	v_div_scale_f32 v16, vcc, 1.0, v6, 1.0
	v_mul_f32_e32 v17, v16, v7
	v_fma_f32 v42, -v0, v17, v16
	v_fmac_f32_e32 v17, v42, v7
	v_fma_f32 v0, -v0, v17, v16
	v_div_fmas_f32 v0, v0, v7, v17
	v_div_fixup_f32 v6, v0, v6, 1.0
	v_lshlrev_b32_e32 v0, 11, v3
	v_pk_mul_f32 v[38:39], v[6:7], v[38:39] op_sel_hi:[0,1]
	v_pk_mul_f32 v[40:41], v[6:7], v[40:41] op_sel_hi:[0,1]
	v_pk_mul_f32 v[30:31], v[6:7], v[30:31] op_sel_hi:[0,1]
	v_pk_mul_f32 v[32:33], v[6:7], v[32:33] op_sel_hi:[0,1]
	v_pk_mul_f32 v[18:19], v[6:7], v[18:19] op_sel_hi:[0,1]
	v_pk_mul_f32 v[20:21], v[6:7], v[20:21] op_sel_hi:[0,1]
	v_pk_mul_f32 v[12:13], v[6:7], v[12:13] op_sel_hi:[0,1]
	v_pk_mul_f32 v[6:7], v[6:7], v[14:15] op_sel_hi:[0,1]
	v_div_scale_f32 v3, s[0:1], v2, v2, 1.0
	v_cvt_pk_bf16_f32 v12, v12, v13
	v_cvt_pk_bf16_f32 v13, v6, v7
	v_rcp_f32_e32 v6, v3
	v_lshl_add_u64 v[16:17], v[4:5], 0, v[0:1]
	global_store_dwordx2 v[16:17], v[12:13], off offset:96
	v_fma_f32 v7, -v3, v6, 1.0
	v_fmac_f32_e32 v6, v7, v6
	v_div_scale_f32 v7, vcc, 1.0, v2, 1.0
	v_mul_f32_e32 v12, v7, v6
	v_fma_f32 v13, -v3, v12, v7
	v_fmac_f32_e32 v12, v13, v6
	v_fma_f32 v3, -v3, v12, v7
	v_div_fmas_f32 v3, v3, v6, v12
	v_div_fixup_f32 v2, v3, v2, 1.0
	v_or_b32_e32 v0, 0x8000, v0
	v_pk_mul_f32 v[6:7], v[2:3], v[34:35] op_sel_hi:[0,1]
	v_pk_mul_f32 v[12:13], v[2:3], v[36:37] op_sel_hi:[0,1]
	v_cvt_pk_bf16_f32 v38, v38, v39
	v_cvt_pk_bf16_f32 v39, v40, v41
	v_cvt_pk_bf16_f32 v30, v30, v31
	v_cvt_pk_bf16_f32 v31, v32, v33
	v_cvt_pk_bf16_f32 v18, v18, v19
	v_cvt_pk_bf16_f32 v19, v20, v21
	v_lshl_add_u64 v[4:5], v[4:5], 0, v[0:1]
	v_cvt_pk_bf16_f32 v6, v6, v7
	v_cvt_pk_bf16_f32 v7, v12, v13
	global_store_dwordx2 v[16:17], v[38:39], off
	global_store_dwordx2 v[16:17], v[30:31], off offset:32
	global_store_dwordx2 v[16:17], v[18:19], off offset:64
	global_store_dwordx2 v[4:5], v[6:7], off
	v_pk_mul_f32 v[6:7], v[2:3], v[26:27] op_sel_hi:[0,1]
	v_pk_mul_f32 v[12:13], v[2:3], v[28:29] op_sel_hi:[0,1]
	v_cvt_pk_bf16_f32 v6, v6, v7
	v_cvt_pk_bf16_f32 v7, v12, v13
	global_store_dwordx2 v[4:5], v[6:7], off offset:32
	v_pk_mul_f32 v[6:7], v[2:3], v[22:23] op_sel_hi:[0,1]
	v_pk_mul_f32 v[12:13], v[2:3], v[24:25] op_sel_hi:[0,1]
	v_cvt_pk_bf16_f32 v6, v6, v7
	v_cvt_pk_bf16_f32 v7, v12, v13
	global_store_dwordx2 v[4:5], v[6:7], off offset:64
	v_pk_mul_f32 v[6:7], v[2:3], v[8:9] op_sel_hi:[0,1]
	v_pk_mul_f32 v[2:3], v[2:3], v[10:11] op_sel_hi:[0,1]
	v_cvt_pk_bf16_f32 v6, v6, v7
	v_cvt_pk_bf16_f32 v7, v2, v3
	global_store_dwordx2 v[4:5], v[6:7], off offset:96

.LBB0_1255:
	s_andn2_b64 vcc, exec, s[0:1]
	s_cbranch_vccnz .LBB0_1272
	s_lshl_b32 s0, s22, 1
	s_addk_i32 s0, 0xfab0
	v_add_u32_e32 v0, s0, v149
	v_ashrrev_i32_e32 v2, 7, v0
	v_mov_b32_e32 v20, v201
	s_movk_i32 s0, 0x1100
	v_bfe_u32 v8, v0, 6, 1
	v_and_b32_e32 v146, 63, v0
	v_mul_lo_u32 v108, v2, s0
	v_bfe_u32 v0, v20, 7, 1
	v_lshl_or_b32 v22, v8, 1, v0
	v_lshrrev_b32_e32 v0, 1, v20
	v_ashrrev_i32_e32 v109, 31, v108
	s_mov_b64 s[0:1], 0x8800
	v_and_b32_e32 v0, 32, v0
	v_lshl_add_u64 v[4:5], v[108:109], 0, s[0:1]
	v_lshl_or_b32 v0, v146, 6, v0
	v_lshlrev_b64 v[6:7], 9, v[4:5]
	v_add_u32_e32 v106, 0x100, v0
	v_lshl_add_u64 v[6:7], s[42:43], 0, v[6:7]
	v_lshlrev_b32_e32 v0, 7, v22
	v_lshlrev_b64 v[4:5], 8, v[4:5]
	v_and_b32_e32 v111, 15, v20
	v_bfe_u32 v21, v20, 4, 2
	v_lshl_add_u64 v[6:7], v[6:7], 0, v[0:1]
	v_lshl_add_u64 v[4:5], s[58:59], 0, v[4:5]
	v_lshlrev_b32_e32 v0, 7, v8
	v_ashrrev_i32_e32 v3, 31, v2
	v_lshl_add_u64 v[4:5], v[4:5], 0, v[0:1]
	v_lshlrev_b64 v[2:3], 7, v[2:3]
	v_or_b32_e32 v23, v106, v111
	v_lshlrev_b32_e32 v0, 4, v21
	v_lshl_or_b32 v2, v8, 6, v2
	s_mov_b64 s[0:1], 0x400
	v_lshl_add_u64 v[6:7], v[6:7], 0, v[0:1]
	v_lshlrev_b32_e32 v0, 9, v23
	v_lshl_add_u64 v[2:3], v[2:3], 0, s[0:1]
	v_lshl_add_u64 v[6:7], v[6:7], 0, v[0:1]
	s_movk_i32 s0, 0x2000
	global_load_dwordx4 v[46:49], v[6:7], off
	global_load_dwordx4 v[42:45], v[6:7], off offset:64
	v_add_co_u32_e32 v6, vcc, s0, v6
	v_readlane_b32 s0, v254, 62
	s_nop 0
	v_addc_co_u32_e32 v7, vcc, 0, v7, vcc
	v_or_b32_e32 v0, s0, v22
	global_load_dwordx4 v[50:53], v[6:7], off
	global_load_dwordx4 v[54:57], v[6:7], off offset:64
	v_lshl_add_u64 v[6:7], v[0:1], 2, s[8:9]
	v_mov_b32 v125, 0xf149f2ca
	global_load_dword v24, v[6:7], off
	v_mov_b64_e32 v[6:7], s[44:45]
	v_and_b32_e32 v25, 7, v20
	v_mad_u64_u32 v[6:7], s[0:1], v2, s85, v[6:7]
	v_bfe_u32 v163, v20, 3, 5
	v_lshlrev_b32_e32 v112, 4, v25
	v_mov_b32_e32 v113, v1
	v_mad_i32_i24 v7, v3, s85, v7
	v_lshl_add_u64 v[114:115], v[4:5], 0, v[112:113]
	v_lshlrev_b32_e32 v0, 8, v163
	v_or_b32_e32 v26, 32, v163
	v_lshl_add_u64 v[18:19], v[6:7], 0, v[112:113]
	v_lshl_add_u64 v[2:3], v[114:115], 0, v[0:1]
	v_lshlrev_b32_e32 v0, 8, v26
	v_mad_u64_u32 v[6:7], s[0:1], v163, s85, v[18:19]
	v_lshl_add_u64 v[10:11], v[114:115], 0, v[0:1]
	v_mad_u64_u32 v[14:15], s[0:1], v26, s85, v[18:19]
	global_load_dwordx4 v[2:5], v[2:3], off
	s_nop 0
	global_load_dwordx4 v[6:9], v[6:7], off
	s_nop 0
	global_load_dwordx4 v[10:13], v[10:11], off
	s_nop 0
	global_load_dwordx4 v[14:17], v[14:15], off
	v_lshrrev_b32_e32 v0, 4, v20
	v_xor_b32_e32 v20, v163, v20
	v_lshlrev_b32_e32 v20, 4, v20
	v_and_b32_e32 v170, 0x70, v20
	v_lshlrev_b32_e32 v165, 7, v163
	v_add_u32_e32 v20, v150, v170
	v_mul_u32_u24_e32 v166, 0x90, v163
	v_bitop3_b32 v0, v0, v25, 3 bitop3:0x6c
	v_lshlrev_b32_e32 v168, 7, v26
	v_lshlrev_b32_e32 v110, 6, v22
	v_add_u32_e32 v22, v20, v165
	v_add3_u32 v27, v150, v112, v166
	v_add_u32_e32 v20, v20, v168
	v_lshlrev_b32_e32 v171, 4, v0
	v_bitop3_b32 v0, v21, v25, 4 bitop3:0x36
	v_lshlrev_b32_e32 v172, 4, v0
	v_xor_b32_e32 v0, 16, v208
	v_lshlrev_b32_e32 v113, 2, v21
	v_add_u32_e32 v144, 0x80, v23
	v_add_u32_e32 v128, 0x90, v23
	v_lshlrev_b32_e32 v107, 3, v21
	v_mov_b32_e32 v38, 1.0
	s_mov_b32 s6, 0
	v_lshlrev_b32_e32 v167, 7, v111
	v_add_u32_e32 v169, -2, v146
	v_mul_u32_u24_e32 v124, 0x90, v111
	v_sub_u32_e32 v145, v144, v113
	v_sub_u32_e32 v129, v128, v113
	v_add_u32_e32 v173, -1, v146
	s_waitcnt vmcnt(0) lgkmcnt(0)
	ds_write_b128 v22, v[2:5]
	ds_write_b128 v27, v[6:9] offset:8192
	ds_write_b128 v20, v[10:13]
	ds_write_b128 v27, v[14:17] offset:12800
	v_and_b32_e32 v2, 64, v208
	v_add_u32_e32 v2, 64, v2
	v_cmp_lt_i32_e32 vcc, v0, v2
	v_xor_b32_e32 v3, -3, v113
	v_xor_b32_e32 v6, 0xffffffee, v113
	v_cndmask_b32_e32 v0, v208, v0, vcc
	v_lshlrev_b32_e32 v126, 2, v0
	v_xor_b32_e32 v0, 32, v208
	v_cmp_lt_i32_e32 vcc, v0, v2
	v_xor_b32_e32 v2, -2, v113
	v_xor_b32_e32 v7, 0xffffffed, v113
	v_cndmask_b32_e32 v0, v208, v0, vcc
	v_lshlrev_b32_e32 v127, 2, v0
	v_mul_u32_u24_e32 v0, 0x1100, v163
	v_sub_u32_e32 v8, 0xffffffe0, v113
	v_xor_b32_e32 v9, 0xffffffdf, v113
	v_xor_b32_e32 v10, 0xffffffde, v113
	v_xor_b32_e32 v11, 0xffffffdd, v113
	v_sub_u32_e32 v12, 0xffffffd0, v113
	v_xor_b32_e32 v13, 0xffffffcf, v113
	v_xor_b32_e32 v14, 0xffffffce, v113
	v_xor_b32_e32 v15, 0xffffffcd, v113
	v_add_u32_e32 v147, v144, v2
	v_add_u32_e32 v151, v144, v3
	v_add_u32_e32 v130, v128, v2
	v_add_u32_e32 v131, v128, v3
	v_lshlrev_b32_e32 v0, 1, v0
	v_mov_b32_e32 v2, v1
	v_mov_b32_e32 v3, v1
	v_mul_f32_e32 v120, 0x3fb8aa3b, v24
	v_sub_u32_e32 v4, -16, v113
	v_xor_b32_e32 v5, 0xffffffef, v113
	v_add_u32_e32 v154, v144, v6
	v_add_u32_e32 v155, v144, v7
	v_add_u32_e32 v156, v144, v8
	v_add_u32_e32 v157, v144, v9
	v_add_u32_e32 v158, v144, v10
	v_add_u32_e32 v159, v144, v11
	v_add_u32_e32 v160, v144, v12
	v_add_u32_e32 v161, v144, v13
	v_add_u32_e32 v162, v144, v14
	v_add_u32_e32 v164, v144, v15
	v_add_u32_e32 v134, v128, v6
	v_add_u32_e32 v135, v128, v7
	v_add_u32_e32 v136, v128, v8
	v_add_u32_e32 v137, v128, v9
	v_add_u32_e32 v138, v128, v10
	v_add_u32_e32 v139, v128, v11
	v_add_u32_e32 v140, v128, v12
	v_add_u32_e32 v141, v128, v13
	v_add_u32_e32 v142, v128, v14
	v_add_u32_e32 v143, v128, v15
	v_lshl_add_u64 v[116:117], v[18:19], 0, v[0:1]
	v_mov_b32_e32 v0, v1
	v_mov_b64_e32 v[20:21], v[2:3]
	v_mov_b64_e32 v[24:25], v[2:3]
	v_mov_b64_e32 v[28:29], v[2:3]
	v_mov_b64_e32 v[32:33], v[2:3]
	v_mov_b64_e32 v[12:13], v[2:3]
	v_mov_b64_e32 v[16:17], v[2:3]
	v_mov_b64_e32 v[8:9], v[2:3]
	v_add_u32_e32 v152, v144, v4
	v_add_u32_e32 v153, v144, v5
	v_add_u32_e32 v132, v128, v4
	v_add_u32_e32 v133, v128, v5
	v_mov_b64_e32 v[18:19], v[0:1]
	v_mov_b64_e32 v[22:23], v[0:1]
	v_mov_b64_e32 v[26:27], v[0:1]
	v_mov_b64_e32 v[30:31], v[0:1]
	v_mov_b64_e32 v[10:11], v[0:1]
	v_mov_b64_e32 v[14:15], v[0:1]
	v_mov_b64_e32 v[6:7], v[0:1]
	v_mov_b64_e32 v[4:5], v[2:3]
	v_mov_b32_e32 v121, v120
	v_mov_b64_e32 v[2:3], v[0:1]
	v_mov_b32_e32 v39, v38
	v_mov_b32_e32 v40, v38
	v_mov_b32_e32 v41, v38
	v_mov_b32_e32 v34, v38
	v_mov_b32_e32 v35, v38
	v_mov_b32_e32 v36, v38
	v_mov_b32_e32 v37, v38
	s_waitcnt lgkmcnt(0)
	s_barrier
.LBB0_1257:
	s_cmp_lt_u32 s6, 4
	s_cselect_b64 vcc, -1, 0
	s_mov_b32 s4, s6
	v_cndmask_b32_e64 v0, v169, 0, vcc
	v_add_u32_e32 v0, s4, v0
	v_add_u32_e32 v58, -4, v0
	v_cmp_gt_u32_e64 s[0:1], 64, v58
	s_or_b64 s[2:3], vcc, s[0:1]
	s_bitcmp1_b32 s6, 0
	v_mov_b32_e32 v58, s6
	s_cselect_b32 s0, 0x4400, 0
	s_add_i32 s6, s6, 1
	v_med3_i32 v0, v0, 4, v227
	s_cmp_lt_u32 s4, 3
	v_cndmask_b32_e32 v118, v0, v58, vcc
	s_cselect_b64 vcc, -1, 0
	v_add_u32_e32 v0, s4, v173
	v_mov_b32_e32 v58, s6
	v_cndmask_b32_e32 v0, v0, v58, vcc
	v_med3_i32 v0, v0, 4, v227
	v_cndmask_b32_e32 v62, v0, v58, vcc
	v_lshl_or_b32 v0, v62, 6, v163
	v_lshlrev_b32_e32 v0, 8, v0
	v_add_u32_e32 v174, s0, v150
	v_lshl_add_u64 v[66:67], v[114:115], 0, v[0:1]
	s_movk_i32 s0, 0x2000
	global_load_dwordx4 v[58:61], v[66:67], off
	v_lshlrev_b32_e32 v0, 7, v62
	v_add_co_u32_e32 v66, vcc, s0, v66
	v_lshl_add_u64 v[70:71], v[116:117], 0, v[0:1]
	s_nop 0
	v_addc_co_u32_e32 v67, vcc, 0, v67, vcc
	s_mov_b32 s0, 0x44000
	global_load_dwordx4 v[62:65], v[70:71], off
	v_add_co_u32_e32 v70, vcc, s0, v70
	global_load_dwordx4 v[66:69], v[66:67], off
	s_nop 0
	v_addc_co_u32_e32 v71, vcc, 0, v71, vcc
	global_load_dwordx4 v[70:73], v[70:71], off
	s_setprio 1
	v_add_u32_e32 v0, v174, v167
	v_add_u32_e32 v102, v0, v171
	ds_read_b128 v[74:77], v102
	ds_read_b128 v[82:85], v102 offset:2048
	v_add_u32_e32 v0, v0, v172
	ds_read_b128 v[86:89], v0
	ds_read_b128 v[98:101], v0 offset:2048
	s_waitcnt lgkmcnt(0)
	v_mfma_f32_16x16x32_bf16 v[78:81], v[74:77], v[46:49], 0
	v_mfma_f32_16x16x32_bf16 v[74:77], v[74:77], v[50:53], 0
	v_mfma_f32_16x16x32_bf16 v[94:97], v[86:89], v[42:45], v[78:81]
	v_mfma_f32_16x16x32_bf16 v[78:81], v[86:89], v[54:57], v[74:77]
	v_mfma_f32_16x16x32_bf16 v[74:77], v[82:85], v[46:49], 0
	v_mfma_f32_16x16x32_bf16 v[90:93], v[98:101], v[42:45], v[74:77]
	v_mfma_f32_16x16x32_bf16 v[74:77], v[82:85], v[50:53], 0
	ds_read_b128 v[82:85], v102 offset:4096
	ds_read_b128 v[176:179], v102 offset:6144
	v_mfma_f32_16x16x32_bf16 v[74:77], v[98:101], v[54:57], v[74:77]
	ds_read_b128 v[98:101], v0 offset:4096
	ds_read_b128 v[180:183], v0 offset:6144
	s_waitcnt lgkmcnt(0)
	v_mfma_f32_16x16x32_bf16 v[86:89], v[82:85], v[46:49], 0
	v_mfma_f32_16x16x32_bf16 v[82:85], v[82:85], v[50:53], 0
	v_mfma_f32_16x16x32_bf16 v[102:105], v[98:101], v[42:45], v[86:89]
	v_mfma_f32_16x16x32_bf16 v[86:89], v[98:101], v[54:57], v[82:85]
	v_mfma_f32_16x16x32_bf16 v[82:85], v[176:179], v[46:49], 0
	v_mfma_f32_16x16x32_bf16 v[98:101], v[180:183], v[42:45], v[82:85]
	v_mfma_f32_16x16x32_bf16 v[82:85], v[176:179], v[50:53], 0
	v_mfma_f32_16x16x32_bf16 v[82:85], v[180:183], v[54:57], v[82:85]
	s_setprio 0
	v_lshlrev_b32_e32 v0, 6, v118
	v_cmp_lt_u32_e64 s[0:1], 3, v118
	v_sub_u32_e32 v0, 0, v0
	s_and_saveexec_b64 s[4:5], s[0:1]
	s_cbranch_execz .LBB0_1259
	v_add_u32_e32 v118, v145, v0
	v_cmp_gt_u32_e32 vcc, s51, v118
	v_add_u32_e32 v118, v144, v0
	s_and_b64 vcc, vcc, s[2:3]
	v_sub_u32_e32 v118, v113, v118
	s_movk_i32 s7, 0xfefe
	v_cndmask_b32_e32 v94, v125, v94, vcc
	v_cmp_lt_u32_e32 vcc, s7, v118
	s_and_b64 vcc, vcc, s[2:3]
	v_add_u32_e32 v118, v147, v0
	v_cndmask_b32_e32 v95, v125, v95, vcc
	v_cmp_gt_u32_e32 vcc, s51, v118
	s_and_b64 vcc, vcc, s[2:3]
	v_add_u32_e32 v118, v151, v0
	v_cndmask_b32_e32 v96, v125, v96, vcc
	v_cmp_gt_u32_e32 vcc, s51, v118
	s_and_b64 vcc, vcc, s[2:3]
	v_add_u32_e32 v118, v152, v0
	v_cndmask_b32_e32 v97, v125, v97, vcc
	v_cmp_gt_u32_e32 vcc, s51, v118
	s_and_b64 vcc, vcc, s[2:3]
	v_add_u32_e32 v118, v153, v0
	v_cndmask_b32_e32 v90, v125, v90, vcc
	v_cmp_gt_u32_e32 vcc, s51, v118
	s_and_b64 vcc, vcc, s[2:3]
	v_add_u32_e32 v118, v154, v0
	v_cndmask_b32_e32 v91, v125, v91, vcc
	v_cmp_gt_u32_e32 vcc, s51, v118
	s_and_b64 vcc, vcc, s[2:3]
	v_add_u32_e32 v118, v155, v0
	v_cndmask_b32_e32 v92, v125, v92, vcc
	v_cmp_gt_u32_e32 vcc, s51, v118
	s_and_b64 vcc, vcc, s[2:3]
	v_add_u32_e32 v118, v156, v0
	v_cndmask_b32_e32 v93, v125, v93, vcc
	v_cmp_gt_u32_e32 vcc, s51, v118
	s_and_b64 vcc, vcc, s[2:3]
	v_add_u32_e32 v118, v157, v0
	v_cndmask_b32_e32 v102, v125, v102, vcc
	v_cmp_gt_u32_e32 vcc, s51, v118
	s_and_b64 vcc, vcc, s[2:3]
	v_add_u32_e32 v118, v158, v0
	v_cndmask_b32_e32 v103, v125, v103, vcc
	v_cmp_gt_u32_e32 vcc, s51, v118
	s_and_b64 vcc, vcc, s[2:3]
	v_add_u32_e32 v118, v159, v0
	v_cndmask_b32_e32 v104, v125, v104, vcc
	v_cmp_gt_u32_e32 vcc, s51, v118
	s_and_b64 vcc, vcc, s[2:3]
	v_add_u32_e32 v118, v160, v0
	v_cndmask_b32_e32 v105, v125, v105, vcc
	v_cmp_gt_u32_e32 vcc, s51, v118
	s_and_b64 vcc, vcc, s[2:3]
	v_add_u32_e32 v118, v161, v0
	v_cndmask_b32_e32 v98, v125, v98, vcc
	v_cmp_gt_u32_e32 vcc, s51, v118
	s_and_b64 vcc, vcc, s[2:3]
	v_add_u32_e32 v118, v162, v0
	v_cndmask_b32_e32 v99, v125, v99, vcc
	v_cmp_gt_u32_e32 vcc, s51, v118
	s_and_b64 vcc, vcc, s[2:3]
	v_add_u32_e32 v118, v164, v0
	v_cndmask_b32_e32 v100, v125, v100, vcc
	v_cmp_gt_u32_e32 vcc, s51, v118
	s_and_b64 vcc, vcc, s[2:3]
	s_nop 0
	v_cndmask_b32_e32 v101, v125, v101, vcc

.LBB0_1271:
	v_sub_f32_e32 v46, v46, v118
	v_exp_f32_e32 v73, v46
	v_sub_f32_e32 v46, v47, v118
	v_exp_f32_e32 v74, v46
	v_sub_f32_e32 v46, v48, v118
	v_exp_f32_e32 v75, v46
	v_sub_f32_e32 v46, v58, v119
	v_exp_f32_e32 v58, v46
	v_sub_f32_e32 v46, v59, v119
	v_exp_f32_e32 v59, v46
	v_sub_f32_e32 v46, v60, v119
	v_exp_f32_e32 v60, v46
	v_sub_f32_e32 v46, v61, v119
	v_exp_f32_e32 v61, v46
	v_sub_f32_e32 v46, v62, v119
	v_exp_f32_e32 v62, v46
	v_sub_f32_e32 v46, v63, v119
	v_exp_f32_e32 v63, v46
	v_sub_f32_e32 v46, v64, v119
	v_sub_f32_e32 v53, v53, v118
	v_sub_f32_e32 v54, v54, v118
	v_sub_f32_e32 v49, v49, v118
	v_sub_f32_e32 v50, v50, v118
	v_sub_f32_e32 v51, v51, v118
	v_sub_f32_e32 v52, v52, v118
	v_exp_f32_e32 v64, v46
	v_sub_f32_e32 v46, v65, v119
	v_exp_f32_e32 v53, v53
	v_exp_f32_e32 v54, v54
	v_exp_f32_e32 v49, v49
	v_exp_f32_e32 v50, v50
	v_exp_f32_e32 v51, v51
	v_exp_f32_e32 v52, v52
	v_exp_f32_e32 v65, v46
	v_sub_f32_e32 v46, v66, v119
	v_exp_f32_e32 v66, v46
	v_sub_f32_e32 v46, v67, v119
	v_exp_f32_e32 v67, v46
	v_sub_f32_e32 v46, v68, v119
	v_sub_f32_e32 v42, v42, v119
	v_exp_f32_e32 v68, v46
	v_sub_f32_e32 v46, v69, v119
	v_exp_f32_e32 v76, v42
	v_sub_f32_e32 v42, v43, v119
	s_mov_b32 s38, s36
	s_mov_b32 s39, s36
	v_sub_f32_e32 v57, v57, v118
	v_sub_f32_e32 v70, v70, v118
	v_sub_f32_e32 v71, v71, v118
	v_sub_f32_e32 v72, v72, v118
	v_sub_f32_e32 v55, v55, v118
	v_sub_f32_e32 v56, v56, v118
	v_exp_f32_e32 v69, v46
	v_exp_f32_e32 v77, v42
	v_sub_f32_e32 v42, v44, v119
	v_cvt_pk_bf16_f32 v44, v53, v54
	v_cvt_pk_bf16_f32 v46, v49, v50
	v_cvt_pk_bf16_f32 v47, v51, v52
	s_mov_b32 s37, s36
	v_mov_b64_e32 v[52:53], s[38:39]
	v_exp_f32_e32 v57, v57
	v_exp_f32_e32 v70, v70
	v_exp_f32_e32 v71, v71
	v_exp_f32_e32 v72, v72
	v_exp_f32_e32 v55, v55
	v_exp_f32_e32 v56, v56
	v_mov_b64_e32 v[50:51], s[36:37]
	v_sub_f32_e32 v0, v0, v118
	v_exp_f32_e32 v78, v42
	v_sub_f32_e32 v42, v45, v119
	v_exp_f32_e32 v0, v0
	v_exp_f32_e32 v79, v42
	v_cvt_pk_bf16_f32 v42, v57, v70
	v_cvt_pk_bf16_f32 v43, v71, v72
	v_cvt_pk_bf16_f32 v45, v55, v56
	v_cvt_pk_bf16_f32 v54, v58, v59
	v_cvt_pk_bf16_f32 v55, v60, v61
	v_cvt_pk_bf16_f32 v56, v62, v63
	v_cvt_pk_bf16_f32 v57, v64, v65
	v_mfma_f32_16x16x32_bf16 v[38:41], v[50:53], v[42:45], v[38:41]
	v_cvt_pk_bf16_f32 v48, v0, v73
	v_cvt_pk_bf16_f32 v49, v74, v75
	v_cvt_pk_bf16_f32 v58, v66, v67
	v_mfma_f32_16x16x32_bf16 v[34:37], v[50:53], v[54:57], v[34:37]
	v_cvt_pk_bf16_f32 v59, v68, v69
	v_cvt_pk_bf16_f32 v60, v76, v77
	v_cvt_pk_bf16_f32 v61, v78, v79
	v_mfma_f32_16x16x32_bf16 v[38:41], v[50:53], v[46:49], v[38:41]
	s_nop 0
	v_mfma_f32_16x16x32_bf16 v[34:37], v[50:53], v[58:61], v[34:37]
	s_setprio 1
	v_add3_u32 v0, v150, v124, v107
	s_nop 5
	v_add_u32_e32 v35, 0x2000, v0
	ds_read2_b64 v[50:53], v35 offset1:4
	s_waitcnt lgkmcnt(0)
	v_mfma_f32_16x16x32_bf16 v[30:33], v[50:53], v[42:45], v[30:33]
	v_mfma_f32_16x16x32_bf16 v[26:29], v[50:53], v[54:57], v[26:29]
	ds_read2_b64 v[50:53], v35 offset0:8 offset1:12
	v_add_u32_e32 v35, 0x2800, v0
	s_waitcnt lgkmcnt(0)
	v_mfma_f32_16x16x32_bf16 v[30:33], v[50:53], v[46:49], v[30:33]
	v_mfma_f32_16x16x32_bf16 v[26:29], v[50:53], v[58:61], v[26:29]
	ds_read2_b64 v[50:53], v35 offset0:32 offset1:36
	s_waitcnt lgkmcnt(0)
	v_mfma_f32_16x16x32_bf16 v[22:25], v[50:53], v[42:45], v[22:25]
	v_mfma_f32_16x16x32_bf16 v[18:21], v[50:53], v[54:57], v[18:21]
	ds_read2_b64 v[50:53], v35 offset0:40 offset1:44
	v_add_u32_e32 v35, 0x3000, v0
	v_add_u32_e32 v0, 0x3800, v0
	s_waitcnt lgkmcnt(0)
	v_mfma_f32_16x16x32_bf16 v[22:25], v[50:53], v[46:49], v[22:25]
	v_mfma_f32_16x16x32_bf16 v[18:21], v[50:53], v[58:61], v[18:21]
	ds_read2_b64 v[50:53], v35 offset0:64 offset1:68
	s_waitcnt lgkmcnt(0)
	v_mfma_f32_16x16x32_bf16 v[10:13], v[50:53], v[42:45], v[10:13]
	v_mfma_f32_16x16x32_bf16 v[14:17], v[50:53], v[54:57], v[14:17]
	ds_read2_b64 v[50:53], v35 offset0:72 offset1:76
	s_waitcnt lgkmcnt(0)
	v_mfma_f32_16x16x32_bf16 v[10:13], v[50:53], v[46:49], v[10:13]
	v_mfma_f32_16x16x32_bf16 v[14:17], v[50:53], v[58:61], v[14:17]
	ds_read2_b64 v[50:53], v0 offset0:96 offset1:100
	s_waitcnt lgkmcnt(0)
	v_mfma_f32_16x16x32_bf16 v[6:9], v[50:53], v[42:45], v[6:9]
	ds_read2_b64 v[40:43], v0 offset0:104 offset1:108
	v_mfma_f32_16x16x32_bf16 v[2:5], v[50:53], v[54:57], v[2:5]
	s_waitcnt lgkmcnt(0)
	v_mfma_f32_16x16x32_bf16 v[6:9], v[40:43], v[46:49], v[6:9]
	v_mfma_f32_16x16x32_bf16 v[2:5], v[40:43], v[58:61], v[2:5]
	s_setprio 0
	v_div_scale_f32 v35, s[0:1], v38, v38, 1.0
	v_rcp_f32_e32 v39, v35
	v_lshlrev_b32_e32 v0, 1, v110
	v_lshl_add_u64 v[40:41], s[72:73], 0, v[0:1]
	v_lshlrev_b32_e32 v0, 1, v113
	v_lshl_add_u64 v[40:41], v[40:41], 0, v[0:1]
	v_fma_f32 v0, -v35, v39, 1.0
	v_fmac_f32_e32 v39, v0, v39
	v_div_scale_f32 v0, vcc, 1.0, v38, 1.0
	v_mul_f32_e32 v42, v0, v39
	v_fma_f32 v43, -v35, v42, v0
	v_fmac_f32_e32 v42, v43, v39
	v_mov_b32_e32 v107, v1
	v_fma_f32 v0, -v35, v42, v0
	v_lshl_add_u64 v[36:37], v[106:107], 0, v[108:109]
	v_div_fmas_f32 v0, v0, v39, v42
	v_or_b32_e32 v36, v36, v111
	v_div_fixup_f32 v0, v0, v38, 1.0
	v_lshlrev_b64 v[36:37], 11, v[36:37]
	v_pk_mul_f32 v[10:11], v[0:1], v[10:11] op_sel_hi:[0,1]
	v_pk_mul_f32 v[12:13], v[0:1], v[12:13] op_sel_hi:[0,1]
	v_lshl_add_u64 v[38:39], v[40:41], 0, v[36:37]
	v_cvt_pk_bf16_f32 v10, v10, v11
	v_cvt_pk_bf16_f32 v11, v12, v13
	s_barrier
	global_store_dwordx2 v[38:39], v[10:11], off offset:64
	v_div_scale_f32 v10, s[0:1], v34, v34, 1.0
	v_rcp_f32_e32 v11, v10
	v_pk_mul_f32 v[30:31], v[0:1], v[30:31] op_sel_hi:[0,1]
	v_pk_mul_f32 v[32:33], v[0:1], v[32:33] op_sel_hi:[0,1]
	v_pk_mul_f32 v[22:23], v[0:1], v[22:23] op_sel_hi:[0,1]
	v_pk_mul_f32 v[24:25], v[0:1], v[24:25] op_sel_hi:[0,1]
	v_pk_mul_f32 v[6:7], v[0:1], v[6:7] op_sel_hi:[0,1]
	v_pk_mul_f32 v[8:9], v[0:1], v[8:9] op_sel_hi:[0,1]
	v_fma_f32 v0, -v10, v11, 1.0
	v_cvt_pk_bf16_f32 v6, v6, v7
	v_cvt_pk_bf16_f32 v7, v8, v9
	v_fmac_f32_e32 v11, v0, v11
	v_div_scale_f32 v0, vcc, 1.0, v34, 1.0
	global_store_dwordx2 v[38:39], v[6:7], off offset:96
	v_mul_f32_e32 v6, v0, v11
	v_fma_f32 v7, -v10, v6, v0
	v_fmac_f32_e32 v6, v7, v11
	v_fma_f32 v0, -v10, v6, v0
	v_div_fmas_f32 v0, v0, v11, v6
	v_div_fixup_f32 v0, v0, v34, 1.0
	v_or_b32_e32 v36, 0x8000, v36
	v_pk_mul_f32 v[8:9], v[0:1], v[26:27] op_sel_hi:[0,1]
	v_pk_mul_f32 v[10:11], v[0:1], v[28:29] op_sel_hi:[0,1]
	v_cvt_pk_bf16_f32 v30, v30, v31
	v_cvt_pk_bf16_f32 v31, v32, v33
	v_cvt_pk_bf16_f32 v22, v22, v23
	v_cvt_pk_bf16_f32 v23, v24, v25
	v_lshl_add_u64 v[6:7], v[40:41], 0, v[36:37]
	v_cvt_pk_bf16_f32 v8, v8, v9
	v_cvt_pk_bf16_f32 v9, v10, v11
	global_store_dwordx2 v[38:39], v[30:31], off
	global_store_dwordx2 v[38:39], v[22:23], off offset:32
	global_store_dwordx2 v[6:7], v[8:9], off
	v_pk_mul_f32 v[8:9], v[0:1], v[18:19] op_sel_hi:[0,1]
	v_pk_mul_f32 v[10:11], v[0:1], v[20:21] op_sel_hi:[0,1]
	v_cvt_pk_bf16_f32 v8, v8, v9
	v_cvt_pk_bf16_f32 v9, v10, v11
	global_store_dwordx2 v[6:7], v[8:9], off offset:32
	v_pk_mul_f32 v[8:9], v[0:1], v[14:15] op_sel_hi:[0,1]
	v_pk_mul_f32 v[10:11], v[0:1], v[16:17] op_sel_hi:[0,1]
	v_pk_mul_f32 v[2:3], v[0:1], v[2:3] op_sel_hi:[0,1]
	v_pk_mul_f32 v[4:5], v[0:1], v[4:5] op_sel_hi:[0,1]
	v_cvt_pk_bf16_f32 v8, v8, v9
	v_cvt_pk_bf16_f32 v9, v10, v11
	v_cvt_pk_bf16_f32 v2, v2, v3
	v_cvt_pk_bf16_f32 v3, v4, v5
	global_store_dwordx2 v[6:7], v[8:9], off offset:64
	global_store_dwordx2 v[6:7], v[2:3], off offset:96

.LBB0_1273:
	s_andn2_b64 vcc, exec, s[0:1]
	s_cbranch_vccnz .LBB0_1287
	s_lshl_b32 s0, s22, 1
	s_addk_i32 s0, 0xfeb0
	v_mov_b32_e32 v20, v201
	v_add_u32_e32 v8, s0, v149
	v_lshlrev_b32_e32 v0, 6, v8
	v_lshrrev_b32_e32 v6, 1, v20
	v_and_b32_e32 v2, 32, v6
	s_movk_i32 s0, 0xfc0
	v_ashrrev_i32_e32 v106, 7, v8
	v_bfe_u32 v5, v8, 6, 1
	v_and_or_b32 v0, v0, s0, v2
	v_mov_b64_e32 v[2:3], s[42:43]
	s_mov_b32 s0, 0x220000
	v_mad_i64_i32 v[2:3], s[0:1], v106, s0, v[2:3]
	v_lshlrev_b32_e32 v4, 7, v5
	v_and_or_b32 v110, v6, 64, v4
	v_mov_b64_e32 v[6:7], s[58:59]
	s_mov_b32 s0, 0x110000
	v_add_u32_e32 v108, 0x100, v0
	v_lshlrev_b32_e32 v0, 1, v110
	v_mad_i64_i32 v[6:7], s[0:1], v106, s0, v[6:7]
	v_and_b32_e32 v107, 15, v20
	v_bfe_u32 v21, v20, 4, 2
	v_lshl_add_u64 v[2:3], v[2:3], 0, v[0:1]
	v_lshlrev_b32_e32 v0, 6, v5
	v_mov_b32_e32 v5, v1
	s_movk_i32 s0, 0xff80
	v_lshl_add_u64 v[4:5], v[6:7], 0, v[4:5]
	v_and_or_b32 v6, v8, s0, v0
	v_or_b32_e32 v7, v108, v107
	v_lshlrev_b32_e32 v0, 4, v21
	v_lshl_add_u64 v[2:3], v[2:3], 0, v[0:1]
	v_lshlrev_b32_e32 v0, 9, v7
	v_lshl_add_u64 v[2:3], v[2:3], 0, v[0:1]
	s_movk_i32 s0, 0x2000
	global_load_dwordx4 v[46:49], v[2:3], off
	global_load_dwordx4 v[42:45], v[2:3], off offset:64
	v_add_co_u32_e32 v2, vcc, s0, v2
	v_and_b32_e32 v22, 7, v20
	s_nop 0
	v_addc_co_u32_e32 v3, vcc, 0, v3, vcc
	global_load_dwordx4 v[50:53], v[2:3], off
	global_load_dwordx4 v[54:57], v[2:3], off offset:64
	v_mov_b64_e32 v[2:3], s[44:45]
	v_bfe_u32 v126, v20, 3, 5
	v_lshlrev_b32_e32 v114, 4, v22
	v_mov_b32_e32 v115, v1
	v_mad_i64_i32 v[2:3], s[0:1], v6, s85, v[2:3]
	v_lshl_add_u64 v[116:117], v[4:5], 0, v[114:115]
	v_lshlrev_b32_e32 v0, 8, v126
	v_or_b32_e32 v23, 32, v126
	v_lshl_add_u64 v[18:19], v[2:3], 0, v[114:115]
	v_lshl_add_u64 v[2:3], v[116:117], 0, v[0:1]
	v_lshlrev_b32_e32 v0, 8, v23
	v_mad_u64_u32 v[6:7], s[0:1], v126, s85, v[18:19]
	v_lshl_add_u64 v[10:11], v[116:117], 0, v[0:1]
	v_mad_u64_u32 v[14:15], s[0:1], v23, s85, v[18:19]
	v_mov_b32 v122, 0xf149f2ca
	global_load_dwordx4 v[2:5], v[2:3], off
	s_nop 0
	global_load_dwordx4 v[6:9], v[6:7], off
	s_nop 0
	global_load_dwordx4 v[10:13], v[10:11], off
	s_nop 0
	global_load_dwordx4 v[14:17], v[14:15], off
	v_lshrrev_b32_e32 v26, 3, v20
	v_lshrrev_b32_e32 v25, 4, v20
	v_xor_b32_e32 v20, v26, v20
	v_lshlrev_b32_e32 v20, 4, v20
	v_and_b32_e32 v132, 0x70, v20
	v_lshlrev_b32_e32 v112, 3, v21
	v_lshlrev_b32_e32 v127, 7, v126
	v_bitop3_b32 v21, v21, v22, 4 bitop3:0x36
	v_add_u32_e32 v20, v150, v132
	v_and_b32_e32 v24, 64, v208
	v_mul_u32_u24_e32 v128, 0x90, v126
	v_lshlrev_b32_e32 v131, 7, v23
	v_lshlrev_b32_e32 v129, 4, v21
	v_add_u32_e32 v21, v20, v127
	v_xor_b32_e32 v0, 16, v208
	v_bitop3_b32 v25, v25, v22, 3 bitop3:0x6c
	v_add3_u32 v22, v150, v114, v128
	v_add_u32_e32 v20, v20, v131
	v_lshlrev_b32_e32 v130, 4, v25
	v_mov_b32_e32 v38, 0
	s_mov_b32 s0, 0
	v_lshlrev_b32_e32 v115, 7, v107
	v_mov_b32_e32 v123, v122
	v_mul_u32_u24_e32 v109, 0x90, v107
	v_mov_b32_e32 v39, v38
	v_mov_b32_e32 v40, v38
	v_mov_b32_e32 v41, v38
	v_mov_b32_e32 v34, v38
	v_mov_b32_e32 v35, v38
	v_mov_b32_e32 v36, v38
	v_mov_b32_e32 v37, v38
	s_waitcnt vmcnt(0) lgkmcnt(0)
	ds_write_b128 v21, v[2:5]
	ds_write_b128 v22, v[6:9] offset:8192
	ds_write_b128 v20, v[10:13]
	ds_write_b128 v22, v[14:17] offset:12800
	v_add_u32_e32 v2, 64, v24
	v_cmp_lt_i32_e32 vcc, v0, v2
	v_mov_b32_e32 v3, v1
	s_waitcnt lgkmcnt(0)
	v_cndmask_b32_e32 v0, v208, v0, vcc
	v_lshlrev_b32_e32 v111, 2, v0
	v_xor_b32_e32 v0, 32, v208
	v_cmp_lt_i32_e32 vcc, v0, v2
	v_mov_b32_e32 v2, v1
	s_barrier
	v_cndmask_b32_e32 v0, v208, v0, vcc
	v_lshlrev_b32_e32 v113, 2, v0
	v_mul_u32_u24_e32 v0, 0x1100, v126
	v_lshlrev_b32_e32 v0, 1, v0
	v_lshl_add_u64 v[120:121], v[18:19], 0, v[0:1]
	v_mov_b32_e32 v0, v1
	v_mov_b64_e32 v[20:21], v[2:3]
	v_mov_b64_e32 v[24:25], v[2:3]
	v_mov_b64_e32 v[28:29], v[2:3]
	v_mov_b64_e32 v[32:33], v[2:3]
	v_mov_b64_e32 v[12:13], v[2:3]
	v_mov_b64_e32 v[16:17], v[2:3]
	v_mov_b64_e32 v[8:9], v[2:3]
	v_mov_b64_e32 v[18:19], v[0:1]
	v_mov_b64_e32 v[22:23], v[0:1]
	v_mov_b64_e32 v[26:27], v[0:1]
	v_mov_b64_e32 v[30:31], v[0:1]
	v_mov_b64_e32 v[10:11], v[0:1]
	v_mov_b64_e32 v[14:15], v[0:1]
	v_mov_b64_e32 v[6:7], v[0:1]
	v_mov_b64_e32 v[4:5], v[2:3]
	v_mov_b64_e32 v[2:3], v[0:1]
.LBB0_1275:
	s_bitcmp1_b32 s0, 0
	s_mov_b32 s1, s0
	s_cselect_b32 s2, 0x4400, 0
	s_add_i32 s0, s0, 1
	s_max_u32 s3, s0, 4
	s_cmp_lt_u32 s1, 3
	s_cselect_b32 s1, s0, s3
	v_lshl_or_b32 v68, s1, 6, v126
	v_lshlrev_b32_e32 v0, 8, v68
	s_lshl_b32 s56, s1, 7
	v_lshl_add_u64 v[58:59], v[116:117], 0, v[0:1]
	v_lshl_add_u64 v[66:67], v[120:121], 0, s[56:57]
	v_or_b32_e32 v0, 32, v68
	s_mov_b32 s1, 0x44000
	v_lshlrev_b64 v[68:69], 8, v[0:1]
	v_add_co_u32_e32 v70, vcc, s1, v66
	v_lshl_add_u64 v[68:69], v[116:117], 0, v[68:69]
	s_nop 0
	v_addc_co_u32_e32 v71, vcc, 0, v67, vcc
	global_load_dwordx4 v[58:61], v[58:59], off
	s_nop 0
	global_load_dwordx4 v[62:65], v[66:67], off
	s_nop 0
	global_load_dwordx4 v[66:69], v[68:69], off
	s_nop 0
	global_load_dwordx4 v[70:73], v[70:71], off
	v_add_u32_e32 v0, s2, v150
	s_setprio 1
	v_add_u32_e32 v86, v0, v115
	v_add_u32_e32 v102, v86, v130
	ds_read_b128 v[74:77], v102
	ds_read_b128 v[82:85], v102 offset:2048
	v_add_u32_e32 v103, v86, v129
	ds_read_b128 v[86:89], v103
	ds_read_b128 v[98:101], v103 offset:2048
	s_waitcnt lgkmcnt(0)
	v_mfma_f32_16x16x32_bf16 v[78:81], v[74:77], v[46:49], 0
	v_mfma_f32_16x16x32_bf16 v[74:77], v[74:77], v[50:53], 0
	v_mfma_f32_16x16x32_bf16 v[94:97], v[86:89], v[42:45], v[78:81]
	v_mfma_f32_16x16x32_bf16 v[78:81], v[86:89], v[54:57], v[74:77]
	v_mfma_f32_16x16x32_bf16 v[74:77], v[82:85], v[46:49], 0
	v_mfma_f32_16x16x32_bf16 v[90:93], v[98:101], v[42:45], v[74:77]
	v_mfma_f32_16x16x32_bf16 v[74:77], v[82:85], v[50:53], 0
	ds_read_b128 v[82:85], v102 offset:4096
	ds_read_b128 v[134:137], v102 offset:6144
	v_mfma_f32_16x16x32_bf16 v[74:77], v[98:101], v[54:57], v[74:77]
	ds_read_b128 v[98:101], v103 offset:4096
	ds_read_b128 v[138:141], v103 offset:6144
	s_waitcnt lgkmcnt(0)
	v_mfma_f32_16x16x32_bf16 v[86:89], v[82:85], v[46:49], 0
	v_mfma_f32_16x16x32_bf16 v[82:85], v[82:85], v[50:53], 0
	v_mfma_f32_16x16x32_bf16 v[102:105], v[98:101], v[42:45], v[86:89]
	v_mfma_f32_16x16x32_bf16 v[86:89], v[98:101], v[54:57], v[82:85]
	v_mfma_f32_16x16x32_bf16 v[82:85], v[134:137], v[46:49], 0
	v_mfma_f32_16x16x32_bf16 v[98:101], v[138:141], v[42:45], v[82:85]
	v_mfma_f32_16x16x32_bf16 v[82:85], v[134:137], v[50:53], 0
	v_mfma_f32_16x16x32_bf16 v[82:85], v[138:141], v[54:57], v[82:85]
	s_setprio 0
	v_max_f32_e32 v118, v95, v95
	v_max_f32_e32 v119, v94, v94
	v_max_f32_e32 v118, v119, v118
	v_max_f32_e32 v119, v97, v97
	v_max_f32_e32 v124, v96, v96
	v_max_f32_e32 v119, v124, v119
	v_max_f32_e32 v124, v93, v93
	v_max_f32_e32 v125, v92, v92
	v_max_f32_e32 v124, v125, v124
	v_max3_f32 v124, v90, v91, v124
	v_max3_f32 v118, v118, v119, v124
	v_max_f32_e32 v119, v105, v105
	v_max_f32_e32 v124, v104, v104
	v_max_f32_e32 v119, v124, v119
	v_max_f32_e32 v124, v101, v101
	v_max_f32_e32 v125, v100, v100
	v_max_f32_e32 v124, v125, v124
	v_max3_f32 v119, v102, v103, v119
	v_max3_f32 v124, v98, v99, v124
	v_max3_f32 v118, v118, v119, v124
	ds_bpermute_b32 v119, v111, v118
	s_waitcnt lgkmcnt(0)
	v_max_f32_e32 v119, v119, v119
	v_max_f32_e32 v118, v118, v119
	ds_bpermute_b32 v119, v113, v118
	s_waitcnt lgkmcnt(0)
	v_max_f32_e32 v119, v119, v119
	v_max_f32_e32 v118, v118, v119
	v_add_f32_e32 v119, 0x41000000, v122
	v_cmp_gt_f32_e32 vcc, v118, v119
	s_cbranch_vccz .LBB0_1277
	v_max_f32_e32 v118, v118, v118
	v_max_f32_e32 v119, v122, v122
	v_max_f32_e32 v124, v119, v118
	v_sub_f32_e32 v118, v122, v124
	v_exp_f32_e32 v118, v118
	v_mov_b32_e32 v125, v123
	v_mov_b32_e32 v122, v124
	v_pk_mul_f32 v[38:39], v[38:39], v[118:119] op_sel_hi:[1,0]
	v_pk_mul_f32 v[40:41], v[40:41], v[118:119] op_sel_hi:[1,0]
	v_pk_mul_f32 v[32:33], v[32:33], v[118:119] op_sel_hi:[1,0]
	v_pk_mul_f32 v[30:31], v[30:31], v[118:119] op_sel_hi:[1,0]
	v_pk_mul_f32 v[24:25], v[24:25], v[118:119] op_sel_hi:[1,0]
	v_pk_mul_f32 v[22:23], v[22:23], v[118:119] op_sel_hi:[1,0]
	v_pk_mul_f32 v[12:13], v[12:13], v[118:119] op_sel_hi:[1,0]
	v_pk_mul_f32 v[10:11], v[10:11], v[118:119] op_sel_hi:[1,0]
	v_pk_mul_f32 v[8:9], v[8:9], v[118:119] op_sel_hi:[1,0]
	v_pk_mul_f32 v[6:7], v[6:7], v[118:119] op_sel_hi:[1,0]
	s_branch .LBB0_1278

.LBB0_1286:
	v_sub_f32_e32 v46, v46, v118
	v_sub_f32_e32 v52, v65, v118
	v_exp_f32_e32 v65, v46
	v_sub_f32_e32 v46, v47, v118
	v_sub_f32_e32 v57, v74, v118
	v_exp_f32_e32 v74, v46
	v_sub_f32_e32 v46, v48, v118
	v_sub_f32_e32 v0, v62, v118
	v_sub_f32_e32 v62, v75, v118
	v_exp_f32_e32 v75, v46
	v_sub_f32_e32 v46, v49, v118
	v_exp_f32_e32 v49, v46
	v_sub_f32_e32 v46, v58, v119
	v_exp_f32_e32 v58, v46
	v_sub_f32_e32 v46, v59, v119
	v_sub_f32_e32 v50, v63, v118
	v_sub_f32_e32 v51, v64, v118
	v_sub_f32_e32 v53, v78, v118
	v_sub_f32_e32 v54, v79, v118
	v_exp_f32_e32 v59, v46
	v_sub_f32_e32 v46, v60, v119
	v_exp_f32_e32 v0, v0
	v_exp_f32_e32 v50, v50
	v_exp_f32_e32 v51, v51
	v_exp_f32_e32 v52, v52
	v_exp_f32_e32 v53, v53
	v_exp_f32_e32 v54, v54
	v_exp_f32_e32 v60, v46
	v_sub_f32_e32 v46, v61, v119
	v_sub_f32_e32 v42, v42, v119
	v_sub_f32_e32 v63, v76, v118
	v_exp_f32_e32 v61, v46
	v_sub_f32_e32 v46, v70, v119
	v_exp_f32_e32 v76, v42
	v_sub_f32_e32 v42, v43, v119
	v_sub_f32_e32 v64, v77, v118
	v_exp_f32_e32 v70, v46
	v_sub_f32_e32 v46, v71, v119
	v_exp_f32_e32 v77, v42
	v_sub_f32_e32 v42, v44, v119
	v_exp_f32_e32 v71, v46
	v_sub_f32_e32 v46, v72, v119
	v_exp_f32_e32 v78, v42
	v_sub_f32_e32 v42, v45, v119
	s_mov_b32 s38, s36
	s_mov_b32 s39, s36
	v_sub_f32_e32 v55, v80, v118
	v_sub_f32_e32 v56, v81, v118
	v_exp_f32_e32 v72, v46
	v_sub_f32_e32 v46, v73, v119
	v_exp_f32_e32 v79, v42
	v_cvt_pk_bf16_f32 v42, v0, v50
	v_cvt_pk_bf16_f32 v43, v51, v52
	v_cvt_pk_bf16_f32 v44, v53, v54
	s_mov_b32 s37, s36
	v_mov_b64_e32 v[52:53], s[38:39]
	v_exp_f32_e32 v55, v55
	v_exp_f32_e32 v56, v56
	v_exp_f32_e32 v57, v57
	v_exp_f32_e32 v62, v62
	v_exp_f32_e32 v73, v46
	v_sub_f32_e32 v46, v66, v119
	v_mov_b64_e32 v[50:51], s[36:37]
	v_exp_f32_e32 v66, v46
	v_sub_f32_e32 v46, v67, v119
	v_exp_f32_e32 v67, v46
	v_sub_f32_e32 v46, v68, v119
	v_exp_f32_e32 v68, v46
	v_sub_f32_e32 v46, v69, v119
	v_exp_f32_e32 v63, v63
	v_exp_f32_e32 v64, v64
	v_exp_f32_e32 v69, v46
	v_cvt_pk_bf16_f32 v45, v55, v56
	v_cvt_pk_bf16_f32 v46, v57, v62
	v_cvt_pk_bf16_f32 v54, v58, v59
	v_cvt_pk_bf16_f32 v55, v60, v61
	v_cvt_pk_bf16_f32 v56, v70, v71
	v_cvt_pk_bf16_f32 v57, v72, v73
	v_mfma_f32_16x16x32_bf16 v[38:41], v[50:53], v[42:45], v[38:41]
	v_cvt_pk_bf16_f32 v47, v63, v64
	v_cvt_pk_bf16_f32 v48, v65, v74
	v_cvt_pk_bf16_f32 v49, v75, v49
	v_mfma_f32_16x16x32_bf16 v[34:37], v[50:53], v[54:57], v[34:37]
	v_cvt_pk_bf16_f32 v58, v66, v67
	v_cvt_pk_bf16_f32 v59, v68, v69
	v_cvt_pk_bf16_f32 v60, v76, v77
	v_cvt_pk_bf16_f32 v61, v78, v79
	v_mfma_f32_16x16x32_bf16 v[38:41], v[50:53], v[46:49], v[38:41]
	s_nop 0
	v_mfma_f32_16x16x32_bf16 v[34:37], v[50:53], v[58:61], v[34:37]
	s_setprio 1
	v_add3_u32 v0, v150, v109, v112
	s_nop 5
	v_add_u32_e32 v35, 0x6000, v0
	ds_read2_b64 v[50:53], v35 offset0:128 offset1:132
	s_waitcnt lgkmcnt(0)
	v_mfma_f32_16x16x32_bf16 v[30:33], v[50:53], v[42:45], v[30:33]
	v_mfma_f32_16x16x32_bf16 v[26:29], v[50:53], v[54:57], v[26:29]
	ds_read2_b64 v[50:53], v35 offset0:136 offset1:140
	v_add_u32_e32 v35, 0x6800, v0
	s_waitcnt lgkmcnt(0)
	v_mfma_f32_16x16x32_bf16 v[30:33], v[50:53], v[46:49], v[30:33]
	v_mfma_f32_16x16x32_bf16 v[26:29], v[50:53], v[58:61], v[26:29]
	ds_read2_b64 v[50:53], v35 offset0:160 offset1:164
	s_waitcnt lgkmcnt(0)
	v_mfma_f32_16x16x32_bf16 v[22:25], v[50:53], v[42:45], v[22:25]
	v_mfma_f32_16x16x32_bf16 v[18:21], v[50:53], v[54:57], v[18:21]
	ds_read2_b64 v[50:53], v35 offset0:168 offset1:172
	v_add_u32_e32 v35, 0x7000, v0
	v_add_u32_e32 v0, 0x7800, v0
	s_waitcnt lgkmcnt(0)
	v_mfma_f32_16x16x32_bf16 v[22:25], v[50:53], v[46:49], v[22:25]
	v_mfma_f32_16x16x32_bf16 v[18:21], v[50:53], v[58:61], v[18:21]
	ds_read2_b64 v[50:53], v35 offset0:192 offset1:196
	s_waitcnt lgkmcnt(0)
	v_mfma_f32_16x16x32_bf16 v[10:13], v[50:53], v[42:45], v[10:13]
	v_mfma_f32_16x16x32_bf16 v[14:17], v[50:53], v[54:57], v[14:17]
	ds_read2_b64 v[50:53], v35 offset0:200 offset1:204
	s_waitcnt lgkmcnt(0)
	v_mfma_f32_16x16x32_bf16 v[10:13], v[50:53], v[46:49], v[10:13]
	v_mfma_f32_16x16x32_bf16 v[14:17], v[50:53], v[58:61], v[14:17]
	ds_read2_b64 v[50:53], v0 offset0:224 offset1:228
	s_waitcnt lgkmcnt(0)
	v_mfma_f32_16x16x32_bf16 v[6:9], v[50:53], v[42:45], v[6:9]
	ds_read2_b64 v[40:43], v0 offset0:232 offset1:236
	v_mfma_f32_16x16x32_bf16 v[2:5], v[50:53], v[54:57], v[2:5]
	s_waitcnt lgkmcnt(0)
	v_mfma_f32_16x16x32_bf16 v[6:9], v[40:43], v[46:49], v[6:9]
	v_mfma_f32_16x16x32_bf16 v[2:5], v[40:43], v[58:61], v[2:5]
	s_setprio 0
	v_mov_b32_e32 v109, v1
	s_movk_i32 s0, 0x1100
	v_lshlrev_b32_e32 v0, 1, v110
	v_mad_i64_i32 v[36:37], s[0:1], v106, s0, v[108:109]
	v_lshl_add_u64 v[40:41], s[74:75], 0, v[0:1]
	v_div_scale_f32 v0, s[0:1], v38, v38, 1.0
	v_rcp_f32_e32 v35, v0
	v_or_b32_e32 v36, v36, v107
	v_mov_b32_e32 v113, v1
	v_lshl_add_u64 v[40:41], v[40:41], 0, v[112:113]
	v_fma_f32 v39, -v0, v35, 1.0
	v_fmac_f32_e32 v35, v39, v35
	v_div_scale_f32 v39, vcc, 1.0, v38, 1.0
	v_mul_f32_e32 v42, v39, v35
	v_fma_f32 v43, -v0, v42, v39
	v_fmac_f32_e32 v42, v43, v35
	v_fma_f32 v0, -v0, v42, v39
	v_div_fmas_f32 v0, v0, v35, v42
	v_div_fixup_f32 v0, v0, v38, 1.0
	v_lshlrev_b64 v[36:37], 11, v[36:37]
	v_pk_mul_f32 v[6:7], v[0:1], v[6:7] op_sel_hi:[0,1]
	v_pk_mul_f32 v[8:9], v[0:1], v[8:9] op_sel_hi:[0,1]
	v_lshl_add_u64 v[38:39], v[40:41], 0, v[36:37]
	v_pk_mul_f32 v[30:31], v[0:1], v[30:31] op_sel_hi:[0,1]
	v_pk_mul_f32 v[32:33], v[0:1], v[32:33] op_sel_hi:[0,1]
	v_pk_mul_f32 v[22:23], v[0:1], v[22:23] op_sel_hi:[0,1]
	v_pk_mul_f32 v[24:25], v[0:1], v[24:25] op_sel_hi:[0,1]
	v_pk_mul_f32 v[10:11], v[0:1], v[10:11] op_sel_hi:[0,1]
	v_pk_mul_f32 v[12:13], v[0:1], v[12:13] op_sel_hi:[0,1]
	v_cvt_pk_bf16_f32 v6, v6, v7
	v_cvt_pk_bf16_f32 v7, v8, v9
	v_div_scale_f32 v0, s[0:1], v34, v34, 1.0
	s_barrier
	global_store_dwordx2 v[38:39], v[6:7], off offset:96
	v_rcp_f32_e32 v6, v0
	v_cvt_pk_bf16_f32 v10, v10, v11
	v_cvt_pk_bf16_f32 v11, v12, v13
	global_store_dwordx2 v[38:39], v[10:11], off offset:64
	v_fma_f32 v7, -v0, v6, 1.0
	v_fmac_f32_e32 v6, v7, v6
	v_div_scale_f32 v7, vcc, 1.0, v34, 1.0
	v_mul_f32_e32 v8, v7, v6
	v_fma_f32 v9, -v0, v8, v7
	v_fmac_f32_e32 v8, v9, v6
	v_fma_f32 v0, -v0, v8, v7
	v_div_fmas_f32 v0, v0, v6, v8
	v_div_fixup_f32 v0, v0, v34, 1.0
	v_or_b32_e32 v36, 0x8000, v36
	v_pk_mul_f32 v[8:9], v[0:1], v[26:27] op_sel_hi:[0,1]
	v_pk_mul_f32 v[10:11], v[0:1], v[28:29] op_sel_hi:[0,1]
	v_cvt_pk_bf16_f32 v30, v30, v31
	v_cvt_pk_bf16_f32 v31, v32, v33
	v_cvt_pk_bf16_f32 v22, v22, v23
	v_cvt_pk_bf16_f32 v23, v24, v25
	v_lshl_add_u64 v[6:7], v[40:41], 0, v[36:37]
	v_cvt_pk_bf16_f32 v8, v8, v9
	v_cvt_pk_bf16_f32 v9, v10, v11
	global_store_dwordx2 v[38:39], v[30:31], off
	global_store_dwordx2 v[38:39], v[22:23], off offset:32
	global_store_dwordx2 v[6:7], v[8:9], off
	v_pk_mul_f32 v[8:9], v[0:1], v[18:19] op_sel_hi:[0,1]
	v_pk_mul_f32 v[10:11], v[0:1], v[20:21] op_sel_hi:[0,1]
	v_cvt_pk_bf16_f32 v8, v8, v9
	v_cvt_pk_bf16_f32 v9, v10, v11
	global_store_dwordx2 v[6:7], v[8:9], off offset:32
	v_pk_mul_f32 v[8:9], v[0:1], v[14:15] op_sel_hi:[0,1]
	v_pk_mul_f32 v[10:11], v[0:1], v[16:17] op_sel_hi:[0,1]
	v_pk_mul_f32 v[2:3], v[0:1], v[2:3] op_sel_hi:[0,1]
	v_pk_mul_f32 v[4:5], v[0:1], v[4:5] op_sel_hi:[0,1]
	v_cvt_pk_bf16_f32 v8, v8, v9
	v_cvt_pk_bf16_f32 v9, v10, v11
	v_cvt_pk_bf16_f32 v2, v2, v3
	v_cvt_pk_bf16_f32 v3, v4, v5
	global_store_dwordx2 v[6:7], v[8:9], off offset:64
	global_store_dwordx2 v[6:7], v[2:3], off offset:96

.LBB0_1290:
	s_and_b32 s4, s3, 0x10000
	s_xor_b32 s5, s4, 0x10000
	v_add_u32_e32 v163, s5, v153
	v_add_u32_e32 v166, 0x8000, v163
	v_lshl_add_u64 v[164:165], v[146:147], 0, s[0:1]
	v_readfirstlane_b32 s5, v163
	v_lshl_add_u64 v[164:165], v[164:165], 0, s[78:79]
	s_mov_b32 m0, s5
	v_readfirstlane_b32 s5, v166
	global_load_lds_dwordx4 v[164:165], off
	v_lshl_add_u64 v[164:165], v[138:139], 0, s[0:1]
	s_mov_b32 m0, s5
	v_add_u32_e32 v166, 0x2000, v163
	global_load_lds_dwordx4 v[164:165], off
	v_lshl_add_u64 v[164:165], v[144:145], 0, s[0:1]
	v_readfirstlane_b32 s5, v166
	v_add_u32_e32 v166, 0xa000, v163
	v_lshl_add_u64 v[164:165], v[164:165], 0, s[78:79]
	s_mov_b32 m0, s5
	v_readfirstlane_b32 s5, v166
	global_load_lds_dwordx4 v[164:165], off
	v_lshl_add_u64 v[164:165], v[136:137], 0, s[0:1]
	s_mov_b32 m0, s5
	v_add_u32_e32 v166, 0x4000, v163
	global_load_lds_dwordx4 v[164:165], off
	v_lshl_add_u64 v[164:165], v[142:143], 0, s[0:1]
	v_readfirstlane_b32 s5, v166
	v_add_u32_e32 v166, 0xc000, v163
	v_lshl_add_u64 v[164:165], v[164:165], 0, s[78:79]
	s_mov_b32 m0, s5
	v_readfirstlane_b32 s5, v166
	global_load_lds_dwordx4 v[164:165], off
	v_lshl_add_u64 v[164:165], v[134:135], 0, s[0:1]
	s_mov_b32 m0, s5
	v_add_u32_e32 v166, 0x6000, v163
	global_load_lds_dwordx4 v[164:165], off
	v_lshl_add_u64 v[164:165], v[140:141], 0, s[0:1]
	v_readfirstlane_b32 s5, v166
	v_add_u32_e32 v163, 0xe000, v163
	v_lshl_add_u64 v[164:165], v[164:165], 0, s[78:79]
	s_mov_b32 m0, s5
	v_readfirstlane_b32 s5, v163
	global_load_lds_dwordx4 v[164:165], off
	v_lshl_add_u64 v[164:165], v[132:133], 0, s[0:1]
	s_mov_b32 m0, s5
	s_addk_i32 s4, 0x400
	global_load_lds_dwordx4 v[164:165], off
	v_add3_u32 v163, s4, v159, v160
	v_add3_u32 v188, s4, v159, v162
	v_add3_u32 v189, s4, v131, v161
	ds_read_b128 v[164:167], v188 offset:34816
	ds_read_b128 v[168:171], v188 offset:36864
	ds_read_b128 v[172:175], v188 offset:32768
	ds_read_b128 v[176:179], v163
	ds_read_b128 v[180:183], v188 offset:38912
	ds_read_b128 v[184:187], v189
	s_setprio 1
	s_waitcnt lgkmcnt(0)
	v_mfma_f32_16x16x32_bf16 v[126:129], v[172:175], v[176:179], v[126:129]
	v_mfma_f32_16x16x32_bf16 v[122:125], v[164:167], v[176:179], v[122:125]
	v_mfma_f32_16x16x32_bf16 v[118:121], v[168:171], v[176:179], v[118:121]
	v_mfma_f32_16x16x32_bf16 v[114:117], v[180:183], v[176:179], v[114:117]
	s_setprio 0
	v_add3_u32 v190, s4, v131, v158
	ds_read_b128 v[176:179], v190
	s_setprio 1
	v_mfma_f32_16x16x32_bf16 v[110:113], v[172:175], v[184:187], v[110:113]
	v_mfma_f32_16x16x32_bf16 v[106:109], v[164:167], v[184:187], v[106:109]
	v_mfma_f32_16x16x32_bf16 v[102:105], v[168:171], v[184:187], v[102:105]
	v_mfma_f32_16x16x32_bf16 v[98:101], v[180:183], v[184:187], v[98:101]
	s_setprio 0
	v_add3_u32 v191, s4, v131, v157
	ds_read_b128 v[184:187], v191
	s_setprio 1
	s_waitcnt lgkmcnt(0)
	v_mfma_f32_16x16x32_bf16 v[94:97], v[172:175], v[176:179], v[94:97]
	v_mfma_f32_16x16x32_bf16 v[90:93], v[164:167], v[176:179], v[90:93]
	v_mfma_f32_16x16x32_bf16 v[86:89], v[168:171], v[176:179], v[86:89]
	v_mfma_f32_16x16x32_bf16 v[82:85], v[180:183], v[176:179], v[82:85]
	s_setprio 0
	v_add3_u32 v192, s4, v131, v156
	ds_read_b128 v[176:179], v192
	s_setprio 1
	v_mfma_f32_16x16x32_bf16 v[78:81], v[172:175], v[184:187], v[78:81]
	v_mfma_f32_16x16x32_bf16 v[74:77], v[164:167], v[184:187], v[74:77]
	v_mfma_f32_16x16x32_bf16 v[70:73], v[168:171], v[184:187], v[70:73]
	v_mfma_f32_16x16x32_bf16 v[66:69], v[180:183], v[184:187], v[66:69]
	s_setprio 0
	v_add3_u32 v193, s4, v131, v155
	ds_read_b128 v[184:187], v193
	s_setprio 1
	s_waitcnt lgkmcnt(0)
	v_mfma_f32_16x16x32_bf16 v[62:65], v[172:175], v[176:179], v[62:65]
	v_mfma_f32_16x16x32_bf16 v[58:61], v[164:167], v[176:179], v[58:61]
	v_mfma_f32_16x16x32_bf16 v[54:57], v[168:171], v[176:179], v[54:57]
	v_mfma_f32_16x16x32_bf16 v[50:53], v[180:183], v[176:179], v[50:53]
	s_setprio 0
	v_add3_u32 v194, s4, v131, v154
	ds_read_b128 v[176:179], v194
	s_setprio 1
	v_mfma_f32_16x16x32_bf16 v[46:49], v[172:175], v[184:187], v[46:49]
	v_mfma_f32_16x16x32_bf16 v[42:45], v[164:167], v[184:187], v[42:45]
	v_mfma_f32_16x16x32_bf16 v[38:41], v[168:171], v[184:187], v[38:41]
	v_mfma_f32_16x16x32_bf16 v[34:37], v[180:183], v[184:187], v[34:37]
	s_setprio 0
	v_add3_u32 v195, s4, v131, v152
	ds_read_b128 v[184:187], v195
	s_setprio 1
	s_waitcnt lgkmcnt(0)
	v_mfma_f32_16x16x32_bf16 v[30:33], v[172:175], v[176:179], v[30:33]
	v_mfma_f32_16x16x32_bf16 v[26:29], v[164:167], v[176:179], v[26:29]
	v_mfma_f32_16x16x32_bf16 v[22:25], v[168:171], v[176:179], v[22:25]
	v_mfma_f32_16x16x32_bf16 v[18:21], v[180:183], v[176:179], v[18:21]
	s_setprio 0
	s_setprio 1
	v_mfma_f32_16x16x32_bf16 v[14:17], v[172:175], v[184:187], v[14:17]
	v_mfma_f32_16x16x32_bf16 v[10:13], v[164:167], v[184:187], v[10:13]
	v_mfma_f32_16x16x32_bf16 v[6:9], v[168:171], v[184:187], v[6:9]
	v_mfma_f32_16x16x32_bf16 v[2:5], v[180:183], v[184:187], v[2:5]
	s_setprio 0
	ds_read_b128 v[164:167], v188 offset:33792
	ds_read_b128 v[168:171], v188 offset:35840
	ds_read_b128 v[172:175], v188 offset:37888
	ds_read_b128 v[176:179], v188 offset:39936
	ds_read_b128 v[180:183], v163 offset:1024
	ds_read_b128 v[184:187], v189 offset:1024
	s_setprio 1
	s_waitcnt lgkmcnt(0)
	v_mfma_f32_16x16x32_bf16 v[126:129], v[164:167], v[180:183], v[126:129]
	v_mfma_f32_16x16x32_bf16 v[122:125], v[168:171], v[180:183], v[122:125]
	v_mfma_f32_16x16x32_bf16 v[118:121], v[172:175], v[180:183], v[118:121]
	v_mfma_f32_16x16x32_bf16 v[114:117], v[176:179], v[180:183], v[114:117]
	s_setprio 0
	ds_read_b128 v[180:183], v190 offset:1024
	s_setprio 1
	v_mfma_f32_16x16x32_bf16 v[110:113], v[164:167], v[184:187], v[110:113]
	v_mfma_f32_16x16x32_bf16 v[106:109], v[168:171], v[184:187], v[106:109]
	v_mfma_f32_16x16x32_bf16 v[102:105], v[172:175], v[184:187], v[102:105]
	v_mfma_f32_16x16x32_bf16 v[98:101], v[176:179], v[184:187], v[98:101]
	s_setprio 0
	ds_read_b128 v[184:187], v191 offset:1024
	s_setprio 1
	s_waitcnt lgkmcnt(0)
	v_mfma_f32_16x16x32_bf16 v[94:97], v[164:167], v[180:183], v[94:97]
	v_mfma_f32_16x16x32_bf16 v[90:93], v[168:171], v[180:183], v[90:93]
	v_mfma_f32_16x16x32_bf16 v[86:89], v[172:175], v[180:183], v[86:89]
	v_mfma_f32_16x16x32_bf16 v[82:85], v[176:179], v[180:183], v[82:85]
	s_setprio 0
	ds_read_b128 v[180:183], v192 offset:1024
	s_setprio 1
	v_mfma_f32_16x16x32_bf16 v[78:81], v[164:167], v[184:187], v[78:81]
	v_mfma_f32_16x16x32_bf16 v[74:77], v[168:171], v[184:187], v[74:77]
	v_mfma_f32_16x16x32_bf16 v[70:73], v[172:175], v[184:187], v[70:73]
	v_mfma_f32_16x16x32_bf16 v[66:69], v[176:179], v[184:187], v[66:69]
	s_setprio 0
	ds_read_b128 v[184:187], v193 offset:1024
	s_setprio 1
	s_waitcnt lgkmcnt(0)
	v_mfma_f32_16x16x32_bf16 v[62:65], v[164:167], v[180:183], v[62:65]
	v_mfma_f32_16x16x32_bf16 v[58:61], v[168:171], v[180:183], v[58:61]
	v_mfma_f32_16x16x32_bf16 v[54:57], v[172:175], v[180:183], v[54:57]
	v_mfma_f32_16x16x32_bf16 v[50:53], v[176:179], v[180:183], v[50:53]
	s_setprio 0
	ds_read_b128 v[180:183], v194 offset:1024
	s_setprio 1
	v_mfma_f32_16x16x32_bf16 v[46:49], v[164:167], v[184:187], v[46:49]
	v_mfma_f32_16x16x32_bf16 v[42:45], v[168:171], v[184:187], v[42:45]
	v_mfma_f32_16x16x32_bf16 v[38:41], v[172:175], v[184:187], v[38:41]
	v_mfma_f32_16x16x32_bf16 v[34:37], v[176:179], v[184:187], v[34:37]
	s_setprio 0
	ds_read_b128 v[184:187], v195 offset:1024
	s_setprio 1
	s_waitcnt lgkmcnt(0)
	v_mfma_f32_16x16x32_bf16 v[30:33], v[164:167], v[180:183], v[30:33]
	v_mfma_f32_16x16x32_bf16 v[26:29], v[168:171], v[180:183], v[26:29]
	v_mfma_f32_16x16x32_bf16 v[22:25], v[172:175], v[180:183], v[22:25]
	v_mfma_f32_16x16x32_bf16 v[18:21], v[176:179], v[180:183], v[18:21]
	s_setprio 0
	s_setprio 1
	v_mfma_f32_16x16x32_bf16 v[14:17], v[164:167], v[184:187], v[14:17]
	v_mfma_f32_16x16x32_bf16 v[10:13], v[168:171], v[184:187], v[10:13]
	v_mfma_f32_16x16x32_bf16 v[6:9], v[172:175], v[184:187], v[6:9]
	v_mfma_f32_16x16x32_bf16 v[2:5], v[176:179], v[184:187], v[2:5]
	s_setprio 0
	s_add_i32 s3, s3, 0x10000
	s_waitcnt vmcnt(0)
	s_add_u32 s0, s0, 0x80
	s_addc_u32 s1, s1, 0
	s_cmpk_lg_i32 s0, 0x380
	s_waitcnt vmcnt(0)
	s_barrier
	s_cbranch_scc1 .LBB0_1290
	v_add3_u32 v153, s53, v159, v162
	v_add3_u32 v168, s33, v159, v160
	v_add3_u32 v169, s33, v131, v161
	ds_read_b128 v[132:135], v153
	ds_read_b128 v[136:139], v153 offset:2048
	ds_read_b128 v[140:143], v153 offset:4096
	ds_read_b128 v[144:147], v153 offset:6144
	ds_read_b128 v[160:163], v168
	ds_read_b128 v[164:167], v169
	s_setprio 1
	s_waitcnt lgkmcnt(1)
	v_mfma_f32_16x16x32_bf16 v[126:129], v[132:135], v[160:163], v[126:129]
	v_mfma_f32_16x16x32_bf16 v[122:125], v[136:139], v[160:163], v[122:125]
	v_mfma_f32_16x16x32_bf16 v[118:121], v[140:143], v[160:163], v[118:121]
	v_mfma_f32_16x16x32_bf16 v[114:117], v[144:147], v[160:163], v[114:117]
	s_setprio 0
	v_add3_u32 v170, s33, v131, v158
	ds_read_b128 v[158:161], v170
	s_setprio 1
	s_waitcnt lgkmcnt(1)
	v_mfma_f32_16x16x32_bf16 v[110:113], v[132:135], v[164:167], v[110:113]
	v_mfma_f32_16x16x32_bf16 v[106:109], v[136:139], v[164:167], v[106:109]
	v_mfma_f32_16x16x32_bf16 v[102:105], v[140:143], v[164:167], v[102:105]
	v_mfma_f32_16x16x32_bf16 v[98:101], v[144:147], v[164:167], v[98:101]
	s_setprio 0
	v_add3_u32 v166, s33, v131, v157
	ds_read_b128 v[162:165], v166
	s_setprio 1
	s_waitcnt lgkmcnt(1)
	v_mfma_f32_16x16x32_bf16 v[94:97], v[132:135], v[158:161], v[94:97]
	v_mfma_f32_16x16x32_bf16 v[90:93], v[136:139], v[158:161], v[90:93]
	v_mfma_f32_16x16x32_bf16 v[86:89], v[140:143], v[158:161], v[86:89]
	v_mfma_f32_16x16x32_bf16 v[82:85], v[144:147], v[158:161], v[82:85]
	s_setprio 0
	v_add3_u32 v167, s33, v131, v156
	ds_read_b128 v[156:159], v167
	s_setprio 1
	s_waitcnt lgkmcnt(1)
	v_mfma_f32_16x16x32_bf16 v[78:81], v[132:135], v[162:165], v[78:81]
	v_mfma_f32_16x16x32_bf16 v[74:77], v[136:139], v[162:165], v[74:77]
	v_mfma_f32_16x16x32_bf16 v[70:73], v[140:143], v[162:165], v[70:73]
	v_mfma_f32_16x16x32_bf16 v[66:69], v[144:147], v[162:165], v[66:69]
	s_setprio 0
	v_add3_u32 v171, s33, v131, v155
	ds_read_b128 v[160:163], v171
	s_setprio 1
	s_waitcnt lgkmcnt(1)
	v_mfma_f32_16x16x32_bf16 v[62:65], v[132:135], v[156:159], v[62:65]
	v_mfma_f32_16x16x32_bf16 v[58:61], v[136:139], v[156:159], v[58:61]
	v_mfma_f32_16x16x32_bf16 v[54:57], v[140:143], v[156:159], v[54:57]
	v_mfma_f32_16x16x32_bf16 v[50:53], v[144:147], v[156:159], v[50:53]
	s_setprio 0
	v_add3_u32 v172, s33, v131, v154
	ds_read_b128 v[154:157], v172
	s_setprio 1
	s_waitcnt lgkmcnt(1)
	v_mfma_f32_16x16x32_bf16 v[46:49], v[132:135], v[160:163], v[46:49]
	v_mfma_f32_16x16x32_bf16 v[42:45], v[136:139], v[160:163], v[42:45]
	v_mfma_f32_16x16x32_bf16 v[38:41], v[140:143], v[160:163], v[38:41]
	v_mfma_f32_16x16x32_bf16 v[34:37], v[144:147], v[160:163], v[34:37]
	s_setprio 0
	v_add3_u32 v131, s33, v131, v152
	ds_read_b128 v[158:161], v131
	s_setprio 1
	s_waitcnt lgkmcnt(1)
	v_mfma_f32_16x16x32_bf16 v[30:33], v[132:135], v[154:157], v[30:33]
	v_mfma_f32_16x16x32_bf16 v[26:29], v[136:139], v[154:157], v[26:29]
	v_mfma_f32_16x16x32_bf16 v[22:25], v[140:143], v[154:157], v[22:25]
	v_mfma_f32_16x16x32_bf16 v[18:21], v[144:147], v[154:157], v[18:21]
	s_setprio 0
	s_setprio 1
	s_waitcnt lgkmcnt(0)
	v_mfma_f32_16x16x32_bf16 v[14:17], v[132:135], v[158:161], v[14:17]
	v_mfma_f32_16x16x32_bf16 v[10:13], v[136:139], v[158:161], v[10:13]
	v_mfma_f32_16x16x32_bf16 v[6:9], v[140:143], v[158:161], v[6:9]
	v_mfma_f32_16x16x32_bf16 v[2:5], v[144:147], v[158:161], v[2:5]
	s_setprio 0
	ds_read_b128 v[132:135], v153 offset:1024
	ds_read_b128 v[136:139], v153 offset:3072
	ds_read_b128 v[140:143], v153 offset:5120
	ds_read_b128 v[144:147], v153 offset:7168
	ds_read_b128 v[152:155], v168 offset:1024
	ds_read_b128 v[156:159], v169 offset:1024
	s_setprio 1
	s_waitcnt lgkmcnt(1)
	v_mfma_f32_16x16x32_bf16 v[126:129], v[132:135], v[152:155], v[126:129]
	v_mfma_f32_16x16x32_bf16 v[122:125], v[136:139], v[152:155], v[122:125]
	v_mfma_f32_16x16x32_bf16 v[118:121], v[140:143], v[152:155], v[118:121]
	v_mfma_f32_16x16x32_bf16 v[114:117], v[144:147], v[152:155], v[114:117]
	s_setprio 0
	ds_read_b128 v[152:155], v170 offset:1024
	s_setprio 1
	s_waitcnt lgkmcnt(1)
	v_mfma_f32_16x16x32_bf16 v[110:113], v[132:135], v[156:159], v[110:113]
	v_mfma_f32_16x16x32_bf16 v[106:109], v[136:139], v[156:159], v[106:109]
	v_mfma_f32_16x16x32_bf16 v[102:105], v[140:143], v[156:159], v[102:105]
	v_mfma_f32_16x16x32_bf16 v[98:101], v[144:147], v[156:159], v[98:101]
	s_setprio 0
	ds_read_b128 v[156:159], v166 offset:1024
	s_setprio 1
	s_waitcnt lgkmcnt(1)
	v_mfma_f32_16x16x32_bf16 v[94:97], v[132:135], v[152:155], v[94:97]
	v_mfma_f32_16x16x32_bf16 v[90:93], v[136:139], v[152:155], v[90:93]
	v_mfma_f32_16x16x32_bf16 v[86:89], v[140:143], v[152:155], v[86:89]
	v_mfma_f32_16x16x32_bf16 v[82:85], v[144:147], v[152:155], v[82:85]
	s_setprio 0
	ds_read_b128 v[152:155], v167 offset:1024
	s_setprio 1
	s_waitcnt lgkmcnt(1)
	v_mfma_f32_16x16x32_bf16 v[78:81], v[132:135], v[156:159], v[78:81]
	v_mfma_f32_16x16x32_bf16 v[160:163], v[136:139], v[156:159], v[74:77]
	v_mfma_f32_16x16x32_bf16 v[164:167], v[140:143], v[156:159], v[70:73]
	v_mfma_f32_16x16x32_bf16 v[66:69], v[144:147], v[156:159], v[66:69]
	s_setprio 0
	s_nop 0
	ds_read_b128 v[70:73], v171 offset:1024
	s_setprio 1
	s_waitcnt lgkmcnt(1)
	v_mfma_f32_16x16x32_bf16 v[62:65], v[132:135], v[152:155], v[62:65]
	v_mfma_f32_16x16x32_bf16 v[58:61], v[136:139], v[152:155], v[58:61]
	v_mfma_f32_16x16x32_bf16 v[54:57], v[140:143], v[152:155], v[54:57]
	v_mfma_f32_16x16x32_bf16 v[50:53], v[144:147], v[152:155], v[50:53]
	s_setprio 0
	ds_read_b128 v[74:77], v172 offset:1024
	s_setprio 1
	s_waitcnt lgkmcnt(1)
	v_mfma_f32_16x16x32_bf16 v[46:49], v[132:135], v[70:73], v[46:49]
	v_mfma_f32_16x16x32_bf16 v[42:45], v[136:139], v[70:73], v[42:45]
	v_mfma_f32_16x16x32_bf16 v[38:41], v[140:143], v[70:73], v[38:41]
	v_mfma_f32_16x16x32_bf16 v[34:37], v[144:147], v[70:73], v[34:37]
	s_setprio 0
	ds_read_b128 v[70:73], v131 offset:1024
	s_setprio 1
	s_waitcnt lgkmcnt(1)
	v_mfma_f32_16x16x32_bf16 v[30:33], v[132:135], v[74:77], v[30:33]
	v_mfma_f32_16x16x32_bf16 v[26:29], v[136:139], v[74:77], v[26:29]
	v_mfma_f32_16x16x32_bf16 v[22:25], v[140:143], v[74:77], v[22:25]
	v_mfma_f32_16x16x32_bf16 v[18:21], v[144:147], v[74:77], v[18:21]
	s_setprio 0
	s_setprio 1
	s_waitcnt lgkmcnt(0)
	v_mfma_f32_16x16x32_bf16 v[14:17], v[132:135], v[70:73], v[14:17]
	v_mfma_f32_16x16x32_bf16 v[10:13], v[136:139], v[70:73], v[10:13]
	v_mfma_f32_16x16x32_bf16 v[6:9], v[140:143], v[70:73], v[6:9]
	v_mfma_f32_16x16x32_bf16 v[2:5], v[144:147], v[70:73], v[2:5]
	s_setprio 0
	s_lshr_b32 s0, s2, 8
	s_mul_i32 s56, s0, 0x1100
	v_ashrrev_i32_e32 v131, 31, v130
	v_lshl_add_u64 v[70:71], v[130:131], 0, s[56:57]
	v_lshlrev_b64 v[70:71], 11, v[70:71]
	v_lshrrev_b32_e32 v0, 1, v0
	v_lshl_add_u64 v[70:71], s[10:11], 0, v[70:71]
	s_mov_b64 s[0:1], 0x4e80600
	v_and_b32_e32 v0, 24, v0
	v_pk_mul_f32 v[72:73], v[126:127], s[80:81] op_sel_hi:[1,0]
	v_pk_mul_f32 v[74:75], v[128:129], s[80:81] op_sel_hi:[1,0]
	v_lshl_add_u64 v[76:77], v[70:71], 0, s[0:1]
	v_lshl_or_b32 v0, v151, 7, v0
	v_cvt_pk_bf16_f32 v72, v72, v73
	v_cvt_pk_bf16_f32 v73, v74, v75
	v_lshl_add_u64 v[70:71], v[76:77], 0, v[0:1]
	s_waitcnt vmcnt(0)
	s_barrier
	global_store_dwordx2 v[70:71], v[72:73], off
	v_pk_mul_f32 v[70:71], v[122:123], s[80:81] op_sel_hi:[1,0]
	v_pk_mul_f32 v[110:111], v[110:111], s[80:81] op_sel_hi:[1,0]
	v_cvt_pk_bf16_f32 v72, v70, v71
	v_pk_mul_f32 v[70:71], v[124:125], s[80:81] op_sel_hi:[1,0]
	v_pk_mul_f32 v[112:113], v[112:113], s[80:81] op_sel_hi:[1,0]
	v_cvt_pk_bf16_f32 v73, v70, v71
	v_or_b32_e32 v70, 32, v0
	v_mov_b32_e32 v71, v1
	v_lshl_add_u64 v[74:75], v[76:77], 0, v[70:71]
	global_store_dwordx2 v[74:75], v[72:73], off
	v_pk_mul_f32 v[72:73], v[118:119], s[80:81] op_sel_hi:[1,0]
	v_pk_mul_f32 v[106:107], v[106:107], s[80:81] op_sel_hi:[1,0]
	v_cvt_pk_bf16_f32 v74, v72, v73
	v_pk_mul_f32 v[72:73], v[120:121], s[80:81] op_sel_hi:[1,0]
	v_pk_mul_f32 v[108:109], v[108:109], s[80:81] op_sel_hi:[1,0]
	v_cvt_pk_bf16_f32 v75, v72, v73
	v_or_b32_e32 v72, 64, v0
	v_mov_b32_e32 v73, v1
	v_lshl_add_u64 v[118:119], v[76:77], 0, v[72:73]
	global_store_dwordx2 v[118:119], v[74:75], off
	v_pk_mul_f32 v[74:75], v[114:115], s[80:81] op_sel_hi:[1,0]
	v_pk_mul_f32 v[102:103], v[102:103], s[80:81] op_sel_hi:[1,0]
	v_cvt_pk_bf16_f32 v114, v74, v75
	v_pk_mul_f32 v[74:75], v[116:117], s[80:81] op_sel_hi:[1,0]
	v_pk_mul_f32 v[104:105], v[104:105], s[80:81] op_sel_hi:[1,0]
	v_cvt_pk_bf16_f32 v115, v74, v75
	v_or_b32_e32 v74, 0x60, v0
	v_mov_b32_e32 v75, v1
	v_lshl_add_u64 v[76:77], v[76:77], 0, v[74:75]
	global_store_dwordx2 v[76:77], v[114:115], off
	v_or_b32_e32 v76, 16, v130
	v_ashrrev_i32_e32 v77, 31, v76
	v_lshl_add_u64 v[76:77], v[76:77], 0, s[56:57]
	v_lshlrev_b64 v[76:77], 11, v[76:77]
	v_lshl_add_u64 v[76:77], s[10:11], 0, v[76:77]
	v_lshl_add_u64 v[76:77], v[76:77], 0, s[0:1]
	v_pk_mul_f32 v[98:99], v[98:99], s[80:81] op_sel_hi:[1,0]
	v_pk_mul_f32 v[100:101], v[100:101], s[80:81] op_sel_hi:[1,0]
	v_cvt_pk_bf16_f32 v110, v110, v111
	v_cvt_pk_bf16_f32 v111, v112, v113
	v_lshl_add_u64 v[112:113], v[76:77], 0, v[0:1]
	v_cvt_pk_bf16_f32 v106, v106, v107
	v_cvt_pk_bf16_f32 v107, v108, v109
	v_lshl_add_u64 v[108:109], v[76:77], 0, v[70:71]
	v_cvt_pk_bf16_f32 v102, v102, v103
	v_cvt_pk_bf16_f32 v103, v104, v105
	v_lshl_add_u64 v[104:105], v[76:77], 0, v[72:73]
	v_cvt_pk_bf16_f32 v98, v98, v99
	v_cvt_pk_bf16_f32 v99, v100, v101
	v_lshl_add_u64 v[76:77], v[76:77], 0, v[74:75]
	global_store_dwordx2 v[76:77], v[98:99], off
	v_or_b32_e32 v76, 32, v130
	v_ashrrev_i32_e32 v77, 31, v76
	v_lshl_add_u64 v[76:77], v[76:77], 0, s[56:57]
	v_lshlrev_b64 v[76:77], 11, v[76:77]
	v_lshl_add_u64 v[76:77], s[10:11], 0, v[76:77]
	v_pk_mul_f32 v[94:95], v[94:95], s[80:81] op_sel_hi:[1,0]
	v_pk_mul_f32 v[96:97], v[96:97], s[80:81] op_sel_hi:[1,0]
	v_lshl_add_u64 v[76:77], v[76:77], 0, s[0:1]
	v_pk_mul_f32 v[90:91], v[90:91], s[80:81] op_sel_hi:[1,0]
	v_pk_mul_f32 v[92:93], v[92:93], s[80:81] op_sel_hi:[1,0]
	v_pk_mul_f32 v[86:87], v[86:87], s[80:81] op_sel_hi:[1,0]
	v_pk_mul_f32 v[88:89], v[88:89], s[80:81] op_sel_hi:[1,0]
	v_pk_mul_f32 v[82:83], v[82:83], s[80:81] op_sel_hi:[1,0]
	v_pk_mul_f32 v[84:85], v[84:85], s[80:81] op_sel_hi:[1,0]
	v_cvt_pk_bf16_f32 v94, v94, v95
	v_cvt_pk_bf16_f32 v95, v96, v97
	v_lshl_add_u64 v[96:97], v[76:77], 0, v[0:1]
	v_cvt_pk_bf16_f32 v90, v90, v91
	v_cvt_pk_bf16_f32 v91, v92, v93
	v_lshl_add_u64 v[92:93], v[76:77], 0, v[70:71]
	v_cvt_pk_bf16_f32 v86, v86, v87
	v_cvt_pk_bf16_f32 v87, v88, v89
	v_lshl_add_u64 v[88:89], v[76:77], 0, v[72:73]
	v_cvt_pk_bf16_f32 v82, v82, v83
	v_cvt_pk_bf16_f32 v83, v84, v85
	v_lshl_add_u64 v[76:77], v[76:77], 0, v[74:75]
	global_store_dwordx2 v[76:77], v[82:83], off
	v_or_b32_e32 v76, 48, v130
	v_ashrrev_i32_e32 v77, 31, v76
	v_lshl_add_u64 v[76:77], v[76:77], 0, s[56:57]
	v_lshlrev_b64 v[76:77], 11, v[76:77]
	v_lshl_add_u64 v[76:77], s[10:11], 0, v[76:77]
	v_lshl_add_u64 v[76:77], v[76:77], 0, s[0:1]
	v_pk_mul_f32 v[66:67], v[66:67], s[80:81] op_sel_hi:[1,0]
	v_pk_mul_f32 v[68:69], v[68:69], s[80:81] op_sel_hi:[1,0]
	v_cvt_pk_bf16_f32 v66, v66, v67
	v_cvt_pk_bf16_f32 v67, v68, v69
	v_lshl_add_u64 v[68:69], v[76:77], 0, v[74:75]
	global_store_dwordx2 v[68:69], v[66:67], off
	v_or_b32_e32 v66, 64, v130
	v_ashrrev_i32_e32 v67, 31, v66
	v_lshl_add_u64 v[66:67], v[66:67], 0, s[56:57]
	v_pk_mul_f32 v[62:63], v[62:63], s[80:81] op_sel_hi:[1,0]
	v_pk_mul_f32 v[64:65], v[64:65], s[80:81] op_sel_hi:[1,0]
	v_cvt_pk_bf16_f32 v62, v62, v63
	v_cvt_pk_bf16_f32 v63, v64, v65
	v_lshlrev_b64 v[64:65], 11, v[66:67]
	v_lshl_add_u64 v[64:65], s[10:11], 0, v[64:65]
	v_lshl_add_u64 v[64:65], v[64:65], 0, s[0:1]
	v_pk_mul_f32 v[50:51], v[50:51], s[80:81] op_sel_hi:[1,0]
	v_pk_mul_f32 v[52:53], v[52:53], s[80:81] op_sel_hi:[1,0]
	v_cvt_pk_bf16_f32 v50, v50, v51
	v_cvt_pk_bf16_f32 v51, v52, v53
	v_lshl_add_u64 v[52:53], v[64:65], 0, v[74:75]
	global_store_dwordx2 v[52:53], v[50:51], off
	v_or_b32_e32 v50, 0x50, v130
	v_ashrrev_i32_e32 v51, 31, v50
	v_lshl_add_u64 v[50:51], v[50:51], 0, s[56:57]
	v_pk_mul_f32 v[46:47], v[46:47], s[80:81] op_sel_hi:[1,0]
	v_pk_mul_f32 v[48:49], v[48:49], s[80:81] op_sel_hi:[1,0]
	v_cvt_pk_bf16_f32 v46, v46, v47
	v_cvt_pk_bf16_f32 v47, v48, v49
	v_lshlrev_b64 v[48:49], 11, v[50:51]
	v_lshl_add_u64 v[48:49], s[10:11], 0, v[48:49]
	v_lshl_add_u64 v[48:49], v[48:49], 0, s[0:1]
	v_pk_mul_f32 v[34:35], v[34:35], s[80:81] op_sel_hi:[1,0]
	v_pk_mul_f32 v[36:37], v[36:37], s[80:81] op_sel_hi:[1,0]
	v_cvt_pk_bf16_f32 v34, v34, v35
	v_cvt_pk_bf16_f32 v35, v36, v37
	v_lshl_add_u64 v[36:37], v[48:49], 0, v[74:75]
	global_store_dwordx2 v[36:37], v[34:35], off
	v_or_b32_e32 v34, 0x60, v130
	v_ashrrev_i32_e32 v35, 31, v34
	v_lshl_add_u64 v[34:35], v[34:35], 0, s[56:57]
	v_pk_mul_f32 v[30:31], v[30:31], s[80:81] op_sel_hi:[1,0]
	v_pk_mul_f32 v[32:33], v[32:33], s[80:81] op_sel_hi:[1,0]
	v_cvt_pk_bf16_f32 v30, v30, v31
	v_cvt_pk_bf16_f32 v31, v32, v33
	v_lshlrev_b64 v[32:33], 11, v[34:35]
	v_lshl_add_u64 v[32:33], s[10:11], 0, v[32:33]
	v_lshl_add_u64 v[32:33], v[32:33], 0, s[0:1]
	v_pk_mul_f32 v[18:19], v[18:19], s[80:81] op_sel_hi:[1,0]
	v_pk_mul_f32 v[20:21], v[20:21], s[80:81] op_sel_hi:[1,0]
	v_cvt_pk_bf16_f32 v18, v18, v19
	v_cvt_pk_bf16_f32 v19, v20, v21
	v_lshl_add_u64 v[20:21], v[32:33], 0, v[74:75]
	global_store_dwordx2 v[20:21], v[18:19], off
	v_or_b32_e32 v18, 0x70, v130
	v_pk_mul_f32 v[78:79], v[78:79], s[80:81] op_sel_hi:[1,0]
	v_pk_mul_f32 v[80:81], v[80:81], s[80:81] op_sel_hi:[1,0]
	v_ashrrev_i32_e32 v19, 31, v18
	v_cvt_pk_bf16_f32 v78, v78, v79
	v_cvt_pk_bf16_f32 v79, v80, v81
	v_lshl_add_u64 v[80:81], v[76:77], 0, v[0:1]
	v_lshl_add_u64 v[18:19], v[18:19], 0, s[56:57]
	v_pk_mul_f32 v[14:15], v[14:15], s[80:81] op_sel_hi:[1,0]
	v_pk_mul_f32 v[16:17], v[16:17], s[80:81] op_sel_hi:[1,0]
	global_store_dwordx2 v[80:81], v[78:79], off
	v_pk_mul_f32 v[78:79], v[160:161], s[80:81] op_sel_hi:[1,0]
	v_pk_mul_f32 v[80:81], v[162:163], s[80:81] op_sel_hi:[1,0]
	v_cvt_pk_bf16_f32 v14, v14, v15
	v_cvt_pk_bf16_f32 v15, v16, v17
	v_lshlrev_b64 v[16:17], 11, v[18:19]
	v_cvt_pk_bf16_f32 v78, v78, v79
	v_cvt_pk_bf16_f32 v79, v80, v81
	v_lshl_add_u64 v[80:81], v[76:77], 0, v[70:71]
	v_lshl_add_u64 v[16:17], s[10:11], 0, v[16:17]
	global_store_dwordx2 v[80:81], v[78:79], off
	v_pk_mul_f32 v[78:79], v[164:165], s[80:81] op_sel_hi:[1,0]
	v_pk_mul_f32 v[80:81], v[166:167], s[80:81] op_sel_hi:[1,0]
	v_pk_mul_f32 v[58:59], v[58:59], s[80:81] op_sel_hi:[1,0]
	v_pk_mul_f32 v[60:61], v[60:61], s[80:81] op_sel_hi:[1,0]
	v_pk_mul_f32 v[54:55], v[54:55], s[80:81] op_sel_hi:[1,0]
	v_pk_mul_f32 v[56:57], v[56:57], s[80:81] op_sel_hi:[1,0]
	v_pk_mul_f32 v[42:43], v[42:43], s[80:81] op_sel_hi:[1,0]
	v_pk_mul_f32 v[44:45], v[44:45], s[80:81] op_sel_hi:[1,0]
	v_pk_mul_f32 v[38:39], v[38:39], s[80:81] op_sel_hi:[1,0]
	v_pk_mul_f32 v[40:41], v[40:41], s[80:81] op_sel_hi:[1,0]
	v_pk_mul_f32 v[26:27], v[26:27], s[80:81] op_sel_hi:[1,0]
	v_pk_mul_f32 v[28:29], v[28:29], s[80:81] op_sel_hi:[1,0]
	v_pk_mul_f32 v[22:23], v[22:23], s[80:81] op_sel_hi:[1,0]
	v_pk_mul_f32 v[24:25], v[24:25], s[80:81] op_sel_hi:[1,0]
	v_lshl_add_u64 v[16:17], v[16:17], 0, s[0:1]
	v_pk_mul_f32 v[10:11], v[10:11], s[80:81] op_sel_hi:[1,0]
	v_pk_mul_f32 v[12:13], v[12:13], s[80:81] op_sel_hi:[1,0]
	v_pk_mul_f32 v[6:7], v[6:7], s[80:81] op_sel_hi:[1,0]
	v_pk_mul_f32 v[8:9], v[8:9], s[80:81] op_sel_hi:[1,0]
	v_pk_mul_f32 v[2:3], v[2:3], s[80:81] op_sel_hi:[1,0]
	v_pk_mul_f32 v[4:5], v[4:5], s[80:81] op_sel_hi:[1,0]
	v_cvt_pk_bf16_f32 v78, v78, v79
	v_cvt_pk_bf16_f32 v79, v80, v81
	v_lshl_add_u64 v[80:81], v[76:77], 0, v[72:73]
	v_lshl_add_u64 v[66:67], v[64:65], 0, v[0:1]
	v_cvt_pk_bf16_f32 v58, v58, v59
	v_cvt_pk_bf16_f32 v59, v60, v61
	v_lshl_add_u64 v[60:61], v[64:65], 0, v[70:71]
	v_cvt_pk_bf16_f32 v54, v54, v55
	v_cvt_pk_bf16_f32 v55, v56, v57
	v_lshl_add_u64 v[56:57], v[64:65], 0, v[72:73]
	v_lshl_add_u64 v[50:51], v[48:49], 0, v[0:1]
	v_cvt_pk_bf16_f32 v42, v42, v43
	v_cvt_pk_bf16_f32 v43, v44, v45
	v_lshl_add_u64 v[44:45], v[48:49], 0, v[70:71]
	v_cvt_pk_bf16_f32 v38, v38, v39
	v_cvt_pk_bf16_f32 v39, v40, v41
	v_lshl_add_u64 v[40:41], v[48:49], 0, v[72:73]
	v_lshl_add_u64 v[34:35], v[32:33], 0, v[0:1]
	v_cvt_pk_bf16_f32 v26, v26, v27
	v_cvt_pk_bf16_f32 v27, v28, v29
	v_lshl_add_u64 v[28:29], v[32:33], 0, v[70:71]
	v_cvt_pk_bf16_f32 v22, v22, v23
	v_cvt_pk_bf16_f32 v23, v24, v25
	v_lshl_add_u64 v[24:25], v[32:33], 0, v[72:73]
	v_lshl_add_u64 v[18:19], v[16:17], 0, v[0:1]
	v_cvt_pk_bf16_f32 v10, v10, v11
	v_cvt_pk_bf16_f32 v11, v12, v13
	v_lshl_add_u64 v[12:13], v[16:17], 0, v[70:71]
	v_cvt_pk_bf16_f32 v6, v6, v7
	v_cvt_pk_bf16_f32 v7, v8, v9
	v_lshl_add_u64 v[8:9], v[16:17], 0, v[72:73]
	v_cvt_pk_bf16_f32 v2, v2, v3
	v_cvt_pk_bf16_f32 v3, v4, v5
	v_lshl_add_u64 v[4:5], v[16:17], 0, v[74:75]
	global_store_dwordx2 v[112:113], v[110:111], off
	global_store_dwordx2 v[108:109], v[106:107], off
	global_store_dwordx2 v[104:105], v[102:103], off
	global_store_dwordx2 v[96:97], v[94:95], off
	global_store_dwordx2 v[92:93], v[90:91], off
	global_store_dwordx2 v[88:89], v[86:87], off
	global_store_dwordx2 v[80:81], v[78:79], off
	global_store_dwordx2 v[66:67], v[62:63], off
	global_store_dwordx2 v[60:61], v[58:59], off
	global_store_dwordx2 v[56:57], v[54:55], off
	global_store_dwordx2 v[50:51], v[46:47], off
	global_store_dwordx2 v[44:45], v[42:43], off
	global_store_dwordx2 v[40:41], v[38:39], off
	global_store_dwordx2 v[34:35], v[30:31], off
	global_store_dwordx2 v[28:29], v[26:27], off
	global_store_dwordx2 v[24:25], v[22:23], off
	global_store_dwordx2 v[18:19], v[14:15], off
	global_store_dwordx2 v[12:13], v[10:11], off
	global_store_dwordx2 v[8:9], v[6:7], off
	global_store_dwordx2 v[4:5], v[2:3], off

.LBB0_1295:
	s_and_b32 s5, s4, 0x10000
	s_xor_b32 s6, s5, 0x10000
	v_add_u32_e32 v166, s6, v154
	v_add_u32_e32 v167, 0x8000, v166
	v_readfirstlane_b32 s6, v166
	v_lshl_add_u64 v[164:165], v[144:145], 0, s[0:1]
	s_mov_b32 m0, s6
	v_readfirstlane_b32 s6, v167
	v_add_u32_e32 v167, 0x2000, v166
	global_load_lds_dwordx4 v[164:165], off
	v_lshl_add_u64 v[164:165], v[136:137], 0, s[0:1]
	s_mov_b32 m0, s6
	v_readfirstlane_b32 s6, v167
	v_add_u32_e32 v167, 0xa000, v166
	global_load_lds_dwordx4 v[164:165], off
	v_lshl_add_u64 v[164:165], v[142:143], 0, s[0:1]
	s_mov_b32 m0, s6
	v_readfirstlane_b32 s6, v167
	v_add_u32_e32 v167, 0x4000, v166
	global_load_lds_dwordx4 v[164:165], off
	v_lshl_add_u64 v[164:165], v[134:135], 0, s[0:1]
	s_mov_b32 m0, s6
	v_readfirstlane_b32 s6, v167
	v_add_u32_e32 v167, 0xc000, v166
	global_load_lds_dwordx4 v[164:165], off
	v_lshl_add_u64 v[164:165], v[140:141], 0, s[0:1]
	s_mov_b32 m0, s6
	v_readfirstlane_b32 s6, v167
	v_add_u32_e32 v167, 0x6000, v166
	global_load_lds_dwordx4 v[164:165], off
	v_lshl_add_u64 v[164:165], v[132:133], 0, s[0:1]
	s_mov_b32 m0, s6
	v_readfirstlane_b32 s6, v167
	v_add_u32_e32 v166, 0xe000, v166
	global_load_lds_dwordx4 v[164:165], off
	v_lshl_add_u64 v[164:165], v[138:139], 0, s[0:1]
	s_mov_b32 m0, s6
	v_readfirstlane_b32 s6, v166
	global_load_lds_dwordx4 v[164:165], off
	v_lshl_add_u64 v[164:165], v[130:131], 0, s[0:1]
	s_mov_b32 m0, s6
	s_addk_i32 s5, 0x400
	global_load_lds_dwordx4 v[164:165], off
	v_add3_u32 v188, s5, v160, v161
	v_add3_u32 v189, s5, v160, v163
	v_add3_u32 v190, s5, v152, v162
	ds_read_b128 v[164:167], v189 offset:34816
	ds_read_b128 v[168:171], v189 offset:36864
	ds_read_b128 v[172:175], v189 offset:32768
	ds_read_b128 v[176:179], v188
	ds_read_b128 v[180:183], v189 offset:38912
	ds_read_b128 v[184:187], v190
	s_setprio 1
	s_waitcnt lgkmcnt(0)
	v_mfma_f32_16x16x32_bf16 v[126:129], v[172:175], v[176:179], v[126:129]
	v_mfma_f32_16x16x32_bf16 v[122:125], v[164:167], v[176:179], v[122:125]
	v_mfma_f32_16x16x32_bf16 v[118:121], v[168:171], v[176:179], v[118:121]
	v_mfma_f32_16x16x32_bf16 v[114:117], v[180:183], v[176:179], v[114:117]
	s_setprio 0
	v_add3_u32 v191, s5, v152, v159
	ds_read_b128 v[176:179], v191
	s_setprio 1
	v_mfma_f32_16x16x32_bf16 v[110:113], v[172:175], v[184:187], v[110:113]
	v_mfma_f32_16x16x32_bf16 v[106:109], v[164:167], v[184:187], v[106:109]
	v_mfma_f32_16x16x32_bf16 v[102:105], v[168:171], v[184:187], v[102:105]
	v_mfma_f32_16x16x32_bf16 v[98:101], v[180:183], v[184:187], v[98:101]
	s_setprio 0
	v_add3_u32 v192, s5, v152, v158
	ds_read_b128 v[184:187], v192
	s_setprio 1
	s_waitcnt lgkmcnt(0)
	v_mfma_f32_16x16x32_bf16 v[94:97], v[172:175], v[176:179], v[94:97]
	v_mfma_f32_16x16x32_bf16 v[90:93], v[164:167], v[176:179], v[90:93]
	v_mfma_f32_16x16x32_bf16 v[86:89], v[168:171], v[176:179], v[86:89]
	v_mfma_f32_16x16x32_bf16 v[82:85], v[180:183], v[176:179], v[82:85]
	s_setprio 0
	v_add3_u32 v193, s5, v152, v157
	ds_read_b128 v[176:179], v193
	s_setprio 1
	v_mfma_f32_16x16x32_bf16 v[78:81], v[172:175], v[184:187], v[78:81]
	v_mfma_f32_16x16x32_bf16 v[74:77], v[164:167], v[184:187], v[74:77]
	v_mfma_f32_16x16x32_bf16 v[70:73], v[168:171], v[184:187], v[70:73]
	v_mfma_f32_16x16x32_bf16 v[66:69], v[180:183], v[184:187], v[66:69]
	s_setprio 0
	v_add3_u32 v194, s5, v152, v156
	ds_read_b128 v[184:187], v194
	s_setprio 1
	s_waitcnt lgkmcnt(0)
	v_mfma_f32_16x16x32_bf16 v[62:65], v[172:175], v[176:179], v[62:65]
	v_mfma_f32_16x16x32_bf16 v[58:61], v[164:167], v[176:179], v[58:61]
	v_mfma_f32_16x16x32_bf16 v[54:57], v[168:171], v[176:179], v[54:57]
	v_mfma_f32_16x16x32_bf16 v[50:53], v[180:183], v[176:179], v[50:53]
	s_setprio 0
	v_add3_u32 v195, s5, v152, v155
	ds_read_b128 v[176:179], v195
	s_setprio 1
	v_mfma_f32_16x16x32_bf16 v[46:49], v[172:175], v[184:187], v[46:49]
	v_mfma_f32_16x16x32_bf16 v[42:45], v[164:167], v[184:187], v[42:45]
	v_mfma_f32_16x16x32_bf16 v[38:41], v[168:171], v[184:187], v[38:41]
	v_mfma_f32_16x16x32_bf16 v[34:37], v[180:183], v[184:187], v[34:37]
	s_setprio 0
	v_add3_u32 v196, s5, v152, v153
	ds_read_b128 v[184:187], v196
	s_setprio 1
	s_waitcnt lgkmcnt(0)
	v_mfma_f32_16x16x32_bf16 v[30:33], v[172:175], v[176:179], v[30:33]
	v_mfma_f32_16x16x32_bf16 v[26:29], v[164:167], v[176:179], v[26:29]
	v_mfma_f32_16x16x32_bf16 v[22:25], v[168:171], v[176:179], v[22:25]
	v_mfma_f32_16x16x32_bf16 v[18:21], v[180:183], v[176:179], v[18:21]
	s_setprio 0
	s_setprio 1
	v_mfma_f32_16x16x32_bf16 v[14:17], v[172:175], v[184:187], v[14:17]
	v_mfma_f32_16x16x32_bf16 v[10:13], v[164:167], v[184:187], v[10:13]
	v_mfma_f32_16x16x32_bf16 v[6:9], v[168:171], v[184:187], v[6:9]
	v_mfma_f32_16x16x32_bf16 v[2:5], v[180:183], v[184:187], v[2:5]
	s_setprio 0
	ds_read_b128 v[164:167], v189 offset:33792
	ds_read_b128 v[168:171], v189 offset:35840
	ds_read_b128 v[172:175], v189 offset:37888
	ds_read_b128 v[176:179], v189 offset:39936
	ds_read_b128 v[180:183], v188 offset:1024
	ds_read_b128 v[184:187], v190 offset:1024
	s_setprio 1
	s_waitcnt lgkmcnt(0)
	v_mfma_f32_16x16x32_bf16 v[126:129], v[164:167], v[180:183], v[126:129]
	v_mfma_f32_16x16x32_bf16 v[122:125], v[168:171], v[180:183], v[122:125]
	v_mfma_f32_16x16x32_bf16 v[118:121], v[172:175], v[180:183], v[118:121]
	v_mfma_f32_16x16x32_bf16 v[114:117], v[176:179], v[180:183], v[114:117]
	s_setprio 0
	ds_read_b128 v[180:183], v191 offset:1024
	s_setprio 1
	v_mfma_f32_16x16x32_bf16 v[110:113], v[164:167], v[184:187], v[110:113]
	v_mfma_f32_16x16x32_bf16 v[106:109], v[168:171], v[184:187], v[106:109]
	v_mfma_f32_16x16x32_bf16 v[102:105], v[172:175], v[184:187], v[102:105]
	v_mfma_f32_16x16x32_bf16 v[98:101], v[176:179], v[184:187], v[98:101]
	s_setprio 0
	ds_read_b128 v[184:187], v192 offset:1024
	s_setprio 1
	s_waitcnt lgkmcnt(0)
	v_mfma_f32_16x16x32_bf16 v[94:97], v[164:167], v[180:183], v[94:97]
	v_mfma_f32_16x16x32_bf16 v[90:93], v[168:171], v[180:183], v[90:93]
	v_mfma_f32_16x16x32_bf16 v[86:89], v[172:175], v[180:183], v[86:89]
	v_mfma_f32_16x16x32_bf16 v[82:85], v[176:179], v[180:183], v[82:85]
	s_setprio 0
	ds_read_b128 v[180:183], v193 offset:1024
	s_setprio 1
	v_mfma_f32_16x16x32_bf16 v[78:81], v[164:167], v[184:187], v[78:81]
	v_mfma_f32_16x16x32_bf16 v[74:77], v[168:171], v[184:187], v[74:77]
	v_mfma_f32_16x16x32_bf16 v[70:73], v[172:175], v[184:187], v[70:73]
	v_mfma_f32_16x16x32_bf16 v[66:69], v[176:179], v[184:187], v[66:69]
	s_setprio 0
	ds_read_b128 v[184:187], v194 offset:1024
	s_setprio 1
	s_waitcnt lgkmcnt(0)
	v_mfma_f32_16x16x32_bf16 v[62:65], v[164:167], v[180:183], v[62:65]
	v_mfma_f32_16x16x32_bf16 v[58:61], v[168:171], v[180:183], v[58:61]
	v_mfma_f32_16x16x32_bf16 v[54:57], v[172:175], v[180:183], v[54:57]
	v_mfma_f32_16x16x32_bf16 v[50:53], v[176:179], v[180:183], v[50:53]
	s_setprio 0
	ds_read_b128 v[180:183], v195 offset:1024
	s_setprio 1
	v_mfma_f32_16x16x32_bf16 v[46:49], v[164:167], v[184:187], v[46:49]
	v_mfma_f32_16x16x32_bf16 v[42:45], v[168:171], v[184:187], v[42:45]
	v_mfma_f32_16x16x32_bf16 v[38:41], v[172:175], v[184:187], v[38:41]
	v_mfma_f32_16x16x32_bf16 v[34:37], v[176:179], v[184:187], v[34:37]
	s_setprio 0
	ds_read_b128 v[184:187], v196 offset:1024
	s_setprio 1
	s_waitcnt lgkmcnt(0)
	v_mfma_f32_16x16x32_bf16 v[30:33], v[164:167], v[180:183], v[30:33]
	v_mfma_f32_16x16x32_bf16 v[26:29], v[168:171], v[180:183], v[26:29]
	v_mfma_f32_16x16x32_bf16 v[22:25], v[172:175], v[180:183], v[22:25]
	v_mfma_f32_16x16x32_bf16 v[18:21], v[176:179], v[180:183], v[18:21]
	s_setprio 0
	s_setprio 1
	v_mfma_f32_16x16x32_bf16 v[14:17], v[164:167], v[184:187], v[14:17]
	v_mfma_f32_16x16x32_bf16 v[10:13], v[168:171], v[184:187], v[10:13]
	v_mfma_f32_16x16x32_bf16 v[6:9], v[172:175], v[184:187], v[6:9]
	v_mfma_f32_16x16x32_bf16 v[2:5], v[176:179], v[184:187], v[2:5]
	s_setprio 0
	s_add_i32 s4, s4, 0x10000
	s_waitcnt vmcnt(0)
	s_add_u32 s0, s0, 0x80
	s_addc_u32 s1, s1, 0
	s_cmpk_lg_i32 s0, 0x2000
	s_waitcnt vmcnt(0)
	s_barrier
	s_cbranch_scc1 .LBB0_1295
	s_movk_i32 s0, 0x400
	v_add3_u32 v168, s0, v160, v163
	v_add3_u32 v169, s0, v160, v161
	v_add3_u32 v170, s0, v152, v162
	ds_read_b128 v[130:133], v168 offset:32768
	ds_read_b128 v[134:137], v168 offset:34816
	ds_read_b128 v[138:141], v168 offset:36864
	ds_read_b128 v[142:145], v168 offset:38912
	ds_read_b128 v[160:163], v169
	ds_read_b128 v[164:167], v170
	s_setprio 1
	s_waitcnt lgkmcnt(1)
	v_mfma_f32_16x16x32_bf16 v[126:129], v[130:133], v[160:163], v[126:129]
	v_mfma_f32_16x16x32_bf16 v[122:125], v[134:137], v[160:163], v[122:125]
	v_mfma_f32_16x16x32_bf16 v[118:121], v[138:141], v[160:163], v[118:121]
	v_mfma_f32_16x16x32_bf16 v[114:117], v[142:145], v[160:163], v[114:117]
	s_setprio 0
	v_add3_u32 v171, s0, v152, v159
	ds_read_b128 v[160:163], v171
	s_setprio 1
	s_waitcnt lgkmcnt(1)
	v_mfma_f32_16x16x32_bf16 v[110:113], v[130:133], v[164:167], v[110:113]
	v_mfma_f32_16x16x32_bf16 v[106:109], v[134:137], v[164:167], v[106:109]
	v_mfma_f32_16x16x32_bf16 v[102:105], v[138:141], v[164:167], v[102:105]
	v_mfma_f32_16x16x32_bf16 v[98:101], v[142:145], v[164:167], v[98:101]
	s_setprio 0
	v_add3_u32 v172, s0, v152, v158
	ds_read_b128 v[164:167], v172
	s_setprio 1
	s_waitcnt lgkmcnt(1)
	v_mfma_f32_16x16x32_bf16 v[94:97], v[130:133], v[160:163], v[94:97]
	v_mfma_f32_16x16x32_bf16 v[90:93], v[134:137], v[160:163], v[90:93]
	v_mfma_f32_16x16x32_bf16 v[86:89], v[138:141], v[160:163], v[86:89]
	v_mfma_f32_16x16x32_bf16 v[82:85], v[142:145], v[160:163], v[82:85]
	s_setprio 0
	v_add3_u32 v173, s0, v152, v157
	ds_read_b128 v[158:161], v173
	s_setprio 1
	s_waitcnt lgkmcnt(1)
	v_mfma_f32_16x16x32_bf16 v[78:81], v[130:133], v[164:167], v[78:81]
	v_mfma_f32_16x16x32_bf16 v[74:77], v[134:137], v[164:167], v[74:77]
	v_mfma_f32_16x16x32_bf16 v[70:73], v[138:141], v[164:167], v[70:73]
	v_mfma_f32_16x16x32_bf16 v[66:69], v[142:145], v[164:167], v[66:69]
	s_setprio 0
	v_add3_u32 v174, s0, v152, v156
	ds_read_b128 v[162:165], v174
	s_setprio 1
	s_waitcnt lgkmcnt(1)
	v_mfma_f32_16x16x32_bf16 v[62:65], v[130:133], v[158:161], v[62:65]
	v_mfma_f32_16x16x32_bf16 v[58:61], v[134:137], v[158:161], v[58:61]
	v_mfma_f32_16x16x32_bf16 v[54:57], v[138:141], v[158:161], v[54:57]
	v_mfma_f32_16x16x32_bf16 v[50:53], v[142:145], v[158:161], v[50:53]
	s_setprio 0
	v_add3_u32 v175, s0, v152, v155
	ds_read_b128 v[154:157], v175
	s_setprio 1
	s_waitcnt lgkmcnt(1)
	v_mfma_f32_16x16x32_bf16 v[46:49], v[130:133], v[162:165], v[46:49]
	v_mfma_f32_16x16x32_bf16 v[42:45], v[134:137], v[162:165], v[42:45]
	v_mfma_f32_16x16x32_bf16 v[38:41], v[138:141], v[162:165], v[38:41]
	v_mfma_f32_16x16x32_bf16 v[34:37], v[142:145], v[162:165], v[34:37]
	s_setprio 0
	v_add3_u32 v176, s0, v152, v153
	ds_read_b128 v[158:161], v176
	s_setprio 1
	s_waitcnt lgkmcnt(1)
	v_mfma_f32_16x16x32_bf16 v[30:33], v[130:133], v[154:157], v[30:33]
	v_mfma_f32_16x16x32_bf16 v[26:29], v[134:137], v[154:157], v[26:29]
	v_mfma_f32_16x16x32_bf16 v[22:25], v[138:141], v[154:157], v[22:25]
	v_mfma_f32_16x16x32_bf16 v[18:21], v[142:145], v[154:157], v[18:21]
	s_setprio 0
	s_setprio 1
	s_waitcnt lgkmcnt(0)
	v_mfma_f32_16x16x32_bf16 v[14:17], v[130:133], v[158:161], v[14:17]
	v_mfma_f32_16x16x32_bf16 v[10:13], v[134:137], v[158:161], v[10:13]
	v_mfma_f32_16x16x32_bf16 v[6:9], v[138:141], v[158:161], v[6:9]
	v_mfma_f32_16x16x32_bf16 v[2:5], v[142:145], v[158:161], v[2:5]
	s_setprio 0
	ds_read_b128 v[130:133], v168 offset:33792
	ds_read_b128 v[134:137], v168 offset:35840
	ds_read_b128 v[138:141], v168 offset:37888
	ds_read_b128 v[142:145], v168 offset:39936
	ds_read_b128 v[152:155], v169 offset:1024
	ds_read_b128 v[156:159], v170 offset:1024
	s_setprio 1
	s_waitcnt lgkmcnt(1)
	v_mfma_f32_16x16x32_bf16 v[126:129], v[130:133], v[152:155], v[126:129]
	v_mfma_f32_16x16x32_bf16 v[122:125], v[134:137], v[152:155], v[122:125]
	v_mfma_f32_16x16x32_bf16 v[118:121], v[138:141], v[152:155], v[118:121]
	v_mfma_f32_16x16x32_bf16 v[114:117], v[142:145], v[152:155], v[114:117]
	s_setprio 0
	ds_read_b128 v[152:155], v171 offset:1024
	s_setprio 1
	s_waitcnt lgkmcnt(1)
	v_mfma_f32_16x16x32_bf16 v[110:113], v[130:133], v[156:159], v[110:113]
	v_mfma_f32_16x16x32_bf16 v[106:109], v[134:137], v[156:159], v[106:109]
	v_mfma_f32_16x16x32_bf16 v[102:105], v[138:141], v[156:159], v[102:105]
	v_mfma_f32_16x16x32_bf16 v[98:101], v[142:145], v[156:159], v[98:101]
	s_setprio 0
	ds_read_b128 v[156:159], v172 offset:1024
	s_setprio 1
	s_waitcnt lgkmcnt(1)
	v_mfma_f32_16x16x32_bf16 v[94:97], v[130:133], v[152:155], v[94:97]
	v_mfma_f32_16x16x32_bf16 v[90:93], v[134:137], v[152:155], v[90:93]
	v_mfma_f32_16x16x32_bf16 v[86:89], v[138:141], v[152:155], v[86:89]
	v_mfma_f32_16x16x32_bf16 v[82:85], v[142:145], v[152:155], v[82:85]
	s_setprio 0
	ds_read_b128 v[152:155], v173 offset:1024
	s_setprio 1
	s_waitcnt lgkmcnt(1)
	v_mfma_f32_16x16x32_bf16 v[78:81], v[130:133], v[156:159], v[78:81]
	v_mfma_f32_16x16x32_bf16 v[160:163], v[134:137], v[156:159], v[74:77]
	v_mfma_f32_16x16x32_bf16 v[164:167], v[138:141], v[156:159], v[70:73]
	v_mfma_f32_16x16x32_bf16 v[66:69], v[142:145], v[156:159], v[66:69]
	s_setprio 0
	s_nop 0
	ds_read_b128 v[70:73], v174 offset:1024
	s_setprio 1
	s_waitcnt lgkmcnt(1)
	v_mfma_f32_16x16x32_bf16 v[62:65], v[130:133], v[152:155], v[62:65]
	v_mfma_f32_16x16x32_bf16 v[58:61], v[134:137], v[152:155], v[58:61]
	v_mfma_f32_16x16x32_bf16 v[54:57], v[138:141], v[152:155], v[54:57]
	v_mfma_f32_16x16x32_bf16 v[50:53], v[142:145], v[152:155], v[50:53]
	s_setprio 0
	ds_read_b128 v[74:77], v175 offset:1024
	s_setprio 1
	s_waitcnt lgkmcnt(1)
	v_mfma_f32_16x16x32_bf16 v[46:49], v[130:133], v[70:73], v[46:49]
	v_mfma_f32_16x16x32_bf16 v[42:45], v[134:137], v[70:73], v[42:45]
	v_mfma_f32_16x16x32_bf16 v[38:41], v[138:141], v[70:73], v[38:41]
	v_mfma_f32_16x16x32_bf16 v[34:37], v[142:145], v[70:73], v[34:37]
	s_setprio 0
	ds_read_b128 v[70:73], v176 offset:1024
	s_setprio 1
	s_waitcnt lgkmcnt(1)
	v_mfma_f32_16x16x32_bf16 v[30:33], v[130:133], v[74:77], v[30:33]
	v_mfma_f32_16x16x32_bf16 v[26:29], v[134:137], v[74:77], v[26:29]
	v_mfma_f32_16x16x32_bf16 v[22:25], v[138:141], v[74:77], v[22:25]
	v_mfma_f32_16x16x32_bf16 v[18:21], v[142:145], v[74:77], v[18:21]
	s_setprio 0
	s_setprio 1
	s_waitcnt lgkmcnt(0)
	v_mfma_f32_16x16x32_bf16 v[14:17], v[130:133], v[70:73], v[14:17]
	v_mfma_f32_16x16x32_bf16 v[10:13], v[134:137], v[70:73], v[10:13]
	v_mfma_f32_16x16x32_bf16 v[6:9], v[138:141], v[70:73], v[6:9]
	v_mfma_f32_16x16x32_bf16 v[2:5], v[142:145], v[70:73], v[2:5]
	s_setprio 0
	v_or_b32_e32 v70, s2, v147
	s_lshr_b32 s0, s3, 8
	v_add_u32_e32 v70, v70, v151
	s_mulk_i32 s0, 0x1100
	s_add_i32 s56, s0, 0x100
	v_ashrrev_i32_e32 v71, 31, v70
	v_lshl_add_u64 v[72:73], v[70:71], 0, s[56:57]
	v_lshlrev_b64 v[72:73], 11, v[72:73]
	v_lshrrev_b32_e32 v0, 1, v0
	v_lshl_add_u64 v[72:73], s[10:11], 0, v[72:73]
	s_mov_b64 s[0:1], 0x4e80600
	v_and_b32_e32 v0, 24, v0
	v_pk_mul_f32 v[74:75], v[126:127], s[84:85] op_sel_hi:[1,0]
	v_pk_mul_f32 v[76:77], v[128:129], s[84:85] op_sel_hi:[1,0]
	v_lshl_add_u64 v[126:127], v[72:73], 0, s[0:1]
	v_lshl_or_b32 v0, v146, 7, v0
	v_cvt_pk_bf16_f32 v74, v74, v75
	v_cvt_pk_bf16_f32 v75, v76, v77
	v_lshl_add_u64 v[72:73], v[126:127], 0, v[0:1]
	s_waitcnt vmcnt(0)
	s_barrier
	global_store_dwordx2 v[72:73], v[74:75], off
	v_pk_mul_f32 v[72:73], v[122:123], s[84:85] op_sel_hi:[1,0]
	v_pk_mul_f32 v[110:111], v[110:111], s[84:85] op_sel_hi:[1,0]
	v_cvt_pk_bf16_f32 v74, v72, v73
	v_pk_mul_f32 v[72:73], v[124:125], s[84:85] op_sel_hi:[1,0]
	v_pk_mul_f32 v[112:113], v[112:113], s[84:85] op_sel_hi:[1,0]
	v_cvt_pk_bf16_f32 v75, v72, v73
	v_or_b32_e32 v72, 32, v0
	v_mov_b32_e32 v73, v1
	v_lshl_add_u64 v[76:77], v[126:127], 0, v[72:73]
	global_store_dwordx2 v[76:77], v[74:75], off
	v_pk_mul_f32 v[74:75], v[118:119], s[84:85] op_sel_hi:[1,0]
	v_cvt_pk_bf16_f32 v110, v110, v111
	v_cvt_pk_bf16_f32 v76, v74, v75
	v_pk_mul_f32 v[74:75], v[120:121], s[84:85] op_sel_hi:[1,0]
	v_cvt_pk_bf16_f32 v111, v112, v113
	v_cvt_pk_bf16_f32 v77, v74, v75
	v_or_b32_e32 v74, 64, v0
	v_mov_b32_e32 v75, v1
	v_lshl_add_u64 v[118:119], v[126:127], 0, v[74:75]
	global_store_dwordx2 v[118:119], v[76:77], off
	v_pk_mul_f32 v[76:77], v[114:115], s[84:85] op_sel_hi:[1,0]
	v_pk_mul_f32 v[98:99], v[98:99], s[84:85] op_sel_hi:[1,0]
	v_cvt_pk_bf16_f32 v114, v76, v77
	v_pk_mul_f32 v[76:77], v[116:117], s[84:85] op_sel_hi:[1,0]
	v_pk_mul_f32 v[100:101], v[100:101], s[84:85] op_sel_hi:[1,0]
	v_cvt_pk_bf16_f32 v115, v76, v77
	v_or_b32_e32 v76, 0x60, v0
	v_mov_b32_e32 v77, v1
	v_lshl_add_u64 v[116:117], v[126:127], 0, v[76:77]
	global_store_dwordx2 v[116:117], v[114:115], off
	v_or_b32_e32 v114, 16, v70
	v_ashrrev_i32_e32 v115, 31, v114
	v_lshl_add_u64 v[114:115], v[114:115], 0, s[56:57]
	v_lshlrev_b64 v[112:113], 11, v[114:115]
	v_lshl_add_u64 v[112:113], s[10:11], 0, v[112:113]
	v_lshl_add_u64 v[112:113], v[112:113], 0, s[0:1]
	v_cvt_pk_bf16_f32 v98, v98, v99
	v_cvt_pk_bf16_f32 v99, v100, v101
	v_lshl_add_u64 v[100:101], v[112:113], 0, v[76:77]
	global_store_dwordx2 v[100:101], v[98:99], off
	v_or_b32_e32 v98, 32, v70
	v_ashrrev_i32_e32 v99, 31, v98
	v_lshl_add_u64 v[98:99], v[98:99], 0, s[56:57]
	v_pk_mul_f32 v[94:95], v[94:95], s[84:85] op_sel_hi:[1,0]
	v_pk_mul_f32 v[96:97], v[96:97], s[84:85] op_sel_hi:[1,0]
	v_cvt_pk_bf16_f32 v94, v94, v95
	v_cvt_pk_bf16_f32 v95, v96, v97
	v_lshlrev_b64 v[96:97], 11, v[98:99]
	v_lshl_add_u64 v[96:97], s[10:11], 0, v[96:97]
	v_lshl_add_u64 v[96:97], v[96:97], 0, s[0:1]
	v_pk_mul_f32 v[82:83], v[82:83], s[84:85] op_sel_hi:[1,0]
	v_pk_mul_f32 v[84:85], v[84:85], s[84:85] op_sel_hi:[1,0]
	v_cvt_pk_bf16_f32 v82, v82, v83
	v_cvt_pk_bf16_f32 v83, v84, v85
	v_lshl_add_u64 v[84:85], v[96:97], 0, v[76:77]
	global_store_dwordx2 v[84:85], v[82:83], off
	v_or_b32_e32 v82, 48, v70
	v_ashrrev_i32_e32 v83, 31, v82
	v_lshl_add_u64 v[82:83], v[82:83], 0, s[56:57]
	v_pk_mul_f32 v[78:79], v[78:79], s[84:85] op_sel_hi:[1,0]
	v_pk_mul_f32 v[80:81], v[80:81], s[84:85] op_sel_hi:[1,0]
	v_cvt_pk_bf16_f32 v78, v78, v79
	v_cvt_pk_bf16_f32 v79, v80, v81
	v_lshlrev_b64 v[80:81], 11, v[82:83]
	v_lshl_add_u64 v[80:81], s[10:11], 0, v[80:81]
	v_lshl_add_u64 v[80:81], v[80:81], 0, s[0:1]
	v_pk_mul_f32 v[66:67], v[66:67], s[84:85] op_sel_hi:[1,0]
	v_pk_mul_f32 v[68:69], v[68:69], s[84:85] op_sel_hi:[1,0]
	v_cvt_pk_bf16_f32 v66, v66, v67
	v_cvt_pk_bf16_f32 v67, v68, v69
	v_lshl_add_u64 v[68:69], v[80:81], 0, v[76:77]
	global_store_dwordx2 v[68:69], v[66:67], off
	v_or_b32_e32 v66, 64, v70
	v_ashrrev_i32_e32 v67, 31, v66
	v_lshl_add_u64 v[66:67], v[66:67], 0, s[56:57]
	v_pk_mul_f32 v[62:63], v[62:63], s[84:85] op_sel_hi:[1,0]
	v_pk_mul_f32 v[64:65], v[64:65], s[84:85] op_sel_hi:[1,0]
	v_cvt_pk_bf16_f32 v62, v62, v63
	v_cvt_pk_bf16_f32 v63, v64, v65
	v_lshlrev_b64 v[64:65], 11, v[66:67]
	v_lshl_add_u64 v[64:65], s[10:11], 0, v[64:65]
	v_lshl_add_u64 v[64:65], v[64:65], 0, s[0:1]
	v_pk_mul_f32 v[50:51], v[50:51], s[84:85] op_sel_hi:[1,0]
	v_pk_mul_f32 v[52:53], v[52:53], s[84:85] op_sel_hi:[1,0]
	v_cvt_pk_bf16_f32 v50, v50, v51
	v_cvt_pk_bf16_f32 v51, v52, v53
	v_lshl_add_u64 v[52:53], v[64:65], 0, v[76:77]
	global_store_dwordx2 v[52:53], v[50:51], off
	v_or_b32_e32 v50, 0x50, v70
	v_ashrrev_i32_e32 v51, 31, v50
	v_lshl_add_u64 v[50:51], v[50:51], 0, s[56:57]
	v_pk_mul_f32 v[46:47], v[46:47], s[84:85] op_sel_hi:[1,0]
	v_pk_mul_f32 v[48:49], v[48:49], s[84:85] op_sel_hi:[1,0]
	v_cvt_pk_bf16_f32 v46, v46, v47
	v_cvt_pk_bf16_f32 v47, v48, v49
	v_lshlrev_b64 v[48:49], 11, v[50:51]
	v_lshl_add_u64 v[48:49], s[10:11], 0, v[48:49]
	v_lshl_add_u64 v[48:49], v[48:49], 0, s[0:1]
	v_pk_mul_f32 v[34:35], v[34:35], s[84:85] op_sel_hi:[1,0]
	v_pk_mul_f32 v[36:37], v[36:37], s[84:85] op_sel_hi:[1,0]
	v_cvt_pk_bf16_f32 v34, v34, v35
	v_cvt_pk_bf16_f32 v35, v36, v37
	v_lshl_add_u64 v[36:37], v[48:49], 0, v[76:77]
	global_store_dwordx2 v[36:37], v[34:35], off
	v_or_b32_e32 v34, 0x60, v70
	v_ashrrev_i32_e32 v35, 31, v34
	v_lshl_add_u64 v[34:35], v[34:35], 0, s[56:57]
	v_pk_mul_f32 v[30:31], v[30:31], s[84:85] op_sel_hi:[1,0]
	v_pk_mul_f32 v[32:33], v[32:33], s[84:85] op_sel_hi:[1,0]
	v_cvt_pk_bf16_f32 v30, v30, v31
	v_cvt_pk_bf16_f32 v31, v32, v33
	v_lshlrev_b64 v[32:33], 11, v[34:35]
	v_lshl_add_u64 v[32:33], s[10:11], 0, v[32:33]
	v_lshl_add_u64 v[32:33], v[32:33], 0, s[0:1]
	v_pk_mul_f32 v[18:19], v[18:19], s[84:85] op_sel_hi:[1,0]
	v_pk_mul_f32 v[20:21], v[20:21], s[84:85] op_sel_hi:[1,0]
	v_cvt_pk_bf16_f32 v18, v18, v19
	v_cvt_pk_bf16_f32 v19, v20, v21
	v_lshl_add_u64 v[20:21], v[32:33], 0, v[76:77]
	global_store_dwordx2 v[20:21], v[18:19], off
	v_or_b32_e32 v18, 0x70, v70
	v_ashrrev_i32_e32 v19, 31, v18
	v_lshl_add_u64 v[82:83], v[80:81], 0, v[0:1]
	v_lshl_add_u64 v[18:19], v[18:19], 0, s[56:57]
	v_pk_mul_f32 v[14:15], v[14:15], s[84:85] op_sel_hi:[1,0]
	v_pk_mul_f32 v[16:17], v[16:17], s[84:85] op_sel_hi:[1,0]
	global_store_dwordx2 v[82:83], v[78:79], off
	v_pk_mul_f32 v[78:79], v[160:161], s[84:85] op_sel_hi:[1,0]
	v_pk_mul_f32 v[82:83], v[162:163], s[84:85] op_sel_hi:[1,0]
	v_cvt_pk_bf16_f32 v14, v14, v15
	v_cvt_pk_bf16_f32 v15, v16, v17
	v_lshlrev_b64 v[16:17], 11, v[18:19]
	v_cvt_pk_bf16_f32 v78, v78, v79
	v_cvt_pk_bf16_f32 v79, v82, v83
	v_lshl_add_u64 v[82:83], v[80:81], 0, v[72:73]
	v_lshl_add_u64 v[16:17], s[10:11], 0, v[16:17]
	v_pk_mul_f32 v[106:107], v[106:107], s[84:85] op_sel_hi:[1,0]
	v_pk_mul_f32 v[108:109], v[108:109], s[84:85] op_sel_hi:[1,0]
	v_pk_mul_f32 v[102:103], v[102:103], s[84:85] op_sel_hi:[1,0]
	v_pk_mul_f32 v[104:105], v[104:105], s[84:85] op_sel_hi:[1,0]
	v_pk_mul_f32 v[90:91], v[90:91], s[84:85] op_sel_hi:[1,0]
	v_pk_mul_f32 v[92:93], v[92:93], s[84:85] op_sel_hi:[1,0]
	v_pk_mul_f32 v[86:87], v[86:87], s[84:85] op_sel_hi:[1,0]
	v_pk_mul_f32 v[88:89], v[88:89], s[84:85] op_sel_hi:[1,0]
	global_store_dwordx2 v[82:83], v[78:79], off
	v_pk_mul_f32 v[78:79], v[164:165], s[84:85] op_sel_hi:[1,0]
	v_pk_mul_f32 v[82:83], v[166:167], s[84:85] op_sel_hi:[1,0]
	v_pk_mul_f32 v[58:59], v[58:59], s[84:85] op_sel_hi:[1,0]
	v_pk_mul_f32 v[60:61], v[60:61], s[84:85] op_sel_hi:[1,0]
	v_pk_mul_f32 v[54:55], v[54:55], s[84:85] op_sel_hi:[1,0]
	v_pk_mul_f32 v[56:57], v[56:57], s[84:85] op_sel_hi:[1,0]
	v_pk_mul_f32 v[42:43], v[42:43], s[84:85] op_sel_hi:[1,0]
	v_pk_mul_f32 v[44:45], v[44:45], s[84:85] op_sel_hi:[1,0]
	v_pk_mul_f32 v[38:39], v[38:39], s[84:85] op_sel_hi:[1,0]
	v_pk_mul_f32 v[40:41], v[40:41], s[84:85] op_sel_hi:[1,0]
	v_pk_mul_f32 v[26:27], v[26:27], s[84:85] op_sel_hi:[1,0]
	v_pk_mul_f32 v[28:29], v[28:29], s[84:85] op_sel_hi:[1,0]
	v_pk_mul_f32 v[22:23], v[22:23], s[84:85] op_sel_hi:[1,0]
	v_pk_mul_f32 v[24:25], v[24:25], s[84:85] op_sel_hi:[1,0]
	v_lshl_add_u64 v[16:17], v[16:17], 0, s[0:1]
	v_pk_mul_f32 v[10:11], v[10:11], s[84:85] op_sel_hi:[1,0]
	v_pk_mul_f32 v[12:13], v[12:13], s[84:85] op_sel_hi:[1,0]
	v_pk_mul_f32 v[6:7], v[6:7], s[84:85] op_sel_hi:[1,0]
	v_pk_mul_f32 v[8:9], v[8:9], s[84:85] op_sel_hi:[1,0]
	v_pk_mul_f32 v[2:3], v[2:3], s[84:85] op_sel_hi:[1,0]
	v_pk_mul_f32 v[4:5], v[4:5], s[84:85] op_sel_hi:[1,0]
	v_lshl_add_u64 v[114:115], v[112:113], 0, v[0:1]
	v_cvt_pk_bf16_f32 v106, v106, v107
	v_cvt_pk_bf16_f32 v107, v108, v109
	v_lshl_add_u64 v[108:109], v[112:113], 0, v[72:73]
	v_cvt_pk_bf16_f32 v102, v102, v103
	v_cvt_pk_bf16_f32 v103, v104, v105
	v_lshl_add_u64 v[104:105], v[112:113], 0, v[74:75]
	v_lshl_add_u64 v[98:99], v[96:97], 0, v[0:1]
	v_cvt_pk_bf16_f32 v90, v90, v91
	v_cvt_pk_bf16_f32 v91, v92, v93
	v_lshl_add_u64 v[92:93], v[96:97], 0, v[72:73]
	v_cvt_pk_bf16_f32 v86, v86, v87
	v_cvt_pk_bf16_f32 v87, v88, v89
	v_lshl_add_u64 v[88:89], v[96:97], 0, v[74:75]
	v_cvt_pk_bf16_f32 v78, v78, v79
	v_cvt_pk_bf16_f32 v79, v82, v83
	v_lshl_add_u64 v[82:83], v[80:81], 0, v[74:75]
	v_lshl_add_u64 v[66:67], v[64:65], 0, v[0:1]
	v_cvt_pk_bf16_f32 v58, v58, v59
	v_cvt_pk_bf16_f32 v59, v60, v61
	v_lshl_add_u64 v[60:61], v[64:65], 0, v[72:73]
	v_cvt_pk_bf16_f32 v54, v54, v55
	v_cvt_pk_bf16_f32 v55, v56, v57
	v_lshl_add_u64 v[56:57], v[64:65], 0, v[74:75]
	v_lshl_add_u64 v[50:51], v[48:49], 0, v[0:1]
	v_cvt_pk_bf16_f32 v42, v42, v43
	v_cvt_pk_bf16_f32 v43, v44, v45
	v_lshl_add_u64 v[44:45], v[48:49], 0, v[72:73]
	v_cvt_pk_bf16_f32 v38, v38, v39
	v_cvt_pk_bf16_f32 v39, v40, v41
	v_lshl_add_u64 v[40:41], v[48:49], 0, v[74:75]
	v_lshl_add_u64 v[34:35], v[32:33], 0, v[0:1]
	v_cvt_pk_bf16_f32 v26, v26, v27
	v_cvt_pk_bf16_f32 v27, v28, v29
	v_lshl_add_u64 v[28:29], v[32:33], 0, v[72:73]
	v_cvt_pk_bf16_f32 v22, v22, v23
	v_cvt_pk_bf16_f32 v23, v24, v25
	v_lshl_add_u64 v[24:25], v[32:33], 0, v[74:75]
	v_lshl_add_u64 v[18:19], v[16:17], 0, v[0:1]
	v_cvt_pk_bf16_f32 v10, v10, v11
	v_cvt_pk_bf16_f32 v11, v12, v13
	v_lshl_add_u64 v[12:13], v[16:17], 0, v[72:73]
	v_cvt_pk_bf16_f32 v6, v6, v7
	v_cvt_pk_bf16_f32 v7, v8, v9
	v_lshl_add_u64 v[8:9], v[16:17], 0, v[74:75]
	v_cvt_pk_bf16_f32 v2, v2, v3
	v_cvt_pk_bf16_f32 v3, v4, v5
	v_lshl_add_u64 v[4:5], v[16:17], 0, v[76:77]
	global_store_dwordx2 v[114:115], v[110:111], off
	global_store_dwordx2 v[108:109], v[106:107], off
	global_store_dwordx2 v[104:105], v[102:103], off
	global_store_dwordx2 v[98:99], v[94:95], off
	global_store_dwordx2 v[92:93], v[90:91], off
	global_store_dwordx2 v[88:89], v[86:87], off
	global_store_dwordx2 v[82:83], v[78:79], off
	global_store_dwordx2 v[66:67], v[62:63], off
	global_store_dwordx2 v[60:61], v[58:59], off
	global_store_dwordx2 v[56:57], v[54:55], off
	global_store_dwordx2 v[50:51], v[46:47], off
	global_store_dwordx2 v[44:45], v[42:43], off
	global_store_dwordx2 v[40:41], v[38:39], off
	global_store_dwordx2 v[34:35], v[30:31], off
	global_store_dwordx2 v[28:29], v[26:27], off
	global_store_dwordx2 v[24:25], v[22:23], off
	global_store_dwordx2 v[18:19], v[14:15], off
	global_store_dwordx2 v[12:13], v[10:11], off
	global_store_dwordx2 v[8:9], v[6:7], off
	global_store_dwordx2 v[4:5], v[2:3], off

.LBB0_1298:
	s_andn2_b64 vcc, exec, s[0:1]
	s_cbranch_vccnz .LBB0_1169
	v_lshl_add_u32 v3, s22, 1, v149
	v_bfe_u32 v5, v3, 1, 2
	v_mov_b32_e32 v9, v201
	v_bfe_u32 v82, v148, 8, 1
	v_and_b32_e32 v0, 0x3ffffff8, v3
	v_lshlrev_b32_e32 v2, 1, v5
	v_or3_b32 v0, v2, v0, v82
	v_bfe_u32 v2, v9, 3, 3
	v_lshlrev_b32_e32 v6, 6, v2
	v_xor_b32_e32 v2, v2, v9
	v_and_b32_e32 v11, 63, v9
	v_bfe_u32 v15, v9, 6, 2
	v_lshlrev_b32_e32 v2, 3, v2
	v_lshlrev_b32_e32 v4, 12, v15
	v_and_b32_e32 v2, 56, v2
	v_or_b32_e32 v21, 64, v11
	v_or3_b32 v2, v6, v2, v4
	v_lshrrev_b32_e32 v6, 3, v21
	v_lshlrev_b32_e32 v7, 6, v6
	v_xor_b32_e32 v6, v6, v9
	v_lshlrev_b32_e32 v6, 3, v6
	v_and_b32_e32 v6, 56, v6
	s_movk_i32 s0, 0x3000
	v_and_b32_e32 v13, 15, v9
	v_or3_b32 v4, v6, v7, v4
	v_bfe_u32 v23, v9, 4, 2
	v_and_b32_e32 v7, 7, v9
	v_mad_i32_i24 v79, v149, s0, v150
	v_lshlrev_b32_e32 v6, 7, v13
	v_bitop3_b32 v16, v23, v9, 7 bitop3:0x78
	v_bitop3_b32 v7, v23, v7, 4 bitop3:0x36
	s_movk_i32 s0, 0x44
	v_lshl_or_b32 v83, v16, 4, v6
	v_lshl_or_b32 v84, v7, 4, v6
	v_mul_lo_u32 v42, v0, s0
	v_mov_b64_e32 v[6:7], s[94:95]
	v_mad_i64_i32 v[6:7], s[0:1], v42, s82, v[6:7]
	v_lshlrev_b32_e32 v0, 1, v2
	v_lshl_add_u32 v85, v15, 13, v79
	v_lshl_add_u64 v[16:17], v[6:7], 0, v[0:1]
	v_lshlrev_b32_e32 v0, 1, v4
	v_readfirstlane_b32 s0, v85
	v_lshl_add_u64 v[18:19], v[6:7], 0, v[0:1]
	v_add_u32_e32 v0, 0x400, v85
	s_mov_b32 m0, s0
	v_readfirstlane_b32 s0, v0
	v_add_u32_e32 v0, 0x800, v85
	global_load_lds_dwordx4 v[16:17], off
	s_mov_b32 m0, s0
	v_readfirstlane_b32 s0, v0
	v_add_u32_e32 v0, 0xc00, v85
	v_or_b32_e32 v8, 0x800, v2
	global_load_lds_dwordx4 v[18:19], off
	v_lshl_add_u64 v[18:19], v[16:17], 0, s[68:69]
	s_mov_b32 m0, s0
	v_readfirstlane_b32 s0, v0
	global_load_lds_dwordx4 v[18:19], off
	v_lshl_add_u64 v[16:17], v[16:17], 0, s[86:87]
	s_mov_b32 m0, s0
	v_lshlrev_b32_e32 v0, 1, v8
	global_load_lds_dwordx4 v[16:17], off
	v_lshl_add_u64 v[16:17], v[6:7], 0, v[0:1]
	v_add_u32_e32 v0, 0x1000, v85
	v_or_b32_e32 v10, 0xa00, v2
	v_readfirstlane_b32 s0, v0
	s_mov_b32 m0, s0
	v_lshlrev_b32_e32 v0, 1, v10
	global_load_lds_dwordx4 v[16:17], off
	v_lshl_add_u64 v[16:17], v[6:7], 0, v[0:1]
	v_add_u32_e32 v0, 0x1400, v85
	v_or_b32_e32 v12, 0xc00, v2
	v_readfirstlane_b32 s0, v0
	s_mov_b32 m0, s0
	v_lshlrev_b32_e32 v0, 1, v12
	v_or_b32_e32 v14, 0xe00, v2
	global_load_lds_dwordx4 v[16:17], off
	v_lshl_add_u64 v[16:17], v[6:7], 0, v[0:1]
	v_add_u32_e32 v0, 0x1800, v85
	v_ashrrev_i32_e32 v43, 31, v42
	v_readfirstlane_b32 s0, v0
	v_lshlrev_b32_e32 v0, 1, v14
	v_lshl_add_u64 v[6:7], v[6:7], 0, v[0:1]
	v_add_u32_e32 v0, 0x1c00, v85
	s_mov_b32 m0, s0
	v_readfirstlane_b32 s0, v0
	global_load_lds_dwordx4 v[16:17], off
	s_mov_b32 m0, s0
	v_lshlrev_b32_e32 v16, 2, v13
	global_load_lds_dwordx4 v[6:7], off
	v_mov_b64_e32 v[6:7], s[10:11]
	v_lshlrev_b32_e32 v0, 8, v15
	v_lshlrev_b32_e32 v13, 6, v23
	v_mad_i64_i32 v[6:7], s[0:1], v42, s82, v[6:7]
	v_or3_b32 v20, v0, v13, v16
	v_lshl_add_u64 v[6:7], v[6:7], 0, s[88:89]
	v_lshlrev_b32_e32 v0, 1, v20
	v_or_b32_e32 v22, 0x400, v20
	v_lshl_add_u64 v[18:19], v[6:7], 0, v[0:1]
	v_lshlrev_b32_e32 v0, 1, v22
	v_or_b32_e32 v30, 0x800, v20
	v_lshl_add_u64 v[24:25], v[6:7], 0, v[0:1]
	v_lshlrev_b32_e32 v0, 1, v30
	v_or_b32_e32 v32, 0xc00, v20
	v_lshl_add_u64 v[26:27], v[6:7], 0, v[0:1]
	v_lshlrev_b32_e32 v0, 1, v32
	v_lshl_add_u64 v[6:7], v[6:7], 0, v[0:1]
	s_waitcnt vmcnt(0)
	global_load_dwordx2 v[18:19], v[18:19], off
	s_nop 0
	global_load_dwordx2 v[28:29], v[24:25], off
	s_nop 0
	global_load_dwordx2 v[26:27], v[26:27], off
	s_nop 0
	global_load_dwordx2 v[80:81], v[6:7], off
	v_lshlrev_b64 v[6:7], 8, v[42:43]
	v_lshl_add_u64 v[6:7], s[16:17], 0, v[6:7]
	v_lshlrev_b32_e32 v0, 2, v11
	v_lshl_add_u64 v[6:7], v[6:7], 0, v[0:1]
	global_load_dword v78, v[6:7], off
	v_mul_u32_u24_e32 v6, 0x50, v15
	v_lshrrev_b32_e32 v3, 3, v3
	v_add_lshl_u32 v24, v6, v11, 5
	v_add_lshl_u32 v34, v6, v21, 5
	v_lshlrev_b32_e32 v6, 2, v23
	s_movk_i32 s0, 0x1100
	v_mul_lo_u32 v43, v3, s0
	v_or_b32_e32 v3, 48, v6
	v_xor_b32_e32 v7, 15, v6
	v_cmp_eq_u32_e64 s[0:1], 0, v82
	v_lshl_add_u64 v[44:45], s[16:17], 0, v[0:1]
	v_lshlrev_b32_e32 v0, 8, v5
	v_cndmask_b32_e64 v86, v7, v3, s[0:1]
	v_xor_b32_e32 v3, 63, v6
	v_cndmask_b32_e64 v87, v3, v6, s[0:1]
	v_or_b32_e32 v3, 1, v6
	v_xor_b32_e32 v7, 62, v6
	v_cndmask_b32_e64 v88, v7, v3, s[0:1]
	v_or_b32_e32 v3, 2, v6
	v_xor_b32_e32 v7, 61, v6
	v_cndmask_b32_e64 v89, v7, v3, s[0:1]
	v_or_b32_e32 v3, 3, v6
	v_xor_b32_e32 v7, 60, v6
	v_cndmask_b32_e64 v90, v7, v3, s[0:1]
	v_or_b32_e32 v3, 16, v6
	v_xor_b32_e32 v7, 47, v6
	v_cndmask_b32_e64 v91, v7, v3, s[0:1]
	v_or_b32_e32 v3, 17, v6
	v_xor_b32_e32 v7, 46, v6
	v_cndmask_b32_e64 v92, v7, v3, s[0:1]
	v_or_b32_e32 v3, 18, v6
	v_xor_b32_e32 v7, 45, v6
	v_cndmask_b32_e64 v93, v7, v3, s[0:1]
	v_or_b32_e32 v3, 19, v6
	v_xor_b32_e32 v7, 44, v6
	v_cndmask_b32_e64 v94, v7, v3, s[0:1]
	v_or_b32_e32 v3, 32, v6
	v_xor_b32_e32 v7, 31, v6
	v_cndmask_b32_e64 v95, v7, v3, s[0:1]
	v_or_b32_e32 v3, 33, v6
	v_xor_b32_e32 v7, 30, v6
	v_cndmask_b32_e64 v96, v7, v3, s[0:1]
	v_or_b32_e32 v3, 34, v6
	v_xor_b32_e32 v7, 29, v6
	v_cndmask_b32_e64 v97, v7, v3, s[0:1]
	v_or_b32_e32 v3, 35, v6
	v_xor_b32_e32 v7, 28, v6
	v_cndmask_b32_e64 v98, v7, v3, s[0:1]
	v_or_b32_e32 v3, 49, v6
	v_xor_b32_e32 v7, 14, v6
	v_cndmask_b32_e64 v99, v7, v3, s[0:1]
	v_or_b32_e32 v3, 50, v6
	v_xor_b32_e32 v7, 13, v6
	v_cndmask_b32_e64 v100, v7, v3, s[0:1]
	v_or_b32_e32 v3, 51, v6
	v_xor_b32_e32 v6, 12, v6
	v_cndmask_b32_e64 v101, v6, v3, s[0:1]
	v_lshl_add_u64 v[6:7], s[18:19], 0, v[0:1]
	v_and_b32_e32 v0, 0xc0, v9
	s_waitcnt vmcnt(0)
	v_lshl_add_u64 v[6:7], v[6:7], 0, v[0:1]
	v_mov_b32_e32 v17, v1
	v_lshl_add_u64 v[46:47], v[6:7], 0, v[16:17]
	v_mov_b32_e32 v6, 0
	v_cmp_gt_u32_e32 vcc, 16, v11
	s_mov_b32 s4, 0
	s_movk_i32 s5, 0x47
	v_mov_b32_e32 v102, 0
	v_lshlrev_b32_e32 v48, 1, v2
	v_lshlrev_b32_e32 v50, 1, v4
	v_lshlrev_b32_e32 v52, 1, v8
	v_lshlrev_b32_e32 v54, 1, v10
	v_lshlrev_b32_e32 v56, 1, v12
	v_lshlrev_b32_e32 v58, 1, v14
	v_lshlrev_b32_e32 v60, 1, v20
	v_lshlrev_b32_e32 v62, 1, v22
	v_lshlrev_b32_e32 v64, 1, v30
	v_lshlrev_b32_e32 v66, 1, v32
	v_lshlrev_b32_e32 v0, 2, v24
	v_lshlrev_b32_e32 v68, 2, v34
	s_mov_b32 s6, 0
	v_mov_b32_e32 v7, v6
	v_mov_b32_e32 v8, v6
	v_mov_b32_e32 v9, v6
	v_mov_b32_e32 v10, v6
	v_mov_b32_e32 v11, v6
	v_mov_b32_e32 v12, v6
	v_mov_b32_e32 v13, v6
	v_mov_b32_e32 v2, v6
	v_mov_b32_e32 v3, v6
	v_mov_b32_e32 v4, v6
	v_mov_b32_e32 v5, v6
	v_mov_b32_e32 v14, v6
	v_mov_b32_e32 v15, v6
	v_mov_b32_e32 v16, v6
	v_mov_b32_e32 v17, v6
	s_waitcnt vmcnt(0) lgkmcnt(0)
	v_mov_b64_e32 v[70:71], v[80:81]
	v_mov_b64_e32 v[72:73], v[26:27]
	v_mov_b64_e32 v[74:75], v[28:29]
	v_mov_b64_e32 v[76:77], v[18:19]
.LBB0_1300:
	s_waitcnt vmcnt(8)
	s_cmpk_eq_i32 s6, 0x43
	v_mov_b32_e32 v49, v78
	s_barrier
	s_cbranch_scc1 .LBB0_1302
	v_add3_u32 v20, v42, s6, 1
	v_mov_b64_e32 v[22:23], s[94:95]
	v_mad_i64_i32 v[22:23], s[2:3], v20, s82, v[22:23]
	s_add_i32 s2, s4, 0x8000
	s_and_b32 s2, s2, 0x8000
	v_add_u32_e32 v32, s2, v85
	v_mov_b32_e32 v49, v1
	v_readfirstlane_b32 s2, v32
	v_add_u32_e32 v33, 0x400, v32
	v_lshl_add_u64 v[24:25], v[22:23], 0, v[48:49]
	s_mov_b32 m0, s2
	v_mov_b32_e32 v51, v1
	v_readfirstlane_b32 s2, v33
	v_add_u32_e32 v33, 0x800, v32
	global_load_lds_dwordx4 v[24:25], off
	v_lshl_add_u64 v[30:31], v[22:23], 0, v[50:51]
	s_mov_b32 m0, s2
	v_readfirstlane_b32 s2, v33
	global_load_lds_dwordx4 v[30:31], off
	v_lshl_add_u64 v[30:31], v[24:25], 0, s[68:69]
	s_mov_b32 m0, s2
	v_lshl_add_u64 v[24:25], v[24:25], 0, s[86:87]
	global_load_lds_dwordx4 v[30:31], off
	v_add_u32_e32 v30, 0xc00, v32
	v_mov_b32_e32 v53, v1
	v_readfirstlane_b32 s2, v30
	v_add_u32_e32 v30, 0x1000, v32
	s_mov_b32 m0, s2
	v_readfirstlane_b32 s2, v30
	v_add_u32_e32 v30, 0x1400, v32
	global_load_lds_dwordx4 v[24:25], off
	v_lshl_add_u64 v[24:25], v[22:23], 0, v[52:53]
	s_mov_b32 m0, s2
	v_mov_b32_e32 v55, v1
	v_readfirstlane_b32 s2, v30
	v_add_u32_e32 v30, 0x1800, v32
	global_load_lds_dwordx4 v[24:25], off
	v_lshl_add_u64 v[24:25], v[22:23], 0, v[54:55]
	s_mov_b32 m0, s2
	v_mov_b32_e32 v57, v1
	v_readfirstlane_b32 s2, v30
	global_load_lds_dwordx4 v[24:25], off
	v_lshl_add_u64 v[24:25], v[22:23], 0, v[56:57]
	s_mov_b32 m0, s2
	v_mov_b32_e32 v59, v1
	global_load_lds_dwordx4 v[24:25], off
	v_add_u32_e32 v24, 0x1c00, v32
	v_lshl_add_u64 v[22:23], v[22:23], 0, v[58:59]
	v_readfirstlane_b32 s2, v24
	s_mov_b32 m0, s2
	v_mov_b32_e32 v61, v1
	global_load_lds_dwordx4 v[22:23], off
	v_mov_b64_e32 v[22:23], s[10:11]
	v_mad_i64_i32 v[22:23], s[2:3], v20, s82, v[22:23]
	v_lshl_add_u64 v[22:23], v[22:23], 0, s[88:89]
	v_ashrrev_i32_e32 v21, 31, v20
	v_lshl_add_u64 v[24:25], v[22:23], 0, v[60:61]
	v_mov_b32_e32 v63, v1
	v_mov_b32_e32 v65, v1
	v_mov_b32_e32 v67, v1
	v_lshl_add_u64 v[30:31], v[22:23], 0, v[62:63]
	v_lshl_add_u64 v[32:33], v[22:23], 0, v[64:65]
	v_lshl_add_u64 v[22:23], v[22:23], 0, v[66:67]
	s_waitcnt vmcnt(0)
	global_load_dwordx2 v[76:77], v[24:25], off
	global_load_dwordx2 v[74:75], v[30:31], off
	global_load_dwordx2 v[72:73], v[32:33], off
	global_load_dwordx2 v[70:71], v[22:23], off
	v_lshlrev_b64 v[20:21], 8, v[20:21]
	v_lshl_add_u64 v[20:21], v[44:45], 0, v[20:21]
	global_load_dword v49, v[20:21], off
.LBB0_1302:
	v_mov_b32_e32 v53, 0
	s_cmpk_gt_u32 s6, 0x41
	v_mov_b32_e32 v51, 0
	s_cbranch_scc1 .LBB0_1306
	v_add3_u32 v22, v42, s6, 2
	v_mov_b64_e32 v[20:21], s[94:95]
	v_mad_i64_i32 v[20:21], s[2:3], v22, s82, v[20:21]
	v_lshl_add_u64 v[22:23], v[20:21], 0, v[0:1]
	global_load_dword v53, v[22:23], off
	v_mov_b32_e32 v51, 0
	s_and_saveexec_b64 s[2:3], vcc
	s_cbranch_execz .LBB0_1305
	v_mov_b32_e32 v69, v1
	v_lshl_add_u64 v[20:21], v[20:21], 0, v[68:69]
	global_load_dword v51, v[20:21], off

.LBB0_1306:
	s_add_i32 s7, s6, 1
	s_and_b32 s2, s4, 0x8000
	v_add_u32_e32 v55, s2, v79
	v_cvt_pk_bf16_f32 v30, v6, v7
	v_cvt_pk_bf16_f32 v31, v8, v9
	v_cvt_pk_bf16_f32 v32, v10, v11
	v_cvt_pk_bf16_f32 v33, v12, v13
	v_cvt_pk_bf16_f32 v22, v2, v3
	v_cvt_pk_bf16_f32 v23, v4, v5
	v_cvt_pk_bf16_f32 v24, v14, v15
	v_cvt_pk_bf16_f32 v25, v16, v17
	s_setprio 1
	v_add_u32_e32 v57, v55, v83
	v_lshlrev_b32_e32 v34, 16, v18
	v_and_b32_e32 v35, 0xffff0000, v18
	v_lshlrev_b32_e32 v36, 16, v19
	v_and_b32_e32 v37, 0xffff0000, v19
	ds_read_b128 v[18:21], v57
	ds_read_b128 v[38:41], v57 offset:8192
	v_add_u32_e32 v55, v55, v84
	s_waitcnt lgkmcnt(0)
	v_mfma_f32_16x16x32_bf16 v[18:21], v[18:21], v[30:33], v[34:37]
	v_mul_f32_e64 v6, v78, v6
	v_mul_f32_e64 v7, v78, v7
	v_pk_mul_f32 v[8:9], v[78:79], v[8:9] op_sel_hi:[0,1]
	v_pk_mul_f32 v[10:11], v[78:79], v[10:11] op_sel_hi:[0,1]
	v_mfma_f32_16x16x32_bf16 v[34:37], v[38:41], v[30:33], 0
	ds_read_b128 v[38:41], v55
	ds_read_b128 v[104:107], v55 offset:8192
	v_pk_mul_f32 v[12:13], v[78:79], v[12:13] op_sel_hi:[0,1]
	v_pk_mul_f32 v[2:3], v[78:79], v[2:3] op_sel_hi:[0,1]
	s_waitcnt lgkmcnt(0)
	v_mfma_f32_16x16x32_bf16 v[38:41], v[38:41], v[22:25], v[18:21]
	v_mul_f32_e64 v4, v78, v4
	v_mul_f32_e64 v5, v78, v5
	v_pk_mul_f32 v[14:15], v[78:79], v[14:15] op_sel_hi:[0,1]
	v_pk_mul_f32 v[16:17], v[78:79], v[16:17] op_sel_hi:[0,1]
	v_mfma_f32_16x16x32_bf16 v[18:21], v[104:107], v[22:25], v[34:37]
	ds_read_b128 v[104:107], v57 offset:2048
	ds_read_b128 v[108:111], v57 offset:10240
	s_nop 0
	v_cvt_pk_bf16_f32 v38, v38, v39
	v_lshlrev_b32_e32 v34, 16, v28
	v_and_b32_e32 v35, 0xffff0000, v28
	v_lshlrev_b32_e32 v36, 16, v29
	v_and_b32_e32 v37, 0xffff0000, v29
	v_cvt_pk_bf16_f32 v39, v40, v41
	s_waitcnt lgkmcnt(0)
	v_mfma_f32_16x16x32_bf16 v[34:37], v[104:107], v[30:33], v[34:37]
	v_mfma_f32_16x16x32_bf16 v[104:107], v[108:111], v[30:33], 0
	ds_read_b128 v[108:111], v55 offset:2048
	ds_read_b128 v[112:115], v55 offset:10240
	s_waitcnt lgkmcnt(0)
	v_mfma_f32_16x16x32_bf16 v[108:111], v[108:111], v[22:25], v[34:37]
	v_mfma_f32_16x16x32_bf16 v[34:37], v[112:115], v[22:25], v[104:107]
	s_nop 6
	v_cvt_pk_bf16_f32 v40, v108, v109
	v_cvt_pk_bf16_f32 v41, v110, v111
	v_lshlrev_b32_e32 v104, 16, v26
	v_and_b32_e32 v105, 0xffff0000, v26
	v_lshlrev_b32_e32 v106, 16, v27
	v_and_b32_e32 v107, 0xffff0000, v27
	ds_read_b128 v[26:29], v57 offset:4096
	ds_read_b128 v[112:115], v57 offset:12288
	s_waitcnt lgkmcnt(0)
	v_mfma_f32_16x16x32_bf16 v[26:29], v[26:29], v[30:33], v[104:107]
	v_mfma_f32_16x16x32_bf16 v[104:107], v[112:115], v[30:33], 0
	ds_read_b128 v[112:115], v55 offset:4096
	ds_read_b128 v[116:119], v55 offset:12288
	s_waitcnt lgkmcnt(0)
	v_mfma_f32_16x16x32_bf16 v[112:115], v[112:115], v[22:25], v[26:29]
	v_mfma_f32_16x16x32_bf16 v[26:29], v[116:119], v[22:25], v[104:107]
	ds_read_b128 v[116:119], v57 offset:6144
	ds_read_b128 v[120:123], v57 offset:14336
	s_nop 0
	v_lshlrev_b32_e32 v104, 16, v80
	v_and_b32_e32 v105, 0xffff0000, v80
	v_lshlrev_b32_e32 v106, 16, v81
	v_and_b32_e32 v107, 0xffff0000, v81
	s_waitcnt lgkmcnt(0)
	s_nop 0
	v_mfma_f32_16x16x32_bf16 v[104:107], v[116:119], v[30:33], v[104:107]
	v_mfma_f32_16x16x32_bf16 v[30:33], v[120:123], v[30:33], 0
	ds_read_b128 v[116:119], v55 offset:6144
	ds_read_b128 v[120:123], v55 offset:14336
	s_waitcnt lgkmcnt(0)
	v_mfma_f32_16x16x32_bf16 v[104:107], v[116:119], v[22:25], v[104:107]
	v_mfma_f32_16x16x32_bf16 v[30:33], v[120:123], v[22:25], v[30:33]
	s_nop 6
	v_cvt_pk_bf16_f32 v24, v104, v105
	v_cvt_pk_bf16_f32 v25, v106, v107
	ds_read_b128 v[104:107], v57 offset:16384
	ds_read_b128 v[108:111], v57 offset:24576
	s_waitcnt lgkmcnt(0)
	v_mfma_f32_16x16x32_bf16 v[18:21], v[104:107], v[38:41], v[18:21]
	v_cvt_pk_bf16_f32 v22, v112, v113
	v_cvt_pk_bf16_f32 v23, v114, v115
	v_mfma_f32_16x16x32_bf16 v[6:9], v[108:111], v[38:41], v[6:9]
	ds_read_b128 v[104:107], v55 offset:16384
	ds_read_b128 v[108:111], v55 offset:24576
	s_waitcnt lgkmcnt(0)
	v_mfma_f32_16x16x32_bf16 v[18:21], v[104:107], v[22:25], v[18:21]
	v_mfma_f32_16x16x32_bf16 v[6:9], v[108:111], v[22:25], v[6:9]
	ds_read_b128 v[104:107], v57 offset:18432
	ds_read_b128 v[108:111], v57 offset:26624
	s_waitcnt lgkmcnt(0)
	v_mfma_f32_16x16x32_bf16 v[34:37], v[104:107], v[38:41], v[34:37]
	v_mfma_f32_16x16x32_bf16 v[10:13], v[108:111], v[38:41], v[10:13]
	ds_read_b128 v[104:107], v55 offset:18432
	ds_read_b128 v[108:111], v55 offset:26624
	s_waitcnt lgkmcnt(0)
	v_mfma_f32_16x16x32_bf16 v[34:37], v[104:107], v[22:25], v[34:37]
	v_mfma_f32_16x16x32_bf16 v[10:13], v[108:111], v[22:25], v[10:13]
	ds_read_b128 v[104:107], v57 offset:20480
	ds_read_b128 v[108:111], v57 offset:28672
	s_waitcnt lgkmcnt(0)
	v_mfma_f32_16x16x32_bf16 v[26:29], v[104:107], v[38:41], v[26:29]
	v_mfma_f32_16x16x32_bf16 v[2:5], v[108:111], v[38:41], v[2:5]
	ds_read_b128 v[104:107], v55 offset:20480
	ds_read_b128 v[108:111], v55 offset:28672
	s_waitcnt lgkmcnt(0)
	v_mfma_f32_16x16x32_bf16 v[26:29], v[104:107], v[22:25], v[26:29]
	v_mfma_f32_16x16x32_bf16 v[2:5], v[108:111], v[22:25], v[2:5]
	ds_read_b128 v[104:107], v57 offset:22528
	ds_read_b128 v[108:111], v57 offset:30720
	s_waitcnt lgkmcnt(0)
	v_mfma_f32_16x16x32_bf16 v[30:33], v[104:107], v[38:41], v[30:33]
	v_mfma_f32_16x16x32_bf16 v[14:17], v[108:111], v[38:41], v[14:17]
	ds_read_b128 v[38:41], v55 offset:22528
	ds_read_b128 v[104:107], v55 offset:30720
	s_waitcnt lgkmcnt(0)
	v_mfma_f32_16x16x32_bf16 v[14:17], v[104:107], v[22:25], v[14:17]
	v_mfma_f32_16x16x32_bf16 v[30:33], v[38:41], v[22:25], v[30:33]
	s_setprio 0
	s_cmp_lt_u32 s6, 4
	v_mov_b32_e32 v23, s6
	s_cselect_b64 s[2:3], -1, 0
	s_add_i32 s6, s5, 0xffffffbc
	v_mov_b32_e32 v24, s5
	v_mov_b32_e32 v25, s6
	v_cndmask_b32_e64 v24, v24, v23, s[0:1]
	v_cndmask_b32_e64 v23, v25, v23, s[0:1]
	v_cndmask_b32_e64 v23, v24, v23, s[2:3]
	v_lshl_add_u32 v39, v23, 6, v43
	v_mov_b32_e32 v22, v82
	v_or_b32_e32 v24, v39, v87
	v_ashrrev_i32_e32 v25, 31, v24
	v_mad_i64_i32 v[22:23], s[2:3], v22, s90, v[46:47]
	v_lshlrev_b64 v[24:25], 10, v[24:25]
	v_lshl_add_u64 v[24:25], v[22:23], 0, v[24:25]
	global_store_dword v[24:25], v18, off
	v_or_b32_e32 v24, v39, v88
	v_ashrrev_i32_e32 v25, 31, v24
	v_lshlrev_b64 v[24:25], 10, v[24:25]
	v_lshl_add_u64 v[24:25], v[22:23], 0, v[24:25]
	v_or_b32_e32 v18, v39, v89
	global_store_dword v[24:25], v19, off
	v_ashrrev_i32_e32 v19, 31, v18
	v_lshlrev_b64 v[18:19], 10, v[18:19]
	v_lshl_add_u64 v[18:19], v[22:23], 0, v[18:19]
	global_store_dword v[18:19], v20, off
	v_or_b32_e32 v18, v39, v90
	v_ashrrev_i32_e32 v19, 31, v18
	v_lshlrev_b64 v[18:19], 10, v[18:19]
	v_lshl_add_u64 v[18:19], v[22:23], 0, v[18:19]
	global_store_dword v[18:19], v21, off
	v_or_b32_e32 v18, v39, v91
	v_ashrrev_i32_e32 v19, 31, v18
	v_lshlrev_b64 v[18:19], 10, v[18:19]
	v_lshl_add_u64 v[18:19], v[22:23], 0, v[18:19]
	global_store_dword v[18:19], v34, off
	v_or_b32_e32 v18, v39, v92
	v_ashrrev_i32_e32 v19, 31, v18
	v_lshlrev_b64 v[18:19], 10, v[18:19]
	v_lshl_add_u64 v[18:19], v[22:23], 0, v[18:19]
	global_store_dword v[18:19], v35, off
	v_or_b32_e32 v18, v39, v93
	v_ashrrev_i32_e32 v19, 31, v18
	v_lshlrev_b64 v[18:19], 10, v[18:19]
	v_lshl_add_u64 v[18:19], v[22:23], 0, v[18:19]
	global_store_dword v[18:19], v36, off
	v_or_b32_e32 v18, v39, v94
	v_ashrrev_i32_e32 v19, 31, v18
	v_lshlrev_b64 v[18:19], 10, v[18:19]
	v_lshl_add_u64 v[18:19], v[22:23], 0, v[18:19]
	global_store_dword v[18:19], v37, off
	v_or_b32_e32 v18, v39, v95
	v_ashrrev_i32_e32 v19, 31, v18
	v_lshlrev_b64 v[18:19], 10, v[18:19]
	v_lshl_add_u64 v[18:19], v[22:23], 0, v[18:19]
	global_store_dword v[18:19], v26, off
	v_or_b32_e32 v18, v39, v96
	v_ashrrev_i32_e32 v19, 31, v18
	v_lshlrev_b64 v[18:19], 10, v[18:19]
	v_lshl_add_u64 v[18:19], v[22:23], 0, v[18:19]
	global_store_dword v[18:19], v27, off
	v_or_b32_e32 v18, v39, v97
	v_ashrrev_i32_e32 v19, 31, v18
	v_lshlrev_b64 v[18:19], 10, v[18:19]
	v_lshl_add_u64 v[18:19], v[22:23], 0, v[18:19]
	global_store_dword v[18:19], v28, off
	v_or_b32_e32 v18, v39, v98
	v_ashrrev_i32_e32 v19, 31, v18
	v_lshlrev_b64 v[18:19], 10, v[18:19]
	v_lshl_add_u64 v[18:19], v[22:23], 0, v[18:19]
	global_store_dword v[18:19], v29, off
	v_or_b32_e32 v18, v39, v86
	v_ashrrev_i32_e32 v19, 31, v18
	v_lshlrev_b64 v[18:19], 10, v[18:19]
	v_lshl_add_u64 v[18:19], v[22:23], 0, v[18:19]
	global_store_dword v[18:19], v30, off
	v_or_b32_e32 v18, v39, v99
	v_ashrrev_i32_e32 v19, 31, v18
	v_lshlrev_b64 v[18:19], 10, v[18:19]
	v_lshl_add_u64 v[18:19], v[22:23], 0, v[18:19]
	global_store_dword v[18:19], v31, off
	v_or_b32_e32 v18, v39, v100
	v_ashrrev_i32_e32 v19, 31, v18
	v_lshlrev_b64 v[18:19], 10, v[18:19]
	v_lshl_add_u64 v[18:19], v[22:23], 0, v[18:19]
	global_store_dword v[18:19], v32, off
	v_or_b32_e32 v18, v39, v101
	v_ashrrev_i32_e32 v19, 31, v18
	s_waitcnt vmcnt(0)
	v_xor_b32_e32 v38, v53, v102
	v_lshlrev_b64 v[18:19], 10, v[18:19]
	s_add_i32 s5, s5, -1
	s_add_i32 s4, s4, 0x8000
	v_lshl_add_u64 v[18:19], v[22:23], 0, v[18:19]
	s_cmpk_eq_i32 s7, 0x44
	v_xor_b32_e32 v102, v38, v51
	global_store_dword v[18:19], v33, off
	s_cbranch_scc1 .LBB0_1308
	v_mov_b64_e32 v[18:19], v[76:77]
	v_mov_b64_e32 v[28:29], v[74:75]
	v_mov_b64_e32 v[26:27], v[72:73]
	v_mov_b64_e32 v[80:81], v[70:71]
	v_mov_b32_e32 v78, v49
	s_mov_b32 s6, s7
	s_branch .LBB0_1300
.LBB0_1308:
	s_mov_b32 s0, 0x9e3779b9
	v_cmp_eq_u32_e32 vcc, s0, v102
	s_waitcnt lgkmcnt(0)
	s_barrier
	s_and_saveexec_b64 s[0:1], vcc
	s_xor_b64 s[0:1], exec, s[0:1]
	s_cbranch_execz .LBB0_1168
	v_mov_b64_e32 v[2:3], s[16:17]
	global_load_dword v0, v[2:3], off
	s_mov_b32 s2, 0x42f6e979
	s_waitcnt vmcnt(0) lgkmcnt(0)
	v_cmp_eq_f32_e32 vcc, s2, v0
	s_and_saveexec_b64 s[2:3], vcc
	s_xor_b64 s[2:3], exec, s[2:3]
	s_cbranch_execz .LBB0_1167
	v_mov_b64_e32 v[2:3], s[18:19]
	global_store_dword v[2:3], v1, off
	s_branch .LBB0_1167

.LBB0_1327:
	s_lshl_b32 s0, s37, 8
	s_add_u32 s23, s38, s0
	s_addc_u32 s22, s39, 0
	v_mov_b32_e32 v3, s23
	v_add_co_u32_e32 v4, vcc, 0x1000, v3
	v_mov_b32_e32 v3, s22
	s_nop 0
	v_addc_co_u32_e32 v5, vcc, 0, v3, vcc
	global_atomic_add v4, v[4:5], v203, off offset:1024 sc0
	v_cvt_f32_u32_e32 v3, v2
	v_sub_u32_e32 v5, 0, v2
	v_rcp_iflag_f32_e32 v3, v3
	s_nop 0
	v_mul_f32_e32 v3, 0x4f7ffffe, v3
	v_cvt_u32_f32_e32 v3, v3
	v_mul_lo_u32 v5, v5, v3
	v_mul_hi_u32 v5, v3, v5
	v_add_u32_e32 v3, v3, v5
	s_waitcnt vmcnt(0) lgkmcnt(0)
	v_mul_hi_u32 v3, v4, v3
	v_mul_lo_u32 v5, v3, v2
	v_sub_u32_e32 v5, v4, v5
	v_cmp_ge_u32_e32 vcc, v5, v2
	v_add_u32_e32 v6, 1, v3
	s_nop 0
	v_cndmask_b32_e32 v3, v3, v6, vcc
	v_sub_u32_e32 v6, v5, v2
	v_cndmask_b32_e32 v5, v5, v6, vcc
	v_cmp_ge_u32_e32 vcc, v5, v2
	v_add_u32_e32 v5, 1, v3
	v_add_u32_e32 v6, 1, v4
	v_cndmask_b32_e32 v3, v3, v5, vcc
	v_mad_u64_u32 v[4:5], s[0:1], v2, v3, v[2:3]
	v_cmp_ne_u32_e32 vcc, v6, v4
	s_and_saveexec_b64 s[0:1], vcc
	s_xor_b64 s[0:1], exec, s[0:1]
	s_cbranch_execz .LBB0_1340
	v_mov_b32_e32 v0, s23
	v_add_co_u32_e32 v4, vcc, 0x2000, v0
	v_mov_b32_e32 v0, s22
	s_nop 0
	v_addc_co_u32_e32 v5, vcc, 0, v0, vcc
	global_load_dword v0, v[4:5], off offset:1024 sc1
	s_add_u32 s4, s23, 0x2400
	s_addc_u32 s5, s22, 0
	s_waitcnt vmcnt(0) lgkmcnt(0)
	v_cmp_eq_u32_e32 vcc, v0, v3
	s_and_saveexec_b64 s[2:3], vcc
	s_cbranch_execz .LBB0_1339
	s_mov_b32 s24, 1
	s_mov_b64 s[6:7], 0
	s_branch .LBB0_1331

.LBB0_1340:
	s_andn2_saveexec_b64 s[0:1], s[0:1]
	s_cbranch_execz .LBB0_1356
	v_mov_b32_e32 v2, s38
	v_add_co_u32_e32 v2, vcc, 0x3000, v2
	v_mov_b32_e32 v3, s39
	buffer_wbl2 sc1
	s_waitcnt vmcnt(0)
	v_addc_co_u32_e32 v3, vcc, 0, v3, vcc
	global_atomic_add v2, v[2:3], v203, off offset:1024 sc0
	v_cvt_f32_u32_e32 v3, v0
	v_sub_u32_e32 v4, 0, v0
	s_mov_b64 s[4:5], -1
	v_rcp_iflag_f32_e32 v3, v3
	s_nop 0
	v_mul_f32_e32 v3, 0x4f7ffffe, v3
	v_cvt_u32_f32_e32 v3, v3
	v_mul_lo_u32 v4, v4, v3
	v_mul_hi_u32 v4, v3, v4
	v_add_u32_e32 v3, v3, v4
	s_waitcnt vmcnt(0) lgkmcnt(0)
	v_mul_hi_u32 v3, v2, v3
	v_mul_lo_u32 v4, v3, v0
	v_sub_u32_e32 v4, v2, v4
	v_cmp_ge_u32_e32 vcc, v4, v0
	v_add_u32_e32 v5, 1, v3
	s_nop 0
	v_cndmask_b32_e32 v3, v3, v5, vcc
	v_sub_u32_e32 v5, v4, v0
	v_cndmask_b32_e32 v4, v4, v5, vcc
	v_cmp_ge_u32_e32 vcc, v4, v0
	v_add_u32_e32 v4, 1, v3
	v_add_u32_e32 v5, 1, v2
	v_cndmask_b32_e32 v4, v3, v4, vcc
	v_mad_u64_u32 v[2:3], s[0:1], v0, v4, v[0:1]
	s_add_u32 s0, s38, 0x3500
	s_addc_u32 s1, s39, 0
	v_cmp_ne_u32_e32 vcc, v5, v2
	v_mov_b64_e32 v[2:3], s[0:1]
	s_and_saveexec_b64 s[2:3], vcc
	s_cbranch_execz .LBB0_1353
	v_mov_b64_e32 v[2:3], s[0:1]
	global_load_dword v0, v[2:3], off sc1
	s_mov_b64 s[8:9], 0
	s_waitcnt vmcnt(0) lgkmcnt(0)
	v_cmp_eq_u32_e32 vcc, v0, v4
	s_and_saveexec_b64 s[6:7], vcc
	s_cbranch_execz .LBB0_1352
	s_add_u32 s4, s38, 0x200
	s_addc_u32 s5, s39, 0
	s_mov_b32 s24, 1
	s_branch .LBB0_1345

.LBB0_1359:
	v_mov_b32_e32 v5, v201
	v_and_b32_e32 v20, 64, v208
	v_bfe_u32 v0, v5, 6, 2
	v_add_u32_e32 v2, v4, v0
	v_ashrrev_i32_e32 v3, 31, v2
	v_and_b32_e32 v24, 63, v5
	v_lshlrev_b64 v[6:7], 10, v[2:3]
	v_lshl_add_u64 v[6:7], s[0:1], 0, v[6:7]
	v_lshlrev_b32_e32 v0, 4, v24
	v_lshl_add_u64 v[10:11], v[6:7], 0, v[0:1]
	v_lshlrev_b32_e32 v0, 4, v5
	v_and_b32_e32 v0, 0xf0, v0
	v_lshlrev_b64 v[6:7], 9, v[2:3]
	v_lshl_add_u64 v[14:15], s[2:3], 0, v[0:1]
	v_lshl_add_u64 v[6:7], s[4:5], 0, v[6:7]
	v_lshlrev_b32_e32 v0, 3, v24
	v_lshl_add_u64 v[6:7], v[6:7], 0, v[0:1]
	global_load_dwordx2 v[18:19], v[6:7], off
	s_nop 0
	global_load_dwordx4 v[6:9], v[10:11], off
	v_add_co_u32_e32 v10, vcc, s90, v10
	v_xor_b32_e32 v5, 1, v208
	s_nop 0
	v_addc_co_u32_e32 v11, vcc, 0, v11, vcc
	global_load_dwordx4 v[10:13], v[10:11], off
	s_nop 0
	global_load_dwordx4 v[14:17], v[14:15], off
	v_add_u32_e32 v20, 64, v20
	v_cmp_lt_i32_e32 vcc, v5, v20
	v_xor_b32_e32 v21, 2, v208
	v_xor_b32_e32 v22, 4, v208
	v_cndmask_b32_e32 v5, v208, v5, vcc
	v_lshlrev_b32_e32 v5, 2, v5
	v_cmp_lt_i32_e32 vcc, v21, v20
	v_xor_b32_e32 v23, 8, v208
	s_waitcnt vmcnt(0) lgkmcnt(0)
	v_pk_add_f32 v[6:7], v[6:7], v[10:11]
	v_pk_add_f32 v[8:9], v[8:9], v[12:13]
	v_pk_mul_f32 v[12:13], v[6:7], v[6:7]
	v_pk_mul_f32 v[10:11], v[8:9], v[8:9]
	v_add_f32_e32 v12, v12, v13
	v_add_f32_e32 v10, v12, v10
	v_add_f32_e32 v10, v10, v11
	ds_bpermute_b32 v5, v5, v10
	v_cndmask_b32_e32 v21, v208, v21, vcc
	v_lshlrev_b32_e32 v25, 2, v21
	v_cmp_lt_i32_e32 vcc, v22, v20
	s_waitcnt lgkmcnt(0)
	v_add_f32_e32 v5, v10, v5
	ds_bpermute_b32 v10, v25, v5
	v_cndmask_b32_e32 v22, v208, v22, vcc
	v_lshlrev_b32_e32 v26, 2, v22
	v_cmp_lt_i32_e32 vcc, v23, v20
	v_lshlrev_b32_e32 v22, 16, v18
	s_waitcnt lgkmcnt(0)
	v_add_f32_e32 v5, v5, v10
	ds_bpermute_b32 v10, v26, v5
	v_cndmask_b32_e32 v20, v208, v23, vcc
	v_lshlrev_b32_e32 v27, 2, v20
	v_and_b32_e32 v23, 0xffff0000, v18
	v_lshlrev_b32_e32 v18, 16, v19
	s_waitcnt lgkmcnt(0)
	v_add_f32_e32 v5, v5, v10
	v_and_b32_e32 v19, 0xffff0000, v19
	ds_bpermute_b32 v26, v27, v5
	v_mul_f32_e32 v11, 0xbfb8aa3b, v22
	v_mul_f32_e32 v12, 0xbfb8aa3b, v23
	v_mul_f32_e32 v13, 0xbfb8aa3b, v18
	v_mul_f32_e32 v28, 0xbfb8aa3b, v19
	v_exp_f32_e32 v11, v11
	v_exp_f32_e32 v12, v12
	v_exp_f32_e32 v13, v13
	v_exp_f32_e32 v25, v28
	s_waitcnt lgkmcnt(0)
	v_add_f32_e32 v5, v5, v26
	v_add_f32_e32 v11, 1.0, v11
	v_add_f32_e32 v12, 1.0, v12
	v_add_f32_e32 v13, 1.0, v13
	v_add_f32_e32 v25, 1.0, v25
	v_fmamk_f32 v5, v5, 0x3c800000, v206
	v_rcp_f32_e32 v10, v11
	v_rcp_f32_e32 v11, v12
	v_rcp_f32_e32 v12, v13
	v_rcp_f32_e32 v13, v25
	v_mul_f32_e32 v25, 0x4b800000, v5
	v_cmp_gt_f32_e32 vcc, s35, v5
	v_lshlrev_b64 v[20:21], 11, v[2:3]
	v_lshl_add_u64 v[20:21], s[6:7], 0, v[20:21]
	v_cndmask_b32_e32 v5, v5, v25, vcc
	v_rsq_f32_e32 v5, v5
	v_lshl_add_u64 v[20:21], v[20:21], 0, v[0:1]
	v_pk_mul_f32 v[10:11], v[10:11], v[22:23]
	v_pk_mul_f32 v[12:13], v[12:13], v[18:19]
	v_mul_f32_e32 v0, 0x45800000, v5
	v_cndmask_b32_e32 v0, v5, v0, vcc
	v_pk_mul_f32 v[6:7], v[6:7], v[0:1] op_sel_hi:[1,0]
	v_pk_mul_f32 v[8:9], v[8:9], v[0:1] op_sel_hi:[1,0]
	v_pk_mul_f32 v[6:7], v[14:15], v[6:7]
	v_pk_mul_f32 v[8:9], v[16:17], v[8:9]
	v_pk_mul_f32 v[6:7], v[6:7], v[10:11]
	v_pk_mul_f32 v[8:9], v[8:9], v[12:13]
	v_cvt_pk_bf16_f32 v6, v6, v7
	v_cvt_pk_bf16_f32 v7, v8, v9
	v_cmp_eq_u32_e32 vcc, 0, v24
	global_store_dwordx2 v[20:21], v[6:7], off
	s_and_saveexec_b64 s[12:13], vcc
	s_cbranch_execz .LBB0_1358
	v_lshlrev_b64 v[2:3], 2, v[2:3]
	v_lshl_add_u64 v[6:7], s[8:9], 0, v[2:3]
	v_lshl_add_u64 v[2:3], s[10:11], 0, v[2:3]
	global_store_dword v[6:7], v1, off
	global_store_dword v[2:3], v1, off
	s_branch .LBB0_1358

.LBB0_1430:
	s_mul_hi_i32 s8, s24, 0x78787879
	s_lshr_b32 s9, s8, 31
	s_ashr_i32 s8, s8, 11
	s_add_i32 s8, s8, s9
	s_mul_i32 s9, s8, 0xffffef00
	s_add_i32 s9, s9, s24
	s_cmpk_gt_i32 s9, 0xff
	s_cselect_b32 s8, s8, 8
	v_readlane_b32 s9, v254, 44
	s_add_i32 s8, s8, s9
	s_mul_hi_i32 s9, s8, 0x6000
	s_mulk_i32 s8, 0x6000
	s_add_u32 s8, s10, s8
	s_waitcnt lgkmcnt(0)
	v_add_u32_sdwa v2, s22, v228 dst_sel:DWORD dst_unused:UNUSED_PAD src0_sel:DWORD src1_sel:BYTE_0
	s_addc_u32 s9, s11, s9
	v_ashrrev_i32_e32 v3, 31, v2
	s_and_saveexec_b64 s[28:29], s[0:1]
	s_xor_b64 s[28:29], exec, s[28:29]
	s_cbranch_execz .LBB0_1432
	v_lshlrev_b64 v[2:3], 2, v[2:3]
	v_lshl_add_u64 v[4:5], s[14:15], 0, v[2:3]
	v_lshl_add_u64 v[2:3], s[8:9], 0, v[2:3]
	v_add_co_u32_e32 v2, vcc, 0x4000, v2
	global_load_dword v0, v[4:5], off
	s_nop 0
	v_addc_co_u32_e32 v3, vcc, 0, v3, vcc
	global_load_dword v2, v[2:3], off
	s_waitcnt vmcnt(0) lgkmcnt(0)
	v_add_f32_e32 v2, 1.0, v2
	v_mul_f32_e32 v0, v0, v2
.LBB0_1432:
	s_andn2_saveexec_b64 s[28:29], s[28:29]
	s_cbranch_execz .LBB0_1434
	v_lshl_add_u64 v[2:3], v[2:3], 2, s[8:9]
	v_add_co_u32_e32 v2, vcc, 0x2000, v2
	s_nop 1
	v_addc_co_u32_e32 v3, vcc, 0, v3, vcc
	global_load_dword v0, v[2:3], off

.LBB0_1452:
	s_or_b64 exec, exec, s[26:27]
	s_waitcnt lgkmcnt(0)
	v_add_u32_e32 v136, s24, v230
	v_mul_hi_i32 v0, v136, s61
	v_lshrrev_b32_e32 v2, 31, v0
	v_ashrrev_i32_e32 v0, 11, v0
	v_add_u32_e32 v0, v0, v2
	v_mad_i32_i24 v3, v0, s48, v136
	v_cmp_lt_i32_e32 vcc, s49, v3
	s_and_saveexec_b64 s[26:27], vcc
	s_xor_b64 s[26:27], exec, s[26:27]
	v_lshlrev_b32_e32 v0, 12, v0
	s_movk_i32 s25, 0xff00
	v_add3_u32 v2, v0, v3, s25
	s_or_saveexec_b64 s[26:27], s[26:27]
	v_mov_b64_e32 v[132:133], s[12:13]
	s_xor_b64 exec, exec, s[26:27]
	v_lshl_add_u32 v2, v0, 8, v3
	v_mov_b64_e32 v[132:133], s[16:17]
	s_or_b64 exec, exec, s[26:27]
	v_ashrrev_i32_e32 v3, 31, v2
	v_lshlrev_b64 v[2:3], 12, v[2:3]
	v_lshl_add_u64 v[2:3], v[132:133], 0, v[2:3]
	v_ashrrev_i32_e32 v137, 31, v136
	v_lshl_add_u64 v[134:135], s[22:23], 2, v[2:3]
	v_lshlrev_b32_e32 v0, 2, v200
	v_lshlrev_b64 v[132:133], 11, v[136:137]
	v_lshl_add_u64 v[2:3], v[134:135], 0, v[0:1]
	v_lshlrev_b32_e32 v138, 2, v202
	v_mov_b32_e32 v139, v1
	v_lshl_add_u64 v[162:163], v[2:3], 0, v[138:139]
	v_lshl_add_u64 v[150:151], s[18:19], 0, v[132:133]
	v_add_u32_e32 v132, s22, v204
	v_lshlrev_b32_e32 v2, 2, v204
	v_mov_b32_e32 v3, v1
	v_add_u32_e32 v140, s56, v2
	v_ashrrev_i32_e32 v133, 31, v132
	v_lshl_add_u64 v[166:167], v[134:135], 0, v[2:3]
	v_lshl_add_u64 v[134:135], s[22:23], 0, v[204:205]
	ds_read_b128 v[142:145], v140 offset:1024
	ds_read_b128 v[146:149], v140 offset:2048
	v_lshl_add_u64 v[168:169], v[132:133], 1, v[150:151]
	v_lshl_add_u64 v[170:171], v[134:135], 1, v[150:151]
	s_waitcnt vmcnt(0)
	global_load_dwordx4 v[150:153], v[162:163], off offset:576
	global_load_dwordx4 v[154:157], v[162:163], off offset:512
	global_load_dwordx4 v[158:161], v[162:163], off offset:64
	s_nop 0
	global_load_dwordx4 v[162:165], v[162:163], off
	s_waitcnt vmcnt(0) lgkmcnt(0)
	v_pk_fma_f32 v[124:125], v[124:125], v[142:143], v[162:163]
	v_pk_fma_f32 v[126:127], v[126:127], v[144:145], v[164:165]
	v_pk_mul_f32 v[142:143], v[146:147], v[124:125]
	v_pk_mul_f32 v[144:145], v[148:149], v[126:127]
	v_cvt_pk_bf16_f32 v142, v142, v143
	v_cvt_pk_bf16_f32 v143, v144, v145
	global_store_dwordx4 v[166:167], v[124:127], off
	global_store_dwordx2 v[168:169], v[142:143], off
	v_pk_mul_f32 v[162:163], v[124:125], v[124:125]
	v_pk_mul_f32 v[146:147], v[126:127], v[126:127]
	ds_read_b128 v[124:127], v140 offset:1088
	ds_read_b128 v[142:145], v140 offset:2112
	v_add_f32_e32 v3, v162, v163
	v_add_f32_e32 v3, v146, v3
	v_add_f32_e32 v3, v147, v3
	s_waitcnt lgkmcnt(0)
	v_pk_fma_f32 v[116:117], v[116:117], v[124:125], v[158:159]
	v_pk_fma_f32 v[118:119], v[118:119], v[126:127], v[160:161]
	global_store_dwordx4 v[166:167], v[116:119], off offset:64
	v_pk_mul_f32 v[148:149], v[116:117], v[116:117]
	v_pk_mul_f32 v[158:159], v[118:119], v[118:119]
	v_pk_mul_f32 v[116:117], v[142:143], v[116:117]
	v_pk_mul_f32 v[118:119], v[144:145], v[118:119]
	v_cvt_pk_bf16_f32 v116, v116, v117
	v_cvt_pk_bf16_f32 v117, v118, v119
	global_store_dwordx2 v[170:171], v[116:117], off offset:32
	ds_read_b128 v[116:119], v140 offset:1536
	ds_read_b128 v[124:127], v140 offset:2560
	v_add_f32_e32 v139, v148, v149
	v_add_f32_e32 v139, v158, v139
	v_add_f32_e32 v139, v159, v139
	s_waitcnt lgkmcnt(0)
	v_pk_fma_f32 v[116:117], v[128:129], v[116:117], v[154:155]
	v_pk_fma_f32 v[118:119], v[130:131], v[118:119], v[156:157]
	global_store_dwordx4 v[166:167], v[116:119], off offset:512
	v_pk_mul_f32 v[128:129], v[116:117], v[116:117]
	v_pk_mul_f32 v[130:131], v[118:119], v[118:119]
	v_pk_mul_f32 v[116:117], v[124:125], v[116:117]
	v_pk_mul_f32 v[118:119], v[126:127], v[118:119]
	v_cvt_pk_bf16_f32 v116, v116, v117
	v_cvt_pk_bf16_f32 v117, v118, v119
	global_store_dwordx2 v[170:171], v[116:117], off offset:256
	ds_read_b128 v[116:119], v140 offset:1600
	ds_read_b128 v[124:127], v140 offset:2624
	v_add_f32_e32 v128, v128, v129
	v_add_f32_e32 v128, v130, v128
	v_add_f32_e32 v3, v3, v139
	s_waitcnt lgkmcnt(0)
	v_pk_fma_f32 v[116:117], v[120:121], v[116:117], v[150:151]
	v_pk_fma_f32 v[118:119], v[122:123], v[118:119], v[152:153]
	global_store_dwordx4 v[166:167], v[116:119], off offset:576
	v_pk_mul_f32 v[120:121], v[116:117], v[116:117]
	v_pk_mul_f32 v[122:123], v[118:119], v[118:119]
	v_pk_mul_f32 v[116:117], v[124:125], v[116:117]
	v_pk_mul_f32 v[118:119], v[126:127], v[118:119]
	v_cvt_pk_bf16_f32 v116, v116, v117
	v_cvt_pk_bf16_f32 v117, v118, v119
	global_store_dwordx2 v[170:171], v[116:117], off offset:288
	v_and_b32_e32 v117, 64, v208
	v_add_f32_e32 v120, v120, v121
	v_xor_b32_e32 v116, 16, v208
	v_add_u32_e32 v117, 64, v117
	v_add_f32_e32 v128, v131, v128
	v_add_f32_e32 v120, v122, v120
	v_cmp_lt_i32_e32 vcc, v116, v117
	v_add_f32_e32 v3, v3, v128
	v_add_f32_e32 v120, v123, v120
	v_cndmask_b32_e32 v116, v208, v116, vcc
	v_add_f32_e32 v3, v3, v120
	v_lshlrev_b32_e32 v122, 2, v116
	ds_bpermute_b32 v116, v122, v3
	s_waitcnt lgkmcnt(0)
	v_add_f32_e32 v3, v3, v116
	v_xor_b32_e32 v116, 32, v208
	v_cmp_lt_i32_e32 vcc, v116, v117
	s_nop 1
	v_cndmask_b32_e32 v116, v208, v116, vcc
	v_lshlrev_b32_e32 v123, 2, v116
	ds_bpermute_b32 v116, v123, v3
	s_and_saveexec_b64 s[26:27], s[6:7]
	s_cbranch_execz .LBB0_1458
	s_waitcnt lgkmcnt(0)
	v_add_f32_e32 v3, v3, v116
	v_lshl_add_u64 v[116:117], v[136:137], 2, s[20:21]
	global_atomic_add_f32 v[116:117], v3, off
.LBB0_1458:
	s_or_b64 exec, exec, s[26:27]
	s_waitcnt lgkmcnt(0)
	v_add_u32_e32 v116, 16, v136
	v_mul_hi_i32 v3, v116, s61
	v_lshrrev_b32_e32 v117, 31, v3
	v_ashrrev_i32_e32 v3, 11, v3
	v_add_u32_e32 v3, v3, v117
	v_mad_i32_i24 v117, v3, s48, v116
	v_cmp_lt_i32_e32 vcc, s49, v117
	s_and_saveexec_b64 s[26:27], vcc
	s_xor_b64 s[26:27], exec, s[26:27]
	v_lshlrev_b32_e32 v3, 12, v3
	s_movk_i32 s25, 0xff00
	v_add3_u32 v118, v3, v117, s25
	s_or_saveexec_b64 s[26:27], s[26:27]
	v_mov_b64_e32 v[120:121], s[12:13]
	s_xor_b64 exec, exec, s[26:27]
	v_lshl_add_u32 v118, v3, 8, v117
	v_mov_b64_e32 v[120:121], s[16:17]
	s_or_b64 exec, exec, s[26:27]
	v_ashrrev_i32_e32 v119, 31, v118
	v_lshlrev_b64 v[118:119], 12, v[118:119]
	v_lshl_add_u64 v[118:119], v[120:121], 0, v[118:119]
	v_lshl_add_u64 v[154:155], s[22:23], 2, v[118:119]
	v_lshl_add_u64 v[118:119], v[154:155], 0, v[0:1]
	v_mov_b32_e32 v139, v1
	v_lshl_add_u64 v[142:143], v[118:119], 0, v[138:139]
	global_load_dwordx4 v[118:121], v[142:143], off
	global_load_dwordx4 v[124:127], v[142:143], off offset:64
	global_load_dwordx4 v[128:131], v[142:143], off offset:512
	s_nop 0
	global_load_dwordx4 v[142:145], v[142:143], off offset:576
	ds_read_b128 v[146:149], v140 offset:1024
	ds_read_b128 v[150:153], v140 offset:2048
	v_ashrrev_i32_e32 v117, 31, v116
	v_mov_b32_e32 v3, v1
	v_lshlrev_b64 v[156:157], 11, v[116:117]
	v_lshl_add_u64 v[156:157], s[18:19], 0, v[156:157]
	v_lshl_add_u64 v[154:155], v[154:155], 0, v[2:3]
	v_lshl_add_u64 v[158:159], v[132:133], 1, v[156:157]
	v_lshl_add_u64 v[156:157], v[134:135], 1, v[156:157]
	s_waitcnt vmcnt(0) lgkmcnt(0)
	v_pk_fma_f32 v[112:113], v[112:113], v[146:147], v[118:119]
	v_pk_fma_f32 v[114:115], v[114:115], v[148:149], v[120:121]
	v_pk_mul_f32 v[120:121], v[150:151], v[112:113]
	v_pk_mul_f32 v[148:149], v[152:153], v[114:115]
	v_pk_mul_f32 v[118:119], v[112:113], v[112:113]
	global_store_dwordx4 v[154:155], v[112:115], off
	v_pk_mul_f32 v[146:147], v[114:115], v[114:115]
	v_add_f32_e32 v3, v118, v119
	v_cvt_pk_bf16_f32 v112, v120, v121
	v_cvt_pk_bf16_f32 v113, v148, v149
	global_store_dwordx2 v[158:159], v[112:113], off
	ds_read_b128 v[112:115], v140 offset:1088
	ds_read_b128 v[118:121], v140 offset:2112
	v_add_f32_e32 v3, v146, v3
	v_add_f32_e32 v3, v147, v3
	s_waitcnt lgkmcnt(0)
	v_pk_fma_f32 v[104:105], v[104:105], v[112:113], v[124:125]
	v_pk_fma_f32 v[106:107], v[106:107], v[114:115], v[126:127]
	global_store_dwordx4 v[154:155], v[104:107], off offset:64
	v_pk_mul_f32 v[112:113], v[104:105], v[104:105]
	v_pk_mul_f32 v[124:125], v[106:107], v[106:107]
	v_pk_mul_f32 v[104:105], v[118:119], v[104:105]
	v_pk_mul_f32 v[106:107], v[120:121], v[106:107]
	v_cvt_pk_bf16_f32 v104, v104, v105
	v_cvt_pk_bf16_f32 v105, v106, v107
	global_store_dwordx2 v[156:157], v[104:105], off offset:32
	v_add_f32_e32 v112, v112, v113
	ds_read_b128 v[104:107], v140 offset:1536
	v_add_f32_e32 v118, v124, v112
	ds_read_b128 v[112:115], v140 offset:2560
	v_add_f32_e32 v118, v125, v118
	v_add_f32_e32 v3, v3, v118
	s_waitcnt lgkmcnt(0)
	v_pk_fma_f32 v[104:105], v[108:109], v[104:105], v[128:129]
	v_pk_fma_f32 v[106:107], v[110:111], v[106:107], v[130:131]
	global_store_dwordx4 v[154:155], v[104:107], off offset:512
	v_pk_mul_f32 v[108:109], v[104:105], v[104:105]
	v_pk_mul_f32 v[118:119], v[106:107], v[106:107]
	v_pk_mul_f32 v[104:105], v[112:113], v[104:105]
	v_pk_mul_f32 v[106:107], v[114:115], v[106:107]
	v_cvt_pk_bf16_f32 v104, v104, v105
	v_cvt_pk_bf16_f32 v105, v106, v107
	global_store_dwordx2 v[156:157], v[104:105], off offset:256
	ds_read_b128 v[104:107], v140 offset:1600
	v_add_f32_e32 v108, v108, v109
	v_add_f32_e32 v112, v118, v108
	ds_read_b128 v[108:111], v140 offset:2624
	v_add_f32_e32 v112, v119, v112
	s_waitcnt lgkmcnt(0)
	v_pk_fma_f32 v[100:101], v[100:101], v[104:105], v[142:143]
	v_pk_fma_f32 v[102:103], v[102:103], v[106:107], v[144:145]
	v_pk_mul_f32 v[104:105], v[100:101], v[100:101]
	v_pk_mul_f32 v[106:107], v[102:103], v[102:103]
	v_add_f32_e32 v104, v104, v105
	v_add_f32_e32 v104, v106, v104
	v_add_f32_e32 v3, v3, v112
	v_add_f32_e32 v104, v107, v104
	v_add_f32_e32 v3, v3, v104
	ds_bpermute_b32 v106, v122, v3
	global_store_dwordx4 v[154:155], v[100:103], off offset:576
	v_pk_mul_f32 v[104:105], v[108:109], v[100:101]
	s_waitcnt lgkmcnt(0)
	v_add_f32_e32 v3, v3, v106
	ds_bpermute_b32 v100, v123, v3
	v_pk_mul_f32 v[102:103], v[110:111], v[102:103]
	v_cvt_pk_bf16_f32 v104, v104, v105
	v_cvt_pk_bf16_f32 v105, v102, v103
	global_store_dwordx2 v[156:157], v[104:105], off offset:288
	s_and_saveexec_b64 s[26:27], s[6:7]
	s_cbranch_execz .LBB0_1464
	s_waitcnt lgkmcnt(0)
	v_add_f32_e32 v3, v3, v100
	v_lshl_add_u64 v[100:101], v[116:117], 2, s[20:21]
	global_atomic_add_f32 v[100:101], v3, off
.LBB0_1464:
	s_or_b64 exec, exec, s[26:27]
	s_waitcnt lgkmcnt(0)
	v_add_u32_e32 v100, 32, v136
	v_mul_hi_i32 v3, v100, s61
	v_lshrrev_b32_e32 v101, 31, v3
	v_ashrrev_i32_e32 v3, 11, v3
	v_add_u32_e32 v3, v3, v101
	v_mad_i32_i24 v101, v3, s48, v100
	v_cmp_lt_i32_e32 vcc, s49, v101
	s_and_saveexec_b64 s[26:27], vcc
	s_xor_b64 s[26:27], exec, s[26:27]
	v_lshlrev_b32_e32 v3, 12, v3
	s_movk_i32 s25, 0xff00
	v_add3_u32 v102, v3, v101, s25
	s_or_saveexec_b64 s[26:27], s[26:27]
	v_mov_b64_e32 v[104:105], s[12:13]
	s_xor_b64 exec, exec, s[26:27]
	v_lshl_add_u32 v102, v3, 8, v101
	v_mov_b64_e32 v[104:105], s[16:17]
	s_or_b64 exec, exec, s[26:27]
	v_ashrrev_i32_e32 v103, 31, v102
	v_lshlrev_b64 v[102:103], 12, v[102:103]
	v_lshl_add_u64 v[102:103], v[104:105], 0, v[102:103]
	v_lshl_add_u64 v[128:129], s[22:23], 2, v[102:103]
	v_lshl_add_u64 v[102:103], v[128:129], 0, v[0:1]
	v_mov_b32_e32 v139, v1
	v_lshl_add_u64 v[114:115], v[102:103], 0, v[138:139]
	global_load_dwordx4 v[102:105], v[114:115], off
	global_load_dwordx4 v[106:109], v[114:115], off offset:64
	global_load_dwordx4 v[110:113], v[114:115], off offset:512
	s_nop 0
	global_load_dwordx4 v[114:117], v[114:115], off offset:576
	ds_read_b128 v[118:121], v140 offset:1024
	ds_read_b128 v[124:127], v140 offset:2048
	v_ashrrev_i32_e32 v101, 31, v100
	v_mov_b32_e32 v3, v1
	v_lshlrev_b64 v[130:131], 11, v[100:101]
	v_lshl_add_u64 v[130:131], s[18:19], 0, v[130:131]
	v_lshl_add_u64 v[128:129], v[128:129], 0, v[2:3]
	v_lshl_add_u64 v[142:143], v[132:133], 1, v[130:131]
	v_lshl_add_u64 v[130:131], v[134:135], 1, v[130:131]
	s_waitcnt vmcnt(0) lgkmcnt(0)
	v_pk_fma_f32 v[96:97], v[96:97], v[118:119], v[102:103]
	v_pk_fma_f32 v[98:99], v[98:99], v[120:121], v[104:105]
	v_pk_mul_f32 v[104:105], v[124:125], v[96:97]
	v_pk_mul_f32 v[120:121], v[126:127], v[98:99]
	v_pk_mul_f32 v[102:103], v[96:97], v[96:97]
	global_store_dwordx4 v[128:129], v[96:99], off
	v_pk_mul_f32 v[118:119], v[98:99], v[98:99]
	v_add_f32_e32 v3, v102, v103
	v_cvt_pk_bf16_f32 v96, v104, v105
	v_cvt_pk_bf16_f32 v97, v120, v121
	global_store_dwordx2 v[142:143], v[96:97], off
	ds_read_b128 v[96:99], v140 offset:1088
	ds_read_b128 v[102:105], v140 offset:2112
	v_add_f32_e32 v3, v118, v3
	v_add_f32_e32 v3, v119, v3
	s_waitcnt lgkmcnt(0)
	v_pk_fma_f32 v[88:89], v[88:89], v[96:97], v[106:107]
	v_pk_fma_f32 v[90:91], v[90:91], v[98:99], v[108:109]
	global_store_dwordx4 v[128:129], v[88:91], off offset:64
	v_pk_mul_f32 v[96:97], v[88:89], v[88:89]
	v_pk_mul_f32 v[106:107], v[90:91], v[90:91]
	v_pk_mul_f32 v[88:89], v[102:103], v[88:89]
	v_pk_mul_f32 v[90:91], v[104:105], v[90:91]
	v_cvt_pk_bf16_f32 v88, v88, v89
	v_cvt_pk_bf16_f32 v89, v90, v91
	global_store_dwordx2 v[130:131], v[88:89], off offset:32
	v_add_f32_e32 v96, v96, v97
	ds_read_b128 v[88:91], v140 offset:1536
	v_add_f32_e32 v102, v106, v96
	ds_read_b128 v[96:99], v140 offset:2560
	v_add_f32_e32 v102, v107, v102
	v_add_f32_e32 v3, v3, v102
	s_waitcnt lgkmcnt(0)
	v_pk_fma_f32 v[88:89], v[92:93], v[88:89], v[110:111]
	v_pk_fma_f32 v[90:91], v[94:95], v[90:91], v[112:113]
	global_store_dwordx4 v[128:129], v[88:91], off offset:512
	v_pk_mul_f32 v[92:93], v[88:89], v[88:89]
	v_pk_mul_f32 v[102:103], v[90:91], v[90:91]
	v_pk_mul_f32 v[88:89], v[96:97], v[88:89]
	v_pk_mul_f32 v[90:91], v[98:99], v[90:91]
	v_cvt_pk_bf16_f32 v88, v88, v89
	v_cvt_pk_bf16_f32 v89, v90, v91
	global_store_dwordx2 v[130:131], v[88:89], off offset:256
	ds_read_b128 v[88:91], v140 offset:1600
	v_add_f32_e32 v92, v92, v93
	v_add_f32_e32 v96, v102, v92
	ds_read_b128 v[92:95], v140 offset:2624
	v_add_f32_e32 v96, v103, v96
	s_waitcnt lgkmcnt(0)
	v_pk_fma_f32 v[84:85], v[84:85], v[88:89], v[114:115]
	v_pk_fma_f32 v[86:87], v[86:87], v[90:91], v[116:117]
	v_pk_mul_f32 v[88:89], v[84:85], v[84:85]
	v_pk_mul_f32 v[90:91], v[86:87], v[86:87]
	v_add_f32_e32 v88, v88, v89
	v_add_f32_e32 v88, v90, v88
	v_add_f32_e32 v3, v3, v96
	v_add_f32_e32 v88, v91, v88
	v_add_f32_e32 v3, v3, v88
	ds_bpermute_b32 v90, v122, v3
	global_store_dwordx4 v[128:129], v[84:87], off offset:576
	v_pk_mul_f32 v[88:89], v[92:93], v[84:85]
	s_waitcnt lgkmcnt(0)
	v_add_f32_e32 v3, v3, v90
	ds_bpermute_b32 v84, v123, v3
	v_pk_mul_f32 v[86:87], v[94:95], v[86:87]
	v_cvt_pk_bf16_f32 v88, v88, v89
	v_cvt_pk_bf16_f32 v89, v86, v87
	global_store_dwordx2 v[130:131], v[88:89], off offset:288
	s_and_saveexec_b64 s[26:27], s[6:7]
	s_cbranch_execz .LBB0_1470
	s_waitcnt lgkmcnt(0)
	v_add_f32_e32 v3, v3, v84
	v_lshl_add_u64 v[84:85], v[100:101], 2, s[20:21]
	global_atomic_add_f32 v[84:85], v3, off
.LBB0_1470:
	s_or_b64 exec, exec, s[26:27]
	s_waitcnt lgkmcnt(0)
	v_add_u32_e32 v84, 48, v136
	v_mul_hi_i32 v3, v84, s61
	v_lshrrev_b32_e32 v85, 31, v3
	v_ashrrev_i32_e32 v3, 11, v3
	v_add_u32_e32 v3, v3, v85
	v_mad_i32_i24 v85, v3, s48, v84
	v_cmp_lt_i32_e32 vcc, s49, v85
	s_and_saveexec_b64 s[26:27], vcc
	s_xor_b64 s[26:27], exec, s[26:27]
	v_lshlrev_b32_e32 v3, 12, v3
	s_movk_i32 s25, 0xff00
	v_add3_u32 v86, v3, v85, s25
	s_or_saveexec_b64 s[26:27], s[26:27]
	v_mov_b64_e32 v[88:89], s[12:13]
	s_xor_b64 exec, exec, s[26:27]
	v_lshl_add_u32 v86, v3, 8, v85
	v_mov_b64_e32 v[88:89], s[16:17]
	s_or_b64 exec, exec, s[26:27]
	v_ashrrev_i32_e32 v87, 31, v86
	v_lshlrev_b64 v[86:87], 12, v[86:87]
	v_lshl_add_u64 v[86:87], v[88:89], 0, v[86:87]
	v_lshl_add_u64 v[110:111], s[22:23], 2, v[86:87]
	v_lshl_add_u64 v[86:87], v[110:111], 0, v[0:1]
	v_mov_b32_e32 v139, v1
	v_lshl_add_u64 v[98:99], v[86:87], 0, v[138:139]
	global_load_dwordx4 v[86:89], v[98:99], off
	global_load_dwordx4 v[90:93], v[98:99], off offset:64
	global_load_dwordx4 v[94:97], v[98:99], off offset:512
	s_nop 0
	global_load_dwordx4 v[98:101], v[98:99], off offset:576
	ds_read_b128 v[102:105], v140 offset:1024
	ds_read_b128 v[106:109], v140 offset:2048
	v_ashrrev_i32_e32 v85, 31, v84
	v_mov_b32_e32 v3, v1
	v_lshlrev_b64 v[112:113], 11, v[84:85]
	v_lshl_add_u64 v[112:113], s[18:19], 0, v[112:113]
	v_lshl_add_u64 v[110:111], v[110:111], 0, v[2:3]
	v_lshl_add_u64 v[114:115], v[132:133], 1, v[112:113]
	v_lshl_add_u64 v[112:113], v[134:135], 1, v[112:113]
	s_waitcnt vmcnt(0) lgkmcnt(0)
	v_pk_fma_f32 v[80:81], v[80:81], v[102:103], v[86:87]
	v_pk_fma_f32 v[82:83], v[82:83], v[104:105], v[88:89]
	v_pk_mul_f32 v[88:89], v[106:107], v[80:81]
	v_pk_mul_f32 v[104:105], v[108:109], v[82:83]
	v_pk_mul_f32 v[86:87], v[80:81], v[80:81]
	global_store_dwordx4 v[110:111], v[80:83], off
	v_pk_mul_f32 v[102:103], v[82:83], v[82:83]
	v_add_f32_e32 v3, v86, v87
	v_cvt_pk_bf16_f32 v80, v88, v89
	v_cvt_pk_bf16_f32 v81, v104, v105
	global_store_dwordx2 v[114:115], v[80:81], off
	ds_read_b128 v[80:83], v140 offset:1088
	ds_read_b128 v[86:89], v140 offset:2112
	v_add_f32_e32 v3, v102, v3
	v_add_f32_e32 v3, v103, v3
	s_waitcnt lgkmcnt(0)
	v_pk_fma_f32 v[72:73], v[72:73], v[80:81], v[90:91]
	v_pk_fma_f32 v[74:75], v[74:75], v[82:83], v[92:93]
	global_store_dwordx4 v[110:111], v[72:75], off offset:64
	v_pk_mul_f32 v[80:81], v[72:73], v[72:73]
	v_pk_mul_f32 v[90:91], v[74:75], v[74:75]
	v_pk_mul_f32 v[72:73], v[86:87], v[72:73]
	v_pk_mul_f32 v[74:75], v[88:89], v[74:75]
	v_cvt_pk_bf16_f32 v72, v72, v73
	v_cvt_pk_bf16_f32 v73, v74, v75
	global_store_dwordx2 v[112:113], v[72:73], off offset:32
	v_add_f32_e32 v80, v80, v81
	ds_read_b128 v[72:75], v140 offset:1536
	v_add_f32_e32 v86, v90, v80
	ds_read_b128 v[80:83], v140 offset:2560
	v_add_f32_e32 v86, v91, v86
	v_add_f32_e32 v3, v3, v86
	s_waitcnt lgkmcnt(0)
	v_pk_fma_f32 v[72:73], v[76:77], v[72:73], v[94:95]
	v_pk_fma_f32 v[74:75], v[78:79], v[74:75], v[96:97]
	global_store_dwordx4 v[110:111], v[72:75], off offset:512
	v_pk_mul_f32 v[76:77], v[72:73], v[72:73]
	v_pk_mul_f32 v[86:87], v[74:75], v[74:75]
	v_pk_mul_f32 v[72:73], v[80:81], v[72:73]
	v_pk_mul_f32 v[74:75], v[82:83], v[74:75]
	v_cvt_pk_bf16_f32 v72, v72, v73
	v_cvt_pk_bf16_f32 v73, v74, v75
	global_store_dwordx2 v[112:113], v[72:73], off offset:256
	ds_read_b128 v[72:75], v140 offset:1600
	v_add_f32_e32 v76, v76, v77
	v_add_f32_e32 v80, v86, v76
	ds_read_b128 v[76:79], v140 offset:2624
	v_add_f32_e32 v80, v87, v80
	s_waitcnt lgkmcnt(0)
	v_pk_fma_f32 v[68:69], v[68:69], v[72:73], v[98:99]
	v_pk_fma_f32 v[70:71], v[70:71], v[74:75], v[100:101]
	v_pk_mul_f32 v[72:73], v[68:69], v[68:69]
	v_pk_mul_f32 v[74:75], v[70:71], v[70:71]
	v_add_f32_e32 v72, v72, v73
	v_add_f32_e32 v72, v74, v72
	v_add_f32_e32 v3, v3, v80
	v_add_f32_e32 v72, v75, v72
	v_add_f32_e32 v3, v3, v72
	ds_bpermute_b32 v74, v122, v3
	global_store_dwordx4 v[110:111], v[68:71], off offset:576
	v_pk_mul_f32 v[72:73], v[76:77], v[68:69]
	s_waitcnt lgkmcnt(0)
	v_add_f32_e32 v3, v3, v74
	ds_bpermute_b32 v68, v123, v3
	v_pk_mul_f32 v[70:71], v[78:79], v[70:71]
	v_cvt_pk_bf16_f32 v72, v72, v73
	v_cvt_pk_bf16_f32 v73, v70, v71
	global_store_dwordx2 v[112:113], v[72:73], off offset:288
	s_and_saveexec_b64 s[26:27], s[6:7]
	s_cbranch_execz .LBB0_1476
	s_waitcnt lgkmcnt(0)
	v_add_f32_e32 v3, v3, v68
	v_lshl_add_u64 v[68:69], v[84:85], 2, s[20:21]
	global_atomic_add_f32 v[68:69], v3, off
.LBB0_1476:
	s_or_b64 exec, exec, s[26:27]
	s_and_b64 vcc, exec, s[8:9]
	s_cbranch_vccnz .LBB0_1407
	s_waitcnt lgkmcnt(0)
	v_add_u32_e32 v68, 0x80, v136
	v_mul_hi_i32 v3, v68, s61
	v_lshrrev_b32_e32 v69, 31, v3
	v_ashrrev_i32_e32 v3, 11, v3
	v_add_u32_e32 v3, v3, v69
	v_mad_i32_i24 v69, v3, s48, v68
	v_cmp_lt_i32_e32 vcc, s49, v69
	s_and_saveexec_b64 s[8:9], vcc
	s_xor_b64 s[8:9], exec, s[8:9]
	v_lshlrev_b32_e32 v3, 12, v3
	s_movk_i32 s25, 0xff00
	v_add3_u32 v70, v3, v69, s25
	s_or_saveexec_b64 s[8:9], s[8:9]
	v_mov_b64_e32 v[72:73], s[12:13]
	s_xor_b64 exec, exec, s[8:9]
	v_lshl_add_u32 v70, v3, 8, v69
	v_mov_b64_e32 v[72:73], s[16:17]
	s_or_b64 exec, exec, s[8:9]
	v_ashrrev_i32_e32 v71, 31, v70
	v_lshlrev_b64 v[70:71], 12, v[70:71]
	v_lshl_add_u64 v[70:71], v[72:73], 0, v[70:71]
	v_lshl_add_u64 v[94:95], s[22:23], 2, v[70:71]
	v_lshl_add_u64 v[70:71], v[94:95], 0, v[0:1]
	v_mov_b32_e32 v139, v1
	v_lshl_add_u64 v[82:83], v[70:71], 0, v[138:139]
	global_load_dwordx4 v[70:73], v[82:83], off
	global_load_dwordx4 v[74:77], v[82:83], off offset:64
	global_load_dwordx4 v[78:81], v[82:83], off offset:512
	s_nop 0
	global_load_dwordx4 v[82:85], v[82:83], off offset:576
	ds_read_b128 v[86:89], v140 offset:1024
	ds_read_b128 v[90:93], v140 offset:2048
	v_ashrrev_i32_e32 v69, 31, v68
	v_mov_b32_e32 v3, v1
	v_lshlrev_b64 v[96:97], 11, v[68:69]
	v_lshl_add_u64 v[96:97], s[18:19], 0, v[96:97]
	v_lshl_add_u64 v[94:95], v[94:95], 0, v[2:3]
	v_lshl_add_u64 v[98:99], v[132:133], 1, v[96:97]
	v_lshl_add_u64 v[96:97], v[134:135], 1, v[96:97]
	s_waitcnt vmcnt(0) lgkmcnt(0)
	v_pk_fma_f32 v[64:65], v[64:65], v[86:87], v[70:71]
	v_pk_fma_f32 v[66:67], v[66:67], v[88:89], v[72:73]
	v_pk_mul_f32 v[72:73], v[90:91], v[64:65]
	v_pk_mul_f32 v[88:89], v[92:93], v[66:67]
	v_pk_mul_f32 v[70:71], v[64:65], v[64:65]
	global_store_dwordx4 v[94:95], v[64:67], off
	v_pk_mul_f32 v[86:87], v[66:67], v[66:67]
	v_add_f32_e32 v3, v70, v71
	v_cvt_pk_bf16_f32 v64, v72, v73
	v_cvt_pk_bf16_f32 v65, v88, v89
	global_store_dwordx2 v[98:99], v[64:65], off
	ds_read_b128 v[64:67], v140 offset:1088
	ds_read_b128 v[70:73], v140 offset:2112
	v_add_f32_e32 v3, v86, v3
	v_add_f32_e32 v3, v87, v3
	s_waitcnt lgkmcnt(0)
	v_pk_fma_f32 v[60:61], v[60:61], v[64:65], v[74:75]
	v_pk_fma_f32 v[62:63], v[62:63], v[66:67], v[76:77]
	global_store_dwordx4 v[94:95], v[60:63], off offset:64
	v_pk_mul_f32 v[64:65], v[60:61], v[60:61]
	v_pk_mul_f32 v[74:75], v[62:63], v[62:63]
	v_pk_mul_f32 v[60:61], v[70:71], v[60:61]
	v_pk_mul_f32 v[62:63], v[72:73], v[62:63]
	v_cvt_pk_bf16_f32 v60, v60, v61
	v_cvt_pk_bf16_f32 v61, v62, v63
	global_store_dwordx2 v[96:97], v[60:61], off offset:32
	v_add_f32_e32 v64, v64, v65
	ds_read_b128 v[60:63], v140 offset:1536
	v_add_f32_e32 v70, v74, v64
	ds_read_b128 v[64:67], v140 offset:2560
	v_add_f32_e32 v70, v75, v70
	v_add_f32_e32 v3, v3, v70
	s_waitcnt lgkmcnt(0)
	v_pk_fma_f32 v[56:57], v[56:57], v[60:61], v[78:79]
	v_pk_fma_f32 v[58:59], v[58:59], v[62:63], v[80:81]
	global_store_dwordx4 v[94:95], v[56:59], off offset:512
	v_pk_mul_f32 v[60:61], v[56:57], v[56:57]
	v_pk_mul_f32 v[70:71], v[58:59], v[58:59]
	v_pk_mul_f32 v[56:57], v[64:65], v[56:57]
	v_pk_mul_f32 v[58:59], v[66:67], v[58:59]
	v_cvt_pk_bf16_f32 v56, v56, v57
	v_cvt_pk_bf16_f32 v57, v58, v59
	global_store_dwordx2 v[96:97], v[56:57], off offset:256
	ds_read_b128 v[56:59], v140 offset:1600
	v_add_f32_e32 v60, v60, v61
	v_add_f32_e32 v64, v70, v60
	ds_read_b128 v[60:63], v140 offset:2624
	v_add_f32_e32 v64, v71, v64
	s_waitcnt lgkmcnt(0)
	v_pk_fma_f32 v[52:53], v[52:53], v[56:57], v[82:83]
	v_pk_fma_f32 v[54:55], v[54:55], v[58:59], v[84:85]
	v_pk_mul_f32 v[56:57], v[52:53], v[52:53]
	v_pk_mul_f32 v[58:59], v[54:55], v[54:55]
	v_add_f32_e32 v56, v56, v57
	v_add_f32_e32 v56, v58, v56
	v_add_f32_e32 v3, v3, v64
	v_add_f32_e32 v56, v59, v56
	v_add_f32_e32 v3, v3, v56
	ds_bpermute_b32 v58, v122, v3
	global_store_dwordx4 v[94:95], v[52:55], off offset:576
	v_pk_mul_f32 v[56:57], v[60:61], v[52:53]
	s_waitcnt lgkmcnt(0)
	v_add_f32_e32 v3, v3, v58
	ds_bpermute_b32 v52, v123, v3
	v_pk_mul_f32 v[54:55], v[62:63], v[54:55]
	v_cvt_pk_bf16_f32 v56, v56, v57
	v_cvt_pk_bf16_f32 v57, v54, v55
	global_store_dwordx2 v[96:97], v[56:57], off offset:288
	s_and_saveexec_b64 s[8:9], s[6:7]
	s_cbranch_execz .LBB0_1483
	s_waitcnt lgkmcnt(0)
	v_add_f32_e32 v3, v3, v52
	v_lshl_add_u64 v[52:53], v[68:69], 2, s[20:21]
	global_atomic_add_f32 v[52:53], v3, off
.LBB0_1483:
	s_or_b64 exec, exec, s[8:9]
	s_waitcnt lgkmcnt(0)
	v_add_u32_e32 v52, 0x90, v136
	v_mul_hi_i32 v3, v52, s61
	v_lshrrev_b32_e32 v53, 31, v3
	v_ashrrev_i32_e32 v3, 11, v3
	v_add_u32_e32 v3, v3, v53
	v_mad_i32_i24 v53, v3, s48, v52
	v_cmp_lt_i32_e32 vcc, s49, v53
	s_and_saveexec_b64 s[8:9], vcc
	s_xor_b64 s[8:9], exec, s[8:9]
	v_lshlrev_b32_e32 v3, 12, v3
	s_movk_i32 s25, 0xff00
	v_add3_u32 v54, v3, v53, s25
	s_or_saveexec_b64 s[8:9], s[8:9]
	v_mov_b64_e32 v[56:57], s[12:13]
	s_xor_b64 exec, exec, s[8:9]
	v_lshl_add_u32 v54, v3, 8, v53
	v_mov_b64_e32 v[56:57], s[16:17]
	s_or_b64 exec, exec, s[8:9]
	v_ashrrev_i32_e32 v55, 31, v54
	v_lshlrev_b64 v[54:55], 12, v[54:55]
	v_lshl_add_u64 v[54:55], v[56:57], 0, v[54:55]
	v_lshl_add_u64 v[78:79], s[22:23], 2, v[54:55]
	v_lshl_add_u64 v[54:55], v[78:79], 0, v[0:1]
	v_mov_b32_e32 v139, v1
	v_lshl_add_u64 v[66:67], v[54:55], 0, v[138:139]
	global_load_dwordx4 v[54:57], v[66:67], off
	global_load_dwordx4 v[58:61], v[66:67], off offset:64
	global_load_dwordx4 v[62:65], v[66:67], off offset:512
	s_nop 0
	global_load_dwordx4 v[66:69], v[66:67], off offset:576
	ds_read_b128 v[70:73], v140 offset:1024
	ds_read_b128 v[74:77], v140 offset:2048
	v_ashrrev_i32_e32 v53, 31, v52
	v_mov_b32_e32 v3, v1
	v_lshlrev_b64 v[80:81], 11, v[52:53]
	v_lshl_add_u64 v[80:81], s[18:19], 0, v[80:81]
	v_lshl_add_u64 v[78:79], v[78:79], 0, v[2:3]
	v_lshl_add_u64 v[82:83], v[132:133], 1, v[80:81]
	v_lshl_add_u64 v[80:81], v[134:135], 1, v[80:81]
	s_waitcnt vmcnt(0) lgkmcnt(0)
	v_pk_fma_f32 v[48:49], v[48:49], v[70:71], v[54:55]
	v_pk_fma_f32 v[50:51], v[50:51], v[72:73], v[56:57]
	v_pk_mul_f32 v[56:57], v[74:75], v[48:49]
	v_pk_mul_f32 v[72:73], v[76:77], v[50:51]
	v_pk_mul_f32 v[54:55], v[48:49], v[48:49]
	global_store_dwordx4 v[78:79], v[48:51], off
	v_pk_mul_f32 v[70:71], v[50:51], v[50:51]
	v_add_f32_e32 v3, v54, v55
	v_cvt_pk_bf16_f32 v48, v56, v57
	v_cvt_pk_bf16_f32 v49, v72, v73
	global_store_dwordx2 v[82:83], v[48:49], off
	ds_read_b128 v[48:51], v140 offset:1088
	ds_read_b128 v[54:57], v140 offset:2112
	v_add_f32_e32 v3, v70, v3
	v_add_f32_e32 v3, v71, v3
	s_waitcnt lgkmcnt(0)
	v_pk_fma_f32 v[44:45], v[44:45], v[48:49], v[58:59]
	v_pk_fma_f32 v[46:47], v[46:47], v[50:51], v[60:61]
	global_store_dwordx4 v[78:79], v[44:47], off offset:64
	v_pk_mul_f32 v[48:49], v[44:45], v[44:45]
	v_pk_mul_f32 v[58:59], v[46:47], v[46:47]
	v_pk_mul_f32 v[44:45], v[54:55], v[44:45]
	v_pk_mul_f32 v[46:47], v[56:57], v[46:47]
	v_cvt_pk_bf16_f32 v44, v44, v45
	v_cvt_pk_bf16_f32 v45, v46, v47
	global_store_dwordx2 v[80:81], v[44:45], off offset:32
	v_add_f32_e32 v48, v48, v49
	ds_read_b128 v[44:47], v140 offset:1536
	v_add_f32_e32 v54, v58, v48
	ds_read_b128 v[48:51], v140 offset:2560
	v_add_f32_e32 v54, v59, v54
	v_add_f32_e32 v3, v3, v54
	s_waitcnt lgkmcnt(0)
	v_pk_fma_f32 v[40:41], v[40:41], v[44:45], v[62:63]
	v_pk_fma_f32 v[42:43], v[42:43], v[46:47], v[64:65]
	global_store_dwordx4 v[78:79], v[40:43], off offset:512
	v_pk_mul_f32 v[44:45], v[40:41], v[40:41]
	v_pk_mul_f32 v[54:55], v[42:43], v[42:43]
	v_pk_mul_f32 v[40:41], v[48:49], v[40:41]
	v_pk_mul_f32 v[42:43], v[50:51], v[42:43]
	v_cvt_pk_bf16_f32 v40, v40, v41
	v_cvt_pk_bf16_f32 v41, v42, v43
	global_store_dwordx2 v[80:81], v[40:41], off offset:256
	ds_read_b128 v[40:43], v140 offset:1600
	v_add_f32_e32 v44, v44, v45
	v_add_f32_e32 v48, v54, v44
	ds_read_b128 v[44:47], v140 offset:2624
	v_add_f32_e32 v48, v55, v48
	s_waitcnt lgkmcnt(0)
	v_pk_fma_f32 v[36:37], v[36:37], v[40:41], v[66:67]
	v_pk_fma_f32 v[38:39], v[38:39], v[42:43], v[68:69]
	v_pk_mul_f32 v[40:41], v[36:37], v[36:37]
	v_pk_mul_f32 v[42:43], v[38:39], v[38:39]
	v_add_f32_e32 v40, v40, v41
	v_add_f32_e32 v40, v42, v40
	v_add_f32_e32 v3, v3, v48
	v_add_f32_e32 v40, v43, v40
	v_add_f32_e32 v3, v3, v40
	ds_bpermute_b32 v42, v122, v3
	global_store_dwordx4 v[78:79], v[36:39], off offset:576
	v_pk_mul_f32 v[40:41], v[44:45], v[36:37]
	s_waitcnt lgkmcnt(0)
	v_add_f32_e32 v3, v3, v42
	ds_bpermute_b32 v36, v123, v3
	v_pk_mul_f32 v[38:39], v[46:47], v[38:39]
	v_cvt_pk_bf16_f32 v40, v40, v41
	v_cvt_pk_bf16_f32 v41, v38, v39
	global_store_dwordx2 v[80:81], v[40:41], off offset:288
	s_and_saveexec_b64 s[8:9], s[6:7]
	s_cbranch_execz .LBB0_1489
	s_waitcnt lgkmcnt(0)
	v_add_f32_e32 v3, v3, v36
	v_lshl_add_u64 v[36:37], v[52:53], 2, s[20:21]
	global_atomic_add_f32 v[36:37], v3, off
.LBB0_1489:
	s_or_b64 exec, exec, s[8:9]
	s_waitcnt lgkmcnt(0)
	v_add_u32_e32 v36, 0xa0, v136
	v_mul_hi_i32 v3, v36, s61
	v_lshrrev_b32_e32 v37, 31, v3
	v_ashrrev_i32_e32 v3, 11, v3
	v_add_u32_e32 v3, v3, v37
	v_mad_i32_i24 v37, v3, s48, v36
	v_cmp_lt_i32_e32 vcc, s49, v37
	s_and_saveexec_b64 s[8:9], vcc
	s_xor_b64 s[8:9], exec, s[8:9]
	v_lshlrev_b32_e32 v3, 12, v3
	s_movk_i32 s25, 0xff00
	v_add3_u32 v38, v3, v37, s25
	s_or_saveexec_b64 s[8:9], s[8:9]
	v_mov_b64_e32 v[40:41], s[12:13]
	s_xor_b64 exec, exec, s[8:9]
	v_lshl_add_u32 v38, v3, 8, v37
	v_mov_b64_e32 v[40:41], s[16:17]
	s_or_b64 exec, exec, s[8:9]
	v_ashrrev_i32_e32 v39, 31, v38
	v_lshlrev_b64 v[38:39], 12, v[38:39]
	v_lshl_add_u64 v[38:39], v[40:41], 0, v[38:39]
	v_lshl_add_u64 v[62:63], s[22:23], 2, v[38:39]
	v_lshl_add_u64 v[38:39], v[62:63], 0, v[0:1]
	v_mov_b32_e32 v139, v1
	v_lshl_add_u64 v[50:51], v[38:39], 0, v[138:139]
	global_load_dwordx4 v[38:41], v[50:51], off
	global_load_dwordx4 v[42:45], v[50:51], off offset:64
	global_load_dwordx4 v[46:49], v[50:51], off offset:512
	s_nop 0
	global_load_dwordx4 v[50:53], v[50:51], off offset:576
	ds_read_b128 v[54:57], v140 offset:1024
	ds_read_b128 v[58:61], v140 offset:2048
	v_ashrrev_i32_e32 v37, 31, v36
	v_mov_b32_e32 v3, v1
	v_lshlrev_b64 v[64:65], 11, v[36:37]
	v_lshl_add_u64 v[64:65], s[18:19], 0, v[64:65]
	v_lshl_add_u64 v[62:63], v[62:63], 0, v[2:3]
	v_lshl_add_u64 v[66:67], v[132:133], 1, v[64:65]
	v_lshl_add_u64 v[64:65], v[134:135], 1, v[64:65]
	s_waitcnt vmcnt(0) lgkmcnt(0)
	v_pk_fma_f32 v[32:33], v[32:33], v[54:55], v[38:39]
	v_pk_fma_f32 v[34:35], v[34:35], v[56:57], v[40:41]
	v_pk_mul_f32 v[40:41], v[58:59], v[32:33]
	v_pk_mul_f32 v[56:57], v[60:61], v[34:35]
	v_pk_mul_f32 v[38:39], v[32:33], v[32:33]
	global_store_dwordx4 v[62:63], v[32:35], off
	v_pk_mul_f32 v[54:55], v[34:35], v[34:35]
	v_add_f32_e32 v3, v38, v39
	v_cvt_pk_bf16_f32 v32, v40, v41
	v_cvt_pk_bf16_f32 v33, v56, v57
	global_store_dwordx2 v[66:67], v[32:33], off
	ds_read_b128 v[32:35], v140 offset:1088
	ds_read_b128 v[38:41], v140 offset:2112
	v_add_f32_e32 v3, v54, v3
	v_add_f32_e32 v3, v55, v3
	s_waitcnt lgkmcnt(0)
	v_pk_fma_f32 v[28:29], v[28:29], v[32:33], v[42:43]
	v_pk_fma_f32 v[30:31], v[30:31], v[34:35], v[44:45]
	global_store_dwordx4 v[62:63], v[28:31], off offset:64
	v_pk_mul_f32 v[32:33], v[28:29], v[28:29]
	v_pk_mul_f32 v[42:43], v[30:31], v[30:31]
	v_pk_mul_f32 v[28:29], v[38:39], v[28:29]
	v_pk_mul_f32 v[30:31], v[40:41], v[30:31]
	v_cvt_pk_bf16_f32 v28, v28, v29
	v_cvt_pk_bf16_f32 v29, v30, v31
	global_store_dwordx2 v[64:65], v[28:29], off offset:32
	v_add_f32_e32 v32, v32, v33
	ds_read_b128 v[28:31], v140 offset:1536
	v_add_f32_e32 v38, v42, v32
	ds_read_b128 v[32:35], v140 offset:2560
	v_add_f32_e32 v38, v43, v38
	v_add_f32_e32 v3, v3, v38
	s_waitcnt lgkmcnt(0)
	v_pk_fma_f32 v[24:25], v[24:25], v[28:29], v[46:47]
	v_pk_fma_f32 v[26:27], v[26:27], v[30:31], v[48:49]
	global_store_dwordx4 v[62:63], v[24:27], off offset:512
	v_pk_mul_f32 v[28:29], v[24:25], v[24:25]
	v_pk_mul_f32 v[38:39], v[26:27], v[26:27]
	v_pk_mul_f32 v[24:25], v[32:33], v[24:25]
	v_pk_mul_f32 v[26:27], v[34:35], v[26:27]
	v_cvt_pk_bf16_f32 v24, v24, v25
	v_cvt_pk_bf16_f32 v25, v26, v27
	global_store_dwordx2 v[64:65], v[24:25], off offset:256
	ds_read_b128 v[24:27], v140 offset:1600
	v_add_f32_e32 v28, v28, v29
	v_add_f32_e32 v32, v38, v28
	ds_read_b128 v[28:31], v140 offset:2624
	v_add_f32_e32 v32, v39, v32
	s_waitcnt lgkmcnt(0)
	v_pk_fma_f32 v[20:21], v[20:21], v[24:25], v[50:51]
	v_pk_fma_f32 v[22:23], v[22:23], v[26:27], v[52:53]
	v_pk_mul_f32 v[24:25], v[20:21], v[20:21]
	v_pk_mul_f32 v[26:27], v[22:23], v[22:23]
	v_add_f32_e32 v24, v24, v25
	v_add_f32_e32 v24, v26, v24
	v_add_f32_e32 v3, v3, v32
	v_add_f32_e32 v24, v27, v24
	v_add_f32_e32 v3, v3, v24
	ds_bpermute_b32 v26, v122, v3
	global_store_dwordx4 v[62:63], v[20:23], off offset:576
	v_pk_mul_f32 v[24:25], v[28:29], v[20:21]
	s_waitcnt lgkmcnt(0)
	v_add_f32_e32 v3, v3, v26
	ds_bpermute_b32 v20, v123, v3
	v_pk_mul_f32 v[22:23], v[30:31], v[22:23]
	v_cvt_pk_bf16_f32 v24, v24, v25
	v_cvt_pk_bf16_f32 v25, v22, v23
	global_store_dwordx2 v[64:65], v[24:25], off offset:288
	s_and_saveexec_b64 s[8:9], s[6:7]
	s_cbranch_execz .LBB0_1495
	s_waitcnt lgkmcnt(0)
	v_add_f32_e32 v3, v3, v20
	v_lshl_add_u64 v[20:21], v[36:37], 2, s[20:21]
	global_atomic_add_f32 v[20:21], v3, off
.LBB0_1495:
	s_or_b64 exec, exec, s[8:9]
	s_waitcnt lgkmcnt(0)
	v_add_u32_e32 v20, 0xb0, v136
	v_mul_hi_i32 v3, v20, s61
	v_lshrrev_b32_e32 v21, 31, v3
	v_ashrrev_i32_e32 v3, 11, v3
	v_add_u32_e32 v3, v3, v21
	v_mad_i32_i24 v21, v3, s48, v20
	v_cmp_lt_i32_e32 vcc, s49, v21
	s_and_saveexec_b64 s[8:9], vcc
	s_xor_b64 s[8:9], exec, s[8:9]
	v_lshlrev_b32_e32 v3, 12, v3
	s_movk_i32 s25, 0xff00
	v_add3_u32 v22, v3, v21, s25
	s_or_saveexec_b64 s[8:9], s[8:9]
	v_mov_b64_e32 v[24:25], s[12:13]
	s_xor_b64 exec, exec, s[8:9]
	v_lshl_add_u32 v22, v3, 8, v21
	v_mov_b64_e32 v[24:25], s[16:17]
	s_or_b64 exec, exec, s[8:9]
	v_ashrrev_i32_e32 v23, 31, v22
	v_lshlrev_b64 v[22:23], 12, v[22:23]
	v_lshl_add_u64 v[22:23], v[24:25], 0, v[22:23]
	v_lshl_add_u64 v[46:47], s[22:23], 2, v[22:23]
	v_lshl_add_u64 v[22:23], v[46:47], 0, v[0:1]
	v_mov_b32_e32 v139, v1
	v_lshl_add_u64 v[34:35], v[22:23], 0, v[138:139]
	global_load_dwordx4 v[22:25], v[34:35], off
	global_load_dwordx4 v[26:29], v[34:35], off offset:64
	global_load_dwordx4 v[30:33], v[34:35], off offset:512
	s_nop 0
	global_load_dwordx4 v[34:37], v[34:35], off offset:576
	ds_read_b128 v[38:41], v140 offset:1024
	ds_read_b128 v[42:45], v140 offset:2048
	v_ashrrev_i32_e32 v21, 31, v20
	v_mov_b32_e32 v3, v1
	v_lshlrev_b64 v[48:49], 11, v[20:21]
	v_lshl_add_u64 v[48:49], s[18:19], 0, v[48:49]
	v_lshl_add_u64 v[46:47], v[46:47], 0, v[2:3]
	v_lshl_add_u64 v[50:51], v[132:133], 1, v[48:49]
	v_lshl_add_u64 v[48:49], v[134:135], 1, v[48:49]
	s_waitcnt vmcnt(0) lgkmcnt(0)
	v_pk_fma_f32 v[16:17], v[16:17], v[38:39], v[22:23]
	v_pk_fma_f32 v[18:19], v[18:19], v[40:41], v[24:25]
	v_pk_mul_f32 v[22:23], v[42:43], v[16:17]
	v_pk_mul_f32 v[24:25], v[44:45], v[18:19]
	v_pk_mul_f32 v[2:3], v[16:17], v[16:17]
	global_store_dwordx4 v[46:47], v[16:19], off
	v_pk_mul_f32 v[38:39], v[18:19], v[18:19]
	v_add_f32_e32 v0, v2, v3
	v_cvt_pk_bf16_f32 v16, v22, v23
	v_cvt_pk_bf16_f32 v17, v24, v25
	global_store_dwordx2 v[50:51], v[16:17], off
	ds_read_b128 v[16:19], v140 offset:1088
	ds_read_b128 v[22:25], v140 offset:2112
	v_add_f32_e32 v0, v38, v0
	v_add_f32_e32 v0, v39, v0
	s_waitcnt lgkmcnt(0)
	v_pk_fma_f32 v[12:13], v[12:13], v[16:17], v[26:27]
	v_pk_fma_f32 v[14:15], v[14:15], v[18:19], v[28:29]
	global_store_dwordx4 v[46:47], v[12:15], off offset:64
	v_pk_mul_f32 v[2:3], v[12:13], v[12:13]
	v_pk_mul_f32 v[26:27], v[14:15], v[14:15]
	v_pk_mul_f32 v[12:13], v[22:23], v[12:13]
	v_pk_mul_f32 v[14:15], v[24:25], v[14:15]
	v_cvt_pk_bf16_f32 v12, v12, v13
	v_cvt_pk_bf16_f32 v13, v14, v15
	global_store_dwordx2 v[48:49], v[12:13], off offset:32
	ds_read_b128 v[12:15], v140 offset:1536
	ds_read_b128 v[16:19], v140 offset:2560
	v_add_f32_e32 v2, v2, v3
	v_add_f32_e32 v2, v26, v2
	v_add_f32_e32 v2, v27, v2
	s_waitcnt lgkmcnt(0)
	v_pk_fma_f32 v[8:9], v[8:9], v[12:13], v[30:31]
	v_pk_fma_f32 v[10:11], v[10:11], v[14:15], v[32:33]
	v_add_f32_e32 v0, v0, v2
	global_store_dwordx4 v[46:47], v[8:11], off offset:512
	v_pk_mul_f32 v[2:3], v[8:9], v[8:9]
	v_pk_mul_f32 v[22:23], v[10:11], v[10:11]
	v_pk_mul_f32 v[8:9], v[16:17], v[8:9]
	v_pk_mul_f32 v[10:11], v[18:19], v[10:11]
	v_cvt_pk_bf16_f32 v8, v8, v9
	v_cvt_pk_bf16_f32 v9, v10, v11
	global_store_dwordx2 v[48:49], v[8:9], off offset:256
	ds_read_b128 v[8:11], v140 offset:1600
	ds_read_b128 v[12:15], v140 offset:2624
	v_add_f32_e32 v2, v2, v3
	v_add_f32_e32 v2, v22, v2
	v_add_f32_e32 v16, v23, v2
	s_waitcnt lgkmcnt(0)
	v_pk_fma_f32 v[2:3], v[4:5], v[8:9], v[34:35]
	v_pk_fma_f32 v[4:5], v[6:7], v[10:11], v[36:37]
	v_pk_mul_f32 v[6:7], v[2:3], v[2:3]
	v_pk_mul_f32 v[8:9], v[4:5], v[4:5]
	v_add_f32_e32 v6, v6, v7
	v_add_f32_e32 v6, v8, v6
	v_add_f32_e32 v0, v0, v16
	v_add_f32_e32 v6, v9, v6
	v_add_f32_e32 v0, v0, v6
	ds_bpermute_b32 v8, v122, v0
	global_store_dwordx4 v[46:47], v[2:5], off offset:576
	v_pk_mul_f32 v[6:7], v[12:13], v[2:3]
	s_waitcnt lgkmcnt(0)
	v_add_f32_e32 v0, v0, v8
	ds_bpermute_b32 v2, v123, v0
	v_pk_mul_f32 v[4:5], v[14:15], v[4:5]
	v_cvt_pk_bf16_f32 v6, v6, v7
	v_cvt_pk_bf16_f32 v7, v4, v5
	global_store_dwordx2 v[48:49], v[6:7], off offset:288
	s_and_saveexec_b64 s[8:9], s[6:7]
	s_cbranch_execz .LBB0_1406
	s_waitcnt lgkmcnt(0)
	v_add_f32_e32 v0, v0, v2
	v_lshl_add_u64 v[2:3], v[20:21], 2, s[20:21]
	global_atomic_add_f32 v[2:3], v0, off
	s_branch .LBB0_1406

.LBB0_1516:
	s_lshl_b32 s0, s42, 8
	s_add_u32 s23, s40, s0
	s_addc_u32 s22, s41, 0
	v_mov_b32_e32 v3, s23
	v_add_co_u32_e32 v4, vcc, 0x1000, v3
	v_mov_b32_e32 v3, s22
	s_nop 0
	v_addc_co_u32_e32 v5, vcc, 0, v3, vcc
	global_atomic_add v4, v[4:5], v203, off offset:1024 sc0
	v_cvt_f32_u32_e32 v3, v2
	v_sub_u32_e32 v5, 0, v2
	v_rcp_iflag_f32_e32 v3, v3
	s_nop 0
	v_mul_f32_e32 v3, 0x4f7ffffe, v3
	v_cvt_u32_f32_e32 v3, v3
	v_mul_lo_u32 v5, v5, v3
	v_mul_hi_u32 v5, v3, v5
	v_add_u32_e32 v3, v3, v5
	s_waitcnt vmcnt(0) lgkmcnt(0)
	v_mul_hi_u32 v3, v4, v3
	v_mul_lo_u32 v5, v3, v2
	v_sub_u32_e32 v5, v4, v5
	v_cmp_ge_u32_e32 vcc, v5, v2
	v_add_u32_e32 v6, 1, v3
	s_nop 0
	v_cndmask_b32_e32 v3, v3, v6, vcc
	v_sub_u32_e32 v6, v5, v2
	v_cndmask_b32_e32 v5, v5, v6, vcc
	v_cmp_ge_u32_e32 vcc, v5, v2
	v_add_u32_e32 v5, 1, v3
	v_add_u32_e32 v6, 1, v4
	v_cndmask_b32_e32 v3, v3, v5, vcc
	v_mad_u64_u32 v[4:5], s[0:1], v2, v3, v[2:3]
	v_cmp_ne_u32_e32 vcc, v6, v4
	s_and_saveexec_b64 s[0:1], vcc
	s_xor_b64 s[0:1], exec, s[0:1]
	s_cbranch_execz .LBB0_1529
	v_mov_b32_e32 v0, s23
	v_add_co_u32_e32 v4, vcc, 0x2000, v0
	v_mov_b32_e32 v0, s22
	s_nop 0
	v_addc_co_u32_e32 v5, vcc, 0, v0, vcc
	global_load_dword v0, v[4:5], off offset:1024 sc1
	s_add_u32 s4, s23, 0x2400
	s_addc_u32 s5, s22, 0
	s_waitcnt vmcnt(0) lgkmcnt(0)
	v_cmp_eq_u32_e32 vcc, v0, v3
	s_and_saveexec_b64 s[2:3], vcc
	s_cbranch_execz .LBB0_1528
	s_mov_b32 s24, 1
	s_mov_b64 s[6:7], 0
	s_branch .LBB0_1520

.LBB0_1546:
	s_or_b64 exec, exec, s[20:21]
	v_lshlrev_b32_e32 v132, 2, v137
	v_lshlrev_b32_e32 v133, 2, v138
	v_add3_u32 v147, s59, v132, v133
	v_add_u32_e32 v148, s16, v136
	v_mov_b64_e32 v[132:133], s[14:15]
	v_or_b32_e32 v149, s18, v137
	v_mad_i64_i32 v[158:159], s[18:19], v148, s46, v[132:133]
	v_lshl_add_u32 v148, v136, 2, s59
	ds_read_b32 v150, v148
	v_ashrrev_i32_e32 v149, 1, v149
	s_add_i32 s56, s56, 1
	s_waitcnt lgkmcnt(0)
	v_fmamk_f32 v150, v150, 0x3a800000, v206
	v_cmp_gt_f32_e32 vcc, s35, v150
	v_mul_f32_e32 v151, 0x4b800000, v150
	s_nop 0
	v_cndmask_b32_e32 v150, v150, v151, vcc
	v_rsq_f32_e32 v150, v150
	s_nop 0
	v_mul_f32_e32 v151, 0x45800000, v150
	v_cndmask_b32_e32 v160, v150, v151, vcc
	ds_read_b128 v[150:153], v147 offset:1024
	ds_read_b128 v[154:157], v147 offset:1088
	s_waitcnt lgkmcnt(0)
	v_pk_fma_f32 v[126:127], v[126:127], v[160:161], v[150:151] op_sel_hi:[1,0,1]
	s_nop 0
	v_mul_f32_e32 v150, 0xbfb8aa3b, v126
	v_mul_f32_e32 v151, 0xbfb8aa3b, v127
	v_exp_f32_e32 v150, v150
	v_exp_f32_e32 v151, v151
	v_pk_fma_f32 v[122:123], v[122:123], v[160:161], v[154:155] op_sel_hi:[1,0,1]
	v_pk_fma_f32 v[124:125], v[124:125], v[160:161], v[156:157] op_sel_hi:[1,0,1]
	v_add_f32_e32 v150, 1.0, v150
	v_add_f32_e32 v151, 1.0, v151
	v_rcp_f32_e32 v150, v150
	v_rcp_f32_e32 v151, v151
	s_nop 0
	v_pk_mul_f32 v[126:127], v[126:127], v[150:151]
	s_nop 0
	v_pk_mul_f32 v[122:123], v[122:123], v[126:127]
	v_pk_fma_f32 v[126:127], v[128:129], v[160:161], v[152:153] op_sel_hi:[1,0,1]
	s_nop 0
	v_mul_f32_e32 v128, 0xbfb8aa3b, v126
	v_mul_f32_e32 v129, 0xbfb8aa3b, v127
	v_exp_f32_e32 v128, v128
	v_exp_f32_e32 v129, v129
	v_add_f32_e32 v128, 1.0, v128
	v_add_f32_e32 v129, 1.0, v129
	v_rcp_f32_e32 v128, v128
	v_rcp_f32_e32 v129, v129
	s_nop 0
	v_pk_mul_f32 v[126:127], v[126:127], v[128:129]
	s_nop 0
	v_pk_mul_f32 v[124:125], v[124:125], v[126:127]
	v_or_b32_e32 v126, v149, v138
	v_ashrrev_i32_e32 v127, 31, v126
	v_cvt_pk_bf16_f32 v128, v122, v123
	v_lshlrev_b64 v[122:123], 1, v[126:127]
	v_cvt_pk_bf16_f32 v129, v124, v125
	v_lshl_add_u64 v[154:155], v[158:159], 0, v[122:123]
	s_waitcnt vmcnt(0)
	global_store_dwordx2 v[154:155], v[128:129], off
	ds_read_b128 v[124:127], v147 offset:1536
	ds_read_b128 v[150:153], v147 offset:1600
	s_waitcnt lgkmcnt(0)
	v_pk_fma_f32 v[118:119], v[118:119], v[160:161], v[124:125] op_sel_hi:[1,0,1]
	s_nop 0
	v_mul_f32_e32 v124, 0xbfb8aa3b, v118
	v_mul_f32_e32 v125, 0xbfb8aa3b, v119
	v_exp_f32_e32 v124, v124
	v_exp_f32_e32 v125, v125
	v_pk_fma_f32 v[114:115], v[114:115], v[160:161], v[150:151] op_sel_hi:[1,0,1]
	v_pk_fma_f32 v[116:117], v[116:117], v[160:161], v[152:153] op_sel_hi:[1,0,1]
	v_add_f32_e32 v124, 1.0, v124
	v_add_f32_e32 v125, 1.0, v125
	v_rcp_f32_e32 v124, v124
	v_rcp_f32_e32 v125, v125
	s_nop 0
	v_pk_mul_f32 v[118:119], v[118:119], v[124:125]
	s_nop 0
	v_pk_mul_f32 v[114:115], v[114:115], v[118:119]
	v_pk_fma_f32 v[118:119], v[120:121], v[160:161], v[126:127] op_sel_hi:[1,0,1]
	v_cvt_pk_bf16_f32 v114, v114, v115
	v_mul_f32_e32 v120, 0xbfb8aa3b, v118
	v_mul_f32_e32 v121, 0xbfb8aa3b, v119
	v_exp_f32_e32 v120, v120
	v_exp_f32_e32 v121, v121
	v_add_f32_e32 v120, 1.0, v120
	v_add_f32_e32 v121, 1.0, v121
	v_rcp_f32_e32 v120, v120
	v_rcp_f32_e32 v121, v121
	s_nop 0
	v_pk_mul_f32 v[118:119], v[118:119], v[120:121]
	s_nop 0
	v_pk_mul_f32 v[116:117], v[116:117], v[118:119]
	s_nop 0
	v_cvt_pk_bf16_f32 v115, v116, v117
	global_store_dwordx2 v[154:155], v[114:115], off offset:128
	v_or_b32_e32 v114, 16, v136
	v_add_u32_e32 v114, s16, v114
	v_mad_i64_i32 v[124:125], s[18:19], v114, s46, v[132:133]
	ds_read_b32 v114, v148 offset:64
	s_waitcnt lgkmcnt(0)
	v_fmamk_f32 v114, v114, 0x3a800000, v206
	v_cmp_gt_f32_e32 vcc, s35, v114
	v_mul_f32_e32 v115, 0x4b800000, v114
	s_nop 0
	v_cndmask_b32_e32 v114, v114, v115, vcc
	v_rsq_f32_e32 v114, v114
	s_nop 0
	v_mul_f32_e32 v115, 0x45800000, v114
	v_cndmask_b32_e32 v126, v114, v115, vcc
	ds_read_b128 v[114:117], v147 offset:1024
	ds_read_b128 v[118:121], v147 offset:1088
	s_waitcnt lgkmcnt(0)
	v_pk_fma_f32 v[110:111], v[110:111], v[126:127], v[114:115] op_sel_hi:[1,0,1]
	s_nop 0
	v_mul_f32_e32 v114, 0xbfb8aa3b, v110
	v_mul_f32_e32 v115, 0xbfb8aa3b, v111
	v_exp_f32_e32 v114, v114
	v_exp_f32_e32 v115, v115
	v_pk_fma_f32 v[106:107], v[106:107], v[126:127], v[118:119] op_sel_hi:[1,0,1]
	v_pk_fma_f32 v[108:109], v[108:109], v[126:127], v[120:121] op_sel_hi:[1,0,1]
	v_add_f32_e32 v114, 1.0, v114
	v_add_f32_e32 v115, 1.0, v115
	v_rcp_f32_e32 v114, v114
	v_rcp_f32_e32 v115, v115
	s_nop 0
	v_pk_mul_f32 v[110:111], v[110:111], v[114:115]
	s_nop 0
	v_pk_mul_f32 v[106:107], v[106:107], v[110:111]
	v_pk_fma_f32 v[110:111], v[112:113], v[126:127], v[116:117] op_sel_hi:[1,0,1]
	v_cvt_pk_bf16_f32 v106, v106, v107
	v_mul_f32_e32 v112, 0xbfb8aa3b, v110
	v_mul_f32_e32 v113, 0xbfb8aa3b, v111
	v_exp_f32_e32 v112, v112
	v_exp_f32_e32 v113, v113
	v_lshl_add_u64 v[114:115], v[124:125], 0, v[122:123]
	v_add_f32_e32 v112, 1.0, v112
	v_add_f32_e32 v113, 1.0, v113
	v_rcp_f32_e32 v112, v112
	v_rcp_f32_e32 v113, v113
	s_nop 0
	v_pk_mul_f32 v[110:111], v[110:111], v[112:113]
	s_nop 0
	v_pk_mul_f32 v[108:109], v[108:109], v[110:111]
	s_nop 0
	v_cvt_pk_bf16_f32 v107, v108, v109
	global_store_dwordx2 v[114:115], v[106:107], off
	ds_read_b128 v[106:109], v147 offset:1536
	ds_read_b128 v[110:113], v147 offset:1600
	s_waitcnt lgkmcnt(0)
	v_pk_fma_f32 v[102:103], v[102:103], v[126:127], v[106:107] op_sel_hi:[1,0,1]
	s_nop 0
	v_mul_f32_e32 v106, 0xbfb8aa3b, v102
	v_mul_f32_e32 v107, 0xbfb8aa3b, v103
	v_exp_f32_e32 v106, v106
	v_exp_f32_e32 v107, v107
	v_pk_fma_f32 v[98:99], v[98:99], v[126:127], v[110:111] op_sel_hi:[1,0,1]
	v_pk_fma_f32 v[100:101], v[100:101], v[126:127], v[112:113] op_sel_hi:[1,0,1]
	v_add_f32_e32 v106, 1.0, v106
	v_add_f32_e32 v107, 1.0, v107
	v_rcp_f32_e32 v106, v106
	v_rcp_f32_e32 v107, v107
	s_nop 0
	v_pk_mul_f32 v[102:103], v[102:103], v[106:107]
	s_nop 0
	v_pk_mul_f32 v[98:99], v[98:99], v[102:103]
	v_pk_fma_f32 v[102:103], v[104:105], v[126:127], v[108:109] op_sel_hi:[1,0,1]
	v_cvt_pk_bf16_f32 v98, v98, v99
	v_mul_f32_e32 v104, 0xbfb8aa3b, v102
	v_mul_f32_e32 v105, 0xbfb8aa3b, v103
	v_exp_f32_e32 v104, v104
	v_exp_f32_e32 v105, v105
	v_add_f32_e32 v104, 1.0, v104
	v_add_f32_e32 v105, 1.0, v105
	v_rcp_f32_e32 v104, v104
	v_rcp_f32_e32 v105, v105
	s_nop 0
	v_pk_mul_f32 v[102:103], v[102:103], v[104:105]
	s_nop 0
	v_pk_mul_f32 v[100:101], v[100:101], v[102:103]
	s_nop 0
	v_cvt_pk_bf16_f32 v99, v100, v101
	global_store_dwordx2 v[114:115], v[98:99], off offset:128
	v_or_b32_e32 v98, 32, v136
	v_add_u32_e32 v98, s16, v98
	v_mad_i64_i32 v[106:107], s[18:19], v98, s46, v[132:133]
	ds_read_b32 v98, v148 offset:128
	s_waitcnt lgkmcnt(0)
	v_fmamk_f32 v98, v98, 0x3a800000, v206
	v_cmp_gt_f32_e32 vcc, s35, v98
	v_mul_f32_e32 v99, 0x4b800000, v98
	s_nop 0
	v_cndmask_b32_e32 v98, v98, v99, vcc
	v_rsq_f32_e32 v98, v98
	s_nop 0
	v_mul_f32_e32 v99, 0x45800000, v98
	v_cndmask_b32_e32 v108, v98, v99, vcc
	ds_read_b128 v[98:101], v147 offset:1024
	ds_read_b128 v[102:105], v147 offset:1088
	s_waitcnt lgkmcnt(0)
	v_pk_fma_f32 v[94:95], v[94:95], v[108:109], v[98:99] op_sel_hi:[1,0,1]
	s_nop 0
	v_mul_f32_e32 v98, 0xbfb8aa3b, v94
	v_mul_f32_e32 v99, 0xbfb8aa3b, v95
	v_exp_f32_e32 v98, v98
	v_exp_f32_e32 v99, v99
	v_pk_fma_f32 v[90:91], v[90:91], v[108:109], v[102:103] op_sel_hi:[1,0,1]
	v_pk_fma_f32 v[92:93], v[92:93], v[108:109], v[104:105] op_sel_hi:[1,0,1]
	v_add_f32_e32 v98, 1.0, v98
	v_add_f32_e32 v99, 1.0, v99
	v_rcp_f32_e32 v98, v98
	v_rcp_f32_e32 v99, v99
	s_nop 0
	v_pk_mul_f32 v[94:95], v[94:95], v[98:99]
	s_nop 0
	v_pk_mul_f32 v[90:91], v[90:91], v[94:95]
	v_pk_fma_f32 v[94:95], v[96:97], v[108:109], v[100:101] op_sel_hi:[1,0,1]
	v_cvt_pk_bf16_f32 v90, v90, v91
	v_mul_f32_e32 v96, 0xbfb8aa3b, v94
	v_mul_f32_e32 v97, 0xbfb8aa3b, v95
	v_exp_f32_e32 v96, v96
	v_exp_f32_e32 v97, v97
	v_lshl_add_u64 v[98:99], v[106:107], 0, v[122:123]
	v_add_f32_e32 v96, 1.0, v96
	v_add_f32_e32 v97, 1.0, v97
	v_rcp_f32_e32 v96, v96
	v_rcp_f32_e32 v97, v97
	s_nop 0
	v_pk_mul_f32 v[94:95], v[94:95], v[96:97]
	s_nop 0
	v_pk_mul_f32 v[92:93], v[92:93], v[94:95]
	s_nop 0
	v_cvt_pk_bf16_f32 v91, v92, v93
	global_store_dwordx2 v[98:99], v[90:91], off
	ds_read_b128 v[90:93], v147 offset:1536
	ds_read_b128 v[94:97], v147 offset:1600
	s_waitcnt lgkmcnt(0)
	v_pk_fma_f32 v[86:87], v[86:87], v[108:109], v[90:91] op_sel_hi:[1,0,1]
	s_nop 0
	v_mul_f32_e32 v90, 0xbfb8aa3b, v86
	v_mul_f32_e32 v91, 0xbfb8aa3b, v87
	v_exp_f32_e32 v90, v90
	v_exp_f32_e32 v91, v91
	v_pk_fma_f32 v[82:83], v[82:83], v[108:109], v[94:95] op_sel_hi:[1,0,1]
	v_pk_fma_f32 v[84:85], v[84:85], v[108:109], v[96:97] op_sel_hi:[1,0,1]
	v_add_f32_e32 v90, 1.0, v90
	v_add_f32_e32 v91, 1.0, v91
	v_rcp_f32_e32 v90, v90
	v_rcp_f32_e32 v91, v91
	s_nop 0
	v_pk_mul_f32 v[86:87], v[86:87], v[90:91]
	s_nop 0
	v_pk_mul_f32 v[82:83], v[82:83], v[86:87]
	v_pk_fma_f32 v[86:87], v[88:89], v[108:109], v[92:93] op_sel_hi:[1,0,1]
	v_cvt_pk_bf16_f32 v82, v82, v83
	v_mul_f32_e32 v88, 0xbfb8aa3b, v86
	v_mul_f32_e32 v89, 0xbfb8aa3b, v87
	v_exp_f32_e32 v88, v88
	v_exp_f32_e32 v89, v89
	v_add_f32_e32 v88, 1.0, v88
	v_add_f32_e32 v89, 1.0, v89
	v_rcp_f32_e32 v88, v88
	v_rcp_f32_e32 v89, v89
	s_nop 0
	v_pk_mul_f32 v[86:87], v[86:87], v[88:89]
	s_nop 0
	v_pk_mul_f32 v[84:85], v[84:85], v[86:87]
	s_nop 0
	v_cvt_pk_bf16_f32 v83, v84, v85
	global_store_dwordx2 v[98:99], v[82:83], off offset:128
	v_or_b32_e32 v82, 48, v136
	v_add_u32_e32 v82, s16, v82
	v_mad_i64_i32 v[90:91], s[18:19], v82, s46, v[132:133]
	ds_read_b32 v82, v148 offset:192
	s_waitcnt lgkmcnt(0)
	v_fmamk_f32 v82, v82, 0x3a800000, v206
	v_cmp_gt_f32_e32 vcc, s35, v82
	v_mul_f32_e32 v83, 0x4b800000, v82
	s_nop 0
	v_cndmask_b32_e32 v82, v82, v83, vcc
	v_rsq_f32_e32 v82, v82
	s_nop 0
	v_mul_f32_e32 v83, 0x45800000, v82
	v_cndmask_b32_e32 v92, v82, v83, vcc
	ds_read_b128 v[82:85], v147 offset:1024
	ds_read_b128 v[86:89], v147 offset:1088
	s_waitcnt lgkmcnt(0)
	v_pk_fma_f32 v[78:79], v[78:79], v[92:93], v[82:83] op_sel_hi:[1,0,1]
	s_nop 0
	v_mul_f32_e32 v82, 0xbfb8aa3b, v78
	v_mul_f32_e32 v83, 0xbfb8aa3b, v79
	v_exp_f32_e32 v82, v82
	v_exp_f32_e32 v83, v83
	v_pk_fma_f32 v[74:75], v[74:75], v[92:93], v[86:87] op_sel_hi:[1,0,1]
	v_pk_fma_f32 v[76:77], v[76:77], v[92:93], v[88:89] op_sel_hi:[1,0,1]
	v_add_f32_e32 v82, 1.0, v82
	v_add_f32_e32 v83, 1.0, v83
	v_rcp_f32_e32 v82, v82
	v_rcp_f32_e32 v83, v83
	s_nop 0
	v_pk_mul_f32 v[78:79], v[78:79], v[82:83]
	s_nop 0
	v_pk_mul_f32 v[74:75], v[74:75], v[78:79]
	v_pk_fma_f32 v[78:79], v[80:81], v[92:93], v[84:85] op_sel_hi:[1,0,1]
	v_cvt_pk_bf16_f32 v74, v74, v75
	v_mul_f32_e32 v80, 0xbfb8aa3b, v78
	v_mul_f32_e32 v81, 0xbfb8aa3b, v79
	v_exp_f32_e32 v80, v80
	v_exp_f32_e32 v81, v81
	v_lshl_add_u64 v[82:83], v[90:91], 0, v[122:123]
	v_add_f32_e32 v80, 1.0, v80
	v_add_f32_e32 v81, 1.0, v81
	v_rcp_f32_e32 v80, v80
	v_rcp_f32_e32 v81, v81
	s_nop 0
	v_pk_mul_f32 v[78:79], v[78:79], v[80:81]
	s_nop 0
	v_pk_mul_f32 v[76:77], v[76:77], v[78:79]
	s_nop 0
	v_cvt_pk_bf16_f32 v75, v76, v77
	global_store_dwordx2 v[82:83], v[74:75], off
	ds_read_b128 v[74:77], v147 offset:1536
	ds_read_b128 v[78:81], v147 offset:1600
	s_waitcnt lgkmcnt(0)
	v_pk_fma_f32 v[70:71], v[70:71], v[92:93], v[74:75] op_sel_hi:[1,0,1]
	s_nop 0
	v_mul_f32_e32 v74, 0xbfb8aa3b, v70
	v_mul_f32_e32 v75, 0xbfb8aa3b, v71
	v_exp_f32_e32 v74, v74
	v_exp_f32_e32 v75, v75
	v_pk_fma_f32 v[66:67], v[66:67], v[92:93], v[78:79] op_sel_hi:[1,0,1]
	v_pk_fma_f32 v[68:69], v[68:69], v[92:93], v[80:81] op_sel_hi:[1,0,1]
	v_add_f32_e32 v74, 1.0, v74
	v_add_f32_e32 v75, 1.0, v75
	v_rcp_f32_e32 v74, v74
	v_rcp_f32_e32 v75, v75
	s_nop 0
	v_pk_mul_f32 v[70:71], v[70:71], v[74:75]
	s_nop 0
	v_pk_mul_f32 v[66:67], v[66:67], v[70:71]
	v_pk_fma_f32 v[70:71], v[72:73], v[92:93], v[76:77] op_sel_hi:[1,0,1]
	v_cvt_pk_bf16_f32 v66, v66, v67
	v_mul_f32_e32 v72, 0xbfb8aa3b, v70
	v_mul_f32_e32 v73, 0xbfb8aa3b, v71
	v_exp_f32_e32 v72, v72
	v_exp_f32_e32 v73, v73
	v_add_f32_e32 v72, 1.0, v72
	v_add_f32_e32 v73, 1.0, v73
	v_rcp_f32_e32 v72, v72
	v_rcp_f32_e32 v73, v73
	s_nop 0
	v_pk_mul_f32 v[70:71], v[70:71], v[72:73]
	s_nop 0
	v_pk_mul_f32 v[68:69], v[68:69], v[70:71]
	s_nop 0
	v_cvt_pk_bf16_f32 v67, v68, v69
	global_store_dwordx2 v[82:83], v[66:67], off offset:128
	v_add_u32_e32 v66, 0x80, v136
	v_add_u32_e32 v66, s16, v66
	v_mad_i64_i32 v[74:75], s[18:19], v66, s46, v[132:133]
	ds_read_b32 v66, v148 offset:512
	s_waitcnt lgkmcnt(0)
	v_fmamk_f32 v66, v66, 0x3a800000, v206
	v_cmp_gt_f32_e32 vcc, s35, v66
	v_mul_f32_e32 v67, 0x4b800000, v66
	s_nop 0
	v_cndmask_b32_e32 v66, v66, v67, vcc
	v_rsq_f32_e32 v66, v66
	s_nop 0
	v_mul_f32_e32 v67, 0x45800000, v66
	v_cndmask_b32_e32 v76, v66, v67, vcc
	ds_read_b128 v[66:69], v147 offset:1024
	ds_read_b128 v[70:73], v147 offset:1088
	s_waitcnt lgkmcnt(0)
	v_pk_fma_f32 v[62:63], v[62:63], v[76:77], v[66:67] op_sel_hi:[1,0,1]
	s_nop 0
	v_mul_f32_e32 v66, 0xbfb8aa3b, v62
	v_mul_f32_e32 v67, 0xbfb8aa3b, v63
	v_exp_f32_e32 v66, v66
	v_exp_f32_e32 v67, v67
	v_pk_fma_f32 v[58:59], v[58:59], v[76:77], v[70:71] op_sel_hi:[1,0,1]
	v_pk_fma_f32 v[60:61], v[60:61], v[76:77], v[72:73] op_sel_hi:[1,0,1]
	v_add_f32_e32 v66, 1.0, v66
	v_add_f32_e32 v67, 1.0, v67
	v_rcp_f32_e32 v66, v66
	v_rcp_f32_e32 v67, v67
	s_nop 0
	v_pk_mul_f32 v[62:63], v[62:63], v[66:67]
	s_nop 0
	v_pk_mul_f32 v[58:59], v[58:59], v[62:63]
	v_pk_fma_f32 v[62:63], v[64:65], v[76:77], v[68:69] op_sel_hi:[1,0,1]
	v_cvt_pk_bf16_f32 v58, v58, v59
	v_mul_f32_e32 v64, 0xbfb8aa3b, v62
	v_mul_f32_e32 v65, 0xbfb8aa3b, v63
	v_exp_f32_e32 v64, v64
	v_exp_f32_e32 v65, v65
	v_lshl_add_u64 v[66:67], v[74:75], 0, v[122:123]
	v_add_f32_e32 v64, 1.0, v64
	v_add_f32_e32 v65, 1.0, v65
	v_rcp_f32_e32 v64, v64
	v_rcp_f32_e32 v65, v65
	s_nop 0
	v_pk_mul_f32 v[62:63], v[62:63], v[64:65]
	s_nop 0
	v_pk_mul_f32 v[60:61], v[60:61], v[62:63]
	s_nop 0
	v_cvt_pk_bf16_f32 v59, v60, v61
	global_store_dwordx2 v[66:67], v[58:59], off
	ds_read_b128 v[58:61], v147 offset:1536
	ds_read_b128 v[62:65], v147 offset:1600
	s_waitcnt lgkmcnt(0)
	v_pk_fma_f32 v[54:55], v[54:55], v[76:77], v[58:59] op_sel_hi:[1,0,1]
	s_nop 0
	v_mul_f32_e32 v58, 0xbfb8aa3b, v54
	v_mul_f32_e32 v59, 0xbfb8aa3b, v55
	v_exp_f32_e32 v58, v58
	v_exp_f32_e32 v59, v59
	v_pk_fma_f32 v[50:51], v[50:51], v[76:77], v[62:63] op_sel_hi:[1,0,1]
	v_pk_fma_f32 v[52:53], v[52:53], v[76:77], v[64:65] op_sel_hi:[1,0,1]
	v_add_f32_e32 v58, 1.0, v58
	v_add_f32_e32 v59, 1.0, v59
	v_rcp_f32_e32 v58, v58
	v_rcp_f32_e32 v59, v59
	s_nop 0
	v_pk_mul_f32 v[54:55], v[54:55], v[58:59]
	s_nop 0
	v_pk_mul_f32 v[50:51], v[50:51], v[54:55]
	v_pk_fma_f32 v[54:55], v[56:57], v[76:77], v[60:61] op_sel_hi:[1,0,1]
	v_cvt_pk_bf16_f32 v50, v50, v51
	v_mul_f32_e32 v56, 0xbfb8aa3b, v54
	v_mul_f32_e32 v57, 0xbfb8aa3b, v55
	v_exp_f32_e32 v56, v56
	v_exp_f32_e32 v57, v57
	v_add_f32_e32 v56, 1.0, v56
	v_add_f32_e32 v57, 1.0, v57
	v_rcp_f32_e32 v56, v56
	v_rcp_f32_e32 v57, v57
	s_nop 0
	v_pk_mul_f32 v[54:55], v[54:55], v[56:57]
	s_nop 0
	v_pk_mul_f32 v[52:53], v[52:53], v[54:55]
	s_nop 0
	v_cvt_pk_bf16_f32 v51, v52, v53
	global_store_dwordx2 v[66:67], v[50:51], off offset:128
	v_add_u32_e32 v50, 0x90, v136
	v_add_u32_e32 v50, s16, v50
	v_mad_i64_i32 v[58:59], s[18:19], v50, s46, v[132:133]
	ds_read_b32 v50, v148 offset:576
	s_waitcnt lgkmcnt(0)
	v_fmamk_f32 v50, v50, 0x3a800000, v206
	v_cmp_gt_f32_e32 vcc, s35, v50
	v_mul_f32_e32 v51, 0x4b800000, v50
	s_nop 0
	v_cndmask_b32_e32 v50, v50, v51, vcc
	v_rsq_f32_e32 v50, v50
	s_nop 0
	v_mul_f32_e32 v51, 0x45800000, v50
	v_cndmask_b32_e32 v60, v50, v51, vcc
	ds_read_b128 v[50:53], v147 offset:1024
	ds_read_b128 v[54:57], v147 offset:1088
	s_waitcnt lgkmcnt(0)
	v_pk_fma_f32 v[46:47], v[46:47], v[60:61], v[50:51] op_sel_hi:[1,0,1]
	s_nop 0
	v_mul_f32_e32 v50, 0xbfb8aa3b, v46
	v_mul_f32_e32 v51, 0xbfb8aa3b, v47
	v_exp_f32_e32 v50, v50
	v_exp_f32_e32 v51, v51
	v_pk_fma_f32 v[42:43], v[42:43], v[60:61], v[54:55] op_sel_hi:[1,0,1]
	v_pk_fma_f32 v[44:45], v[44:45], v[60:61], v[56:57] op_sel_hi:[1,0,1]
	v_add_f32_e32 v50, 1.0, v50
	v_add_f32_e32 v51, 1.0, v51
	v_rcp_f32_e32 v50, v50
	v_rcp_f32_e32 v51, v51
	s_nop 0
	v_pk_mul_f32 v[46:47], v[46:47], v[50:51]
	s_nop 0
	v_pk_mul_f32 v[42:43], v[42:43], v[46:47]
	v_pk_fma_f32 v[46:47], v[48:49], v[60:61], v[52:53] op_sel_hi:[1,0,1]
	v_cvt_pk_bf16_f32 v42, v42, v43
	v_mul_f32_e32 v48, 0xbfb8aa3b, v46
	v_mul_f32_e32 v49, 0xbfb8aa3b, v47
	v_exp_f32_e32 v48, v48
	v_exp_f32_e32 v49, v49
	v_lshl_add_u64 v[50:51], v[58:59], 0, v[122:123]
	v_add_f32_e32 v48, 1.0, v48
	v_add_f32_e32 v49, 1.0, v49
	v_rcp_f32_e32 v48, v48
	v_rcp_f32_e32 v49, v49
	s_nop 0
	v_pk_mul_f32 v[46:47], v[46:47], v[48:49]
	s_nop 0
	v_pk_mul_f32 v[44:45], v[44:45], v[46:47]
	s_nop 0
	v_cvt_pk_bf16_f32 v43, v44, v45
	global_store_dwordx2 v[50:51], v[42:43], off
	ds_read_b128 v[42:45], v147 offset:1536
	ds_read_b128 v[46:49], v147 offset:1600
	s_waitcnt lgkmcnt(0)
	v_pk_fma_f32 v[38:39], v[38:39], v[60:61], v[42:43] op_sel_hi:[1,0,1]
	s_nop 0
	v_mul_f32_e32 v42, 0xbfb8aa3b, v38
	v_mul_f32_e32 v43, 0xbfb8aa3b, v39
	v_exp_f32_e32 v42, v42
	v_exp_f32_e32 v43, v43
	v_pk_fma_f32 v[34:35], v[34:35], v[60:61], v[46:47] op_sel_hi:[1,0,1]
	v_pk_fma_f32 v[36:37], v[36:37], v[60:61], v[48:49] op_sel_hi:[1,0,1]
	v_add_f32_e32 v42, 1.0, v42
	v_add_f32_e32 v43, 1.0, v43
	v_rcp_f32_e32 v42, v42
	v_rcp_f32_e32 v43, v43
	s_nop 0
	v_pk_mul_f32 v[38:39], v[38:39], v[42:43]
	s_nop 0
	v_pk_mul_f32 v[34:35], v[34:35], v[38:39]
	v_pk_fma_f32 v[38:39], v[40:41], v[60:61], v[44:45] op_sel_hi:[1,0,1]
	v_cvt_pk_bf16_f32 v34, v34, v35
	v_mul_f32_e32 v40, 0xbfb8aa3b, v38
	v_mul_f32_e32 v41, 0xbfb8aa3b, v39
	v_exp_f32_e32 v40, v40
	v_exp_f32_e32 v41, v41
	v_add_f32_e32 v40, 1.0, v40
	v_add_f32_e32 v41, 1.0, v41
	v_rcp_f32_e32 v40, v40
	v_rcp_f32_e32 v41, v41
	s_nop 0
	v_pk_mul_f32 v[38:39], v[38:39], v[40:41]
	s_nop 0
	v_pk_mul_f32 v[36:37], v[36:37], v[38:39]
	s_nop 0
	v_cvt_pk_bf16_f32 v35, v36, v37
	global_store_dwordx2 v[50:51], v[34:35], off offset:128
	v_add_u32_e32 v34, 0xa0, v136
	v_add_u32_e32 v34, s16, v34
	v_mad_i64_i32 v[42:43], s[18:19], v34, s46, v[132:133]
	ds_read_b32 v34, v148 offset:640
	s_waitcnt lgkmcnt(0)
	v_fmamk_f32 v34, v34, 0x3a800000, v206
	v_cmp_gt_f32_e32 vcc, s35, v34
	v_mul_f32_e32 v35, 0x4b800000, v34
	s_nop 0
	v_cndmask_b32_e32 v34, v34, v35, vcc
	v_rsq_f32_e32 v34, v34
	s_nop 0
	v_mul_f32_e32 v35, 0x45800000, v34
	v_cndmask_b32_e32 v44, v34, v35, vcc
	ds_read_b128 v[34:37], v147 offset:1024
	ds_read_b128 v[38:41], v147 offset:1088
	s_waitcnt lgkmcnt(0)
	v_pk_fma_f32 v[30:31], v[30:31], v[44:45], v[34:35] op_sel_hi:[1,0,1]
	s_nop 0
	v_mul_f32_e32 v34, 0xbfb8aa3b, v30
	v_mul_f32_e32 v35, 0xbfb8aa3b, v31
	v_exp_f32_e32 v34, v34
	v_exp_f32_e32 v35, v35
	v_pk_fma_f32 v[26:27], v[26:27], v[44:45], v[38:39] op_sel_hi:[1,0,1]
	v_pk_fma_f32 v[28:29], v[28:29], v[44:45], v[40:41] op_sel_hi:[1,0,1]
	v_add_f32_e32 v34, 1.0, v34
	v_add_f32_e32 v35, 1.0, v35
	v_rcp_f32_e32 v34, v34
	v_rcp_f32_e32 v35, v35
	s_nop 0
	v_pk_mul_f32 v[30:31], v[30:31], v[34:35]
	s_nop 0
	v_pk_mul_f32 v[26:27], v[26:27], v[30:31]
	v_pk_fma_f32 v[30:31], v[32:33], v[44:45], v[36:37] op_sel_hi:[1,0,1]
	v_cvt_pk_bf16_f32 v26, v26, v27
	v_mul_f32_e32 v32, 0xbfb8aa3b, v30
	v_mul_f32_e32 v33, 0xbfb8aa3b, v31
	v_exp_f32_e32 v32, v32
	v_exp_f32_e32 v33, v33
	v_lshl_add_u64 v[34:35], v[42:43], 0, v[122:123]
	v_add_f32_e32 v32, 1.0, v32
	v_add_f32_e32 v33, 1.0, v33
	v_rcp_f32_e32 v32, v32
	v_rcp_f32_e32 v33, v33
	s_nop 0
	v_pk_mul_f32 v[30:31], v[30:31], v[32:33]
	s_nop 0
	v_pk_mul_f32 v[28:29], v[28:29], v[30:31]
	s_nop 0
	v_cvt_pk_bf16_f32 v27, v28, v29
	global_store_dwordx2 v[34:35], v[26:27], off
	ds_read_b128 v[26:29], v147 offset:1536
	ds_read_b128 v[30:33], v147 offset:1600
	s_waitcnt lgkmcnt(0)
	v_pk_fma_f32 v[22:23], v[22:23], v[44:45], v[26:27] op_sel_hi:[1,0,1]
	s_nop 0
	v_mul_f32_e32 v26, 0xbfb8aa3b, v22
	v_mul_f32_e32 v27, 0xbfb8aa3b, v23
	v_exp_f32_e32 v26, v26
	v_exp_f32_e32 v27, v27
	v_pk_fma_f32 v[18:19], v[18:19], v[44:45], v[30:31] op_sel_hi:[1,0,1]
	v_pk_fma_f32 v[20:21], v[20:21], v[44:45], v[32:33] op_sel_hi:[1,0,1]
	v_add_f32_e32 v26, 1.0, v26
	v_add_f32_e32 v27, 1.0, v27
	v_rcp_f32_e32 v26, v26
	v_rcp_f32_e32 v27, v27
	s_nop 0
	v_pk_mul_f32 v[22:23], v[22:23], v[26:27]
	s_nop 0
	v_pk_mul_f32 v[18:19], v[18:19], v[22:23]
	v_pk_fma_f32 v[22:23], v[24:25], v[44:45], v[28:29] op_sel_hi:[1,0,1]
	v_cvt_pk_bf16_f32 v18, v18, v19
	v_mul_f32_e32 v24, 0xbfb8aa3b, v22
	v_mul_f32_e32 v25, 0xbfb8aa3b, v23
	v_exp_f32_e32 v24, v24
	v_exp_f32_e32 v25, v25
	v_add_f32_e32 v24, 1.0, v24
	v_add_f32_e32 v25, 1.0, v25
	v_rcp_f32_e32 v24, v24
	v_rcp_f32_e32 v25, v25
	s_nop 0
	v_pk_mul_f32 v[22:23], v[22:23], v[24:25]
	s_nop 0
	v_pk_mul_f32 v[20:21], v[20:21], v[22:23]
	s_nop 0
	v_cvt_pk_bf16_f32 v19, v20, v21
	global_store_dwordx2 v[34:35], v[18:19], off offset:128
	v_add_u32_e32 v18, 0xb0, v136
	v_add_u32_e32 v18, s16, v18
	v_mad_i64_i32 v[26:27], s[16:17], v18, s46, v[132:133]
	ds_read_b32 v18, v148 offset:704
	s_mov_b64 s[16:17], 0
	s_waitcnt lgkmcnt(0)
	v_fmamk_f32 v18, v18, 0x3a800000, v206
	v_cmp_gt_f32_e32 vcc, s35, v18
	v_mul_f32_e32 v19, 0x4b800000, v18
	s_nop 0
	v_cndmask_b32_e32 v18, v18, v19, vcc
	v_rsq_f32_e32 v18, v18
	s_nop 0
	v_mul_f32_e32 v19, 0x45800000, v18
	v_cndmask_b32_e32 v28, v18, v19, vcc
	ds_read_b128 v[18:21], v147 offset:1024
	ds_read_b128 v[22:25], v147 offset:1088
	s_waitcnt lgkmcnt(0)
	v_pk_fma_f32 v[14:15], v[14:15], v[28:29], v[18:19] op_sel_hi:[1,0,1]
	s_nop 0
	v_mul_f32_e32 v18, 0xbfb8aa3b, v14
	v_mul_f32_e32 v19, 0xbfb8aa3b, v15
	v_exp_f32_e32 v18, v18
	v_exp_f32_e32 v19, v19
	v_pk_fma_f32 v[10:11], v[10:11], v[28:29], v[22:23] op_sel_hi:[1,0,1]
	v_pk_fma_f32 v[12:13], v[12:13], v[28:29], v[24:25] op_sel_hi:[1,0,1]
	v_add_f32_e32 v18, 1.0, v18
	v_add_f32_e32 v19, 1.0, v19
	v_rcp_f32_e32 v18, v18
	v_rcp_f32_e32 v19, v19
	s_nop 0
	v_pk_mul_f32 v[14:15], v[14:15], v[18:19]
	s_nop 0
	v_pk_mul_f32 v[10:11], v[10:11], v[14:15]
	v_pk_fma_f32 v[14:15], v[16:17], v[28:29], v[20:21] op_sel_hi:[1,0,1]
	v_cvt_pk_bf16_f32 v10, v10, v11
	v_mul_f32_e32 v16, 0xbfb8aa3b, v14
	v_mul_f32_e32 v17, 0xbfb8aa3b, v15
	v_exp_f32_e32 v16, v16
	v_exp_f32_e32 v17, v17
	v_lshl_add_u64 v[18:19], v[26:27], 0, v[122:123]
	v_add_f32_e32 v16, 1.0, v16
	v_add_f32_e32 v17, 1.0, v17
	v_rcp_f32_e32 v16, v16
	v_rcp_f32_e32 v17, v17
	s_nop 0
	v_pk_mul_f32 v[14:15], v[14:15], v[16:17]
	s_nop 0
	v_pk_mul_f32 v[12:13], v[12:13], v[14:15]
	s_nop 0
	v_cvt_pk_bf16_f32 v11, v12, v13
	global_store_dwordx2 v[18:19], v[10:11], off
	ds_read_b128 v[10:13], v147 offset:1536
	ds_read_b128 v[14:17], v147 offset:1600
	s_waitcnt lgkmcnt(0)
	v_pk_fma_f32 v[6:7], v[6:7], v[28:29], v[10:11] op_sel_hi:[1,0,1]
	s_nop 0
	v_mul_f32_e32 v10, 0xbfb8aa3b, v6
	v_mul_f32_e32 v11, 0xbfb8aa3b, v7
	v_exp_f32_e32 v10, v10
	v_exp_f32_e32 v11, v11
	v_pk_fma_f32 v[2:3], v[2:3], v[28:29], v[14:15] op_sel_hi:[1,0,1]
	v_pk_fma_f32 v[4:5], v[4:5], v[28:29], v[16:17] op_sel_hi:[1,0,1]
	v_add_f32_e32 v10, 1.0, v10
	v_add_f32_e32 v11, 1.0, v11
	v_rcp_f32_e32 v10, v10
	v_rcp_f32_e32 v11, v11
	s_nop 0
	v_pk_mul_f32 v[6:7], v[6:7], v[10:11]
	s_nop 0
	v_pk_mul_f32 v[2:3], v[2:3], v[6:7]
	v_pk_fma_f32 v[6:7], v[8:9], v[28:29], v[12:13] op_sel_hi:[1,0,1]
	v_cvt_pk_bf16_f32 v2, v2, v3
	v_mul_f32_e32 v8, 0xbfb8aa3b, v6
	v_mul_f32_e32 v9, 0xbfb8aa3b, v7
	v_exp_f32_e32 v8, v8
	v_exp_f32_e32 v9, v9
	v_add_f32_e32 v8, 1.0, v8
	v_add_f32_e32 v9, 1.0, v9
	v_rcp_f32_e32 v8, v8
	v_rcp_f32_e32 v9, v9
	s_nop 0
	v_pk_mul_f32 v[6:7], v[6:7], v[8:9]
	s_nop 0
	v_pk_mul_f32 v[4:5], v[4:5], v[6:7]
	s_nop 0
	v_cvt_pk_bf16_f32 v3, v4, v5
	global_store_dwordx2 v[18:19], v[2:3], off offset:128

.LBB0_1557:
	s_andn2_saveexec_b64 s[20:21], s[20:21]
	v_add_u32_e32 v2, s16, v134
	v_ashrrev_i32_e32 v3, 31, v2
	v_lshl_add_u64 v[2:3], v[2:3], 2, s[12:13]
	s_or_b64 exec, exec, s[20:21]
	global_load_dword v2, v[2:3], off
	s_lshl_b32 s17, s56, 12
	s_and_b32 s17, s17, 0x1000
	s_add_i32 s59, s17, 0x400
	s_ashr_i32 s19, s18, 31
	s_add_i32 s59, s59, 0x20000
	s_lshl_b64 s[20:21], s[18:19], 11
	s_add_u32 s26, s44, s20
	v_add_u32_e32 v132, s33, v135
	v_lshl_add_u32 v3, v134, 2, s59
	s_addc_u32 s27, s45, s21
	v_readfirstlane_b32 s17, v132
	v_add_u32_e32 v133, 0x2000, v132
	s_mov_b32 m0, s17
	v_readfirstlane_b32 s17, v133
	v_add_u32_e32 v147, 0x400, v135
	v_add_u32_e32 v148, 0x2000, v147
	v_add_u32_e32 v149, s52, v135
	v_add_u32_e32 v150, 0x2000, v149
	v_add_u32_e32 v151, 0x4000, v147
	v_add_u32_e32 v152, 0x6000, v147
	s_waitcnt vmcnt(0) lgkmcnt(0)
	ds_write_b32 v3, v2
	v_lshl_add_u64 v[2:3], s[26:27], 0, v[0:1]
	s_waitcnt lgkmcnt(0)
	s_barrier
	global_load_lds_dwordx4 v[2:3], off
	s_mov_b32 m0, s17
	s_ashr_i32 s17, s16, 31
	s_lshl_b64 s[22:23], s[16:17], 11
	s_add_u32 s28, s42, s22
	s_addc_u32 s29, s43, s23
	s_or_b32 s24, s18, 0x80
	s_ashr_i32 s25, s24, 31
	s_lshl_b64 s[24:25], s[24:25], 11
	s_add_u32 s30, s44, s24
	v_lshl_add_u64 v[2:3], s[26:27], 0, v[130:131]
	v_readfirstlane_b32 s17, v147
	s_addc_u32 s31, s45, s25
	s_or_b32 s24, s16, 0x80
	global_load_lds_dwordx4 v[2:3], off
	v_lshl_add_u64 v[2:3], s[28:29], 0, v[0:1]
	s_mov_b32 m0, s17
	v_readfirstlane_b32 s17, v148
	s_ashr_i32 s25, s24, 31
	global_load_lds_dwordx4 v[2:3], off
	v_lshl_add_u64 v[2:3], s[28:29], 0, v[130:131]
	s_mov_b32 m0, s17
	v_readfirstlane_b32 s17, v149
	s_lshl_b64 s[24:25], s[24:25], 11
	global_load_lds_dwordx4 v[2:3], off
	v_lshl_add_u64 v[2:3], s[30:31], 0, v[0:1]
	s_mov_b32 m0, s17
	v_readfirstlane_b32 s17, v150
	s_add_u32 s24, s42, s24
	global_load_lds_dwordx4 v[2:3], off
	v_lshl_add_u64 v[2:3], s[30:31], 0, v[130:131]
	s_mov_b32 m0, s17
	s_addc_u32 s25, s43, s25
	v_readfirstlane_b32 s17, v151
	global_load_lds_dwordx4 v[2:3], off
	v_lshl_add_u64 v[2:3], s[24:25], 0, v[0:1]
	s_mov_b32 m0, s17
	v_readfirstlane_b32 s17, v152
	global_load_lds_dwordx4 v[2:3], off
	v_lshl_add_u64 v[2:3], s[24:25], 0, v[130:131]
	s_mov_b32 m0, s17
	s_nop 0
	global_load_lds_dwordx4 v[2:3], off
	s_and_saveexec_b64 s[40:41], s[2:3]
	s_cbranch_execz .LBB0_1561
	s_barrier

.LBB0_1634:
	s_mul_hi_i32 s10, s56, 0x78787879
	s_lshr_b32 s11, s10, 31
	s_ashr_i32 s10, s10, 11
	s_add_i32 s10, s10, s11
	s_mul_i32 s11, s10, 0xffffef00
	s_add_i32 s11, s11, s56
	s_cmpk_gt_i32 s11, 0xff
	s_waitcnt lgkmcnt(0)
	v_add_u32_sdwa v2, s24, v205 dst_sel:DWORD dst_unused:UNUSED_PAD src0_sel:DWORD src1_sel:BYTE_0
	s_cselect_b32 s25, s10, 8
	v_ashrrev_i32_e32 v3, 31, v2
	s_and_saveexec_b64 s[10:11], s[0:1]
	s_xor_b64 s[10:11], exec, s[10:11]
	s_cbranch_execz .LBB0_1636
	s_add_i32 s26, s25, s55
	s_mul_hi_i32 s27, s26, 0x6000
	s_mulk_i32 s26, 0x6000
	s_add_u32 s26, s12, s26
	s_addc_u32 s27, s13, s27
	v_lshlrev_b64 v[2:3], 2, v[2:3]
	v_lshl_add_u64 v[4:5], s[16:17], 0, v[2:3]
	v_lshl_add_u64 v[2:3], s[26:27], 0, v[2:3]
	v_add_co_u32_e32 v2, vcc, 0x1000, v2
	global_load_dword v0, v[4:5], off
	s_nop 0
	v_addc_co_u32_e32 v3, vcc, 0, v3, vcc
	global_load_dword v2, v[2:3], off
	s_waitcnt vmcnt(0) lgkmcnt(0)
	v_add_f32_e32 v2, 1.0, v2
	v_mul_f32_e32 v0, v0, v2
.LBB0_1636:
	s_andn2_saveexec_b64 s[10:11], s[10:11]
	s_cbranch_execz .LBB0_1638
	v_readlane_b32 s26, v254, 44
	s_add_i32 s25, s25, s26
	s_mul_hi_i32 s27, s25, 0x6000
	s_mulk_i32 s25, 0x6000
	s_add_u32 s26, s12, s25
	s_addc_u32 s27, s13, s27
	v_lshl_add_u64 v[2:3], v[2:3], 2, s[26:27]
	v_add_co_u32_e32 v2, vcc, 0x5000, v2
	s_nop 1
	v_addc_co_u32_e32 v3, vcc, 0, v3, vcc
	global_load_dword v0, v[2:3], off

.LBB0_1656:
	s_or_b64 exec, exec, s[8:9]
	v_add_u32_e32 v150, s56, v229
	v_mul_hi_i32 v0, v150, s61
	v_lshrrev_b32_e32 v2, 31, v0
	v_ashrrev_i32_e32 v0, 11, v0
	v_add_u32_e32 v0, v0, v2
	v_mad_i32_i24 v3, v0, s48, v150
	v_cmp_lt_i32_e32 vcc, s49, v3
	s_and_saveexec_b64 s[8:9], vcc
	s_xor_b64 s[8:9], exec, s[8:9]
	v_lshlrev_b32_e32 v0, 12, v0
	s_movk_i32 s26, 0xff00
	v_add3_u32 v2, v0, v3, s26
	s_or_saveexec_b64 s[8:9], s[8:9]
	s_waitcnt lgkmcnt(0)
	v_mov_b64_e32 v[132:133], s[14:15]
	s_xor_b64 exec, exec, s[8:9]
	v_lshl_add_u32 v2, v0, 8, v3
	v_mov_b64_e32 v[132:133], s[18:19]
	s_or_b64 exec, exec, s[8:9]
	v_ashrrev_i32_e32 v3, 31, v2
	v_lshlrev_b64 v[2:3], 12, v[2:3]
	v_lshl_add_u64 v[2:3], v[132:133], 0, v[2:3]
	v_lshl_add_u64 v[164:165], s[24:25], 2, v[2:3]
	v_lshlrev_b32_e32 v0, 2, v200
	v_ashrrev_i32_e32 v151, 31, v150
	v_lshl_add_u64 v[2:3], v[164:165], 0, v[0:1]
	v_lshlrev_b32_e32 v152, 2, v202
	v_mov_b32_e32 v153, v1
	v_lshlrev_b32_e32 v148, 2, v204
	v_lshlrev_b64 v[144:145], 11, v[150:151]
	v_lshl_add_u64 v[160:161], v[2:3], 0, v[152:153]
	v_add_u32_e32 v158, s58, v148
	s_waitcnt vmcnt(0)
	global_load_dwordx4 v[140:143], v[160:161], off offset:64
	global_load_dwordx4 v[136:139], v[160:161], off offset:512
	global_load_dwordx4 v[132:135], v[160:161], off offset:576
	v_lshl_add_u64 v[166:167], s[20:21], 0, v[144:145]
	ds_read_b128 v[154:157], v158 offset:1024
	ds_read_b128 v[144:147], v158 offset:2048
	global_load_dwordx4 v[160:163], v[160:161], off
	v_add_u32_e32 v2, s24, v204
	v_ashrrev_i32_e32 v3, 31, v2
	v_mov_b32_e32 v149, v1
	v_cndmask_b32_e64 v153, 0, 1, s[92:93]
	v_cmp_ne_u32_e64 s[8:9], 1, v153
	s_andn2_b64 vcc, exec, s[92:93]
	s_waitcnt vmcnt(0) lgkmcnt(0)
	v_pk_fma_f32 v[128:129], v[128:129], v[154:155], v[160:161]
	v_pk_fma_f32 v[130:131], v[130:131], v[156:157], v[162:163]
	v_lshl_add_u64 v[154:155], v[164:165], 0, v[148:149]
	v_mov_b32_e32 v149, 0
	v_lshl_add_u64 v[156:157], v[2:3], 1, v[166:167]
	global_store_dwordx4 v[154:155], v[128:131], off
	s_cbranch_vccnz .LBB0_1662
	v_pk_mul_f32 v[160:161], v[128:129], v[128:129]
	v_pk_mul_f32 v[162:163], v[130:131], v[130:131]
	v_add_f32_e32 v149, v160, v161
	v_add_f32_e32 v149, v162, v149
	v_pk_mul_f32 v[128:129], v[144:145], v[128:129]
	v_pk_mul_f32 v[130:131], v[146:147], v[130:131]
	v_add_f32_e32 v149, v163, v149
	v_cvt_pk_bf16_f32 v128, v128, v129
	v_cvt_pk_bf16_f32 v129, v130, v131
	global_store_dwordx2 v[156:157], v[128:129], off
.LBB0_1662:
	ds_read_b128 v[144:147], v158 offset:1088
	ds_read_b128 v[128:131], v158 offset:2112
	s_and_b64 vcc, exec, s[8:9]
	s_waitcnt lgkmcnt(0)
	v_pk_fma_f32 v[124:125], v[124:125], v[144:145], v[140:141]
	v_pk_fma_f32 v[126:127], v[126:127], v[146:147], v[142:143]
	global_store_dwordx4 v[154:155], v[124:127], off offset:64
	s_cbranch_vccnz .LBB0_1664
	v_pk_mul_f32 v[140:141], v[124:125], v[124:125]
	v_pk_mul_f32 v[142:143], v[126:127], v[126:127]
	v_add_f32_e32 v140, v140, v141
	v_add_f32_e32 v140, v142, v140
	v_add_f32_e32 v140, v143, v140
	v_pk_mul_f32 v[124:125], v[128:129], v[124:125]
	v_pk_mul_f32 v[126:127], v[130:131], v[126:127]
	v_add_f32_e32 v149, v149, v140
	v_cvt_pk_bf16_f32 v124, v124, v125
	v_cvt_pk_bf16_f32 v125, v126, v127
	global_store_dwordx2 v[156:157], v[124:125], off offset:32
.LBB0_1664:
	ds_read_b128 v[128:131], v158 offset:1536
	ds_read_b128 v[124:127], v158 offset:2560
	s_and_b64 vcc, exec, s[8:9]
	s_waitcnt lgkmcnt(0)
	v_pk_fma_f32 v[120:121], v[120:121], v[128:129], v[136:137]
	v_pk_fma_f32 v[122:123], v[122:123], v[130:131], v[138:139]
	global_store_dwordx4 v[154:155], v[120:123], off offset:512
	s_cbranch_vccnz .LBB0_1666
	v_pk_mul_f32 v[128:129], v[120:121], v[120:121]
	v_pk_mul_f32 v[130:131], v[122:123], v[122:123]
	v_add_f32_e32 v128, v128, v129
	v_add_f32_e32 v128, v130, v128
	v_add_f32_e32 v128, v131, v128
	v_pk_mul_f32 v[120:121], v[124:125], v[120:121]
	v_pk_mul_f32 v[122:123], v[126:127], v[122:123]
	v_add_f32_e32 v149, v149, v128
	v_cvt_pk_bf16_f32 v120, v120, v121
	v_cvt_pk_bf16_f32 v121, v122, v123
	global_store_dwordx2 v[156:157], v[120:121], off offset:256
.LBB0_1666:
	ds_read_b128 v[124:127], v158 offset:1600
	ds_read_b128 v[120:123], v158 offset:2624
	s_and_b64 vcc, exec, s[8:9]
	s_waitcnt lgkmcnt(0)
	v_pk_fma_f32 v[116:117], v[116:117], v[124:125], v[132:133]
	v_pk_fma_f32 v[118:119], v[118:119], v[126:127], v[134:135]
	global_store_dwordx4 v[154:155], v[116:119], off offset:576
	s_cbranch_vccnz .LBB0_1670
	v_pk_mul_f32 v[124:125], v[116:117], v[116:117]
	v_pk_mul_f32 v[126:127], v[118:119], v[118:119]
	v_add_f32_e32 v124, v124, v125
	v_add_f32_e32 v124, v126, v124
	v_and_b32_e32 v126, 64, v208
	v_xor_b32_e32 v125, 16, v208
	v_add_u32_e32 v126, 64, v126
	v_cmp_lt_i32_e32 vcc, v125, v126
	v_add_f32_e32 v124, v127, v124
	v_add_f32_e32 v124, v149, v124
	v_cndmask_b32_e32 v125, v208, v125, vcc
	v_lshlrev_b32_e32 v125, 2, v125
	ds_bpermute_b32 v125, v125, v124
	v_pk_mul_f32 v[120:121], v[120:121], v[116:117]
	v_xor_b32_e32 v117, 32, v208
	v_cmp_lt_i32_e32 vcc, v117, v126
	v_pk_mul_f32 v[118:119], v[122:123], v[118:119]
	s_waitcnt lgkmcnt(0)
	v_add_f32_e32 v116, v124, v125
	v_cndmask_b32_e32 v117, v208, v117, vcc
	v_lshlrev_b32_e32 v117, 2, v117
	ds_bpermute_b32 v117, v117, v116
	v_cvt_pk_bf16_f32 v120, v120, v121
	v_cvt_pk_bf16_f32 v121, v118, v119
	global_store_dwordx2 v[156:157], v[120:121], off offset:288
	s_and_saveexec_b64 s[26:27], s[6:7]
	s_cbranch_execz .LBB0_1669
	s_waitcnt lgkmcnt(0)
	v_add_f32_e32 v118, v116, v117
	v_lshl_add_u64 v[116:117], v[150:151], 2, s[22:23]
	global_atomic_add_f32 v[116:117], v118, off

.LBB0_1670:
	v_add_u32_e32 v132, 16, v150
	v_mul_hi_i32 v116, v132, s61
	s_waitcnt lgkmcnt(0)
	v_lshrrev_b32_e32 v117, 31, v116
	v_ashrrev_i32_e32 v116, 11, v116
	v_add_u32_e32 v117, v116, v117
	v_mad_i32_i24 v120, v117, s48, v132
	v_cmp_lt_i32_e32 vcc, s49, v120
	s_and_saveexec_b64 s[26:27], vcc
	s_xor_b64 s[26:27], exec, s[26:27]
	v_lshlrev_b32_e32 v116, 12, v117
	s_movk_i32 s28, 0xff00
	v_add3_u32 v116, v116, v120, s28
	s_or_saveexec_b64 s[26:27], s[26:27]
	v_mov_b64_e32 v[118:119], s[14:15]
	s_xor_b64 exec, exec, s[26:27]
	v_lshl_add_u32 v116, v117, 8, v120
	v_mov_b64_e32 v[118:119], s[18:19]
	s_or_b64 exec, exec, s[26:27]
	v_ashrrev_i32_e32 v117, 31, v116
	v_lshlrev_b64 v[116:117], 12, v[116:117]
	v_lshl_add_u64 v[116:117], v[118:119], 0, v[116:117]
	v_lshl_add_u64 v[142:143], s[24:25], 2, v[116:117]
	v_ashrrev_i32_e32 v133, 31, v132
	v_lshl_add_u64 v[116:117], v[142:143], 0, v[0:1]
	v_mov_b32_e32 v153, v1
	v_lshlrev_b64 v[128:129], 11, v[132:133]
	v_lshl_add_u64 v[138:139], v[116:117], 0, v[152:153]
	global_load_dwordx4 v[124:127], v[138:139], off offset:64
	global_load_dwordx4 v[120:123], v[138:139], off offset:512
	global_load_dwordx4 v[116:119], v[138:139], off offset:576
	v_lshl_add_u64 v[144:145], s[20:21], 0, v[128:129]
	ds_read_b128 v[134:137], v158 offset:1024
	ds_read_b128 v[128:131], v158 offset:2048
	global_load_dwordx4 v[138:141], v[138:139], off
	v_mov_b32_e32 v149, v1
	s_and_b64 vcc, exec, s[8:9]
	s_waitcnt vmcnt(0) lgkmcnt(0)
	v_pk_fma_f32 v[112:113], v[112:113], v[134:135], v[138:139]
	v_pk_fma_f32 v[114:115], v[114:115], v[136:137], v[140:141]
	v_lshl_add_u64 v[134:135], v[142:143], 0, v[148:149]
	v_mov_b32_e32 v138, 0
	v_lshl_add_u64 v[136:137], v[2:3], 1, v[144:145]
	global_store_dwordx4 v[134:135], v[112:115], off
	s_cbranch_vccnz .LBB0_1676
	v_pk_mul_f32 v[138:139], v[112:113], v[112:113]
	v_pk_mul_f32 v[140:141], v[114:115], v[114:115]
	v_add_f32_e32 v138, v138, v139
	v_add_f32_e32 v138, v140, v138
	v_pk_mul_f32 v[112:113], v[128:129], v[112:113]
	v_pk_mul_f32 v[114:115], v[130:131], v[114:115]
	v_add_f32_e32 v138, v141, v138
	v_cvt_pk_bf16_f32 v112, v112, v113
	v_cvt_pk_bf16_f32 v113, v114, v115
	global_store_dwordx2 v[136:137], v[112:113], off
.LBB0_1676:
	ds_read_b128 v[128:131], v158 offset:1088
	ds_read_b128 v[112:115], v158 offset:2112
	s_and_b64 vcc, exec, s[8:9]
	s_waitcnt lgkmcnt(0)
	v_pk_fma_f32 v[108:109], v[108:109], v[128:129], v[124:125]
	v_pk_fma_f32 v[110:111], v[110:111], v[130:131], v[126:127]
	global_store_dwordx4 v[134:135], v[108:111], off offset:64
	s_cbranch_vccnz .LBB0_1678
	v_pk_mul_f32 v[124:125], v[108:109], v[108:109]
	v_pk_mul_f32 v[126:127], v[110:111], v[110:111]
	v_add_f32_e32 v124, v124, v125
	v_add_f32_e32 v124, v126, v124
	v_add_f32_e32 v124, v127, v124
	v_pk_mul_f32 v[108:109], v[112:113], v[108:109]
	v_pk_mul_f32 v[110:111], v[114:115], v[110:111]
	v_add_f32_e32 v138, v138, v124
	v_cvt_pk_bf16_f32 v108, v108, v109
	v_cvt_pk_bf16_f32 v109, v110, v111
	global_store_dwordx2 v[136:137], v[108:109], off offset:32
.LBB0_1678:
	ds_read_b128 v[112:115], v158 offset:1536
	ds_read_b128 v[108:111], v158 offset:2560
	s_and_b64 vcc, exec, s[8:9]
	s_waitcnt lgkmcnt(0)
	v_pk_fma_f32 v[104:105], v[104:105], v[112:113], v[120:121]
	v_pk_fma_f32 v[106:107], v[106:107], v[114:115], v[122:123]
	global_store_dwordx4 v[134:135], v[104:107], off offset:512
	s_cbranch_vccnz .LBB0_1680
	v_pk_mul_f32 v[112:113], v[104:105], v[104:105]
	v_pk_mul_f32 v[114:115], v[106:107], v[106:107]
	v_add_f32_e32 v112, v112, v113
	v_add_f32_e32 v112, v114, v112
	v_add_f32_e32 v112, v115, v112
	v_pk_mul_f32 v[104:105], v[108:109], v[104:105]
	v_pk_mul_f32 v[106:107], v[110:111], v[106:107]
	v_add_f32_e32 v138, v138, v112
	v_cvt_pk_bf16_f32 v104, v104, v105
	v_cvt_pk_bf16_f32 v105, v106, v107
	global_store_dwordx2 v[136:137], v[104:105], off offset:256
.LBB0_1680:
	ds_read_b128 v[108:111], v158 offset:1600
	ds_read_b128 v[104:107], v158 offset:2624
	s_and_b64 vcc, exec, s[8:9]
	s_waitcnt lgkmcnt(0)
	v_pk_fma_f32 v[100:101], v[100:101], v[108:109], v[116:117]
	v_pk_fma_f32 v[102:103], v[102:103], v[110:111], v[118:119]
	global_store_dwordx4 v[134:135], v[100:103], off offset:576
	s_cbranch_vccnz .LBB0_1684
	v_pk_mul_f32 v[108:109], v[100:101], v[100:101]
	v_pk_mul_f32 v[110:111], v[102:103], v[102:103]
	v_add_f32_e32 v108, v108, v109
	v_add_f32_e32 v108, v110, v108
	v_and_b32_e32 v110, 64, v208
	v_xor_b32_e32 v109, 16, v208
	v_add_u32_e32 v110, 64, v110
	v_cmp_lt_i32_e32 vcc, v109, v110
	v_add_f32_e32 v108, v111, v108
	v_add_f32_e32 v108, v138, v108
	v_cndmask_b32_e32 v109, v208, v109, vcc
	v_lshlrev_b32_e32 v109, 2, v109
	ds_bpermute_b32 v109, v109, v108
	v_pk_mul_f32 v[104:105], v[104:105], v[100:101]
	v_xor_b32_e32 v101, 32, v208
	v_cmp_lt_i32_e32 vcc, v101, v110
	v_pk_mul_f32 v[102:103], v[106:107], v[102:103]
	s_waitcnt lgkmcnt(0)
	v_add_f32_e32 v100, v108, v109
	v_cndmask_b32_e32 v101, v208, v101, vcc
	v_lshlrev_b32_e32 v101, 2, v101
	ds_bpermute_b32 v101, v101, v100
	v_cvt_pk_bf16_f32 v104, v104, v105
	v_cvt_pk_bf16_f32 v105, v102, v103
	global_store_dwordx2 v[136:137], v[104:105], off offset:288
	s_and_saveexec_b64 s[26:27], s[6:7]
	s_cbranch_execz .LBB0_1683
	s_waitcnt lgkmcnt(0)
	v_add_f32_e32 v102, v100, v101
	v_lshl_add_u64 v[100:101], v[132:133], 2, s[22:23]
	global_atomic_add_f32 v[100:101], v102, off

.LBB0_1684:
	v_add_u32_e32 v116, 32, v150
	v_mul_hi_i32 v100, v116, s61
	s_waitcnt lgkmcnt(0)
	v_lshrrev_b32_e32 v101, 31, v100
	v_ashrrev_i32_e32 v100, 11, v100
	v_add_u32_e32 v101, v100, v101
	v_mad_i32_i24 v104, v101, s48, v116
	v_cmp_lt_i32_e32 vcc, s49, v104
	s_and_saveexec_b64 s[26:27], vcc
	s_xor_b64 s[26:27], exec, s[26:27]
	v_lshlrev_b32_e32 v100, 12, v101
	s_movk_i32 s28, 0xff00
	v_add3_u32 v100, v100, v104, s28
	s_or_saveexec_b64 s[26:27], s[26:27]
	v_mov_b64_e32 v[102:103], s[14:15]
	s_xor_b64 exec, exec, s[26:27]
	v_lshl_add_u32 v100, v101, 8, v104
	v_mov_b64_e32 v[102:103], s[18:19]
	s_or_b64 exec, exec, s[26:27]
	v_ashrrev_i32_e32 v101, 31, v100
	v_lshlrev_b64 v[100:101], 12, v[100:101]
	v_lshl_add_u64 v[100:101], v[102:103], 0, v[100:101]
	v_lshl_add_u64 v[126:127], s[24:25], 2, v[100:101]
	v_ashrrev_i32_e32 v117, 31, v116
	v_lshl_add_u64 v[100:101], v[126:127], 0, v[0:1]
	v_mov_b32_e32 v153, v1
	v_lshlrev_b64 v[112:113], 11, v[116:117]
	v_lshl_add_u64 v[122:123], v[100:101], 0, v[152:153]
	global_load_dwordx4 v[108:111], v[122:123], off offset:64
	global_load_dwordx4 v[104:107], v[122:123], off offset:512
	global_load_dwordx4 v[100:103], v[122:123], off offset:576
	v_lshl_add_u64 v[128:129], s[20:21], 0, v[112:113]
	ds_read_b128 v[118:121], v158 offset:1024
	ds_read_b128 v[112:115], v158 offset:2048
	global_load_dwordx4 v[122:125], v[122:123], off
	v_mov_b32_e32 v149, v1
	s_and_b64 vcc, exec, s[8:9]
	s_waitcnt vmcnt(0) lgkmcnt(0)
	v_pk_fma_f32 v[96:97], v[96:97], v[118:119], v[122:123]
	v_pk_fma_f32 v[98:99], v[98:99], v[120:121], v[124:125]
	v_lshl_add_u64 v[118:119], v[126:127], 0, v[148:149]
	v_mov_b32_e32 v122, 0
	v_lshl_add_u64 v[120:121], v[2:3], 1, v[128:129]
	global_store_dwordx4 v[118:119], v[96:99], off
	s_cbranch_vccnz .LBB0_1690
	v_pk_mul_f32 v[122:123], v[96:97], v[96:97]
	v_pk_mul_f32 v[124:125], v[98:99], v[98:99]
	v_add_f32_e32 v122, v122, v123
	v_add_f32_e32 v122, v124, v122
	v_pk_mul_f32 v[96:97], v[112:113], v[96:97]
	v_pk_mul_f32 v[98:99], v[114:115], v[98:99]
	v_add_f32_e32 v122, v125, v122
	v_cvt_pk_bf16_f32 v96, v96, v97
	v_cvt_pk_bf16_f32 v97, v98, v99
	global_store_dwordx2 v[120:121], v[96:97], off
.LBB0_1690:
	ds_read_b128 v[112:115], v158 offset:1088
	ds_read_b128 v[96:99], v158 offset:2112
	s_and_b64 vcc, exec, s[8:9]
	s_waitcnt lgkmcnt(0)
	v_pk_fma_f32 v[92:93], v[92:93], v[112:113], v[108:109]
	v_pk_fma_f32 v[94:95], v[94:95], v[114:115], v[110:111]
	global_store_dwordx4 v[118:119], v[92:95], off offset:64
	s_cbranch_vccnz .LBB0_1692
	v_pk_mul_f32 v[108:109], v[92:93], v[92:93]
	v_pk_mul_f32 v[110:111], v[94:95], v[94:95]
	v_add_f32_e32 v108, v108, v109
	v_add_f32_e32 v108, v110, v108
	v_add_f32_e32 v108, v111, v108
	v_pk_mul_f32 v[92:93], v[96:97], v[92:93]
	v_pk_mul_f32 v[94:95], v[98:99], v[94:95]
	v_add_f32_e32 v122, v122, v108
	v_cvt_pk_bf16_f32 v92, v92, v93
	v_cvt_pk_bf16_f32 v93, v94, v95
	global_store_dwordx2 v[120:121], v[92:93], off offset:32
.LBB0_1692:
	ds_read_b128 v[96:99], v158 offset:1536
	ds_read_b128 v[92:95], v158 offset:2560
	s_and_b64 vcc, exec, s[8:9]
	s_waitcnt lgkmcnt(0)
	v_pk_fma_f32 v[88:89], v[88:89], v[96:97], v[104:105]
	v_pk_fma_f32 v[90:91], v[90:91], v[98:99], v[106:107]
	global_store_dwordx4 v[118:119], v[88:91], off offset:512
	s_cbranch_vccnz .LBB0_1694
	v_pk_mul_f32 v[96:97], v[88:89], v[88:89]
	v_pk_mul_f32 v[98:99], v[90:91], v[90:91]
	v_add_f32_e32 v96, v96, v97
	v_add_f32_e32 v96, v98, v96
	v_add_f32_e32 v96, v99, v96
	v_pk_mul_f32 v[88:89], v[92:93], v[88:89]
	v_pk_mul_f32 v[90:91], v[94:95], v[90:91]
	v_add_f32_e32 v122, v122, v96
	v_cvt_pk_bf16_f32 v88, v88, v89
	v_cvt_pk_bf16_f32 v89, v90, v91
	global_store_dwordx2 v[120:121], v[88:89], off offset:256
.LBB0_1694:
	ds_read_b128 v[92:95], v158 offset:1600
	ds_read_b128 v[88:91], v158 offset:2624
	s_and_b64 vcc, exec, s[8:9]
	s_waitcnt lgkmcnt(0)
	v_pk_fma_f32 v[84:85], v[84:85], v[92:93], v[100:101]
	v_pk_fma_f32 v[86:87], v[86:87], v[94:95], v[102:103]
	global_store_dwordx4 v[118:119], v[84:87], off offset:576
	s_cbranch_vccnz .LBB0_1698
	v_pk_mul_f32 v[92:93], v[84:85], v[84:85]
	v_pk_mul_f32 v[94:95], v[86:87], v[86:87]
	v_add_f32_e32 v92, v92, v93
	v_add_f32_e32 v92, v94, v92
	v_and_b32_e32 v94, 64, v208
	v_xor_b32_e32 v93, 16, v208
	v_add_u32_e32 v94, 64, v94
	v_cmp_lt_i32_e32 vcc, v93, v94
	v_add_f32_e32 v92, v95, v92
	v_add_f32_e32 v92, v122, v92
	v_cndmask_b32_e32 v93, v208, v93, vcc
	v_lshlrev_b32_e32 v93, 2, v93
	ds_bpermute_b32 v93, v93, v92
	v_pk_mul_f32 v[88:89], v[88:89], v[84:85]
	v_xor_b32_e32 v85, 32, v208
	v_cmp_lt_i32_e32 vcc, v85, v94
	v_pk_mul_f32 v[86:87], v[90:91], v[86:87]
	s_waitcnt lgkmcnt(0)
	v_add_f32_e32 v84, v92, v93
	v_cndmask_b32_e32 v85, v208, v85, vcc
	v_lshlrev_b32_e32 v85, 2, v85
	ds_bpermute_b32 v85, v85, v84
	v_cvt_pk_bf16_f32 v88, v88, v89
	v_cvt_pk_bf16_f32 v89, v86, v87
	global_store_dwordx2 v[120:121], v[88:89], off offset:288
	s_and_saveexec_b64 s[26:27], s[6:7]
	s_cbranch_execz .LBB0_1697
	s_waitcnt lgkmcnt(0)
	v_add_f32_e32 v86, v84, v85
	v_lshl_add_u64 v[84:85], v[116:117], 2, s[22:23]
	global_atomic_add_f32 v[84:85], v86, off

.LBB0_1698:
	v_add_u32_e32 v100, 48, v150
	v_mul_hi_i32 v84, v100, s61
	s_waitcnt lgkmcnt(0)
	v_lshrrev_b32_e32 v85, 31, v84
	v_ashrrev_i32_e32 v84, 11, v84
	v_add_u32_e32 v85, v84, v85
	v_mad_i32_i24 v88, v85, s48, v100
	v_cmp_lt_i32_e32 vcc, s49, v88
	s_and_saveexec_b64 s[26:27], vcc
	s_xor_b64 s[26:27], exec, s[26:27]
	v_lshlrev_b32_e32 v84, 12, v85
	s_movk_i32 s28, 0xff00
	v_add3_u32 v84, v84, v88, s28
	s_or_saveexec_b64 s[26:27], s[26:27]
	v_mov_b64_e32 v[86:87], s[14:15]
	s_xor_b64 exec, exec, s[26:27]
	v_lshl_add_u32 v84, v85, 8, v88
	v_mov_b64_e32 v[86:87], s[18:19]
	s_or_b64 exec, exec, s[26:27]
	v_ashrrev_i32_e32 v85, 31, v84
	v_lshlrev_b64 v[84:85], 12, v[84:85]
	v_lshl_add_u64 v[84:85], v[86:87], 0, v[84:85]
	v_lshl_add_u64 v[110:111], s[24:25], 2, v[84:85]
	v_ashrrev_i32_e32 v101, 31, v100
	v_lshl_add_u64 v[84:85], v[110:111], 0, v[0:1]
	v_mov_b32_e32 v153, v1
	v_lshlrev_b64 v[96:97], 11, v[100:101]
	v_lshl_add_u64 v[106:107], v[84:85], 0, v[152:153]
	global_load_dwordx4 v[92:95], v[106:107], off offset:64
	global_load_dwordx4 v[88:91], v[106:107], off offset:512
	global_load_dwordx4 v[84:87], v[106:107], off offset:576
	v_lshl_add_u64 v[112:113], s[20:21], 0, v[96:97]
	ds_read_b128 v[102:105], v158 offset:1024
	ds_read_b128 v[96:99], v158 offset:2048
	global_load_dwordx4 v[106:109], v[106:107], off
	v_mov_b32_e32 v149, v1
	s_and_b64 vcc, exec, s[8:9]
	s_waitcnt vmcnt(0) lgkmcnt(0)
	v_pk_fma_f32 v[80:81], v[80:81], v[102:103], v[106:107]
	v_pk_fma_f32 v[82:83], v[82:83], v[104:105], v[108:109]
	v_lshl_add_u64 v[102:103], v[110:111], 0, v[148:149]
	v_mov_b32_e32 v106, 0
	v_lshl_add_u64 v[104:105], v[2:3], 1, v[112:113]
	global_store_dwordx4 v[102:103], v[80:83], off
	s_cbranch_vccnz .LBB0_1704
	v_pk_mul_f32 v[106:107], v[80:81], v[80:81]
	v_pk_mul_f32 v[108:109], v[82:83], v[82:83]
	v_add_f32_e32 v106, v106, v107
	v_add_f32_e32 v106, v108, v106
	v_pk_mul_f32 v[80:81], v[96:97], v[80:81]
	v_pk_mul_f32 v[82:83], v[98:99], v[82:83]
	v_add_f32_e32 v106, v109, v106
	v_cvt_pk_bf16_f32 v80, v80, v81
	v_cvt_pk_bf16_f32 v81, v82, v83
	global_store_dwordx2 v[104:105], v[80:81], off
.LBB0_1704:
	ds_read_b128 v[96:99], v158 offset:1088
	ds_read_b128 v[80:83], v158 offset:2112
	s_and_b64 vcc, exec, s[8:9]
	s_waitcnt lgkmcnt(0)
	v_pk_fma_f32 v[76:77], v[76:77], v[96:97], v[92:93]
	v_pk_fma_f32 v[78:79], v[78:79], v[98:99], v[94:95]
	global_store_dwordx4 v[102:103], v[76:79], off offset:64
	s_cbranch_vccnz .LBB0_1706
	v_pk_mul_f32 v[92:93], v[76:77], v[76:77]
	v_pk_mul_f32 v[94:95], v[78:79], v[78:79]
	v_add_f32_e32 v92, v92, v93
	v_add_f32_e32 v92, v94, v92
	v_add_f32_e32 v92, v95, v92
	v_pk_mul_f32 v[76:77], v[80:81], v[76:77]
	v_pk_mul_f32 v[78:79], v[82:83], v[78:79]
	v_add_f32_e32 v106, v106, v92
	v_cvt_pk_bf16_f32 v76, v76, v77
	v_cvt_pk_bf16_f32 v77, v78, v79
	global_store_dwordx2 v[104:105], v[76:77], off offset:32
.LBB0_1706:
	ds_read_b128 v[80:83], v158 offset:1536
	ds_read_b128 v[76:79], v158 offset:2560
	s_and_b64 vcc, exec, s[8:9]
	s_waitcnt lgkmcnt(0)
	v_pk_fma_f32 v[72:73], v[72:73], v[80:81], v[88:89]
	v_pk_fma_f32 v[74:75], v[74:75], v[82:83], v[90:91]
	global_store_dwordx4 v[102:103], v[72:75], off offset:512
	s_cbranch_vccnz .LBB0_1708
	v_pk_mul_f32 v[80:81], v[72:73], v[72:73]
	v_pk_mul_f32 v[82:83], v[74:75], v[74:75]
	v_add_f32_e32 v80, v80, v81
	v_add_f32_e32 v80, v82, v80
	v_add_f32_e32 v80, v83, v80
	v_pk_mul_f32 v[72:73], v[76:77], v[72:73]
	v_pk_mul_f32 v[74:75], v[78:79], v[74:75]
	v_add_f32_e32 v106, v106, v80
	v_cvt_pk_bf16_f32 v72, v72, v73
	v_cvt_pk_bf16_f32 v73, v74, v75
	global_store_dwordx2 v[104:105], v[72:73], off offset:256
.LBB0_1708:
	ds_read_b128 v[76:79], v158 offset:1600
	ds_read_b128 v[72:75], v158 offset:2624
	s_and_b64 vcc, exec, s[8:9]
	s_waitcnt lgkmcnt(0)
	v_pk_fma_f32 v[68:69], v[68:69], v[76:77], v[84:85]
	v_pk_fma_f32 v[70:71], v[70:71], v[78:79], v[86:87]
	global_store_dwordx4 v[102:103], v[68:71], off offset:576
	s_cbranch_vccnz .LBB0_1712
	v_pk_mul_f32 v[76:77], v[68:69], v[68:69]
	v_pk_mul_f32 v[78:79], v[70:71], v[70:71]
	v_add_f32_e32 v76, v76, v77
	v_add_f32_e32 v76, v78, v76
	v_and_b32_e32 v78, 64, v208
	v_xor_b32_e32 v77, 16, v208
	v_add_u32_e32 v78, 64, v78
	v_cmp_lt_i32_e32 vcc, v77, v78
	v_add_f32_e32 v76, v79, v76
	v_add_f32_e32 v76, v106, v76
	v_cndmask_b32_e32 v77, v208, v77, vcc
	v_lshlrev_b32_e32 v77, 2, v77
	ds_bpermute_b32 v77, v77, v76
	v_pk_mul_f32 v[72:73], v[72:73], v[68:69]
	v_xor_b32_e32 v69, 32, v208
	v_cmp_lt_i32_e32 vcc, v69, v78
	v_pk_mul_f32 v[70:71], v[74:75], v[70:71]
	s_waitcnt lgkmcnt(0)
	v_add_f32_e32 v68, v76, v77
	v_cndmask_b32_e32 v69, v208, v69, vcc
	v_lshlrev_b32_e32 v69, 2, v69
	ds_bpermute_b32 v69, v69, v68
	v_cvt_pk_bf16_f32 v72, v72, v73
	v_cvt_pk_bf16_f32 v73, v70, v71
	global_store_dwordx2 v[104:105], v[72:73], off offset:288
	s_and_saveexec_b64 s[26:27], s[6:7]
	s_cbranch_execz .LBB0_1711
	s_waitcnt lgkmcnt(0)
	v_add_f32_e32 v70, v68, v69
	v_lshl_add_u64 v[68:69], v[100:101], 2, s[22:23]
	global_atomic_add_f32 v[68:69], v70, off

.LBB0_1712:
	s_and_b64 vcc, exec, s[10:11]
	s_cbranch_vccnz .LBB0_1611
	v_add_u32_e32 v84, 0x80, v150
	v_mul_hi_i32 v68, v84, s61
	s_waitcnt lgkmcnt(0)
	v_lshrrev_b32_e32 v69, 31, v68
	v_ashrrev_i32_e32 v68, 11, v68
	v_add_u32_e32 v69, v68, v69
	v_mad_i32_i24 v72, v69, s48, v84
	v_cmp_lt_i32_e32 vcc, s49, v72
	s_and_saveexec_b64 s[10:11], vcc
	s_xor_b64 s[10:11], exec, s[10:11]
	v_lshlrev_b32_e32 v68, 12, v69
	s_movk_i32 s26, 0xff00
	v_add3_u32 v68, v68, v72, s26
	s_or_saveexec_b64 s[10:11], s[10:11]
	v_mov_b64_e32 v[70:71], s[14:15]
	s_xor_b64 exec, exec, s[10:11]
	v_lshl_add_u32 v68, v69, 8, v72
	v_mov_b64_e32 v[70:71], s[18:19]
	s_or_b64 exec, exec, s[10:11]
	v_ashrrev_i32_e32 v69, 31, v68
	v_lshlrev_b64 v[68:69], 12, v[68:69]
	v_lshl_add_u64 v[68:69], v[70:71], 0, v[68:69]
	v_lshl_add_u64 v[94:95], s[24:25], 2, v[68:69]
	v_ashrrev_i32_e32 v85, 31, v84
	v_lshl_add_u64 v[68:69], v[94:95], 0, v[0:1]
	v_mov_b32_e32 v153, v1
	v_lshlrev_b64 v[80:81], 11, v[84:85]
	v_lshl_add_u64 v[90:91], v[68:69], 0, v[152:153]
	global_load_dwordx4 v[76:79], v[90:91], off offset:64
	global_load_dwordx4 v[72:75], v[90:91], off offset:512
	global_load_dwordx4 v[68:71], v[90:91], off offset:576
	v_lshl_add_u64 v[96:97], s[20:21], 0, v[80:81]
	ds_read_b128 v[86:89], v158 offset:1024
	ds_read_b128 v[80:83], v158 offset:2048
	global_load_dwordx4 v[90:93], v[90:91], off
	v_mov_b32_e32 v149, v1
	s_and_b64 vcc, exec, s[8:9]
	s_waitcnt vmcnt(0) lgkmcnt(0)
	v_pk_fma_f32 v[64:65], v[64:65], v[86:87], v[90:91]
	v_pk_fma_f32 v[66:67], v[66:67], v[88:89], v[92:93]
	v_lshl_add_u64 v[86:87], v[94:95], 0, v[148:149]
	v_mov_b32_e32 v90, 0
	v_lshl_add_u64 v[88:89], v[2:3], 1, v[96:97]
	global_store_dwordx4 v[86:87], v[64:67], off
	s_cbranch_vccnz .LBB0_1719
	v_pk_mul_f32 v[90:91], v[64:65], v[64:65]
	v_pk_mul_f32 v[92:93], v[66:67], v[66:67]
	v_add_f32_e32 v90, v90, v91
	v_add_f32_e32 v90, v92, v90
	v_pk_mul_f32 v[64:65], v[80:81], v[64:65]
	v_pk_mul_f32 v[66:67], v[82:83], v[66:67]
	v_add_f32_e32 v90, v93, v90
	v_cvt_pk_bf16_f32 v64, v64, v65
	v_cvt_pk_bf16_f32 v65, v66, v67
	global_store_dwordx2 v[88:89], v[64:65], off
.LBB0_1719:
	ds_read_b128 v[80:83], v158 offset:1088
	ds_read_b128 v[64:67], v158 offset:2112
	s_and_b64 vcc, exec, s[8:9]
	s_waitcnt lgkmcnt(0)
	v_pk_fma_f32 v[60:61], v[60:61], v[80:81], v[76:77]
	v_pk_fma_f32 v[62:63], v[62:63], v[82:83], v[78:79]
	global_store_dwordx4 v[86:87], v[60:63], off offset:64
	s_cbranch_vccnz .LBB0_1721
	v_pk_mul_f32 v[76:77], v[60:61], v[60:61]
	v_pk_mul_f32 v[78:79], v[62:63], v[62:63]
	v_add_f32_e32 v76, v76, v77
	v_add_f32_e32 v76, v78, v76
	v_add_f32_e32 v76, v79, v76
	v_pk_mul_f32 v[60:61], v[64:65], v[60:61]
	v_pk_mul_f32 v[62:63], v[66:67], v[62:63]
	v_add_f32_e32 v90, v90, v76
	v_cvt_pk_bf16_f32 v60, v60, v61
	v_cvt_pk_bf16_f32 v61, v62, v63
	global_store_dwordx2 v[88:89], v[60:61], off offset:32
.LBB0_1721:
	ds_read_b128 v[64:67], v158 offset:1536
	ds_read_b128 v[60:63], v158 offset:2560
	s_and_b64 vcc, exec, s[8:9]
	s_waitcnt lgkmcnt(0)
	v_pk_fma_f32 v[56:57], v[56:57], v[64:65], v[72:73]
	v_pk_fma_f32 v[58:59], v[58:59], v[66:67], v[74:75]
	global_store_dwordx4 v[86:87], v[56:59], off offset:512
	s_cbranch_vccnz .LBB0_1723
	v_pk_mul_f32 v[64:65], v[56:57], v[56:57]
	v_pk_mul_f32 v[66:67], v[58:59], v[58:59]
	v_add_f32_e32 v64, v64, v65
	v_add_f32_e32 v64, v66, v64
	v_add_f32_e32 v64, v67, v64
	v_pk_mul_f32 v[56:57], v[60:61], v[56:57]
	v_pk_mul_f32 v[58:59], v[62:63], v[58:59]
	v_add_f32_e32 v90, v90, v64
	v_cvt_pk_bf16_f32 v56, v56, v57
	v_cvt_pk_bf16_f32 v57, v58, v59
	global_store_dwordx2 v[88:89], v[56:57], off offset:256
.LBB0_1723:
	ds_read_b128 v[60:63], v158 offset:1600
	ds_read_b128 v[56:59], v158 offset:2624
	s_and_b64 vcc, exec, s[8:9]
	s_waitcnt lgkmcnt(0)
	v_pk_fma_f32 v[52:53], v[52:53], v[60:61], v[68:69]
	v_pk_fma_f32 v[54:55], v[54:55], v[62:63], v[70:71]
	global_store_dwordx4 v[86:87], v[52:55], off offset:576
	s_cbranch_vccnz .LBB0_1727
	v_pk_mul_f32 v[60:61], v[52:53], v[52:53]
	v_pk_mul_f32 v[62:63], v[54:55], v[54:55]
	v_add_f32_e32 v60, v60, v61
	v_add_f32_e32 v60, v62, v60
	v_and_b32_e32 v62, 64, v208
	v_xor_b32_e32 v61, 16, v208
	v_add_u32_e32 v62, 64, v62
	v_cmp_lt_i32_e32 vcc, v61, v62
	v_add_f32_e32 v60, v63, v60
	v_add_f32_e32 v60, v90, v60
	v_cndmask_b32_e32 v61, v208, v61, vcc
	v_lshlrev_b32_e32 v61, 2, v61
	ds_bpermute_b32 v61, v61, v60
	v_pk_mul_f32 v[56:57], v[56:57], v[52:53]
	v_xor_b32_e32 v53, 32, v208
	v_cmp_lt_i32_e32 vcc, v53, v62
	v_pk_mul_f32 v[54:55], v[58:59], v[54:55]
	s_waitcnt lgkmcnt(0)
	v_add_f32_e32 v52, v60, v61
	v_cndmask_b32_e32 v53, v208, v53, vcc
	v_lshlrev_b32_e32 v53, 2, v53
	ds_bpermute_b32 v53, v53, v52
	v_cvt_pk_bf16_f32 v56, v56, v57
	v_cvt_pk_bf16_f32 v57, v54, v55
	global_store_dwordx2 v[88:89], v[56:57], off offset:288
	s_and_saveexec_b64 s[10:11], s[6:7]
	s_cbranch_execz .LBB0_1726
	s_waitcnt lgkmcnt(0)
	v_add_f32_e32 v54, v52, v53
	v_lshl_add_u64 v[52:53], v[84:85], 2, s[22:23]
	global_atomic_add_f32 v[52:53], v54, off

.LBB0_1727:
	v_add_u32_e32 v68, 0x90, v150
	v_mul_hi_i32 v52, v68, s61
	s_waitcnt lgkmcnt(0)
	v_lshrrev_b32_e32 v53, 31, v52
	v_ashrrev_i32_e32 v52, 11, v52
	v_add_u32_e32 v53, v52, v53
	v_mad_i32_i24 v56, v53, s48, v68
	v_cmp_lt_i32_e32 vcc, s49, v56
	s_and_saveexec_b64 s[10:11], vcc
	s_xor_b64 s[10:11], exec, s[10:11]
	v_lshlrev_b32_e32 v52, 12, v53
	s_movk_i32 s26, 0xff00
	v_add3_u32 v52, v52, v56, s26
	s_or_saveexec_b64 s[10:11], s[10:11]
	v_mov_b64_e32 v[54:55], s[14:15]
	s_xor_b64 exec, exec, s[10:11]
	v_lshl_add_u32 v52, v53, 8, v56
	v_mov_b64_e32 v[54:55], s[18:19]
	s_or_b64 exec, exec, s[10:11]
	v_ashrrev_i32_e32 v53, 31, v52
	v_lshlrev_b64 v[52:53], 12, v[52:53]
	v_lshl_add_u64 v[52:53], v[54:55], 0, v[52:53]
	v_lshl_add_u64 v[78:79], s[24:25], 2, v[52:53]
	v_ashrrev_i32_e32 v69, 31, v68
	v_lshl_add_u64 v[52:53], v[78:79], 0, v[0:1]
	v_mov_b32_e32 v153, v1
	v_lshlrev_b64 v[64:65], 11, v[68:69]
	v_lshl_add_u64 v[74:75], v[52:53], 0, v[152:153]
	global_load_dwordx4 v[60:63], v[74:75], off offset:64
	global_load_dwordx4 v[56:59], v[74:75], off offset:512
	global_load_dwordx4 v[52:55], v[74:75], off offset:576
	v_lshl_add_u64 v[80:81], s[20:21], 0, v[64:65]
	ds_read_b128 v[70:73], v158 offset:1024
	ds_read_b128 v[64:67], v158 offset:2048
	global_load_dwordx4 v[74:77], v[74:75], off
	v_mov_b32_e32 v149, v1
	s_and_b64 vcc, exec, s[8:9]
	s_waitcnt vmcnt(0) lgkmcnt(0)
	v_pk_fma_f32 v[48:49], v[48:49], v[70:71], v[74:75]
	v_pk_fma_f32 v[50:51], v[50:51], v[72:73], v[76:77]
	v_lshl_add_u64 v[70:71], v[78:79], 0, v[148:149]
	v_mov_b32_e32 v74, 0
	v_lshl_add_u64 v[72:73], v[2:3], 1, v[80:81]
	global_store_dwordx4 v[70:71], v[48:51], off
	s_cbranch_vccnz .LBB0_1733
	v_pk_mul_f32 v[74:75], v[48:49], v[48:49]
	v_pk_mul_f32 v[76:77], v[50:51], v[50:51]
	v_add_f32_e32 v74, v74, v75
	v_add_f32_e32 v74, v76, v74
	v_pk_mul_f32 v[48:49], v[64:65], v[48:49]
	v_pk_mul_f32 v[50:51], v[66:67], v[50:51]
	v_add_f32_e32 v74, v77, v74
	v_cvt_pk_bf16_f32 v48, v48, v49
	v_cvt_pk_bf16_f32 v49, v50, v51
	global_store_dwordx2 v[72:73], v[48:49], off
.LBB0_1733:
	ds_read_b128 v[64:67], v158 offset:1088
	ds_read_b128 v[48:51], v158 offset:2112
	s_and_b64 vcc, exec, s[8:9]
	s_waitcnt lgkmcnt(0)
	v_pk_fma_f32 v[44:45], v[44:45], v[64:65], v[60:61]
	v_pk_fma_f32 v[46:47], v[46:47], v[66:67], v[62:63]
	global_store_dwordx4 v[70:71], v[44:47], off offset:64
	s_cbranch_vccnz .LBB0_1735
	v_pk_mul_f32 v[60:61], v[44:45], v[44:45]
	v_pk_mul_f32 v[62:63], v[46:47], v[46:47]
	v_add_f32_e32 v60, v60, v61
	v_add_f32_e32 v60, v62, v60
	v_add_f32_e32 v60, v63, v60
	v_pk_mul_f32 v[44:45], v[48:49], v[44:45]
	v_pk_mul_f32 v[46:47], v[50:51], v[46:47]
	v_add_f32_e32 v74, v74, v60
	v_cvt_pk_bf16_f32 v44, v44, v45
	v_cvt_pk_bf16_f32 v45, v46, v47
	global_store_dwordx2 v[72:73], v[44:45], off offset:32
.LBB0_1735:
	ds_read_b128 v[48:51], v158 offset:1536
	ds_read_b128 v[44:47], v158 offset:2560
	s_and_b64 vcc, exec, s[8:9]
	s_waitcnt lgkmcnt(0)
	v_pk_fma_f32 v[40:41], v[40:41], v[48:49], v[56:57]
	v_pk_fma_f32 v[42:43], v[42:43], v[50:51], v[58:59]
	global_store_dwordx4 v[70:71], v[40:43], off offset:512
	s_cbranch_vccnz .LBB0_1737
	v_pk_mul_f32 v[48:49], v[40:41], v[40:41]
	v_pk_mul_f32 v[50:51], v[42:43], v[42:43]
	v_add_f32_e32 v48, v48, v49
	v_add_f32_e32 v48, v50, v48
	v_add_f32_e32 v48, v51, v48
	v_pk_mul_f32 v[40:41], v[44:45], v[40:41]
	v_pk_mul_f32 v[42:43], v[46:47], v[42:43]
	v_add_f32_e32 v74, v74, v48
	v_cvt_pk_bf16_f32 v40, v40, v41
	v_cvt_pk_bf16_f32 v41, v42, v43
	global_store_dwordx2 v[72:73], v[40:41], off offset:256
.LBB0_1737:
	ds_read_b128 v[44:47], v158 offset:1600
	ds_read_b128 v[40:43], v158 offset:2624
	s_and_b64 vcc, exec, s[8:9]
	s_waitcnt lgkmcnt(0)
	v_pk_fma_f32 v[36:37], v[36:37], v[44:45], v[52:53]
	v_pk_fma_f32 v[38:39], v[38:39], v[46:47], v[54:55]
	global_store_dwordx4 v[70:71], v[36:39], off offset:576
	s_cbranch_vccnz .LBB0_1741
	v_pk_mul_f32 v[44:45], v[36:37], v[36:37]
	v_pk_mul_f32 v[46:47], v[38:39], v[38:39]
	v_add_f32_e32 v44, v44, v45
	v_add_f32_e32 v44, v46, v44
	v_and_b32_e32 v46, 64, v208
	v_xor_b32_e32 v45, 16, v208
	v_add_u32_e32 v46, 64, v46
	v_cmp_lt_i32_e32 vcc, v45, v46
	v_add_f32_e32 v44, v47, v44
	v_add_f32_e32 v44, v74, v44
	v_cndmask_b32_e32 v45, v208, v45, vcc
	v_lshlrev_b32_e32 v45, 2, v45
	ds_bpermute_b32 v45, v45, v44
	v_pk_mul_f32 v[40:41], v[40:41], v[36:37]
	v_xor_b32_e32 v37, 32, v208
	v_cmp_lt_i32_e32 vcc, v37, v46
	v_pk_mul_f32 v[38:39], v[42:43], v[38:39]
	s_waitcnt lgkmcnt(0)
	v_add_f32_e32 v36, v44, v45
	v_cndmask_b32_e32 v37, v208, v37, vcc
	v_lshlrev_b32_e32 v37, 2, v37
	ds_bpermute_b32 v37, v37, v36
	v_cvt_pk_bf16_f32 v40, v40, v41
	v_cvt_pk_bf16_f32 v41, v38, v39
	global_store_dwordx2 v[72:73], v[40:41], off offset:288
	s_and_saveexec_b64 s[10:11], s[6:7]
	s_cbranch_execz .LBB0_1740
	s_waitcnt lgkmcnt(0)
	v_add_f32_e32 v38, v36, v37
	v_lshl_add_u64 v[36:37], v[68:69], 2, s[22:23]
	global_atomic_add_f32 v[36:37], v38, off

.LBB0_1741:
	v_add_u32_e32 v52, 0xa0, v150
	v_mul_hi_i32 v36, v52, s61
	s_waitcnt lgkmcnt(0)
	v_lshrrev_b32_e32 v37, 31, v36
	v_ashrrev_i32_e32 v36, 11, v36
	v_add_u32_e32 v37, v36, v37
	v_mad_i32_i24 v40, v37, s48, v52
	v_cmp_lt_i32_e32 vcc, s49, v40
	s_and_saveexec_b64 s[10:11], vcc
	s_xor_b64 s[10:11], exec, s[10:11]
	v_lshlrev_b32_e32 v36, 12, v37
	s_movk_i32 s26, 0xff00
	v_add3_u32 v36, v36, v40, s26
	s_or_saveexec_b64 s[10:11], s[10:11]
	v_mov_b64_e32 v[38:39], s[14:15]
	s_xor_b64 exec, exec, s[10:11]
	v_lshl_add_u32 v36, v37, 8, v40
	v_mov_b64_e32 v[38:39], s[18:19]
	s_or_b64 exec, exec, s[10:11]
	v_ashrrev_i32_e32 v37, 31, v36
	v_lshlrev_b64 v[36:37], 12, v[36:37]
	v_lshl_add_u64 v[36:37], v[38:39], 0, v[36:37]
	v_lshl_add_u64 v[62:63], s[24:25], 2, v[36:37]
	v_ashrrev_i32_e32 v53, 31, v52
	v_lshl_add_u64 v[36:37], v[62:63], 0, v[0:1]
	v_mov_b32_e32 v153, v1
	v_lshlrev_b64 v[48:49], 11, v[52:53]
	v_lshl_add_u64 v[58:59], v[36:37], 0, v[152:153]
	global_load_dwordx4 v[44:47], v[58:59], off offset:64
	global_load_dwordx4 v[40:43], v[58:59], off offset:512
	global_load_dwordx4 v[36:39], v[58:59], off offset:576
	v_lshl_add_u64 v[64:65], s[20:21], 0, v[48:49]
	ds_read_b128 v[54:57], v158 offset:1024
	ds_read_b128 v[48:51], v158 offset:2048
	global_load_dwordx4 v[58:61], v[58:59], off
	v_mov_b32_e32 v149, v1
	s_and_b64 vcc, exec, s[8:9]
	s_waitcnt vmcnt(0) lgkmcnt(0)
	v_pk_fma_f32 v[32:33], v[32:33], v[54:55], v[58:59]
	v_pk_fma_f32 v[34:35], v[34:35], v[56:57], v[60:61]
	v_lshl_add_u64 v[54:55], v[62:63], 0, v[148:149]
	v_mov_b32_e32 v58, 0
	v_lshl_add_u64 v[56:57], v[2:3], 1, v[64:65]
	global_store_dwordx4 v[54:55], v[32:35], off
	s_cbranch_vccnz .LBB0_1747
	v_pk_mul_f32 v[58:59], v[32:33], v[32:33]
	v_pk_mul_f32 v[60:61], v[34:35], v[34:35]
	v_add_f32_e32 v58, v58, v59
	v_add_f32_e32 v58, v60, v58
	v_pk_mul_f32 v[32:33], v[48:49], v[32:33]
	v_pk_mul_f32 v[34:35], v[50:51], v[34:35]
	v_add_f32_e32 v58, v61, v58
	v_cvt_pk_bf16_f32 v32, v32, v33
	v_cvt_pk_bf16_f32 v33, v34, v35
	global_store_dwordx2 v[56:57], v[32:33], off
.LBB0_1747:
	ds_read_b128 v[48:51], v158 offset:1088
	ds_read_b128 v[32:35], v158 offset:2112
	s_and_b64 vcc, exec, s[8:9]
	s_waitcnt lgkmcnt(0)
	v_pk_fma_f32 v[28:29], v[28:29], v[48:49], v[44:45]
	v_pk_fma_f32 v[30:31], v[30:31], v[50:51], v[46:47]
	global_store_dwordx4 v[54:55], v[28:31], off offset:64
	s_cbranch_vccnz .LBB0_1749
	v_pk_mul_f32 v[44:45], v[28:29], v[28:29]
	v_pk_mul_f32 v[46:47], v[30:31], v[30:31]
	v_add_f32_e32 v44, v44, v45
	v_add_f32_e32 v44, v46, v44
	v_add_f32_e32 v44, v47, v44
	v_pk_mul_f32 v[28:29], v[32:33], v[28:29]
	v_pk_mul_f32 v[30:31], v[34:35], v[30:31]
	v_add_f32_e32 v58, v58, v44
	v_cvt_pk_bf16_f32 v28, v28, v29
	v_cvt_pk_bf16_f32 v29, v30, v31
	global_store_dwordx2 v[56:57], v[28:29], off offset:32
.LBB0_1749:
	ds_read_b128 v[32:35], v158 offset:1536
	ds_read_b128 v[28:31], v158 offset:2560
	s_and_b64 vcc, exec, s[8:9]
	s_waitcnt lgkmcnt(0)
	v_pk_fma_f32 v[24:25], v[24:25], v[32:33], v[40:41]
	v_pk_fma_f32 v[26:27], v[26:27], v[34:35], v[42:43]
	global_store_dwordx4 v[54:55], v[24:27], off offset:512
	s_cbranch_vccnz .LBB0_1751
	v_pk_mul_f32 v[32:33], v[24:25], v[24:25]
	v_pk_mul_f32 v[34:35], v[26:27], v[26:27]
	v_add_f32_e32 v32, v32, v33
	v_add_f32_e32 v32, v34, v32
	v_add_f32_e32 v32, v35, v32
	v_pk_mul_f32 v[24:25], v[28:29], v[24:25]
	v_pk_mul_f32 v[26:27], v[30:31], v[26:27]
	v_add_f32_e32 v58, v58, v32
	v_cvt_pk_bf16_f32 v24, v24, v25
	v_cvt_pk_bf16_f32 v25, v26, v27
	global_store_dwordx2 v[56:57], v[24:25], off offset:256
.LBB0_1751:
	ds_read_b128 v[28:31], v158 offset:1600
	ds_read_b128 v[24:27], v158 offset:2624
	s_and_b64 vcc, exec, s[8:9]
	s_waitcnt lgkmcnt(0)
	v_pk_fma_f32 v[20:21], v[20:21], v[28:29], v[36:37]
	v_pk_fma_f32 v[22:23], v[22:23], v[30:31], v[38:39]
	global_store_dwordx4 v[54:55], v[20:23], off offset:576
	s_cbranch_vccnz .LBB0_1755
	v_pk_mul_f32 v[28:29], v[20:21], v[20:21]
	v_pk_mul_f32 v[30:31], v[22:23], v[22:23]
	v_add_f32_e32 v28, v28, v29
	v_add_f32_e32 v28, v30, v28
	v_and_b32_e32 v30, 64, v208
	v_xor_b32_e32 v29, 16, v208
	v_add_u32_e32 v30, 64, v30
	v_cmp_lt_i32_e32 vcc, v29, v30
	v_add_f32_e32 v28, v31, v28
	v_add_f32_e32 v28, v58, v28
	v_cndmask_b32_e32 v29, v208, v29, vcc
	v_lshlrev_b32_e32 v29, 2, v29
	ds_bpermute_b32 v29, v29, v28
	v_pk_mul_f32 v[24:25], v[24:25], v[20:21]
	v_xor_b32_e32 v21, 32, v208
	v_cmp_lt_i32_e32 vcc, v21, v30
	v_pk_mul_f32 v[22:23], v[26:27], v[22:23]
	s_waitcnt lgkmcnt(0)
	v_add_f32_e32 v20, v28, v29
	v_cndmask_b32_e32 v21, v208, v21, vcc
	v_lshlrev_b32_e32 v21, 2, v21
	ds_bpermute_b32 v21, v21, v20
	v_cvt_pk_bf16_f32 v24, v24, v25
	v_cvt_pk_bf16_f32 v25, v22, v23
	global_store_dwordx2 v[56:57], v[24:25], off offset:288
	s_and_saveexec_b64 s[10:11], s[6:7]
	s_cbranch_execz .LBB0_1754
	s_waitcnt lgkmcnt(0)
	v_add_f32_e32 v22, v20, v21
	v_lshl_add_u64 v[20:21], v[52:53], 2, s[22:23]
	global_atomic_add_f32 v[20:21], v22, off

.LBB0_1755:
	v_add_u32_e32 v36, 0xb0, v150
	v_mul_hi_i32 v20, v36, s61
	s_waitcnt lgkmcnt(0)
	v_lshrrev_b32_e32 v21, 31, v20
	v_ashrrev_i32_e32 v20, 11, v20
	v_add_u32_e32 v21, v20, v21
	v_mad_i32_i24 v24, v21, s48, v36
	v_cmp_lt_i32_e32 vcc, s49, v24
	s_and_saveexec_b64 s[10:11], vcc
	s_xor_b64 s[10:11], exec, s[10:11]
	v_lshlrev_b32_e32 v20, 12, v21
	s_movk_i32 s26, 0xff00
	v_add3_u32 v20, v20, v24, s26
	s_or_saveexec_b64 s[10:11], s[10:11]
	v_mov_b64_e32 v[22:23], s[14:15]
	s_xor_b64 exec, exec, s[10:11]
	v_lshl_add_u32 v20, v21, 8, v24
	v_mov_b64_e32 v[22:23], s[18:19]
	s_or_b64 exec, exec, s[10:11]
	v_ashrrev_i32_e32 v21, 31, v20
	v_lshlrev_b64 v[20:21], 12, v[20:21]
	v_lshl_add_u64 v[20:21], v[22:23], 0, v[20:21]
	v_lshl_add_u64 v[38:39], s[24:25], 2, v[20:21]
	v_lshl_add_u64 v[20:21], v[38:39], 0, v[0:1]
	v_mov_b32_e32 v153, v1
	v_lshl_add_u64 v[20:21], v[20:21], 0, v[152:153]
	global_load_dwordx4 v[42:45], v[20:21], off
	global_load_dwordx4 v[28:31], v[20:21], off offset:64
	global_load_dwordx4 v[24:27], v[20:21], off offset:512
	s_nop 0
	global_load_dwordx4 v[20:23], v[20:21], off offset:576
	ds_read_b128 v[46:49], v158 offset:1024
	ds_read_b128 v[32:35], v158 offset:2048
	v_ashrrev_i32_e32 v37, 31, v36
	v_lshlrev_b64 v[40:41], 11, v[36:37]
	v_mov_b32_e32 v149, v1
	v_lshl_add_u64 v[50:51], s[20:21], 0, v[40:41]
	v_mov_b32_e32 v0, 0
	s_and_b64 vcc, exec, s[8:9]
	v_lshl_add_u64 v[40:41], v[38:39], 0, v[148:149]
	v_lshl_add_u64 v[38:39], v[2:3], 1, v[50:51]
	s_waitcnt vmcnt(0) lgkmcnt(0)
	v_pk_fma_f32 v[16:17], v[16:17], v[46:47], v[42:43]
	v_pk_fma_f32 v[18:19], v[18:19], v[48:49], v[44:45]
	global_store_dwordx4 v[40:41], v[16:19], off
	s_cbranch_vccnz .LBB0_1761
	v_pk_mul_f32 v[2:3], v[16:17], v[16:17]
	v_pk_mul_f32 v[42:43], v[18:19], v[18:19]
	v_add_f32_e32 v0, v2, v3
	v_add_f32_e32 v0, v42, v0
	v_pk_mul_f32 v[2:3], v[32:33], v[16:17]
	v_pk_mul_f32 v[16:17], v[34:35], v[18:19]
	v_add_f32_e32 v0, v43, v0
	v_cvt_pk_bf16_f32 v2, v2, v3
	v_cvt_pk_bf16_f32 v3, v16, v17
	global_store_dwordx2 v[38:39], v[2:3], off
.LBB0_1761:
	ds_read_b128 v[32:35], v158 offset:1088
	ds_read_b128 v[16:19], v158 offset:2112
	s_and_b64 vcc, exec, s[8:9]
	s_waitcnt lgkmcnt(0)
	v_pk_fma_f32 v[12:13], v[12:13], v[32:33], v[28:29]
	v_pk_fma_f32 v[14:15], v[14:15], v[34:35], v[30:31]
	global_store_dwordx4 v[40:41], v[12:15], off offset:64
	s_cbranch_vccnz .LBB0_1763
	v_pk_mul_f32 v[2:3], v[12:13], v[12:13]
	v_pk_mul_f32 v[28:29], v[14:15], v[14:15]
	v_add_f32_e32 v2, v2, v3
	v_add_f32_e32 v2, v28, v2
	v_add_f32_e32 v2, v29, v2
	v_add_f32_e32 v0, v0, v2
	v_pk_mul_f32 v[2:3], v[16:17], v[12:13]
	v_pk_mul_f32 v[12:13], v[18:19], v[14:15]
	v_cvt_pk_bf16_f32 v2, v2, v3
	v_cvt_pk_bf16_f32 v3, v12, v13
	global_store_dwordx2 v[38:39], v[2:3], off offset:32
.LBB0_1763:
	ds_read_b128 v[16:19], v158 offset:1536
	ds_read_b128 v[12:15], v158 offset:2560
	s_and_b64 vcc, exec, s[8:9]
	s_waitcnt lgkmcnt(0)
	v_pk_fma_f32 v[8:9], v[8:9], v[16:17], v[24:25]
	v_pk_fma_f32 v[10:11], v[10:11], v[18:19], v[26:27]
	global_store_dwordx4 v[40:41], v[8:11], off offset:512
	s_cbranch_vccnz .LBB0_1765
	v_pk_mul_f32 v[2:3], v[8:9], v[8:9]
	v_pk_mul_f32 v[16:17], v[10:11], v[10:11]
	v_add_f32_e32 v2, v2, v3
	v_add_f32_e32 v2, v16, v2
	v_add_f32_e32 v2, v17, v2
	v_add_f32_e32 v0, v0, v2
	v_pk_mul_f32 v[2:3], v[12:13], v[8:9]
	v_pk_mul_f32 v[8:9], v[14:15], v[10:11]
	v_cvt_pk_bf16_f32 v2, v2, v3
	v_cvt_pk_bf16_f32 v3, v8, v9
	global_store_dwordx2 v[38:39], v[2:3], off offset:256
.LBB0_1765:
	ds_read_b128 v[12:15], v158 offset:1600
	ds_read_b128 v[8:11], v158 offset:2624
	s_and_b64 vcc, exec, s[8:9]
	s_waitcnt lgkmcnt(0)
	v_pk_fma_f32 v[2:3], v[4:5], v[12:13], v[20:21]
	v_pk_fma_f32 v[4:5], v[6:7], v[14:15], v[22:23]
	global_store_dwordx4 v[40:41], v[2:5], off offset:576
	s_cbranch_vccnz .LBB0_1611
	v_pk_mul_f32 v[6:7], v[2:3], v[2:3]
	v_pk_mul_f32 v[12:13], v[4:5], v[4:5]
	v_add_f32_e32 v6, v6, v7
	v_add_f32_e32 v6, v12, v6
	v_add_f32_e32 v6, v13, v6
	v_and_b32_e32 v7, 64, v208
	v_add_f32_e32 v0, v0, v6
	v_xor_b32_e32 v6, 16, v208
	v_add_u32_e32 v12, 64, v7
	v_cmp_lt_i32_e32 vcc, v6, v12
	v_pk_mul_f32 v[4:5], v[10:11], v[4:5]
	s_nop 0
	v_cndmask_b32_e32 v6, v208, v6, vcc
	v_lshlrev_b32_e32 v6, 2, v6
	ds_bpermute_b32 v13, v6, v0
	v_pk_mul_f32 v[6:7], v[8:9], v[2:3]
	v_xor_b32_e32 v2, 32, v208
	v_cmp_lt_i32_e32 vcc, v2, v12
	v_cvt_pk_bf16_f32 v6, v6, v7
	s_waitcnt lgkmcnt(0)
	v_add_f32_e32 v0, v0, v13
	v_cndmask_b32_e32 v2, v208, v2, vcc
	v_lshlrev_b32_e32 v2, 2, v2
	ds_bpermute_b32 v2, v2, v0
	v_cvt_pk_bf16_f32 v7, v4, v5
	global_store_dwordx2 v[38:39], v[6:7], off offset:288
	s_and_saveexec_b64 s[8:9], s[6:7]
	s_cbranch_execz .LBB0_1610
	s_waitcnt lgkmcnt(0)
	v_add_f32_e32 v0, v0, v2
	v_lshl_add_u64 v[2:3], v[36:37], 2, s[22:23]
	global_atomic_add_f32 v[2:3], v0, off
	s_branch .LBB0_1610

.LBB0_1797:
	v_mov_b32_e32 v2, s38
	v_add_co_u32_e32 v2, vcc, 0x3000, v2
	v_mov_b32_e32 v3, s39
	buffer_wbl2 sc1
	s_waitcnt vmcnt(0)
	v_addc_co_u32_e32 v3, vcc, 0, v3, vcc
	global_atomic_add v2, v[2:3], v203, off offset:1024 sc0
	v_cvt_f32_u32_e32 v3, v0
	v_sub_u32_e32 v4, 0, v0
	s_mov_b64 s[4:5], -1
	v_rcp_iflag_f32_e32 v3, v3
	s_nop 0
	v_mul_f32_e32 v3, 0x4f7ffffe, v3
	v_cvt_u32_f32_e32 v3, v3
	v_mul_lo_u32 v4, v4, v3
	v_mul_hi_u32 v4, v3, v4
	v_add_u32_e32 v3, v3, v4
	s_waitcnt vmcnt(0) lgkmcnt(0)
	v_mul_hi_u32 v3, v2, v3
	v_mul_lo_u32 v4, v3, v0
	v_sub_u32_e32 v4, v2, v4
	v_cmp_ge_u32_e32 vcc, v4, v0
	v_add_u32_e32 v5, 1, v3
	s_nop 0
	v_cndmask_b32_e32 v3, v3, v5, vcc
	v_sub_u32_e32 v5, v4, v0
	v_cndmask_b32_e32 v4, v4, v5, vcc
	v_cmp_ge_u32_e32 vcc, v4, v0
	v_add_u32_e32 v4, 1, v3
	v_add_u32_e32 v5, 1, v2
	v_cndmask_b32_e32 v4, v3, v4, vcc
	v_mad_u64_u32 v[2:3], s[0:1], v0, v4, v[0:1]
	s_add_u32 s0, s38, 0x3500
	s_addc_u32 s1, s39, 0
	v_cmp_ne_u32_e32 vcc, v5, v2
	v_mov_b64_e32 v[2:3], s[0:1]
	s_and_saveexec_b64 s[2:3], vcc
	s_cbranch_execz .LBB0_1809
	v_mov_b64_e32 v[2:3], s[0:1]
	global_load_dword v0, v[2:3], off sc1
	s_mov_b64 s[8:9], 0
	s_waitcnt vmcnt(0) lgkmcnt(0)
	v_cmp_eq_u32_e32 vcc, v0, v4
	s_and_saveexec_b64 s[6:7], vcc
	s_cbranch_execz .LBB0_1808
	s_add_u32 s4, s38, 0x200
	s_addc_u32 s5, s39, 0
	s_mov_b32 s24, 1
	s_branch .LBB0_1801

.LBB0_1810:
	global_atomic_add v[2:3], v203, off
	s_getpc_b64 s[98:99]
